# GEMM K-loops: phase-closing s_barrier issued before the last MFMA of each 16-MFMA segment (hides barrier release latency)
# speedup vs baseline: 1.0512x; 1.0026x over previous
; #define PG8_STAGE(bufoff, gbase, voff) do { _Pragma("unroll") for (int _i = 0; _i < 2; ++_i) \
;         __builtin_amdgcn_global_load_lds((const unsigned*)((const char*)(gbase) + (voff)[_i]), (LAS unsigned*)(lds + (bufoff) + ldsw + _i * 8192), 16, 0, 0); } while (0)
; #define PG8_LDA(dst, b, h) do { _Pragma("unroll") for (int m = 0; m < 4; ++m) _Pragma("unroll") for (int k = 0; k < 2; ++k) dst[m][k] = *(const LAS bf16x8*)(lds + PG8_SA(b, h) + aoff + m * 2048 + k * 1024); } while (0)
; #define PG8_LDB(dst, b, h) do { _Pragma("unroll") for (int n = 0; n < 2; ++n) _Pragma("unroll") for (int k = 0; k < 2; ++k) dst[n][k] = *(const LAS bf16x8*)(lds + PG8_SB(b, h) + boff + n * 2048 + k * 1024); } while (0)
; #define PG8_MMA(ai, bj, At, Bt) do { __builtin_amdgcn_s_setprio(1); _Pragma("unroll") for (int m = 0; m < 4; ++m) _Pragma("unroll") for (int n = 0; n < 2; ++n) _Pragma("unroll") for (int k = 0; k < 2; ++k) \
;         acc[ai][bj][m][n] = __builtin_amdgcn_mfma_f32_16x16x32_bf16(Bt[n][k], At[m][k], acc[ai][bj][m][n], 0, 0, 0); __builtin_amdgcn_s_setprio(0); } while (0)
; #define PG8_WAIT_L(n) asm volatile("s_waitcnt lgkmcnt(" #n ")" ::: "memory")
; #define PG8_BAR __builtin_amdgcn_s_barrier()
; #define PG8_SCHED __builtin_amdgcn_sched_barrier(0)
; template <class Epi>
; __device__ __forceinline__ void gemm_phase(LAS unsigned char* lds, const Gemm g, const Sched& S, const Epi& E) {
;     ...
;             PG8_LDB(B0, 0, 0); PG8_SCHED; PG8_LDA(At, 0, 0); PG8_STAGE(PG8_SA(1, 1), a1 + hstepA, voffA);
;             PG8_WAIT_L(8); PG8_BAR; PG8_WAIT_L(0); PG8_MMA(0, 0, At, B0); PG8_BAR; PG8_SCHED;
;             PG8_LDB(B1, 0, 1); PG8_STAGE(PG8_SB(0, 0), b2, voffB);
;             PG8_BAR; PG8_WAIT_L(0); PG8_MMA(0, 1, At, B1); PG8_BAR;
;             PG8_LDA(At, 0, 1); PG8_STAGE(PG8_SA(0, 0), a2, voffA);
;             PG8_BAR; PG8_WAIT_L(0); PG8_MMA(1, 0, At, B0); PG8_BAR; PG8_SCHED;
.LBB0_177:
	v_add_u32_e32 v162, s62, v148
	s_add_u32 s38, s10, s24
	ds_read_b128 v[150:153], v162
	ds_read_b128 v[154:157], v162 offset:1024
	ds_read_b128 v[158:161], v162 offset:2048
	ds_read_b128 v[162:165], v162 offset:3072
	s_addc_u32 s39, s11, s25
	s_add_u32 s38, s38, 0x100
	s_addc_u32 s39, s39, 0
	s_add_u32 s71, s9, s24
	s_addc_u32 s80, s51, s25
	s_cmpk_eq_i32 s24, 0xf00
	s_cselect_b32 s53, s19, s39
	s_cselect_b32 s52, s66, s38
	s_cselect_b32 s39, s17, s80
	s_cselect_b32 s38, s67, s71
	v_lshl_add_u64 v[190:191], v[144:145], 0, s[24:25]
	s_add_i32 m0, s35, 0xc000
	ds_read_b128 v[166:169], v149
	ds_read_b128 v[170:173], v149 offset:1024
	ds_read_b128 v[174:177], v149 offset:2048
	ds_read_b128 v[178:181], v149 offset:3072
	ds_read_b128 v[182:185], v149 offset:4096
	ds_read_b128 v[186:189], v149 offset:5120
	ds_read_b128 v[194:197], v149 offset:6144
	ds_read_b128 v[198:201], v149 offset:7168
	global_load_lds_dwordx4 v[190:191], off
	v_lshl_add_u64 v[190:191], v[146:147], 0, s[24:25]
	s_add_i32 m0, s35, 0xe000
	s_nop 0
	global_load_lds_dwordx4 v[190:191], off
	s_waitcnt lgkmcnt(8)
	s_barrier
	s_waitcnt lgkmcnt(0)
	s_setprio 1
	s_waitcnt lgkmcnt(0)
	v_mfma_f32_16x16x32_bf16 v[124:127], v[150:153], v[166:169], v[124:127]
	v_mfma_f32_16x16x32_bf16 v[120:123], v[158:161], v[166:169], v[120:123]
	v_mfma_f32_16x16x32_bf16 v[116:119], v[150:153], v[174:177], v[116:119]
	v_mfma_f32_16x16x32_bf16 v[112:115], v[158:161], v[174:177], v[112:115]
	v_mfma_f32_16x16x32_bf16 v[108:111], v[150:153], v[182:185], v[108:111]
	v_mfma_f32_16x16x32_bf16 v[104:107], v[158:161], v[182:185], v[104:107]
	v_mfma_f32_16x16x32_bf16 v[100:103], v[150:153], v[194:197], v[100:103]
	v_mfma_f32_16x16x32_bf16 v[96:99], v[158:161], v[194:197], v[96:99]
	v_mfma_f32_16x16x32_bf16 v[124:127], v[154:157], v[170:173], v[124:127]
	v_mfma_f32_16x16x32_bf16 v[120:123], v[162:165], v[170:173], v[120:123]
	v_mfma_f32_16x16x32_bf16 v[116:119], v[154:157], v[178:181], v[116:119]
	v_mfma_f32_16x16x32_bf16 v[112:115], v[162:165], v[178:181], v[112:115]
	v_mfma_f32_16x16x32_bf16 v[108:111], v[154:157], v[186:189], v[108:111]
	v_mfma_f32_16x16x32_bf16 v[104:107], v[162:165], v[186:189], v[104:107]
	v_mfma_f32_16x16x32_bf16 v[100:103], v[154:157], v[198:201], v[100:103]
	s_barrier
	v_mfma_f32_16x16x32_bf16 v[96:99], v[162:165], v[198:201], v[96:99]
	s_setprio 0
	v_add_u32_e32 v190, s63, v148
	s_add_i32 s71, s62, s1
	ds_read_b128 v[202:205], v190
	ds_read_b128 v[206:209], v190 offset:1024
	ds_read_b128 v[210:213], v190 offset:2048
	ds_read_b128 v[214:217], v190 offset:3072
	v_lshl_add_u64 v[190:191], s[38:39], 0, v[130:131]
	s_mov_b32 m0, s71
	v_lshl_add_u64 v[218:219], s[38:39], 0, v[128:129]
	global_load_lds_dwordx4 v[190:191], off
	s_add_i32 m0, s71, 0x2000
	s_nop 0
	global_load_lds_dwordx4 v[218:219], off
	s_barrier
	s_waitcnt lgkmcnt(0)
	s_setprio 1
	s_waitcnt lgkmcnt(0)
	v_mfma_f32_16x16x32_bf16 v[92:95], v[202:205], v[166:169], v[92:95]
	v_mfma_f32_16x16x32_bf16 v[88:91], v[210:213], v[166:169], v[88:91]
	v_mfma_f32_16x16x32_bf16 v[84:87], v[202:205], v[174:177], v[84:87]
	v_mfma_f32_16x16x32_bf16 v[80:83], v[210:213], v[174:177], v[80:83]
	v_mfma_f32_16x16x32_bf16 v[76:79], v[202:205], v[182:185], v[76:79]
	v_mfma_f32_16x16x32_bf16 v[72:75], v[210:213], v[182:185], v[72:75]
	v_mfma_f32_16x16x32_bf16 v[68:71], v[202:205], v[194:197], v[68:71]
	v_mfma_f32_16x16x32_bf16 v[64:67], v[210:213], v[194:197], v[64:67]
	v_mfma_f32_16x16x32_bf16 v[92:95], v[206:209], v[170:173], v[92:95]
	v_mfma_f32_16x16x32_bf16 v[88:91], v[214:217], v[170:173], v[88:91]
	v_mfma_f32_16x16x32_bf16 v[84:87], v[206:209], v[178:181], v[84:87]
	v_mfma_f32_16x16x32_bf16 v[80:83], v[214:217], v[178:181], v[80:83]
	v_mfma_f32_16x16x32_bf16 v[76:79], v[206:209], v[186:189], v[76:79]
	v_mfma_f32_16x16x32_bf16 v[72:75], v[214:217], v[186:189], v[72:75]
	v_mfma_f32_16x16x32_bf16 v[68:71], v[206:209], v[198:201], v[68:71]
	s_barrier
	v_mfma_f32_16x16x32_bf16 v[64:67], v[214:217], v[198:201], v[64:67]
	s_setprio 0
	s_mov_b32 m0, s35
	v_lshl_add_u64 v[220:221], s[52:53], 0, v[130:131]
	ds_read_b128 v[166:169], v149 offset:16384
	ds_read_b128 v[170:173], v149 offset:17408
	ds_read_b128 v[174:177], v149 offset:18432
	ds_read_b128 v[178:181], v149 offset:19456
	ds_read_b128 v[182:185], v149 offset:20480
	ds_read_b128 v[186:189], v149 offset:21504
	ds_read_b128 v[194:197], v149 offset:22528
	ds_read_b128 v[198:201], v149 offset:23552
	global_load_lds_dwordx4 v[220:221], off
	v_lshl_add_u64 v[222:223], s[52:53], 0, v[128:129]
	s_mov_b32 m0, s43
	s_nop 0
	global_load_lds_dwordx4 v[222:223], off
	s_barrier
	s_waitcnt lgkmcnt(0)
	s_setprio 1
	s_waitcnt lgkmcnt(0)
	v_mfma_f32_16x16x32_bf16 v[60:63], v[150:153], v[166:169], v[60:63]
	v_mfma_f32_16x16x32_bf16 v[56:59], v[158:161], v[166:169], v[56:59]
	v_mfma_f32_16x16x32_bf16 v[52:55], v[150:153], v[174:177], v[52:55]
	v_mfma_f32_16x16x32_bf16 v[48:51], v[158:161], v[174:177], v[48:51]
	v_mfma_f32_16x16x32_bf16 v[44:47], v[150:153], v[182:185], v[44:47]
	v_mfma_f32_16x16x32_bf16 v[40:43], v[158:161], v[182:185], v[40:43]
	v_mfma_f32_16x16x32_bf16 v[36:39], v[150:153], v[194:197], v[36:39]
	v_mfma_f32_16x16x32_bf16 v[32:35], v[158:161], v[194:197], v[32:35]
	v_mfma_f32_16x16x32_bf16 v[60:63], v[154:157], v[170:173], v[60:63]
	v_mfma_f32_16x16x32_bf16 v[56:59], v[162:165], v[170:173], v[56:59]
	v_mfma_f32_16x16x32_bf16 v[52:55], v[154:157], v[178:181], v[52:55]
	v_mfma_f32_16x16x32_bf16 v[48:51], v[162:165], v[178:181], v[48:51]
	v_mfma_f32_16x16x32_bf16 v[44:47], v[154:157], v[186:189], v[44:47]
	v_mfma_f32_16x16x32_bf16 v[40:43], v[162:165], v[186:189], v[40:43]
	v_mfma_f32_16x16x32_bf16 v[36:39], v[154:157], v[198:201], v[36:39]
	s_barrier
; #define PG8_STAGE(bufoff, gbase, voff) do { _Pragma("unroll") for (int _i = 0; _i < 2; ++_i) \
;         __builtin_amdgcn_global_load_lds((const unsigned*)((const char*)(gbase) + (voff)[_i]), (LAS unsigned*)(lds + (bufoff) + ldsw + _i * 8192), 16, 0, 0); } while (0)
; #define PG8_LDA(dst, b, h) do { _Pragma("unroll") for (int m = 0; m < 4; ++m) _Pragma("unroll") for (int k = 0; k < 2; ++k) dst[m][k] = *(const LAS bf16x8*)(lds + PG8_SA(b, h) + aoff + m * 2048 + k * 1024); } while (0)
; #define PG8_LDB(dst, b, h) do { _Pragma("unroll") for (int n = 0; n < 2; ++n) _Pragma("unroll") for (int k = 0; k < 2; ++k) dst[n][k] = *(const LAS bf16x8*)(lds + PG8_SB(b, h) + boff + n * 2048 + k * 1024); } while (0)
; #define PG8_MMA(ai, bj, At, Bt) do { __builtin_amdgcn_s_setprio(1); _Pragma("unroll") for (int m = 0; m < 4; ++m) _Pragma("unroll") for (int n = 0; n < 2; ++n) _Pragma("unroll") for (int k = 0; k < 2; ++k) \
;         acc[ai][bj][m][n] = __builtin_amdgcn_mfma_f32_16x16x32_bf16(Bt[n][k], At[m][k], acc[ai][bj][m][n], 0, 0, 0); __builtin_amdgcn_s_setprio(0); } while (0)
; #define PG8_WAIT_V(n) asm volatile("s_waitcnt vmcnt(" #n ")" ::: "memory")
; #define PG8_WAIT_L(n) asm volatile("s_waitcnt lgkmcnt(" #n ")" ::: "memory")
; #define PG8_BAR __builtin_amdgcn_s_barrier()
; #define PG8_SCHED __builtin_amdgcn_sched_barrier(0)
; template <class Epi>
; __device__ __forceinline__ void gemm_phase(LAS unsigned char* lds, const Gemm g, const Sched& S, const Epi& E) {
;     ...
;             PG8_STAGE(PG8_SB(0, 1), b2 + hstepB, voffB);
;             PG8_WAIT_V(6); PG8_BAR; PG8_MMA(1, 1, At, B1); PG8_BAR;
;             PG8_LDB(B0, 1, 0); PG8_SCHED; PG8_LDA(At, 1, 0); PG8_STAGE(PG8_SA(0, 1), a2 + hstepA, voffA);
;             PG8_WAIT_L(8); PG8_BAR; PG8_WAIT_L(0); PG8_MMA(0, 0, At, B0); PG8_BAR; PG8_SCHED;
;             PG8_LDB(B1, 1, 1); PG8_STAGE(PG8_SB(1, 0), b3, voffB);
;             PG8_BAR; PG8_WAIT_L(0); PG8_MMA(0, 1, At, B1); PG8_BAR;
;             PG8_LDA(At, 1, 1); PG8_STAGE(PG8_SA(1, 0), a3, voffA);
;             PG8_BAR; PG8_WAIT_L(0); PG8_MMA(1, 0, At, B0); PG8_BAR; PG8_SCHED;
	v_mfma_f32_16x16x32_bf16 v[32:35], v[162:165], v[198:201], v[32:35]
	s_setprio 0
	s_add_u32 s80, s38, 0x80000
	s_addc_u32 s81, s39, 0
	s_add_i32 s71, s63, s1
	v_lshl_add_u64 v[150:151], s[80:81], 0, v[130:131]
	s_mov_b32 m0, s71
	s_nop 0
	global_load_lds_dwordx4 v[150:151], off
	v_lshl_add_u64 v[150:151], s[80:81], 0, v[128:129]
	s_add_i32 m0, s71, 0x2000
	s_nop 0
	global_load_lds_dwordx4 v[150:151], off
	s_waitcnt vmcnt(6)
	s_barrier
	s_setprio 1
	v_mfma_f32_16x16x32_bf16 v[28:31], v[202:205], v[166:169], v[28:31]
	v_mfma_f32_16x16x32_bf16 v[24:27], v[210:213], v[166:169], v[24:27]
	v_mfma_f32_16x16x32_bf16 v[20:23], v[202:205], v[174:177], v[20:23]
	v_mfma_f32_16x16x32_bf16 v[16:19], v[210:213], v[174:177], v[16:19]
	v_mfma_f32_16x16x32_bf16 v[12:15], v[202:205], v[182:185], v[12:15]
	v_mfma_f32_16x16x32_bf16 v[8:11], v[210:213], v[182:185], v[8:11]
	v_mfma_f32_16x16x32_bf16 v[4:7], v[202:205], v[194:197], v[4:7]
	v_mfma_f32_16x16x32_bf16 v[0:3], v[210:213], v[194:197], v[0:3]
	v_mfma_f32_16x16x32_bf16 v[28:31], v[206:209], v[170:173], v[28:31]
	v_mfma_f32_16x16x32_bf16 v[24:27], v[214:217], v[170:173], v[24:27]
	v_mfma_f32_16x16x32_bf16 v[20:23], v[206:209], v[178:181], v[20:23]
	v_mfma_f32_16x16x32_bf16 v[16:19], v[214:217], v[178:181], v[16:19]
	v_mfma_f32_16x16x32_bf16 v[12:15], v[206:209], v[186:189], v[12:15]
	v_mfma_f32_16x16x32_bf16 v[8:11], v[214:217], v[186:189], v[8:11]
	v_mfma_f32_16x16x32_bf16 v[4:7], v[206:209], v[198:201], v[4:7]
	s_barrier
	v_mfma_f32_16x16x32_bf16 v[0:3], v[214:217], v[198:201], v[0:3]
	s_setprio 0
	s_add_i32 s71, 0, 0x18000
	v_add_u32_e32 v162, s71, v148
	ds_read_b128 v[150:153], v162
	ds_read_b128 v[154:157], v162 offset:1024
	ds_read_b128 v[158:161], v162 offset:2048
	ds_read_b128 v[162:165], v162 offset:3072
	s_add_u32 s52, s52, 0x80000
	s_addc_u32 s53, s53, 0
	s_mov_b32 m0, s54
	v_lshl_add_u64 v[202:203], s[52:53], 0, v[130:131]
	ds_read_b128 v[166:169], v149 offset:32768
	ds_read_b128 v[170:173], v149 offset:33792
	ds_read_b128 v[174:177], v149 offset:34816
	ds_read_b128 v[178:181], v149 offset:35840
	ds_read_b128 v[182:185], v149 offset:36864
	ds_read_b128 v[186:189], v149 offset:37888
	ds_read_b128 v[194:197], v149 offset:38912
	ds_read_b128 v[198:201], v149 offset:39936
	global_load_lds_dwordx4 v[202:203], off
	v_lshl_add_u64 v[202:203], s[52:53], 0, v[128:129]
	s_mov_b32 m0, s55
	s_nop 0
	global_load_lds_dwordx4 v[202:203], off
	s_waitcnt lgkmcnt(8)
	s_barrier
	s_waitcnt lgkmcnt(0)
	s_setprio 1
	s_waitcnt lgkmcnt(0)
	v_mfma_f32_16x16x32_bf16 v[124:127], v[150:153], v[166:169], v[124:127]
	v_mfma_f32_16x16x32_bf16 v[120:123], v[158:161], v[166:169], v[120:123]
	v_mfma_f32_16x16x32_bf16 v[116:119], v[150:153], v[174:177], v[116:119]
	v_mfma_f32_16x16x32_bf16 v[112:115], v[158:161], v[174:177], v[112:115]
	v_mfma_f32_16x16x32_bf16 v[108:111], v[150:153], v[182:185], v[108:111]
	v_mfma_f32_16x16x32_bf16 v[104:107], v[158:161], v[182:185], v[104:107]
	v_mfma_f32_16x16x32_bf16 v[100:103], v[150:153], v[194:197], v[100:103]
	v_mfma_f32_16x16x32_bf16 v[96:99], v[158:161], v[194:197], v[96:99]
	v_mfma_f32_16x16x32_bf16 v[124:127], v[154:157], v[170:173], v[124:127]
	v_mfma_f32_16x16x32_bf16 v[120:123], v[162:165], v[170:173], v[120:123]
	v_mfma_f32_16x16x32_bf16 v[116:119], v[154:157], v[178:181], v[116:119]
	v_mfma_f32_16x16x32_bf16 v[112:115], v[162:165], v[178:181], v[112:115]
	v_mfma_f32_16x16x32_bf16 v[108:111], v[154:157], v[186:189], v[108:111]
	v_mfma_f32_16x16x32_bf16 v[104:107], v[162:165], v[186:189], v[104:107]
	v_mfma_f32_16x16x32_bf16 v[100:103], v[154:157], v[198:201], v[100:103]
	s_barrier
	v_mfma_f32_16x16x32_bf16 v[96:99], v[162:165], v[198:201], v[96:99]
	s_setprio 0
	s_add_i32 s52, 0, 0x1c000
	s_add_i32 s53, s71, s1
	v_add_u32_e32 v214, s52, v148
	v_lshl_add_u64 v[190:191], v[190:191], 0, s[14:15]
	s_mov_b32 m0, s53
	ds_read_b128 v[202:205], v214
	ds_read_b128 v[206:209], v214 offset:1024
	ds_read_b128 v[210:213], v214 offset:2048
	ds_read_b128 v[214:217], v214 offset:3072
	global_load_lds_dwordx4 v[190:191], off
	v_lshl_add_u64 v[190:191], v[218:219], 0, s[14:15]
	s_add_i32 m0, s53, 0x2000
	s_nop 0
	global_load_lds_dwordx4 v[190:191], off
	s_barrier
	s_waitcnt lgkmcnt(0)
	s_setprio 1
	s_waitcnt lgkmcnt(0)
	v_mfma_f32_16x16x32_bf16 v[92:95], v[202:205], v[166:169], v[92:95]
	v_mfma_f32_16x16x32_bf16 v[88:91], v[210:213], v[166:169], v[88:91]
	v_mfma_f32_16x16x32_bf16 v[84:87], v[202:205], v[174:177], v[84:87]
	v_mfma_f32_16x16x32_bf16 v[80:83], v[210:213], v[174:177], v[80:83]
	v_mfma_f32_16x16x32_bf16 v[76:79], v[202:205], v[182:185], v[76:79]
	v_mfma_f32_16x16x32_bf16 v[72:75], v[210:213], v[182:185], v[72:75]
	v_mfma_f32_16x16x32_bf16 v[68:71], v[202:205], v[194:197], v[68:71]
	v_mfma_f32_16x16x32_bf16 v[64:67], v[210:213], v[194:197], v[64:67]
	v_mfma_f32_16x16x32_bf16 v[92:95], v[206:209], v[170:173], v[92:95]
	v_mfma_f32_16x16x32_bf16 v[88:91], v[214:217], v[170:173], v[88:91]
	v_mfma_f32_16x16x32_bf16 v[84:87], v[206:209], v[178:181], v[84:87]
	v_mfma_f32_16x16x32_bf16 v[80:83], v[214:217], v[178:181], v[80:83]
	v_mfma_f32_16x16x32_bf16 v[76:79], v[206:209], v[186:189], v[76:79]
	v_mfma_f32_16x16x32_bf16 v[72:75], v[214:217], v[186:189], v[72:75]
	v_mfma_f32_16x16x32_bf16 v[68:71], v[206:209], v[198:201], v[68:71]
	s_barrier
	v_mfma_f32_16x16x32_bf16 v[64:67], v[214:217], v[198:201], v[64:67]
	s_setprio 0
	s_mov_b32 m0, s59
	v_lshl_add_u64 v[190:191], v[220:221], 0, s[14:15]
	ds_read_b128 v[166:169], v149 offset:49152
	ds_read_b128 v[170:173], v149 offset:50176
	ds_read_b128 v[174:177], v149 offset:51200
	ds_read_b128 v[178:181], v149 offset:52224
	ds_read_b128 v[182:185], v149 offset:53248
	ds_read_b128 v[186:189], v149 offset:54272
	ds_read_b128 v[194:197], v149 offset:55296
	ds_read_b128 v[198:201], v149 offset:56320
	global_load_lds_dwordx4 v[190:191], off
	v_lshl_add_u64 v[190:191], v[222:223], 0, s[14:15]
	s_mov_b32 m0, s61
	s_nop 0
	global_load_lds_dwordx4 v[190:191], off
	s_barrier
; __device__ __forceinline__ unsigned cvt_pk_bf16(float lo, float hi) { unsigned r; asm volatile("v_cvt_pk_bf16_f32 %0, %1, %2" : "=v"(r) : "v"(lo), "v"(hi)); return r; }
; #define PG8_STAGE(bufoff, gbase, voff) do { _Pragma("unroll") for (int _i = 0; _i < 2; ++_i) \
;         __builtin_amdgcn_global_load_lds((const unsigned*)((const char*)(gbase) + (voff)[_i]), (LAS unsigned*)(lds + (bufoff) + ldsw + _i * 8192), 16, 0, 0); } while (0)
; #define PG8_MMA(ai, bj, At, Bt) do { __builtin_amdgcn_s_setprio(1); _Pragma("unroll") for (int m = 0; m < 4; ++m) _Pragma("unroll") for (int n = 0; n < 2; ++n) _Pragma("unroll") for (int k = 0; k < 2; ++k) \
;         acc[ai][bj][m][n] = __builtin_amdgcn_mfma_f32_16x16x32_bf16(Bt[n][k], At[m][k], acc[ai][bj][m][n], 0, 0, 0); __builtin_amdgcn_s_setprio(0); } while (0)
; #define PG8_WAIT_V(n) asm volatile("s_waitcnt vmcnt(" #n ")" ::: "memory")
; #define PG8_WAIT_L(n) asm volatile("s_waitcnt lgkmcnt(" #n ")" ::: "memory")
; #define PG8_BAR __builtin_amdgcn_s_barrier()
; #define PG8_SCHED __builtin_amdgcn_sched_barrier(0)
; template <class Epi>
; __device__ __forceinline__ void gemm_phase(LAS unsigned char* lds, const Gemm g, const Sched& S, const Epi& E) {
;     ...
;             PG8_BAR; PG8_WAIT_L(0); PG8_MMA(1, 0, At, B0); PG8_BAR; PG8_SCHED;
;             PG8_STAGE(PG8_SB(1, 1), b3 + hstepB, voffB);
;             PG8_WAIT_V(6); PG8_BAR; PG8_MMA(1, 1, At, B1); PG8_BAR;
;         }
;         E(acc, cur, wr, wc, fr, fq);
;     __device__ __forceinline__ void operator()(AccRef acc, const Unit& u, int wr, int wc, int fr, int fq) const {
;     ...
;                 for (int bj = 0; bj < 2; ++bj) { const f32x4 gg = acc[ai][bj][m][0], uu = acc[ai][bj][m][1];
; #pragma unroll
;                     for (int j = 0; j < 4; ++j) o[4 * bj + j] = gg[j] * __builtin_amdgcn_rcpf(1.0f + __expf(-gg[j])) * uu[j]; }
;                 u32x4 w; w.x = cvt_pk_bf16(o[0], o[1]); w.y = cvt_pk_bf16(o[2], o[3]); w.z = cvt_pk_bf16(o[4], o[5]); w.w = cvt_pk_bf16(o[6], o[7]);
;                 *(u32x4*)(act + row * FF_ + (u.pn * 4 + wc) * 32 + 8 * fq) = w; }
	s_waitcnt lgkmcnt(0)
	s_setprio 1
	s_waitcnt lgkmcnt(0)
	v_mfma_f32_16x16x32_bf16 v[60:63], v[150:153], v[166:169], v[60:63]
	v_mfma_f32_16x16x32_bf16 v[56:59], v[158:161], v[166:169], v[56:59]
	v_mfma_f32_16x16x32_bf16 v[52:55], v[150:153], v[174:177], v[52:55]
	v_mfma_f32_16x16x32_bf16 v[48:51], v[158:161], v[174:177], v[48:51]
	v_mfma_f32_16x16x32_bf16 v[44:47], v[150:153], v[182:185], v[44:47]
	v_mfma_f32_16x16x32_bf16 v[40:43], v[158:161], v[182:185], v[40:43]
	v_mfma_f32_16x16x32_bf16 v[36:39], v[150:153], v[194:197], v[36:39]
	v_mfma_f32_16x16x32_bf16 v[32:35], v[158:161], v[194:197], v[32:35]
	v_mfma_f32_16x16x32_bf16 v[60:63], v[154:157], v[170:173], v[60:63]
	v_mfma_f32_16x16x32_bf16 v[56:59], v[162:165], v[170:173], v[56:59]
	v_mfma_f32_16x16x32_bf16 v[52:55], v[154:157], v[178:181], v[52:55]
	v_mfma_f32_16x16x32_bf16 v[48:51], v[162:165], v[178:181], v[48:51]
	v_mfma_f32_16x16x32_bf16 v[44:47], v[154:157], v[186:189], v[44:47]
	v_mfma_f32_16x16x32_bf16 v[40:43], v[162:165], v[186:189], v[40:43]
	v_mfma_f32_16x16x32_bf16 v[36:39], v[154:157], v[198:201], v[36:39]
	s_barrier
	v_mfma_f32_16x16x32_bf16 v[32:35], v[162:165], v[198:201], v[32:35]
	s_setprio 0
	s_add_u32 s38, s38, 0x80080
	s_addc_u32 s39, s39, 0
	s_add_i32 s52, s52, s1
	v_lshl_add_u64 v[150:151], s[38:39], 0, v[130:131]
	s_mov_b32 m0, s52
	s_nop 0
	global_load_lds_dwordx4 v[150:151], off
	v_lshl_add_u64 v[150:151], s[38:39], 0, v[128:129]
	s_add_i32 m0, s52, 0x2000
	s_nop 0
	global_load_lds_dwordx4 v[150:151], off
	s_waitcnt vmcnt(6)
	s_barrier
	s_setprio 1
	v_mfma_f32_16x16x32_bf16 v[28:31], v[202:205], v[166:169], v[28:31]
	v_mfma_f32_16x16x32_bf16 v[24:27], v[210:213], v[166:169], v[24:27]
	v_mfma_f32_16x16x32_bf16 v[20:23], v[202:205], v[174:177], v[20:23]
	v_mfma_f32_16x16x32_bf16 v[16:19], v[210:213], v[174:177], v[16:19]
	v_mfma_f32_16x16x32_bf16 v[12:15], v[202:205], v[182:185], v[12:15]
	v_mfma_f32_16x16x32_bf16 v[8:11], v[210:213], v[182:185], v[8:11]
	v_mfma_f32_16x16x32_bf16 v[4:7], v[202:205], v[194:197], v[4:7]
	v_mfma_f32_16x16x32_bf16 v[0:3], v[210:213], v[194:197], v[0:3]
	v_mfma_f32_16x16x32_bf16 v[28:31], v[206:209], v[170:173], v[28:31]
	v_mfma_f32_16x16x32_bf16 v[24:27], v[214:217], v[170:173], v[24:27]
	v_mfma_f32_16x16x32_bf16 v[20:23], v[206:209], v[178:181], v[20:23]
	v_mfma_f32_16x16x32_bf16 v[16:19], v[214:217], v[178:181], v[16:19]
	v_mfma_f32_16x16x32_bf16 v[12:15], v[206:209], v[186:189], v[12:15]
	v_mfma_f32_16x16x32_bf16 v[8:11], v[214:217], v[186:189], v[8:11]
	v_mfma_f32_16x16x32_bf16 v[4:7], v[206:209], v[198:201], v[4:7]
	s_barrier
	v_mfma_f32_16x16x32_bf16 v[0:3], v[214:217], v[198:201], v[0:3]
	s_setprio 0
	s_add_i32 s70, s70, 2
	s_add_u32 s24, s24, 0x100
	s_addc_u32 s25, s25, 0
	s_cmp_gt_u32 s70, 29
	s_cbranch_scc0 .LBB0_177
	v_mul_f32_e32 v150, 0xbfb8aa3b, v126
	v_exp_f32_e32 v150, v150
	v_mul_f32_e32 v151, 0xbfb8aa3b, v127
	v_exp_f32_e32 v151, v151
	v_mul_f32_e32 v152, 0xbfb8aa3b, v92
	v_add_f32_e32 v150, 1.0, v150
	v_rcp_f32_e32 v150, v150
	v_add_f32_e32 v151, 1.0, v151
	v_rcp_f32_e32 v151, v151
	v_exp_f32_e32 v152, v152
	v_mul_f32_e32 v150, v126, v150
	v_mul_f32_e32 v153, v122, v150
	v_mul_f32_e32 v150, v127, v151
	v_add_f32_e32 v151, 1.0, v152
	v_rcp_f32_e32 v151, v151
	v_mul_f32_e32 v152, 0xbfb8aa3b, v93
	v_exp_f32_e32 v152, v152
	v_mul_f32_e32 v146, 0xbfb8aa3b, v124
	v_mul_f32_e32 v147, 0xbfb8aa3b, v125
	v_mul_f32_e32 v154, v123, v150
	v_mul_f32_e32 v150, v92, v151
	v_mul_f32_e32 v151, 0xbfb8aa3b, v94
	v_exp_f32_e32 v146, v146
	v_exp_f32_e32 v147, v147
	v_mul_f32_e32 v155, v88, v150
	v_add_f32_e32 v150, 1.0, v152
	v_exp_f32_e32 v151, v151
	v_mul_f32_e32 v152, 0xbfb8aa3b, v95
	v_exp_f32_e32 v152, v152
	v_add_f32_e32 v146, 1.0, v146
	v_add_f32_e32 v147, 1.0, v147
	v_rcp_f32_e32 v150, v150
	v_add_f32_e32 v151, 1.0, v151
	v_rcp_f32_e32 v146, v146
	v_rcp_f32_e32 v147, v147
	v_rcp_f32_e32 v151, v151
	v_add_f32_e32 v152, 1.0, v152
	v_rcp_f32_e32 v152, v152
	s_add_u32 s24, s9, 0xffffff00
	v_mul_f32_e32 v150, v93, v150
	s_addc_u32 s25, s51, -1
	s_ashr_i32 s9, s8, 31
	v_mul_f32_e32 v146, v124, v146
	v_mul_f32_e32 v147, v125, v147
	v_mul_f32_e32 v156, v89, v150
	v_mul_f32_e32 v150, v94, v151
	s_lshl_b64 s[38:39], s[8:9], 8
	v_mul_f32_e32 v146, v120, v146
	v_mul_f32_e32 v147, v121, v147
	v_mul_f32_e32 v157, v90, v150
	v_mul_f32_e32 v150, v95, v152
	v_lshl_add_u64 v[144:145], v[134:135], 0, s[38:39]
	v_mul_f32_e32 v158, v91, v150
	v_cvt_pk_bf16_f32 v150, v146, v147
	v_mov_b64_e32 v[146:147], s[44:45]
	v_mad_u64_u32 v[146:147], s[52:53], v144, s64, v[146:147]
	s_lshl_b32 s9, s57, 7
	v_mov_b32_e32 v144, v147
	s_or_b32 s38, s9, s58
	v_mad_u64_u32 v[144:145], s[52:53], v145, s64, v[144:145]
	s_ashr_i32 s39, s38, 31
	v_mov_b32_e32 v147, v144
	v_lshl_add_u64 v[144:145], s[38:39], 1, v[146:147]
	v_lshl_add_u64 v[144:145], v[144:145], 0, v[132:133]
	v_cvt_pk_bf16_f32 v151, v153, v154
	v_cvt_pk_bf16_f32 v152, v155, v156
	v_cvt_pk_bf16_f32 v153, v157, v158
	global_store_dwordx4 v[144:145], v[150:153], off
	v_mul_f32_e32 v146, 0xbfb8aa3b, v116
	v_exp_f32_e32 v146, v146
	v_mul_f32_e32 v150, 0xbfb8aa3b, v118
	v_exp_f32_e32 v150, v150
	v_mul_f32_e32 v151, 0xbfb8aa3b, v119
	v_exp_f32_e32 v151, v151
	v_mul_f32_e32 v152, 0xbfb8aa3b, v84
	v_add_f32_e32 v150, 1.0, v150
	v_rcp_f32_e32 v150, v150
	v_add_f32_e32 v151, 1.0, v151
	v_rcp_f32_e32 v151, v151
	v_exp_f32_e32 v152, v152
	v_mul_f32_e32 v150, v118, v150
	v_mul_f32_e32 v153, v114, v150
	v_mul_f32_e32 v150, v119, v151
	v_add_f32_e32 v151, 1.0, v152
	v_rcp_f32_e32 v151, v151
	v_mul_f32_e32 v152, 0xbfb8aa3b, v85
	v_exp_f32_e32 v152, v152
	v_mul_f32_e32 v154, v115, v150
	v_mul_f32_e32 v150, v84, v151
; __device__ __forceinline__ unsigned cvt_pk_bf16(float lo, float hi) { unsigned r; asm volatile("v_cvt_pk_bf16_f32 %0, %1, %2" : "=v"(r) : "v"(lo), "v"(hi)); return r; }
;     __device__ __forceinline__ void operator()(AccRef acc, const Unit& u, int wr, int wc, int fr, int fq) const {
; #pragma unroll
;         for (int ai = 0; ai < 2; ++ai)
; #pragma unroll
;             for (int m = 0; m < 4; ++m) { const size_t row = (size_t)u.pm * 256 + ai * 128 + wr * 64 + m * 16 + fr; float o[8];
; #pragma unroll
;                 for (int bj = 0; bj < 2; ++bj) { const f32x4 gg = acc[ai][bj][m][0], uu = acc[ai][bj][m][1];
; #pragma unroll
;                     for (int j = 0; j < 4; ++j) o[4 * bj + j] = gg[j] * __builtin_amdgcn_rcpf(1.0f + __expf(-gg[j])) * uu[j]; }
;                 u32x4 w; w.x = cvt_pk_bf16(o[0], o[1]); w.y = cvt_pk_bf16(o[2], o[3]); w.z = cvt_pk_bf16(o[4], o[5]); w.w = cvt_pk_bf16(o[6], o[7]);
;                 *(u32x4*)(act + row * FF_ + (u.pn * 4 + wc) * 32 + 8 * fq) = w; }
	v_mul_f32_e32 v151, 0xbfb8aa3b, v86
	v_mul_f32_e32 v147, 0xbfb8aa3b, v117
	v_mul_f32_e32 v155, v80, v150
	v_add_f32_e32 v150, 1.0, v152
	v_exp_f32_e32 v151, v151
	v_mul_f32_e32 v152, 0xbfb8aa3b, v87
	v_exp_f32_e32 v147, v147
	v_exp_f32_e32 v152, v152
	v_add_f32_e32 v146, 1.0, v146
	v_rcp_f32_e32 v150, v150
	v_add_f32_e32 v151, 1.0, v151
	v_rcp_f32_e32 v146, v146
	v_add_f32_e32 v147, 1.0, v147
	v_rcp_f32_e32 v151, v151
	v_add_f32_e32 v152, 1.0, v152
	v_rcp_f32_e32 v147, v147
	v_rcp_f32_e32 v152, v152
	v_mul_f32_e32 v150, v85, v150
	v_mul_f32_e32 v146, v116, v146
	v_mul_f32_e32 v156, v81, v150
	v_mul_f32_e32 v150, v86, v151
	v_mul_f32_e32 v146, v112, v146
	v_mul_f32_e32 v147, v117, v147
	v_mul_f32_e32 v157, v82, v150
	v_mul_f32_e32 v150, v87, v152
	v_mul_f32_e32 v147, v113, v147
	v_mul_f32_e32 v158, v83, v150
	v_cvt_pk_bf16_f32 v150, v146, v147
	v_mul_f32_e32 v146, 0xbfb8aa3b, v108
	v_cvt_pk_bf16_f32 v151, v153, v154
	v_exp_f32_e32 v154, v146
	v_mul_f32_e32 v146, 0xbfb8aa3b, v109
	s_mov_b32 s9, 0x2c000
	v_cvt_pk_bf16_f32 v152, v155, v156
	v_exp_f32_e32 v155, v146
	v_add_co_u32_e32 v146, vcc, s9, v144
	v_cvt_pk_bf16_f32 v153, v157, v158
	v_add_f32_e32 v154, 1.0, v154
	s_nop 0
	v_addc_co_u32_e32 v147, vcc, 0, v145, vcc
	global_store_dwordx4 v[146:147], v[150:153], off
	v_rcp_f32_e32 v154, v154
	v_add_f32_e32 v155, 1.0, v155
	v_mul_f32_e32 v150, 0xbfb8aa3b, v110
	v_exp_f32_e32 v150, v150
	v_mul_f32_e32 v151, 0xbfb8aa3b, v111
	v_exp_f32_e32 v151, v151
	v_mul_f32_e32 v152, 0xbfb8aa3b, v76
	v_add_f32_e32 v150, 1.0, v150
	v_rcp_f32_e32 v150, v150
	v_add_f32_e32 v151, 1.0, v151
	v_rcp_f32_e32 v151, v151
	v_exp_f32_e32 v152, v152
	v_mul_f32_e32 v150, v110, v150
	v_mul_f32_e32 v153, v106, v150
	v_mul_f32_e32 v150, v111, v151
	v_add_f32_e32 v151, 1.0, v152
	v_rcp_f32_e32 v151, v151
	v_mul_f32_e32 v152, 0xbfb8aa3b, v77
	v_rcp_f32_e32 v155, v155
	v_exp_f32_e32 v152, v152
	v_mul_f32_e32 v146, v108, v154
	v_mul_f32_e32 v154, v107, v150
	v_mul_f32_e32 v150, v76, v151
	v_mul_f32_e32 v151, 0xbfb8aa3b, v78
	v_mul_f32_e32 v147, v109, v155
	v_mul_f32_e32 v155, v72, v150
	v_add_f32_e32 v150, 1.0, v152
	v_exp_f32_e32 v151, v151
	v_mul_f32_e32 v152, 0xbfb8aa3b, v79
	v_exp_f32_e32 v152, v152
	v_rcp_f32_e32 v150, v150
	v_add_f32_e32 v151, 1.0, v151
	v_rcp_f32_e32 v151, v151
	v_add_f32_e32 v152, 1.0, v152
	v_rcp_f32_e32 v152, v152
	v_mul_f32_e32 v150, v77, v150
	v_mul_f32_e32 v156, v73, v150
	v_mul_f32_e32 v150, v78, v151
	v_mul_f32_e32 v146, v104, v146
	v_mul_f32_e32 v157, v74, v150
	v_mul_f32_e32 v150, v79, v152
	v_mul_f32_e32 v147, v105, v147
	v_mul_f32_e32 v158, v75, v150
	v_cvt_pk_bf16_f32 v150, v146, v147
	v_mul_f32_e32 v146, 0xbfb8aa3b, v100
	v_cvt_pk_bf16_f32 v151, v153, v154
	v_exp_f32_e32 v154, v146
	v_mul_f32_e32 v146, 0xbfb8aa3b, v101
	s_mov_b32 s9, 0x58000
	v_cvt_pk_bf16_f32 v152, v155, v156
	v_exp_f32_e32 v155, v146
	v_add_co_u32_e32 v146, vcc, s9, v144
	v_cvt_pk_bf16_f32 v153, v157, v158
	v_add_f32_e32 v154, 1.0, v154
	s_nop 0
	v_addc_co_u32_e32 v147, vcc, 0, v145, vcc
	global_store_dwordx4 v[146:147], v[150:153], off
	v_rcp_f32_e32 v154, v154
	v_add_f32_e32 v155, 1.0, v155
	v_mul_f32_e32 v150, 0xbfb8aa3b, v102
	v_exp_f32_e32 v150, v150
	v_mul_f32_e32 v151, 0xbfb8aa3b, v103
	v_exp_f32_e32 v151, v151
	v_mul_f32_e32 v152, 0xbfb8aa3b, v68
	v_add_f32_e32 v150, 1.0, v150
	v_rcp_f32_e32 v150, v150
	v_add_f32_e32 v151, 1.0, v151
	v_rcp_f32_e32 v151, v151
	v_exp_f32_e32 v152, v152
	v_mul_f32_e32 v150, v102, v150
	v_mul_f32_e32 v153, v98, v150
	v_mul_f32_e32 v150, v103, v151
	v_add_f32_e32 v151, 1.0, v152
	v_rcp_f32_e32 v151, v151
	v_mul_f32_e32 v152, 0xbfb8aa3b, v69
	v_rcp_f32_e32 v155, v155
	v_exp_f32_e32 v152, v152
	v_mul_f32_e32 v146, v100, v154
	v_mul_f32_e32 v154, v99, v150
	v_mul_f32_e32 v150, v68, v151
	v_mul_f32_e32 v151, 0xbfb8aa3b, v70
	v_mul_f32_e32 v147, v101, v155
	v_mul_f32_e32 v155, v64, v150
	v_add_f32_e32 v150, 1.0, v152
	v_exp_f32_e32 v151, v151
	v_mul_f32_e32 v152, 0xbfb8aa3b, v71
	v_exp_f32_e32 v152, v152
	v_rcp_f32_e32 v150, v150
	v_add_f32_e32 v151, 1.0, v151
	v_rcp_f32_e32 v151, v151
	v_add_f32_e32 v152, 1.0, v152
	v_rcp_f32_e32 v152, v152
	v_mul_f32_e32 v150, v69, v150
	v_mul_f32_e32 v156, v65, v150
	v_mul_f32_e32 v150, v70, v151
	v_mul_f32_e32 v146, v96, v146
	v_mul_f32_e32 v157, v66, v150
	v_mul_f32_e32 v150, v71, v152
	v_mul_f32_e32 v147, v97, v147
	v_mul_f32_e32 v158, v67, v150
	v_cvt_pk_bf16_f32 v150, v146, v147
	v_mul_f32_e32 v146, 0xbfb8aa3b, v60
	v_cvt_pk_bf16_f32 v151, v153, v154
	v_exp_f32_e32 v154, v146
	v_mul_f32_e32 v146, 0xbfb8aa3b, v61
	s_mov_b32 s9, 0x84000
	v_cvt_pk_bf16_f32 v152, v155, v156
	v_exp_f32_e32 v155, v146
	v_add_co_u32_e32 v146, vcc, s9, v144
	v_cvt_pk_bf16_f32 v153, v157, v158
	v_add_f32_e32 v154, 1.0, v154
	s_nop 0
	v_addc_co_u32_e32 v147, vcc, 0, v145, vcc
	global_store_dwordx4 v[146:147], v[150:153], off
	v_rcp_f32_e32 v154, v154
	v_add_f32_e32 v155, 1.0, v155
	v_mul_f32_e32 v150, 0xbfb8aa3b, v62
	v_exp_f32_e32 v150, v150
	v_mul_f32_e32 v151, 0xbfb8aa3b, v63
	v_exp_f32_e32 v151, v151
	v_mul_f32_e32 v152, 0xbfb8aa3b, v28
	v_add_f32_e32 v150, 1.0, v150
	v_rcp_f32_e32 v150, v150
	v_add_f32_e32 v151, 1.0, v151
	v_rcp_f32_e32 v151, v151
	v_exp_f32_e32 v152, v152
	v_mul_f32_e32 v150, v62, v150
	v_mul_f32_e32 v153, v58, v150
	v_mul_f32_e32 v150, v63, v151
	v_add_f32_e32 v151, 1.0, v152
	v_rcp_f32_e32 v151, v151
	v_mul_f32_e32 v152, 0xbfb8aa3b, v29
	v_rcp_f32_e32 v155, v155
	v_exp_f32_e32 v152, v152
	v_mul_f32_e32 v146, v60, v154
	v_mul_f32_e32 v154, v59, v150
	v_mul_f32_e32 v150, v28, v151
	v_mul_f32_e32 v151, 0xbfb8aa3b, v30
	v_mul_f32_e32 v147, v61, v155
	v_mul_f32_e32 v155, v24, v150
	v_add_f32_e32 v150, 1.0, v152
; __device__ __forceinline__ unsigned cvt_pk_bf16(float lo, float hi) { unsigned r; asm volatile("v_cvt_pk_bf16_f32 %0, %1, %2" : "=v"(r) : "v"(lo), "v"(hi)); return r; }
; template <class Epi>
; __device__ __forceinline__ void gemm_phase(LAS unsigned char* lds, const Gemm g, const Sched& S, const Epi& E) {
;     ...
;         if (!has_next) break;
; #pragma unroll
;         for (int a = 0; a < 2; ++a)
; #pragma unroll
;             for (int b = 0; b < 2; ++b)
; #pragma unroll
;                 for (int m = 0; m < 4; ++m)
; #pragma unroll
;                     for (int n = 0; n < 2; ++n) acc[a][b][m][n] = (f32x4){0.f, 0.f, 0.f, 0.f};
;         cur = nxt; cA = nA; cB = nB; ++ui;
;     __device__ __forceinline__ void operator()(AccRef acc, const Unit& u, int wr, int wc, int fr, int fq) const {
; #pragma unroll
;         for (int ai = 0; ai < 2; ++ai)
; #pragma unroll
;             for (int m = 0; m < 4; ++m) { const size_t row = (size_t)u.pm * 256 + ai * 128 + wr * 64 + m * 16 + fr; float o[8];
; #pragma unroll
;                 for (int bj = 0; bj < 2; ++bj) { const f32x4 gg = acc[ai][bj][m][0], uu = acc[ai][bj][m][1];
; #pragma unroll
;                     for (int j = 0; j < 4; ++j) o[4 * bj + j] = gg[j] * __builtin_amdgcn_rcpf(1.0f + __expf(-gg[j])) * uu[j]; }
;                 u32x4 w; w.x = cvt_pk_bf16(o[0], o[1]); w.y = cvt_pk_bf16(o[2], o[3]); w.z = cvt_pk_bf16(o[4], o[5]); w.w = cvt_pk_bf16(o[6], o[7]);
;                 *(u32x4*)(act + row * FF_ + (u.pn * 4 + wc) * 32 + 8 * fq) = w; }
	v_exp_f32_e32 v151, v151
	v_mul_f32_e32 v152, 0xbfb8aa3b, v31
	v_exp_f32_e32 v152, v152
	v_rcp_f32_e32 v150, v150
	v_add_f32_e32 v151, 1.0, v151
	v_rcp_f32_e32 v151, v151
	v_add_f32_e32 v152, 1.0, v152
	v_rcp_f32_e32 v152, v152
	v_mul_f32_e32 v150, v29, v150
	v_mul_f32_e32 v156, v25, v150
	v_mul_f32_e32 v150, v30, v151
	v_mul_f32_e32 v146, v56, v146
	v_mul_f32_e32 v157, v26, v150
	v_mul_f32_e32 v150, v31, v152
	v_mul_f32_e32 v147, v57, v147
	v_mul_f32_e32 v158, v27, v150
	v_cvt_pk_bf16_f32 v150, v146, v147
	v_mul_f32_e32 v146, 0xbfb8aa3b, v52
	v_cvt_pk_bf16_f32 v151, v153, v154
	v_exp_f32_e32 v154, v146
	v_mul_f32_e32 v146, 0xbfb8aa3b, v53
	s_mov_b32 s9, 0x160000
	v_cvt_pk_bf16_f32 v152, v155, v156
	v_exp_f32_e32 v155, v146
	v_add_co_u32_e32 v146, vcc, s9, v144
	v_cvt_pk_bf16_f32 v153, v157, v158
	v_add_f32_e32 v154, 1.0, v154
	s_nop 0
	v_addc_co_u32_e32 v147, vcc, 0, v145, vcc
	global_store_dwordx4 v[146:147], v[150:153], off
	v_rcp_f32_e32 v154, v154
	v_add_f32_e32 v155, 1.0, v155
	v_mul_f32_e32 v150, 0xbfb8aa3b, v54
	v_exp_f32_e32 v150, v150
	v_mul_f32_e32 v151, 0xbfb8aa3b, v55
	v_exp_f32_e32 v151, v151
	v_mul_f32_e32 v152, 0xbfb8aa3b, v20
	v_add_f32_e32 v150, 1.0, v150
	v_rcp_f32_e32 v150, v150
	v_add_f32_e32 v151, 1.0, v151
	v_rcp_f32_e32 v151, v151
	v_exp_f32_e32 v152, v152
	v_mul_f32_e32 v150, v54, v150
	v_mul_f32_e32 v153, v50, v150
	v_mul_f32_e32 v150, v55, v151
	v_add_f32_e32 v151, 1.0, v152
	v_rcp_f32_e32 v151, v151
	v_mul_f32_e32 v152, 0xbfb8aa3b, v21
	v_rcp_f32_e32 v155, v155
	v_exp_f32_e32 v152, v152
	v_mul_f32_e32 v146, v52, v154
	v_mul_f32_e32 v154, v51, v150
	v_mul_f32_e32 v150, v20, v151
	v_mul_f32_e32 v151, 0xbfb8aa3b, v22
	v_mul_f32_e32 v147, v53, v155
	v_mul_f32_e32 v155, v16, v150
	v_add_f32_e32 v150, 1.0, v152
	v_exp_f32_e32 v151, v151
	v_mul_f32_e32 v152, 0xbfb8aa3b, v23
	v_exp_f32_e32 v152, v152
	v_rcp_f32_e32 v150, v150
	v_add_f32_e32 v151, 1.0, v151
	v_rcp_f32_e32 v151, v151
	v_add_f32_e32 v152, 1.0, v152
	v_rcp_f32_e32 v152, v152
	v_mul_f32_e32 v150, v21, v150
	v_mul_f32_e32 v156, v17, v150
	v_mul_f32_e32 v150, v22, v151
	v_mul_f32_e32 v146, v48, v146
	v_mul_f32_e32 v157, v18, v150
	v_mul_f32_e32 v150, v23, v152
	v_mul_f32_e32 v147, v49, v147
	v_mul_f32_e32 v158, v19, v150
	v_cvt_pk_bf16_f32 v150, v146, v147
	v_mul_f32_e32 v146, 0xbfb8aa3b, v44
	v_cvt_pk_bf16_f32 v151, v153, v154
	v_exp_f32_e32 v154, v146
	v_mul_f32_e32 v146, 0xbfb8aa3b, v45
	s_mov_b32 s9, 0x18c000
	v_cvt_pk_bf16_f32 v152, v155, v156
	v_exp_f32_e32 v155, v146
	v_add_co_u32_e32 v146, vcc, s9, v144
	v_cvt_pk_bf16_f32 v153, v157, v158
	v_add_f32_e32 v154, 1.0, v154
	s_nop 0
	v_addc_co_u32_e32 v147, vcc, 0, v145, vcc
	global_store_dwordx4 v[146:147], v[150:153], off
	v_rcp_f32_e32 v154, v154
	v_add_f32_e32 v155, 1.0, v155
	v_mul_f32_e32 v150, 0xbfb8aa3b, v46
	v_exp_f32_e32 v150, v150
	v_mul_f32_e32 v151, 0xbfb8aa3b, v47
	v_exp_f32_e32 v151, v151
	v_mul_f32_e32 v152, 0xbfb8aa3b, v12
	v_add_f32_e32 v150, 1.0, v150
	v_rcp_f32_e32 v150, v150
	v_add_f32_e32 v151, 1.0, v151
	v_rcp_f32_e32 v151, v151
	v_exp_f32_e32 v152, v152
	v_mul_f32_e32 v150, v46, v150
	v_mul_f32_e32 v153, v42, v150
	v_mul_f32_e32 v150, v47, v151
	v_add_f32_e32 v151, 1.0, v152
	v_rcp_f32_e32 v151, v151
	v_mul_f32_e32 v152, 0xbfb8aa3b, v13
	v_rcp_f32_e32 v155, v155
	v_exp_f32_e32 v152, v152
	v_mul_f32_e32 v146, v44, v154
	v_mul_f32_e32 v154, v43, v150
	v_mul_f32_e32 v150, v12, v151
	v_mul_f32_e32 v151, 0xbfb8aa3b, v14
	v_mul_f32_e32 v147, v45, v155
	v_mul_f32_e32 v155, v8, v150
	v_add_f32_e32 v150, 1.0, v152
	v_exp_f32_e32 v151, v151
	v_mul_f32_e32 v152, 0xbfb8aa3b, v15
	v_exp_f32_e32 v152, v152
	v_rcp_f32_e32 v150, v150
	v_add_f32_e32 v151, 1.0, v151
	v_rcp_f32_e32 v151, v151
	v_add_f32_e32 v152, 1.0, v152
	v_rcp_f32_e32 v152, v152
	v_mul_f32_e32 v150, v13, v150
	v_mul_f32_e32 v156, v9, v150
	v_mul_f32_e32 v150, v14, v151
	v_mul_f32_e32 v146, v40, v146
	v_mul_f32_e32 v157, v10, v150
	v_mul_f32_e32 v150, v15, v152
	v_mul_f32_e32 v147, v41, v147
	v_mul_f32_e32 v158, v11, v150
	v_cvt_pk_bf16_f32 v150, v146, v147
	v_mul_f32_e32 v146, 0xbfb8aa3b, v36
	v_cvt_pk_bf16_f32 v151, v153, v154
	v_exp_f32_e32 v154, v146
	v_mul_f32_e32 v146, 0xbfb8aa3b, v37
	v_cvt_pk_bf16_f32 v152, v155, v156
	v_exp_f32_e32 v155, v146
	v_add_co_u32_e32 v146, vcc, s65, v144
	v_cvt_pk_bf16_f32 v153, v157, v158
	v_add_f32_e32 v154, 1.0, v154
	s_nop 0
	v_addc_co_u32_e32 v147, vcc, 0, v145, vcc
	global_store_dwordx4 v[146:147], v[150:153], off
	v_rcp_f32_e32 v154, v154
	v_add_f32_e32 v155, 1.0, v155
	v_mul_f32_e32 v150, 0xbfb8aa3b, v38
	v_exp_f32_e32 v150, v150
	v_mul_f32_e32 v151, 0xbfb8aa3b, v39
	v_exp_f32_e32 v151, v151
	v_mul_f32_e32 v152, 0xbfb8aa3b, v4
	v_add_f32_e32 v150, 1.0, v150
	v_rcp_f32_e32 v150, v150
	v_add_f32_e32 v151, 1.0, v151
	v_rcp_f32_e32 v151, v151
	v_exp_f32_e32 v152, v152
	v_mul_f32_e32 v150, v38, v150
	v_mul_f32_e32 v153, v34, v150
	v_mul_f32_e32 v150, v39, v151
	v_add_f32_e32 v151, 1.0, v152
	v_rcp_f32_e32 v151, v151
	v_mul_f32_e32 v152, 0xbfb8aa3b, v5
	v_rcp_f32_e32 v155, v155
	v_exp_f32_e32 v152, v152
	v_mul_f32_e32 v146, v36, v154
	v_mul_f32_e32 v154, v35, v150
	v_mul_f32_e32 v150, v4, v151
	v_mul_f32_e32 v151, 0xbfb8aa3b, v6
	v_mul_f32_e32 v147, v37, v155
	v_mul_f32_e32 v155, v0, v150
	v_add_f32_e32 v150, 1.0, v152
	v_exp_f32_e32 v151, v151
	v_mul_f32_e32 v152, 0xbfb8aa3b, v7
	v_exp_f32_e32 v152, v152
	v_rcp_f32_e32 v150, v150
	v_add_f32_e32 v151, 1.0, v151
	v_rcp_f32_e32 v151, v151
	v_add_f32_e32 v152, 1.0, v152
	v_rcp_f32_e32 v152, v152
	v_mul_f32_e32 v150, v5, v150
	v_add_co_u32_e32 v144, vcc, 0x1e4000, v144
	v_mul_f32_e32 v156, v1, v150
	v_mul_f32_e32 v150, v6, v151
	v_addc_co_u32_e32 v145, vcc, 0, v145, vcc
	v_mul_f32_e32 v157, v2, v150
	v_mul_f32_e32 v150, v7, v152
	s_andn2_b64 vcc, exec, s[6:7]
	v_mul_f32_e32 v146, v32, v146
	v_mul_f32_e32 v147, v33, v147
	v_mul_f32_e32 v158, v3, v150
	v_cvt_pk_bf16_f32 v150, v146, v147
	v_cvt_pk_bf16_f32 v151, v153, v154
	v_cvt_pk_bf16_f32 v152, v155, v156
	v_cvt_pk_bf16_f32 v153, v157, v158
	global_store_dwordx4 v[144:145], v[150:153], off
	s_cbranch_vccz .LBB0_173
	s_mov_b64 s[20:21], s[24:25]
	s_andn2_b64 vcc, exec, s[4:5]
	s_mov_b64 s[24:25], s[20:21]
	s_cbranch_vccnz .LBB0_174

; #define PG8_STAGE(bufoff, gbase, voff) do { _Pragma("unroll") for (int _i = 0; _i < 2; ++_i) \
;         __builtin_amdgcn_global_load_lds((const unsigned*)((const char*)(gbase) + (voff)[_i]), (LAS unsigned*)(lds + (bufoff) + ldsw + _i * 8192), 16, 0, 0); } while (0)
; #define PG8_LDA(dst, b, h) do { _Pragma("unroll") for (int m = 0; m < 4; ++m) _Pragma("unroll") for (int k = 0; k < 2; ++k) dst[m][k] = *(const LAS bf16x8*)(lds + PG8_SA(b, h) + aoff + m * 2048 + k * 1024); } while (0)
; #define PG8_LDB(dst, b, h) do { _Pragma("unroll") for (int n = 0; n < 2; ++n) _Pragma("unroll") for (int k = 0; k < 2; ++k) dst[n][k] = *(const LAS bf16x8*)(lds + PG8_SB(b, h) + boff + n * 2048 + k * 1024); } while (0)
; #define PG8_MMA(ai, bj, At, Bt) do { __builtin_amdgcn_s_setprio(1); _Pragma("unroll") for (int m = 0; m < 4; ++m) _Pragma("unroll") for (int n = 0; n < 2; ++n) _Pragma("unroll") for (int k = 0; k < 2; ++k) \
;         acc[ai][bj][m][n] = __builtin_amdgcn_mfma_f32_16x16x32_bf16(Bt[n][k], At[m][k], acc[ai][bj][m][n], 0, 0, 0); __builtin_amdgcn_s_setprio(0); } while (0)
; #define PG8_WAIT_L(n) asm volatile("s_waitcnt lgkmcnt(" #n ")" ::: "memory")
; #define PG8_BAR __builtin_amdgcn_s_barrier()
; #define PG8_SCHED __builtin_amdgcn_sched_barrier(0)
; template <class Epi>
; __device__ __forceinline__ void gemm_phase(LAS unsigned char* lds, const Gemm g, const Sched& S, const Epi& E) {
;     ...
;             PG8_LDB(B0, 0, 0); PG8_SCHED; PG8_LDA(At, 0, 0); PG8_STAGE(PG8_SA(1, 1), a1 + hstepA, voffA);
;             PG8_WAIT_L(8); PG8_BAR; PG8_WAIT_L(0); PG8_MMA(0, 0, At, B0); PG8_BAR; PG8_SCHED;
;             PG8_LDB(B1, 0, 1); PG8_STAGE(PG8_SB(0, 0), b2, voffB);
;             PG8_BAR; PG8_WAIT_L(0); PG8_MMA(0, 1, At, B1); PG8_BAR;
;             PG8_LDA(At, 0, 1); PG8_STAGE(PG8_SA(0, 0), a2, voffA);
;             PG8_BAR; PG8_WAIT_L(0); PG8_MMA(1, 0, At, B0); PG8_BAR; PG8_SCHED;
.LBB0_255:
	v_add_u32_e32 v160, s55, v146
	s_add_u32 s22, s14, s20
	ds_read_b128 v[148:151], v160
	ds_read_b128 v[152:155], v160 offset:1024
	ds_read_b128 v[156:159], v160 offset:2048
	ds_read_b128 v[160:163], v160 offset:3072
	s_addc_u32 s23, s15, s21
	s_add_u32 s22, s22, 0x100
	s_addc_u32 s23, s23, 0
	s_add_u32 s70, s11, s20
	s_addc_u32 s71, s51, s21
	s_cmpk_eq_i32 s20, 0x2b00
	s_cselect_b32 s25, s19, s23
	s_cselect_b32 s24, s18, s22
	s_cselect_b32 s23, s9, s71
	s_cselect_b32 s22, s8, s70
	v_lshl_add_u64 v[198:199], v[142:143], 0, s[20:21]
	s_add_i32 m0, s34, 0xc000
	ds_read_b128 v[164:167], v147
	ds_read_b128 v[168:171], v147 offset:1024
	ds_read_b128 v[172:175], v147 offset:2048
	ds_read_b128 v[176:179], v147 offset:3072
	ds_read_b128 v[180:183], v147 offset:4096
	ds_read_b128 v[184:187], v147 offset:5120
	ds_read_b128 v[188:191], v147 offset:6144
	ds_read_b128 v[194:197], v147 offset:7168
	global_load_lds_dwordx4 v[198:199], off
	v_lshl_add_u64 v[198:199], v[144:145], 0, s[20:21]
	s_add_i32 m0, s34, 0xe000
	s_nop 0
	global_load_lds_dwordx4 v[198:199], off
	s_waitcnt lgkmcnt(8)
	s_barrier
	s_waitcnt lgkmcnt(0)
	s_setprio 1
	s_waitcnt lgkmcnt(0)
	v_mfma_f32_16x16x32_bf16 v[124:127], v[148:151], v[164:167], v[124:127]
	v_mfma_f32_16x16x32_bf16 v[120:123], v[156:159], v[164:167], v[120:123]
	v_mfma_f32_16x16x32_bf16 v[116:119], v[148:151], v[172:175], v[116:119]
	v_mfma_f32_16x16x32_bf16 v[112:115], v[156:159], v[172:175], v[112:115]
	v_mfma_f32_16x16x32_bf16 v[108:111], v[148:151], v[180:183], v[108:111]
	v_mfma_f32_16x16x32_bf16 v[104:107], v[156:159], v[180:183], v[104:107]
	v_mfma_f32_16x16x32_bf16 v[100:103], v[148:151], v[188:191], v[100:103]
	v_mfma_f32_16x16x32_bf16 v[96:99], v[156:159], v[188:191], v[96:99]
	v_mfma_f32_16x16x32_bf16 v[124:127], v[152:155], v[168:171], v[124:127]
	v_mfma_f32_16x16x32_bf16 v[120:123], v[160:163], v[168:171], v[120:123]
	v_mfma_f32_16x16x32_bf16 v[116:119], v[152:155], v[176:179], v[116:119]
	v_mfma_f32_16x16x32_bf16 v[112:115], v[160:163], v[176:179], v[112:115]
	v_mfma_f32_16x16x32_bf16 v[108:111], v[152:155], v[184:187], v[108:111]
	v_mfma_f32_16x16x32_bf16 v[104:107], v[160:163], v[184:187], v[104:107]
	v_mfma_f32_16x16x32_bf16 v[100:103], v[152:155], v[194:197], v[100:103]
	s_barrier
	v_mfma_f32_16x16x32_bf16 v[96:99], v[160:163], v[194:197], v[96:99]
	s_setprio 0
	s_add_i32 s70, s55, s1
	v_add_u32_e32 v210, s56, v146
	v_lshl_add_u64 v[214:215], s[22:23], 0, v[128:129]
	s_mov_b32 m0, s70
	ds_read_b128 v[198:201], v210
	ds_read_b128 v[202:205], v210 offset:1024
	ds_read_b128 v[206:209], v210 offset:2048
	ds_read_b128 v[210:213], v210 offset:3072
	global_load_lds_dwordx4 v[214:215], off
	v_lshl_add_u64 v[216:217], s[22:23], 0, v[130:131]
	s_add_i32 m0, s70, 0x2000
	s_nop 0
	global_load_lds_dwordx4 v[216:217], off
	s_barrier
	s_waitcnt lgkmcnt(0)
	s_setprio 1
	s_waitcnt lgkmcnt(0)
	v_mfma_f32_16x16x32_bf16 v[92:95], v[198:201], v[164:167], v[92:95]
	v_mfma_f32_16x16x32_bf16 v[88:91], v[206:209], v[164:167], v[88:91]
	v_mfma_f32_16x16x32_bf16 v[84:87], v[198:201], v[172:175], v[84:87]
	v_mfma_f32_16x16x32_bf16 v[80:83], v[206:209], v[172:175], v[80:83]
	v_mfma_f32_16x16x32_bf16 v[76:79], v[198:201], v[180:183], v[76:79]
	v_mfma_f32_16x16x32_bf16 v[72:75], v[206:209], v[180:183], v[72:75]
	v_mfma_f32_16x16x32_bf16 v[68:71], v[198:201], v[188:191], v[68:71]
	v_mfma_f32_16x16x32_bf16 v[64:67], v[206:209], v[188:191], v[64:67]
	v_mfma_f32_16x16x32_bf16 v[92:95], v[202:205], v[168:171], v[92:95]
	v_mfma_f32_16x16x32_bf16 v[88:91], v[210:213], v[168:171], v[88:91]
	v_mfma_f32_16x16x32_bf16 v[84:87], v[202:205], v[176:179], v[84:87]
	v_mfma_f32_16x16x32_bf16 v[80:83], v[210:213], v[176:179], v[80:83]
	v_mfma_f32_16x16x32_bf16 v[76:79], v[202:205], v[184:187], v[76:79]
	v_mfma_f32_16x16x32_bf16 v[72:75], v[210:213], v[184:187], v[72:75]
	v_mfma_f32_16x16x32_bf16 v[68:71], v[202:205], v[194:197], v[68:71]
	s_barrier
	v_mfma_f32_16x16x32_bf16 v[64:67], v[210:213], v[194:197], v[64:67]
	s_setprio 0
	s_mov_b32 m0, s34
	v_lshl_add_u64 v[218:219], s[24:25], 0, v[128:129]
	ds_read_b128 v[164:167], v147 offset:16384
	ds_read_b128 v[168:171], v147 offset:17408
	ds_read_b128 v[172:175], v147 offset:18432
	ds_read_b128 v[176:179], v147 offset:19456
	ds_read_b128 v[180:183], v147 offset:20480
	ds_read_b128 v[184:187], v147 offset:21504
	ds_read_b128 v[188:191], v147 offset:22528
	ds_read_b128 v[194:197], v147 offset:23552
	global_load_lds_dwordx4 v[218:219], off
	v_lshl_add_u64 v[220:221], s[24:25], 0, v[130:131]
	s_mov_b32 m0, s35
	s_nop 0
	global_load_lds_dwordx4 v[220:221], off
	s_barrier
	s_waitcnt lgkmcnt(0)
	s_setprio 1
	s_waitcnt lgkmcnt(0)
	v_mfma_f32_16x16x32_bf16 v[60:63], v[148:151], v[164:167], v[60:63]
	v_mfma_f32_16x16x32_bf16 v[56:59], v[156:159], v[164:167], v[56:59]
	v_mfma_f32_16x16x32_bf16 v[52:55], v[148:151], v[172:175], v[52:55]
	v_mfma_f32_16x16x32_bf16 v[48:51], v[156:159], v[172:175], v[48:51]
	v_mfma_f32_16x16x32_bf16 v[44:47], v[148:151], v[180:183], v[44:47]
	v_mfma_f32_16x16x32_bf16 v[40:43], v[156:159], v[180:183], v[40:43]
	v_mfma_f32_16x16x32_bf16 v[36:39], v[148:151], v[188:191], v[36:39]
	v_mfma_f32_16x16x32_bf16 v[32:35], v[156:159], v[188:191], v[32:35]
	v_mfma_f32_16x16x32_bf16 v[60:63], v[152:155], v[168:171], v[60:63]
	v_mfma_f32_16x16x32_bf16 v[56:59], v[160:163], v[168:171], v[56:59]
	v_mfma_f32_16x16x32_bf16 v[52:55], v[152:155], v[176:179], v[52:55]
	v_mfma_f32_16x16x32_bf16 v[48:51], v[160:163], v[176:179], v[48:51]
	v_mfma_f32_16x16x32_bf16 v[44:47], v[152:155], v[184:187], v[44:47]
	v_mfma_f32_16x16x32_bf16 v[40:43], v[160:163], v[184:187], v[40:43]
	v_mfma_f32_16x16x32_bf16 v[36:39], v[152:155], v[194:197], v[36:39]
	s_barrier
; #define PG8_STAGE(bufoff, gbase, voff) do { _Pragma("unroll") for (int _i = 0; _i < 2; ++_i) \
;         __builtin_amdgcn_global_load_lds((const unsigned*)((const char*)(gbase) + (voff)[_i]), (LAS unsigned*)(lds + (bufoff) + ldsw + _i * 8192), 16, 0, 0); } while (0)
; #define PG8_LDA(dst, b, h) do { _Pragma("unroll") for (int m = 0; m < 4; ++m) _Pragma("unroll") for (int k = 0; k < 2; ++k) dst[m][k] = *(const LAS bf16x8*)(lds + PG8_SA(b, h) + aoff + m * 2048 + k * 1024); } while (0)
; #define PG8_LDB(dst, b, h) do { _Pragma("unroll") for (int n = 0; n < 2; ++n) _Pragma("unroll") for (int k = 0; k < 2; ++k) dst[n][k] = *(const LAS bf16x8*)(lds + PG8_SB(b, h) + boff + n * 2048 + k * 1024); } while (0)
; #define PG8_MMA(ai, bj, At, Bt) do { __builtin_amdgcn_s_setprio(1); _Pragma("unroll") for (int m = 0; m < 4; ++m) _Pragma("unroll") for (int n = 0; n < 2; ++n) _Pragma("unroll") for (int k = 0; k < 2; ++k) \
;         acc[ai][bj][m][n] = __builtin_amdgcn_mfma_f32_16x16x32_bf16(Bt[n][k], At[m][k], acc[ai][bj][m][n], 0, 0, 0); __builtin_amdgcn_s_setprio(0); } while (0)
; #define PG8_WAIT_V(n) asm volatile("s_waitcnt vmcnt(" #n ")" ::: "memory")
; #define PG8_WAIT_L(n) asm volatile("s_waitcnt lgkmcnt(" #n ")" ::: "memory")
; #define PG8_BAR __builtin_amdgcn_s_barrier()
; #define PG8_SCHED __builtin_amdgcn_sched_barrier(0)
; template <class Epi>
; __device__ __forceinline__ void gemm_phase(LAS unsigned char* lds, const Gemm g, const Sched& S, const Epi& E) {
;     ...
;             PG8_STAGE(PG8_SB(0, 1), b2 + hstepB, voffB);
;             PG8_WAIT_V(6); PG8_BAR; PG8_MMA(1, 1, At, B1); PG8_BAR;
;             PG8_LDB(B0, 1, 0); PG8_SCHED; PG8_LDA(At, 1, 0); PG8_STAGE(PG8_SA(0, 1), a2 + hstepA, voffA);
;             PG8_WAIT_L(8); PG8_BAR; PG8_WAIT_L(0); PG8_MMA(0, 0, At, B0); PG8_BAR; PG8_SCHED;
;             PG8_LDB(B1, 1, 1); PG8_STAGE(PG8_SB(1, 0), b3, voffB);
;             PG8_BAR; PG8_WAIT_L(0); PG8_MMA(0, 1, At, B1); PG8_BAR;
;             PG8_LDA(At, 1, 1); PG8_STAGE(PG8_SA(1, 0), a3, voffA);
;             PG8_BAR; PG8_WAIT_L(0); PG8_MMA(1, 0, At, B0); PG8_BAR; PG8_SCHED;
	v_mfma_f32_16x16x32_bf16 v[32:35], v[160:163], v[194:197], v[32:35]
	s_setprio 0
	s_add_u32 s70, s22, 0x160000
	s_addc_u32 s71, s23, 0
	s_add_i32 s80, s56, s1
	v_lshl_add_u64 v[148:149], s[70:71], 0, v[128:129]
	s_mov_b32 m0, s80
	s_nop 0
	global_load_lds_dwordx4 v[148:149], off
	v_lshl_add_u64 v[148:149], s[70:71], 0, v[130:131]
	s_add_i32 m0, s80, 0x2000
	s_nop 0
	global_load_lds_dwordx4 v[148:149], off
	s_waitcnt vmcnt(6)
	s_barrier
	s_setprio 1
	v_mfma_f32_16x16x32_bf16 v[28:31], v[198:201], v[164:167], v[28:31]
	v_mfma_f32_16x16x32_bf16 v[24:27], v[206:209], v[164:167], v[24:27]
	v_mfma_f32_16x16x32_bf16 v[20:23], v[198:201], v[172:175], v[20:23]
	v_mfma_f32_16x16x32_bf16 v[16:19], v[206:209], v[172:175], v[16:19]
	v_mfma_f32_16x16x32_bf16 v[12:15], v[198:201], v[180:183], v[12:15]
	v_mfma_f32_16x16x32_bf16 v[8:11], v[206:209], v[180:183], v[8:11]
	v_mfma_f32_16x16x32_bf16 v[4:7], v[198:201], v[188:191], v[4:7]
	v_mfma_f32_16x16x32_bf16 v[0:3], v[206:209], v[188:191], v[0:3]
	v_mfma_f32_16x16x32_bf16 v[28:31], v[202:205], v[168:171], v[28:31]
	v_mfma_f32_16x16x32_bf16 v[24:27], v[210:213], v[168:171], v[24:27]
	v_mfma_f32_16x16x32_bf16 v[20:23], v[202:205], v[176:179], v[20:23]
	v_mfma_f32_16x16x32_bf16 v[16:19], v[210:213], v[176:179], v[16:19]
	v_mfma_f32_16x16x32_bf16 v[12:15], v[202:205], v[184:187], v[12:15]
	v_mfma_f32_16x16x32_bf16 v[8:11], v[210:213], v[184:187], v[8:11]
	v_mfma_f32_16x16x32_bf16 v[4:7], v[202:205], v[194:197], v[4:7]
	s_barrier
	v_mfma_f32_16x16x32_bf16 v[0:3], v[210:213], v[194:197], v[0:3]
	s_setprio 0
	s_add_i32 s70, 0, 0x18000
	v_add_u32_e32 v160, s70, v146
	ds_read_b128 v[148:151], v160
	ds_read_b128 v[152:155], v160 offset:1024
	ds_read_b128 v[156:159], v160 offset:2048
	ds_read_b128 v[160:163], v160 offset:3072
	s_add_u32 s24, s24, 0x160000
	s_addc_u32 s25, s25, 0
	s_mov_b32 m0, s38
	v_lshl_add_u64 v[198:199], s[24:25], 0, v[128:129]
	ds_read_b128 v[164:167], v147 offset:32768
	ds_read_b128 v[168:171], v147 offset:33792
	ds_read_b128 v[172:175], v147 offset:34816
	ds_read_b128 v[176:179], v147 offset:35840
	ds_read_b128 v[180:183], v147 offset:36864
	ds_read_b128 v[184:187], v147 offset:37888
	ds_read_b128 v[188:191], v147 offset:38912
	ds_read_b128 v[194:197], v147 offset:39936
	global_load_lds_dwordx4 v[198:199], off
	v_lshl_add_u64 v[198:199], s[24:25], 0, v[130:131]
	s_mov_b32 m0, s39
	s_nop 0
	global_load_lds_dwordx4 v[198:199], off
	s_waitcnt lgkmcnt(8)
	s_barrier
	s_waitcnt lgkmcnt(0)
	s_setprio 1
	s_waitcnt lgkmcnt(0)
	v_mfma_f32_16x16x32_bf16 v[124:127], v[148:151], v[164:167], v[124:127]
	v_mfma_f32_16x16x32_bf16 v[120:123], v[156:159], v[164:167], v[120:123]
	v_mfma_f32_16x16x32_bf16 v[116:119], v[148:151], v[172:175], v[116:119]
	v_mfma_f32_16x16x32_bf16 v[112:115], v[156:159], v[172:175], v[112:115]
	v_mfma_f32_16x16x32_bf16 v[108:111], v[148:151], v[180:183], v[108:111]
	v_mfma_f32_16x16x32_bf16 v[104:107], v[156:159], v[180:183], v[104:107]
	v_mfma_f32_16x16x32_bf16 v[100:103], v[148:151], v[188:191], v[100:103]
	v_mfma_f32_16x16x32_bf16 v[96:99], v[156:159], v[188:191], v[96:99]
	v_mfma_f32_16x16x32_bf16 v[124:127], v[152:155], v[168:171], v[124:127]
	v_mfma_f32_16x16x32_bf16 v[120:123], v[160:163], v[168:171], v[120:123]
	v_mfma_f32_16x16x32_bf16 v[116:119], v[152:155], v[176:179], v[116:119]
	v_mfma_f32_16x16x32_bf16 v[112:115], v[160:163], v[176:179], v[112:115]
	v_mfma_f32_16x16x32_bf16 v[108:111], v[152:155], v[184:187], v[108:111]
	v_mfma_f32_16x16x32_bf16 v[104:107], v[160:163], v[184:187], v[104:107]
	v_mfma_f32_16x16x32_bf16 v[100:103], v[152:155], v[194:197], v[100:103]
	s_barrier
	v_mfma_f32_16x16x32_bf16 v[96:99], v[160:163], v[194:197], v[96:99]
	s_setprio 0
	s_add_i32 s24, 0, 0x1c000
	s_add_i32 s25, s70, s1
	v_add_u32_e32 v210, s24, v146
	v_lshl_add_u64 v[214:215], v[214:215], 0, s[16:17]
	s_mov_b32 m0, s25
	ds_read_b128 v[198:201], v210
	ds_read_b128 v[202:205], v210 offset:1024
	ds_read_b128 v[206:209], v210 offset:2048
	ds_read_b128 v[210:213], v210 offset:3072
	global_load_lds_dwordx4 v[214:215], off
	v_lshl_add_u64 v[214:215], v[216:217], 0, s[16:17]
	s_add_i32 m0, s25, 0x2000
	s_nop 0
	global_load_lds_dwordx4 v[214:215], off
	s_barrier
	s_waitcnt lgkmcnt(0)
	s_setprio 1
	s_waitcnt lgkmcnt(0)
	v_mfma_f32_16x16x32_bf16 v[92:95], v[198:201], v[164:167], v[92:95]
	v_mfma_f32_16x16x32_bf16 v[88:91], v[206:209], v[164:167], v[88:91]
	v_mfma_f32_16x16x32_bf16 v[84:87], v[198:201], v[172:175], v[84:87]
	v_mfma_f32_16x16x32_bf16 v[80:83], v[206:209], v[172:175], v[80:83]
	v_mfma_f32_16x16x32_bf16 v[76:79], v[198:201], v[180:183], v[76:79]
	v_mfma_f32_16x16x32_bf16 v[72:75], v[206:209], v[180:183], v[72:75]
	v_mfma_f32_16x16x32_bf16 v[68:71], v[198:201], v[188:191], v[68:71]
	v_mfma_f32_16x16x32_bf16 v[64:67], v[206:209], v[188:191], v[64:67]
	v_mfma_f32_16x16x32_bf16 v[92:95], v[202:205], v[168:171], v[92:95]
	v_mfma_f32_16x16x32_bf16 v[88:91], v[210:213], v[168:171], v[88:91]
	v_mfma_f32_16x16x32_bf16 v[84:87], v[202:205], v[176:179], v[84:87]
	v_mfma_f32_16x16x32_bf16 v[80:83], v[210:213], v[176:179], v[80:83]
	v_mfma_f32_16x16x32_bf16 v[76:79], v[202:205], v[184:187], v[76:79]
	v_mfma_f32_16x16x32_bf16 v[72:75], v[210:213], v[184:187], v[72:75]
	v_mfma_f32_16x16x32_bf16 v[68:71], v[202:205], v[194:197], v[68:71]
	s_barrier
	v_mfma_f32_16x16x32_bf16 v[64:67], v[210:213], v[194:197], v[64:67]
	s_setprio 0
	s_mov_b32 m0, s53
	v_lshl_add_u64 v[214:215], v[218:219], 0, s[16:17]
	ds_read_b128 v[164:167], v147 offset:49152
	ds_read_b128 v[168:171], v147 offset:50176
	ds_read_b128 v[172:175], v147 offset:51200
	ds_read_b128 v[176:179], v147 offset:52224
	ds_read_b128 v[180:183], v147 offset:53248
	ds_read_b128 v[184:187], v147 offset:54272
	ds_read_b128 v[188:191], v147 offset:55296
	ds_read_b128 v[194:197], v147 offset:56320
	global_load_lds_dwordx4 v[214:215], off
	v_lshl_add_u64 v[214:215], v[220:221], 0, s[16:17]
	s_mov_b32 m0, s54
	s_nop 0
	global_load_lds_dwordx4 v[214:215], off
	s_barrier
; #define PG8_STAGE(bufoff, gbase, voff) do { _Pragma("unroll") for (int _i = 0; _i < 2; ++_i) \
;         __builtin_amdgcn_global_load_lds((const unsigned*)((const char*)(gbase) + (voff)[_i]), (LAS unsigned*)(lds + (bufoff) + ldsw + _i * 8192), 16, 0, 0); } while (0)
; #define PG8_MMA(ai, bj, At, Bt) do { __builtin_amdgcn_s_setprio(1); _Pragma("unroll") for (int m = 0; m < 4; ++m) _Pragma("unroll") for (int n = 0; n < 2; ++n) _Pragma("unroll") for (int k = 0; k < 2; ++k) \
;         acc[ai][bj][m][n] = __builtin_amdgcn_mfma_f32_16x16x32_bf16(Bt[n][k], At[m][k], acc[ai][bj][m][n], 0, 0, 0); __builtin_amdgcn_s_setprio(0); } while (0)
; #define PG8_WAIT_V(n) asm volatile("s_waitcnt vmcnt(" #n ")" ::: "memory")
; #define PG8_WAIT_L(n) asm volatile("s_waitcnt lgkmcnt(" #n ")" ::: "memory")
; #define PG8_BAR __builtin_amdgcn_s_barrier()
; #define PG8_SCHED __builtin_amdgcn_sched_barrier(0)
; #define RES_LOAD(dst_, k_) do { _Pragma("unroll") for (int mm = 0; mm < 2; ++mm) _Pragma("unroll") for (int bj = 0; bj < 2; ++bj) _Pragma("unroll") for (int n = 0; n < 2; ++n) \
;             dst_[mm][bj][n] = *(const f32x4*)(xin + RES_OFF(k_, mm, bj, n)); } while (0)
; #define RES_STORE(src_, k_) do { _Pragma("unroll") for (int mm = 0; mm < 2; ++mm) _Pragma("unroll") for (int bj = 0; bj < 2; ++bj) _Pragma("unroll") for (int n = 0; n < 2; ++n) \
;             *(f32x4*)(xout + RES_OFF(k_, mm, bj, n)) = src_[mm][bj][n] + al * acc[(k_) >> 1][bj][((k_) & 1) * 2 + mm][n]; } while (0)
; template <class Epi>
; __device__ __forceinline__ void gemm_phase(LAS unsigned char* lds, const Gemm g, const Sched& S, const Epi& E) {
;     ...
;             PG8_BAR; PG8_WAIT_L(0); PG8_MMA(1, 0, At, B0); PG8_BAR; PG8_SCHED;
;             PG8_STAGE(PG8_SB(1, 1), b3 + hstepB, voffB);
;             PG8_WAIT_V(6); PG8_BAR; PG8_MMA(1, 1, At, B1); PG8_BAR;
;         }
;         E(acc, cur, wr, wc, fr, fq);
;     __device__ __forceinline__ void operator()(AccRef acc, const Unit& u, int wr, int wc, int fr, int fq) const {
;         const float al = alpha;
;         const size_t base = ((size_t)u.pm * 256 + wr * 64 + fr) * D_ + u.pn * 256 + wc * 32 + 4 * fq;
;         f32x4 xa[2][2][2], xb[2][2][2];
;     ...
;         RES_LOAD(xa, 0); RES_LOAD(xb, 1);
;         RES_STORE(xa, 0); RES_LOAD(xa, 2);
;         RES_STORE(xb, 1); RES_LOAD(xb, 3);
;         RES_STORE(xa, 2); RES_STORE(xb, 3);
	s_waitcnt lgkmcnt(0)
	s_setprio 1
	s_waitcnt lgkmcnt(0)
	v_mfma_f32_16x16x32_bf16 v[60:63], v[148:151], v[164:167], v[60:63]
	v_mfma_f32_16x16x32_bf16 v[56:59], v[156:159], v[164:167], v[56:59]
	v_mfma_f32_16x16x32_bf16 v[52:55], v[148:151], v[172:175], v[52:55]
	v_mfma_f32_16x16x32_bf16 v[48:51], v[156:159], v[172:175], v[48:51]
	v_mfma_f32_16x16x32_bf16 v[44:47], v[148:151], v[180:183], v[44:47]
	v_mfma_f32_16x16x32_bf16 v[40:43], v[156:159], v[180:183], v[40:43]
	v_mfma_f32_16x16x32_bf16 v[36:39], v[148:151], v[188:191], v[36:39]
	v_mfma_f32_16x16x32_bf16 v[32:35], v[156:159], v[188:191], v[32:35]
	v_mfma_f32_16x16x32_bf16 v[60:63], v[152:155], v[168:171], v[60:63]
	v_mfma_f32_16x16x32_bf16 v[56:59], v[160:163], v[168:171], v[56:59]
	v_mfma_f32_16x16x32_bf16 v[52:55], v[152:155], v[176:179], v[52:55]
	v_mfma_f32_16x16x32_bf16 v[48:51], v[160:163], v[176:179], v[48:51]
	v_mfma_f32_16x16x32_bf16 v[44:47], v[152:155], v[184:187], v[44:47]
	v_mfma_f32_16x16x32_bf16 v[40:43], v[160:163], v[184:187], v[40:43]
	v_mfma_f32_16x16x32_bf16 v[36:39], v[152:155], v[194:197], v[36:39]
	s_barrier
	v_mfma_f32_16x16x32_bf16 v[32:35], v[160:163], v[194:197], v[32:35]
	s_setprio 0
	s_add_u32 s22, s22, 0x160080
	s_addc_u32 s23, s23, 0
	s_add_i32 s24, s24, s1
	v_lshl_add_u64 v[148:149], s[22:23], 0, v[128:129]
	s_mov_b32 m0, s24
	s_nop 0
	global_load_lds_dwordx4 v[148:149], off
	v_lshl_add_u64 v[148:149], s[22:23], 0, v[130:131]
	s_add_i32 m0, s24, 0x2000
	s_nop 0
	global_load_lds_dwordx4 v[148:149], off
	s_waitcnt vmcnt(6)
	s_barrier
	s_setprio 1
	v_mfma_f32_16x16x32_bf16 v[28:31], v[198:201], v[164:167], v[28:31]
	v_mfma_f32_16x16x32_bf16 v[24:27], v[206:209], v[164:167], v[24:27]
	v_mfma_f32_16x16x32_bf16 v[20:23], v[198:201], v[172:175], v[20:23]
	v_mfma_f32_16x16x32_bf16 v[16:19], v[206:209], v[172:175], v[16:19]
	v_mfma_f32_16x16x32_bf16 v[12:15], v[198:201], v[180:183], v[12:15]
	v_mfma_f32_16x16x32_bf16 v[8:11], v[206:209], v[180:183], v[8:11]
	v_mfma_f32_16x16x32_bf16 v[4:7], v[198:201], v[188:191], v[4:7]
	v_mfma_f32_16x16x32_bf16 v[0:3], v[206:209], v[188:191], v[0:3]
	v_mfma_f32_16x16x32_bf16 v[28:31], v[202:205], v[168:171], v[28:31]
	v_mfma_f32_16x16x32_bf16 v[24:27], v[210:213], v[168:171], v[24:27]
	v_mfma_f32_16x16x32_bf16 v[20:23], v[202:205], v[176:179], v[20:23]
	v_mfma_f32_16x16x32_bf16 v[16:19], v[210:213], v[176:179], v[16:19]
	v_mfma_f32_16x16x32_bf16 v[12:15], v[202:205], v[184:187], v[12:15]
	v_mfma_f32_16x16x32_bf16 v[8:11], v[210:213], v[184:187], v[8:11]
	v_mfma_f32_16x16x32_bf16 v[4:7], v[202:205], v[194:197], v[4:7]
	s_barrier
	v_mfma_f32_16x16x32_bf16 v[0:3], v[210:213], v[194:197], v[0:3]
	s_setprio 0
	s_add_i32 s67, s67, 2
	s_add_u32 s20, s20, 0x100
	s_addc_u32 s21, s21, 0
	s_cmpk_gt_u32 s67, 0x55
	s_cbranch_scc0 .LBB0_255
	s_add_u32 s20, s11, 0xffffff00
	s_addc_u32 s21, s51, -1
	s_ashr_i32 s11, s10, 31
	s_lshl_b64 s[22:23], s[10:11], 19
	s_lshl_b32 s11, s52, 8
	s_ashr_i32 s24, s11, 31
	s_add_u32 s22, s22, s11
	s_addc_u32 s23, s23, s24
	v_lshl_add_u64 v[142:143], s[22:23], 0, v[132:133]
	v_lshlrev_b64 v[142:143], 2, v[142:143]
	v_lshl_add_u64 v[144:145], s[36:37], 0, v[142:143]
	v_add_co_u32_e32 v176, vcc, s57, v144
	global_load_dwordx4 v[148:151], v[144:145], off
	global_load_dwordx4 v[152:155], v[144:145], off offset:64
	global_load_dwordx4 v[156:159], v[144:145], off offset:512
	global_load_dwordx4 v[160:163], v[144:145], off offset:576
	v_addc_co_u32_e32 v177, vcc, 0, v145, vcc
	global_load_dwordx4 v[164:167], v[176:177], off
	global_load_dwordx4 v[168:171], v[176:177], off offset:64
	global_load_dwordx4 v[172:175], v[176:177], off offset:512
	s_nop 0
	global_load_dwordx4 v[176:179], v[176:177], off offset:576
	v_add_co_u32_e32 v194, vcc, s58, v144
	v_lshl_add_u64 v[142:143], s[28:29], 0, v[142:143]
	s_nop 0
	v_addc_co_u32_e32 v195, vcc, 0, v145, vcc
	global_load_dwordx4 v[180:183], v[194:195], off
	global_load_dwordx4 v[184:187], v[194:195], off offset:64
	global_load_dwordx4 v[188:191], v[194:195], off offset:512
	s_nop 0
	global_load_dwordx4 v[194:197], v[194:195], off offset:576
	v_add_co_u32_e32 v210, vcc, s59, v144
	s_waitcnt vmcnt(0)
	v_pk_fma_f32 v[150:151], v[126:127], 0.5, v[150:151] op_sel_hi:[1,0,1]
	v_addc_co_u32_e32 v211, vcc, 0, v145, vcc
	global_load_dwordx4 v[198:201], v[210:211], off
	global_load_dwordx4 v[202:205], v[210:211], off offset:64
	global_load_dwordx4 v[206:209], v[210:211], off offset:512
	s_nop 0
	global_load_dwordx4 v[210:213], v[210:211], off offset:576
	v_add_co_u32_e32 v214, vcc, s57, v142
	v_pk_fma_f32 v[148:149], v[124:125], 0.5, v[148:149] op_sel_hi:[1,0,1]
	s_nop 0
	v_addc_co_u32_e32 v215, vcc, 0, v143, vcc
	v_add_co_u32_e32 v216, vcc, s61, v144
	v_pk_fma_f32 v[154:155], v[122:123], 0.5, v[154:155] op_sel_hi:[1,0,1]
	s_nop 0
	v_addc_co_u32_e32 v217, vcc, 0, v145, vcc
	v_add_co_u32_e32 v218, vcc, s62, v144
	v_pk_fma_f32 v[152:153], v[120:121], 0.5, v[152:153] op_sel_hi:[1,0,1]
	s_nop 0
	v_addc_co_u32_e32 v219, vcc, 0, v145, vcc
	v_add_co_u32_e32 v220, vcc, s58, v142
	v_pk_fma_f32 v[158:159], v[94:95], 0.5, v[158:159] op_sel_hi:[1,0,1]
	v_pk_fma_f32 v[156:157], v[92:93], 0.5, v[156:157] op_sel_hi:[1,0,1]
	v_pk_fma_f32 v[162:163], v[90:91], 0.5, v[162:163] op_sel_hi:[1,0,1]
	v_pk_fma_f32 v[160:161], v[88:89], 0.5, v[160:161] op_sel_hi:[1,0,1]
	global_store_dwordx4 v[142:143], v[148:151], off
	global_store_dwordx4 v[142:143], v[152:155], off offset:64
	global_store_dwordx4 v[142:143], v[156:159], off offset:512
	global_store_dwordx4 v[142:143], v[160:163], off offset:576
	v_pk_fma_f32 v[150:151], v[118:119], 0.5, v[166:167] op_sel_hi:[1,0,1]
	v_pk_fma_f32 v[148:149], v[116:117], 0.5, v[164:165] op_sel_hi:[1,0,1]
; #define RES_LOAD(dst_, k_) do { _Pragma("unroll") for (int mm = 0; mm < 2; ++mm) _Pragma("unroll") for (int bj = 0; bj < 2; ++bj) _Pragma("unroll") for (int n = 0; n < 2; ++n) \
;             dst_[mm][bj][n] = *(const f32x4*)(xin + RES_OFF(k_, mm, bj, n)); } while (0)
; #define RES_STORE(src_, k_) do { _Pragma("unroll") for (int mm = 0; mm < 2; ++mm) _Pragma("unroll") for (int bj = 0; bj < 2; ++bj) _Pragma("unroll") for (int n = 0; n < 2; ++n) \
;             *(f32x4*)(xout + RES_OFF(k_, mm, bj, n)) = src_[mm][bj][n] + al * acc[(k_) >> 1][bj][((k_) & 1) * 2 + mm][n]; } while (0)
;     __device__ __forceinline__ void operator()(AccRef acc, const Unit& u, int wr, int wc, int fr, int fq) const {
;     ...
;         RES_LOAD(xa, 0); RES_LOAD(xb, 1);
;         RES_STORE(xa, 0); RES_LOAD(xa, 2);
;         RES_STORE(xb, 1); RES_LOAD(xb, 3);
	v_addc_co_u32_e32 v221, vcc, 0, v143, vcc
	v_pk_fma_f32 v[154:155], v[114:115], 0.5, v[170:171] op_sel_hi:[1,0,1]
	v_pk_fma_f32 v[152:153], v[112:113], 0.5, v[168:169] op_sel_hi:[1,0,1]
	v_pk_fma_f32 v[158:159], v[86:87], 0.5, v[174:175] op_sel_hi:[1,0,1]
	v_pk_fma_f32 v[156:157], v[84:85], 0.5, v[172:173] op_sel_hi:[1,0,1]
	v_pk_fma_f32 v[162:163], v[82:83], 0.5, v[178:179] op_sel_hi:[1,0,1]
	v_pk_fma_f32 v[160:161], v[80:81], 0.5, v[176:177] op_sel_hi:[1,0,1]
	v_pk_fma_f32 v[166:167], v[110:111], 0.5, v[182:183] op_sel_hi:[1,0,1]
	v_pk_fma_f32 v[164:165], v[108:109], 0.5, v[180:181] op_sel_hi:[1,0,1]
	global_store_dwordx4 v[214:215], v[148:151], off
	global_store_dwordx4 v[214:215], v[152:155], off offset:64
	global_store_dwordx4 v[214:215], v[156:159], off offset:512
	global_store_dwordx4 v[214:215], v[160:163], off offset:576
	v_pk_fma_f32 v[168:169], v[106:107], 0.5, v[186:187] op_sel_hi:[1,0,1]
	global_load_dwordx4 v[148:151], v[216:217], off
	global_load_dwordx4 v[152:155], v[216:217], off offset:64
	global_load_dwordx4 v[156:159], v[216:217], off offset:512
	global_load_dwordx4 v[160:163], v[216:217], off offset:576
	global_load_dwordx4 v[170:173], v[218:219], off
	global_load_dwordx4 v[174:177], v[218:219], off offset:64
	global_load_dwordx4 v[178:181], v[218:219], off offset:512
	s_nop 0
	global_load_dwordx4 v[214:217], v[218:219], off offset:576
	s_waitcnt vmcnt(0)
	v_pk_fma_f32 v[150:151], v[62:63], 0.5, v[150:151] op_sel_hi:[1,0,1]
	global_store_dwordx4 v[220:221], v[164:167], off
	v_pk_fma_f32 v[148:149], v[60:61], 0.5, v[148:149] op_sel_hi:[1,0,1]
	v_pk_fma_f32 v[152:153], v[56:57], 0.5, v[152:153] op_sel_hi:[1,0,1]
	v_pk_fma_f32 v[166:167], v[104:105], 0.5, v[184:185] op_sel_hi:[1,0,1]
	global_store_dwordx4 v[220:221], v[166:169], off offset:64
	v_pk_fma_f32 v[164:165], v[76:77], 0.5, v[188:189] op_sel_hi:[1,0,1]
	v_pk_fma_f32 v[154:155], v[58:59], 0.5, v[154:155] op_sel_hi:[1,0,1]
	v_pk_fma_f32 v[166:167], v[78:79], 0.5, v[190:191] op_sel_hi:[1,0,1]
	global_store_dwordx4 v[220:221], v[164:167], off offset:512
	v_add_co_u32_e32 v168, vcc, s59, v142
	s_nop 0
	v_pk_fma_f32 v[166:167], v[74:75], 0.5, v[196:197] op_sel_hi:[1,0,1]
	v_pk_fma_f32 v[164:165], v[72:73], 0.5, v[194:195] op_sel_hi:[1,0,1]
	global_store_dwordx4 v[220:221], v[164:167], off offset:576
	v_addc_co_u32_e32 v169, vcc, 0, v143, vcc
	s_nop 0
	v_pk_fma_f32 v[166:167], v[102:103], 0.5, v[200:201] op_sel_hi:[1,0,1]
	v_pk_fma_f32 v[164:165], v[100:101], 0.5, v[198:199] op_sel_hi:[1,0,1]
	global_store_dwordx4 v[168:169], v[164:167], off
	v_pk_fma_f32 v[158:159], v[30:31], 0.5, v[158:159] op_sel_hi:[1,0,1]
	v_pk_fma_f32 v[156:157], v[28:29], 0.5, v[156:157] op_sel_hi:[1,0,1]
	v_pk_fma_f32 v[166:167], v[98:99], 0.5, v[204:205] op_sel_hi:[1,0,1]
	v_pk_fma_f32 v[164:165], v[96:97], 0.5, v[202:203] op_sel_hi:[1,0,1]
	global_store_dwordx4 v[168:169], v[164:167], off offset:64
	v_pk_fma_f32 v[162:163], v[26:27], 0.5, v[162:163] op_sel_hi:[1,0,1]
	v_pk_fma_f32 v[160:161], v[24:25], 0.5, v[160:161] op_sel_hi:[1,0,1]
	v_pk_fma_f32 v[166:167], v[70:71], 0.5, v[208:209] op_sel_hi:[1,0,1]
	v_pk_fma_f32 v[164:165], v[68:69], 0.5, v[206:207] op_sel_hi:[1,0,1]
	global_store_dwordx4 v[168:169], v[164:167], off offset:512
	v_pk_fma_f32 v[172:173], v[54:55], 0.5, v[172:173] op_sel_hi:[1,0,1]
	v_pk_fma_f32 v[170:171], v[52:53], 0.5, v[170:171] op_sel_hi:[1,0,1]
	v_pk_fma_f32 v[166:167], v[66:67], 0.5, v[212:213] op_sel_hi:[1,0,1]
	v_pk_fma_f32 v[164:165], v[64:65], 0.5, v[210:211] op_sel_hi:[1,0,1]
	global_store_dwordx4 v[168:169], v[164:167], off offset:576
	v_add_co_u32_e32 v168, vcc, s63, v144
	v_pk_fma_f32 v[176:177], v[50:51], 0.5, v[176:177] op_sel_hi:[1,0,1]
	s_nop 0
	v_addc_co_u32_e32 v169, vcc, 0, v145, vcc
	global_load_dwordx4 v[164:167], v[168:169], off
	global_load_dwordx4 v[182:185], v[168:169], off offset:64
	global_load_dwordx4 v[186:189], v[168:169], off offset:512
	global_load_dwordx4 v[194:197], v[168:169], off offset:576
	v_add_co_u32_e32 v144, vcc, s64, v144
	v_pk_fma_f32 v[174:175], v[48:49], 0.5, v[174:175] op_sel_hi:[1,0,1]
	s_nop 0
	v_addc_co_u32_e32 v145, vcc, 0, v145, vcc
	global_load_dwordx4 v[198:201], v[144:145], off
	global_load_dwordx4 v[202:205], v[144:145], off offset:64
	global_load_dwordx4 v[206:209], v[144:145], off offset:512
	global_load_dwordx4 v[210:213], v[144:145], off offset:576
	v_add_co_u32_e32 v144, vcc, s61, v142
	v_pk_fma_f32 v[180:181], v[22:23], 0.5, v[180:181] op_sel_hi:[1,0,1]
	s_nop 0
	v_addc_co_u32_e32 v145, vcc, 0, v143, vcc
	v_add_co_u32_e32 v168, vcc, s62, v142
	v_pk_fma_f32 v[178:179], v[20:21], 0.5, v[178:179] op_sel_hi:[1,0,1]
	s_nop 0
	v_addc_co_u32_e32 v169, vcc, 0, v143, vcc
	v_add_co_u32_e32 v190, vcc, s63, v142
	v_pk_fma_f32 v[216:217], v[18:19], 0.5, v[216:217] op_sel_hi:[1,0,1]
	s_nop 0
	v_addc_co_u32_e32 v191, vcc, 0, v143, vcc
	v_pk_fma_f32 v[214:215], v[16:17], 0.5, v[214:215] op_sel_hi:[1,0,1]
	global_store_dwordx4 v[144:145], v[148:151], off
	global_store_dwordx4 v[144:145], v[152:155], off offset:64
	global_store_dwordx4 v[144:145], v[156:159], off offset:512
	global_store_dwordx4 v[144:145], v[160:163], off offset:576
	global_store_dwordx4 v[168:169], v[170:173], off
	global_store_dwordx4 v[168:169], v[174:177], off offset:64
	global_store_dwordx4 v[168:169], v[178:181], off offset:512
	global_store_dwordx4 v[168:169], v[214:217], off offset:576
	s_waitcnt vmcnt(0)
; #define RES_LOAD(dst_, k_) do { _Pragma("unroll") for (int mm = 0; mm < 2; ++mm) _Pragma("unroll") for (int bj = 0; bj < 2; ++bj) _Pragma("unroll") for (int n = 0; n < 2; ++n) \
;             dst_[mm][bj][n] = *(const f32x4*)(xin + RES_OFF(k_, mm, bj, n)); } while (0)
; #define RES_STORE(src_, k_) do { _Pragma("unroll") for (int mm = 0; mm < 2; ++mm) _Pragma("unroll") for (int bj = 0; bj < 2; ++bj) _Pragma("unroll") for (int n = 0; n < 2; ++n) \
;             *(f32x4*)(xout + RES_OFF(k_, mm, bj, n)) = src_[mm][bj][n] + al * acc[(k_) >> 1][bj][((k_) & 1) * 2 + mm][n]; } while (0)
;     __device__ __forceinline__ void operator()(AccRef acc, const Unit& u, int wr, int wc, int fr, int fq) const {
;     ...
;         RES_LOAD(xa, 0); RES_LOAD(xb, 1);
;         RES_STORE(xa, 0); RES_LOAD(xa, 2);
;         RES_STORE(xb, 1); RES_LOAD(xb, 3);
;         RES_STORE(xa, 2); RES_STORE(xb, 3);
	v_pk_fma_f32 v[150:151], v[46:47], 0.5, v[166:167] op_sel_hi:[1,0,1]
	v_pk_fma_f32 v[148:149], v[44:45], 0.5, v[164:165] op_sel_hi:[1,0,1]
	v_pk_fma_f32 v[152:153], v[40:41], 0.5, v[182:183] op_sel_hi:[1,0,1]
	v_pk_fma_f32 v[154:155], v[42:43], 0.5, v[184:185] op_sel_hi:[1,0,1]
	global_store_dwordx4 v[190:191], v[148:151], off
	global_store_dwordx4 v[190:191], v[152:155], off offset:64
	v_pk_fma_f32 v[144:145], v[34:35], 0.5, v[204:205] op_sel_hi:[1,0,1]
	s_nop 0
	v_add_co_u32_e32 v152, vcc, s64, v142
	v_pk_fma_f32 v[150:151], v[14:15], 0.5, v[188:189] op_sel_hi:[1,0,1]
	v_pk_fma_f32 v[148:149], v[12:13], 0.5, v[186:187] op_sel_hi:[1,0,1]
	v_addc_co_u32_e32 v153, vcc, 0, v143, vcc
	v_pk_fma_f32 v[142:143], v[32:33], 0.5, v[202:203] op_sel_hi:[1,0,1]
	global_store_dwordx4 v[190:191], v[148:151], off offset:512
	global_store_dwordx4 v[152:153], v[142:145], off offset:64
	s_and_b64 vcc, exec, s[6:7]
	v_pk_fma_f32 v[150:151], v[10:11], 0.5, v[196:197] op_sel_hi:[1,0,1]
	v_pk_fma_f32 v[148:149], v[8:9], 0.5, v[194:195] op_sel_hi:[1,0,1]
	v_pk_fma_f32 v[144:145], v[6:7], 0.5, v[208:209] op_sel_hi:[1,0,1]
	v_pk_fma_f32 v[142:143], v[4:5], 0.5, v[206:207] op_sel_hi:[1,0,1]
	global_store_dwordx4 v[190:191], v[148:151], off offset:576
	global_store_dwordx4 v[152:153], v[142:145], off offset:512
	s_nop 0
	v_pk_fma_f32 v[150:151], v[38:39], 0.5, v[200:201] op_sel_hi:[1,0,1]
	v_pk_fma_f32 v[148:149], v[36:37], 0.5, v[198:199] op_sel_hi:[1,0,1]
	v_pk_fma_f32 v[144:145], v[2:3], 0.5, v[212:213] op_sel_hi:[1,0,1]
	v_pk_fma_f32 v[142:143], v[0:1], 0.5, v[210:211] op_sel_hi:[1,0,1]
	global_store_dwordx4 v[152:153], v[148:151], off
	global_store_dwordx4 v[152:153], v[142:145], off offset:576
	s_cbranch_vccz .LBB0_243
	s_mov_b64 s[8:9], s[20:21]
	s_andn2_b64 vcc, exec, s[4:5]
	s_mov_b64 s[20:21], s[8:9]
	s_cbranch_vccnz .LBB0_244

; #define PG8_STAGE(bufoff, gbase, voff) do { _Pragma("unroll") for (int _i = 0; _i < 2; ++_i) \
;         __builtin_amdgcn_global_load_lds((const unsigned*)((const char*)(gbase) + (voff)[_i]), (LAS unsigned*)(lds + (bufoff) + ldsw + _i * 8192), 16, 0, 0); } while (0)
; #define PG8_LDA(dst, b, h) do { _Pragma("unroll") for (int m = 0; m < 4; ++m) _Pragma("unroll") for (int k = 0; k < 2; ++k) dst[m][k] = *(const LAS bf16x8*)(lds + PG8_SA(b, h) + aoff + m * 2048 + k * 1024); } while (0)
; #define PG8_LDB(dst, b, h) do { _Pragma("unroll") for (int n = 0; n < 2; ++n) _Pragma("unroll") for (int k = 0; k < 2; ++k) dst[n][k] = *(const LAS bf16x8*)(lds + PG8_SB(b, h) + boff + n * 2048 + k * 1024); } while (0)
; #define PG8_MMA(ai, bj, At, Bt) do { __builtin_amdgcn_s_setprio(1); _Pragma("unroll") for (int m = 0; m < 4; ++m) _Pragma("unroll") for (int n = 0; n < 2; ++n) _Pragma("unroll") for (int k = 0; k < 2; ++k) \
;         acc[ai][bj][m][n] = __builtin_amdgcn_mfma_f32_16x16x32_bf16(Bt[n][k], At[m][k], acc[ai][bj][m][n], 0, 0, 0); __builtin_amdgcn_s_setprio(0); } while (0)
; #define PG8_WAIT_L(n) asm volatile("s_waitcnt lgkmcnt(" #n ")" ::: "memory")
; #define PG8_BAR __builtin_amdgcn_s_barrier()
; #define PG8_SCHED __builtin_amdgcn_sched_barrier(0)
; template <class Epi>
; __device__ __forceinline__ void gemm_phase(LAS unsigned char* lds, const Gemm g, const Sched& S, const Epi& E) {
;     ...
;             const char* a1 = cA + (size_t)(t + 1) * kstep;
;             const char* a2 = last ? nA : cA + (size_t)(t + 2) * kstep; const char* b2 = last ? nB : cB + (size_t)(t + 2) * kstep;
;             const char* a3 = a2 + kstep; const char* b3 = b2 + kstep;
;             PG8_LDB(B0, 0, 0); PG8_SCHED; PG8_LDA(At, 0, 0); PG8_STAGE(PG8_SA(1, 1), a1 + hstepA, voffA);
;             PG8_WAIT_L(8); PG8_BAR; PG8_WAIT_L(0); PG8_MMA(0, 0, At, B0); PG8_BAR; PG8_SCHED;
;             PG8_LDB(B1, 0, 1); PG8_STAGE(PG8_SB(0, 0), b2, voffB);
;             PG8_BAR; PG8_WAIT_L(0); PG8_MMA(0, 1, At, B1); PG8_BAR;
;             PG8_LDA(At, 0, 1); PG8_STAGE(PG8_SA(0, 0), a2, voffA);
;             PG8_BAR; PG8_WAIT_L(0); PG8_MMA(1, 0, At, B0); PG8_BAR; PG8_SCHED;
.LBB0_378:
	ds_read_b128 v[128:131], v232
	ds_read_b128 v[132:135], v232 offset:1024
	ds_read_b128 v[136:139], v232 offset:2048
	ds_read_b128 v[140:143], v232 offset:3072
	s_add_u32 s51, s8, 0xfff80080
	s_addc_u32 s53, s9, -1
	s_cmp_eq_u32 s50, 28
	s_cselect_b32 s83, s7, s53
	s_cselect_b32 s82, s10, s51
	s_cselect_b32 s81, s11, s39
	s_cselect_b32 s80, s34, s35
	v_lshl_add_u64 v[176:177], s[8:9], 0, v[208:209]
	s_add_i32 m0, s33, 0xc000
	ds_read_b128 v[144:147], v233
	ds_read_b128 v[148:151], v233 offset:1024
	ds_read_b128 v[152:155], v233 offset:2048
	ds_read_b128 v[156:159], v233 offset:3072
	ds_read_b128 v[160:163], v233 offset:4096
	ds_read_b128 v[164:167], v233 offset:5120
	ds_read_b128 v[168:171], v233 offset:6144
	ds_read_b128 v[172:175], v233 offset:7168
	global_load_lds_dwordx4 v[176:177], off
	v_lshl_add_u64 v[176:177], s[8:9], 0, v[210:211]
	s_add_i32 m0, s33, 0xe000
	s_nop 0
	global_load_lds_dwordx4 v[176:177], off
	s_waitcnt lgkmcnt(8)
	s_barrier
	s_waitcnt lgkmcnt(0)
	s_setprio 1
	s_waitcnt lgkmcnt(0)
	v_mfma_f32_16x16x32_bf16 v[124:127], v[128:131], v[144:147], v[124:127]
	v_mfma_f32_16x16x32_bf16 v[120:123], v[136:139], v[144:147], v[120:123]
	v_mfma_f32_16x16x32_bf16 v[116:119], v[128:131], v[152:155], v[116:119]
	v_mfma_f32_16x16x32_bf16 v[112:115], v[136:139], v[152:155], v[112:115]
	v_mfma_f32_16x16x32_bf16 v[108:111], v[128:131], v[160:163], v[108:111]
	v_mfma_f32_16x16x32_bf16 v[104:107], v[136:139], v[160:163], v[104:107]
	v_mfma_f32_16x16x32_bf16 v[100:103], v[128:131], v[168:171], v[100:103]
	v_mfma_f32_16x16x32_bf16 v[96:99], v[136:139], v[168:171], v[96:99]
	v_mfma_f32_16x16x32_bf16 v[124:127], v[132:135], v[148:151], v[124:127]
	v_mfma_f32_16x16x32_bf16 v[120:123], v[140:143], v[148:151], v[120:123]
	v_mfma_f32_16x16x32_bf16 v[116:119], v[132:135], v[156:159], v[116:119]
	v_mfma_f32_16x16x32_bf16 v[112:115], v[140:143], v[156:159], v[112:115]
	v_mfma_f32_16x16x32_bf16 v[108:111], v[132:135], v[164:167], v[108:111]
	v_mfma_f32_16x16x32_bf16 v[104:107], v[140:143], v[164:167], v[104:107]
	v_mfma_f32_16x16x32_bf16 v[100:103], v[132:135], v[172:175], v[100:103]
	s_barrier
	v_mfma_f32_16x16x32_bf16 v[96:99], v[140:143], v[172:175], v[96:99]
	s_setprio 0
	s_add_i32 s51, s87, s1
	v_lshl_add_u64 v[216:217], s[80:81], 0, v[194:195]
	s_mov_b32 m0, s51
	ds_read_b128 v[176:179], v234
	ds_read_b128 v[180:183], v234 offset:1024
	ds_read_b128 v[184:187], v234 offset:2048
	ds_read_b128 v[188:191], v234 offset:3072
	global_load_lds_dwordx4 v[216:217], off
	v_lshl_add_u64 v[218:219], s[80:81], 0, v[196:197]
	s_add_i32 m0, s51, 0x2000
	s_nop 0
	global_load_lds_dwordx4 v[218:219], off
	s_barrier
	s_waitcnt lgkmcnt(0)
	s_setprio 1
	s_waitcnt lgkmcnt(0)
	v_mfma_f32_16x16x32_bf16 v[60:63], v[176:179], v[144:147], v[60:63]
	v_mfma_f32_16x16x32_bf16 v[56:59], v[184:187], v[144:147], v[56:59]
	v_mfma_f32_16x16x32_bf16 v[52:55], v[176:179], v[152:155], v[52:55]
	v_mfma_f32_16x16x32_bf16 v[48:51], v[184:187], v[152:155], v[48:51]
	v_mfma_f32_16x16x32_bf16 v[44:47], v[176:179], v[160:163], v[44:47]
	v_mfma_f32_16x16x32_bf16 v[40:43], v[184:187], v[160:163], v[40:43]
	v_mfma_f32_16x16x32_bf16 v[36:39], v[176:179], v[168:171], v[36:39]
	v_mfma_f32_16x16x32_bf16 v[32:35], v[184:187], v[168:171], v[32:35]
	v_mfma_f32_16x16x32_bf16 v[60:63], v[180:183], v[148:151], v[60:63]
	v_mfma_f32_16x16x32_bf16 v[56:59], v[188:191], v[148:151], v[56:59]
	v_mfma_f32_16x16x32_bf16 v[52:55], v[180:183], v[156:159], v[52:55]
	v_mfma_f32_16x16x32_bf16 v[48:51], v[188:191], v[156:159], v[48:51]
	v_mfma_f32_16x16x32_bf16 v[44:47], v[180:183], v[164:167], v[44:47]
	v_mfma_f32_16x16x32_bf16 v[40:43], v[188:191], v[164:167], v[40:43]
	v_mfma_f32_16x16x32_bf16 v[36:39], v[180:183], v[172:175], v[36:39]
	s_barrier
	v_mfma_f32_16x16x32_bf16 v[32:35], v[188:191], v[172:175], v[32:35]
	s_setprio 0
	s_mov_b32 m0, s33
	v_lshl_add_u64 v[220:221], s[82:83], 0, v[194:195]
	ds_read_b128 v[144:147], v233 offset:16384
	ds_read_b128 v[148:151], v233 offset:17408
	ds_read_b128 v[152:155], v233 offset:18432
	ds_read_b128 v[156:159], v233 offset:19456
	ds_read_b128 v[160:163], v233 offset:20480
	ds_read_b128 v[164:167], v233 offset:21504
	ds_read_b128 v[168:171], v233 offset:22528
	ds_read_b128 v[172:175], v233 offset:23552
	global_load_lds_dwordx4 v[220:221], off
	v_lshl_add_u64 v[222:223], s[82:83], 0, v[196:197]
	s_mov_b32 m0, s43
	s_nop 0
	global_load_lds_dwordx4 v[222:223], off
	s_barrier
	s_waitcnt lgkmcnt(0)
	s_setprio 1
	s_waitcnt lgkmcnt(0)
	v_mfma_f32_16x16x32_bf16 v[92:95], v[128:131], v[144:147], v[92:95]
	v_mfma_f32_16x16x32_bf16 v[88:91], v[136:139], v[144:147], v[88:91]
	v_mfma_f32_16x16x32_bf16 v[84:87], v[128:131], v[152:155], v[84:87]
	v_mfma_f32_16x16x32_bf16 v[80:83], v[136:139], v[152:155], v[80:83]
	v_mfma_f32_16x16x32_bf16 v[76:79], v[128:131], v[160:163], v[76:79]
	v_mfma_f32_16x16x32_bf16 v[72:75], v[136:139], v[160:163], v[72:75]
	v_mfma_f32_16x16x32_bf16 v[68:71], v[128:131], v[168:171], v[68:71]
	v_mfma_f32_16x16x32_bf16 v[64:67], v[136:139], v[168:171], v[64:67]
	v_mfma_f32_16x16x32_bf16 v[92:95], v[132:135], v[148:151], v[92:95]
	v_mfma_f32_16x16x32_bf16 v[88:91], v[140:143], v[148:151], v[88:91]
	v_mfma_f32_16x16x32_bf16 v[84:87], v[132:135], v[156:159], v[84:87]
	v_mfma_f32_16x16x32_bf16 v[80:83], v[140:143], v[156:159], v[80:83]
	v_mfma_f32_16x16x32_bf16 v[76:79], v[132:135], v[164:167], v[76:79]
	v_mfma_f32_16x16x32_bf16 v[72:75], v[140:143], v[164:167], v[72:75]
	v_mfma_f32_16x16x32_bf16 v[68:71], v[132:135], v[172:175], v[68:71]
	s_barrier
; #define PG8_STAGE(bufoff, gbase, voff) do { _Pragma("unroll") for (int _i = 0; _i < 2; ++_i) \
;         __builtin_amdgcn_global_load_lds((const unsigned*)((const char*)(gbase) + (voff)[_i]), (LAS unsigned*)(lds + (bufoff) + ldsw + _i * 8192), 16, 0, 0); } while (0)
; #define PG8_LDA(dst, b, h) do { _Pragma("unroll") for (int m = 0; m < 4; ++m) _Pragma("unroll") for (int k = 0; k < 2; ++k) dst[m][k] = *(const LAS bf16x8*)(lds + PG8_SA(b, h) + aoff + m * 2048 + k * 1024); } while (0)
; #define PG8_LDB(dst, b, h) do { _Pragma("unroll") for (int n = 0; n < 2; ++n) _Pragma("unroll") for (int k = 0; k < 2; ++k) dst[n][k] = *(const LAS bf16x8*)(lds + PG8_SB(b, h) + boff + n * 2048 + k * 1024); } while (0)
; #define PG8_MMA(ai, bj, At, Bt) do { __builtin_amdgcn_s_setprio(1); _Pragma("unroll") for (int m = 0; m < 4; ++m) _Pragma("unroll") for (int n = 0; n < 2; ++n) _Pragma("unroll") for (int k = 0; k < 2; ++k) \
;         acc[ai][bj][m][n] = __builtin_amdgcn_mfma_f32_16x16x32_bf16(Bt[n][k], At[m][k], acc[ai][bj][m][n], 0, 0, 0); __builtin_amdgcn_s_setprio(0); } while (0)
; #define PG8_WAIT_V(n) asm volatile("s_waitcnt vmcnt(" #n ")" ::: "memory")
; #define PG8_WAIT_L(n) asm volatile("s_waitcnt lgkmcnt(" #n ")" ::: "memory")
; #define PG8_BAR __builtin_amdgcn_s_barrier()
; #define PG8_SCHED __builtin_amdgcn_sched_barrier(0)
; template <class Epi>
; __device__ __forceinline__ void gemm_phase(LAS unsigned char* lds, const Gemm g, const Sched& S, const Epi& E) {
;     ...
;             PG8_BAR; PG8_WAIT_L(0); PG8_MMA(1, 0, At, B0); PG8_BAR; PG8_SCHED;
;             PG8_STAGE(PG8_SB(0, 1), b2 + hstepB, voffB);
;             PG8_WAIT_V(6); PG8_BAR; PG8_MMA(1, 1, At, B1); PG8_BAR;
;             PG8_LDB(B0, 1, 0); PG8_SCHED; PG8_LDA(At, 1, 0); PG8_STAGE(PG8_SA(0, 1), a2 + hstepA, voffA);
;             PG8_WAIT_L(8); PG8_BAR; PG8_WAIT_L(0); PG8_MMA(0, 0, At, B0); PG8_BAR; PG8_SCHED;
;             PG8_LDB(B1, 1, 1); PG8_STAGE(PG8_SB(1, 0), b3, voffB);
;             PG8_BAR; PG8_WAIT_L(0); PG8_MMA(0, 1, At, B1); PG8_BAR;
	v_mfma_f32_16x16x32_bf16 v[64:67], v[140:143], v[172:175], v[64:67]
	s_setprio 0
	s_add_u32 vcc_lo, s80, 0x80000
	s_addc_u32 vcc_hi, s81, 0
	s_add_i32 s51, s88, s1
	v_lshl_add_u64 v[128:129], vcc, 0, v[194:195]
	s_mov_b32 m0, s51
	s_nop 0
	global_load_lds_dwordx4 v[128:129], off
	v_lshl_add_u64 v[128:129], vcc, 0, v[196:197]
	s_add_i32 m0, s51, 0x2000
	s_nop 0
	global_load_lds_dwordx4 v[128:129], off
	s_waitcnt vmcnt(6)
	s_barrier
	s_setprio 1
	v_mfma_f32_16x16x32_bf16 v[28:31], v[176:179], v[144:147], v[28:31]
	v_mfma_f32_16x16x32_bf16 v[24:27], v[184:187], v[144:147], v[24:27]
	v_mfma_f32_16x16x32_bf16 v[20:23], v[176:179], v[152:155], v[20:23]
	v_mfma_f32_16x16x32_bf16 v[16:19], v[184:187], v[152:155], v[16:19]
	v_mfma_f32_16x16x32_bf16 v[12:15], v[176:179], v[160:163], v[12:15]
	v_mfma_f32_16x16x32_bf16 v[8:11], v[184:187], v[160:163], v[8:11]
	v_mfma_f32_16x16x32_bf16 v[4:7], v[176:179], v[168:171], v[4:7]
	v_mfma_f32_16x16x32_bf16 v[0:3], v[184:187], v[168:171], v[0:3]
	v_mfma_f32_16x16x32_bf16 v[28:31], v[180:183], v[148:151], v[28:31]
	v_mfma_f32_16x16x32_bf16 v[24:27], v[188:191], v[148:151], v[24:27]
	v_mfma_f32_16x16x32_bf16 v[20:23], v[180:183], v[156:159], v[20:23]
	v_mfma_f32_16x16x32_bf16 v[16:19], v[188:191], v[156:159], v[16:19]
	v_mfma_f32_16x16x32_bf16 v[12:15], v[180:183], v[164:167], v[12:15]
	v_mfma_f32_16x16x32_bf16 v[8:11], v[188:191], v[164:167], v[8:11]
	v_mfma_f32_16x16x32_bf16 v[4:7], v[180:183], v[172:175], v[4:7]
	s_barrier
	v_mfma_f32_16x16x32_bf16 v[0:3], v[188:191], v[172:175], v[0:3]
	s_setprio 0
	s_add_i32 s51, 0, 0x18000
	v_add_u32_e32 v140, s51, v203
	ds_read_b128 v[128:131], v140
	ds_read_b128 v[132:135], v140 offset:1024
	ds_read_b128 v[136:139], v140 offset:2048
	ds_read_b128 v[140:143], v140 offset:3072
	s_add_u32 s82, s82, 0x80000
	s_addc_u32 s83, s83, 0
	s_mov_b32 m0, s54
	v_lshl_add_u64 v[176:177], s[82:83], 0, v[194:195]
	ds_read_b128 v[144:147], v233 offset:32768
	ds_read_b128 v[148:151], v233 offset:33792
	ds_read_b128 v[152:155], v233 offset:34816
	ds_read_b128 v[156:159], v233 offset:35840
	ds_read_b128 v[160:163], v233 offset:36864
	ds_read_b128 v[164:167], v233 offset:37888
	ds_read_b128 v[168:171], v233 offset:38912
	ds_read_b128 v[172:175], v233 offset:39936
	global_load_lds_dwordx4 v[176:177], off
	v_lshl_add_u64 v[176:177], s[82:83], 0, v[196:197]
	s_mov_b32 m0, s55
	s_nop 0
	global_load_lds_dwordx4 v[176:177], off
	s_waitcnt lgkmcnt(8)
	s_barrier
	s_waitcnt lgkmcnt(0)
	s_setprio 1
	s_waitcnt lgkmcnt(0)
	v_mfma_f32_16x16x32_bf16 v[124:127], v[128:131], v[144:147], v[124:127]
	v_mfma_f32_16x16x32_bf16 v[120:123], v[136:139], v[144:147], v[120:123]
	v_mfma_f32_16x16x32_bf16 v[116:119], v[128:131], v[152:155], v[116:119]
	v_mfma_f32_16x16x32_bf16 v[112:115], v[136:139], v[152:155], v[112:115]
	v_mfma_f32_16x16x32_bf16 v[108:111], v[128:131], v[160:163], v[108:111]
	v_mfma_f32_16x16x32_bf16 v[104:107], v[136:139], v[160:163], v[104:107]
	v_mfma_f32_16x16x32_bf16 v[100:103], v[128:131], v[168:171], v[100:103]
	v_mfma_f32_16x16x32_bf16 v[96:99], v[136:139], v[168:171], v[96:99]
	v_mfma_f32_16x16x32_bf16 v[124:127], v[132:135], v[148:151], v[124:127]
	v_mfma_f32_16x16x32_bf16 v[120:123], v[140:143], v[148:151], v[120:123]
	v_mfma_f32_16x16x32_bf16 v[116:119], v[132:135], v[156:159], v[116:119]
	v_mfma_f32_16x16x32_bf16 v[112:115], v[140:143], v[156:159], v[112:115]
	v_mfma_f32_16x16x32_bf16 v[108:111], v[132:135], v[164:167], v[108:111]
	v_mfma_f32_16x16x32_bf16 v[104:107], v[140:143], v[164:167], v[104:107]
	v_mfma_f32_16x16x32_bf16 v[100:103], v[132:135], v[172:175], v[100:103]
	s_barrier
	v_mfma_f32_16x16x32_bf16 v[96:99], v[140:143], v[172:175], v[96:99]
	s_setprio 0
	s_add_i32 s53, 0, 0x1c000
	s_add_i32 s51, s51, s1
	v_add_u32_e32 v188, s53, v203
	v_lshl_add_u64 v[216:217], v[216:217], 0, s[14:15]
	s_mov_b32 m0, s51
	ds_read_b128 v[176:179], v188
	ds_read_b128 v[180:183], v188 offset:1024
	ds_read_b128 v[184:187], v188 offset:2048
	ds_read_b128 v[188:191], v188 offset:3072
	global_load_lds_dwordx4 v[216:217], off
	v_lshl_add_u64 v[216:217], v[218:219], 0, s[14:15]
	s_add_i32 m0, s51, 0x2000
	s_nop 0
	global_load_lds_dwordx4 v[216:217], off
	s_barrier
	s_waitcnt lgkmcnt(0)
	s_setprio 1
	s_waitcnt lgkmcnt(0)
	v_mfma_f32_16x16x32_bf16 v[60:63], v[176:179], v[144:147], v[60:63]
	v_mfma_f32_16x16x32_bf16 v[56:59], v[184:187], v[144:147], v[56:59]
	v_mfma_f32_16x16x32_bf16 v[52:55], v[176:179], v[152:155], v[52:55]
	v_mfma_f32_16x16x32_bf16 v[48:51], v[184:187], v[152:155], v[48:51]
	v_mfma_f32_16x16x32_bf16 v[44:47], v[176:179], v[160:163], v[44:47]
	v_mfma_f32_16x16x32_bf16 v[40:43], v[184:187], v[160:163], v[40:43]
	v_mfma_f32_16x16x32_bf16 v[36:39], v[176:179], v[168:171], v[36:39]
	v_mfma_f32_16x16x32_bf16 v[32:35], v[184:187], v[168:171], v[32:35]
	v_mfma_f32_16x16x32_bf16 v[60:63], v[180:183], v[148:151], v[60:63]
	v_mfma_f32_16x16x32_bf16 v[56:59], v[188:191], v[148:151], v[56:59]
	v_mfma_f32_16x16x32_bf16 v[52:55], v[180:183], v[156:159], v[52:55]
	v_mfma_f32_16x16x32_bf16 v[48:51], v[188:191], v[156:159], v[48:51]
	v_mfma_f32_16x16x32_bf16 v[44:47], v[180:183], v[164:167], v[44:47]
	v_mfma_f32_16x16x32_bf16 v[40:43], v[188:191], v[164:167], v[40:43]
	v_mfma_f32_16x16x32_bf16 v[36:39], v[180:183], v[172:175], v[36:39]
	s_barrier
	v_mfma_f32_16x16x32_bf16 v[32:35], v[188:191], v[172:175], v[32:35]
	s_setprio 0
	s_mov_b32 m0, s62
	v_lshl_add_u64 v[216:217], v[220:221], 0, s[14:15]
	ds_read_b128 v[144:147], v233 offset:49152
	ds_read_b128 v[148:151], v233 offset:50176
	ds_read_b128 v[152:155], v233 offset:51200
	ds_read_b128 v[156:159], v233 offset:52224
	ds_read_b128 v[160:163], v233 offset:53248
	ds_read_b128 v[164:167], v233 offset:54272
	ds_read_b128 v[168:171], v233 offset:55296
	ds_read_b128 v[172:175], v233 offset:56320
	global_load_lds_dwordx4 v[216:217], off
	v_lshl_add_u64 v[216:217], v[222:223], 0, s[14:15]
	s_mov_b32 m0, s63
	s_nop 0
	global_load_lds_dwordx4 v[216:217], off
	s_barrier
; #define PG8_BAR __builtin_amdgcn_s_barrier()
; template <class Epi>
; __device__ __forceinline__ void gemm_phase(LAS unsigned char* lds, const Gemm g, const Sched& S, const Epi& E) {
;     ...
;             PG8_BAR; PG8_WAIT_L(0); PG8_MMA(1, 0, At, B0); PG8_BAR; PG8_SCHED;
;             PG8_STAGE(PG8_SB(1, 1), b3 + hstepB, voffB);
;             PG8_WAIT_V(6); PG8_BAR; PG8_MMA(1, 1, At, B1); PG8_BAR;
;         }
;         E(acc, cur, wr, wc, fr, fq);
;         if (!has_next) break;
;     __device__ __forceinline__ void operator()(AccRef acc, const Unit& u, int wr, int wc, int fr, int fq) const {
;     ...
;         for (int bj = 0; bj < 2; ++bj) {
;             const int hc = (u.pn + pn0) * 2 + bj;
;             if (hc >= 41) continue;
;             const int idx = hc - 16, br = idx >> 3, kvs = (idx >> 2) & 1, g = idx & 3;
;             const int row0 = u.pm * 256 + wr * 64 + fr;
;             if (hc == 40) {
; #pragma unroll
;                 for (int ai = 0; ai < 2; ++ai)
; #pragma unroll
;                     for (int m = 0; m < 4; ++m)
; #pragma unroll
;                         for (int n = 0; n < 2; ++n) { const int row = row0 + ai * 128 + m * 16, p0 = wc * 32 + n * 16 + 4 * fq; const f32x4 v = acc[ai][bj][m][n];
;                             if (p0 < 48) {
; #pragma unroll
;                                 for (int j = 0; j < 4; ++j) ((float*)(big + N_GATE))[(size_t)row * 48 + p0 + j] = __builtin_amdgcn_rcpf(1.0f + __expf(-v[j])); } }
;             } else if (hc >= 16 && kvs == 1 && br >= 1) {
;                 bf16_t* vb = (bf16_t*)(big + ((br == 1) ? N_VSLC : N_VWIN));
; #pragma unroll
;                 for (int ai = 0; ai < 2; ++ai)
; #pragma unroll
;                     for (int m = 0; m < 4; ++m)
; #pragma unroll
;                         for (int n = 0; n < 2; ++n) { const int row = row0 + ai * 128 + m * 16, p0 = wc * 32 + n * 16 + 4 * fq; const f32x4 v = acc[ai][bj][m][n];
;                             const int b = row >> 14, sx = row & (S_ - 1); bf16_t* base = vb + ((size_t)(b * 4 + g) * 128 + p0) * S_ + kperm(sx);
; #pragma unroll
;                             for (int j = 0; j < 4; ++j) base[(size_t)j * S_] = f2bf(v[j]); }
;             } else {
;                 const bool isq = hc < 16;
;                 const size_t boff = isq ? N_Q : (kvs ? N_TOKV : (br == 0 ? N_TOKK : (br == 1 ? N_KSLC : N_KWIN)));
;                 bf16_t* base = (bf16_t*)(big + boff);
	s_waitcnt lgkmcnt(0)
	s_setprio 1
	s_waitcnt lgkmcnt(0)
	v_mfma_f32_16x16x32_bf16 v[92:95], v[128:131], v[144:147], v[92:95]
	v_mfma_f32_16x16x32_bf16 v[88:91], v[136:139], v[144:147], v[88:91]
	v_mfma_f32_16x16x32_bf16 v[84:87], v[128:131], v[152:155], v[84:87]
	v_mfma_f32_16x16x32_bf16 v[80:83], v[136:139], v[152:155], v[80:83]
	v_mfma_f32_16x16x32_bf16 v[76:79], v[128:131], v[160:163], v[76:79]
	v_mfma_f32_16x16x32_bf16 v[72:75], v[136:139], v[160:163], v[72:75]
	v_mfma_f32_16x16x32_bf16 v[68:71], v[128:131], v[168:171], v[68:71]
	v_mfma_f32_16x16x32_bf16 v[64:67], v[136:139], v[168:171], v[64:67]
	v_mfma_f32_16x16x32_bf16 v[92:95], v[132:135], v[148:151], v[92:95]
	v_mfma_f32_16x16x32_bf16 v[88:91], v[140:143], v[148:151], v[88:91]
	v_mfma_f32_16x16x32_bf16 v[84:87], v[132:135], v[156:159], v[84:87]
	v_mfma_f32_16x16x32_bf16 v[80:83], v[140:143], v[156:159], v[80:83]
	v_mfma_f32_16x16x32_bf16 v[76:79], v[132:135], v[164:167], v[76:79]
	v_mfma_f32_16x16x32_bf16 v[72:75], v[140:143], v[164:167], v[72:75]
	v_mfma_f32_16x16x32_bf16 v[68:71], v[132:135], v[172:175], v[68:71]
	s_barrier
	v_mfma_f32_16x16x32_bf16 v[64:67], v[140:143], v[172:175], v[64:67]
	s_setprio 0
	s_add_u32 s80, s80, 0x80080
	s_addc_u32 s81, s81, 0
	s_add_i32 s51, s53, s1
	v_lshl_add_u64 v[128:129], s[80:81], 0, v[194:195]
	s_mov_b32 m0, s51
	s_nop 0
	global_load_lds_dwordx4 v[128:129], off
	v_lshl_add_u64 v[128:129], s[80:81], 0, v[196:197]
	s_add_i32 m0, s51, 0x2000
	s_nop 0
	global_load_lds_dwordx4 v[128:129], off
	s_waitcnt vmcnt(6)
	s_barrier
	s_setprio 1
	v_mfma_f32_16x16x32_bf16 v[28:31], v[176:179], v[144:147], v[28:31]
	v_mfma_f32_16x16x32_bf16 v[24:27], v[184:187], v[144:147], v[24:27]
	v_mfma_f32_16x16x32_bf16 v[20:23], v[176:179], v[152:155], v[20:23]
	v_mfma_f32_16x16x32_bf16 v[16:19], v[184:187], v[152:155], v[16:19]
	v_mfma_f32_16x16x32_bf16 v[12:15], v[176:179], v[160:163], v[12:15]
	v_mfma_f32_16x16x32_bf16 v[8:11], v[184:187], v[160:163], v[8:11]
	v_mfma_f32_16x16x32_bf16 v[4:7], v[176:179], v[168:171], v[4:7]
	v_mfma_f32_16x16x32_bf16 v[0:3], v[184:187], v[168:171], v[0:3]
	v_mfma_f32_16x16x32_bf16 v[28:31], v[180:183], v[148:151], v[28:31]
	v_mfma_f32_16x16x32_bf16 v[24:27], v[188:191], v[148:151], v[24:27]
	v_mfma_f32_16x16x32_bf16 v[20:23], v[180:183], v[156:159], v[20:23]
	v_mfma_f32_16x16x32_bf16 v[16:19], v[188:191], v[156:159], v[16:19]
	v_mfma_f32_16x16x32_bf16 v[12:15], v[180:183], v[164:167], v[12:15]
	v_mfma_f32_16x16x32_bf16 v[8:11], v[188:191], v[164:167], v[8:11]
	v_mfma_f32_16x16x32_bf16 v[4:7], v[180:183], v[172:175], v[4:7]
	s_barrier
	v_mfma_f32_16x16x32_bf16 v[0:3], v[188:191], v[172:175], v[0:3]
	s_setprio 0
	s_add_i32 s50, s50, 2
	s_add_u32 s8, s8, 0x100
	s_addc_u32 s9, s9, 0
	s_add_u32 s35, s35, 0x100
	s_addc_u32 s39, s39, 0
	s_cmp_gt_u32 s50, 29
	s_cbranch_scc0 .LBB0_378
	s_lshl_b32 s10, s6, 8
	s_add_i32 s10, s10, s61
	s_lshl_b32 s11, s66, 1
	s_cmp_gt_i32 s66, 20
	v_or_b32_e32 v216, s10, v201
	s_cbranch_scc1 .LBB0_424
	s_cmp_lg_u32 s66, 20
	s_mov_b64 s[6:7], -1
	s_cbranch_scc0 .LBB0_390
	s_add_i32 s8, s11, -16
	s_ashr_i32 s35, s8, 3
	s_and_b32 s34, s11, 2
	s_cmp_gt_i32 s66, 7
	s_cselect_b64 s[6:7], -1, 0
	s_bitcmp1_b32 s11, 2
	s_cselect_b64 s[50:51], -1, 0
	s_and_b64 s[6:7], s[6:7], s[50:51]
	s_cmp_gt_i32 s35, 0
	s_cselect_b64 s[80:81], -1, 0
	s_and_b64 s[6:7], s[6:7], s[80:81]
	s_andn2_b64 vcc, exec, s[6:7]
	s_mov_b64 s[6:7], -1
	s_cbranch_vccz .LBB0_387
	s_bfe_u32 s6, s11, 0x10002
	s_cmp_eq_u32 s35, 1
	s_cselect_b32 s7, s89, 0x10004000
	s_cmp_gt_u32 s8, 7
	s_cselect_b32 s8, s7, 0x8000000
	s_cmp_eq_u32 s6, 0
	s_cselect_b64 s[50:51], -1, 0
	s_and_b64 s[6:7], s[50:51], exec
	s_cselect_b32 s39, s8, 0xa002000
	s_cmp_lt_i32 s66, 8
	s_cselect_b64 s[6:7], -1, 0
	s_and_b64 s[8:9], s[6:7], exec
	s_cselect_b32 s8, 0, s39
	s_add_u32 s8, s44, s8
	s_addc_u32 s9, s45, 0
	s_and_b64 s[50:51], s[50:51], s[80:81]
	s_or_b64 s[50:51], s[6:7], s[50:51]
	s_mov_b64 s[80:81], -1
	s_and_b64 vcc, exec, s[50:51]
	s_cbranch_vccnz .LBB0_384
; __device__ __forceinline__ unsigned cvt_pk_bf16(float lo, float hi) { unsigned r; asm volatile("v_cvt_pk_bf16_f32 %0, %1, %2" : "=v"(r) : "v"(lo), "v"(hi)); return r; }
; __device__ __forceinline__ void st_bf4(bf16_t* p, const f32x4 v) { u32x2 w; w.x = cvt_pk_bf16(v[0], v[1]); w.y = cvt_pk_bf16(v[2], v[3]); *(u32x2*)p = w; }
;     __device__ __forceinline__ void operator()(AccRef acc, const Unit& u, int wr, int wc, int fr, int fq) const {
;     ...
;                 } else {
; #pragma unroll
;                     for (int ai = 0; ai < 2; ++ai)
; #pragma unroll
;                         for (int m = 0; m < 4; ++m)
; #pragma unroll
;                             for (int n = 0; n < 2; ++n) { const int row = row0 + ai * 128 + m * 16, p0 = wc * 32 + n * 16 + 4 * fq;
;                                 const size_t ro = ((size_t)row + (size_t)(3 * (row >> 14) + g) * S_) * 128;
;                                 st_bf4(base + ro + p0, acc[ai][bj][m][n]); }
	s_ashr_i32 s39, s10, 14
	s_mul_i32 s39, s39, 3
	s_add_i32 s50, s39, s34
	s_ashr_i32 s51, s50, 31
	s_lshl_b64 s[50:51], s[50:51], 22
	s_add_u32 s50, s8, s50
	v_ashrrev_i32_e32 v217, 31, v216
	s_addc_u32 s51, s9, s51
	v_lshlrev_b64 v[128:129], 8, v[216:217]
	v_lshl_add_u64 v[130:131], s[50:51], 0, v[128:129]
	v_lshlrev_b32_e32 v198, 1, v200
	v_lshl_add_u64 v[130:131], v[130:131], 0, v[198:199]
	v_cvt_pk_bf16_f32 v132, v124, v125
	v_cvt_pk_bf16_f32 v133, v126, v127
	global_store_dwordx2 v[130:131], v[132:133], off
	v_cvt_pk_bf16_f32 v132, v120, v121
	v_cvt_pk_bf16_f32 v133, v122, v123
	global_store_dwordx2 v[130:131], v[132:133], off offset:32
	v_or_b32_e32 v130, 16, v216
	v_ashrrev_i32_e32 v131, 31, v130
	v_lshlrev_b64 v[130:131], 8, v[130:131]
	v_lshl_add_u64 v[130:131], s[50:51], 0, v[130:131]
	v_lshl_add_u64 v[130:131], v[130:131], 0, v[198:199]
	v_cvt_pk_bf16_f32 v132, v116, v117
	v_cvt_pk_bf16_f32 v133, v118, v119
	global_store_dwordx2 v[130:131], v[132:133], off
	v_cvt_pk_bf16_f32 v132, v112, v113
	v_cvt_pk_bf16_f32 v133, v114, v115
	global_store_dwordx2 v[130:131], v[132:133], off offset:32
	v_or_b32_e32 v130, 32, v216
	v_ashrrev_i32_e32 v131, 31, v130
	v_lshlrev_b64 v[130:131], 8, v[130:131]
	v_lshl_add_u64 v[130:131], s[50:51], 0, v[130:131]
	v_lshl_add_u64 v[130:131], v[130:131], 0, v[198:199]
	v_cvt_pk_bf16_f32 v132, v108, v109
	v_cvt_pk_bf16_f32 v133, v110, v111
	global_store_dwordx2 v[130:131], v[132:133], off
	v_cvt_pk_bf16_f32 v132, v104, v105
	v_cvt_pk_bf16_f32 v133, v106, v107
	global_store_dwordx2 v[130:131], v[132:133], off offset:32
	v_or_b32_e32 v130, 48, v216
	v_ashrrev_i32_e32 v131, 31, v130
	v_lshlrev_b64 v[130:131], 8, v[130:131]
	v_lshl_add_u64 v[130:131], s[50:51], 0, v[130:131]
	v_lshl_add_u64 v[130:131], v[130:131], 0, v[198:199]
	v_cvt_pk_bf16_f32 v132, v100, v101
	v_cvt_pk_bf16_f32 v133, v102, v103
	global_store_dwordx2 v[130:131], v[132:133], off
	v_cvt_pk_bf16_f32 v132, v96, v97
	v_cvt_pk_bf16_f32 v133, v98, v99
	global_store_dwordx2 v[130:131], v[132:133], off offset:32
	v_add_u32_e32 v130, 0x80, v216
	v_ashrrev_i32_e32 v131, 14, v130
	v_mad_i32_i24 v132, v131, 3, s34
	v_ashrrev_i32_e32 v133, 31, v132
	v_lshlrev_b64 v[132:133], 22, v[132:133]
	v_ashrrev_i32_e32 v131, 31, v130
	v_lshl_add_u64 v[132:133], s[8:9], 0, v[132:133]
	v_lshlrev_b64 v[130:131], 8, v[130:131]
	v_lshl_add_u64 v[130:131], v[132:133], 0, v[130:131]
	v_lshl_add_u64 v[130:131], v[130:131], 0, v[198:199]
	v_cvt_pk_bf16_f32 v134, v92, v93
	v_lshl_add_u64 v[128:129], v[132:133], 0, v[128:129]
	v_cvt_pk_bf16_f32 v135, v94, v95
	global_store_dwordx2 v[130:131], v[134:135], off
	v_cvt_pk_bf16_f32 v134, v88, v89
	v_lshl_add_u64 v[128:129], v[128:129], 0, v[198:199]
	v_cvt_pk_bf16_f32 v135, v90, v91
	global_store_dwordx2 v[130:131], v[134:135], off offset:32
	v_add_co_u32_e32 v134, vcc, s84, v128
	v_cvt_pk_bf16_f32 v132, v84, v85
	v_cvt_pk_bf16_f32 v133, v86, v87
	v_lshl_add_u64 v[130:131], v[128:129], 0, s[22:23]
	s_nop 0
	v_addc_co_u32_e32 v135, vcc, 0, v129, vcc
	global_store_dwordx2 v[134:135], v[132:133], off offset:-4096
	v_cvt_pk_bf16_f32 v132, v80, v81
	v_cvt_pk_bf16_f32 v133, v82, v83
	global_store_dwordx2 v[130:131], v[132:133], off offset:32
	v_lshl_add_u64 v[130:131], v[128:129], 0, s[24:25]
	v_cvt_pk_bf16_f32 v132, v76, v77
	v_cvt_pk_bf16_f32 v133, v78, v79
	global_store_dwordx2 v[134:135], v[132:133], off
	v_cvt_pk_bf16_f32 v132, v72, v73
	v_cvt_pk_bf16_f32 v133, v74, v75
	global_store_dwordx2 v[130:131], v[132:133], off offset:32
	v_lshl_add_u64 v[130:131], v[128:129], 0, s[36:37]
	v_add_co_u32_e32 v128, vcc, 0xb000, v128
	s_mov_b64 s[80:81], 0
	s_nop 0
	v_addc_co_u32_e32 v129, vcc, 0, v129, vcc
	v_cvt_pk_bf16_f32 v132, v68, v69
	v_cvt_pk_bf16_f32 v133, v70, v71
	global_store_dwordx2 v[128:129], v[132:133], off
	v_cvt_pk_bf16_f32 v128, v64, v65
	v_cvt_pk_bf16_f32 v129, v66, v67
	global_store_dwordx2 v[130:131], v[128:129], off offset:32

; #define PG8_STAGE(bufoff, gbase, voff) do { _Pragma("unroll") for (int _i = 0; _i < 2; ++_i) \
;         __builtin_amdgcn_global_load_lds((const unsigned*)((const char*)(gbase) + (voff)[_i]), (LAS unsigned*)(lds + (bufoff) + ldsw + _i * 8192), 16, 0, 0); } while (0)
; #define PG8_LDA(dst, b, h) do { _Pragma("unroll") for (int m = 0; m < 4; ++m) _Pragma("unroll") for (int k = 0; k < 2; ++k) dst[m][k] = *(const LAS bf16x8*)(lds + PG8_SA(b, h) + aoff + m * 2048 + k * 1024); } while (0)
; #define PG8_LDB(dst, b, h) do { _Pragma("unroll") for (int n = 0; n < 2; ++n) _Pragma("unroll") for (int k = 0; k < 2; ++k) dst[n][k] = *(const LAS bf16x8*)(lds + PG8_SB(b, h) + boff + n * 2048 + k * 1024); } while (0)
; #define PG8_MMA(ai, bj, At, Bt) do { __builtin_amdgcn_s_setprio(1); _Pragma("unroll") for (int m = 0; m < 4; ++m) _Pragma("unroll") for (int n = 0; n < 2; ++n) _Pragma("unroll") for (int k = 0; k < 2; ++k) \
;         acc[ai][bj][m][n] = __builtin_amdgcn_mfma_f32_16x16x32_bf16(Bt[n][k], At[m][k], acc[ai][bj][m][n], 0, 0, 0); __builtin_amdgcn_s_setprio(0); } while (0)
; #define PG8_WAIT_L(n) asm volatile("s_waitcnt lgkmcnt(" #n ")" ::: "memory")
; #define PG8_BAR __builtin_amdgcn_s_barrier()
; #define PG8_SCHED __builtin_amdgcn_sched_barrier(0)
; template <class Epi>
; __device__ __forceinline__ void gemm_phase(LAS unsigned char* lds, const Gemm g, const Sched& S, const Epi& E) {
;     ...
;             const char* a1 = cA + (size_t)(t + 1) * kstep;
;             const char* a2 = last ? nA : cA + (size_t)(t + 2) * kstep; const char* b2 = last ? nB : cB + (size_t)(t + 2) * kstep;
;             const char* a3 = a2 + kstep; const char* b3 = b2 + kstep;
;             PG8_LDB(B0, 0, 0); PG8_SCHED; PG8_LDA(At, 0, 0); PG8_STAGE(PG8_SA(1, 1), a1 + hstepA, voffA);
;             PG8_WAIT_L(8); PG8_BAR; PG8_WAIT_L(0); PG8_MMA(0, 0, At, B0); PG8_BAR; PG8_SCHED;
;             PG8_LDB(B1, 0, 1); PG8_STAGE(PG8_SB(0, 0), b2, voffB);
;             PG8_BAR; PG8_WAIT_L(0); PG8_MMA(0, 1, At, B1); PG8_BAR;
;             PG8_LDA(At, 0, 1); PG8_STAGE(PG8_SA(0, 0), a2, voffA);
;             PG8_BAR; PG8_WAIT_L(0); PG8_MMA(1, 0, At, B0); PG8_BAR; PG8_SCHED;
.LBB0_497:
	ds_read_b128 v[144:147], v152
	ds_read_b128 v[156:159], v152 offset:1024
	ds_read_b128 v[160:163], v152 offset:2048
	ds_read_b128 v[164:167], v152 offset:3072
	s_add_u32 s23, s24, 0xfff80080
	s_addc_u32 s34, s25, -1
	s_cmp_eq_u32 s21, 60
	s_cselect_b32 s39, s17, s34
	s_cselect_b32 s38, s16, s23
	s_cselect_b32 s37, s7, s11
	s_cselect_b32 s36, s9, s10
	v_lshl_add_u64 v[148:149], s[24:25], 0, v[140:141]
	s_add_i32 m0, s54, 0xc000
	ds_read_b128 v[168:171], v153
	ds_read_b128 v[172:175], v153 offset:1024
	ds_read_b128 v[176:179], v153 offset:2048
	ds_read_b128 v[180:183], v153 offset:3072
	ds_read_b128 v[184:187], v153 offset:4096
	ds_read_b128 v[188:191], v153 offset:5120
	ds_read_b128 v[194:197], v153 offset:6144
	ds_read_b128 v[198:201], v153 offset:7168
	global_load_lds_dwordx4 v[148:149], off
	v_lshl_add_u64 v[148:149], s[24:25], 0, v[142:143]
	s_add_i32 m0, s54, 0xe000
	s_nop 0
	global_load_lds_dwordx4 v[148:149], off
	s_waitcnt lgkmcnt(8)
	s_barrier
	s_waitcnt lgkmcnt(0)
	s_setprio 1
	s_waitcnt lgkmcnt(0)
	v_mfma_f32_16x16x32_bf16 v[124:127], v[144:147], v[168:171], v[124:127]
	v_mfma_f32_16x16x32_bf16 v[120:123], v[160:163], v[168:171], v[120:123]
	v_mfma_f32_16x16x32_bf16 v[108:111], v[144:147], v[176:179], v[108:111]
	v_mfma_f32_16x16x32_bf16 v[104:107], v[160:163], v[176:179], v[104:107]
	v_mfma_f32_16x16x32_bf16 v[92:95], v[144:147], v[184:187], v[92:95]
	v_mfma_f32_16x16x32_bf16 v[88:91], v[160:163], v[184:187], v[88:91]
	v_mfma_f32_16x16x32_bf16 v[76:79], v[144:147], v[194:197], v[76:79]
	v_mfma_f32_16x16x32_bf16 v[72:75], v[160:163], v[194:197], v[72:75]
	v_mfma_f32_16x16x32_bf16 v[124:127], v[156:159], v[172:175], v[124:127]
	v_mfma_f32_16x16x32_bf16 v[120:123], v[164:167], v[172:175], v[120:123]
	v_mfma_f32_16x16x32_bf16 v[108:111], v[156:159], v[180:183], v[108:111]
	v_mfma_f32_16x16x32_bf16 v[104:107], v[164:167], v[180:183], v[104:107]
	v_mfma_f32_16x16x32_bf16 v[92:95], v[156:159], v[188:191], v[92:95]
	v_mfma_f32_16x16x32_bf16 v[88:91], v[164:167], v[188:191], v[88:91]
	v_mfma_f32_16x16x32_bf16 v[76:79], v[156:159], v[198:201], v[76:79]
	s_barrier
	v_mfma_f32_16x16x32_bf16 v[72:75], v[164:167], v[198:201], v[72:75]
	s_setprio 0
	s_add_i32 s23, s63, s53
	v_lshl_add_u64 v[148:149], s[36:37], 0, v[132:133]
	s_mov_b32 m0, s23
	ds_read_b128 v[202:205], v154
	ds_read_b128 v[206:209], v154 offset:1024
	ds_read_b128 v[210:213], v154 offset:2048
	ds_read_b128 v[214:217], v154 offset:3072
	global_load_lds_dwordx4 v[148:149], off
	v_lshl_add_u64 v[218:219], s[36:37], 0, v[128:129]
	s_add_i32 m0, s23, 0x2000
	s_nop 0
	global_load_lds_dwordx4 v[218:219], off
	s_barrier
	s_waitcnt lgkmcnt(0)
	s_setprio 1
	s_waitcnt lgkmcnt(0)
	v_mfma_f32_16x16x32_bf16 v[116:119], v[202:205], v[168:171], v[116:119]
	v_mfma_f32_16x16x32_bf16 v[112:115], v[210:213], v[168:171], v[112:115]
	v_mfma_f32_16x16x32_bf16 v[100:103], v[202:205], v[176:179], v[100:103]
	v_mfma_f32_16x16x32_bf16 v[96:99], v[210:213], v[176:179], v[96:99]
	v_mfma_f32_16x16x32_bf16 v[84:87], v[202:205], v[184:187], v[84:87]
	v_mfma_f32_16x16x32_bf16 v[80:83], v[210:213], v[184:187], v[80:83]
	v_mfma_f32_16x16x32_bf16 v[68:71], v[202:205], v[194:197], v[68:71]
	v_mfma_f32_16x16x32_bf16 v[64:67], v[210:213], v[194:197], v[64:67]
	v_mfma_f32_16x16x32_bf16 v[116:119], v[206:209], v[172:175], v[116:119]
	v_mfma_f32_16x16x32_bf16 v[112:115], v[214:217], v[172:175], v[112:115]
	v_mfma_f32_16x16x32_bf16 v[100:103], v[206:209], v[180:183], v[100:103]
	v_mfma_f32_16x16x32_bf16 v[96:99], v[214:217], v[180:183], v[96:99]
	v_mfma_f32_16x16x32_bf16 v[84:87], v[206:209], v[188:191], v[84:87]
	v_mfma_f32_16x16x32_bf16 v[80:83], v[214:217], v[188:191], v[80:83]
	v_mfma_f32_16x16x32_bf16 v[68:71], v[206:209], v[198:201], v[68:71]
	s_barrier
	v_mfma_f32_16x16x32_bf16 v[64:67], v[214:217], v[198:201], v[64:67]
	s_setprio 0
	s_mov_b32 m0, s54
	v_lshl_add_u64 v[220:221], s[38:39], 0, v[134:135]
	ds_read_b128 v[168:171], v153 offset:16384
	ds_read_b128 v[172:175], v153 offset:17408
	ds_read_b128 v[176:179], v153 offset:18432
	ds_read_b128 v[180:183], v153 offset:19456
	ds_read_b128 v[184:187], v153 offset:20480
	ds_read_b128 v[188:191], v153 offset:21504
	ds_read_b128 v[194:197], v153 offset:22528
	ds_read_b128 v[198:201], v153 offset:23552
	global_load_lds_dwordx4 v[220:221], off
	v_lshl_add_u64 v[222:223], s[38:39], 0, v[130:131]
	s_mov_b32 m0, s55
	s_nop 0
	global_load_lds_dwordx4 v[222:223], off
	s_barrier
	s_waitcnt lgkmcnt(0)
	s_setprio 1
	s_waitcnt lgkmcnt(0)
	v_mfma_f32_16x16x32_bf16 v[60:63], v[144:147], v[168:171], v[60:63]
	v_mfma_f32_16x16x32_bf16 v[56:59], v[160:163], v[168:171], v[56:59]
	v_mfma_f32_16x16x32_bf16 v[44:47], v[144:147], v[176:179], v[44:47]
	v_mfma_f32_16x16x32_bf16 v[40:43], v[160:163], v[176:179], v[40:43]
	v_mfma_f32_16x16x32_bf16 v[28:31], v[144:147], v[184:187], v[28:31]
	v_mfma_f32_16x16x32_bf16 v[24:27], v[160:163], v[184:187], v[24:27]
	v_mfma_f32_16x16x32_bf16 v[12:15], v[144:147], v[194:197], v[12:15]
	v_mfma_f32_16x16x32_bf16 v[8:11], v[160:163], v[194:197], v[8:11]
	v_mfma_f32_16x16x32_bf16 v[60:63], v[156:159], v[172:175], v[60:63]
	v_mfma_f32_16x16x32_bf16 v[56:59], v[164:167], v[172:175], v[56:59]
	v_mfma_f32_16x16x32_bf16 v[44:47], v[156:159], v[180:183], v[44:47]
	v_mfma_f32_16x16x32_bf16 v[40:43], v[164:167], v[180:183], v[40:43]
	v_mfma_f32_16x16x32_bf16 v[28:31], v[156:159], v[188:191], v[28:31]
	v_mfma_f32_16x16x32_bf16 v[24:27], v[164:167], v[188:191], v[24:27]
	v_mfma_f32_16x16x32_bf16 v[12:15], v[156:159], v[198:201], v[12:15]
	s_barrier
; #define PG8_STAGE(bufoff, gbase, voff) do { _Pragma("unroll") for (int _i = 0; _i < 2; ++_i) \
;         __builtin_amdgcn_global_load_lds((const unsigned*)((const char*)(gbase) + (voff)[_i]), (LAS unsigned*)(lds + (bufoff) + ldsw + _i * 8192), 16, 0, 0); } while (0)
; #define PG8_LDA(dst, b, h) do { _Pragma("unroll") for (int m = 0; m < 4; ++m) _Pragma("unroll") for (int k = 0; k < 2; ++k) dst[m][k] = *(const LAS bf16x8*)(lds + PG8_SA(b, h) + aoff + m * 2048 + k * 1024); } while (0)
; #define PG8_LDB(dst, b, h) do { _Pragma("unroll") for (int n = 0; n < 2; ++n) _Pragma("unroll") for (int k = 0; k < 2; ++k) dst[n][k] = *(const LAS bf16x8*)(lds + PG8_SB(b, h) + boff + n * 2048 + k * 1024); } while (0)
; #define PG8_MMA(ai, bj, At, Bt) do { __builtin_amdgcn_s_setprio(1); _Pragma("unroll") for (int m = 0; m < 4; ++m) _Pragma("unroll") for (int n = 0; n < 2; ++n) _Pragma("unroll") for (int k = 0; k < 2; ++k) \
;         acc[ai][bj][m][n] = __builtin_amdgcn_mfma_f32_16x16x32_bf16(Bt[n][k], At[m][k], acc[ai][bj][m][n], 0, 0, 0); __builtin_amdgcn_s_setprio(0); } while (0)
; #define PG8_WAIT_V(n) asm volatile("s_waitcnt vmcnt(" #n ")" ::: "memory")
; #define PG8_WAIT_L(n) asm volatile("s_waitcnt lgkmcnt(" #n ")" ::: "memory")
; #define PG8_BAR __builtin_amdgcn_s_barrier()
; #define PG8_SCHED __builtin_amdgcn_sched_barrier(0)
; template <class Epi>
; __device__ __forceinline__ void gemm_phase(LAS unsigned char* lds, const Gemm g, const Sched& S, const Epi& E) {
;     ...
;             PG8_BAR; PG8_WAIT_L(0); PG8_MMA(1, 0, At, B0); PG8_BAR; PG8_SCHED;
;             PG8_STAGE(PG8_SB(0, 1), b2 + hstepB, voffB);
;             PG8_WAIT_V(6); PG8_BAR; PG8_MMA(1, 1, At, B1); PG8_BAR;
;             PG8_LDB(B0, 1, 0); PG8_SCHED; PG8_LDA(At, 1, 0); PG8_STAGE(PG8_SA(0, 1), a2 + hstepA, voffA);
;             PG8_WAIT_L(8); PG8_BAR; PG8_WAIT_L(0); PG8_MMA(0, 0, At, B0); PG8_BAR; PG8_SCHED;
;             PG8_LDB(B1, 1, 1); PG8_STAGE(PG8_SB(1, 0), b3, voffB);
;             PG8_BAR; PG8_WAIT_L(0); PG8_MMA(0, 1, At, B1); PG8_BAR;
	v_mfma_f32_16x16x32_bf16 v[8:11], v[164:167], v[198:201], v[8:11]
	s_setprio 0
	s_add_u32 s34, s36, 0x100000
	s_addc_u32 s35, s37, 0
	s_add_i32 s23, s64, s53
	v_lshl_add_u64 v[144:145], s[34:35], 0, v[132:133]
	s_mov_b32 m0, s23
	s_nop 0
	global_load_lds_dwordx4 v[144:145], off
	v_lshl_add_u64 v[144:145], s[34:35], 0, v[128:129]
	s_add_i32 m0, s23, 0x2000
	s_nop 0
	global_load_lds_dwordx4 v[144:145], off
	s_waitcnt vmcnt(6)
	s_barrier
	s_setprio 1
	v_mfma_f32_16x16x32_bf16 v[52:55], v[202:205], v[168:171], v[52:55]
	v_mfma_f32_16x16x32_bf16 v[48:51], v[210:213], v[168:171], v[48:51]
	v_mfma_f32_16x16x32_bf16 v[36:39], v[202:205], v[176:179], v[36:39]
	v_mfma_f32_16x16x32_bf16 v[32:35], v[210:213], v[176:179], v[32:35]
	v_mfma_f32_16x16x32_bf16 v[20:23], v[202:205], v[184:187], v[20:23]
	v_mfma_f32_16x16x32_bf16 v[16:19], v[210:213], v[184:187], v[16:19]
	v_mfma_f32_16x16x32_bf16 v[4:7], v[202:205], v[194:197], v[4:7]
	v_mfma_f32_16x16x32_bf16 v[0:3], v[210:213], v[194:197], v[0:3]
	v_mfma_f32_16x16x32_bf16 v[52:55], v[206:209], v[172:175], v[52:55]
	v_mfma_f32_16x16x32_bf16 v[48:51], v[214:217], v[172:175], v[48:51]
	v_mfma_f32_16x16x32_bf16 v[36:39], v[206:209], v[180:183], v[36:39]
	v_mfma_f32_16x16x32_bf16 v[32:35], v[214:217], v[180:183], v[32:35]
	v_mfma_f32_16x16x32_bf16 v[20:23], v[206:209], v[188:191], v[20:23]
	v_mfma_f32_16x16x32_bf16 v[16:19], v[214:217], v[188:191], v[16:19]
	v_mfma_f32_16x16x32_bf16 v[4:7], v[206:209], v[198:201], v[4:7]
	s_barrier
	v_mfma_f32_16x16x32_bf16 v[0:3], v[214:217], v[198:201], v[0:3]
	s_setprio 0
	s_add_i32 s23, 0, 0x18000
	v_add_u32_e32 v155, s23, v151
	ds_read_b128 v[144:147], v155
	ds_read_b128 v[156:159], v155 offset:1024
	ds_read_b128 v[160:163], v155 offset:2048
	ds_read_b128 v[164:167], v155 offset:3072
	s_add_u32 s34, s38, 0x80000
	s_addc_u32 s35, s39, 0
	s_mov_b32 m0, s56
	v_lshl_add_u64 v[202:203], s[34:35], 0, v[134:135]
	ds_read_b128 v[168:171], v153 offset:32768
	ds_read_b128 v[172:175], v153 offset:33792
	ds_read_b128 v[176:179], v153 offset:34816
	ds_read_b128 v[180:183], v153 offset:35840
	ds_read_b128 v[184:187], v153 offset:36864
	ds_read_b128 v[188:191], v153 offset:37888
	ds_read_b128 v[194:197], v153 offset:38912
	ds_read_b128 v[198:201], v153 offset:39936
	global_load_lds_dwordx4 v[202:203], off
	v_lshl_add_u64 v[202:203], s[34:35], 0, v[130:131]
	s_mov_b32 m0, s57
	s_nop 0
	global_load_lds_dwordx4 v[202:203], off
	s_waitcnt lgkmcnt(8)
	s_barrier
	s_waitcnt lgkmcnt(0)
	s_setprio 1
	s_waitcnt lgkmcnt(0)
	v_mfma_f32_16x16x32_bf16 v[124:127], v[144:147], v[168:171], v[124:127]
	v_mfma_f32_16x16x32_bf16 v[120:123], v[160:163], v[168:171], v[120:123]
	v_mfma_f32_16x16x32_bf16 v[108:111], v[144:147], v[176:179], v[108:111]
	v_mfma_f32_16x16x32_bf16 v[104:107], v[160:163], v[176:179], v[104:107]
	v_mfma_f32_16x16x32_bf16 v[92:95], v[144:147], v[184:187], v[92:95]
	v_mfma_f32_16x16x32_bf16 v[88:91], v[160:163], v[184:187], v[88:91]
	v_mfma_f32_16x16x32_bf16 v[76:79], v[144:147], v[194:197], v[76:79]
	v_mfma_f32_16x16x32_bf16 v[72:75], v[160:163], v[194:197], v[72:75]
	v_mfma_f32_16x16x32_bf16 v[124:127], v[156:159], v[172:175], v[124:127]
	v_mfma_f32_16x16x32_bf16 v[120:123], v[164:167], v[172:175], v[120:123]
	v_mfma_f32_16x16x32_bf16 v[108:111], v[156:159], v[180:183], v[108:111]
	v_mfma_f32_16x16x32_bf16 v[104:107], v[164:167], v[180:183], v[104:107]
	v_mfma_f32_16x16x32_bf16 v[92:95], v[156:159], v[188:191], v[92:95]
	v_mfma_f32_16x16x32_bf16 v[88:91], v[164:167], v[188:191], v[88:91]
	v_mfma_f32_16x16x32_bf16 v[76:79], v[156:159], v[198:201], v[76:79]
	s_barrier
	v_mfma_f32_16x16x32_bf16 v[72:75], v[164:167], v[198:201], v[72:75]
	s_setprio 0
	s_add_i32 s38, 0, 0x1c000
	s_add_i32 s23, s23, s53
	v_add_u32_e32 v155, s38, v151
	v_lshl_add_u64 v[148:149], v[148:149], 0, s[4:5]
	s_mov_b32 m0, s23
	ds_read_b128 v[202:205], v155
	ds_read_b128 v[206:209], v155 offset:1024
	ds_read_b128 v[210:213], v155 offset:2048
	ds_read_b128 v[214:217], v155 offset:3072
	global_load_lds_dwordx4 v[148:149], off
	v_lshl_add_u64 v[148:149], v[218:219], 0, s[4:5]
	s_add_i32 m0, s23, 0x2000
	s_nop 0
	global_load_lds_dwordx4 v[148:149], off
	s_barrier
	s_waitcnt lgkmcnt(0)
	s_setprio 1
	s_waitcnt lgkmcnt(0)
	v_mfma_f32_16x16x32_bf16 v[116:119], v[202:205], v[168:171], v[116:119]
	v_mfma_f32_16x16x32_bf16 v[112:115], v[210:213], v[168:171], v[112:115]
	v_mfma_f32_16x16x32_bf16 v[100:103], v[202:205], v[176:179], v[100:103]
	v_mfma_f32_16x16x32_bf16 v[96:99], v[210:213], v[176:179], v[96:99]
	v_mfma_f32_16x16x32_bf16 v[84:87], v[202:205], v[184:187], v[84:87]
	v_mfma_f32_16x16x32_bf16 v[80:83], v[210:213], v[184:187], v[80:83]
	v_mfma_f32_16x16x32_bf16 v[68:71], v[202:205], v[194:197], v[68:71]
	v_mfma_f32_16x16x32_bf16 v[64:67], v[210:213], v[194:197], v[64:67]
	v_mfma_f32_16x16x32_bf16 v[116:119], v[206:209], v[172:175], v[116:119]
	v_mfma_f32_16x16x32_bf16 v[112:115], v[214:217], v[172:175], v[112:115]
	v_mfma_f32_16x16x32_bf16 v[100:103], v[206:209], v[180:183], v[100:103]
	v_mfma_f32_16x16x32_bf16 v[96:99], v[214:217], v[180:183], v[96:99]
	v_mfma_f32_16x16x32_bf16 v[84:87], v[206:209], v[188:191], v[84:87]
	v_mfma_f32_16x16x32_bf16 v[80:83], v[214:217], v[188:191], v[80:83]
	v_mfma_f32_16x16x32_bf16 v[68:71], v[206:209], v[198:201], v[68:71]
	s_barrier
	v_mfma_f32_16x16x32_bf16 v[64:67], v[214:217], v[198:201], v[64:67]
	s_setprio 0
	s_mov_b32 m0, s59
	v_lshl_add_u64 v[148:149], v[220:221], 0, s[4:5]
	ds_read_b128 v[168:171], v153 offset:49152
	ds_read_b128 v[172:175], v153 offset:50176
	ds_read_b128 v[176:179], v153 offset:51200
	ds_read_b128 v[180:183], v153 offset:52224
	ds_read_b128 v[184:187], v153 offset:53248
	ds_read_b128 v[188:191], v153 offset:54272
	ds_read_b128 v[194:197], v153 offset:55296
	ds_read_b128 v[198:201], v153 offset:56320
	global_load_lds_dwordx4 v[148:149], off
	v_lshl_add_u64 v[148:149], v[222:223], 0, s[4:5]
	s_mov_b32 m0, s60
	s_nop 0
	global_load_lds_dwordx4 v[148:149], off
	s_barrier
; #define PG8_STAGE(bufoff, gbase, voff) do { _Pragma("unroll") for (int _i = 0; _i < 2; ++_i) \
;         __builtin_amdgcn_global_load_lds((const unsigned*)((const char*)(gbase) + (voff)[_i]), (LAS unsigned*)(lds + (bufoff) + ldsw + _i * 8192), 16, 0, 0); } while (0)
; #define PG8_MMA(ai, bj, At, Bt) do { __builtin_amdgcn_s_setprio(1); _Pragma("unroll") for (int m = 0; m < 4; ++m) _Pragma("unroll") for (int n = 0; n < 2; ++n) _Pragma("unroll") for (int k = 0; k < 2; ++k) \
;         acc[ai][bj][m][n] = __builtin_amdgcn_mfma_f32_16x16x32_bf16(Bt[n][k], At[m][k], acc[ai][bj][m][n], 0, 0, 0); __builtin_amdgcn_s_setprio(0); } while (0)
; #define PG8_WAIT_V(n) asm volatile("s_waitcnt vmcnt(" #n ")" ::: "memory")
; #define PG8_WAIT_L(n) asm volatile("s_waitcnt lgkmcnt(" #n ")" ::: "memory")
; #define PG8_BAR __builtin_amdgcn_s_barrier()
; #define PG8_SCHED __builtin_amdgcn_sched_barrier(0)
; template <class Epi>
; __device__ __forceinline__ void gemm_phase(LAS unsigned char* lds, const Gemm g, const Sched& S, const Epi& E) {
;     ...
;             PG8_BAR; PG8_WAIT_L(0); PG8_MMA(1, 0, At, B0); PG8_BAR; PG8_SCHED;
;             PG8_STAGE(PG8_SB(1, 1), b3 + hstepB, voffB);
;             PG8_WAIT_V(6); PG8_BAR; PG8_MMA(1, 1, At, B1); PG8_BAR;
;         }
;         E(acc, cur, wr, wc, fr, fq);
;     __device__ __forceinline__ void operator()(AccRef acc, const Unit& u, int wr, int wc, int fr, int fq) const {
;         const int kv = u.z >> 3;
; #pragma unroll
;         for (int ai = 0; ai < 2; ++ai)
; #pragma unroll
;             for (int m = 0; m < 4; ++m) { const int row = u.pm * 256 + ai * 128 + wr * 64 + m * 16 + fr;
; #pragma unroll
;                 for (int bj = 0; bj < 2; ++bj)
; #pragma unroll
;                     for (int n = 0; n < 2; ++n) { const int col = bj * 128 + wc * 32 + n * 16 + 4 * fq; const f32x4 bv = *(const f32x4*)(bias + kv * 256 + col); f32x4 o;
; #pragma unroll
;                         for (int j = 0; j < 4; ++j) { const float xx = acc[ai][bj][m][n][j] + bv[j]; const float z2 = 2.0f * 0.7978845608028654f * (xx + 0.044715f * xx * xx * xx); const float th = 1.0f - 2.0f * __builtin_amdgcn_rcpf(__expf(z2) + 1.0f); o[j] = 0.5f * xx * (1.0f + th); }
;                         st_bf4(HID + ((size_t)u.z * 1024 + row) * 256 + col, o); } }
;     }
	s_waitcnt lgkmcnt(0)
	s_setprio 1
	s_waitcnt lgkmcnt(0)
	v_mfma_f32_16x16x32_bf16 v[60:63], v[144:147], v[168:171], v[60:63]
	v_mfma_f32_16x16x32_bf16 v[56:59], v[160:163], v[168:171], v[56:59]
	v_mfma_f32_16x16x32_bf16 v[44:47], v[144:147], v[176:179], v[44:47]
	v_mfma_f32_16x16x32_bf16 v[40:43], v[160:163], v[176:179], v[40:43]
	v_mfma_f32_16x16x32_bf16 v[28:31], v[144:147], v[184:187], v[28:31]
	v_mfma_f32_16x16x32_bf16 v[24:27], v[160:163], v[184:187], v[24:27]
	v_mfma_f32_16x16x32_bf16 v[12:15], v[144:147], v[194:197], v[12:15]
	v_mfma_f32_16x16x32_bf16 v[8:11], v[160:163], v[194:197], v[8:11]
	v_mfma_f32_16x16x32_bf16 v[60:63], v[156:159], v[172:175], v[60:63]
	v_mfma_f32_16x16x32_bf16 v[56:59], v[164:167], v[172:175], v[56:59]
	v_mfma_f32_16x16x32_bf16 v[44:47], v[156:159], v[180:183], v[44:47]
	v_mfma_f32_16x16x32_bf16 v[40:43], v[164:167], v[180:183], v[40:43]
	v_mfma_f32_16x16x32_bf16 v[28:31], v[156:159], v[188:191], v[28:31]
	v_mfma_f32_16x16x32_bf16 v[24:27], v[164:167], v[188:191], v[24:27]
	v_mfma_f32_16x16x32_bf16 v[12:15], v[156:159], v[198:201], v[12:15]
	s_barrier
	v_mfma_f32_16x16x32_bf16 v[8:11], v[164:167], v[198:201], v[8:11]
	s_setprio 0
	s_add_u32 s34, s36, 0x100080
	s_addc_u32 s35, s37, 0
	s_add_i32 s23, s38, s53
	v_lshl_add_u64 v[144:145], s[34:35], 0, v[132:133]
	s_mov_b32 m0, s23
	s_nop 0
	global_load_lds_dwordx4 v[144:145], off
	v_lshl_add_u64 v[144:145], s[34:35], 0, v[128:129]
	s_add_i32 m0, s23, 0x2000
	s_nop 0
	global_load_lds_dwordx4 v[144:145], off
	s_waitcnt vmcnt(6)
	s_barrier
	s_setprio 1
	v_mfma_f32_16x16x32_bf16 v[52:55], v[202:205], v[168:171], v[52:55]
	v_mfma_f32_16x16x32_bf16 v[48:51], v[210:213], v[168:171], v[48:51]
	v_mfma_f32_16x16x32_bf16 v[36:39], v[202:205], v[176:179], v[36:39]
	v_mfma_f32_16x16x32_bf16 v[32:35], v[210:213], v[176:179], v[32:35]
	v_mfma_f32_16x16x32_bf16 v[20:23], v[202:205], v[184:187], v[20:23]
	v_mfma_f32_16x16x32_bf16 v[16:19], v[210:213], v[184:187], v[16:19]
	v_mfma_f32_16x16x32_bf16 v[4:7], v[202:205], v[194:197], v[4:7]
	v_mfma_f32_16x16x32_bf16 v[0:3], v[210:213], v[194:197], v[0:3]
	v_mfma_f32_16x16x32_bf16 v[52:55], v[206:209], v[172:175], v[52:55]
	v_mfma_f32_16x16x32_bf16 v[48:51], v[214:217], v[172:175], v[48:51]
	v_mfma_f32_16x16x32_bf16 v[36:39], v[206:209], v[180:183], v[36:39]
	v_mfma_f32_16x16x32_bf16 v[32:35], v[214:217], v[180:183], v[32:35]
	v_mfma_f32_16x16x32_bf16 v[20:23], v[206:209], v[188:191], v[20:23]
	v_mfma_f32_16x16x32_bf16 v[16:19], v[214:217], v[188:191], v[16:19]
	v_mfma_f32_16x16x32_bf16 v[4:7], v[206:209], v[198:201], v[4:7]
	s_barrier
	v_mfma_f32_16x16x32_bf16 v[0:3], v[214:217], v[198:201], v[0:3]
	s_setprio 0
	s_add_i32 s21, s21, 2
	s_add_u32 s24, s24, 0x100
	s_addc_u32 s25, s25, 0
	s_add_u32 s10, s10, 0x100
	s_addc_u32 s11, s11, 0
	s_cmp_gt_u32 s21, 61
	s_cbranch_scc0 .LBB0_497
	s_lshl_b32 s7, s22, 5
	s_and_b32 s10, s7, 0xffffff00
	s_ashr_i32 s11, s10, 31
	v_lshl_add_u64 v[144:145], s[10:11], 2, v[138:139]
	global_load_dwordx4 v[156:159], v[144:145], off
	v_lshl_add_u32 v146, s20, 8, v150
	v_ashrrev_i32_e32 v147, 31, v146
	v_lshlrev_b64 v[148:149], 9, v[146:147]
	s_ashr_i32 s23, s22, 31
	s_lshl_b64 s[10:11], s[22:23], 19
	s_add_u32 s20, s0, s10
	s_addc_u32 s21, s1, s11
	v_lshl_add_u64 v[148:149], s[20:21], 0, v[148:149]
	v_lshl_add_u64 v[148:149], v[148:149], 0, v[136:137]
	s_mov_b64 s[36:37], s[18:19]
	s_mov_b64 s[24:25], s[16:17]
	s_mov_b32 s22, s6
	s_and_b64 vcc, exec, s[14:15]
	s_waitcnt vmcnt(0)
	v_add_f32_e32 v124, v124, v156
	v_add_f32_e32 v125, v125, v157
	v_add_f32_e32 v126, v126, v158
	v_add_f32_e32 v127, v127, v159
	v_mul_f32_e32 v147, 0x3d372713, v124
	v_mul_f32_e32 v156, 0x3d372713, v125
	v_mul_f32_e32 v158, 0x3d372713, v126
	v_mul_f32_e32 v160, 0x3d372713, v127
	v_mul_f32_e32 v147, v124, v147
	v_mul_f32_e32 v156, v125, v156
	v_mul_f32_e32 v155, 0.5, v124
	v_mul_f32_e32 v157, 0.5, v125
	v_mul_f32_e32 v158, v126, v158
	v_mul_f32_e32 v160, v127, v160
	v_fma_f32 v124, v124, v147, v124
	v_fma_f32 v125, v125, v156, v125
	v_mul_f32_e32 v159, 0.5, v126
	v_mul_f32_e32 v161, 0.5, v127
	v_fma_f32 v126, v126, v158, v126
	v_fma_f32 v127, v127, v160, v127
	v_mul_f32_e32 v124, 0x3fcc422a, v124
	v_mul_f32_e32 v125, 0x3fcc422a, v125
	v_mul_f32_e32 v126, 0x3fcc422a, v126
	v_mul_f32_e32 v127, 0x3fcc422a, v127
	v_mul_f32_e32 v124, 0x3fb8aa3b, v124
	v_mul_f32_e32 v125, 0x3fb8aa3b, v125
	v_mul_f32_e32 v126, 0x3fb8aa3b, v126
	v_mul_f32_e32 v127, 0x3fb8aa3b, v127
	v_exp_f32_e32 v124, v124
	v_exp_f32_e32 v125, v125
	v_exp_f32_e32 v126, v126
	v_exp_f32_e32 v127, v127
	v_add_f32_e32 v124, 1.0, v124
	v_add_f32_e32 v125, 1.0, v125
	v_add_f32_e32 v126, 1.0, v126
	v_add_f32_e32 v127, 1.0, v127
	v_rcp_f32_e32 v124, v124
	v_rcp_f32_e32 v125, v125
	v_rcp_f32_e32 v126, v126
	v_rcp_f32_e32 v127, v127
	v_fma_f32 v124, v124, -2.0, 1.0
	v_fma_f32 v125, v125, -2.0, 1.0
	v_fma_f32 v126, v126, -2.0, 1.0
	v_fma_f32 v127, v127, -2.0, 1.0
	v_add_f32_e32 v124, 1.0, v124
	v_add_f32_e32 v125, 1.0, v125
	v_add_f32_e32 v126, 1.0, v126
	v_add_f32_e32 v127, 1.0, v127
	v_mul_f32_e32 v124, v155, v124
	v_mul_f32_e32 v125, v157, v125
	v_mul_f32_e32 v126, v159, v126
	v_mul_f32_e32 v127, v161, v127
	v_cvt_pk_bf16_f32 v124, v124, v125
	v_cvt_pk_bf16_f32 v125, v126, v127
	global_store_dwordx2 v[148:149], v[124:125], off
	global_load_dwordx4 v[124:127], v[144:145], off offset:64
	s_waitcnt vmcnt(0)
; __device__ __forceinline__ void st_bf4(bf16_t* p, const f32x4 v) { u32x2 w; w.x = cvt_pk_bf16(v[0], v[1]); w.y = cvt_pk_bf16(v[2], v[3]); *(u32x2*)p = w; }
;     __device__ __forceinline__ void operator()(AccRef acc, const Unit& u, int wr, int wc, int fr, int fq) const {
;     ...
;             for (int m = 0; m < 4; ++m) { const int row = u.pm * 256 + ai * 128 + wr * 64 + m * 16 + fr;
; #pragma unroll
;                 for (int bj = 0; bj < 2; ++bj)
; #pragma unroll
;                     for (int n = 0; n < 2; ++n) { const int col = bj * 128 + wc * 32 + n * 16 + 4 * fq; const f32x4 bv = *(const f32x4*)(bias + kv * 256 + col); f32x4 o;
; #pragma unroll
;                         for (int j = 0; j < 4; ++j) { const float xx = acc[ai][bj][m][n][j] + bv[j]; const float z2 = 2.0f * 0.7978845608028654f * (xx + 0.044715f * xx * xx * xx); const float th = 1.0f - 2.0f * __builtin_amdgcn_rcpf(__expf(z2) + 1.0f); o[j] = 0.5f * xx * (1.0f + th); }
;                         st_bf4(HID + ((size_t)u.z * 1024 + row) * 256 + col, o); } }
	v_add_f32_e32 v120, v120, v124
	v_add_f32_e32 v121, v121, v125
	v_add_f32_e32 v122, v122, v126
	v_add_f32_e32 v123, v123, v127
	v_mul_f32_e32 v124, 0x3d372713, v120
	v_mul_f32_e32 v126, 0x3d372713, v121
	v_mul_f32_e32 v147, 0x3d372713, v122
	v_mul_f32_e32 v156, 0x3d372713, v123
	v_mul_f32_e32 v124, v120, v124
	v_mul_f32_e32 v126, v121, v126
	v_mul_f32_e32 v125, 0.5, v120
	v_mul_f32_e32 v127, 0.5, v121
	v_mul_f32_e32 v147, v122, v147
	v_mul_f32_e32 v156, v123, v156
	v_fma_f32 v120, v120, v124, v120
	v_fma_f32 v121, v121, v126, v121
	v_mul_f32_e32 v155, 0.5, v122
	v_mul_f32_e32 v157, 0.5, v123
	v_fma_f32 v122, v122, v147, v122
	v_fma_f32 v123, v123, v156, v123
	v_mul_f32_e32 v120, 0x3fcc422a, v120
	v_mul_f32_e32 v121, 0x3fcc422a, v121
	v_mul_f32_e32 v122, 0x3fcc422a, v122
	v_mul_f32_e32 v123, 0x3fcc422a, v123
	v_mul_f32_e32 v120, 0x3fb8aa3b, v120
	v_mul_f32_e32 v121, 0x3fb8aa3b, v121
	v_mul_f32_e32 v122, 0x3fb8aa3b, v122
	v_mul_f32_e32 v123, 0x3fb8aa3b, v123
	v_exp_f32_e32 v120, v120
	v_exp_f32_e32 v121, v121
	v_exp_f32_e32 v122, v122
	v_exp_f32_e32 v123, v123
	v_add_f32_e32 v120, 1.0, v120
	v_add_f32_e32 v121, 1.0, v121
	v_add_f32_e32 v122, 1.0, v122
	v_add_f32_e32 v123, 1.0, v123
	v_rcp_f32_e32 v120, v120
	v_rcp_f32_e32 v121, v121
	v_rcp_f32_e32 v122, v122
	v_rcp_f32_e32 v123, v123
	v_fma_f32 v120, v120, -2.0, 1.0
	v_fma_f32 v121, v121, -2.0, 1.0
	v_fma_f32 v122, v122, -2.0, 1.0
	v_fma_f32 v123, v123, -2.0, 1.0
	v_add_f32_e32 v120, 1.0, v120
	v_add_f32_e32 v121, 1.0, v121
	v_add_f32_e32 v122, 1.0, v122
	v_add_f32_e32 v123, 1.0, v123
	v_mul_f32_e32 v120, v125, v120
	v_mul_f32_e32 v121, v127, v121
	v_mul_f32_e32 v122, v155, v122
	v_mul_f32_e32 v123, v157, v123
	v_cvt_pk_bf16_f32 v120, v120, v121
	v_cvt_pk_bf16_f32 v121, v122, v123
	global_store_dwordx2 v[148:149], v[120:121], off offset:32
	global_load_dwordx4 v[120:123], v[144:145], off offset:512
	s_waitcnt vmcnt(0)
	v_add_f32_e32 v116, v116, v120
	v_add_f32_e32 v117, v117, v121
	v_add_f32_e32 v118, v118, v122
	v_add_f32_e32 v119, v119, v123
	v_mul_f32_e32 v120, 0x3d372713, v116
	v_mul_f32_e32 v122, 0x3d372713, v117
	v_mul_f32_e32 v124, 0x3d372713, v118
	v_mul_f32_e32 v126, 0x3d372713, v119
	v_mul_f32_e32 v120, v116, v120
	v_mul_f32_e32 v122, v117, v122
	v_mul_f32_e32 v121, 0.5, v116
	v_mul_f32_e32 v123, 0.5, v117
	v_mul_f32_e32 v124, v118, v124
	v_mul_f32_e32 v126, v119, v126
	v_fma_f32 v116, v116, v120, v116
	v_fma_f32 v117, v117, v122, v117
	v_mul_f32_e32 v125, 0.5, v118
	v_mul_f32_e32 v127, 0.5, v119
	v_fma_f32 v118, v118, v124, v118
	v_fma_f32 v119, v119, v126, v119
	v_mul_f32_e32 v116, 0x3fcc422a, v116
	v_mul_f32_e32 v117, 0x3fcc422a, v117
	v_mul_f32_e32 v118, 0x3fcc422a, v118
	v_mul_f32_e32 v119, 0x3fcc422a, v119
	v_mul_f32_e32 v116, 0x3fb8aa3b, v116
	v_mul_f32_e32 v117, 0x3fb8aa3b, v117
	v_mul_f32_e32 v118, 0x3fb8aa3b, v118
	v_mul_f32_e32 v119, 0x3fb8aa3b, v119
	v_exp_f32_e32 v116, v116
	v_exp_f32_e32 v117, v117
	v_exp_f32_e32 v118, v118
	v_exp_f32_e32 v119, v119
	v_add_f32_e32 v116, 1.0, v116
	v_add_f32_e32 v117, 1.0, v117
	v_add_f32_e32 v118, 1.0, v118
	v_add_f32_e32 v119, 1.0, v119
	v_rcp_f32_e32 v116, v116
	v_rcp_f32_e32 v117, v117
	v_rcp_f32_e32 v118, v118
	v_rcp_f32_e32 v119, v119
	v_fma_f32 v116, v116, -2.0, 1.0
	v_fma_f32 v117, v117, -2.0, 1.0
	v_fma_f32 v118, v118, -2.0, 1.0
	v_fma_f32 v119, v119, -2.0, 1.0
	v_add_f32_e32 v116, 1.0, v116
	v_add_f32_e32 v117, 1.0, v117
	v_add_f32_e32 v118, 1.0, v118
	v_add_f32_e32 v119, 1.0, v119
	v_mul_f32_e32 v116, v121, v116
	v_mul_f32_e32 v117, v123, v117
	v_mul_f32_e32 v118, v125, v118
	v_mul_f32_e32 v119, v127, v119
	v_cvt_pk_bf16_f32 v116, v116, v117
	v_cvt_pk_bf16_f32 v117, v118, v119
	global_store_dwordx2 v[148:149], v[116:117], off offset:256
	global_load_dwordx4 v[116:119], v[144:145], off offset:576
	s_waitcnt vmcnt(0)
	v_add_f32_e32 v112, v112, v116
	v_add_f32_e32 v113, v113, v117
	v_add_f32_e32 v114, v114, v118
	v_add_f32_e32 v115, v115, v119
	v_mul_f32_e32 v116, 0x3d372713, v112
	v_mul_f32_e32 v118, 0x3d372713, v113
	v_mul_f32_e32 v120, 0x3d372713, v114
	v_mul_f32_e32 v122, 0x3d372713, v115
	v_mul_f32_e32 v116, v112, v116
	v_mul_f32_e32 v118, v113, v118
	v_mul_f32_e32 v117, 0.5, v112
	v_mul_f32_e32 v119, 0.5, v113
	v_mul_f32_e32 v120, v114, v120
	v_mul_f32_e32 v122, v115, v122
	v_fma_f32 v112, v112, v116, v112
	v_fma_f32 v113, v113, v118, v113
	v_mul_f32_e32 v121, 0.5, v114
	v_mul_f32_e32 v123, 0.5, v115
	v_fma_f32 v114, v114, v120, v114
	v_fma_f32 v115, v115, v122, v115
	v_mul_f32_e32 v112, 0x3fcc422a, v112
	v_mul_f32_e32 v113, 0x3fcc422a, v113
	v_mul_f32_e32 v114, 0x3fcc422a, v114
	v_mul_f32_e32 v115, 0x3fcc422a, v115
	v_mul_f32_e32 v112, 0x3fb8aa3b, v112
	v_mul_f32_e32 v113, 0x3fb8aa3b, v113
	v_mul_f32_e32 v114, 0x3fb8aa3b, v114
	v_mul_f32_e32 v115, 0x3fb8aa3b, v115
	v_exp_f32_e32 v112, v112
	v_exp_f32_e32 v113, v113
	v_exp_f32_e32 v114, v114
	v_exp_f32_e32 v115, v115
	v_add_f32_e32 v112, 1.0, v112
	v_add_f32_e32 v113, 1.0, v113
	v_add_f32_e32 v114, 1.0, v114
	v_add_f32_e32 v115, 1.0, v115
	v_rcp_f32_e32 v112, v112
	v_rcp_f32_e32 v113, v113
	v_rcp_f32_e32 v114, v114
	v_rcp_f32_e32 v115, v115
	v_fma_f32 v112, v112, -2.0, 1.0
	v_fma_f32 v113, v113, -2.0, 1.0
	v_fma_f32 v114, v114, -2.0, 1.0
	v_fma_f32 v115, v115, -2.0, 1.0
	v_add_f32_e32 v112, 1.0, v112
	v_add_f32_e32 v113, 1.0, v113
	v_add_f32_e32 v114, 1.0, v114
	v_add_f32_e32 v115, 1.0, v115
	v_mul_f32_e32 v112, v117, v112
	v_mul_f32_e32 v113, v119, v113
	v_mul_f32_e32 v114, v121, v114
	v_mul_f32_e32 v115, v123, v115
	v_cvt_pk_bf16_f32 v112, v112, v113
	v_cvt_pk_bf16_f32 v113, v114, v115
	global_store_dwordx2 v[148:149], v[112:113], off offset:288
	global_load_dwordx4 v[114:117], v[144:145], off
	v_or_b32_e32 v112, 16, v146
	v_ashrrev_i32_e32 v113, 31, v112
	v_lshlrev_b64 v[112:113], 9, v[112:113]
	v_lshl_add_u64 v[112:113], s[20:21], 0, v[112:113]
	v_lshl_add_u64 v[112:113], v[112:113], 0, v[136:137]
	s_waitcnt vmcnt(0)
; __device__ __forceinline__ void st_bf4(bf16_t* p, const f32x4 v) { u32x2 w; w.x = cvt_pk_bf16(v[0], v[1]); w.y = cvt_pk_bf16(v[2], v[3]); *(u32x2*)p = w; }
;     __device__ __forceinline__ void operator()(AccRef acc, const Unit& u, int wr, int wc, int fr, int fq) const {
;     ...
;             for (int m = 0; m < 4; ++m) { const int row = u.pm * 256 + ai * 128 + wr * 64 + m * 16 + fr;
; #pragma unroll
;                 for (int bj = 0; bj < 2; ++bj)
; #pragma unroll
;                     for (int n = 0; n < 2; ++n) { const int col = bj * 128 + wc * 32 + n * 16 + 4 * fq; const f32x4 bv = *(const f32x4*)(bias + kv * 256 + col); f32x4 o;
; #pragma unroll
;                         for (int j = 0; j < 4; ++j) { const float xx = acc[ai][bj][m][n][j] + bv[j]; const float z2 = 2.0f * 0.7978845608028654f * (xx + 0.044715f * xx * xx * xx); const float th = 1.0f - 2.0f * __builtin_amdgcn_rcpf(__expf(z2) + 1.0f); o[j] = 0.5f * xx * (1.0f + th); }
;                         st_bf4(HID + ((size_t)u.z * 1024 + row) * 256 + col, o); } }
	v_add_f32_e32 v108, v108, v114
	v_add_f32_e32 v109, v109, v115
	v_add_f32_e32 v110, v110, v116
	v_add_f32_e32 v111, v111, v117
	v_mul_f32_e32 v114, 0x3d372713, v108
	v_mul_f32_e32 v116, 0x3d372713, v109
	v_mul_f32_e32 v118, 0x3d372713, v110
	v_mul_f32_e32 v120, 0x3d372713, v111
	v_mul_f32_e32 v114, v108, v114
	v_mul_f32_e32 v116, v109, v116
	v_mul_f32_e32 v115, 0.5, v108
	v_mul_f32_e32 v117, 0.5, v109
	v_mul_f32_e32 v118, v110, v118
	v_mul_f32_e32 v120, v111, v120
	v_fma_f32 v108, v108, v114, v108
	v_fma_f32 v109, v109, v116, v109
	v_mul_f32_e32 v119, 0.5, v110
	v_mul_f32_e32 v121, 0.5, v111
	v_fma_f32 v110, v110, v118, v110
	v_fma_f32 v111, v111, v120, v111
	v_mul_f32_e32 v108, 0x3fcc422a, v108
	v_mul_f32_e32 v109, 0x3fcc422a, v109
	v_mul_f32_e32 v110, 0x3fcc422a, v110
	v_mul_f32_e32 v111, 0x3fcc422a, v111
	v_mul_f32_e32 v108, 0x3fb8aa3b, v108
	v_mul_f32_e32 v109, 0x3fb8aa3b, v109
	v_mul_f32_e32 v110, 0x3fb8aa3b, v110
	v_mul_f32_e32 v111, 0x3fb8aa3b, v111
	v_exp_f32_e32 v108, v108
	v_exp_f32_e32 v109, v109
	v_exp_f32_e32 v110, v110
	v_exp_f32_e32 v111, v111
	v_add_f32_e32 v108, 1.0, v108
	v_add_f32_e32 v109, 1.0, v109
	v_add_f32_e32 v110, 1.0, v110
	v_add_f32_e32 v111, 1.0, v111
	v_rcp_f32_e32 v108, v108
	v_rcp_f32_e32 v109, v109
	v_rcp_f32_e32 v110, v110
	v_rcp_f32_e32 v111, v111
	v_fma_f32 v108, v108, -2.0, 1.0
	v_fma_f32 v109, v109, -2.0, 1.0
	v_fma_f32 v110, v110, -2.0, 1.0
	v_fma_f32 v111, v111, -2.0, 1.0
	v_add_f32_e32 v108, 1.0, v108
	v_add_f32_e32 v109, 1.0, v109
	v_add_f32_e32 v110, 1.0, v110
	v_add_f32_e32 v111, 1.0, v111
	v_mul_f32_e32 v108, v115, v108
	v_mul_f32_e32 v109, v117, v109
	v_mul_f32_e32 v110, v119, v110
	v_mul_f32_e32 v111, v121, v111
	v_cvt_pk_bf16_f32 v108, v108, v109
	v_cvt_pk_bf16_f32 v109, v110, v111
	global_store_dwordx2 v[112:113], v[108:109], off
	global_load_dwordx4 v[108:111], v[144:145], off offset:64
	s_waitcnt vmcnt(0)
	v_add_f32_e32 v104, v104, v108
	v_add_f32_e32 v105, v105, v109
	v_add_f32_e32 v106, v106, v110
	v_add_f32_e32 v107, v107, v111
	v_mul_f32_e32 v108, 0x3d372713, v104
	v_mul_f32_e32 v110, 0x3d372713, v105
	v_mul_f32_e32 v114, 0x3d372713, v106
	v_mul_f32_e32 v116, 0x3d372713, v107
	v_mul_f32_e32 v108, v104, v108
	v_mul_f32_e32 v110, v105, v110
	v_mul_f32_e32 v109, 0.5, v104
	v_mul_f32_e32 v111, 0.5, v105
	v_mul_f32_e32 v114, v106, v114
	v_mul_f32_e32 v116, v107, v116
	v_fma_f32 v104, v104, v108, v104
	v_fma_f32 v105, v105, v110, v105
	v_mul_f32_e32 v115, 0.5, v106
	v_mul_f32_e32 v117, 0.5, v107
	v_fma_f32 v106, v106, v114, v106
	v_fma_f32 v107, v107, v116, v107
	v_mul_f32_e32 v104, 0x3fcc422a, v104
	v_mul_f32_e32 v105, 0x3fcc422a, v105
	v_mul_f32_e32 v106, 0x3fcc422a, v106
	v_mul_f32_e32 v107, 0x3fcc422a, v107
	v_mul_f32_e32 v104, 0x3fb8aa3b, v104
	v_mul_f32_e32 v105, 0x3fb8aa3b, v105
	v_mul_f32_e32 v106, 0x3fb8aa3b, v106
	v_mul_f32_e32 v107, 0x3fb8aa3b, v107
	v_exp_f32_e32 v104, v104
	v_exp_f32_e32 v105, v105
	v_exp_f32_e32 v106, v106
	v_exp_f32_e32 v107, v107
	v_add_f32_e32 v104, 1.0, v104
	v_add_f32_e32 v105, 1.0, v105
	v_add_f32_e32 v106, 1.0, v106
	v_add_f32_e32 v107, 1.0, v107
	v_rcp_f32_e32 v104, v104
	v_rcp_f32_e32 v105, v105
	v_rcp_f32_e32 v106, v106
	v_rcp_f32_e32 v107, v107
	v_fma_f32 v104, v104, -2.0, 1.0
	v_fma_f32 v105, v105, -2.0, 1.0
	v_fma_f32 v106, v106, -2.0, 1.0
	v_fma_f32 v107, v107, -2.0, 1.0
	v_add_f32_e32 v104, 1.0, v104
	v_add_f32_e32 v105, 1.0, v105
	v_add_f32_e32 v106, 1.0, v106
	v_add_f32_e32 v107, 1.0, v107
	v_mul_f32_e32 v104, v109, v104
	v_mul_f32_e32 v105, v111, v105
	v_mul_f32_e32 v106, v115, v106
	v_mul_f32_e32 v107, v117, v107
	v_cvt_pk_bf16_f32 v104, v104, v105
	v_cvt_pk_bf16_f32 v105, v106, v107
	global_store_dwordx2 v[112:113], v[104:105], off offset:32
	global_load_dwordx4 v[104:107], v[144:145], off offset:512
	s_waitcnt vmcnt(0)
	v_add_f32_e32 v100, v100, v104
	v_add_f32_e32 v101, v101, v105
	v_add_f32_e32 v102, v102, v106
	v_add_f32_e32 v103, v103, v107
	v_mul_f32_e32 v104, 0x3d372713, v100
	v_mul_f32_e32 v106, 0x3d372713, v101
	v_mul_f32_e32 v108, 0x3d372713, v102
	v_mul_f32_e32 v110, 0x3d372713, v103
	v_mul_f32_e32 v104, v100, v104
	v_mul_f32_e32 v106, v101, v106
	v_mul_f32_e32 v105, 0.5, v100
	v_mul_f32_e32 v107, 0.5, v101
	v_mul_f32_e32 v108, v102, v108
	v_mul_f32_e32 v110, v103, v110
	v_fma_f32 v100, v100, v104, v100
	v_fma_f32 v101, v101, v106, v101
	v_mul_f32_e32 v109, 0.5, v102
	v_mul_f32_e32 v111, 0.5, v103
	v_fma_f32 v102, v102, v108, v102
	v_fma_f32 v103, v103, v110, v103
	v_mul_f32_e32 v100, 0x3fcc422a, v100
	v_mul_f32_e32 v101, 0x3fcc422a, v101
	v_mul_f32_e32 v102, 0x3fcc422a, v102
	v_mul_f32_e32 v103, 0x3fcc422a, v103
	v_mul_f32_e32 v100, 0x3fb8aa3b, v100
	v_mul_f32_e32 v101, 0x3fb8aa3b, v101
	v_mul_f32_e32 v102, 0x3fb8aa3b, v102
	v_mul_f32_e32 v103, 0x3fb8aa3b, v103
	v_exp_f32_e32 v100, v100
	v_exp_f32_e32 v101, v101
	v_exp_f32_e32 v102, v102
	v_exp_f32_e32 v103, v103
	v_add_f32_e32 v100, 1.0, v100
	v_add_f32_e32 v101, 1.0, v101
	v_add_f32_e32 v102, 1.0, v102
	v_add_f32_e32 v103, 1.0, v103
	v_rcp_f32_e32 v100, v100
	v_rcp_f32_e32 v101, v101
	v_rcp_f32_e32 v102, v102
	v_rcp_f32_e32 v103, v103
	v_fma_f32 v100, v100, -2.0, 1.0
	v_fma_f32 v101, v101, -2.0, 1.0
	v_fma_f32 v102, v102, -2.0, 1.0
	v_fma_f32 v103, v103, -2.0, 1.0
	v_add_f32_e32 v100, 1.0, v100
	v_add_f32_e32 v101, 1.0, v101
	v_add_f32_e32 v102, 1.0, v102
	v_add_f32_e32 v103, 1.0, v103
	v_mul_f32_e32 v100, v105, v100
	v_mul_f32_e32 v101, v107, v101
	v_mul_f32_e32 v102, v109, v102
	v_mul_f32_e32 v103, v111, v103
	v_cvt_pk_bf16_f32 v100, v100, v101
	v_cvt_pk_bf16_f32 v101, v102, v103
	global_store_dwordx2 v[112:113], v[100:101], off offset:256
	global_load_dwordx4 v[100:103], v[144:145], off offset:576
	s_waitcnt vmcnt(0)
; __device__ __forceinline__ void st_bf4(bf16_t* p, const f32x4 v) { u32x2 w; w.x = cvt_pk_bf16(v[0], v[1]); w.y = cvt_pk_bf16(v[2], v[3]); *(u32x2*)p = w; }
;     __device__ __forceinline__ void operator()(AccRef acc, const Unit& u, int wr, int wc, int fr, int fq) const {
;     ...
;             for (int m = 0; m < 4; ++m) { const int row = u.pm * 256 + ai * 128 + wr * 64 + m * 16 + fr;
; #pragma unroll
;                 for (int bj = 0; bj < 2; ++bj)
; #pragma unroll
;                     for (int n = 0; n < 2; ++n) { const int col = bj * 128 + wc * 32 + n * 16 + 4 * fq; const f32x4 bv = *(const f32x4*)(bias + kv * 256 + col); f32x4 o;
; #pragma unroll
;                         for (int j = 0; j < 4; ++j) { const float xx = acc[ai][bj][m][n][j] + bv[j]; const float z2 = 2.0f * 0.7978845608028654f * (xx + 0.044715f * xx * xx * xx); const float th = 1.0f - 2.0f * __builtin_amdgcn_rcpf(__expf(z2) + 1.0f); o[j] = 0.5f * xx * (1.0f + th); }
;                         st_bf4(HID + ((size_t)u.z * 1024 + row) * 256 + col, o); } }
	v_add_f32_e32 v96, v96, v100
	v_add_f32_e32 v97, v97, v101
	v_add_f32_e32 v98, v98, v102
	v_add_f32_e32 v99, v99, v103
	v_mul_f32_e32 v100, 0x3d372713, v96
	v_mul_f32_e32 v102, 0x3d372713, v97
	v_mul_f32_e32 v104, 0x3d372713, v98
	v_mul_f32_e32 v106, 0x3d372713, v99
	v_mul_f32_e32 v100, v96, v100
	v_mul_f32_e32 v102, v97, v102
	v_mul_f32_e32 v101, 0.5, v96
	v_mul_f32_e32 v103, 0.5, v97
	v_mul_f32_e32 v104, v98, v104
	v_mul_f32_e32 v106, v99, v106
	v_fma_f32 v96, v96, v100, v96
	v_fma_f32 v97, v97, v102, v97
	v_mul_f32_e32 v105, 0.5, v98
	v_mul_f32_e32 v107, 0.5, v99
	v_fma_f32 v98, v98, v104, v98
	v_fma_f32 v99, v99, v106, v99
	v_mul_f32_e32 v96, 0x3fcc422a, v96
	v_mul_f32_e32 v97, 0x3fcc422a, v97
	v_mul_f32_e32 v98, 0x3fcc422a, v98
	v_mul_f32_e32 v99, 0x3fcc422a, v99
	v_mul_f32_e32 v96, 0x3fb8aa3b, v96
	v_mul_f32_e32 v97, 0x3fb8aa3b, v97
	v_mul_f32_e32 v98, 0x3fb8aa3b, v98
	v_mul_f32_e32 v99, 0x3fb8aa3b, v99
	v_exp_f32_e32 v96, v96
	v_exp_f32_e32 v97, v97
	v_exp_f32_e32 v98, v98
	v_exp_f32_e32 v99, v99
	v_add_f32_e32 v96, 1.0, v96
	v_add_f32_e32 v97, 1.0, v97
	v_add_f32_e32 v98, 1.0, v98
	v_add_f32_e32 v99, 1.0, v99
	v_rcp_f32_e32 v96, v96
	v_rcp_f32_e32 v97, v97
	v_rcp_f32_e32 v98, v98
	v_rcp_f32_e32 v99, v99
	v_fma_f32 v96, v96, -2.0, 1.0
	v_fma_f32 v97, v97, -2.0, 1.0
	v_fma_f32 v98, v98, -2.0, 1.0
	v_fma_f32 v99, v99, -2.0, 1.0
	v_add_f32_e32 v96, 1.0, v96
	v_add_f32_e32 v97, 1.0, v97
	v_add_f32_e32 v98, 1.0, v98
	v_add_f32_e32 v99, 1.0, v99
	v_mul_f32_e32 v96, v101, v96
	v_mul_f32_e32 v97, v103, v97
	v_mul_f32_e32 v98, v105, v98
	v_mul_f32_e32 v99, v107, v99
	v_cvt_pk_bf16_f32 v96, v96, v97
	v_cvt_pk_bf16_f32 v97, v98, v99
	global_store_dwordx2 v[112:113], v[96:97], off offset:288
	global_load_dwordx4 v[98:101], v[144:145], off
	v_or_b32_e32 v96, 32, v146
	v_ashrrev_i32_e32 v97, 31, v96
	v_lshlrev_b64 v[96:97], 9, v[96:97]
	v_lshl_add_u64 v[96:97], s[20:21], 0, v[96:97]
	v_lshl_add_u64 v[96:97], v[96:97], 0, v[136:137]
	s_waitcnt vmcnt(0)
	v_add_f32_e32 v92, v92, v98
	v_add_f32_e32 v93, v93, v99
	v_add_f32_e32 v94, v94, v100
	v_add_f32_e32 v95, v95, v101
	v_mul_f32_e32 v98, 0x3d372713, v92
	v_mul_f32_e32 v100, 0x3d372713, v93
	v_mul_f32_e32 v102, 0x3d372713, v94
	v_mul_f32_e32 v104, 0x3d372713, v95
	v_mul_f32_e32 v98, v92, v98
	v_mul_f32_e32 v100, v93, v100
	v_mul_f32_e32 v99, 0.5, v92
	v_mul_f32_e32 v101, 0.5, v93
	v_mul_f32_e32 v102, v94, v102
	v_mul_f32_e32 v104, v95, v104
	v_fma_f32 v92, v92, v98, v92
	v_fma_f32 v93, v93, v100, v93
	v_mul_f32_e32 v103, 0.5, v94
	v_mul_f32_e32 v105, 0.5, v95
	v_fma_f32 v94, v94, v102, v94
	v_fma_f32 v95, v95, v104, v95
	v_mul_f32_e32 v92, 0x3fcc422a, v92
	v_mul_f32_e32 v93, 0x3fcc422a, v93
	v_mul_f32_e32 v94, 0x3fcc422a, v94
	v_mul_f32_e32 v95, 0x3fcc422a, v95
	v_mul_f32_e32 v92, 0x3fb8aa3b, v92
	v_mul_f32_e32 v93, 0x3fb8aa3b, v93
	v_mul_f32_e32 v94, 0x3fb8aa3b, v94
	v_mul_f32_e32 v95, 0x3fb8aa3b, v95
	v_exp_f32_e32 v92, v92
	v_exp_f32_e32 v93, v93
	v_exp_f32_e32 v94, v94
	v_exp_f32_e32 v95, v95
	v_add_f32_e32 v92, 1.0, v92
	v_add_f32_e32 v93, 1.0, v93
	v_add_f32_e32 v94, 1.0, v94
	v_add_f32_e32 v95, 1.0, v95
	v_rcp_f32_e32 v92, v92
	v_rcp_f32_e32 v93, v93
	v_rcp_f32_e32 v94, v94
	v_rcp_f32_e32 v95, v95
	v_fma_f32 v92, v92, -2.0, 1.0
	v_fma_f32 v93, v93, -2.0, 1.0
	v_fma_f32 v94, v94, -2.0, 1.0
	v_fma_f32 v95, v95, -2.0, 1.0
	v_add_f32_e32 v92, 1.0, v92
	v_add_f32_e32 v93, 1.0, v93
	v_add_f32_e32 v94, 1.0, v94
	v_add_f32_e32 v95, 1.0, v95
	v_mul_f32_e32 v92, v99, v92
	v_mul_f32_e32 v93, v101, v93
	v_mul_f32_e32 v94, v103, v94
	v_mul_f32_e32 v95, v105, v95
	v_cvt_pk_bf16_f32 v92, v92, v93
	v_cvt_pk_bf16_f32 v93, v94, v95
	global_store_dwordx2 v[96:97], v[92:93], off
	global_load_dwordx4 v[92:95], v[144:145], off offset:64
	s_waitcnt vmcnt(0)
	v_add_f32_e32 v88, v88, v92
	v_add_f32_e32 v89, v89, v93
	v_add_f32_e32 v90, v90, v94
	v_add_f32_e32 v91, v91, v95
	v_mul_f32_e32 v92, 0x3d372713, v88
	v_mul_f32_e32 v94, 0x3d372713, v89
	v_mul_f32_e32 v98, 0x3d372713, v90
	v_mul_f32_e32 v100, 0x3d372713, v91
	v_mul_f32_e32 v92, v88, v92
	v_mul_f32_e32 v94, v89, v94
	v_mul_f32_e32 v93, 0.5, v88
	v_mul_f32_e32 v95, 0.5, v89
	v_mul_f32_e32 v98, v90, v98
	v_mul_f32_e32 v100, v91, v100
	v_fma_f32 v88, v88, v92, v88
	v_fma_f32 v89, v89, v94, v89
	v_mul_f32_e32 v99, 0.5, v90
	v_mul_f32_e32 v101, 0.5, v91
	v_fma_f32 v90, v90, v98, v90
	v_fma_f32 v91, v91, v100, v91
	v_mul_f32_e32 v88, 0x3fcc422a, v88
	v_mul_f32_e32 v89, 0x3fcc422a, v89
	v_mul_f32_e32 v90, 0x3fcc422a, v90
	v_mul_f32_e32 v91, 0x3fcc422a, v91
	v_mul_f32_e32 v88, 0x3fb8aa3b, v88
	v_mul_f32_e32 v89, 0x3fb8aa3b, v89
	v_mul_f32_e32 v90, 0x3fb8aa3b, v90
	v_mul_f32_e32 v91, 0x3fb8aa3b, v91
	v_exp_f32_e32 v88, v88
	v_exp_f32_e32 v89, v89
	v_exp_f32_e32 v90, v90
	v_exp_f32_e32 v91, v91
	v_add_f32_e32 v88, 1.0, v88
	v_add_f32_e32 v89, 1.0, v89
	v_add_f32_e32 v90, 1.0, v90
	v_add_f32_e32 v91, 1.0, v91
	v_rcp_f32_e32 v88, v88
	v_rcp_f32_e32 v89, v89
	v_rcp_f32_e32 v90, v90
	v_rcp_f32_e32 v91, v91
	v_fma_f32 v88, v88, -2.0, 1.0
	v_fma_f32 v89, v89, -2.0, 1.0
	v_fma_f32 v90, v90, -2.0, 1.0
	v_fma_f32 v91, v91, -2.0, 1.0
	v_add_f32_e32 v88, 1.0, v88
	v_add_f32_e32 v89, 1.0, v89
	v_add_f32_e32 v90, 1.0, v90
	v_add_f32_e32 v91, 1.0, v91
	v_mul_f32_e32 v88, v93, v88
	v_mul_f32_e32 v89, v95, v89
	v_mul_f32_e32 v90, v99, v90
	v_mul_f32_e32 v91, v101, v91
	v_cvt_pk_bf16_f32 v88, v88, v89
	v_cvt_pk_bf16_f32 v89, v90, v91
	global_store_dwordx2 v[96:97], v[88:89], off offset:32
	global_load_dwordx4 v[88:91], v[144:145], off offset:512
	s_waitcnt vmcnt(0)
; __device__ __forceinline__ void st_bf4(bf16_t* p, const f32x4 v) { u32x2 w; w.x = cvt_pk_bf16(v[0], v[1]); w.y = cvt_pk_bf16(v[2], v[3]); *(u32x2*)p = w; }
;     __device__ __forceinline__ void operator()(AccRef acc, const Unit& u, int wr, int wc, int fr, int fq) const {
;     ...
;             for (int m = 0; m < 4; ++m) { const int row = u.pm * 256 + ai * 128 + wr * 64 + m * 16 + fr;
; #pragma unroll
;                 for (int bj = 0; bj < 2; ++bj)
; #pragma unroll
;                     for (int n = 0; n < 2; ++n) { const int col = bj * 128 + wc * 32 + n * 16 + 4 * fq; const f32x4 bv = *(const f32x4*)(bias + kv * 256 + col); f32x4 o;
; #pragma unroll
;                         for (int j = 0; j < 4; ++j) { const float xx = acc[ai][bj][m][n][j] + bv[j]; const float z2 = 2.0f * 0.7978845608028654f * (xx + 0.044715f * xx * xx * xx); const float th = 1.0f - 2.0f * __builtin_amdgcn_rcpf(__expf(z2) + 1.0f); o[j] = 0.5f * xx * (1.0f + th); }
;                         st_bf4(HID + ((size_t)u.z * 1024 + row) * 256 + col, o); } }
	v_add_f32_e32 v84, v84, v88
	v_add_f32_e32 v85, v85, v89
	v_add_f32_e32 v86, v86, v90
	v_add_f32_e32 v87, v87, v91
	v_mul_f32_e32 v88, 0x3d372713, v84
	v_mul_f32_e32 v90, 0x3d372713, v85
	v_mul_f32_e32 v92, 0x3d372713, v86
	v_mul_f32_e32 v94, 0x3d372713, v87
	v_mul_f32_e32 v88, v84, v88
	v_mul_f32_e32 v90, v85, v90
	v_mul_f32_e32 v89, 0.5, v84
	v_mul_f32_e32 v91, 0.5, v85
	v_mul_f32_e32 v92, v86, v92
	v_mul_f32_e32 v94, v87, v94
	v_fma_f32 v84, v84, v88, v84
	v_fma_f32 v85, v85, v90, v85
	v_mul_f32_e32 v93, 0.5, v86
	v_mul_f32_e32 v95, 0.5, v87
	v_fma_f32 v86, v86, v92, v86
	v_fma_f32 v87, v87, v94, v87
	v_mul_f32_e32 v84, 0x3fcc422a, v84
	v_mul_f32_e32 v85, 0x3fcc422a, v85
	v_mul_f32_e32 v86, 0x3fcc422a, v86
	v_mul_f32_e32 v87, 0x3fcc422a, v87
	v_mul_f32_e32 v84, 0x3fb8aa3b, v84
	v_mul_f32_e32 v85, 0x3fb8aa3b, v85
	v_mul_f32_e32 v86, 0x3fb8aa3b, v86
	v_mul_f32_e32 v87, 0x3fb8aa3b, v87
	v_exp_f32_e32 v84, v84
	v_exp_f32_e32 v85, v85
	v_exp_f32_e32 v86, v86
	v_exp_f32_e32 v87, v87
	v_add_f32_e32 v84, 1.0, v84
	v_add_f32_e32 v85, 1.0, v85
	v_add_f32_e32 v86, 1.0, v86
	v_add_f32_e32 v87, 1.0, v87
	v_rcp_f32_e32 v84, v84
	v_rcp_f32_e32 v85, v85
	v_rcp_f32_e32 v86, v86
	v_rcp_f32_e32 v87, v87
	v_fma_f32 v84, v84, -2.0, 1.0
	v_fma_f32 v85, v85, -2.0, 1.0
	v_fma_f32 v86, v86, -2.0, 1.0
	v_fma_f32 v87, v87, -2.0, 1.0
	v_add_f32_e32 v84, 1.0, v84
	v_add_f32_e32 v85, 1.0, v85
	v_add_f32_e32 v86, 1.0, v86
	v_add_f32_e32 v87, 1.0, v87
	v_mul_f32_e32 v84, v89, v84
	v_mul_f32_e32 v85, v91, v85
	v_mul_f32_e32 v86, v93, v86
	v_mul_f32_e32 v87, v95, v87
	v_cvt_pk_bf16_f32 v84, v84, v85
	v_cvt_pk_bf16_f32 v85, v86, v87
	global_store_dwordx2 v[96:97], v[84:85], off offset:256
	global_load_dwordx4 v[84:87], v[144:145], off offset:576
	s_waitcnt vmcnt(0)
	v_add_f32_e32 v80, v80, v84
	v_add_f32_e32 v81, v81, v85
	v_add_f32_e32 v82, v82, v86
	v_add_f32_e32 v83, v83, v87
	v_mul_f32_e32 v84, 0x3d372713, v80
	v_mul_f32_e32 v86, 0x3d372713, v81
	v_mul_f32_e32 v88, 0x3d372713, v82
	v_mul_f32_e32 v90, 0x3d372713, v83
	v_mul_f32_e32 v84, v80, v84
	v_mul_f32_e32 v86, v81, v86
	v_mul_f32_e32 v85, 0.5, v80
	v_mul_f32_e32 v87, 0.5, v81
	v_mul_f32_e32 v88, v82, v88
	v_mul_f32_e32 v90, v83, v90
	v_fma_f32 v80, v80, v84, v80
	v_fma_f32 v81, v81, v86, v81
	v_mul_f32_e32 v89, 0.5, v82
	v_mul_f32_e32 v91, 0.5, v83
	v_fma_f32 v82, v82, v88, v82
	v_fma_f32 v83, v83, v90, v83
	v_mul_f32_e32 v80, 0x3fcc422a, v80
	v_mul_f32_e32 v81, 0x3fcc422a, v81
	v_mul_f32_e32 v82, 0x3fcc422a, v82
	v_mul_f32_e32 v83, 0x3fcc422a, v83
	v_mul_f32_e32 v80, 0x3fb8aa3b, v80
	v_mul_f32_e32 v81, 0x3fb8aa3b, v81
	v_mul_f32_e32 v82, 0x3fb8aa3b, v82
	v_mul_f32_e32 v83, 0x3fb8aa3b, v83
	v_exp_f32_e32 v80, v80
	v_exp_f32_e32 v81, v81
	v_exp_f32_e32 v82, v82
	v_exp_f32_e32 v83, v83
	v_add_f32_e32 v80, 1.0, v80
	v_add_f32_e32 v81, 1.0, v81
	v_add_f32_e32 v82, 1.0, v82
	v_add_f32_e32 v83, 1.0, v83
	v_rcp_f32_e32 v80, v80
	v_rcp_f32_e32 v81, v81
	v_rcp_f32_e32 v82, v82
	v_rcp_f32_e32 v83, v83
	v_fma_f32 v80, v80, -2.0, 1.0
	v_fma_f32 v81, v81, -2.0, 1.0
	v_fma_f32 v82, v82, -2.0, 1.0
	v_fma_f32 v83, v83, -2.0, 1.0
	v_add_f32_e32 v80, 1.0, v80
	v_add_f32_e32 v81, 1.0, v81
	v_add_f32_e32 v82, 1.0, v82
	v_add_f32_e32 v83, 1.0, v83
	v_mul_f32_e32 v80, v85, v80
	v_mul_f32_e32 v81, v87, v81
	v_mul_f32_e32 v82, v89, v82
	v_mul_f32_e32 v83, v91, v83
	v_cvt_pk_bf16_f32 v80, v80, v81
	v_cvt_pk_bf16_f32 v81, v82, v83
	global_store_dwordx2 v[96:97], v[80:81], off offset:288
	global_load_dwordx4 v[82:85], v[144:145], off
	v_or_b32_e32 v80, 48, v146
	v_ashrrev_i32_e32 v81, 31, v80
	v_lshlrev_b64 v[80:81], 9, v[80:81]
	v_lshl_add_u64 v[80:81], s[20:21], 0, v[80:81]
	v_lshl_add_u64 v[80:81], v[80:81], 0, v[136:137]
	s_waitcnt vmcnt(0)
	v_add_f32_e32 v76, v76, v82
	v_add_f32_e32 v77, v77, v83
	v_add_f32_e32 v78, v78, v84
	v_add_f32_e32 v79, v79, v85
	v_mul_f32_e32 v82, 0x3d372713, v76
	v_mul_f32_e32 v84, 0x3d372713, v77
	v_mul_f32_e32 v86, 0x3d372713, v78
	v_mul_f32_e32 v88, 0x3d372713, v79
	v_mul_f32_e32 v82, v76, v82
	v_mul_f32_e32 v84, v77, v84
	v_mul_f32_e32 v83, 0.5, v76
	v_mul_f32_e32 v85, 0.5, v77
	v_mul_f32_e32 v86, v78, v86
	v_mul_f32_e32 v88, v79, v88
	v_fma_f32 v76, v76, v82, v76
	v_fma_f32 v77, v77, v84, v77
	v_mul_f32_e32 v87, 0.5, v78
	v_mul_f32_e32 v89, 0.5, v79
	v_fma_f32 v78, v78, v86, v78
	v_fma_f32 v79, v79, v88, v79
	v_mul_f32_e32 v76, 0x3fcc422a, v76
	v_mul_f32_e32 v77, 0x3fcc422a, v77
	v_mul_f32_e32 v78, 0x3fcc422a, v78
	v_mul_f32_e32 v79, 0x3fcc422a, v79
	v_mul_f32_e32 v76, 0x3fb8aa3b, v76
	v_mul_f32_e32 v77, 0x3fb8aa3b, v77
	v_mul_f32_e32 v78, 0x3fb8aa3b, v78
	v_mul_f32_e32 v79, 0x3fb8aa3b, v79
	v_exp_f32_e32 v76, v76
	v_exp_f32_e32 v77, v77
	v_exp_f32_e32 v78, v78
	v_exp_f32_e32 v79, v79
	v_add_f32_e32 v76, 1.0, v76
	v_add_f32_e32 v77, 1.0, v77
	v_add_f32_e32 v78, 1.0, v78
	v_add_f32_e32 v79, 1.0, v79
	v_rcp_f32_e32 v76, v76
	v_rcp_f32_e32 v77, v77
	v_rcp_f32_e32 v78, v78
	v_rcp_f32_e32 v79, v79
	v_fma_f32 v76, v76, -2.0, 1.0
	v_fma_f32 v77, v77, -2.0, 1.0
	v_fma_f32 v78, v78, -2.0, 1.0
	v_fma_f32 v79, v79, -2.0, 1.0
	v_add_f32_e32 v76, 1.0, v76
	v_add_f32_e32 v77, 1.0, v77
	v_add_f32_e32 v78, 1.0, v78
	v_add_f32_e32 v79, 1.0, v79
	v_mul_f32_e32 v76, v83, v76
	v_mul_f32_e32 v77, v85, v77
	v_mul_f32_e32 v78, v87, v78
	v_mul_f32_e32 v79, v89, v79
	v_cvt_pk_bf16_f32 v76, v76, v77
	v_cvt_pk_bf16_f32 v77, v78, v79
	global_store_dwordx2 v[80:81], v[76:77], off
	global_load_dwordx4 v[76:79], v[144:145], off offset:64
	s_waitcnt vmcnt(0)
; __device__ __forceinline__ void st_bf4(bf16_t* p, const f32x4 v) { u32x2 w; w.x = cvt_pk_bf16(v[0], v[1]); w.y = cvt_pk_bf16(v[2], v[3]); *(u32x2*)p = w; }
;     __device__ __forceinline__ void operator()(AccRef acc, const Unit& u, int wr, int wc, int fr, int fq) const {
;     ...
;             for (int m = 0; m < 4; ++m) { const int row = u.pm * 256 + ai * 128 + wr * 64 + m * 16 + fr;
; #pragma unroll
;                 for (int bj = 0; bj < 2; ++bj)
; #pragma unroll
;                     for (int n = 0; n < 2; ++n) { const int col = bj * 128 + wc * 32 + n * 16 + 4 * fq; const f32x4 bv = *(const f32x4*)(bias + kv * 256 + col); f32x4 o;
; #pragma unroll
;                         for (int j = 0; j < 4; ++j) { const float xx = acc[ai][bj][m][n][j] + bv[j]; const float z2 = 2.0f * 0.7978845608028654f * (xx + 0.044715f * xx * xx * xx); const float th = 1.0f - 2.0f * __builtin_amdgcn_rcpf(__expf(z2) + 1.0f); o[j] = 0.5f * xx * (1.0f + th); }
;                         st_bf4(HID + ((size_t)u.z * 1024 + row) * 256 + col, o); } }
	v_add_f32_e32 v72, v72, v76
	v_add_f32_e32 v73, v73, v77
	v_add_f32_e32 v74, v74, v78
	v_add_f32_e32 v75, v75, v79
	v_mul_f32_e32 v76, 0x3d372713, v72
	v_mul_f32_e32 v78, 0x3d372713, v73
	v_mul_f32_e32 v82, 0x3d372713, v74
	v_mul_f32_e32 v84, 0x3d372713, v75
	v_mul_f32_e32 v76, v72, v76
	v_mul_f32_e32 v78, v73, v78
	v_mul_f32_e32 v77, 0.5, v72
	v_mul_f32_e32 v79, 0.5, v73
	v_mul_f32_e32 v82, v74, v82
	v_mul_f32_e32 v84, v75, v84
	v_fma_f32 v72, v72, v76, v72
	v_fma_f32 v73, v73, v78, v73
	v_mul_f32_e32 v83, 0.5, v74
	v_mul_f32_e32 v85, 0.5, v75
	v_fma_f32 v74, v74, v82, v74
	v_fma_f32 v75, v75, v84, v75
	v_mul_f32_e32 v72, 0x3fcc422a, v72
	v_mul_f32_e32 v73, 0x3fcc422a, v73
	v_mul_f32_e32 v74, 0x3fcc422a, v74
	v_mul_f32_e32 v75, 0x3fcc422a, v75
	v_mul_f32_e32 v72, 0x3fb8aa3b, v72
	v_mul_f32_e32 v73, 0x3fb8aa3b, v73
	v_mul_f32_e32 v74, 0x3fb8aa3b, v74
	v_mul_f32_e32 v75, 0x3fb8aa3b, v75
	v_exp_f32_e32 v72, v72
	v_exp_f32_e32 v73, v73
	v_exp_f32_e32 v74, v74
	v_exp_f32_e32 v75, v75
	v_add_f32_e32 v72, 1.0, v72
	v_add_f32_e32 v73, 1.0, v73
	v_add_f32_e32 v74, 1.0, v74
	v_add_f32_e32 v75, 1.0, v75
	v_rcp_f32_e32 v72, v72
	v_rcp_f32_e32 v73, v73
	v_rcp_f32_e32 v74, v74
	v_rcp_f32_e32 v75, v75
	v_fma_f32 v72, v72, -2.0, 1.0
	v_fma_f32 v73, v73, -2.0, 1.0
	v_fma_f32 v74, v74, -2.0, 1.0
	v_fma_f32 v75, v75, -2.0, 1.0
	v_add_f32_e32 v72, 1.0, v72
	v_add_f32_e32 v73, 1.0, v73
	v_add_f32_e32 v74, 1.0, v74
	v_add_f32_e32 v75, 1.0, v75
	v_mul_f32_e32 v72, v77, v72
	v_mul_f32_e32 v73, v79, v73
	v_mul_f32_e32 v74, v83, v74
	v_mul_f32_e32 v75, v85, v75
	v_cvt_pk_bf16_f32 v72, v72, v73
	v_cvt_pk_bf16_f32 v73, v74, v75
	global_store_dwordx2 v[80:81], v[72:73], off offset:32
	global_load_dwordx4 v[72:75], v[144:145], off offset:512
	s_waitcnt vmcnt(0)
	v_add_f32_e32 v68, v68, v72
	v_add_f32_e32 v69, v69, v73
	v_add_f32_e32 v70, v70, v74
	v_add_f32_e32 v71, v71, v75
	v_mul_f32_e32 v72, 0x3d372713, v68
	v_mul_f32_e32 v74, 0x3d372713, v69
	v_mul_f32_e32 v76, 0x3d372713, v70
	v_mul_f32_e32 v78, 0x3d372713, v71
	v_mul_f32_e32 v72, v68, v72
	v_mul_f32_e32 v74, v69, v74
	v_mul_f32_e32 v73, 0.5, v68
	v_mul_f32_e32 v75, 0.5, v69
	v_mul_f32_e32 v76, v70, v76
	v_mul_f32_e32 v78, v71, v78
	v_fma_f32 v68, v68, v72, v68
	v_fma_f32 v69, v69, v74, v69
	v_mul_f32_e32 v77, 0.5, v70
	v_mul_f32_e32 v79, 0.5, v71
	v_fma_f32 v70, v70, v76, v70
	v_fma_f32 v71, v71, v78, v71
	v_mul_f32_e32 v68, 0x3fcc422a, v68
	v_mul_f32_e32 v69, 0x3fcc422a, v69
	v_mul_f32_e32 v70, 0x3fcc422a, v70
	v_mul_f32_e32 v71, 0x3fcc422a, v71
	v_mul_f32_e32 v68, 0x3fb8aa3b, v68
	v_mul_f32_e32 v69, 0x3fb8aa3b, v69
	v_mul_f32_e32 v70, 0x3fb8aa3b, v70
	v_mul_f32_e32 v71, 0x3fb8aa3b, v71
	v_exp_f32_e32 v68, v68
	v_exp_f32_e32 v69, v69
	v_exp_f32_e32 v70, v70
	v_exp_f32_e32 v71, v71
	v_add_f32_e32 v68, 1.0, v68
	v_add_f32_e32 v69, 1.0, v69
	v_add_f32_e32 v70, 1.0, v70
	v_add_f32_e32 v71, 1.0, v71
	v_rcp_f32_e32 v68, v68
	v_rcp_f32_e32 v69, v69
	v_rcp_f32_e32 v70, v70
	v_rcp_f32_e32 v71, v71
	v_fma_f32 v68, v68, -2.0, 1.0
	v_fma_f32 v69, v69, -2.0, 1.0
	v_fma_f32 v70, v70, -2.0, 1.0
	v_fma_f32 v71, v71, -2.0, 1.0
	v_add_f32_e32 v68, 1.0, v68
	v_add_f32_e32 v69, 1.0, v69
	v_add_f32_e32 v70, 1.0, v70
	v_add_f32_e32 v71, 1.0, v71
	v_mul_f32_e32 v68, v73, v68
	v_mul_f32_e32 v69, v75, v69
	v_mul_f32_e32 v70, v77, v70
	v_mul_f32_e32 v71, v79, v71
	v_cvt_pk_bf16_f32 v68, v68, v69
	v_cvt_pk_bf16_f32 v69, v70, v71
	global_store_dwordx2 v[80:81], v[68:69], off offset:256
	global_load_dwordx4 v[68:71], v[144:145], off offset:576
	s_waitcnt vmcnt(0)
	v_add_f32_e32 v64, v64, v68
	v_add_f32_e32 v65, v65, v69
	v_add_f32_e32 v66, v66, v70
	v_add_f32_e32 v67, v67, v71
	v_mul_f32_e32 v68, 0x3d372713, v64
	v_mul_f32_e32 v70, 0x3d372713, v65
	v_mul_f32_e32 v72, 0x3d372713, v66
	v_mul_f32_e32 v74, 0x3d372713, v67
	v_mul_f32_e32 v68, v64, v68
	v_mul_f32_e32 v70, v65, v70
	v_mul_f32_e32 v69, 0.5, v64
	v_mul_f32_e32 v71, 0.5, v65
	v_mul_f32_e32 v72, v66, v72
	v_mul_f32_e32 v74, v67, v74
	v_fma_f32 v64, v64, v68, v64
	v_fma_f32 v65, v65, v70, v65
	v_mul_f32_e32 v73, 0.5, v66
	v_mul_f32_e32 v75, 0.5, v67
	v_fma_f32 v66, v66, v72, v66
	v_fma_f32 v67, v67, v74, v67
	v_mul_f32_e32 v64, 0x3fcc422a, v64
	v_mul_f32_e32 v65, 0x3fcc422a, v65
	v_mul_f32_e32 v66, 0x3fcc422a, v66
	v_mul_f32_e32 v67, 0x3fcc422a, v67
	v_mul_f32_e32 v64, 0x3fb8aa3b, v64
	v_mul_f32_e32 v65, 0x3fb8aa3b, v65
	v_mul_f32_e32 v66, 0x3fb8aa3b, v66
	v_mul_f32_e32 v67, 0x3fb8aa3b, v67
	v_exp_f32_e32 v64, v64
	v_exp_f32_e32 v65, v65
	v_exp_f32_e32 v66, v66
	v_exp_f32_e32 v67, v67
	v_add_f32_e32 v64, 1.0, v64
	v_add_f32_e32 v65, 1.0, v65
	v_add_f32_e32 v66, 1.0, v66
	v_add_f32_e32 v67, 1.0, v67
	v_rcp_f32_e32 v64, v64
	v_rcp_f32_e32 v65, v65
	v_rcp_f32_e32 v66, v66
	v_rcp_f32_e32 v67, v67
	v_fma_f32 v64, v64, -2.0, 1.0
	v_fma_f32 v65, v65, -2.0, 1.0
	v_fma_f32 v66, v66, -2.0, 1.0
	v_fma_f32 v67, v67, -2.0, 1.0
	v_add_f32_e32 v64, 1.0, v64
	v_add_f32_e32 v65, 1.0, v65
	v_add_f32_e32 v66, 1.0, v66
	v_add_f32_e32 v67, 1.0, v67
	v_mul_f32_e32 v64, v69, v64
	v_mul_f32_e32 v65, v71, v65
	v_mul_f32_e32 v66, v73, v66
	v_mul_f32_e32 v67, v75, v67
	v_cvt_pk_bf16_f32 v64, v64, v65
	v_cvt_pk_bf16_f32 v65, v66, v67
	global_store_dwordx2 v[80:81], v[64:65], off offset:288
	global_load_dwordx4 v[66:69], v[144:145], off
	v_add_u32_e32 v64, 0x80, v146
	v_ashrrev_i32_e32 v65, 31, v64
	v_lshlrev_b64 v[64:65], 9, v[64:65]
	v_lshl_add_u64 v[64:65], s[20:21], 0, v[64:65]
	v_lshl_add_u64 v[64:65], v[64:65], 0, v[136:137]
	s_waitcnt vmcnt(0)
; __device__ __forceinline__ void st_bf4(bf16_t* p, const f32x4 v) { u32x2 w; w.x = cvt_pk_bf16(v[0], v[1]); w.y = cvt_pk_bf16(v[2], v[3]); *(u32x2*)p = w; }
;     __device__ __forceinline__ void operator()(AccRef acc, const Unit& u, int wr, int wc, int fr, int fq) const {
;     ...
;             for (int m = 0; m < 4; ++m) { const int row = u.pm * 256 + ai * 128 + wr * 64 + m * 16 + fr;
; #pragma unroll
;                 for (int bj = 0; bj < 2; ++bj)
; #pragma unroll
;                     for (int n = 0; n < 2; ++n) { const int col = bj * 128 + wc * 32 + n * 16 + 4 * fq; const f32x4 bv = *(const f32x4*)(bias + kv * 256 + col); f32x4 o;
; #pragma unroll
;                         for (int j = 0; j < 4; ++j) { const float xx = acc[ai][bj][m][n][j] + bv[j]; const float z2 = 2.0f * 0.7978845608028654f * (xx + 0.044715f * xx * xx * xx); const float th = 1.0f - 2.0f * __builtin_amdgcn_rcpf(__expf(z2) + 1.0f); o[j] = 0.5f * xx * (1.0f + th); }
;                         st_bf4(HID + ((size_t)u.z * 1024 + row) * 256 + col, o); } }
	v_add_f32_e32 v60, v60, v66
	v_add_f32_e32 v61, v61, v67
	v_add_f32_e32 v62, v62, v68
	v_add_f32_e32 v63, v63, v69
	v_mul_f32_e32 v66, 0x3d372713, v60
	v_mul_f32_e32 v68, 0x3d372713, v61
	v_mul_f32_e32 v70, 0x3d372713, v62
	v_mul_f32_e32 v72, 0x3d372713, v63
	v_mul_f32_e32 v66, v60, v66
	v_mul_f32_e32 v68, v61, v68
	v_mul_f32_e32 v67, 0.5, v60
	v_mul_f32_e32 v69, 0.5, v61
	v_mul_f32_e32 v70, v62, v70
	v_mul_f32_e32 v72, v63, v72
	v_fma_f32 v60, v60, v66, v60
	v_fma_f32 v61, v61, v68, v61
	v_mul_f32_e32 v71, 0.5, v62
	v_mul_f32_e32 v73, 0.5, v63
	v_fma_f32 v62, v62, v70, v62
	v_fma_f32 v63, v63, v72, v63
	v_mul_f32_e32 v60, 0x3fcc422a, v60
	v_mul_f32_e32 v61, 0x3fcc422a, v61
	v_mul_f32_e32 v62, 0x3fcc422a, v62
	v_mul_f32_e32 v63, 0x3fcc422a, v63
	v_mul_f32_e32 v60, 0x3fb8aa3b, v60
	v_mul_f32_e32 v61, 0x3fb8aa3b, v61
	v_mul_f32_e32 v62, 0x3fb8aa3b, v62
	v_mul_f32_e32 v63, 0x3fb8aa3b, v63
	v_exp_f32_e32 v60, v60
	v_exp_f32_e32 v61, v61
	v_exp_f32_e32 v62, v62
	v_exp_f32_e32 v63, v63
	v_add_f32_e32 v60, 1.0, v60
	v_add_f32_e32 v61, 1.0, v61
	v_add_f32_e32 v62, 1.0, v62
	v_add_f32_e32 v63, 1.0, v63
	v_rcp_f32_e32 v60, v60
	v_rcp_f32_e32 v61, v61
	v_rcp_f32_e32 v62, v62
	v_rcp_f32_e32 v63, v63
	v_fma_f32 v60, v60, -2.0, 1.0
	v_fma_f32 v61, v61, -2.0, 1.0
	v_fma_f32 v62, v62, -2.0, 1.0
	v_fma_f32 v63, v63, -2.0, 1.0
	v_add_f32_e32 v60, 1.0, v60
	v_add_f32_e32 v61, 1.0, v61
	v_add_f32_e32 v62, 1.0, v62
	v_add_f32_e32 v63, 1.0, v63
	v_mul_f32_e32 v60, v67, v60
	v_mul_f32_e32 v61, v69, v61
	v_mul_f32_e32 v62, v71, v62
	v_mul_f32_e32 v63, v73, v63
	v_cvt_pk_bf16_f32 v60, v60, v61
	v_cvt_pk_bf16_f32 v61, v62, v63
	global_store_dwordx2 v[64:65], v[60:61], off
	global_load_dwordx4 v[60:63], v[144:145], off offset:64
	s_waitcnt vmcnt(0)
	v_add_f32_e32 v56, v56, v60
	v_add_f32_e32 v57, v57, v61
	v_add_f32_e32 v58, v58, v62
	v_add_f32_e32 v59, v59, v63
	v_mul_f32_e32 v60, 0x3d372713, v56
	v_mul_f32_e32 v62, 0x3d372713, v57
	v_mul_f32_e32 v66, 0x3d372713, v58
	v_mul_f32_e32 v68, 0x3d372713, v59
	v_mul_f32_e32 v60, v56, v60
	v_mul_f32_e32 v62, v57, v62
	v_mul_f32_e32 v61, 0.5, v56
	v_mul_f32_e32 v63, 0.5, v57
	v_mul_f32_e32 v66, v58, v66
	v_mul_f32_e32 v68, v59, v68
	v_fma_f32 v56, v56, v60, v56
	v_fma_f32 v57, v57, v62, v57
	v_mul_f32_e32 v67, 0.5, v58
	v_mul_f32_e32 v69, 0.5, v59
	v_fma_f32 v58, v58, v66, v58
	v_fma_f32 v59, v59, v68, v59
	v_mul_f32_e32 v56, 0x3fcc422a, v56
	v_mul_f32_e32 v57, 0x3fcc422a, v57
	v_mul_f32_e32 v58, 0x3fcc422a, v58
	v_mul_f32_e32 v59, 0x3fcc422a, v59
	v_mul_f32_e32 v56, 0x3fb8aa3b, v56
	v_mul_f32_e32 v57, 0x3fb8aa3b, v57
	v_mul_f32_e32 v58, 0x3fb8aa3b, v58
	v_mul_f32_e32 v59, 0x3fb8aa3b, v59
	v_exp_f32_e32 v56, v56
	v_exp_f32_e32 v57, v57
	v_exp_f32_e32 v58, v58
	v_exp_f32_e32 v59, v59
	v_add_f32_e32 v56, 1.0, v56
	v_add_f32_e32 v57, 1.0, v57
	v_add_f32_e32 v58, 1.0, v58
	v_add_f32_e32 v59, 1.0, v59
	v_rcp_f32_e32 v56, v56
	v_rcp_f32_e32 v57, v57
	v_rcp_f32_e32 v58, v58
	v_rcp_f32_e32 v59, v59
	v_fma_f32 v56, v56, -2.0, 1.0
	v_fma_f32 v57, v57, -2.0, 1.0
	v_fma_f32 v58, v58, -2.0, 1.0
	v_fma_f32 v59, v59, -2.0, 1.0
	v_add_f32_e32 v56, 1.0, v56
	v_add_f32_e32 v57, 1.0, v57
	v_add_f32_e32 v58, 1.0, v58
	v_add_f32_e32 v59, 1.0, v59
	v_mul_f32_e32 v56, v61, v56
	v_mul_f32_e32 v57, v63, v57
	v_mul_f32_e32 v58, v67, v58
	v_mul_f32_e32 v59, v69, v59
	v_cvt_pk_bf16_f32 v56, v56, v57
	v_cvt_pk_bf16_f32 v57, v58, v59
	global_store_dwordx2 v[64:65], v[56:57], off offset:32
	global_load_dwordx4 v[56:59], v[144:145], off offset:512
	s_waitcnt vmcnt(0)
	v_add_f32_e32 v52, v52, v56
	v_add_f32_e32 v53, v53, v57
	v_add_f32_e32 v54, v54, v58
	v_add_f32_e32 v55, v55, v59
	v_mul_f32_e32 v56, 0x3d372713, v52
	v_mul_f32_e32 v58, 0x3d372713, v53
	v_mul_f32_e32 v60, 0x3d372713, v54
	v_mul_f32_e32 v62, 0x3d372713, v55
	v_mul_f32_e32 v56, v52, v56
	v_mul_f32_e32 v58, v53, v58
	v_mul_f32_e32 v57, 0.5, v52
	v_mul_f32_e32 v59, 0.5, v53
	v_mul_f32_e32 v60, v54, v60
	v_mul_f32_e32 v62, v55, v62
	v_fma_f32 v52, v52, v56, v52
	v_fma_f32 v53, v53, v58, v53
	v_mul_f32_e32 v61, 0.5, v54
	v_mul_f32_e32 v63, 0.5, v55
	v_fma_f32 v54, v54, v60, v54
	v_fma_f32 v55, v55, v62, v55
	v_mul_f32_e32 v52, 0x3fcc422a, v52
	v_mul_f32_e32 v53, 0x3fcc422a, v53
	v_mul_f32_e32 v54, 0x3fcc422a, v54
	v_mul_f32_e32 v55, 0x3fcc422a, v55
	v_mul_f32_e32 v52, 0x3fb8aa3b, v52
	v_mul_f32_e32 v53, 0x3fb8aa3b, v53
	v_mul_f32_e32 v54, 0x3fb8aa3b, v54
	v_mul_f32_e32 v55, 0x3fb8aa3b, v55
	v_exp_f32_e32 v52, v52
	v_exp_f32_e32 v53, v53
	v_exp_f32_e32 v54, v54
	v_exp_f32_e32 v55, v55
	v_add_f32_e32 v52, 1.0, v52
	v_add_f32_e32 v53, 1.0, v53
	v_add_f32_e32 v54, 1.0, v54
	v_add_f32_e32 v55, 1.0, v55
	v_rcp_f32_e32 v52, v52
	v_rcp_f32_e32 v53, v53
	v_rcp_f32_e32 v54, v54
	v_rcp_f32_e32 v55, v55
	v_fma_f32 v52, v52, -2.0, 1.0
	v_fma_f32 v53, v53, -2.0, 1.0
	v_fma_f32 v54, v54, -2.0, 1.0
	v_fma_f32 v55, v55, -2.0, 1.0
	v_add_f32_e32 v52, 1.0, v52
	v_add_f32_e32 v53, 1.0, v53
	v_add_f32_e32 v54, 1.0, v54
	v_add_f32_e32 v55, 1.0, v55
	v_mul_f32_e32 v52, v57, v52
	v_mul_f32_e32 v53, v59, v53
	v_mul_f32_e32 v54, v61, v54
	v_mul_f32_e32 v55, v63, v55
	v_cvt_pk_bf16_f32 v52, v52, v53
	v_cvt_pk_bf16_f32 v53, v54, v55
	global_store_dwordx2 v[64:65], v[52:53], off offset:256
	global_load_dwordx4 v[52:55], v[144:145], off offset:576
	s_waitcnt vmcnt(0)
; __device__ __forceinline__ void st_bf4(bf16_t* p, const f32x4 v) { u32x2 w; w.x = cvt_pk_bf16(v[0], v[1]); w.y = cvt_pk_bf16(v[2], v[3]); *(u32x2*)p = w; }
;     __device__ __forceinline__ void operator()(AccRef acc, const Unit& u, int wr, int wc, int fr, int fq) const {
;     ...
;             for (int m = 0; m < 4; ++m) { const int row = u.pm * 256 + ai * 128 + wr * 64 + m * 16 + fr;
; #pragma unroll
;                 for (int bj = 0; bj < 2; ++bj)
; #pragma unroll
;                     for (int n = 0; n < 2; ++n) { const int col = bj * 128 + wc * 32 + n * 16 + 4 * fq; const f32x4 bv = *(const f32x4*)(bias + kv * 256 + col); f32x4 o;
; #pragma unroll
;                         for (int j = 0; j < 4; ++j) { const float xx = acc[ai][bj][m][n][j] + bv[j]; const float z2 = 2.0f * 0.7978845608028654f * (xx + 0.044715f * xx * xx * xx); const float th = 1.0f - 2.0f * __builtin_amdgcn_rcpf(__expf(z2) + 1.0f); o[j] = 0.5f * xx * (1.0f + th); }
;                         st_bf4(HID + ((size_t)u.z * 1024 + row) * 256 + col, o); } }
	v_add_f32_e32 v48, v48, v52
	v_add_f32_e32 v49, v49, v53
	v_add_f32_e32 v50, v50, v54
	v_add_f32_e32 v51, v51, v55
	v_mul_f32_e32 v52, 0x3d372713, v48
	v_mul_f32_e32 v54, 0x3d372713, v49
	v_mul_f32_e32 v56, 0x3d372713, v50
	v_mul_f32_e32 v58, 0x3d372713, v51
	v_mul_f32_e32 v52, v48, v52
	v_mul_f32_e32 v54, v49, v54
	v_mul_f32_e32 v53, 0.5, v48
	v_mul_f32_e32 v55, 0.5, v49
	v_mul_f32_e32 v56, v50, v56
	v_mul_f32_e32 v58, v51, v58
	v_fma_f32 v48, v48, v52, v48
	v_fma_f32 v49, v49, v54, v49
	v_mul_f32_e32 v57, 0.5, v50
	v_mul_f32_e32 v59, 0.5, v51
	v_fma_f32 v50, v50, v56, v50
	v_fma_f32 v51, v51, v58, v51
	v_mul_f32_e32 v48, 0x3fcc422a, v48
	v_mul_f32_e32 v49, 0x3fcc422a, v49
	v_mul_f32_e32 v50, 0x3fcc422a, v50
	v_mul_f32_e32 v51, 0x3fcc422a, v51
	v_mul_f32_e32 v48, 0x3fb8aa3b, v48
	v_mul_f32_e32 v49, 0x3fb8aa3b, v49
	v_mul_f32_e32 v50, 0x3fb8aa3b, v50
	v_mul_f32_e32 v51, 0x3fb8aa3b, v51
	v_exp_f32_e32 v48, v48
	v_exp_f32_e32 v49, v49
	v_exp_f32_e32 v50, v50
	v_exp_f32_e32 v51, v51
	v_add_f32_e32 v48, 1.0, v48
	v_add_f32_e32 v49, 1.0, v49
	v_add_f32_e32 v50, 1.0, v50
	v_add_f32_e32 v51, 1.0, v51
	v_rcp_f32_e32 v48, v48
	v_rcp_f32_e32 v49, v49
	v_rcp_f32_e32 v50, v50
	v_rcp_f32_e32 v51, v51
	v_fma_f32 v48, v48, -2.0, 1.0
	v_fma_f32 v49, v49, -2.0, 1.0
	v_fma_f32 v50, v50, -2.0, 1.0
	v_fma_f32 v51, v51, -2.0, 1.0
	v_add_f32_e32 v48, 1.0, v48
	v_add_f32_e32 v49, 1.0, v49
	v_add_f32_e32 v50, 1.0, v50
	v_add_f32_e32 v51, 1.0, v51
	v_mul_f32_e32 v48, v53, v48
	v_mul_f32_e32 v49, v55, v49
	v_mul_f32_e32 v50, v57, v50
	v_mul_f32_e32 v51, v59, v51
	v_cvt_pk_bf16_f32 v48, v48, v49
	v_cvt_pk_bf16_f32 v49, v50, v51
	global_store_dwordx2 v[64:65], v[48:49], off offset:288
	global_load_dwordx4 v[50:53], v[144:145], off
	v_add_u32_e32 v48, 0x90, v146
	v_ashrrev_i32_e32 v49, 31, v48
	v_lshlrev_b64 v[48:49], 9, v[48:49]
	v_lshl_add_u64 v[48:49], s[20:21], 0, v[48:49]
	v_lshl_add_u64 v[48:49], v[48:49], 0, v[136:137]
	s_waitcnt vmcnt(0)
	v_add_f32_e32 v44, v44, v50
	v_add_f32_e32 v45, v45, v51
	v_add_f32_e32 v46, v46, v52
	v_add_f32_e32 v47, v47, v53
	v_mul_f32_e32 v50, 0x3d372713, v44
	v_mul_f32_e32 v52, 0x3d372713, v45
	v_mul_f32_e32 v54, 0x3d372713, v46
	v_mul_f32_e32 v56, 0x3d372713, v47
	v_mul_f32_e32 v50, v44, v50
	v_mul_f32_e32 v52, v45, v52
	v_mul_f32_e32 v51, 0.5, v44
	v_mul_f32_e32 v53, 0.5, v45
	v_mul_f32_e32 v54, v46, v54
	v_mul_f32_e32 v56, v47, v56
	v_fma_f32 v44, v44, v50, v44
	v_fma_f32 v45, v45, v52, v45
	v_mul_f32_e32 v55, 0.5, v46
	v_mul_f32_e32 v57, 0.5, v47
	v_fma_f32 v46, v46, v54, v46
	v_fma_f32 v47, v47, v56, v47
	v_mul_f32_e32 v44, 0x3fcc422a, v44
	v_mul_f32_e32 v45, 0x3fcc422a, v45
	v_mul_f32_e32 v46, 0x3fcc422a, v46
	v_mul_f32_e32 v47, 0x3fcc422a, v47
	v_mul_f32_e32 v44, 0x3fb8aa3b, v44
	v_mul_f32_e32 v45, 0x3fb8aa3b, v45
	v_mul_f32_e32 v46, 0x3fb8aa3b, v46
	v_mul_f32_e32 v47, 0x3fb8aa3b, v47
	v_exp_f32_e32 v44, v44
	v_exp_f32_e32 v45, v45
	v_exp_f32_e32 v46, v46
	v_exp_f32_e32 v47, v47
	v_add_f32_e32 v44, 1.0, v44
	v_add_f32_e32 v45, 1.0, v45
	v_add_f32_e32 v46, 1.0, v46
	v_add_f32_e32 v47, 1.0, v47
	v_rcp_f32_e32 v44, v44
	v_rcp_f32_e32 v45, v45
	v_rcp_f32_e32 v46, v46
	v_rcp_f32_e32 v47, v47
	v_fma_f32 v44, v44, -2.0, 1.0
	v_fma_f32 v45, v45, -2.0, 1.0
	v_fma_f32 v46, v46, -2.0, 1.0
	v_fma_f32 v47, v47, -2.0, 1.0
	v_add_f32_e32 v44, 1.0, v44
	v_add_f32_e32 v45, 1.0, v45
	v_add_f32_e32 v46, 1.0, v46
	v_add_f32_e32 v47, 1.0, v47
	v_mul_f32_e32 v44, v51, v44
	v_mul_f32_e32 v45, v53, v45
	v_mul_f32_e32 v46, v55, v46
	v_mul_f32_e32 v47, v57, v47
	v_cvt_pk_bf16_f32 v44, v44, v45
	v_cvt_pk_bf16_f32 v45, v46, v47
	global_store_dwordx2 v[48:49], v[44:45], off
	global_load_dwordx4 v[44:47], v[144:145], off offset:64
	s_waitcnt vmcnt(0)
	v_add_f32_e32 v40, v40, v44
	v_add_f32_e32 v41, v41, v45
	v_add_f32_e32 v42, v42, v46
	v_add_f32_e32 v43, v43, v47
	v_mul_f32_e32 v44, 0x3d372713, v40
	v_mul_f32_e32 v46, 0x3d372713, v41
	v_mul_f32_e32 v50, 0x3d372713, v42
	v_mul_f32_e32 v52, 0x3d372713, v43
	v_mul_f32_e32 v44, v40, v44
	v_mul_f32_e32 v46, v41, v46
	v_mul_f32_e32 v45, 0.5, v40
	v_mul_f32_e32 v47, 0.5, v41
	v_mul_f32_e32 v50, v42, v50
	v_mul_f32_e32 v52, v43, v52
	v_fma_f32 v40, v40, v44, v40
	v_fma_f32 v41, v41, v46, v41
	v_mul_f32_e32 v51, 0.5, v42
	v_mul_f32_e32 v53, 0.5, v43
	v_fma_f32 v42, v42, v50, v42
	v_fma_f32 v43, v43, v52, v43
	v_mul_f32_e32 v40, 0x3fcc422a, v40
	v_mul_f32_e32 v41, 0x3fcc422a, v41
	v_mul_f32_e32 v42, 0x3fcc422a, v42
	v_mul_f32_e32 v43, 0x3fcc422a, v43
	v_mul_f32_e32 v40, 0x3fb8aa3b, v40
	v_mul_f32_e32 v41, 0x3fb8aa3b, v41
	v_mul_f32_e32 v42, 0x3fb8aa3b, v42
	v_mul_f32_e32 v43, 0x3fb8aa3b, v43
	v_exp_f32_e32 v40, v40
	v_exp_f32_e32 v41, v41
	v_exp_f32_e32 v42, v42
	v_exp_f32_e32 v43, v43
	v_add_f32_e32 v40, 1.0, v40
	v_add_f32_e32 v41, 1.0, v41
	v_add_f32_e32 v42, 1.0, v42
	v_add_f32_e32 v43, 1.0, v43
	v_rcp_f32_e32 v40, v40
	v_rcp_f32_e32 v41, v41
	v_rcp_f32_e32 v42, v42
	v_rcp_f32_e32 v43, v43
	v_fma_f32 v40, v40, -2.0, 1.0
	v_fma_f32 v41, v41, -2.0, 1.0
	v_fma_f32 v42, v42, -2.0, 1.0
	v_fma_f32 v43, v43, -2.0, 1.0
	v_add_f32_e32 v40, 1.0, v40
	v_add_f32_e32 v41, 1.0, v41
	v_add_f32_e32 v42, 1.0, v42
	v_add_f32_e32 v43, 1.0, v43
	v_mul_f32_e32 v40, v45, v40
	v_mul_f32_e32 v41, v47, v41
	v_mul_f32_e32 v42, v51, v42
	v_mul_f32_e32 v43, v53, v43
	v_cvt_pk_bf16_f32 v40, v40, v41
	v_cvt_pk_bf16_f32 v41, v42, v43
	global_store_dwordx2 v[48:49], v[40:41], off offset:32
	global_load_dwordx4 v[40:43], v[144:145], off offset:512
	s_waitcnt vmcnt(0)
; __device__ __forceinline__ void st_bf4(bf16_t* p, const f32x4 v) { u32x2 w; w.x = cvt_pk_bf16(v[0], v[1]); w.y = cvt_pk_bf16(v[2], v[3]); *(u32x2*)p = w; }
;     __device__ __forceinline__ void operator()(AccRef acc, const Unit& u, int wr, int wc, int fr, int fq) const {
;     ...
;             for (int m = 0; m < 4; ++m) { const int row = u.pm * 256 + ai * 128 + wr * 64 + m * 16 + fr;
; #pragma unroll
;                 for (int bj = 0; bj < 2; ++bj)
; #pragma unroll
;                     for (int n = 0; n < 2; ++n) { const int col = bj * 128 + wc * 32 + n * 16 + 4 * fq; const f32x4 bv = *(const f32x4*)(bias + kv * 256 + col); f32x4 o;
; #pragma unroll
;                         for (int j = 0; j < 4; ++j) { const float xx = acc[ai][bj][m][n][j] + bv[j]; const float z2 = 2.0f * 0.7978845608028654f * (xx + 0.044715f * xx * xx * xx); const float th = 1.0f - 2.0f * __builtin_amdgcn_rcpf(__expf(z2) + 1.0f); o[j] = 0.5f * xx * (1.0f + th); }
;                         st_bf4(HID + ((size_t)u.z * 1024 + row) * 256 + col, o); } }
	v_add_f32_e32 v36, v36, v40
	v_add_f32_e32 v37, v37, v41
	v_add_f32_e32 v38, v38, v42
	v_add_f32_e32 v39, v39, v43
	v_mul_f32_e32 v40, 0x3d372713, v36
	v_mul_f32_e32 v42, 0x3d372713, v37
	v_mul_f32_e32 v44, 0x3d372713, v38
	v_mul_f32_e32 v46, 0x3d372713, v39
	v_mul_f32_e32 v40, v36, v40
	v_mul_f32_e32 v42, v37, v42
	v_mul_f32_e32 v41, 0.5, v36
	v_mul_f32_e32 v43, 0.5, v37
	v_mul_f32_e32 v44, v38, v44
	v_mul_f32_e32 v46, v39, v46
	v_fma_f32 v36, v36, v40, v36
	v_fma_f32 v37, v37, v42, v37
	v_mul_f32_e32 v45, 0.5, v38
	v_mul_f32_e32 v47, 0.5, v39
	v_fma_f32 v38, v38, v44, v38
	v_fma_f32 v39, v39, v46, v39
	v_mul_f32_e32 v36, 0x3fcc422a, v36
	v_mul_f32_e32 v37, 0x3fcc422a, v37
	v_mul_f32_e32 v38, 0x3fcc422a, v38
	v_mul_f32_e32 v39, 0x3fcc422a, v39
	v_mul_f32_e32 v36, 0x3fb8aa3b, v36
	v_mul_f32_e32 v37, 0x3fb8aa3b, v37
	v_mul_f32_e32 v38, 0x3fb8aa3b, v38
	v_mul_f32_e32 v39, 0x3fb8aa3b, v39
	v_exp_f32_e32 v36, v36
	v_exp_f32_e32 v37, v37
	v_exp_f32_e32 v38, v38
	v_exp_f32_e32 v39, v39
	v_add_f32_e32 v36, 1.0, v36
	v_add_f32_e32 v37, 1.0, v37
	v_add_f32_e32 v38, 1.0, v38
	v_add_f32_e32 v39, 1.0, v39
	v_rcp_f32_e32 v36, v36
	v_rcp_f32_e32 v37, v37
	v_rcp_f32_e32 v38, v38
	v_rcp_f32_e32 v39, v39
	v_fma_f32 v36, v36, -2.0, 1.0
	v_fma_f32 v37, v37, -2.0, 1.0
	v_fma_f32 v38, v38, -2.0, 1.0
	v_fma_f32 v39, v39, -2.0, 1.0
	v_add_f32_e32 v36, 1.0, v36
	v_add_f32_e32 v37, 1.0, v37
	v_add_f32_e32 v38, 1.0, v38
	v_add_f32_e32 v39, 1.0, v39
	v_mul_f32_e32 v36, v41, v36
	v_mul_f32_e32 v37, v43, v37
	v_mul_f32_e32 v38, v45, v38
	v_mul_f32_e32 v39, v47, v39
	v_cvt_pk_bf16_f32 v36, v36, v37
	v_cvt_pk_bf16_f32 v37, v38, v39
	global_store_dwordx2 v[48:49], v[36:37], off offset:256
	global_load_dwordx4 v[36:39], v[144:145], off offset:576
	s_waitcnt vmcnt(0)
	v_add_f32_e32 v32, v32, v36
	v_add_f32_e32 v33, v33, v37
	v_add_f32_e32 v34, v34, v38
	v_add_f32_e32 v35, v35, v39
	v_mul_f32_e32 v36, 0x3d372713, v32
	v_mul_f32_e32 v38, 0x3d372713, v33
	v_mul_f32_e32 v40, 0x3d372713, v34
	v_mul_f32_e32 v42, 0x3d372713, v35
	v_mul_f32_e32 v36, v32, v36
	v_mul_f32_e32 v38, v33, v38
	v_mul_f32_e32 v37, 0.5, v32
	v_mul_f32_e32 v39, 0.5, v33
	v_mul_f32_e32 v40, v34, v40
	v_mul_f32_e32 v42, v35, v42
	v_fma_f32 v32, v32, v36, v32
	v_fma_f32 v33, v33, v38, v33
	v_mul_f32_e32 v41, 0.5, v34
	v_mul_f32_e32 v43, 0.5, v35
	v_fma_f32 v34, v34, v40, v34
	v_fma_f32 v35, v35, v42, v35
	v_mul_f32_e32 v32, 0x3fcc422a, v32
	v_mul_f32_e32 v33, 0x3fcc422a, v33
	v_mul_f32_e32 v34, 0x3fcc422a, v34
	v_mul_f32_e32 v35, 0x3fcc422a, v35
	v_mul_f32_e32 v32, 0x3fb8aa3b, v32
	v_mul_f32_e32 v33, 0x3fb8aa3b, v33
	v_mul_f32_e32 v34, 0x3fb8aa3b, v34
	v_mul_f32_e32 v35, 0x3fb8aa3b, v35
	v_exp_f32_e32 v32, v32
	v_exp_f32_e32 v33, v33
	v_exp_f32_e32 v34, v34
	v_exp_f32_e32 v35, v35
	v_add_f32_e32 v32, 1.0, v32
	v_add_f32_e32 v33, 1.0, v33
	v_add_f32_e32 v34, 1.0, v34
	v_add_f32_e32 v35, 1.0, v35
	v_rcp_f32_e32 v32, v32
	v_rcp_f32_e32 v33, v33
	v_rcp_f32_e32 v34, v34
	v_rcp_f32_e32 v35, v35
	v_fma_f32 v32, v32, -2.0, 1.0
	v_fma_f32 v33, v33, -2.0, 1.0
	v_fma_f32 v34, v34, -2.0, 1.0
	v_fma_f32 v35, v35, -2.0, 1.0
	v_add_f32_e32 v32, 1.0, v32
	v_add_f32_e32 v33, 1.0, v33
	v_add_f32_e32 v34, 1.0, v34
	v_add_f32_e32 v35, 1.0, v35
	v_mul_f32_e32 v32, v37, v32
	v_mul_f32_e32 v33, v39, v33
	v_mul_f32_e32 v34, v41, v34
	v_mul_f32_e32 v35, v43, v35
	v_cvt_pk_bf16_f32 v32, v32, v33
	v_cvt_pk_bf16_f32 v33, v34, v35
	global_store_dwordx2 v[48:49], v[32:33], off offset:288
	global_load_dwordx4 v[34:37], v[144:145], off
	v_add_u32_e32 v32, 0xa0, v146
	v_ashrrev_i32_e32 v33, 31, v32
	v_lshlrev_b64 v[32:33], 9, v[32:33]
	v_lshl_add_u64 v[32:33], s[20:21], 0, v[32:33]
	v_lshl_add_u64 v[32:33], v[32:33], 0, v[136:137]
	s_waitcnt vmcnt(0)
	v_add_f32_e32 v28, v28, v34
	v_add_f32_e32 v29, v29, v35
	v_add_f32_e32 v30, v30, v36
	v_add_f32_e32 v31, v31, v37
	v_mul_f32_e32 v34, 0x3d372713, v28
	v_mul_f32_e32 v36, 0x3d372713, v29
	v_mul_f32_e32 v38, 0x3d372713, v30
	v_mul_f32_e32 v40, 0x3d372713, v31
	v_mul_f32_e32 v34, v28, v34
	v_mul_f32_e32 v36, v29, v36
	v_mul_f32_e32 v35, 0.5, v28
	v_mul_f32_e32 v37, 0.5, v29
	v_mul_f32_e32 v38, v30, v38
	v_mul_f32_e32 v40, v31, v40
	v_fma_f32 v28, v28, v34, v28
	v_fma_f32 v29, v29, v36, v29
	v_mul_f32_e32 v39, 0.5, v30
	v_mul_f32_e32 v41, 0.5, v31
	v_fma_f32 v30, v30, v38, v30
	v_fma_f32 v31, v31, v40, v31
	v_mul_f32_e32 v28, 0x3fcc422a, v28
	v_mul_f32_e32 v29, 0x3fcc422a, v29
	v_mul_f32_e32 v30, 0x3fcc422a, v30
	v_mul_f32_e32 v31, 0x3fcc422a, v31
	v_mul_f32_e32 v28, 0x3fb8aa3b, v28
	v_mul_f32_e32 v29, 0x3fb8aa3b, v29
	v_mul_f32_e32 v30, 0x3fb8aa3b, v30
	v_mul_f32_e32 v31, 0x3fb8aa3b, v31
	v_exp_f32_e32 v28, v28
	v_exp_f32_e32 v29, v29
	v_exp_f32_e32 v30, v30
	v_exp_f32_e32 v31, v31
	v_add_f32_e32 v28, 1.0, v28
	v_add_f32_e32 v29, 1.0, v29
	v_add_f32_e32 v30, 1.0, v30
	v_add_f32_e32 v31, 1.0, v31
	v_rcp_f32_e32 v28, v28
	v_rcp_f32_e32 v29, v29
	v_rcp_f32_e32 v30, v30
	v_rcp_f32_e32 v31, v31
	v_fma_f32 v28, v28, -2.0, 1.0
	v_fma_f32 v29, v29, -2.0, 1.0
	v_fma_f32 v30, v30, -2.0, 1.0
	v_fma_f32 v31, v31, -2.0, 1.0
	v_add_f32_e32 v28, 1.0, v28
	v_add_f32_e32 v29, 1.0, v29
	v_add_f32_e32 v30, 1.0, v30
	v_add_f32_e32 v31, 1.0, v31
	v_mul_f32_e32 v28, v35, v28
	v_mul_f32_e32 v29, v37, v29
	v_mul_f32_e32 v30, v39, v30
	v_mul_f32_e32 v31, v41, v31
	v_cvt_pk_bf16_f32 v28, v28, v29
	v_cvt_pk_bf16_f32 v29, v30, v31
	global_store_dwordx2 v[32:33], v[28:29], off
	global_load_dwordx4 v[28:31], v[144:145], off offset:64
	s_waitcnt vmcnt(0)
; __device__ __forceinline__ void st_bf4(bf16_t* p, const f32x4 v) { u32x2 w; w.x = cvt_pk_bf16(v[0], v[1]); w.y = cvt_pk_bf16(v[2], v[3]); *(u32x2*)p = w; }
;     __device__ __forceinline__ void operator()(AccRef acc, const Unit& u, int wr, int wc, int fr, int fq) const {
;     ...
;             for (int m = 0; m < 4; ++m) { const int row = u.pm * 256 + ai * 128 + wr * 64 + m * 16 + fr;
; #pragma unroll
;                 for (int bj = 0; bj < 2; ++bj)
; #pragma unroll
;                     for (int n = 0; n < 2; ++n) { const int col = bj * 128 + wc * 32 + n * 16 + 4 * fq; const f32x4 bv = *(const f32x4*)(bias + kv * 256 + col); f32x4 o;
; #pragma unroll
;                         for (int j = 0; j < 4; ++j) { const float xx = acc[ai][bj][m][n][j] + bv[j]; const float z2 = 2.0f * 0.7978845608028654f * (xx + 0.044715f * xx * xx * xx); const float th = 1.0f - 2.0f * __builtin_amdgcn_rcpf(__expf(z2) + 1.0f); o[j] = 0.5f * xx * (1.0f + th); }
;                         st_bf4(HID + ((size_t)u.z * 1024 + row) * 256 + col, o); } }
	v_add_f32_e32 v24, v24, v28
	v_add_f32_e32 v25, v25, v29
	v_add_f32_e32 v26, v26, v30
	v_add_f32_e32 v27, v27, v31
	v_mul_f32_e32 v28, 0x3d372713, v24
	v_mul_f32_e32 v30, 0x3d372713, v25
	v_mul_f32_e32 v34, 0x3d372713, v26
	v_mul_f32_e32 v36, 0x3d372713, v27
	v_mul_f32_e32 v28, v24, v28
	v_mul_f32_e32 v30, v25, v30
	v_mul_f32_e32 v29, 0.5, v24
	v_mul_f32_e32 v31, 0.5, v25
	v_mul_f32_e32 v34, v26, v34
	v_mul_f32_e32 v36, v27, v36
	v_fma_f32 v24, v24, v28, v24
	v_fma_f32 v25, v25, v30, v25
	v_mul_f32_e32 v35, 0.5, v26
	v_mul_f32_e32 v37, 0.5, v27
	v_fma_f32 v26, v26, v34, v26
	v_fma_f32 v27, v27, v36, v27
	v_mul_f32_e32 v24, 0x3fcc422a, v24
	v_mul_f32_e32 v25, 0x3fcc422a, v25
	v_mul_f32_e32 v26, 0x3fcc422a, v26
	v_mul_f32_e32 v27, 0x3fcc422a, v27
	v_mul_f32_e32 v24, 0x3fb8aa3b, v24
	v_mul_f32_e32 v25, 0x3fb8aa3b, v25
	v_mul_f32_e32 v26, 0x3fb8aa3b, v26
	v_mul_f32_e32 v27, 0x3fb8aa3b, v27
	v_exp_f32_e32 v24, v24
	v_exp_f32_e32 v25, v25
	v_exp_f32_e32 v26, v26
	v_exp_f32_e32 v27, v27
	v_add_f32_e32 v24, 1.0, v24
	v_add_f32_e32 v25, 1.0, v25
	v_add_f32_e32 v26, 1.0, v26
	v_add_f32_e32 v27, 1.0, v27
	v_rcp_f32_e32 v24, v24
	v_rcp_f32_e32 v25, v25
	v_rcp_f32_e32 v26, v26
	v_rcp_f32_e32 v27, v27
	v_fma_f32 v24, v24, -2.0, 1.0
	v_fma_f32 v25, v25, -2.0, 1.0
	v_fma_f32 v26, v26, -2.0, 1.0
	v_fma_f32 v27, v27, -2.0, 1.0
	v_add_f32_e32 v24, 1.0, v24
	v_add_f32_e32 v25, 1.0, v25
	v_add_f32_e32 v26, 1.0, v26
	v_add_f32_e32 v27, 1.0, v27
	v_mul_f32_e32 v24, v29, v24
	v_mul_f32_e32 v25, v31, v25
	v_mul_f32_e32 v26, v35, v26
	v_mul_f32_e32 v27, v37, v27
	v_cvt_pk_bf16_f32 v24, v24, v25
	v_cvt_pk_bf16_f32 v25, v26, v27
	global_store_dwordx2 v[32:33], v[24:25], off offset:32
	global_load_dwordx4 v[24:27], v[144:145], off offset:512
	s_waitcnt vmcnt(0)
	v_add_f32_e32 v20, v20, v24
	v_add_f32_e32 v21, v21, v25
	v_add_f32_e32 v22, v22, v26
	v_add_f32_e32 v23, v23, v27
	v_mul_f32_e32 v24, 0x3d372713, v20
	v_mul_f32_e32 v26, 0x3d372713, v21
	v_mul_f32_e32 v28, 0x3d372713, v22
	v_mul_f32_e32 v30, 0x3d372713, v23
	v_mul_f32_e32 v24, v20, v24
	v_mul_f32_e32 v26, v21, v26
	v_mul_f32_e32 v25, 0.5, v20
	v_mul_f32_e32 v27, 0.5, v21
	v_mul_f32_e32 v28, v22, v28
	v_mul_f32_e32 v30, v23, v30
	v_fma_f32 v20, v20, v24, v20
	v_fma_f32 v21, v21, v26, v21
	v_mul_f32_e32 v29, 0.5, v22
	v_mul_f32_e32 v31, 0.5, v23
	v_fma_f32 v22, v22, v28, v22
	v_fma_f32 v23, v23, v30, v23
	v_mul_f32_e32 v20, 0x3fcc422a, v20
	v_mul_f32_e32 v21, 0x3fcc422a, v21
	v_mul_f32_e32 v22, 0x3fcc422a, v22
	v_mul_f32_e32 v23, 0x3fcc422a, v23
	v_mul_f32_e32 v20, 0x3fb8aa3b, v20
	v_mul_f32_e32 v21, 0x3fb8aa3b, v21
	v_mul_f32_e32 v22, 0x3fb8aa3b, v22
	v_mul_f32_e32 v23, 0x3fb8aa3b, v23
	v_exp_f32_e32 v20, v20
	v_exp_f32_e32 v21, v21
	v_exp_f32_e32 v22, v22
	v_exp_f32_e32 v23, v23
	v_add_f32_e32 v20, 1.0, v20
	v_add_f32_e32 v21, 1.0, v21
	v_add_f32_e32 v22, 1.0, v22
	v_add_f32_e32 v23, 1.0, v23
	v_rcp_f32_e32 v20, v20
	v_rcp_f32_e32 v21, v21
	v_rcp_f32_e32 v22, v22
	v_rcp_f32_e32 v23, v23
	v_fma_f32 v20, v20, -2.0, 1.0
	v_fma_f32 v21, v21, -2.0, 1.0
	v_fma_f32 v22, v22, -2.0, 1.0
	v_fma_f32 v23, v23, -2.0, 1.0
	v_add_f32_e32 v20, 1.0, v20
	v_add_f32_e32 v21, 1.0, v21
	v_add_f32_e32 v22, 1.0, v22
	v_add_f32_e32 v23, 1.0, v23
	v_mul_f32_e32 v20, v25, v20
	v_mul_f32_e32 v21, v27, v21
	v_mul_f32_e32 v22, v29, v22
	v_mul_f32_e32 v23, v31, v23
	v_cvt_pk_bf16_f32 v20, v20, v21
	v_cvt_pk_bf16_f32 v21, v22, v23
	global_store_dwordx2 v[32:33], v[20:21], off offset:256
	global_load_dwordx4 v[20:23], v[144:145], off offset:576
	s_waitcnt vmcnt(0)
	v_add_f32_e32 v16, v16, v20
	v_add_f32_e32 v17, v17, v21
	v_add_f32_e32 v18, v18, v22
	v_add_f32_e32 v19, v19, v23
	v_mul_f32_e32 v20, 0x3d372713, v16
	v_mul_f32_e32 v22, 0x3d372713, v17
	v_mul_f32_e32 v24, 0x3d372713, v18
	v_mul_f32_e32 v26, 0x3d372713, v19
	v_mul_f32_e32 v20, v16, v20
	v_mul_f32_e32 v22, v17, v22
	v_mul_f32_e32 v21, 0.5, v16
	v_mul_f32_e32 v23, 0.5, v17
	v_mul_f32_e32 v24, v18, v24
	v_mul_f32_e32 v26, v19, v26
	v_fma_f32 v16, v16, v20, v16
	v_fma_f32 v17, v17, v22, v17
	v_mul_f32_e32 v25, 0.5, v18
	v_mul_f32_e32 v27, 0.5, v19
	v_fma_f32 v18, v18, v24, v18
	v_fma_f32 v19, v19, v26, v19
	v_mul_f32_e32 v16, 0x3fcc422a, v16
	v_mul_f32_e32 v17, 0x3fcc422a, v17
	v_mul_f32_e32 v18, 0x3fcc422a, v18
	v_mul_f32_e32 v19, 0x3fcc422a, v19
	v_mul_f32_e32 v16, 0x3fb8aa3b, v16
	v_mul_f32_e32 v17, 0x3fb8aa3b, v17
	v_mul_f32_e32 v18, 0x3fb8aa3b, v18
	v_mul_f32_e32 v19, 0x3fb8aa3b, v19
	v_exp_f32_e32 v16, v16
	v_exp_f32_e32 v17, v17
	v_exp_f32_e32 v18, v18
	v_exp_f32_e32 v19, v19
	v_add_f32_e32 v16, 1.0, v16
	v_add_f32_e32 v17, 1.0, v17
	v_add_f32_e32 v18, 1.0, v18
	v_add_f32_e32 v19, 1.0, v19
	v_rcp_f32_e32 v16, v16
	v_rcp_f32_e32 v17, v17
	v_rcp_f32_e32 v18, v18
	v_rcp_f32_e32 v19, v19
	v_fma_f32 v16, v16, -2.0, 1.0
	v_fma_f32 v17, v17, -2.0, 1.0
	v_fma_f32 v18, v18, -2.0, 1.0
	v_fma_f32 v19, v19, -2.0, 1.0
	v_add_f32_e32 v16, 1.0, v16
	v_add_f32_e32 v17, 1.0, v17
	v_add_f32_e32 v18, 1.0, v18
	v_add_f32_e32 v19, 1.0, v19
	v_mul_f32_e32 v16, v21, v16
	v_mul_f32_e32 v17, v23, v17
	v_mul_f32_e32 v18, v25, v18
	v_mul_f32_e32 v19, v27, v19
	v_cvt_pk_bf16_f32 v16, v16, v17
	v_cvt_pk_bf16_f32 v17, v18, v19
	global_store_dwordx2 v[32:33], v[16:17], off offset:288
	global_load_dwordx4 v[18:21], v[144:145], off
	v_add_u32_e32 v16, 0xb0, v146
	v_ashrrev_i32_e32 v17, 31, v16
	v_lshlrev_b64 v[16:17], 9, v[16:17]
	v_lshl_add_u64 v[16:17], s[20:21], 0, v[16:17]
	v_lshl_add_u64 v[16:17], v[16:17], 0, v[136:137]
	s_mov_b32 s20, s8
	s_waitcnt vmcnt(0)
; #define PG8_WAIT_V(n) asm volatile("s_waitcnt vmcnt(" #n ")" ::: "memory")
; #define PG8_BAR __builtin_amdgcn_s_barrier()
; __device__ __forceinline__ void st_bf4(bf16_t* p, const f32x4 v) { u32x2 w; w.x = cvt_pk_bf16(v[0], v[1]); w.y = cvt_pk_bf16(v[2], v[3]); *(u32x2*)p = w; }
; template <class Epi>
; __device__ __forceinline__ void gemm_phase(LAS unsigned char* lds, const Gemm g, const Sched& S, const Epi& E) {
;     ...
;         if (!has_next) break;
; #pragma unroll
;         for (int a = 0; a < 2; ++a)
; #pragma unroll
;             for (int b = 0; b < 2; ++b)
; #pragma unroll
;                 for (int m = 0; m < 4; ++m)
; #pragma unroll
;                     for (int n = 0; n < 2; ++n) acc[a][b][m][n] = (f32x4){0.f, 0.f, 0.f, 0.f};
;         cur = nxt; cA = nA; cB = nB; ++ui;
;     }
;     PG8_WAIT_V(0);
;     if (wr == 0) PG8_BAR;
;     PG8_BAR;
;     __device__ __forceinline__ void operator()(AccRef acc, const Unit& u, int wr, int wc, int fr, int fq) const {
;     ...
;             for (int m = 0; m < 4; ++m) { const int row = u.pm * 256 + ai * 128 + wr * 64 + m * 16 + fr;
; #pragma unroll
;                 for (int bj = 0; bj < 2; ++bj)
; #pragma unroll
;                     for (int n = 0; n < 2; ++n) { const int col = bj * 128 + wc * 32 + n * 16 + 4 * fq; const f32x4 bv = *(const f32x4*)(bias + kv * 256 + col); f32x4 o;
; #pragma unroll
;                         for (int j = 0; j < 4; ++j) { const float xx = acc[ai][bj][m][n][j] + bv[j]; const float z2 = 2.0f * 0.7978845608028654f * (xx + 0.044715f * xx * xx * xx); const float th = 1.0f - 2.0f * __builtin_amdgcn_rcpf(__expf(z2) + 1.0f); o[j] = 0.5f * xx * (1.0f + th); }
;                         st_bf4(HID + ((size_t)u.z * 1024 + row) * 256 + col, o); } }
	v_add_f32_e32 v12, v12, v18
	v_add_f32_e32 v13, v13, v19
	v_add_f32_e32 v14, v14, v20
	v_add_f32_e32 v15, v15, v21
	v_mul_f32_e32 v18, 0x3d372713, v12
	v_mul_f32_e32 v20, 0x3d372713, v13
	v_mul_f32_e32 v22, 0x3d372713, v14
	v_mul_f32_e32 v24, 0x3d372713, v15
	v_mul_f32_e32 v18, v12, v18
	v_mul_f32_e32 v20, v13, v20
	v_mul_f32_e32 v19, 0.5, v12
	v_mul_f32_e32 v21, 0.5, v13
	v_mul_f32_e32 v22, v14, v22
	v_mul_f32_e32 v24, v15, v24
	v_fma_f32 v12, v12, v18, v12
	v_fma_f32 v13, v13, v20, v13
	v_mul_f32_e32 v23, 0.5, v14
	v_mul_f32_e32 v25, 0.5, v15
	v_fma_f32 v14, v14, v22, v14
	v_fma_f32 v15, v15, v24, v15
	v_mul_f32_e32 v12, 0x3fcc422a, v12
	v_mul_f32_e32 v13, 0x3fcc422a, v13
	v_mul_f32_e32 v14, 0x3fcc422a, v14
	v_mul_f32_e32 v15, 0x3fcc422a, v15
	v_mul_f32_e32 v12, 0x3fb8aa3b, v12
	v_mul_f32_e32 v13, 0x3fb8aa3b, v13
	v_mul_f32_e32 v14, 0x3fb8aa3b, v14
	v_mul_f32_e32 v15, 0x3fb8aa3b, v15
	v_exp_f32_e32 v12, v12
	v_exp_f32_e32 v13, v13
	v_exp_f32_e32 v14, v14
	v_exp_f32_e32 v15, v15
	v_add_f32_e32 v12, 1.0, v12
	v_add_f32_e32 v13, 1.0, v13
	v_add_f32_e32 v14, 1.0, v14
	v_add_f32_e32 v15, 1.0, v15
	v_rcp_f32_e32 v12, v12
	v_rcp_f32_e32 v13, v13
	v_rcp_f32_e32 v14, v14
	v_rcp_f32_e32 v15, v15
	v_fma_f32 v12, v12, -2.0, 1.0
	v_fma_f32 v13, v13, -2.0, 1.0
	v_fma_f32 v14, v14, -2.0, 1.0
	v_fma_f32 v15, v15, -2.0, 1.0
	v_add_f32_e32 v12, 1.0, v12
	v_add_f32_e32 v13, 1.0, v13
	v_add_f32_e32 v14, 1.0, v14
	v_add_f32_e32 v15, 1.0, v15
	v_mul_f32_e32 v12, v19, v12
	v_mul_f32_e32 v13, v21, v13
	v_mul_f32_e32 v14, v23, v14
	v_mul_f32_e32 v15, v25, v15
	v_cvt_pk_bf16_f32 v12, v12, v13
	v_cvt_pk_bf16_f32 v13, v14, v15
	global_store_dwordx2 v[16:17], v[12:13], off
	global_load_dwordx4 v[12:15], v[144:145], off offset:64
	s_waitcnt vmcnt(0)
	v_add_f32_e32 v8, v8, v12
	v_add_f32_e32 v9, v9, v13
	v_add_f32_e32 v10, v10, v14
	v_add_f32_e32 v11, v11, v15
	v_mul_f32_e32 v12, 0x3d372713, v8
	v_mul_f32_e32 v14, 0x3d372713, v9
	v_mul_f32_e32 v18, 0x3d372713, v10
	v_mul_f32_e32 v20, 0x3d372713, v11
	v_mul_f32_e32 v12, v8, v12
	v_mul_f32_e32 v14, v9, v14
	v_mul_f32_e32 v13, 0.5, v8
	v_mul_f32_e32 v15, 0.5, v9
	v_mul_f32_e32 v18, v10, v18
	v_mul_f32_e32 v20, v11, v20
	v_fma_f32 v8, v8, v12, v8
	v_fma_f32 v9, v9, v14, v9
	v_mul_f32_e32 v19, 0.5, v10
	v_mul_f32_e32 v21, 0.5, v11
	v_fma_f32 v10, v10, v18, v10
	v_fma_f32 v11, v11, v20, v11
	v_mul_f32_e32 v8, 0x3fcc422a, v8
	v_mul_f32_e32 v9, 0x3fcc422a, v9
	v_mul_f32_e32 v10, 0x3fcc422a, v10
	v_mul_f32_e32 v11, 0x3fcc422a, v11
	v_mul_f32_e32 v8, 0x3fb8aa3b, v8
	v_mul_f32_e32 v9, 0x3fb8aa3b, v9
	v_mul_f32_e32 v10, 0x3fb8aa3b, v10
	v_mul_f32_e32 v11, 0x3fb8aa3b, v11
	v_exp_f32_e32 v8, v8
	v_exp_f32_e32 v9, v9
	v_exp_f32_e32 v10, v10
	v_exp_f32_e32 v11, v11
	v_add_f32_e32 v8, 1.0, v8
	v_add_f32_e32 v9, 1.0, v9
	v_add_f32_e32 v10, 1.0, v10
	v_add_f32_e32 v11, 1.0, v11
	v_rcp_f32_e32 v8, v8
	v_rcp_f32_e32 v9, v9
	v_rcp_f32_e32 v10, v10
	v_rcp_f32_e32 v11, v11
	v_fma_f32 v8, v8, -2.0, 1.0
	v_fma_f32 v9, v9, -2.0, 1.0
	v_fma_f32 v10, v10, -2.0, 1.0
	v_fma_f32 v11, v11, -2.0, 1.0
	v_add_f32_e32 v8, 1.0, v8
	v_add_f32_e32 v9, 1.0, v9
	v_add_f32_e32 v10, 1.0, v10
	v_add_f32_e32 v11, 1.0, v11
	v_mul_f32_e32 v8, v13, v8
	v_mul_f32_e32 v9, v15, v9
	v_mul_f32_e32 v10, v19, v10
	v_mul_f32_e32 v11, v21, v11
	v_cvt_pk_bf16_f32 v8, v8, v9
	v_cvt_pk_bf16_f32 v9, v10, v11
	global_store_dwordx2 v[16:17], v[8:9], off offset:32
	global_load_dwordx4 v[8:11], v[144:145], off offset:512
	s_waitcnt vmcnt(0)
	v_add_f32_e32 v4, v4, v8
	v_add_f32_e32 v5, v5, v9
	v_add_f32_e32 v6, v6, v10
	v_add_f32_e32 v7, v7, v11
	v_mul_f32_e32 v8, 0x3d372713, v4
	v_mul_f32_e32 v10, 0x3d372713, v5
	v_mul_f32_e32 v12, 0x3d372713, v6
	v_mul_f32_e32 v14, 0x3d372713, v7
	v_mul_f32_e32 v8, v4, v8
	v_mul_f32_e32 v10, v5, v10
	v_mul_f32_e32 v9, 0.5, v4
	v_mul_f32_e32 v11, 0.5, v5
	v_mul_f32_e32 v12, v6, v12
	v_mul_f32_e32 v14, v7, v14
	v_fma_f32 v4, v4, v8, v4
	v_fma_f32 v5, v5, v10, v5
	v_mul_f32_e32 v13, 0.5, v6
	v_mul_f32_e32 v15, 0.5, v7
	v_fma_f32 v6, v6, v12, v6
	v_fma_f32 v7, v7, v14, v7
	v_mul_f32_e32 v4, 0x3fcc422a, v4
	v_mul_f32_e32 v5, 0x3fcc422a, v5
	v_mul_f32_e32 v6, 0x3fcc422a, v6
	v_mul_f32_e32 v7, 0x3fcc422a, v7
	v_mul_f32_e32 v4, 0x3fb8aa3b, v4
	v_mul_f32_e32 v5, 0x3fb8aa3b, v5
	v_mul_f32_e32 v6, 0x3fb8aa3b, v6
	v_mul_f32_e32 v7, 0x3fb8aa3b, v7
	v_exp_f32_e32 v4, v4
	v_exp_f32_e32 v5, v5
	v_exp_f32_e32 v6, v6
	v_exp_f32_e32 v7, v7
	v_add_f32_e32 v4, 1.0, v4
	v_add_f32_e32 v5, 1.0, v5
	v_add_f32_e32 v6, 1.0, v6
	v_add_f32_e32 v7, 1.0, v7
	v_rcp_f32_e32 v4, v4
	v_rcp_f32_e32 v5, v5
	v_rcp_f32_e32 v6, v6
	v_rcp_f32_e32 v7, v7
	v_fma_f32 v4, v4, -2.0, 1.0
	v_fma_f32 v5, v5, -2.0, 1.0
	v_fma_f32 v6, v6, -2.0, 1.0
	v_fma_f32 v7, v7, -2.0, 1.0
	v_add_f32_e32 v4, 1.0, v4
	v_add_f32_e32 v5, 1.0, v5
	v_add_f32_e32 v6, 1.0, v6
	v_add_f32_e32 v7, 1.0, v7
	v_mul_f32_e32 v4, v9, v4
	v_mul_f32_e32 v5, v11, v5
	v_mul_f32_e32 v6, v13, v6
	v_mul_f32_e32 v7, v15, v7
	v_cvt_pk_bf16_f32 v4, v4, v5
	v_cvt_pk_bf16_f32 v5, v6, v7
	global_store_dwordx2 v[16:17], v[4:5], off offset:256
	global_load_dwordx4 v[4:7], v[144:145], off offset:576
	s_waitcnt vmcnt(0)
	v_add_f32_e32 v0, v0, v4
	v_add_f32_e32 v1, v1, v5
	v_add_f32_e32 v2, v2, v6
	v_add_f32_e32 v3, v3, v7
	v_mul_f32_e32 v4, 0x3d372713, v0
	v_mul_f32_e32 v6, 0x3d372713, v1
	v_mul_f32_e32 v8, 0x3d372713, v2
	v_mul_f32_e32 v10, 0x3d372713, v3
	v_mul_f32_e32 v4, v0, v4
	v_mul_f32_e32 v6, v1, v6
	v_mul_f32_e32 v5, 0.5, v0
	v_mul_f32_e32 v7, 0.5, v1
	v_mul_f32_e32 v8, v2, v8
	v_mul_f32_e32 v10, v3, v10
	v_fma_f32 v0, v0, v4, v0
	v_fma_f32 v1, v1, v6, v1
	v_mul_f32_e32 v9, 0.5, v2
	v_mul_f32_e32 v11, 0.5, v3
	v_fma_f32 v2, v2, v8, v2
	v_fma_f32 v3, v3, v10, v3
	v_mul_f32_e32 v0, 0x3fcc422a, v0
	v_mul_f32_e32 v1, 0x3fcc422a, v1
	v_mul_f32_e32 v2, 0x3fcc422a, v2
	v_mul_f32_e32 v3, 0x3fcc422a, v3
	v_mul_f32_e32 v0, 0x3fb8aa3b, v0
	v_mul_f32_e32 v1, 0x3fb8aa3b, v1
	v_mul_f32_e32 v2, 0x3fb8aa3b, v2
	v_mul_f32_e32 v3, 0x3fb8aa3b, v3
	v_exp_f32_e32 v0, v0
	v_exp_f32_e32 v1, v1
	v_exp_f32_e32 v2, v2
	v_exp_f32_e32 v3, v3
	v_add_f32_e32 v0, 1.0, v0
	v_add_f32_e32 v1, 1.0, v1
	v_add_f32_e32 v2, 1.0, v2
	v_add_f32_e32 v3, 1.0, v3
	v_rcp_f32_e32 v0, v0
	v_rcp_f32_e32 v1, v1
	v_rcp_f32_e32 v2, v2
	v_rcp_f32_e32 v3, v3
	v_fma_f32 v0, v0, -2.0, 1.0
	v_fma_f32 v1, v1, -2.0, 1.0
	v_fma_f32 v2, v2, -2.0, 1.0
	v_fma_f32 v3, v3, -2.0, 1.0
	v_add_f32_e32 v0, 1.0, v0
	v_add_f32_e32 v1, 1.0, v1
	v_add_f32_e32 v2, 1.0, v2
	v_add_f32_e32 v3, 1.0, v3
	v_mul_f32_e32 v0, v5, v0
	v_mul_f32_e32 v1, v7, v1
	v_mul_f32_e32 v2, v9, v2
	v_mul_f32_e32 v3, v11, v3
	v_cvt_pk_bf16_f32 v0, v0, v1
	v_cvt_pk_bf16_f32 v1, v2, v3
	global_store_dwordx2 v[16:17], v[0:1], off offset:288
	s_cbranch_vccz .LBB0_492
	s_waitcnt vmcnt(0)
	s_cmpk_gt_u32 s33, 0xff
	s_cbranch_scc1 .LBB0_501
	s_barrier

; #define PG8_STAGE(bufoff, gbase, voff) do { _Pragma("unroll") for (int _i = 0; _i < 2; ++_i) \
;         __builtin_amdgcn_global_load_lds((const unsigned*)((const char*)(gbase) + (voff)[_i]), (LAS unsigned*)(lds + (bufoff) + ldsw + _i * 8192), 16, 0, 0); } while (0)
; #define PG8_LDA(dst, b, h) do { _Pragma("unroll") for (int m = 0; m < 4; ++m) _Pragma("unroll") for (int k = 0; k < 2; ++k) dst[m][k] = *(const LAS bf16x8*)(lds + PG8_SA(b, h) + aoff + m * 2048 + k * 1024); } while (0)
; #define PG8_LDB(dst, b, h) do { _Pragma("unroll") for (int n = 0; n < 2; ++n) _Pragma("unroll") for (int k = 0; k < 2; ++k) dst[n][k] = *(const LAS bf16x8*)(lds + PG8_SB(b, h) + boff + n * 2048 + k * 1024); } while (0)
; #define PG8_MMA(ai, bj, At, Bt) do { __builtin_amdgcn_s_setprio(1); _Pragma("unroll") for (int m = 0; m < 4; ++m) _Pragma("unroll") for (int n = 0; n < 2; ++n) _Pragma("unroll") for (int k = 0; k < 2; ++k) \
;         acc[ai][bj][m][n] = __builtin_amdgcn_mfma_f32_16x16x32_bf16(Bt[n][k], At[m][k], acc[ai][bj][m][n], 0, 0, 0); __builtin_amdgcn_s_setprio(0); } while (0)
; #define PG8_WAIT_L(n) asm volatile("s_waitcnt lgkmcnt(" #n ")" ::: "memory")
; #define PG8_BAR __builtin_amdgcn_s_barrier()
; #define PG8_SCHED __builtin_amdgcn_sched_barrier(0)
; template <class Epi>
; __device__ __forceinline__ void gemm_phase(LAS unsigned char* lds, const Gemm g, const Sched& S, const Epi& E) {
;     ...
;             const char* a1 = cA + (size_t)(t + 1) * kstep;
;             const char* a2 = last ? nA : cA + (size_t)(t + 2) * kstep; const char* b2 = last ? nB : cB + (size_t)(t + 2) * kstep;
;             const char* a3 = a2 + kstep; const char* b3 = b2 + kstep;
;             PG8_LDB(B0, 0, 0); PG8_SCHED; PG8_LDA(At, 0, 0); PG8_STAGE(PG8_SA(1, 1), a1 + hstepA, voffA);
;             PG8_WAIT_L(8); PG8_BAR; PG8_WAIT_L(0); PG8_MMA(0, 0, At, B0); PG8_BAR; PG8_SCHED;
;             PG8_LDB(B1, 0, 1); PG8_STAGE(PG8_SB(0, 0), b2, voffB);
;             PG8_BAR; PG8_WAIT_L(0); PG8_MMA(0, 1, At, B1); PG8_BAR;
;             PG8_LDA(At, 0, 1); PG8_STAGE(PG8_SA(0, 0), a2, voffA);
;             PG8_BAR; PG8_WAIT_L(0); PG8_MMA(1, 0, At, B0); PG8_BAR; PG8_SCHED;
.LBB0_520:
	ds_read_b128 v[128:131], v224
	ds_read_b128 v[132:135], v224 offset:1024
	ds_read_b128 v[136:139], v224 offset:2048
	ds_read_b128 v[140:143], v224 offset:3072
	s_add_u32 s80, s8, 0xfff80080
	s_addc_u32 s81, s9, -1
	s_cmp_eq_u32 s59, 28
	s_cselect_b32 s83, s7, s81
	s_cselect_b32 s82, s34, s80
	s_cselect_b32 s81, s35, s53
	s_cselect_b32 s80, s50, s51
	v_lshl_add_u64 v[176:177], s[8:9], 0, v[200:201]
	s_add_i32 m0, s56, 0xc000
	ds_read_b128 v[144:147], v225
	ds_read_b128 v[148:151], v225 offset:1024
	ds_read_b128 v[152:155], v225 offset:2048
	ds_read_b128 v[156:159], v225 offset:3072
	ds_read_b128 v[160:163], v225 offset:4096
	ds_read_b128 v[164:167], v225 offset:5120
	ds_read_b128 v[168:171], v225 offset:6144
	ds_read_b128 v[172:175], v225 offset:7168
	global_load_lds_dwordx4 v[176:177], off
	v_lshl_add_u64 v[176:177], s[8:9], 0, v[202:203]
	s_add_i32 m0, s56, 0xe000
	s_nop 0
	global_load_lds_dwordx4 v[176:177], off
	s_waitcnt lgkmcnt(8)
	s_barrier
	s_waitcnt lgkmcnt(0)
	s_setprio 1
	s_waitcnt lgkmcnt(0)
	v_mfma_f32_16x16x32_bf16 v[124:127], v[128:131], v[144:147], v[124:127]
	v_mfma_f32_16x16x32_bf16 v[120:123], v[136:139], v[144:147], v[120:123]
	v_mfma_f32_16x16x32_bf16 v[116:119], v[128:131], v[152:155], v[116:119]
	v_mfma_f32_16x16x32_bf16 v[112:115], v[136:139], v[152:155], v[112:115]
	v_mfma_f32_16x16x32_bf16 v[108:111], v[128:131], v[160:163], v[108:111]
	v_mfma_f32_16x16x32_bf16 v[104:107], v[136:139], v[160:163], v[104:107]
	v_mfma_f32_16x16x32_bf16 v[100:103], v[128:131], v[168:171], v[100:103]
	v_mfma_f32_16x16x32_bf16 v[96:99], v[136:139], v[168:171], v[96:99]
	v_mfma_f32_16x16x32_bf16 v[124:127], v[132:135], v[148:151], v[124:127]
	v_mfma_f32_16x16x32_bf16 v[120:123], v[140:143], v[148:151], v[120:123]
	v_mfma_f32_16x16x32_bf16 v[116:119], v[132:135], v[156:159], v[116:119]
	v_mfma_f32_16x16x32_bf16 v[112:115], v[140:143], v[156:159], v[112:115]
	v_mfma_f32_16x16x32_bf16 v[108:111], v[132:135], v[164:167], v[108:111]
	v_mfma_f32_16x16x32_bf16 v[104:107], v[140:143], v[164:167], v[104:107]
	v_mfma_f32_16x16x32_bf16 v[100:103], v[132:135], v[172:175], v[100:103]
	s_barrier
	v_mfma_f32_16x16x32_bf16 v[96:99], v[140:143], v[172:175], v[96:99]
	s_setprio 0
	s_add_i32 vcc_lo, s90, s55
	v_lshl_add_u64 v[216:217], s[80:81], 0, v[184:185]
	s_mov_b32 m0, vcc_lo
	ds_read_b128 v[176:179], v226
	ds_read_b128 v[180:183], v226 offset:1024
	ds_read_b128 v[208:211], v226 offset:2048
	ds_read_b128 v[212:215], v226 offset:3072
	global_load_lds_dwordx4 v[216:217], off
	v_lshl_add_u64 v[218:219], s[80:81], 0, v[186:187]
	s_add_i32 m0, vcc_lo, 0x2000
	s_nop 0
	global_load_lds_dwordx4 v[218:219], off
	s_barrier
	s_waitcnt lgkmcnt(0)
	s_setprio 1
	s_waitcnt lgkmcnt(0)
	v_mfma_f32_16x16x32_bf16 v[60:63], v[176:179], v[144:147], v[60:63]
	v_mfma_f32_16x16x32_bf16 v[56:59], v[208:211], v[144:147], v[56:59]
	v_mfma_f32_16x16x32_bf16 v[52:55], v[176:179], v[152:155], v[52:55]
	v_mfma_f32_16x16x32_bf16 v[48:51], v[208:211], v[152:155], v[48:51]
	v_mfma_f32_16x16x32_bf16 v[44:47], v[176:179], v[160:163], v[44:47]
	v_mfma_f32_16x16x32_bf16 v[40:43], v[208:211], v[160:163], v[40:43]
	v_mfma_f32_16x16x32_bf16 v[36:39], v[176:179], v[168:171], v[36:39]
	v_mfma_f32_16x16x32_bf16 v[32:35], v[208:211], v[168:171], v[32:35]
	v_mfma_f32_16x16x32_bf16 v[60:63], v[180:183], v[148:151], v[60:63]
	v_mfma_f32_16x16x32_bf16 v[56:59], v[212:215], v[148:151], v[56:59]
	v_mfma_f32_16x16x32_bf16 v[52:55], v[180:183], v[156:159], v[52:55]
	v_mfma_f32_16x16x32_bf16 v[48:51], v[212:215], v[156:159], v[48:51]
	v_mfma_f32_16x16x32_bf16 v[44:47], v[180:183], v[164:167], v[44:47]
	v_mfma_f32_16x16x32_bf16 v[40:43], v[212:215], v[164:167], v[40:43]
	v_mfma_f32_16x16x32_bf16 v[36:39], v[180:183], v[172:175], v[36:39]
	s_barrier
	v_mfma_f32_16x16x32_bf16 v[32:35], v[212:215], v[172:175], v[32:35]
	s_setprio 0
	s_mov_b32 m0, s56
	v_lshl_add_u64 v[220:221], s[82:83], 0, v[184:185]
	ds_read_b128 v[144:147], v225 offset:16384
	ds_read_b128 v[148:151], v225 offset:17408
	ds_read_b128 v[152:155], v225 offset:18432
	ds_read_b128 v[156:159], v225 offset:19456
	ds_read_b128 v[160:163], v225 offset:20480
	ds_read_b128 v[164:167], v225 offset:21504
	ds_read_b128 v[168:171], v225 offset:22528
	ds_read_b128 v[172:175], v225 offset:23552
	global_load_lds_dwordx4 v[220:221], off
	v_lshl_add_u64 v[222:223], s[82:83], 0, v[186:187]
	s_mov_b32 m0, s57
	s_nop 0
	global_load_lds_dwordx4 v[222:223], off
	s_barrier
	s_waitcnt lgkmcnt(0)
	s_setprio 1
	s_waitcnt lgkmcnt(0)
	v_mfma_f32_16x16x32_bf16 v[92:95], v[128:131], v[144:147], v[92:95]
	v_mfma_f32_16x16x32_bf16 v[88:91], v[136:139], v[144:147], v[88:91]
	v_mfma_f32_16x16x32_bf16 v[84:87], v[128:131], v[152:155], v[84:87]
	v_mfma_f32_16x16x32_bf16 v[80:83], v[136:139], v[152:155], v[80:83]
	v_mfma_f32_16x16x32_bf16 v[76:79], v[128:131], v[160:163], v[76:79]
	v_mfma_f32_16x16x32_bf16 v[72:75], v[136:139], v[160:163], v[72:75]
	v_mfma_f32_16x16x32_bf16 v[68:71], v[128:131], v[168:171], v[68:71]
	v_mfma_f32_16x16x32_bf16 v[64:67], v[136:139], v[168:171], v[64:67]
	v_mfma_f32_16x16x32_bf16 v[92:95], v[132:135], v[148:151], v[92:95]
	v_mfma_f32_16x16x32_bf16 v[88:91], v[140:143], v[148:151], v[88:91]
	v_mfma_f32_16x16x32_bf16 v[84:87], v[132:135], v[156:159], v[84:87]
	v_mfma_f32_16x16x32_bf16 v[80:83], v[140:143], v[156:159], v[80:83]
	v_mfma_f32_16x16x32_bf16 v[76:79], v[132:135], v[164:167], v[76:79]
	v_mfma_f32_16x16x32_bf16 v[72:75], v[140:143], v[164:167], v[72:75]
	v_mfma_f32_16x16x32_bf16 v[68:71], v[132:135], v[172:175], v[68:71]
	s_barrier
; #define PG8_STAGE(bufoff, gbase, voff) do { _Pragma("unroll") for (int _i = 0; _i < 2; ++_i) \
;         __builtin_amdgcn_global_load_lds((const unsigned*)((const char*)(gbase) + (voff)[_i]), (LAS unsigned*)(lds + (bufoff) + ldsw + _i * 8192), 16, 0, 0); } while (0)
; #define PG8_LDA(dst, b, h) do { _Pragma("unroll") for (int m = 0; m < 4; ++m) _Pragma("unroll") for (int k = 0; k < 2; ++k) dst[m][k] = *(const LAS bf16x8*)(lds + PG8_SA(b, h) + aoff + m * 2048 + k * 1024); } while (0)
; #define PG8_LDB(dst, b, h) do { _Pragma("unroll") for (int n = 0; n < 2; ++n) _Pragma("unroll") for (int k = 0; k < 2; ++k) dst[n][k] = *(const LAS bf16x8*)(lds + PG8_SB(b, h) + boff + n * 2048 + k * 1024); } while (0)
; #define PG8_MMA(ai, bj, At, Bt) do { __builtin_amdgcn_s_setprio(1); _Pragma("unroll") for (int m = 0; m < 4; ++m) _Pragma("unroll") for (int n = 0; n < 2; ++n) _Pragma("unroll") for (int k = 0; k < 2; ++k) \
;         acc[ai][bj][m][n] = __builtin_amdgcn_mfma_f32_16x16x32_bf16(Bt[n][k], At[m][k], acc[ai][bj][m][n], 0, 0, 0); __builtin_amdgcn_s_setprio(0); } while (0)
; #define PG8_WAIT_V(n) asm volatile("s_waitcnt vmcnt(" #n ")" ::: "memory")
; #define PG8_WAIT_L(n) asm volatile("s_waitcnt lgkmcnt(" #n ")" ::: "memory")
; #define PG8_BAR __builtin_amdgcn_s_barrier()
; #define PG8_SCHED __builtin_amdgcn_sched_barrier(0)
; template <class Epi>
; __device__ __forceinline__ void gemm_phase(LAS unsigned char* lds, const Gemm g, const Sched& S, const Epi& E) {
;     ...
;             PG8_BAR; PG8_WAIT_L(0); PG8_MMA(1, 0, At, B0); PG8_BAR; PG8_SCHED;
;             PG8_STAGE(PG8_SB(0, 1), b2 + hstepB, voffB);
;             PG8_WAIT_V(6); PG8_BAR; PG8_MMA(1, 1, At, B1); PG8_BAR;
;             PG8_LDB(B0, 1, 0); PG8_SCHED; PG8_LDA(At, 1, 0); PG8_STAGE(PG8_SA(0, 1), a2 + hstepA, voffA);
;             PG8_WAIT_L(8); PG8_BAR; PG8_WAIT_L(0); PG8_MMA(0, 0, At, B0); PG8_BAR; PG8_SCHED;
;             PG8_LDB(B1, 1, 1); PG8_STAGE(PG8_SB(1, 0), b3, voffB);
;             PG8_BAR; PG8_WAIT_L(0); PG8_MMA(0, 1, At, B1); PG8_BAR;
	v_mfma_f32_16x16x32_bf16 v[64:67], v[140:143], v[172:175], v[64:67]
	s_setprio 0
	s_add_u32 vcc_lo, s80, 0x80000
	s_addc_u32 vcc_hi, s81, 0
	s_add_i32 s12, s91, s55
	v_lshl_add_u64 v[128:129], vcc, 0, v[184:185]
	s_mov_b32 m0, s12
	s_nop 0
	global_load_lds_dwordx4 v[128:129], off
	v_lshl_add_u64 v[128:129], vcc, 0, v[186:187]
	s_add_i32 m0, s12, 0x2000
	s_nop 0
	global_load_lds_dwordx4 v[128:129], off
	s_waitcnt vmcnt(6)
	s_barrier
	s_setprio 1
	v_mfma_f32_16x16x32_bf16 v[28:31], v[176:179], v[144:147], v[28:31]
	v_mfma_f32_16x16x32_bf16 v[24:27], v[208:211], v[144:147], v[24:27]
	v_mfma_f32_16x16x32_bf16 v[20:23], v[176:179], v[152:155], v[20:23]
	v_mfma_f32_16x16x32_bf16 v[16:19], v[208:211], v[152:155], v[16:19]
	v_mfma_f32_16x16x32_bf16 v[12:15], v[176:179], v[160:163], v[12:15]
	v_mfma_f32_16x16x32_bf16 v[8:11], v[208:211], v[160:163], v[8:11]
	v_mfma_f32_16x16x32_bf16 v[4:7], v[176:179], v[168:171], v[4:7]
	v_mfma_f32_16x16x32_bf16 v[0:3], v[208:211], v[168:171], v[0:3]
	v_mfma_f32_16x16x32_bf16 v[28:31], v[180:183], v[148:151], v[28:31]
	v_mfma_f32_16x16x32_bf16 v[24:27], v[212:215], v[148:151], v[24:27]
	v_mfma_f32_16x16x32_bf16 v[20:23], v[180:183], v[156:159], v[20:23]
	v_mfma_f32_16x16x32_bf16 v[16:19], v[212:215], v[156:159], v[16:19]
	v_mfma_f32_16x16x32_bf16 v[12:15], v[180:183], v[164:167], v[12:15]
	v_mfma_f32_16x16x32_bf16 v[8:11], v[212:215], v[164:167], v[8:11]
	v_mfma_f32_16x16x32_bf16 v[4:7], v[180:183], v[172:175], v[4:7]
	s_barrier
	v_mfma_f32_16x16x32_bf16 v[0:3], v[212:215], v[172:175], v[0:3]
	s_setprio 0
	s_add_i32 s12, 0, 0x18000
	v_add_u32_e32 v140, s12, v195
	ds_read_b128 v[128:131], v140
	ds_read_b128 v[132:135], v140 offset:1024
	ds_read_b128 v[136:139], v140 offset:2048
	ds_read_b128 v[140:143], v140 offset:3072
	s_add_u32 s82, s82, 0x80000
	s_addc_u32 s83, s83, 0
	s_mov_b32 m0, s60
	v_lshl_add_u64 v[176:177], s[82:83], 0, v[184:185]
	ds_read_b128 v[144:147], v225 offset:32768
	ds_read_b128 v[148:151], v225 offset:33792
	ds_read_b128 v[152:155], v225 offset:34816
	ds_read_b128 v[156:159], v225 offset:35840
	ds_read_b128 v[160:163], v225 offset:36864
	ds_read_b128 v[164:167], v225 offset:37888
	ds_read_b128 v[168:171], v225 offset:38912
	ds_read_b128 v[172:175], v225 offset:39936
	global_load_lds_dwordx4 v[176:177], off
	v_lshl_add_u64 v[176:177], s[82:83], 0, v[186:187]
	s_mov_b32 m0, s61
	s_nop 0
	global_load_lds_dwordx4 v[176:177], off
	s_waitcnt lgkmcnt(8)
	s_barrier
	s_waitcnt lgkmcnt(0)
	s_setprio 1
	s_waitcnt lgkmcnt(0)
	v_mfma_f32_16x16x32_bf16 v[124:127], v[128:131], v[144:147], v[124:127]
	v_mfma_f32_16x16x32_bf16 v[120:123], v[136:139], v[144:147], v[120:123]
	v_mfma_f32_16x16x32_bf16 v[116:119], v[128:131], v[152:155], v[116:119]
	v_mfma_f32_16x16x32_bf16 v[112:115], v[136:139], v[152:155], v[112:115]
	v_mfma_f32_16x16x32_bf16 v[108:111], v[128:131], v[160:163], v[108:111]
	v_mfma_f32_16x16x32_bf16 v[104:107], v[136:139], v[160:163], v[104:107]
	v_mfma_f32_16x16x32_bf16 v[100:103], v[128:131], v[168:171], v[100:103]
	v_mfma_f32_16x16x32_bf16 v[96:99], v[136:139], v[168:171], v[96:99]
	v_mfma_f32_16x16x32_bf16 v[124:127], v[132:135], v[148:151], v[124:127]
	v_mfma_f32_16x16x32_bf16 v[120:123], v[140:143], v[148:151], v[120:123]
	v_mfma_f32_16x16x32_bf16 v[116:119], v[132:135], v[156:159], v[116:119]
	v_mfma_f32_16x16x32_bf16 v[112:115], v[140:143], v[156:159], v[112:115]
	v_mfma_f32_16x16x32_bf16 v[108:111], v[132:135], v[164:167], v[108:111]
	v_mfma_f32_16x16x32_bf16 v[104:107], v[140:143], v[164:167], v[104:107]
	v_mfma_f32_16x16x32_bf16 v[100:103], v[132:135], v[172:175], v[100:103]
	s_barrier
	v_mfma_f32_16x16x32_bf16 v[96:99], v[140:143], v[172:175], v[96:99]
	s_setprio 0
	s_add_i32 s13, 0, 0x1c000
	s_add_i32 s12, s12, s55
	v_add_u32_e32 v188, s13, v195
	v_lshl_add_u64 v[216:217], v[216:217], 0, s[16:17]
	s_mov_b32 m0, s12
	ds_read_b128 v[176:179], v188
	ds_read_b128 v[180:183], v188 offset:1024
	ds_read_b128 v[208:211], v188 offset:2048
	ds_read_b128 v[212:215], v188 offset:3072
	global_load_lds_dwordx4 v[216:217], off
	v_lshl_add_u64 v[216:217], v[218:219], 0, s[16:17]
	s_add_i32 m0, s12, 0x2000
	s_nop 0
	global_load_lds_dwordx4 v[216:217], off
	s_barrier
	s_waitcnt lgkmcnt(0)
	s_setprio 1
	s_waitcnt lgkmcnt(0)
	v_mfma_f32_16x16x32_bf16 v[60:63], v[176:179], v[144:147], v[60:63]
	v_mfma_f32_16x16x32_bf16 v[56:59], v[208:211], v[144:147], v[56:59]
	v_mfma_f32_16x16x32_bf16 v[52:55], v[176:179], v[152:155], v[52:55]
	v_mfma_f32_16x16x32_bf16 v[48:51], v[208:211], v[152:155], v[48:51]
	v_mfma_f32_16x16x32_bf16 v[44:47], v[176:179], v[160:163], v[44:47]
	v_mfma_f32_16x16x32_bf16 v[40:43], v[208:211], v[160:163], v[40:43]
	v_mfma_f32_16x16x32_bf16 v[36:39], v[176:179], v[168:171], v[36:39]
	v_mfma_f32_16x16x32_bf16 v[32:35], v[208:211], v[168:171], v[32:35]
	v_mfma_f32_16x16x32_bf16 v[60:63], v[180:183], v[148:151], v[60:63]
	v_mfma_f32_16x16x32_bf16 v[56:59], v[212:215], v[148:151], v[56:59]
	v_mfma_f32_16x16x32_bf16 v[52:55], v[180:183], v[156:159], v[52:55]
	v_mfma_f32_16x16x32_bf16 v[48:51], v[212:215], v[156:159], v[48:51]
	v_mfma_f32_16x16x32_bf16 v[44:47], v[180:183], v[164:167], v[44:47]
	v_mfma_f32_16x16x32_bf16 v[40:43], v[212:215], v[164:167], v[40:43]
	v_mfma_f32_16x16x32_bf16 v[36:39], v[180:183], v[172:175], v[36:39]
	s_barrier
	v_mfma_f32_16x16x32_bf16 v[32:35], v[212:215], v[172:175], v[32:35]
	s_setprio 0
	s_mov_b32 m0, s84
	v_lshl_add_u64 v[216:217], v[220:221], 0, s[16:17]
	ds_read_b128 v[144:147], v225 offset:49152
	ds_read_b128 v[148:151], v225 offset:50176
	ds_read_b128 v[152:155], v225 offset:51200
	ds_read_b128 v[156:159], v225 offset:52224
	ds_read_b128 v[160:163], v225 offset:53248
	ds_read_b128 v[164:167], v225 offset:54272
	ds_read_b128 v[168:171], v225 offset:55296
	ds_read_b128 v[172:175], v225 offset:56320
	global_load_lds_dwordx4 v[216:217], off
	v_lshl_add_u64 v[216:217], v[222:223], 0, s[16:17]
	s_mov_b32 m0, s85
	s_nop 0
	global_load_lds_dwordx4 v[216:217], off
	s_barrier
; #define PG8_STAGE(bufoff, gbase, voff) do { _Pragma("unroll") for (int _i = 0; _i < 2; ++_i) \
;         __builtin_amdgcn_global_load_lds((const unsigned*)((const char*)(gbase) + (voff)[_i]), (LAS unsigned*)(lds + (bufoff) + ldsw + _i * 8192), 16, 0, 0); } while (0)
; #define PG8_MMA(ai, bj, At, Bt) do { __builtin_amdgcn_s_setprio(1); _Pragma("unroll") for (int m = 0; m < 4; ++m) _Pragma("unroll") for (int n = 0; n < 2; ++n) _Pragma("unroll") for (int k = 0; k < 2; ++k) \
;         acc[ai][bj][m][n] = __builtin_amdgcn_mfma_f32_16x16x32_bf16(Bt[n][k], At[m][k], acc[ai][bj][m][n], 0, 0, 0); __builtin_amdgcn_s_setprio(0); } while (0)
; #define PG8_WAIT_V(n) asm volatile("s_waitcnt vmcnt(" #n ")" ::: "memory")
; #define PG8_WAIT_L(n) asm volatile("s_waitcnt lgkmcnt(" #n ")" ::: "memory")
; #define PG8_BAR __builtin_amdgcn_s_barrier()
; #define PG8_SCHED __builtin_amdgcn_sched_barrier(0)
; template <class Epi>
; __device__ __forceinline__ void gemm_phase(LAS unsigned char* lds, const Gemm g, const Sched& S, const Epi& E) {
;     ...
;             PG8_BAR; PG8_WAIT_L(0); PG8_MMA(1, 0, At, B0); PG8_BAR; PG8_SCHED;
;             PG8_STAGE(PG8_SB(1, 1), b3 + hstepB, voffB);
;             PG8_WAIT_V(6); PG8_BAR; PG8_MMA(1, 1, At, B1); PG8_BAR;
;         }
;         E(acc, cur, wr, wc, fr, fq);
;         if (!has_next) break;
;     __device__ __forceinline__ void operator()(AccRef acc, const Unit& u, int wr, int wc, int fr, int fq) const {
;     ...
;         for (int bj = 0; bj < 2; ++bj) {
;             const int hc = (u.pn + pn0) * 2 + bj;
;             if (hc >= 41) continue;
;             const int idx = hc - 16, br = idx >> 3, kvs = (idx >> 2) & 1, g = idx & 3;
;             const int row0 = u.pm * 256 + wr * 64 + fr;
;             if (hc == 40) {
; #pragma unroll
;                 for (int ai = 0; ai < 2; ++ai)
; #pragma unroll
;                     for (int m = 0; m < 4; ++m)
; #pragma unroll
;                         for (int n = 0; n < 2; ++n) { const int row = row0 + ai * 128 + m * 16, p0 = wc * 32 + n * 16 + 4 * fq; const f32x4 v = acc[ai][bj][m][n];
;                             if (p0 < 48) {
; #pragma unroll
;                                 for (int j = 0; j < 4; ++j) ((float*)(big + N_GATE))[(size_t)row * 48 + p0 + j] = __builtin_amdgcn_rcpf(1.0f + __expf(-v[j])); } }
;             } else if (hc >= 16 && kvs == 1 && br >= 1) {
	s_waitcnt lgkmcnt(0)
	s_setprio 1
	s_waitcnt lgkmcnt(0)
	v_mfma_f32_16x16x32_bf16 v[92:95], v[128:131], v[144:147], v[92:95]
	v_mfma_f32_16x16x32_bf16 v[88:91], v[136:139], v[144:147], v[88:91]
	v_mfma_f32_16x16x32_bf16 v[84:87], v[128:131], v[152:155], v[84:87]
	v_mfma_f32_16x16x32_bf16 v[80:83], v[136:139], v[152:155], v[80:83]
	v_mfma_f32_16x16x32_bf16 v[76:79], v[128:131], v[160:163], v[76:79]
	v_mfma_f32_16x16x32_bf16 v[72:75], v[136:139], v[160:163], v[72:75]
	v_mfma_f32_16x16x32_bf16 v[68:71], v[128:131], v[168:171], v[68:71]
	v_mfma_f32_16x16x32_bf16 v[64:67], v[136:139], v[168:171], v[64:67]
	v_mfma_f32_16x16x32_bf16 v[92:95], v[132:135], v[148:151], v[92:95]
	v_mfma_f32_16x16x32_bf16 v[88:91], v[140:143], v[148:151], v[88:91]
	v_mfma_f32_16x16x32_bf16 v[84:87], v[132:135], v[156:159], v[84:87]
	v_mfma_f32_16x16x32_bf16 v[80:83], v[140:143], v[156:159], v[80:83]
	v_mfma_f32_16x16x32_bf16 v[76:79], v[132:135], v[164:167], v[76:79]
	v_mfma_f32_16x16x32_bf16 v[72:75], v[140:143], v[164:167], v[72:75]
	v_mfma_f32_16x16x32_bf16 v[68:71], v[132:135], v[172:175], v[68:71]
	s_barrier
	v_mfma_f32_16x16x32_bf16 v[64:67], v[140:143], v[172:175], v[64:67]
	s_setprio 0
	s_add_u32 s80, s80, 0x80080
	s_addc_u32 s81, s81, 0
	s_add_i32 s12, s13, s55
	v_lshl_add_u64 v[128:129], s[80:81], 0, v[184:185]
	s_mov_b32 m0, s12
	s_nop 0
	global_load_lds_dwordx4 v[128:129], off
	v_lshl_add_u64 v[128:129], s[80:81], 0, v[186:187]
	s_add_i32 m0, s12, 0x2000
	s_nop 0
	global_load_lds_dwordx4 v[128:129], off
	s_waitcnt vmcnt(6)
	s_barrier
	s_setprio 1
	v_mfma_f32_16x16x32_bf16 v[28:31], v[176:179], v[144:147], v[28:31]
	v_mfma_f32_16x16x32_bf16 v[24:27], v[208:211], v[144:147], v[24:27]
	v_mfma_f32_16x16x32_bf16 v[20:23], v[176:179], v[152:155], v[20:23]
	v_mfma_f32_16x16x32_bf16 v[16:19], v[208:211], v[152:155], v[16:19]
	v_mfma_f32_16x16x32_bf16 v[12:15], v[176:179], v[160:163], v[12:15]
	v_mfma_f32_16x16x32_bf16 v[8:11], v[208:211], v[160:163], v[8:11]
	v_mfma_f32_16x16x32_bf16 v[4:7], v[176:179], v[168:171], v[4:7]
	v_mfma_f32_16x16x32_bf16 v[0:3], v[208:211], v[168:171], v[0:3]
	v_mfma_f32_16x16x32_bf16 v[28:31], v[180:183], v[148:151], v[28:31]
	v_mfma_f32_16x16x32_bf16 v[24:27], v[212:215], v[148:151], v[24:27]
	v_mfma_f32_16x16x32_bf16 v[20:23], v[180:183], v[156:159], v[20:23]
	v_mfma_f32_16x16x32_bf16 v[16:19], v[212:215], v[156:159], v[16:19]
	v_mfma_f32_16x16x32_bf16 v[12:15], v[180:183], v[164:167], v[12:15]
	v_mfma_f32_16x16x32_bf16 v[8:11], v[212:215], v[164:167], v[8:11]
	v_mfma_f32_16x16x32_bf16 v[4:7], v[180:183], v[172:175], v[4:7]
	s_barrier
	v_mfma_f32_16x16x32_bf16 v[0:3], v[212:215], v[172:175], v[0:3]
	s_setprio 0
	s_add_i32 s59, s59, 2
	s_add_u32 s8, s8, 0x100
	s_addc_u32 s9, s9, 0
	s_add_u32 s51, s51, 0x100
	s_addc_u32 s53, s53, 0
	s_cmp_gt_u32 s59, 29
	s_cbranch_scc0 .LBB0_520
	s_lshl_b32 s34, s6, 8
	s_lshl_b32 s53, s11, 1
	s_add_i32 s34, s34, s71
	s_add_i32 s35, s53, 40
	s_cmp_gt_i32 s11, 0
	v_or_b32_e32 v208, s34, v191
	s_cbranch_scc1 .LBB0_566
	s_cmp_lg_u32 s11, 0
	s_cbranch_scc0 .LBB0_565
	s_add_i32 s59, s53, 24
	s_ashr_i32 s51, s59, 3
	s_and_b32 s50, s53, 2
	s_bitcmp1_b32 s53, 2
	s_cselect_b64 s[6:7], -1, 0
	s_cmp_gt_i32 s51, 0
	s_cselect_b64 s[8:9], -1, 0
	s_and_b64 s[6:7], s[6:7], s[8:9]
	s_andn2_b64 vcc, exec, s[6:7]
	s_mov_b64 s[6:7], -1
	s_cbranch_vccz .LBB0_529
	s_bfe_u32 s6, s53, 0x10002
	s_cmp_eq_u32 s6, 0
	s_cselect_b64 s[80:81], -1, 0
	s_cmp_eq_u32 s51, 1
	s_cselect_b32 s6, s94, 0x10004000
	s_cmp_gt_u32 s59, 7
	s_cselect_b32 s53, s6, 0x8000000
	s_and_b64 s[6:7], s[80:81], exec
	s_cselect_b32 s6, s53, 0xa002000
	s_add_u32 s6, s44, s6
	s_addc_u32 s7, s45, 0
	s_and_b64 s[80:81], s[80:81], s[8:9]
	s_mov_b64 s[8:9], -1
	s_and_b64 vcc, exec, s[80:81]
	s_cbranch_vccnz .LBB0_526
; __device__ __forceinline__ unsigned cvt_pk_bf16(float lo, float hi) { unsigned r; asm volatile("v_cvt_pk_bf16_f32 %0, %1, %2" : "=v"(r) : "v"(lo), "v"(hi)); return r; }
; __device__ __forceinline__ void st_bf4(bf16_t* p, const f32x4 v) { u32x2 w; w.x = cvt_pk_bf16(v[0], v[1]); w.y = cvt_pk_bf16(v[2], v[3]); *(u32x2*)p = w; }
;     __device__ __forceinline__ void operator()(AccRef acc, const Unit& u, int wr, int wc, int fr, int fq) const {
;     ...
;                 } else {
; #pragma unroll
;                     for (int ai = 0; ai < 2; ++ai)
; #pragma unroll
;                         for (int m = 0; m < 4; ++m)
; #pragma unroll
;                             for (int n = 0; n < 2; ++n) { const int row = row0 + ai * 128 + m * 16, p0 = wc * 32 + n * 16 + 4 * fq;
;                                 const size_t ro = ((size_t)row + (size_t)(3 * (row >> 14) + g) * S_) * 128;
;                                 st_bf4(base + ro + p0, acc[ai][bj][m][n]); }
	s_ashr_i32 s8, s34, 14
	s_mul_i32 s8, s8, 3
	s_add_i32 s8, s8, s50
	s_ashr_i32 s9, s8, 31
	s_lshl_b64 s[8:9], s[8:9], 22
	s_add_u32 s8, s6, s8
	v_ashrrev_i32_e32 v209, 31, v208
	s_addc_u32 s9, s7, s9
	v_lshlrev_b64 v[128:129], 8, v[208:209]
	v_lshl_add_u64 v[130:131], s[8:9], 0, v[128:129]
	v_lshlrev_b32_e32 v188, 1, v190
	v_lshl_add_u64 v[130:131], v[130:131], 0, v[188:189]
	v_cvt_pk_bf16_f32 v132, v124, v125
	v_cvt_pk_bf16_f32 v133, v126, v127
	global_store_dwordx2 v[130:131], v[132:133], off
	v_cvt_pk_bf16_f32 v132, v120, v121
	v_cvt_pk_bf16_f32 v133, v122, v123
	global_store_dwordx2 v[130:131], v[132:133], off offset:32
	v_or_b32_e32 v130, 16, v208
	v_ashrrev_i32_e32 v131, 31, v130
	v_lshlrev_b64 v[130:131], 8, v[130:131]
	v_lshl_add_u64 v[130:131], s[8:9], 0, v[130:131]
	v_lshl_add_u64 v[130:131], v[130:131], 0, v[188:189]
	v_cvt_pk_bf16_f32 v132, v116, v117
	v_cvt_pk_bf16_f32 v133, v118, v119
	global_store_dwordx2 v[130:131], v[132:133], off
	v_cvt_pk_bf16_f32 v132, v112, v113
	v_cvt_pk_bf16_f32 v133, v114, v115
	global_store_dwordx2 v[130:131], v[132:133], off offset:32
	v_or_b32_e32 v130, 32, v208
	v_ashrrev_i32_e32 v131, 31, v130
	v_lshlrev_b64 v[130:131], 8, v[130:131]
	v_lshl_add_u64 v[130:131], s[8:9], 0, v[130:131]
	v_lshl_add_u64 v[130:131], v[130:131], 0, v[188:189]
	v_cvt_pk_bf16_f32 v132, v108, v109
	v_cvt_pk_bf16_f32 v133, v110, v111
	global_store_dwordx2 v[130:131], v[132:133], off
	v_cvt_pk_bf16_f32 v132, v104, v105
	v_cvt_pk_bf16_f32 v133, v106, v107
	global_store_dwordx2 v[130:131], v[132:133], off offset:32
	v_or_b32_e32 v130, 48, v208
	v_ashrrev_i32_e32 v131, 31, v130
	v_lshlrev_b64 v[130:131], 8, v[130:131]
	v_lshl_add_u64 v[130:131], s[8:9], 0, v[130:131]
	v_lshl_add_u64 v[130:131], v[130:131], 0, v[188:189]
	v_cvt_pk_bf16_f32 v132, v100, v101
	v_cvt_pk_bf16_f32 v133, v102, v103
	global_store_dwordx2 v[130:131], v[132:133], off
	v_cvt_pk_bf16_f32 v132, v96, v97
	v_cvt_pk_bf16_f32 v133, v98, v99
	global_store_dwordx2 v[130:131], v[132:133], off offset:32
	v_add_u32_e32 v130, 0x80, v208
	v_ashrrev_i32_e32 v131, 14, v130
	v_mad_i32_i24 v132, v131, 3, s50
	v_ashrrev_i32_e32 v133, 31, v132
	v_lshlrev_b64 v[132:133], 22, v[132:133]
	v_ashrrev_i32_e32 v131, 31, v130
	v_lshl_add_u64 v[132:133], s[6:7], 0, v[132:133]
	v_lshlrev_b64 v[130:131], 8, v[130:131]
	v_lshl_add_u64 v[130:131], v[132:133], 0, v[130:131]
	v_lshl_add_u64 v[130:131], v[130:131], 0, v[188:189]
	v_cvt_pk_bf16_f32 v134, v92, v93
	v_lshl_add_u64 v[128:129], v[132:133], 0, v[128:129]
	v_cvt_pk_bf16_f32 v135, v94, v95
	global_store_dwordx2 v[130:131], v[134:135], off
	v_cvt_pk_bf16_f32 v134, v88, v89
	v_lshl_add_u64 v[128:129], v[128:129], 0, v[188:189]
	v_cvt_pk_bf16_f32 v135, v90, v91
	global_store_dwordx2 v[130:131], v[134:135], off offset:32
	v_add_co_u32_e32 v134, vcc, s88, v128
	v_cvt_pk_bf16_f32 v132, v84, v85
	v_cvt_pk_bf16_f32 v133, v86, v87
	v_lshl_add_u64 v[130:131], v[128:129], 0, s[24:25]
	s_nop 0
	v_addc_co_u32_e32 v135, vcc, 0, v129, vcc
	global_store_dwordx2 v[134:135], v[132:133], off offset:-4096
	v_cvt_pk_bf16_f32 v132, v80, v81
	v_cvt_pk_bf16_f32 v133, v82, v83
	global_store_dwordx2 v[130:131], v[132:133], off offset:32
	v_lshl_add_u64 v[130:131], v[128:129], 0, s[36:37]
	v_cvt_pk_bf16_f32 v132, v76, v77
	v_cvt_pk_bf16_f32 v133, v78, v79
	global_store_dwordx2 v[134:135], v[132:133], off
	v_cvt_pk_bf16_f32 v132, v72, v73
	v_cvt_pk_bf16_f32 v133, v74, v75
	global_store_dwordx2 v[130:131], v[132:133], off offset:32
	v_lshl_add_u64 v[130:131], v[128:129], 0, s[38:39]
	v_add_co_u32_e32 v128, vcc, 0xb000, v128
	s_mov_b64 s[8:9], 0
	s_nop 0
	v_addc_co_u32_e32 v129, vcc, 0, v129, vcc
	v_cvt_pk_bf16_f32 v132, v68, v69
	v_cvt_pk_bf16_f32 v133, v70, v71
	global_store_dwordx2 v[128:129], v[132:133], off
	v_cvt_pk_bf16_f32 v128, v64, v65
	v_cvt_pk_bf16_f32 v129, v66, v67
	global_store_dwordx2 v[130:131], v[128:129], off offset:32

; #define PG8_STAGE(bufoff, gbase, voff) do { _Pragma("unroll") for (int _i = 0; _i < 2; ++_i) \
;         __builtin_amdgcn_global_load_lds((const unsigned*)((const char*)(gbase) + (voff)[_i]), (LAS unsigned*)(lds + (bufoff) + ldsw + _i * 8192), 16, 0, 0); } while (0)
; #define PG8_LDA(dst, b, h) do { _Pragma("unroll") for (int m = 0; m < 4; ++m) _Pragma("unroll") for (int k = 0; k < 2; ++k) dst[m][k] = *(const LAS bf16x8*)(lds + PG8_SA(b, h) + aoff + m * 2048 + k * 1024); } while (0)
; #define PG8_LDB(dst, b, h) do { _Pragma("unroll") for (int n = 0; n < 2; ++n) _Pragma("unroll") for (int k = 0; k < 2; ++k) dst[n][k] = *(const LAS bf16x8*)(lds + PG8_SB(b, h) + boff + n * 2048 + k * 1024); } while (0)
; #define PG8_WAIT_V(n) asm volatile("s_waitcnt vmcnt(" #n ")" ::: "memory")
; #define PG8_WAIT_L(n) asm volatile("s_waitcnt lgkmcnt(" #n ")" ::: "memory")
; #define PG8_BAR __builtin_amdgcn_s_barrier()
; #define PG8_SCHED __builtin_amdgcn_sched_barrier(0)
; template <class Epi>
; __device__ __forceinline__ void gemm_phase(LAS unsigned char* lds, const Gemm g, const Sched& S, const Epi& E) {
;     ...
;         for (int t = 0; t < nt; t += 2) {
;             const bool last = (t == nt - 2);
;             const char* a1 = cA + (size_t)(t + 1) * kstep;
;             const char* a2 = last ? nA : cA + (size_t)(t + 2) * kstep; const char* b2 = last ? nB : cB + (size_t)(t + 2) * kstep;
;             const char* a3 = a2 + kstep; const char* b3 = b2 + kstep;
;             PG8_LDB(B0, 0, 0); PG8_SCHED; PG8_LDA(At, 0, 0); PG8_STAGE(PG8_SA(1, 1), a1 + hstepA, voffA);
;             PG8_WAIT_L(8); PG8_BAR; PG8_WAIT_L(0); PG8_MMA(0, 0, At, B0); PG8_BAR; PG8_SCHED;
;             PG8_LDB(B1, 0, 1); PG8_STAGE(PG8_SB(0, 0), b2, voffB);
;             PG8_BAR; PG8_WAIT_L(0); PG8_MMA(0, 1, At, B1); PG8_BAR;
;             PG8_LDA(At, 0, 1); PG8_STAGE(PG8_SA(0, 0), a2, voffA);
;             PG8_BAR; PG8_WAIT_L(0); PG8_MMA(1, 0, At, B0); PG8_BAR; PG8_SCHED;
;             PG8_STAGE(PG8_SB(0, 1), b2 + hstepB, voffB);
;             PG8_WAIT_V(6); PG8_BAR; PG8_MMA(1, 1, At, B1); PG8_BAR;
;             PG8_LDB(B0, 1, 0); PG8_SCHED; PG8_LDA(At, 1, 0); PG8_STAGE(PG8_SA(0, 1), a2 + hstepA, voffA);
;             PG8_WAIT_L(8); PG8_BAR; PG8_WAIT_L(0); PG8_MMA(0, 0, At, B0); PG8_BAR; PG8_SCHED;
.LBB0_641:
	ds_read_b128 v[0:3], v125
	ds_read_b128 v[4:7], v125 offset:1024
	ds_read_b128 v[8:11], v125 offset:2048
	ds_read_b128 v[12:15], v125 offset:3072
	s_lshl_b64 s[24:25], s[24:25], 17
	s_add_u32 s24, s92, s24
	s_addc_u32 s25, s93, s25
	s_and_b64 s[38:39], s[38:39], exec
	s_cselect_b32 s39, s25, s37
	s_cselect_b32 s38, s24, s36
	s_add_u32 s52, s4, 0x10080
	s_addc_u32 s53, s5, 0
	s_mov_b32 m0, s70
	s_waitcnt vmcnt(0)
	v_lshl_add_u64 v[48:49], s[52:53], 0, v[96:97]
	ds_read_b128 v[16:19], v126
	ds_read_b128 v[20:23], v126 offset:1024
	ds_read_b128 v[24:27], v126 offset:2048
	ds_read_b128 v[28:31], v126 offset:3072
	ds_read_b128 v[32:35], v126 offset:4096
	ds_read_b128 v[36:39], v126 offset:5120
	ds_read_b128 v[40:43], v126 offset:6144
	ds_read_b128 v[44:47], v126 offset:7168
	global_load_lds_dwordx4 v[48:49], off
	v_lshl_add_u64 v[48:49], s[52:53], 0, v[98:99]
	s_mov_b32 m0, s71
	s_nop 0
	global_load_lds_dwordx4 v[48:49], off
	s_waitcnt lgkmcnt(8)
	s_barrier
	s_waitcnt lgkmcnt(0)
	s_setprio 1
	s_waitcnt lgkmcnt(0)
	v_mfma_f32_16x16x32_bf16 v[48:51], v[0:3], v[16:19], 0
	v_mfma_f32_16x16x32_bf16 v[16:19], v[8:11], v[16:19], 0
	v_mfma_f32_16x16x32_bf16 v[48:51], v[4:7], v[20:23], v[48:51]
	v_mfma_f32_16x16x32_bf16 v[16:19], v[12:15], v[20:23], v[16:19]
	v_mfma_f32_16x16x32_bf16 v[20:23], v[0:3], v[24:27], 0
	v_mfma_f32_16x16x32_bf16 v[24:27], v[8:11], v[24:27], 0
	v_mfma_f32_16x16x32_bf16 v[20:23], v[4:7], v[28:31], v[20:23]
	v_mfma_f32_16x16x32_bf16 v[24:27], v[12:15], v[28:31], v[24:27]
	v_mfma_f32_16x16x32_bf16 v[28:31], v[0:3], v[32:35], 0
	v_mfma_f32_16x16x32_bf16 v[32:35], v[8:11], v[32:35], 0
	v_mfma_f32_16x16x32_bf16 v[28:31], v[4:7], v[36:39], v[28:31]
	v_mfma_f32_16x16x32_bf16 v[32:35], v[12:15], v[36:39], v[32:35]
	v_mfma_f32_16x16x32_bf16 v[36:39], v[0:3], v[40:43], 0
	v_mfma_f32_16x16x32_bf16 v[40:43], v[8:11], v[40:43], 0
	v_mfma_f32_16x16x32_bf16 v[36:39], v[4:7], v[44:47], v[36:39]
	s_barrier
	v_mfma_f32_16x16x32_bf16 v[40:43], v[12:15], v[44:47], v[40:43]
	s_setprio 0
	v_lshl_add_u64 v[132:133], s[36:37], 0, v[96:97]
	s_mov_b32 m0, s84
	v_lshl_add_u64 v[44:45], v[132:133], 0, s[10:11]
	v_lshl_add_u64 v[134:135], s[36:37], 0, v[98:99]
	global_load_lds_dwordx4 v[44:45], off
	v_lshl_add_u64 v[44:45], v[134:135], 0, s[10:11]
	s_mov_b32 m0, s85
	s_nop 0
	global_load_lds_dwordx4 v[44:45], off
	s_barrier
	s_waitcnt lgkmcnt(0)
	s_setprio 1
	s_setprio 0
	v_lshl_add_u64 v[136:137], s[4:5], 0, v[96:97]
	s_mov_b32 m0, s35
	v_lshl_add_u64 v[80:81], v[136:137], 0, s[10:11]
	v_lshl_add_u64 v[138:139], s[4:5], 0, v[98:99]
	s_barrier
	ds_read_b128 v[44:47], v126 offset:16384
	ds_read_b128 v[52:55], v126 offset:17408
	ds_read_b128 v[56:59], v126 offset:18432
	ds_read_b128 v[60:63], v126 offset:19456
	ds_read_b128 v[64:67], v126 offset:20480
	ds_read_b128 v[68:71], v126 offset:21504
	ds_read_b128 v[72:75], v126 offset:22528
	ds_read_b128 v[76:79], v126 offset:23552
	global_load_lds_dwordx4 v[80:81], off
	v_lshl_add_u64 v[80:81], v[138:139], 0, s[10:11]
	s_mov_b32 m0, s43
	s_nop 0
	global_load_lds_dwordx4 v[80:81], off
	s_barrier
	s_waitcnt lgkmcnt(0)
	s_setprio 1
	s_waitcnt lgkmcnt(0)
	v_mfma_f32_16x16x32_bf16 v[80:83], v[0:3], v[44:47], 0
	v_mfma_f32_16x16x32_bf16 v[44:47], v[8:11], v[44:47], 0
	v_mfma_f32_16x16x32_bf16 v[80:83], v[4:7], v[52:55], v[80:83]
	v_mfma_f32_16x16x32_bf16 v[44:47], v[12:15], v[52:55], v[44:47]
	v_mfma_f32_16x16x32_bf16 v[52:55], v[0:3], v[56:59], 0
	v_mfma_f32_16x16x32_bf16 v[56:59], v[8:11], v[56:59], 0
	v_mfma_f32_16x16x32_bf16 v[52:55], v[4:7], v[60:63], v[52:55]
	v_mfma_f32_16x16x32_bf16 v[56:59], v[12:15], v[60:63], v[56:59]
	v_mfma_f32_16x16x32_bf16 v[60:63], v[0:3], v[64:67], 0
	v_mfma_f32_16x16x32_bf16 v[0:3], v[0:3], v[72:75], 0
	v_mfma_f32_16x16x32_bf16 v[60:63], v[4:7], v[68:71], v[60:63]
	v_mfma_f32_16x16x32_bf16 v[64:67], v[8:11], v[64:67], 0
	v_mfma_f32_16x16x32_bf16 v[0:3], v[4:7], v[76:79], v[0:3]
	v_mfma_f32_16x16x32_bf16 v[4:7], v[8:11], v[72:75], 0
	v_mfma_f32_16x16x32_bf16 v[64:67], v[12:15], v[68:71], v[64:67]
	s_barrier
	v_mfma_f32_16x16x32_bf16 v[4:7], v[12:15], v[76:79], v[4:7]
	s_setprio 0
	s_add_u32 s52, s36, 0x10100
	s_addc_u32 s53, s37, 0
	s_mov_b32 m0, s50
	v_lshl_add_u64 v[8:9], s[52:53], 0, v[96:97]
	global_load_lds_dwordx4 v[8:9], off
	v_lshl_add_u64 v[8:9], s[52:53], 0, v[98:99]
	s_mov_b32 m0, s51
	s_nop 0
	global_load_lds_dwordx4 v[8:9], off
	s_waitcnt vmcnt(6)
	s_barrier
	s_setprio 1
	s_setprio 0
	s_add_i32 s19, 0, 0x18000
	v_add_u32_e32 v100, s19, v121
	s_barrier
	ds_read_b128 v[8:11], v100
	ds_read_b128 v[12:15], v100 offset:1024
	ds_read_b128 v[68:71], v100 offset:2048
	ds_read_b128 v[72:75], v100 offset:3072
	s_add_u32 s52, s4, 0x10100
	s_addc_u32 s53, s5, 0
	s_mov_b32 m0, s54
	v_lshl_add_u64 v[140:141], s[52:53], 0, v[96:97]
	ds_read_b128 v[76:79], v126 offset:32768
	ds_read_b128 v[84:87], v126 offset:33792
	ds_read_b128 v[88:91], v126 offset:34816
	ds_read_b128 v[92:95], v126 offset:35840
	ds_read_b128 v[108:111], v126 offset:36864
	ds_read_b128 v[112:115], v126 offset:37888
	ds_read_b128 v[116:119], v126 offset:38912
	ds_read_b128 v[128:131], v126 offset:39936
	global_load_lds_dwordx4 v[140:141], off
	v_lshl_add_u64 v[140:141], s[52:53], 0, v[98:99]
	s_mov_b32 m0, s55
	s_nop 0
	global_load_lds_dwordx4 v[140:141], off
	s_waitcnt lgkmcnt(8)
	s_barrier
; #define PG8_STAGE(bufoff, gbase, voff) do { _Pragma("unroll") for (int _i = 0; _i < 2; ++_i) \
;         __builtin_amdgcn_global_load_lds((const unsigned*)((const char*)(gbase) + (voff)[_i]), (LAS unsigned*)(lds + (bufoff) + ldsw + _i * 8192), 16, 0, 0); } while (0)
; #define PG8_LDA(dst, b, h) do { _Pragma("unroll") for (int m = 0; m < 4; ++m) _Pragma("unroll") for (int k = 0; k < 2; ++k) dst[m][k] = *(const LAS bf16x8*)(lds + PG8_SA(b, h) + aoff + m * 2048 + k * 1024); } while (0)
; #define PG8_LDB(dst, b, h) do { _Pragma("unroll") for (int n = 0; n < 2; ++n) _Pragma("unroll") for (int k = 0; k < 2; ++k) dst[n][k] = *(const LAS bf16x8*)(lds + PG8_SB(b, h) + boff + n * 2048 + k * 1024); } while (0)
; #define PG8_MMA(ai, bj, At, Bt) do { __builtin_amdgcn_s_setprio(1); _Pragma("unroll") for (int m = 0; m < 4; ++m) _Pragma("unroll") for (int n = 0; n < 2; ++n) _Pragma("unroll") for (int k = 0; k < 2; ++k) \
;         acc[ai][bj][m][n] = __builtin_amdgcn_mfma_f32_16x16x32_bf16(Bt[n][k], At[m][k], acc[ai][bj][m][n], 0, 0, 0); __builtin_amdgcn_s_setprio(0); } while (0)
; #define PG8_WAIT_V(n) asm volatile("s_waitcnt vmcnt(" #n ")" ::: "memory")
; #define PG8_WAIT_L(n) asm volatile("s_waitcnt lgkmcnt(" #n ")" ::: "memory")
; #define PG8_BAR __builtin_amdgcn_s_barrier()
; #define PG8_SCHED __builtin_amdgcn_sched_barrier(0)
; template <class Epi>
; __device__ __forceinline__ void gemm_phase(LAS unsigned char* lds, const Gemm g, const Sched& S, const Epi& E) {
;     ...
;             PG8_WAIT_V(6); PG8_BAR; PG8_MMA(1, 1, At, B1); PG8_BAR;
;             PG8_LDB(B0, 1, 0); PG8_SCHED; PG8_LDA(At, 1, 0); PG8_STAGE(PG8_SA(0, 1), a2 + hstepA, voffA);
;             PG8_WAIT_L(8); PG8_BAR; PG8_WAIT_L(0); PG8_MMA(0, 0, At, B0); PG8_BAR; PG8_SCHED;
;             PG8_LDB(B1, 1, 1); PG8_STAGE(PG8_SB(1, 0), b3, voffB);
;             PG8_BAR; PG8_WAIT_L(0); PG8_MMA(0, 1, At, B1); PG8_BAR;
;             PG8_LDA(At, 1, 1); PG8_STAGE(PG8_SA(1, 0), a3, voffA);
;             PG8_BAR; PG8_WAIT_L(0); PG8_MMA(1, 0, At, B0); PG8_BAR; PG8_SCHED;
;             PG8_STAGE(PG8_SB(1, 1), b3 + hstepB, voffB);
;             PG8_WAIT_V(6); PG8_BAR; PG8_MMA(1, 1, At, B1); PG8_BAR;
	s_waitcnt lgkmcnt(0)
	s_setprio 1
	s_waitcnt lgkmcnt(0)
	v_mfma_f32_16x16x32_bf16 v[48:51], v[8:11], v[76:79], v[48:51]
	v_mfma_f32_16x16x32_bf16 v[16:19], v[68:71], v[76:79], v[16:19]
	v_mfma_f32_16x16x32_bf16 v[20:23], v[8:11], v[88:91], v[20:23]
	v_mfma_f32_16x16x32_bf16 v[24:27], v[68:71], v[88:91], v[24:27]
	v_mfma_f32_16x16x32_bf16 v[28:31], v[8:11], v[108:111], v[28:31]
	v_mfma_f32_16x16x32_bf16 v[32:35], v[68:71], v[108:111], v[32:35]
	v_mfma_f32_16x16x32_bf16 v[36:39], v[8:11], v[116:119], v[36:39]
	v_mfma_f32_16x16x32_bf16 v[40:43], v[68:71], v[116:119], v[40:43]
	v_mfma_f32_16x16x32_bf16 v[48:51], v[12:15], v[84:87], v[48:51]
	v_mfma_f32_16x16x32_bf16 v[16:19], v[72:75], v[84:87], v[16:19]
	v_mfma_f32_16x16x32_bf16 v[20:23], v[12:15], v[92:95], v[20:23]
	v_mfma_f32_16x16x32_bf16 v[24:27], v[72:75], v[92:95], v[24:27]
	v_mfma_f32_16x16x32_bf16 v[28:31], v[12:15], v[112:115], v[28:31]
	v_mfma_f32_16x16x32_bf16 v[32:35], v[72:75], v[112:115], v[32:35]
	v_mfma_f32_16x16x32_bf16 v[36:39], v[12:15], v[128:131], v[36:39]
	s_barrier
	v_mfma_f32_16x16x32_bf16 v[40:43], v[72:75], v[128:131], v[40:43]
	s_setprio 0
	s_add_i32 s19, s19, s34
	v_lshl_add_u64 v[76:77], v[132:133], 0, s[12:13]
	s_mov_b32 m0, s19
	s_add_i32 s17, s19, 0x2000
	global_load_lds_dwordx4 v[76:77], off
	v_lshl_add_u64 v[76:77], v[134:135], 0, s[12:13]
	s_mov_b32 m0, s17
	s_nop 0
	global_load_lds_dwordx4 v[76:77], off
	s_barrier
	s_waitcnt lgkmcnt(0)
	s_setprio 1
	s_setprio 0
	s_mov_b32 m0, s56
	v_lshl_add_u64 v[132:133], v[136:137], 0, s[12:13]
	s_barrier
	ds_read_b128 v[76:79], v126 offset:49152
	ds_read_b128 v[84:87], v126 offset:50176
	ds_read_b128 v[88:91], v126 offset:51200
	ds_read_b128 v[92:95], v126 offset:52224
	ds_read_b128 v[108:111], v126 offset:53248
	ds_read_b128 v[112:115], v126 offset:54272
	ds_read_b128 v[116:119], v126 offset:55296
	ds_read_b128 v[128:131], v126 offset:56320
	global_load_lds_dwordx4 v[132:133], off
	v_lshl_add_u64 v[132:133], v[138:139], 0, s[12:13]
	s_mov_b32 m0, s57
	s_nop 0
	global_load_lds_dwordx4 v[132:133], off
	s_barrier
	s_waitcnt lgkmcnt(0)
	s_setprio 1
	s_waitcnt lgkmcnt(0)
	v_mfma_f32_16x16x32_bf16 v[80:83], v[8:11], v[76:79], v[80:83]
	v_mfma_f32_16x16x32_bf16 v[44:47], v[68:71], v[76:79], v[44:47]
	v_mfma_f32_16x16x32_bf16 v[52:55], v[8:11], v[88:91], v[52:55]
	v_mfma_f32_16x16x32_bf16 v[56:59], v[68:71], v[88:91], v[56:59]
	v_mfma_f32_16x16x32_bf16 v[60:63], v[8:11], v[108:111], v[60:63]
	v_mfma_f32_16x16x32_bf16 v[64:67], v[68:71], v[108:111], v[64:67]
	v_mfma_f32_16x16x32_bf16 v[0:3], v[8:11], v[116:119], v[0:3]
	v_mfma_f32_16x16x32_bf16 v[4:7], v[68:71], v[116:119], v[4:7]
	v_mfma_f32_16x16x32_bf16 v[80:83], v[12:15], v[84:87], v[80:83]
	v_mfma_f32_16x16x32_bf16 v[44:47], v[72:75], v[84:87], v[44:47]
	v_mfma_f32_16x16x32_bf16 v[52:55], v[12:15], v[92:95], v[52:55]
	v_mfma_f32_16x16x32_bf16 v[56:59], v[72:75], v[92:95], v[56:59]
	v_mfma_f32_16x16x32_bf16 v[60:63], v[12:15], v[112:115], v[60:63]
	v_mfma_f32_16x16x32_bf16 v[64:67], v[72:75], v[112:115], v[64:67]
	v_mfma_f32_16x16x32_bf16 v[0:3], v[12:15], v[128:131], v[0:3]
	s_barrier
	v_mfma_f32_16x16x32_bf16 v[4:7], v[72:75], v[128:131], v[4:7]
	s_setprio 0
	s_add_u32 s36, s36, 0x10180
	s_addc_u32 s37, s37, 0
	s_mov_b32 m0, s60
	v_lshl_add_u64 v[8:9], s[36:37], 0, v[96:97]
	global_load_lds_dwordx4 v[8:9], off
	v_lshl_add_u64 v[8:9], s[36:37], 0, v[98:99]
	s_mov_b32 m0, s61
	s_nop 0
	global_load_lds_dwordx4 v[8:9], off
	s_waitcnt vmcnt(6)
	s_barrier
	s_setprio 1
	s_setprio 0
	s_barrier
	ds_read_b128 v[8:11], v125
	ds_read_b128 v[12:15], v125 offset:1024
	ds_read_b128 v[68:71], v125 offset:2048
	ds_read_b128 v[72:75], v125 offset:3072
	s_add_u32 s4, s4, 0x10180
	s_addc_u32 s5, s5, 0
	s_mov_b32 m0, s70
	v_lshl_add_u64 v[132:133], s[4:5], 0, v[96:97]
	ds_read_b128 v[76:79], v126
	ds_read_b128 v[84:87], v126 offset:1024
	ds_read_b128 v[88:91], v126 offset:2048
	ds_read_b128 v[92:95], v126 offset:3072
	ds_read_b128 v[108:111], v126 offset:4096
	ds_read_b128 v[112:115], v126 offset:5120
	ds_read_b128 v[116:119], v126 offset:6144
	ds_read_b128 v[128:131], v126 offset:7168
	global_load_lds_dwordx4 v[132:133], off
	v_lshl_add_u64 v[132:133], s[4:5], 0, v[98:99]
	s_mov_b32 m0, s71
	s_nop 0
	global_load_lds_dwordx4 v[132:133], off
	s_waitcnt lgkmcnt(8)
	s_barrier
	s_waitcnt lgkmcnt(0)
	s_setprio 1
	s_waitcnt lgkmcnt(0)
	v_mfma_f32_16x16x32_bf16 v[48:51], v[8:11], v[76:79], v[48:51]
	v_mfma_f32_16x16x32_bf16 v[16:19], v[68:71], v[76:79], v[16:19]
	v_mfma_f32_16x16x32_bf16 v[20:23], v[8:11], v[88:91], v[20:23]
	v_mfma_f32_16x16x32_bf16 v[24:27], v[68:71], v[88:91], v[24:27]
	v_mfma_f32_16x16x32_bf16 v[28:31], v[8:11], v[108:111], v[28:31]
	v_mfma_f32_16x16x32_bf16 v[32:35], v[68:71], v[108:111], v[32:35]
	v_mfma_f32_16x16x32_bf16 v[36:39], v[8:11], v[116:119], v[36:39]
	v_mfma_f32_16x16x32_bf16 v[40:43], v[68:71], v[116:119], v[40:43]
	v_mfma_f32_16x16x32_bf16 v[48:51], v[12:15], v[84:87], v[48:51]
	v_mfma_f32_16x16x32_bf16 v[16:19], v[72:75], v[84:87], v[16:19]
	v_mfma_f32_16x16x32_bf16 v[20:23], v[12:15], v[92:95], v[20:23]
	v_mfma_f32_16x16x32_bf16 v[24:27], v[72:75], v[92:95], v[24:27]
	v_mfma_f32_16x16x32_bf16 v[28:31], v[12:15], v[112:115], v[28:31]
	v_mfma_f32_16x16x32_bf16 v[32:35], v[72:75], v[112:115], v[32:35]
	v_mfma_f32_16x16x32_bf16 v[36:39], v[12:15], v[128:131], v[36:39]
	s_barrier
	v_mfma_f32_16x16x32_bf16 v[40:43], v[72:75], v[128:131], v[40:43]
	s_setprio 0
	s_mov_b32 m0, s84
	v_lshl_add_u64 v[152:153], s[38:39], 0, v[96:97]
	global_load_lds_dwordx4 v[152:153], off
	v_lshl_add_u64 v[154:155], s[38:39], 0, v[98:99]
	s_mov_b32 m0, s85
	s_nop 0
	global_load_lds_dwordx4 v[154:155], off
	s_barrier
; #define PG8_STAGE(bufoff, gbase, voff) do { _Pragma("unroll") for (int _i = 0; _i < 2; ++_i) \
;         __builtin_amdgcn_global_load_lds((const unsigned*)((const char*)(gbase) + (voff)[_i]), (LAS unsigned*)(lds + (bufoff) + ldsw + _i * 8192), 16, 0, 0); } while (0)
; #define PG8_LDA(dst, b, h) do { _Pragma("unroll") for (int m = 0; m < 4; ++m) _Pragma("unroll") for (int k = 0; k < 2; ++k) dst[m][k] = *(const LAS bf16x8*)(lds + PG8_SA(b, h) + aoff + m * 2048 + k * 1024); } while (0)
; #define PG8_LDB(dst, b, h) do { _Pragma("unroll") for (int n = 0; n < 2; ++n) _Pragma("unroll") for (int k = 0; k < 2; ++k) dst[n][k] = *(const LAS bf16x8*)(lds + PG8_SB(b, h) + boff + n * 2048 + k * 1024); } while (0)
; #define PG8_WAIT_V(n) asm volatile("s_waitcnt vmcnt(" #n ")" ::: "memory")
; #define PG8_WAIT_L(n) asm volatile("s_waitcnt lgkmcnt(" #n ")" ::: "memory")
; #define PG8_BAR __builtin_amdgcn_s_barrier()
; #define PG8_SCHED __builtin_amdgcn_sched_barrier(0)
; template <class Epi>
; __device__ __forceinline__ void gemm_phase(LAS unsigned char* lds, const Gemm g, const Sched& S, const Epi& E) {
;     ...
;             PG8_LDB(B0, 0, 0); PG8_SCHED; PG8_LDA(At, 0, 0); PG8_STAGE(PG8_SA(1, 1), a1 + hstepA, voffA);
;             PG8_WAIT_L(8); PG8_BAR; PG8_WAIT_L(0); PG8_MMA(0, 0, At, B0); PG8_BAR; PG8_SCHED;
;             PG8_LDB(B1, 0, 1); PG8_STAGE(PG8_SB(0, 0), b2, voffB);
;             PG8_BAR; PG8_WAIT_L(0); PG8_MMA(0, 1, At, B1); PG8_BAR;
;             PG8_LDA(At, 0, 1); PG8_STAGE(PG8_SA(0, 0), a2, voffA);
;             PG8_BAR; PG8_WAIT_L(0); PG8_MMA(1, 0, At, B0); PG8_BAR; PG8_SCHED;
;             PG8_STAGE(PG8_SB(0, 1), b2 + hstepB, voffB);
;             PG8_WAIT_V(6); PG8_BAR; PG8_MMA(1, 1, At, B1); PG8_BAR;
;             PG8_LDB(B0, 1, 0); PG8_SCHED; PG8_LDA(At, 1, 0); PG8_STAGE(PG8_SA(0, 1), a2 + hstepA, voffA);
;             PG8_WAIT_L(8); PG8_BAR; PG8_WAIT_L(0); PG8_MMA(0, 0, At, B0); PG8_BAR; PG8_SCHED;
;             PG8_LDB(B1, 1, 1); PG8_STAGE(PG8_SB(1, 0), b3, voffB);
;             PG8_BAR; PG8_WAIT_L(0); PG8_MMA(0, 1, At, B1); PG8_BAR;
;             PG8_LDA(At, 1, 1); PG8_STAGE(PG8_SA(1, 0), a3, voffA);
;             PG8_BAR; PG8_WAIT_L(0); PG8_MMA(1, 0, At, B0); PG8_BAR; PG8_SCHED;
;             PG8_STAGE(PG8_SB(1, 1), b3 + hstepB, voffB);
;             PG8_WAIT_V(6); PG8_BAR; PG8_MMA(1, 1, At, B1); PG8_BAR;
	s_waitcnt lgkmcnt(0)
	s_setprio 1
	s_setprio 0
	s_mov_b32 m0, s35
	v_lshl_add_u64 v[156:157], s[22:23], 0, v[96:97]
	s_barrier
	ds_read_b128 v[76:79], v126 offset:16384
	ds_read_b128 v[84:87], v126 offset:17408
	ds_read_b128 v[88:91], v126 offset:18432
	ds_read_b128 v[92:95], v126 offset:19456
	ds_read_b128 v[108:111], v126 offset:20480
	ds_read_b128 v[112:115], v126 offset:21504
	ds_read_b128 v[116:119], v126 offset:22528
	ds_read_b128 v[128:131], v126 offset:23552
	global_load_lds_dwordx4 v[156:157], off
	v_lshl_add_u64 v[158:159], s[22:23], 0, v[98:99]
	s_mov_b32 m0, s43
	s_nop 0
	global_load_lds_dwordx4 v[158:159], off
	s_barrier
	s_waitcnt lgkmcnt(0)
	s_setprio 1
	s_waitcnt lgkmcnt(0)
	v_mfma_f32_16x16x32_bf16 v[52:55], v[8:11], v[88:91], v[52:55]
	v_mfma_f32_16x16x32_bf16 v[136:139], v[12:15], v[92:95], v[52:55]
	v_mfma_f32_16x16x32_bf16 v[52:55], v[68:71], v[88:91], v[56:59]
	v_mfma_f32_16x16x32_bf16 v[56:59], v[72:75], v[92:95], v[52:55]
	v_mfma_f32_16x16x32_bf16 v[52:55], v[8:11], v[108:111], v[60:63]
	v_mfma_f32_16x16x32_bf16 v[44:47], v[68:71], v[76:79], v[44:47]
	v_mfma_f32_16x16x32_bf16 v[60:63], v[12:15], v[112:115], v[52:55]
	v_mfma_f32_16x16x32_bf16 v[52:55], v[68:71], v[108:111], v[64:67]
	v_mfma_f32_16x16x32_bf16 v[0:3], v[8:11], v[116:119], v[0:3]
	v_mfma_f32_16x16x32_bf16 v[4:7], v[68:71], v[116:119], v[4:7]
	v_mfma_f32_16x16x32_bf16 v[80:83], v[8:11], v[76:79], v[80:83]
	v_mfma_f32_16x16x32_bf16 v[44:47], v[72:75], v[84:87], v[44:47]
	v_mfma_f32_16x16x32_bf16 v[108:111], v[72:75], v[112:115], v[52:55]
	v_mfma_f32_16x16x32_bf16 v[0:3], v[12:15], v[128:131], v[0:3]
	v_mfma_f32_16x16x32_bf16 v[112:115], v[72:75], v[128:131], v[4:7]
	s_barrier
	v_mfma_f32_16x16x32_bf16 v[132:135], v[12:15], v[84:87], v[80:83]
	s_setprio 0
	s_add_u32 s4, s38, 0x10000
	s_addc_u32 s5, s39, 0
	s_mov_b32 m0, s50
	v_lshl_add_u64 v[4:5], s[4:5], 0, v[96:97]
	global_load_lds_dwordx4 v[4:5], off
	v_lshl_add_u64 v[4:5], s[4:5], 0, v[98:99]
	s_mov_b32 m0, s51
	s_nop 0
	global_load_lds_dwordx4 v[4:5], off
	s_waitcnt vmcnt(6)
	s_barrier
	s_setprio 1
	s_setprio 0
	s_barrier
	ds_read_b128 v[4:7], v100
	ds_read_b128 v[116:119], v100 offset:1024
	ds_read_b128 v[128:131], v100 offset:2048
	ds_read_b128 v[140:143], v100 offset:3072
	s_add_u32 s4, s22, 0x10000
	s_addc_u32 s5, s23, 0
	s_mov_b32 m0, s54
	v_lshl_add_u64 v[76:77], s[4:5], 0, v[96:97]
	ds_read_b128 v[8:11], v126 offset:32768
	ds_read_b128 v[12:15], v126 offset:33792
	ds_read_b128 v[52:55], v126 offset:34816
	ds_read_b128 v[64:67], v126 offset:35840
	ds_read_b128 v[68:71], v126 offset:36864
	ds_read_b128 v[72:75], v126 offset:37888
	ds_read_b128 v[144:147], v126 offset:38912
	ds_read_b128 v[148:151], v126 offset:39936
	global_load_lds_dwordx4 v[76:77], off
	v_lshl_add_u64 v[76:77], s[4:5], 0, v[98:99]
	s_mov_b32 m0, s55
	s_nop 0
	global_load_lds_dwordx4 v[76:77], off
	s_waitcnt lgkmcnt(8)
	s_barrier
	s_waitcnt lgkmcnt(0)
	s_setprio 1
	s_waitcnt lgkmcnt(0)
	v_mfma_f32_16x16x32_bf16 v[48:51], v[4:7], v[8:11], v[48:51]
	v_mfma_f32_16x16x32_bf16 v[8:11], v[128:131], v[8:11], v[16:19]
	v_mfma_f32_16x16x32_bf16 v[88:91], v[140:143], v[12:15], v[8:11]
	v_mfma_f32_16x16x32_bf16 v[8:11], v[4:7], v[52:55], v[20:23]
	v_mfma_f32_16x16x32_bf16 v[84:87], v[116:119], v[64:67], v[8:11]
	v_mfma_f32_16x16x32_bf16 v[8:11], v[128:131], v[52:55], v[24:27]
	v_mfma_f32_16x16x32_bf16 v[80:83], v[140:143], v[64:67], v[8:11]
	v_mfma_f32_16x16x32_bf16 v[8:11], v[4:7], v[68:71], v[28:31]
	v_mfma_f32_16x16x32_bf16 v[76:79], v[116:119], v[72:75], v[8:11]
	v_mfma_f32_16x16x32_bf16 v[8:11], v[128:131], v[68:71], v[32:35]
	v_mfma_f32_16x16x32_bf16 v[72:75], v[140:143], v[72:75], v[8:11]
	v_mfma_f32_16x16x32_bf16 v[8:11], v[4:7], v[144:147], v[36:39]
	v_mfma_f32_16x16x32_bf16 v[68:71], v[116:119], v[148:151], v[8:11]
	v_mfma_f32_16x16x32_bf16 v[8:11], v[128:131], v[144:147], v[40:43]
	v_mfma_f32_16x16x32_bf16 v[92:95], v[116:119], v[12:15], v[48:51]
	s_barrier
; #define PG8_STAGE(bufoff, gbase, voff) do { _Pragma("unroll") for (int _i = 0; _i < 2; ++_i) \
;         __builtin_amdgcn_global_load_lds((const unsigned*)((const char*)(gbase) + (voff)[_i]), (LAS unsigned*)(lds + (bufoff) + ldsw + _i * 8192), 16, 0, 0); } while (0)
; #define PG8_LDA(dst, b, h) do { _Pragma("unroll") for (int m = 0; m < 4; ++m) _Pragma("unroll") for (int k = 0; k < 2; ++k) dst[m][k] = *(const LAS bf16x8*)(lds + PG8_SA(b, h) + aoff + m * 2048 + k * 1024); } while (0)
; #define PG8_LDB(dst, b, h) do { _Pragma("unroll") for (int n = 0; n < 2; ++n) _Pragma("unroll") for (int k = 0; k < 2; ++k) dst[n][k] = *(const LAS bf16x8*)(lds + PG8_SB(b, h) + boff + n * 2048 + k * 1024); } while (0)
; #define PG8_WAIT_V(n) asm volatile("s_waitcnt vmcnt(" #n ")" ::: "memory")
; #define PG8_WAIT_L(n) asm volatile("s_waitcnt lgkmcnt(" #n ")" ::: "memory")
; template <class Epi>
; __device__ __forceinline__ void gemm_phase(LAS unsigned char* lds, const Gemm g, const Sched& S, const Epi& E) {
;     ...
;             PG8_WAIT_V(6); PG8_BAR; PG8_MMA(1, 1, At, B1); PG8_BAR;
;             PG8_LDB(B0, 1, 0); PG8_SCHED; PG8_LDA(At, 1, 0); PG8_STAGE(PG8_SA(0, 1), a2 + hstepA, voffA);
;             PG8_WAIT_L(8); PG8_BAR; PG8_WAIT_L(0); PG8_MMA(0, 0, At, B0); PG8_BAR; PG8_SCHED;
;             PG8_LDB(B1, 1, 1); PG8_STAGE(PG8_SB(1, 0), b3, voffB);
;             PG8_BAR; PG8_WAIT_L(0); PG8_MMA(0, 1, At, B1); PG8_BAR;
;             PG8_LDA(At, 1, 1); PG8_STAGE(PG8_SA(1, 0), a3, voffA);
;             PG8_BAR; PG8_WAIT_L(0); PG8_MMA(1, 0, At, B0); PG8_BAR; PG8_SCHED;
;             PG8_STAGE(PG8_SB(1, 1), b3 + hstepB, voffB);
;             PG8_WAIT_V(6); PG8_BAR; PG8_MMA(1, 1, At, B1); PG8_BAR;
;     __device__ __forceinline__ void operator()(AccRef acc, const Unit& u, int wr, int wc, int fr, int fq) const {
;     ...
;         for (int ai = 0; ai < 2; ++ai) {
;             f32x2 t0[4][2], t1[4][2];
;             if (kv == 0) {
; #pragma unroll
;                 for (int m = 0; m < 4; ++m)
; #pragma unroll
;                     for (int n = 0; n < 2; ++n) { const int n_ = u.pm * 256 + ai * 128 + wr * 64 + m * 16 + fr; int sp = 16 * n_ + 31; sp = sp < S_ ? sp : S_ - 1; const int p0 = wc * 32 + n * 16 + 4 * fq;
;                         const f32x2* tb = rope + ((size_t)b * S_ + sp) * 64 + (p0 >> 1); t0[m][n] = tb[0]; t1[m][n] = tb[1]; }
;             }
	v_mfma_f32_16x16x32_bf16 v[64:67], v[140:143], v[148:151], v[8:11]
	s_setprio 0
	s_mov_b32 m0, s19
	s_nop 2
	v_lshl_add_u64 v[8:9], v[152:153], 0, s[8:9]
	global_load_lds_dwordx4 v[8:9], off
	v_lshl_add_u64 v[8:9], v[154:155], 0, s[8:9]
	s_mov_b32 m0, s17
	s_nop 0
	global_load_lds_dwordx4 v[8:9], off
	s_barrier
	s_waitcnt lgkmcnt(0)
	s_setprio 1
	s_setprio 0
	s_mov_b32 m0, s56
	v_lshl_add_u64 v[32:33], v[156:157], 0, s[8:9]
	s_barrier
	ds_read_b128 v[8:11], v126 offset:49152
	ds_read_b128 v[12:15], v126 offset:50176
	ds_read_b128 v[16:19], v126 offset:51200
	ds_read_b128 v[20:23], v126 offset:52224
	ds_read_b128 v[24:27], v126 offset:53248
	ds_read_b128 v[28:31], v126 offset:54272
	ds_read_b128 v[36:39], v126 offset:55296
	ds_read_b128 v[48:51], v126 offset:56320
	global_load_lds_dwordx4 v[32:33], off
	v_lshl_add_u64 v[32:33], v[158:159], 0, s[8:9]
	s_mov_b32 m0, s57
	s_nop 0
	global_load_lds_dwordx4 v[32:33], off
	s_barrier
	s_waitcnt lgkmcnt(0)
	s_setprio 1
	s_waitcnt lgkmcnt(0)
	v_mfma_f32_16x16x32_bf16 v[32:35], v[4:7], v[8:11], v[132:135]
	v_mfma_f32_16x16x32_bf16 v[8:11], v[128:131], v[8:11], v[44:47]
	v_mfma_f32_16x16x32_bf16 v[40:43], v[140:143], v[12:15], v[8:11]
	v_mfma_f32_16x16x32_bf16 v[8:11], v[4:7], v[16:19], v[136:139]
	v_mfma_f32_16x16x32_bf16 v[52:55], v[116:119], v[12:15], v[32:35]
	v_mfma_f32_16x16x32_bf16 v[32:35], v[116:119], v[20:23], v[8:11]
	v_mfma_f32_16x16x32_bf16 v[8:11], v[128:131], v[16:19], v[56:59]
	v_mfma_f32_16x16x32_bf16 v[20:23], v[140:143], v[20:23], v[8:11]
	v_mfma_f32_16x16x32_bf16 v[8:11], v[4:7], v[24:27], v[60:63]
	v_mfma_f32_16x16x32_bf16 v[0:3], v[4:7], v[36:39], v[0:3]
	v_mfma_f32_16x16x32_bf16 v[12:15], v[116:119], v[28:31], v[8:11]
	v_mfma_f32_16x16x32_bf16 v[8:11], v[128:131], v[24:27], v[108:111]
	v_mfma_f32_16x16x32_bf16 v[4:7], v[116:119], v[48:51], v[0:3]
	v_mfma_f32_16x16x32_bf16 v[0:3], v[128:131], v[36:39], v[112:115]
	v_mfma_f32_16x16x32_bf16 v[8:11], v[140:143], v[28:31], v[8:11]
	s_barrier
	v_mfma_f32_16x16x32_bf16 v[0:3], v[140:143], v[48:51], v[0:3]
	s_setprio 0
	s_add_u32 s4, s38, 0x10080
	s_addc_u32 s5, s39, 0
	s_mov_b32 m0, s60
	v_lshl_add_u64 v[16:17], s[4:5], 0, v[96:97]
	global_load_lds_dwordx4 v[16:17], off
	v_lshl_add_u64 v[16:17], s[4:5], 0, v[98:99]
	s_mov_b32 m0, s61
	s_nop 0
	global_load_lds_dwordx4 v[16:17], off
	s_waitcnt vmcnt(6)
	s_barrier
	s_setprio 1
	s_setprio 0
	s_cmp_lt_u32 s66, 8
	s_cselect_b64 s[38:39], -1, 0
	s_cmp_gt_u32 s66, 7
	s_cselect_b64 s[52:53], -1, 0
	v_lshl_add_u32 v108, s6, 8, v120
	s_lshl_b32 s4, s66, 12
	s_and_b32 s6, s4, 0x4000
	s_and_b64 vcc, exec, s[52:53]
	v_or_b32_e32 v114, 16, v108
	v_or_b32_e32 v112, 32, v108
	v_or_b32_e32 v110, 48, v108
	s_barrier
	s_cbranch_vccnz .LBB0_643
	v_lshl_add_u32 v16, v108, 4, 31
	v_cmp_gt_i32_e32 vcc, s80, v108
	s_nop 1
	v_cndmask_b32_e32 v16, v127, v16, vcc
	v_ashrrev_i32_e32 v17, 31, v16
	v_lshl_add_u64 v[16:17], v[16:17], 0, s[6:7]
	v_lshlrev_b64 v[16:17], 9, v[16:17]
	v_lshl_add_u64 v[16:17], v[104:105], 0, v[16:17]
	global_load_dwordx4 v[60:63], v[16:17], off
	global_load_dwordx4 v[56:59], v[16:17], off offset:64
	v_lshl_add_u32 v16, v114, 4, 31
	v_cmp_gt_i32_e32 vcc, s80, v114
	s_nop 1
	v_cndmask_b32_e32 v16, v127, v16, vcc
	v_ashrrev_i32_e32 v17, 31, v16
	v_lshl_add_u64 v[16:17], v[16:17], 0, s[6:7]
	v_lshlrev_b64 v[16:17], 9, v[16:17]
	v_lshl_add_u64 v[16:17], v[104:105], 0, v[16:17]
	global_load_dwordx4 v[48:51], v[16:17], off
	global_load_dwordx4 v[44:47], v[16:17], off offset:64
	v_lshl_add_u32 v16, v112, 4, 31
	v_cmp_gt_i32_e32 vcc, s80, v112
	s_nop 1
	v_cndmask_b32_e32 v16, v127, v16, vcc
	v_ashrrev_i32_e32 v17, 31, v16
	v_lshl_add_u64 v[16:17], v[16:17], 0, s[6:7]
	v_lshlrev_b64 v[16:17], 9, v[16:17]
	v_lshl_add_u64 v[16:17], v[104:105], 0, v[16:17]
	global_load_dwordx4 v[36:39], v[16:17], off
	global_load_dwordx4 v[28:31], v[16:17], off offset:64
	v_lshl_add_u32 v16, v110, 4, 31
	v_cmp_gt_i32_e32 vcc, s80, v110
	s_nop 1
	v_cndmask_b32_e32 v16, v127, v16, vcc
	v_ashrrev_i32_e32 v17, 31, v16
	v_lshl_add_u64 v[16:17], v[16:17], 0, s[6:7]
	v_lshlrev_b64 v[16:17], 9, v[16:17]
	v_lshl_add_u64 v[16:17], v[104:105], 0, v[16:17]
	global_load_dwordx4 v[24:27], v[16:17], off
	s_nop 0
	global_load_dwordx4 v[16:19], v[16:17], off offset:64

; #define PG8_STAGE(bufoff, gbase, voff) do { _Pragma("unroll") for (int _i = 0; _i < 2; ++_i) \
;         __builtin_amdgcn_global_load_lds((const unsigned*)((const char*)(gbase) + (voff)[_i]), (LAS unsigned*)(lds + (bufoff) + ldsw + _i * 8192), 16, 0, 0); } while (0)
; #define PG8_LDA(dst, b, h) do { _Pragma("unroll") for (int m = 0; m < 4; ++m) _Pragma("unroll") for (int k = 0; k < 2; ++k) dst[m][k] = *(const LAS bf16x8*)(lds + PG8_SA(b, h) + aoff + m * 2048 + k * 1024); } while (0)
; #define PG8_LDB(dst, b, h) do { _Pragma("unroll") for (int n = 0; n < 2; ++n) _Pragma("unroll") for (int k = 0; k < 2; ++k) dst[n][k] = *(const LAS bf16x8*)(lds + PG8_SB(b, h) + boff + n * 2048 + k * 1024); } while (0)
; #define PG8_MMA(ai, bj, At, Bt) do { __builtin_amdgcn_s_setprio(1); _Pragma("unroll") for (int m = 0; m < 4; ++m) _Pragma("unroll") for (int n = 0; n < 2; ++n) _Pragma("unroll") for (int k = 0; k < 2; ++k) \
;         acc[ai][bj][m][n] = __builtin_amdgcn_mfma_f32_16x16x32_bf16(Bt[n][k], At[m][k], acc[ai][bj][m][n], 0, 0, 0); __builtin_amdgcn_s_setprio(0); } while (0)
; #define PG8_WAIT_V(n) asm volatile("s_waitcnt vmcnt(" #n ")" ::: "memory")
; #define PG8_WAIT_L(n) asm volatile("s_waitcnt lgkmcnt(" #n ")" ::: "memory")
; #define PG8_BAR __builtin_amdgcn_s_barrier()
; #define PG8_SCHED __builtin_amdgcn_sched_barrier(0)
; template <class Epi>
; __device__ __forceinline__ void gemm_phase(LAS unsigned char* lds, const Gemm g, const Sched& S, const Epi& E) {
;     ...
;             PG8_LDB(B0, 0, 0); PG8_SCHED; PG8_LDA(At, 0, 0); PG8_STAGE(PG8_SA(1, 1), a1 + hstepA, voffA);
;             PG8_WAIT_L(8); PG8_BAR; PG8_WAIT_L(0); PG8_MMA(0, 0, At, B0); PG8_BAR; PG8_SCHED;
;             PG8_LDB(B1, 0, 1); PG8_STAGE(PG8_SB(0, 0), b2, voffB);
;             PG8_BAR; PG8_WAIT_L(0); PG8_MMA(0, 1, At, B1); PG8_BAR;
;             PG8_LDA(At, 0, 1); PG8_STAGE(PG8_SA(0, 0), a2, voffA);
;             PG8_BAR; PG8_WAIT_L(0); PG8_MMA(1, 0, At, B0); PG8_BAR; PG8_SCHED;
;             PG8_STAGE(PG8_SB(0, 1), b2 + hstepB, voffB);
;             PG8_WAIT_V(6); PG8_BAR; PG8_MMA(1, 1, At, B1); PG8_BAR;
.LBB0_1967:
	v_add_u32_e32 v144, s56, v202
	s_add_u32 s36, s12, s24
	ds_read_b128 v[132:135], v144
	ds_read_b128 v[136:139], v144 offset:1024
	ds_read_b128 v[140:143], v144 offset:2048
	ds_read_b128 v[144:147], v144 offset:3072
	s_addc_u32 s37, s13, s25
	s_add_u32 s36, s36, 0x100
	s_addc_u32 s37, s37, 0
	s_add_u32 s70, s11, s24
	s_addc_u32 s71, s51, s25
	s_cmpk_eq_i32 s24, 0xf00
	s_cselect_b32 s39, s19, s37
	s_cselect_b32 s38, s65, s36
	s_cselect_b32 s37, s17, s71
	s_cselect_b32 s36, s66, s70
	v_lshl_add_u64 v[198:199], v[128:129], 0, s[24:25]
	s_add_i32 m0, s33, 0xc000
	ds_read_b128 v[148:151], v203
	ds_read_b128 v[152:155], v203 offset:1024
	ds_read_b128 v[156:159], v203 offset:2048
	ds_read_b128 v[160:163], v203 offset:3072
	ds_read_b128 v[164:167], v203 offset:4096
	ds_read_b128 v[168:171], v203 offset:5120
	ds_read_b128 v[172:175], v203 offset:6144
	ds_read_b128 v[194:197], v203 offset:7168
	global_load_lds_dwordx4 v[198:199], off
	v_lshl_add_u64 v[198:199], v[130:131], 0, s[24:25]
	s_add_i32 m0, s33, 0xe000
	s_nop 0
	global_load_lds_dwordx4 v[198:199], off
	s_waitcnt lgkmcnt(8)
	s_barrier
	s_waitcnt lgkmcnt(0)
	s_setprio 1
	s_waitcnt lgkmcnt(0)
	v_mfma_f32_16x16x32_bf16 v[124:127], v[132:135], v[148:151], v[124:127]
	v_mfma_f32_16x16x32_bf16 v[120:123], v[140:143], v[148:151], v[120:123]
	v_mfma_f32_16x16x32_bf16 v[116:119], v[132:135], v[156:159], v[116:119]
	v_mfma_f32_16x16x32_bf16 v[112:115], v[140:143], v[156:159], v[112:115]
	v_mfma_f32_16x16x32_bf16 v[108:111], v[132:135], v[164:167], v[108:111]
	v_mfma_f32_16x16x32_bf16 v[104:107], v[140:143], v[164:167], v[104:107]
	v_mfma_f32_16x16x32_bf16 v[100:103], v[132:135], v[172:175], v[100:103]
	v_mfma_f32_16x16x32_bf16 v[96:99], v[140:143], v[172:175], v[96:99]
	v_mfma_f32_16x16x32_bf16 v[124:127], v[136:139], v[152:155], v[124:127]
	v_mfma_f32_16x16x32_bf16 v[120:123], v[144:147], v[152:155], v[120:123]
	v_mfma_f32_16x16x32_bf16 v[116:119], v[136:139], v[160:163], v[116:119]
	v_mfma_f32_16x16x32_bf16 v[112:115], v[144:147], v[160:163], v[112:115]
	v_mfma_f32_16x16x32_bf16 v[108:111], v[136:139], v[168:171], v[108:111]
	v_mfma_f32_16x16x32_bf16 v[104:107], v[144:147], v[168:171], v[104:107]
	v_mfma_f32_16x16x32_bf16 v[100:103], v[136:139], v[194:197], v[100:103]
	s_barrier
	v_mfma_f32_16x16x32_bf16 v[96:99], v[144:147], v[194:197], v[96:99]
	s_setprio 0
	s_add_i32 s70, s56, s1
	v_add_u32_e32 v212, s57, v202
	v_lshl_add_u64 v[216:217], s[36:37], 0, v[176:177]
	s_mov_b32 m0, s70
	ds_read_b128 v[198:201], v212
	ds_read_b128 v[204:207], v212 offset:1024
	ds_read_b128 v[208:211], v212 offset:2048
	ds_read_b128 v[212:215], v212 offset:3072
	global_load_lds_dwordx4 v[216:217], off
	v_lshl_add_u64 v[218:219], s[36:37], 0, v[178:179]
	s_add_i32 m0, s70, 0x2000
	s_nop 0
	global_load_lds_dwordx4 v[218:219], off
	s_barrier
	s_waitcnt lgkmcnt(0)
	s_setprio 1
	s_waitcnt lgkmcnt(0)
	v_mfma_f32_16x16x32_bf16 v[92:95], v[198:201], v[148:151], v[92:95]
	v_mfma_f32_16x16x32_bf16 v[88:91], v[208:211], v[148:151], v[88:91]
	v_mfma_f32_16x16x32_bf16 v[84:87], v[198:201], v[156:159], v[84:87]
	v_mfma_f32_16x16x32_bf16 v[80:83], v[208:211], v[156:159], v[80:83]
	v_mfma_f32_16x16x32_bf16 v[76:79], v[198:201], v[164:167], v[76:79]
	v_mfma_f32_16x16x32_bf16 v[72:75], v[208:211], v[164:167], v[72:75]
	v_mfma_f32_16x16x32_bf16 v[68:71], v[198:201], v[172:175], v[68:71]
	v_mfma_f32_16x16x32_bf16 v[64:67], v[208:211], v[172:175], v[64:67]
	v_mfma_f32_16x16x32_bf16 v[92:95], v[204:207], v[152:155], v[92:95]
	v_mfma_f32_16x16x32_bf16 v[88:91], v[212:215], v[152:155], v[88:91]
	v_mfma_f32_16x16x32_bf16 v[84:87], v[204:207], v[160:163], v[84:87]
	v_mfma_f32_16x16x32_bf16 v[80:83], v[212:215], v[160:163], v[80:83]
	v_mfma_f32_16x16x32_bf16 v[76:79], v[204:207], v[168:171], v[76:79]
	v_mfma_f32_16x16x32_bf16 v[72:75], v[212:215], v[168:171], v[72:75]
	v_mfma_f32_16x16x32_bf16 v[68:71], v[204:207], v[194:197], v[68:71]
	s_barrier
	v_mfma_f32_16x16x32_bf16 v[64:67], v[212:215], v[194:197], v[64:67]
	s_setprio 0
	s_mov_b32 m0, s33
	v_lshl_add_u64 v[220:221], s[38:39], 0, v[176:177]
	ds_read_b128 v[148:151], v203 offset:16384
	ds_read_b128 v[152:155], v203 offset:17408
	ds_read_b128 v[156:159], v203 offset:18432
	ds_read_b128 v[160:163], v203 offset:19456
	ds_read_b128 v[164:167], v203 offset:20480
	ds_read_b128 v[168:171], v203 offset:21504
	ds_read_b128 v[172:175], v203 offset:22528
	ds_read_b128 v[194:197], v203 offset:23552
	global_load_lds_dwordx4 v[220:221], off
	v_lshl_add_u64 v[222:223], s[38:39], 0, v[178:179]
	s_mov_b32 m0, s34
	s_nop 0
	global_load_lds_dwordx4 v[222:223], off
	s_barrier
	s_waitcnt lgkmcnt(0)
	s_setprio 1
	s_waitcnt lgkmcnt(0)
	v_mfma_f32_16x16x32_bf16 v[60:63], v[132:135], v[148:151], v[60:63]
	v_mfma_f32_16x16x32_bf16 v[56:59], v[140:143], v[148:151], v[56:59]
	v_mfma_f32_16x16x32_bf16 v[52:55], v[132:135], v[156:159], v[52:55]
	v_mfma_f32_16x16x32_bf16 v[48:51], v[140:143], v[156:159], v[48:51]
	v_mfma_f32_16x16x32_bf16 v[44:47], v[132:135], v[164:167], v[44:47]
	v_mfma_f32_16x16x32_bf16 v[40:43], v[140:143], v[164:167], v[40:43]
	v_mfma_f32_16x16x32_bf16 v[36:39], v[132:135], v[172:175], v[36:39]
	v_mfma_f32_16x16x32_bf16 v[32:35], v[140:143], v[172:175], v[32:35]
	v_mfma_f32_16x16x32_bf16 v[60:63], v[136:139], v[152:155], v[60:63]
	v_mfma_f32_16x16x32_bf16 v[56:59], v[144:147], v[152:155], v[56:59]
	v_mfma_f32_16x16x32_bf16 v[52:55], v[136:139], v[160:163], v[52:55]
	v_mfma_f32_16x16x32_bf16 v[48:51], v[144:147], v[160:163], v[48:51]
	v_mfma_f32_16x16x32_bf16 v[44:47], v[136:139], v[168:171], v[44:47]
	v_mfma_f32_16x16x32_bf16 v[40:43], v[144:147], v[168:171], v[40:43]
	v_mfma_f32_16x16x32_bf16 v[36:39], v[136:139], v[194:197], v[36:39]
	s_barrier
; #define PG8_STAGE(bufoff, gbase, voff) do { _Pragma("unroll") for (int _i = 0; _i < 2; ++_i) \
;         __builtin_amdgcn_global_load_lds((const unsigned*)((const char*)(gbase) + (voff)[_i]), (LAS unsigned*)(lds + (bufoff) + ldsw + _i * 8192), 16, 0, 0); } while (0)
; #define PG8_LDA(dst, b, h) do { _Pragma("unroll") for (int m = 0; m < 4; ++m) _Pragma("unroll") for (int k = 0; k < 2; ++k) dst[m][k] = *(const LAS bf16x8*)(lds + PG8_SA(b, h) + aoff + m * 2048 + k * 1024); } while (0)
; #define PG8_LDB(dst, b, h) do { _Pragma("unroll") for (int n = 0; n < 2; ++n) _Pragma("unroll") for (int k = 0; k < 2; ++k) dst[n][k] = *(const LAS bf16x8*)(lds + PG8_SB(b, h) + boff + n * 2048 + k * 1024); } while (0)
; #define PG8_MMA(ai, bj, At, Bt) do { __builtin_amdgcn_s_setprio(1); _Pragma("unroll") for (int m = 0; m < 4; ++m) _Pragma("unroll") for (int n = 0; n < 2; ++n) _Pragma("unroll") for (int k = 0; k < 2; ++k) \
;         acc[ai][bj][m][n] = __builtin_amdgcn_mfma_f32_16x16x32_bf16(Bt[n][k], At[m][k], acc[ai][bj][m][n], 0, 0, 0); __builtin_amdgcn_s_setprio(0); } while (0)
; #define PG8_WAIT_V(n) asm volatile("s_waitcnt vmcnt(" #n ")" ::: "memory")
; #define PG8_WAIT_L(n) asm volatile("s_waitcnt lgkmcnt(" #n ")" ::: "memory")
; #define PG8_BAR __builtin_amdgcn_s_barrier()
; #define PG8_SCHED __builtin_amdgcn_sched_barrier(0)
; template <class Epi>
; __device__ __forceinline__ void gemm_phase(LAS unsigned char* lds, const Gemm g, const Sched& S, const Epi& E) {
;     ...
;             PG8_BAR; PG8_WAIT_L(0); PG8_MMA(1, 0, At, B0); PG8_BAR; PG8_SCHED;
;             PG8_STAGE(PG8_SB(0, 1), b2 + hstepB, voffB);
;             PG8_WAIT_V(6); PG8_BAR; PG8_MMA(1, 1, At, B1); PG8_BAR;
;             PG8_LDB(B0, 1, 0); PG8_SCHED; PG8_LDA(At, 1, 0); PG8_STAGE(PG8_SA(0, 1), a2 + hstepA, voffA);
;             PG8_WAIT_L(8); PG8_BAR; PG8_WAIT_L(0); PG8_MMA(0, 0, At, B0); PG8_BAR; PG8_SCHED;
;             PG8_LDB(B1, 1, 1); PG8_STAGE(PG8_SB(1, 0), b3, voffB);
;             PG8_BAR; PG8_WAIT_L(0); PG8_MMA(0, 1, At, B1); PG8_BAR;
;             PG8_LDA(At, 1, 1); PG8_STAGE(PG8_SA(1, 0), a3, voffA);
;             PG8_BAR; PG8_WAIT_L(0); PG8_MMA(1, 0, At, B0); PG8_BAR; PG8_SCHED;
	v_mfma_f32_16x16x32_bf16 v[32:35], v[144:147], v[194:197], v[32:35]
	s_setprio 0
	s_add_u32 s70, s36, 0x80000
	s_addc_u32 s71, s37, 0
	s_add_i32 s80, s57, s1
	v_lshl_add_u64 v[132:133], s[70:71], 0, v[176:177]
	s_mov_b32 m0, s80
	s_nop 0
	global_load_lds_dwordx4 v[132:133], off
	v_lshl_add_u64 v[132:133], s[70:71], 0, v[178:179]
	s_add_i32 m0, s80, 0x2000
	s_nop 0
	global_load_lds_dwordx4 v[132:133], off
	s_waitcnt vmcnt(6)
	s_barrier
	s_setprio 1
	v_mfma_f32_16x16x32_bf16 v[28:31], v[198:201], v[148:151], v[28:31]
	v_mfma_f32_16x16x32_bf16 v[24:27], v[208:211], v[148:151], v[24:27]
	v_mfma_f32_16x16x32_bf16 v[20:23], v[198:201], v[156:159], v[20:23]
	v_mfma_f32_16x16x32_bf16 v[16:19], v[208:211], v[156:159], v[16:19]
	v_mfma_f32_16x16x32_bf16 v[12:15], v[198:201], v[164:167], v[12:15]
	v_mfma_f32_16x16x32_bf16 v[8:11], v[208:211], v[164:167], v[8:11]
	v_mfma_f32_16x16x32_bf16 v[4:7], v[198:201], v[172:175], v[4:7]
	v_mfma_f32_16x16x32_bf16 v[0:3], v[208:211], v[172:175], v[0:3]
	v_mfma_f32_16x16x32_bf16 v[28:31], v[204:207], v[152:155], v[28:31]
	v_mfma_f32_16x16x32_bf16 v[24:27], v[212:215], v[152:155], v[24:27]
	v_mfma_f32_16x16x32_bf16 v[20:23], v[204:207], v[160:163], v[20:23]
	v_mfma_f32_16x16x32_bf16 v[16:19], v[212:215], v[160:163], v[16:19]
	v_mfma_f32_16x16x32_bf16 v[12:15], v[204:207], v[168:171], v[12:15]
	v_mfma_f32_16x16x32_bf16 v[8:11], v[212:215], v[168:171], v[8:11]
	v_mfma_f32_16x16x32_bf16 v[4:7], v[204:207], v[194:197], v[4:7]
	s_barrier
	v_mfma_f32_16x16x32_bf16 v[0:3], v[212:215], v[194:197], v[0:3]
	s_setprio 0
	s_add_i32 s70, 0, 0x18000
	v_add_u32_e32 v144, s70, v202
	ds_read_b128 v[132:135], v144
	ds_read_b128 v[136:139], v144 offset:1024
	ds_read_b128 v[140:143], v144 offset:2048
	ds_read_b128 v[144:147], v144 offset:3072
	s_add_u32 s38, s38, 0x80000
	s_addc_u32 s39, s39, 0
	s_mov_b32 m0, s35
	v_lshl_add_u64 v[198:199], s[38:39], 0, v[176:177]
	ds_read_b128 v[148:151], v203 offset:32768
	ds_read_b128 v[152:155], v203 offset:33792
	ds_read_b128 v[156:159], v203 offset:34816
	ds_read_b128 v[160:163], v203 offset:35840
	ds_read_b128 v[164:167], v203 offset:36864
	ds_read_b128 v[168:171], v203 offset:37888
	ds_read_b128 v[172:175], v203 offset:38912
	ds_read_b128 v[194:197], v203 offset:39936
	global_load_lds_dwordx4 v[198:199], off
	v_lshl_add_u64 v[198:199], s[38:39], 0, v[178:179]
	s_mov_b32 m0, s43
	s_nop 0
	global_load_lds_dwordx4 v[198:199], off
	s_waitcnt lgkmcnt(8)
	s_barrier
	s_waitcnt lgkmcnt(0)
	s_setprio 1
	s_waitcnt lgkmcnt(0)
	v_mfma_f32_16x16x32_bf16 v[124:127], v[132:135], v[148:151], v[124:127]
	v_mfma_f32_16x16x32_bf16 v[120:123], v[140:143], v[148:151], v[120:123]
	v_mfma_f32_16x16x32_bf16 v[116:119], v[132:135], v[156:159], v[116:119]
	v_mfma_f32_16x16x32_bf16 v[112:115], v[140:143], v[156:159], v[112:115]
	v_mfma_f32_16x16x32_bf16 v[108:111], v[132:135], v[164:167], v[108:111]
	v_mfma_f32_16x16x32_bf16 v[104:107], v[140:143], v[164:167], v[104:107]
	v_mfma_f32_16x16x32_bf16 v[100:103], v[132:135], v[172:175], v[100:103]
	v_mfma_f32_16x16x32_bf16 v[96:99], v[140:143], v[172:175], v[96:99]
	v_mfma_f32_16x16x32_bf16 v[124:127], v[136:139], v[152:155], v[124:127]
	v_mfma_f32_16x16x32_bf16 v[120:123], v[144:147], v[152:155], v[120:123]
	v_mfma_f32_16x16x32_bf16 v[116:119], v[136:139], v[160:163], v[116:119]
	v_mfma_f32_16x16x32_bf16 v[112:115], v[144:147], v[160:163], v[112:115]
	v_mfma_f32_16x16x32_bf16 v[108:111], v[136:139], v[168:171], v[108:111]
	v_mfma_f32_16x16x32_bf16 v[104:107], v[144:147], v[168:171], v[104:107]
	v_mfma_f32_16x16x32_bf16 v[100:103], v[136:139], v[194:197], v[100:103]
	s_barrier
	v_mfma_f32_16x16x32_bf16 v[96:99], v[144:147], v[194:197], v[96:99]
	s_setprio 0
	s_add_i32 s38, 0, 0x1c000
	s_add_i32 s39, s70, s1
	v_add_u32_e32 v212, s38, v202
	v_lshl_add_u64 v[216:217], v[216:217], 0, s[14:15]
	s_mov_b32 m0, s39
	ds_read_b128 v[198:201], v212
	ds_read_b128 v[204:207], v212 offset:1024
	ds_read_b128 v[208:211], v212 offset:2048
	ds_read_b128 v[212:215], v212 offset:3072
	global_load_lds_dwordx4 v[216:217], off
	v_lshl_add_u64 v[216:217], v[218:219], 0, s[14:15]
	s_add_i32 m0, s39, 0x2000
	s_nop 0
	global_load_lds_dwordx4 v[216:217], off
	s_barrier
	s_waitcnt lgkmcnt(0)
	s_setprio 1
	s_waitcnt lgkmcnt(0)
	v_mfma_f32_16x16x32_bf16 v[92:95], v[198:201], v[148:151], v[92:95]
	v_mfma_f32_16x16x32_bf16 v[88:91], v[208:211], v[148:151], v[88:91]
	v_mfma_f32_16x16x32_bf16 v[84:87], v[198:201], v[156:159], v[84:87]
	v_mfma_f32_16x16x32_bf16 v[80:83], v[208:211], v[156:159], v[80:83]
	v_mfma_f32_16x16x32_bf16 v[76:79], v[198:201], v[164:167], v[76:79]
	v_mfma_f32_16x16x32_bf16 v[72:75], v[208:211], v[164:167], v[72:75]
	v_mfma_f32_16x16x32_bf16 v[68:71], v[198:201], v[172:175], v[68:71]
	v_mfma_f32_16x16x32_bf16 v[64:67], v[208:211], v[172:175], v[64:67]
	v_mfma_f32_16x16x32_bf16 v[92:95], v[204:207], v[152:155], v[92:95]
	v_mfma_f32_16x16x32_bf16 v[88:91], v[212:215], v[152:155], v[88:91]
	v_mfma_f32_16x16x32_bf16 v[84:87], v[204:207], v[160:163], v[84:87]
	v_mfma_f32_16x16x32_bf16 v[80:83], v[212:215], v[160:163], v[80:83]
	v_mfma_f32_16x16x32_bf16 v[76:79], v[204:207], v[168:171], v[76:79]
	v_mfma_f32_16x16x32_bf16 v[72:75], v[212:215], v[168:171], v[72:75]
	v_mfma_f32_16x16x32_bf16 v[68:71], v[204:207], v[194:197], v[68:71]
	s_barrier
	v_mfma_f32_16x16x32_bf16 v[64:67], v[212:215], v[194:197], v[64:67]
	s_setprio 0
	s_mov_b32 m0, s54
	v_lshl_add_u64 v[216:217], v[220:221], 0, s[14:15]
	ds_read_b128 v[148:151], v203 offset:49152
	ds_read_b128 v[152:155], v203 offset:50176
	ds_read_b128 v[156:159], v203 offset:51200
	ds_read_b128 v[160:163], v203 offset:52224
	ds_read_b128 v[164:167], v203 offset:53248
	ds_read_b128 v[168:171], v203 offset:54272
	ds_read_b128 v[172:175], v203 offset:55296
	ds_read_b128 v[194:197], v203 offset:56320
	global_load_lds_dwordx4 v[216:217], off
	v_lshl_add_u64 v[216:217], v[222:223], 0, s[14:15]
	s_mov_b32 m0, s55
	s_nop 0
	global_load_lds_dwordx4 v[216:217], off
	s_barrier
; #define PG8_STAGE(bufoff, gbase, voff) do { _Pragma("unroll") for (int _i = 0; _i < 2; ++_i) \
;         __builtin_amdgcn_global_load_lds((const unsigned*)((const char*)(gbase) + (voff)[_i]), (LAS unsigned*)(lds + (bufoff) + ldsw + _i * 8192), 16, 0, 0); } while (0)
; #define PG8_MMA(ai, bj, At, Bt) do { __builtin_amdgcn_s_setprio(1); _Pragma("unroll") for (int m = 0; m < 4; ++m) _Pragma("unroll") for (int n = 0; n < 2; ++n) _Pragma("unroll") for (int k = 0; k < 2; ++k) \
;         acc[ai][bj][m][n] = __builtin_amdgcn_mfma_f32_16x16x32_bf16(Bt[n][k], At[m][k], acc[ai][bj][m][n], 0, 0, 0); __builtin_amdgcn_s_setprio(0); } while (0)
; #define PG8_WAIT_V(n) asm volatile("s_waitcnt vmcnt(" #n ")" ::: "memory")
; #define PG8_WAIT_L(n) asm volatile("s_waitcnt lgkmcnt(" #n ")" ::: "memory")
; #define PG8_BAR __builtin_amdgcn_s_barrier()
; #define PG8_SCHED __builtin_amdgcn_sched_barrier(0)
; #define RES_LOAD(dst_, k_) do { _Pragma("unroll") for (int mm = 0; mm < 2; ++mm) _Pragma("unroll") for (int bj = 0; bj < 2; ++bj) _Pragma("unroll") for (int n = 0; n < 2; ++n) \
;             dst_[mm][bj][n] = *(const f32x4*)(xin + RES_OFF(k_, mm, bj, n)); } while (0)
; #define RES_STORE(src_, k_) do { _Pragma("unroll") for (int mm = 0; mm < 2; ++mm) _Pragma("unroll") for (int bj = 0; bj < 2; ++bj) _Pragma("unroll") for (int n = 0; n < 2; ++n) \
;             *(f32x4*)(xout + RES_OFF(k_, mm, bj, n)) = src_[mm][bj][n] + al * acc[(k_) >> 1][bj][((k_) & 1) * 2 + mm][n]; } while (0)
; template <class Epi>
; __device__ __forceinline__ void gemm_phase(LAS unsigned char* lds, const Gemm g, const Sched& S, const Epi& E) {
;     ...
;             PG8_BAR; PG8_WAIT_L(0); PG8_MMA(1, 0, At, B0); PG8_BAR; PG8_SCHED;
;             PG8_STAGE(PG8_SB(1, 1), b3 + hstepB, voffB);
;             PG8_WAIT_V(6); PG8_BAR; PG8_MMA(1, 1, At, B1); PG8_BAR;
;     __device__ __forceinline__ void operator()(AccRef acc, const Unit& u, int wr, int wc, int fr, int fq) const {
;         const float al = alpha;
;         const size_t base = ((size_t)u.pm * 256 + wr * 64 + fr) * D_ + u.pn * 256 + wc * 32 + 4 * fq;
;         f32x4 xa[2][2][2], xb[2][2][2];
;     ...
;         RES_LOAD(xa, 0); RES_LOAD(xb, 1);
;         RES_STORE(xa, 0); RES_LOAD(xa, 2);
;         RES_STORE(xb, 1); RES_LOAD(xb, 3);
;         RES_STORE(xa, 2); RES_STORE(xb, 3);
	s_waitcnt lgkmcnt(0)
	s_setprio 1
	s_waitcnt lgkmcnt(0)
	v_mfma_f32_16x16x32_bf16 v[60:63], v[132:135], v[148:151], v[60:63]
	v_mfma_f32_16x16x32_bf16 v[56:59], v[140:143], v[148:151], v[56:59]
	v_mfma_f32_16x16x32_bf16 v[52:55], v[132:135], v[156:159], v[52:55]
	v_mfma_f32_16x16x32_bf16 v[48:51], v[140:143], v[156:159], v[48:51]
	v_mfma_f32_16x16x32_bf16 v[44:47], v[132:135], v[164:167], v[44:47]
	v_mfma_f32_16x16x32_bf16 v[40:43], v[140:143], v[164:167], v[40:43]
	v_mfma_f32_16x16x32_bf16 v[36:39], v[132:135], v[172:175], v[36:39]
	v_mfma_f32_16x16x32_bf16 v[32:35], v[140:143], v[172:175], v[32:35]
	v_mfma_f32_16x16x32_bf16 v[60:63], v[136:139], v[152:155], v[60:63]
	v_mfma_f32_16x16x32_bf16 v[56:59], v[144:147], v[152:155], v[56:59]
	v_mfma_f32_16x16x32_bf16 v[52:55], v[136:139], v[160:163], v[52:55]
	v_mfma_f32_16x16x32_bf16 v[48:51], v[144:147], v[160:163], v[48:51]
	v_mfma_f32_16x16x32_bf16 v[44:47], v[136:139], v[168:171], v[44:47]
	v_mfma_f32_16x16x32_bf16 v[40:43], v[144:147], v[168:171], v[40:43]
	v_mfma_f32_16x16x32_bf16 v[36:39], v[136:139], v[194:197], v[36:39]
	s_barrier
	v_mfma_f32_16x16x32_bf16 v[32:35], v[144:147], v[194:197], v[32:35]
	s_setprio 0
	s_add_u32 s36, s36, 0x80080
	s_addc_u32 s37, s37, 0
	s_add_i32 s38, s38, s1
	v_lshl_add_u64 v[132:133], s[36:37], 0, v[176:177]
	s_mov_b32 m0, s38
	s_nop 0
	global_load_lds_dwordx4 v[132:133], off
	v_lshl_add_u64 v[132:133], s[36:37], 0, v[178:179]
	s_add_i32 m0, s38, 0x2000
	s_nop 0
	global_load_lds_dwordx4 v[132:133], off
	s_waitcnt vmcnt(6)
	s_barrier
	s_setprio 1
	v_mfma_f32_16x16x32_bf16 v[28:31], v[198:201], v[148:151], v[28:31]
	v_mfma_f32_16x16x32_bf16 v[24:27], v[208:211], v[148:151], v[24:27]
	v_mfma_f32_16x16x32_bf16 v[20:23], v[198:201], v[156:159], v[20:23]
	v_mfma_f32_16x16x32_bf16 v[16:19], v[208:211], v[156:159], v[16:19]
	v_mfma_f32_16x16x32_bf16 v[12:15], v[198:201], v[164:167], v[12:15]
	v_mfma_f32_16x16x32_bf16 v[8:11], v[208:211], v[164:167], v[8:11]
	v_mfma_f32_16x16x32_bf16 v[4:7], v[198:201], v[172:175], v[4:7]
	v_mfma_f32_16x16x32_bf16 v[0:3], v[208:211], v[172:175], v[0:3]
	v_mfma_f32_16x16x32_bf16 v[28:31], v[204:207], v[152:155], v[28:31]
	v_mfma_f32_16x16x32_bf16 v[24:27], v[212:215], v[152:155], v[24:27]
	v_mfma_f32_16x16x32_bf16 v[20:23], v[204:207], v[160:163], v[20:23]
	v_mfma_f32_16x16x32_bf16 v[16:19], v[212:215], v[160:163], v[16:19]
	v_mfma_f32_16x16x32_bf16 v[12:15], v[204:207], v[168:171], v[12:15]
	v_mfma_f32_16x16x32_bf16 v[8:11], v[212:215], v[168:171], v[8:11]
	v_mfma_f32_16x16x32_bf16 v[4:7], v[204:207], v[194:197], v[4:7]
	s_barrier
	v_mfma_f32_16x16x32_bf16 v[0:3], v[212:215], v[194:197], v[0:3]
	s_setprio 0
	s_add_i32 s67, s67, 2
	s_add_u32 s24, s24, 0x100
	s_addc_u32 s25, s25, 0
	s_cmp_gt_u32 s67, 29
	s_cbranch_scc0 .LBB0_1967
	s_add_u32 s24, s11, 0xffffff00
	s_addc_u32 s25, s51, -1
	s_ashr_i32 s11, s10, 31
	s_lshl_b32 s36, s53, 8
	s_lshl_b64 s[38:39], s[10:11], 21
	s_ashr_i32 s37, s36, 31
	v_lshl_add_u64 v[128:129], v[182:183], 0, s[38:39]
	v_lshl_add_u64 v[128:129], s[36:37], 2, v[128:129]
	v_lshl_add_u64 v[194:195], v[128:129], 0, v[180:181]
	global_load_dwordx4 v[128:131], v[194:195], off
	global_load_dwordx4 v[132:135], v[194:195], off offset:64
	global_load_dwordx4 v[136:139], v[194:195], off offset:512
	global_load_dwordx4 v[140:143], v[194:195], off offset:576
	v_add_co_u32_e32 v196, vcc, s58, v194
	s_waitcnt vmcnt(0)
	v_pk_add_f32 v[130:131], v[126:127], v[130:131]
	v_addc_co_u32_e32 v197, vcc, 0, v195, vcc
	global_load_dwordx4 v[144:147], v[196:197], off
	global_load_dwordx4 v[148:151], v[196:197], off offset:64
	global_load_dwordx4 v[152:155], v[196:197], off offset:512
	global_load_dwordx4 v[156:159], v[196:197], off offset:576
	v_add_co_u32_e32 v200, vcc, s59, v194
	v_pk_add_f32 v[128:129], v[124:125], v[128:129]
	s_nop 0
	v_addc_co_u32_e32 v201, vcc, 0, v195, vcc
	global_load_dwordx4 v[160:163], v[200:201], off
	global_load_dwordx4 v[164:167], v[200:201], off offset:64
	global_load_dwordx4 v[168:171], v[200:201], off offset:512
	global_load_dwordx4 v[172:175], v[200:201], off offset:576
	v_add_co_u32_e32 v220, vcc, s60, v194
	s_waitcnt vmcnt(0)
	v_pk_add_f32 v[162:163], v[110:111], v[162:163]
	v_addc_co_u32_e32 v221, vcc, 0, v195, vcc
	global_load_dwordx4 v[204:207], v[220:221], off
	global_load_dwordx4 v[208:211], v[220:221], off offset:64
	global_load_dwordx4 v[212:215], v[220:221], off offset:512
	global_load_dwordx4 v[216:219], v[220:221], off offset:576
	v_add_co_u32_e32 v198, vcc, s61, v194
	global_store_dwordx4 v[194:195], v[128:131], off
	s_nop 0
	v_addc_co_u32_e32 v199, vcc, 0, v195, vcc
	v_pk_add_f32 v[130:131], v[122:123], v[134:135]
	v_pk_add_f32 v[128:129], v[120:121], v[132:133]
	global_store_dwordx4 v[194:195], v[128:131], off offset:64
	v_pk_add_f32 v[160:161], v[108:109], v[160:161]
	s_nop 0
	v_pk_add_f32 v[130:131], v[94:95], v[138:139]
	v_pk_add_f32 v[128:129], v[92:93], v[136:137]
	global_store_dwordx4 v[194:195], v[128:131], off offset:512
	s_nop 1
	v_pk_add_f32 v[130:131], v[90:91], v[142:143]
	v_pk_add_f32 v[128:129], v[88:89], v[140:141]
	global_store_dwordx4 v[194:195], v[128:131], off offset:576
	s_nop 1
	v_pk_add_f32 v[130:131], v[118:119], v[146:147]
	v_pk_add_f32 v[128:129], v[116:117], v[144:145]
	global_store_dwordx4 v[196:197], v[128:131], off
	s_nop 1
	v_pk_add_f32 v[130:131], v[114:115], v[150:151]
	v_pk_add_f32 v[128:129], v[112:113], v[148:149]
	global_store_dwordx4 v[196:197], v[128:131], off offset:64
	s_nop 1
	v_pk_add_f32 v[130:131], v[86:87], v[154:155]
	v_pk_add_f32 v[128:129], v[84:85], v[152:153]
	global_store_dwordx4 v[196:197], v[128:131], off offset:512
	s_nop 1
	v_pk_add_f32 v[130:131], v[82:83], v[158:159]
	v_pk_add_f32 v[128:129], v[80:81], v[156:157]
	global_store_dwordx4 v[196:197], v[128:131], off offset:576
	v_add_co_u32_e32 v196, vcc, s62, v194
	global_load_dwordx4 v[156:159], v[198:199], off
	global_load_dwordx4 v[152:155], v[198:199], off offset:64
	global_load_dwordx4 v[144:147], v[198:199], off offset:512
	global_load_dwordx4 v[136:139], v[198:199], off offset:576
	v_addc_co_u32_e32 v197, vcc, 0, v195, vcc
	global_load_dwordx4 v[148:151], v[196:197], off
	global_load_dwordx4 v[140:143], v[196:197], off offset:64
	global_load_dwordx4 v[132:135], v[196:197], off offset:512
	global_load_dwordx4 v[128:131], v[196:197], off offset:576
	s_waitcnt vmcnt(0)
; #define RES_LOAD(dst_, k_) do { _Pragma("unroll") for (int mm = 0; mm < 2; ++mm) _Pragma("unroll") for (int bj = 0; bj < 2; ++bj) _Pragma("unroll") for (int n = 0; n < 2; ++n) \
;             dst_[mm][bj][n] = *(const f32x4*)(xin + RES_OFF(k_, mm, bj, n)); } while (0)
; #define RES_STORE(src_, k_) do { _Pragma("unroll") for (int mm = 0; mm < 2; ++mm) _Pragma("unroll") for (int bj = 0; bj < 2; ++bj) _Pragma("unroll") for (int n = 0; n < 2; ++n) \
;             *(f32x4*)(xout + RES_OFF(k_, mm, bj, n)) = src_[mm][bj][n] + al * acc[(k_) >> 1][bj][((k_) & 1) * 2 + mm][n]; } while (0)
;     __device__ __forceinline__ void operator()(AccRef acc, const Unit& u, int wr, int wc, int fr, int fq) const {
;     ...
;         RES_LOAD(xa, 0); RES_LOAD(xb, 1);
;         RES_STORE(xa, 0); RES_LOAD(xa, 2);
;         RES_STORE(xb, 1); RES_LOAD(xb, 3);
;         RES_STORE(xa, 2); RES_STORE(xb, 3);
	v_pk_add_f32 v[158:159], v[62:63], v[158:159]
	global_store_dwordx4 v[200:201], v[160:163], off
	v_pk_add_f32 v[156:157], v[60:61], v[156:157]
	v_pk_add_f32 v[138:139], v[26:27], v[138:139]
	v_pk_add_f32 v[162:163], v[106:107], v[166:167]
	v_pk_add_f32 v[160:161], v[104:105], v[164:165]
	global_store_dwordx4 v[200:201], v[160:163], off offset:64
	v_pk_add_f32 v[130:131], v[18:19], v[130:131]
	v_pk_add_f32 v[128:129], v[16:17], v[128:129]
	v_pk_add_f32 v[162:163], v[78:79], v[170:171]
	v_pk_add_f32 v[160:161], v[76:77], v[168:169]
	global_store_dwordx4 v[200:201], v[160:163], off offset:512
	v_pk_add_f32 v[136:137], v[24:25], v[136:137]
	v_pk_add_f32 v[154:155], v[58:59], v[154:155]
	v_pk_add_f32 v[162:163], v[74:75], v[174:175]
	v_pk_add_f32 v[160:161], v[72:73], v[172:173]
	global_store_dwordx4 v[200:201], v[160:163], off offset:576
	v_add_co_u32_e32 v200, vcc, s63, v194
	s_nop 0
	v_pk_add_f32 v[162:163], v[102:103], v[206:207]
	v_pk_add_f32 v[160:161], v[100:101], v[204:205]
	global_store_dwordx4 v[220:221], v[160:163], off
	v_addc_co_u32_e32 v201, vcc, 0, v195, vcc
	s_nop 0
	v_pk_add_f32 v[162:163], v[98:99], v[210:211]
	v_pk_add_f32 v[160:161], v[96:97], v[208:209]
	global_store_dwordx4 v[220:221], v[160:163], off offset:64
	v_add_co_u32_e32 v194, vcc, s64, v194
	s_nop 0
	v_pk_add_f32 v[162:163], v[70:71], v[214:215]
	v_pk_add_f32 v[160:161], v[68:69], v[212:213]
	global_store_dwordx4 v[220:221], v[160:163], off offset:512
	v_addc_co_u32_e32 v195, vcc, 0, v195, vcc
	s_nop 0
	v_pk_add_f32 v[162:163], v[66:67], v[218:219]
	v_pk_add_f32 v[160:161], v[64:65], v[216:217]
	global_store_dwordx4 v[220:221], v[160:163], off offset:576
	global_load_dwordx4 v[172:175], v[200:201], off
	global_load_dwordx4 v[168:171], v[200:201], off offset:64
	global_load_dwordx4 v[164:167], v[200:201], off offset:512
	s_nop 0
	global_load_dwordx4 v[160:163], v[200:201], off offset:576
	global_load_dwordx4 v[204:207], v[194:195], off
	global_load_dwordx4 v[208:211], v[194:195], off offset:64
	global_load_dwordx4 v[212:215], v[194:195], off offset:512
	global_load_dwordx4 v[216:219], v[194:195], off offset:576
	v_pk_add_f32 v[152:153], v[56:57], v[152:153]
	global_store_dwordx4 v[196:197], v[128:131], off offset:576
	global_store_dwordx4 v[198:199], v[136:139], off offset:576
	v_pk_add_f32 v[146:147], v[30:31], v[146:147]
	v_pk_add_f32 v[144:145], v[28:29], v[144:145]
	v_pk_add_f32 v[138:139], v[54:55], v[150:151]
	v_pk_add_f32 v[136:137], v[52:53], v[148:149]
	global_store_dwordx4 v[196:197], v[136:139], off
	v_pk_add_f32 v[134:135], v[22:23], v[134:135]
	v_pk_add_f32 v[132:133], v[20:21], v[132:133]
	v_pk_add_f32 v[138:139], v[50:51], v[142:143]
	v_pk_add_f32 v[136:137], v[48:49], v[140:141]
	s_andn2_b64 vcc, exec, s[8:9]
	global_store_dwordx4 v[198:199], v[156:159], off
	global_store_dwordx4 v[198:199], v[152:155], off offset:64
	global_store_dwordx4 v[198:199], v[144:147], off offset:512
	global_store_dwordx4 v[196:197], v[136:139], off offset:64
	global_store_dwordx4 v[196:197], v[132:135], off offset:512
	s_waitcnt vmcnt(0)
	v_pk_add_f32 v[130:131], v[46:47], v[174:175]
	v_pk_add_f32 v[128:129], v[44:45], v[172:173]
	global_store_dwordx4 v[200:201], v[128:131], off
	s_nop 1
	v_pk_add_f32 v[130:131], v[42:43], v[170:171]
	v_pk_add_f32 v[128:129], v[40:41], v[168:169]
	global_store_dwordx4 v[200:201], v[128:131], off offset:64
	s_nop 1
	v_pk_add_f32 v[130:131], v[14:15], v[166:167]
	v_pk_add_f32 v[128:129], v[12:13], v[164:165]
	global_store_dwordx4 v[200:201], v[128:131], off offset:512
	s_nop 1
	v_pk_add_f32 v[130:131], v[10:11], v[162:163]
	v_pk_add_f32 v[128:129], v[8:9], v[160:161]
	global_store_dwordx4 v[200:201], v[128:131], off offset:576
	s_nop 1
	v_pk_add_f32 v[130:131], v[38:39], v[206:207]
	v_pk_add_f32 v[128:129], v[36:37], v[204:205]
	global_store_dwordx4 v[194:195], v[128:131], off
	s_nop 1
	v_pk_add_f32 v[130:131], v[34:35], v[210:211]
	v_pk_add_f32 v[128:129], v[32:33], v[208:209]
	global_store_dwordx4 v[194:195], v[128:131], off offset:64
	s_nop 1
	v_pk_add_f32 v[130:131], v[6:7], v[214:215]
	v_pk_add_f32 v[128:129], v[4:5], v[212:213]
	global_store_dwordx4 v[194:195], v[128:131], off offset:512
	s_nop 1
	v_pk_add_f32 v[130:131], v[2:3], v[218:219]
	v_pk_add_f32 v[128:129], v[0:1], v[216:217]
	global_store_dwordx4 v[194:195], v[128:131], off offset:576
	s_cbranch_vccz .LBB0_1959
	s_mov_b64 s[20:21], s[24:25]
	s_andn2_b64 vcc, exec, s[6:7]
	s_mov_b64 s[24:25], s[20:21]
	s_cbranch_vccnz .LBB0_1960

; #define PG8_STAGE(bufoff, gbase, voff) do { _Pragma("unroll") for (int _i = 0; _i < 2; ++_i) \
;         __builtin_amdgcn_global_load_lds((const unsigned*)((const char*)(gbase) + (voff)[_i]), (LAS unsigned*)(lds + (bufoff) + ldsw + _i * 8192), 16, 0, 0); } while (0)
; #define PG8_LDA(dst, b, h) do { _Pragma("unroll") for (int m = 0; m < 4; ++m) _Pragma("unroll") for (int k = 0; k < 2; ++k) dst[m][k] = *(const LAS bf16x8*)(lds + PG8_SA(b, h) + aoff + m * 2048 + k * 1024); } while (0)
; #define PG8_LDB(dst, b, h) do { _Pragma("unroll") for (int n = 0; n < 2; ++n) _Pragma("unroll") for (int k = 0; k < 2; ++k) dst[n][k] = *(const LAS bf16x8*)(lds + PG8_SB(b, h) + boff + n * 2048 + k * 1024); } while (0)
; #define PG8_MMA(ai, bj, At, Bt) do { __builtin_amdgcn_s_setprio(1); _Pragma("unroll") for (int m = 0; m < 4; ++m) _Pragma("unroll") for (int n = 0; n < 2; ++n) _Pragma("unroll") for (int k = 0; k < 2; ++k) \
;         acc[ai][bj][m][n] = __builtin_amdgcn_mfma_f32_16x16x32_bf16(Bt[n][k], At[m][k], acc[ai][bj][m][n], 0, 0, 0); __builtin_amdgcn_s_setprio(0); } while (0)
; #define PG8_WAIT_V(n) asm volatile("s_waitcnt vmcnt(" #n ")" ::: "memory")
; #define PG8_WAIT_L(n) asm volatile("s_waitcnt lgkmcnt(" #n ")" ::: "memory")
; #define PG8_BAR __builtin_amdgcn_s_barrier()
; #define PG8_SCHED __builtin_amdgcn_sched_barrier(0)
; template <class Epi>
; __device__ __forceinline__ void gemm_phase(LAS unsigned char* lds, const Gemm g, const Sched& S, const Epi& E) {
;     ...
;             PG8_LDB(B0, 0, 0); PG8_SCHED; PG8_LDA(At, 0, 0); PG8_STAGE(PG8_SA(1, 1), a1 + hstepA, voffA);
;             PG8_WAIT_L(8); PG8_BAR; PG8_WAIT_L(0); PG8_MMA(0, 0, At, B0); PG8_BAR; PG8_SCHED;
;             PG8_LDB(B1, 0, 1); PG8_STAGE(PG8_SB(0, 0), b2, voffB);
;             PG8_BAR; PG8_WAIT_L(0); PG8_MMA(0, 1, At, B1); PG8_BAR;
;             PG8_LDA(At, 0, 1); PG8_STAGE(PG8_SA(0, 0), a2, voffA);
;             PG8_BAR; PG8_WAIT_L(0); PG8_MMA(1, 0, At, B0); PG8_BAR; PG8_SCHED;
;             PG8_STAGE(PG8_SB(0, 1), b2 + hstepB, voffB);
;             PG8_WAIT_V(6); PG8_BAR; PG8_MMA(1, 1, At, B1); PG8_BAR;
.LBB0_2088:
	v_add_u32_e32 v162, s62, v148
	s_add_u32 s38, s14, s36
	ds_read_b128 v[150:153], v162
	ds_read_b128 v[154:157], v162 offset:1024
	ds_read_b128 v[158:161], v162 offset:2048
	ds_read_b128 v[162:165], v162 offset:3072
	s_addc_u32 s39, s15, s37
	s_add_u32 s38, s38, 0x100
	s_addc_u32 s39, s39, 0
	s_add_u32 s82, s13, s36
	s_addc_u32 s83, s51, s37
	s_cmpk_eq_i32 s36, 0xf00
	s_cselect_b32 s55, s21, s39
	s_cselect_b32 s54, s79, s38
	s_cselect_b32 s39, s19, s83
	s_cselect_b32 s38, s80, s82
	v_lshl_add_u64 v[190:191], v[144:145], 0, s[36:37]
	s_add_i32 m0, s43, 0xc000
	ds_read_b128 v[166:169], v149
	ds_read_b128 v[170:173], v149 offset:1024
	ds_read_b128 v[174:177], v149 offset:2048
	ds_read_b128 v[178:181], v149 offset:3072
	ds_read_b128 v[182:185], v149 offset:4096
	ds_read_b128 v[186:189], v149 offset:5120
	ds_read_b128 v[194:197], v149 offset:6144
	ds_read_b128 v[198:201], v149 offset:7168
	global_load_lds_dwordx4 v[190:191], off
	v_lshl_add_u64 v[190:191], v[146:147], 0, s[36:37]
	s_add_i32 m0, s43, 0xe000
	s_nop 0
	global_load_lds_dwordx4 v[190:191], off
	s_waitcnt lgkmcnt(8)
	s_barrier
	s_waitcnt lgkmcnt(0)
	s_setprio 1
	s_waitcnt lgkmcnt(0)
	v_mfma_f32_16x16x32_bf16 v[124:127], v[150:153], v[166:169], v[124:127]
	v_mfma_f32_16x16x32_bf16 v[120:123], v[158:161], v[166:169], v[120:123]
	v_mfma_f32_16x16x32_bf16 v[116:119], v[150:153], v[174:177], v[116:119]
	v_mfma_f32_16x16x32_bf16 v[112:115], v[158:161], v[174:177], v[112:115]
	v_mfma_f32_16x16x32_bf16 v[108:111], v[150:153], v[182:185], v[108:111]
	v_mfma_f32_16x16x32_bf16 v[104:107], v[158:161], v[182:185], v[104:107]
	v_mfma_f32_16x16x32_bf16 v[100:103], v[150:153], v[194:197], v[100:103]
	v_mfma_f32_16x16x32_bf16 v[96:99], v[158:161], v[194:197], v[96:99]
	v_mfma_f32_16x16x32_bf16 v[124:127], v[154:157], v[170:173], v[124:127]
	v_mfma_f32_16x16x32_bf16 v[120:123], v[162:165], v[170:173], v[120:123]
	v_mfma_f32_16x16x32_bf16 v[116:119], v[154:157], v[178:181], v[116:119]
	v_mfma_f32_16x16x32_bf16 v[112:115], v[162:165], v[178:181], v[112:115]
	v_mfma_f32_16x16x32_bf16 v[108:111], v[154:157], v[186:189], v[108:111]
	v_mfma_f32_16x16x32_bf16 v[104:107], v[162:165], v[186:189], v[104:107]
	v_mfma_f32_16x16x32_bf16 v[100:103], v[154:157], v[198:201], v[100:103]
	s_barrier
	v_mfma_f32_16x16x32_bf16 v[96:99], v[162:165], v[198:201], v[96:99]
	s_setprio 0
	v_add_u32_e32 v190, s63, v148
	s_add_i32 s82, s62, s34
	ds_read_b128 v[202:205], v190
	ds_read_b128 v[206:209], v190 offset:1024
	ds_read_b128 v[210:213], v190 offset:2048
	ds_read_b128 v[214:217], v190 offset:3072
	v_lshl_add_u64 v[190:191], s[38:39], 0, v[130:131]
	s_mov_b32 m0, s82
	v_lshl_add_u64 v[218:219], s[38:39], 0, v[128:129]
	global_load_lds_dwordx4 v[190:191], off
	s_add_i32 m0, s82, 0x2000
	s_nop 0
	global_load_lds_dwordx4 v[218:219], off
	s_barrier
	s_waitcnt lgkmcnt(0)
	s_setprio 1
	s_waitcnt lgkmcnt(0)
	v_mfma_f32_16x16x32_bf16 v[92:95], v[202:205], v[166:169], v[92:95]
	v_mfma_f32_16x16x32_bf16 v[88:91], v[210:213], v[166:169], v[88:91]
	v_mfma_f32_16x16x32_bf16 v[84:87], v[202:205], v[174:177], v[84:87]
	v_mfma_f32_16x16x32_bf16 v[80:83], v[210:213], v[174:177], v[80:83]
	v_mfma_f32_16x16x32_bf16 v[76:79], v[202:205], v[182:185], v[76:79]
	v_mfma_f32_16x16x32_bf16 v[72:75], v[210:213], v[182:185], v[72:75]
	v_mfma_f32_16x16x32_bf16 v[68:71], v[202:205], v[194:197], v[68:71]
	v_mfma_f32_16x16x32_bf16 v[64:67], v[210:213], v[194:197], v[64:67]
	v_mfma_f32_16x16x32_bf16 v[92:95], v[206:209], v[170:173], v[92:95]
	v_mfma_f32_16x16x32_bf16 v[88:91], v[214:217], v[170:173], v[88:91]
	v_mfma_f32_16x16x32_bf16 v[84:87], v[206:209], v[178:181], v[84:87]
	v_mfma_f32_16x16x32_bf16 v[80:83], v[214:217], v[178:181], v[80:83]
	v_mfma_f32_16x16x32_bf16 v[76:79], v[206:209], v[186:189], v[76:79]
	v_mfma_f32_16x16x32_bf16 v[72:75], v[214:217], v[186:189], v[72:75]
	v_mfma_f32_16x16x32_bf16 v[68:71], v[206:209], v[198:201], v[68:71]
	s_barrier
	v_mfma_f32_16x16x32_bf16 v[64:67], v[214:217], v[198:201], v[64:67]
	s_setprio 0
	s_mov_b32 m0, s43
	v_lshl_add_u64 v[220:221], s[54:55], 0, v[130:131]
	ds_read_b128 v[166:169], v149 offset:16384
	ds_read_b128 v[170:173], v149 offset:17408
	ds_read_b128 v[174:177], v149 offset:18432
	ds_read_b128 v[178:181], v149 offset:19456
	ds_read_b128 v[182:185], v149 offset:20480
	ds_read_b128 v[186:189], v149 offset:21504
	ds_read_b128 v[194:197], v149 offset:22528
	ds_read_b128 v[198:201], v149 offset:23552
	global_load_lds_dwordx4 v[220:221], off
	v_lshl_add_u64 v[222:223], s[54:55], 0, v[128:129]
	s_mov_b32 m0, s52
	s_nop 0
	global_load_lds_dwordx4 v[222:223], off
	s_barrier
	s_waitcnt lgkmcnt(0)
	s_setprio 1
	s_waitcnt lgkmcnt(0)
	v_mfma_f32_16x16x32_bf16 v[60:63], v[150:153], v[166:169], v[60:63]
	v_mfma_f32_16x16x32_bf16 v[56:59], v[158:161], v[166:169], v[56:59]
	v_mfma_f32_16x16x32_bf16 v[52:55], v[150:153], v[174:177], v[52:55]
	v_mfma_f32_16x16x32_bf16 v[48:51], v[158:161], v[174:177], v[48:51]
	v_mfma_f32_16x16x32_bf16 v[44:47], v[150:153], v[182:185], v[44:47]
	v_mfma_f32_16x16x32_bf16 v[40:43], v[158:161], v[182:185], v[40:43]
	v_mfma_f32_16x16x32_bf16 v[36:39], v[150:153], v[194:197], v[36:39]
	v_mfma_f32_16x16x32_bf16 v[32:35], v[158:161], v[194:197], v[32:35]
	v_mfma_f32_16x16x32_bf16 v[60:63], v[154:157], v[170:173], v[60:63]
	v_mfma_f32_16x16x32_bf16 v[56:59], v[162:165], v[170:173], v[56:59]
	v_mfma_f32_16x16x32_bf16 v[52:55], v[154:157], v[178:181], v[52:55]
	v_mfma_f32_16x16x32_bf16 v[48:51], v[162:165], v[178:181], v[48:51]
	v_mfma_f32_16x16x32_bf16 v[44:47], v[154:157], v[186:189], v[44:47]
	v_mfma_f32_16x16x32_bf16 v[40:43], v[162:165], v[186:189], v[40:43]
	v_mfma_f32_16x16x32_bf16 v[36:39], v[154:157], v[198:201], v[36:39]
	s_barrier
; #define PG8_STAGE(bufoff, gbase, voff) do { _Pragma("unroll") for (int _i = 0; _i < 2; ++_i) \
;         __builtin_amdgcn_global_load_lds((const unsigned*)((const char*)(gbase) + (voff)[_i]), (LAS unsigned*)(lds + (bufoff) + ldsw + _i * 8192), 16, 0, 0); } while (0)
; #define PG8_LDA(dst, b, h) do { _Pragma("unroll") for (int m = 0; m < 4; ++m) _Pragma("unroll") for (int k = 0; k < 2; ++k) dst[m][k] = *(const LAS bf16x8*)(lds + PG8_SA(b, h) + aoff + m * 2048 + k * 1024); } while (0)
; #define PG8_LDB(dst, b, h) do { _Pragma("unroll") for (int n = 0; n < 2; ++n) _Pragma("unroll") for (int k = 0; k < 2; ++k) dst[n][k] = *(const LAS bf16x8*)(lds + PG8_SB(b, h) + boff + n * 2048 + k * 1024); } while (0)
; #define PG8_MMA(ai, bj, At, Bt) do { __builtin_amdgcn_s_setprio(1); _Pragma("unroll") for (int m = 0; m < 4; ++m) _Pragma("unroll") for (int n = 0; n < 2; ++n) _Pragma("unroll") for (int k = 0; k < 2; ++k) \
;         acc[ai][bj][m][n] = __builtin_amdgcn_mfma_f32_16x16x32_bf16(Bt[n][k], At[m][k], acc[ai][bj][m][n], 0, 0, 0); __builtin_amdgcn_s_setprio(0); } while (0)
; #define PG8_WAIT_V(n) asm volatile("s_waitcnt vmcnt(" #n ")" ::: "memory")
; #define PG8_WAIT_L(n) asm volatile("s_waitcnt lgkmcnt(" #n ")" ::: "memory")
; #define PG8_BAR __builtin_amdgcn_s_barrier()
; #define PG8_SCHED __builtin_amdgcn_sched_barrier(0)
; template <class Epi>
; __device__ __forceinline__ void gemm_phase(LAS unsigned char* lds, const Gemm g, const Sched& S, const Epi& E) {
;     ...
;             PG8_BAR; PG8_WAIT_L(0); PG8_MMA(1, 0, At, B0); PG8_BAR; PG8_SCHED;
;             PG8_STAGE(PG8_SB(0, 1), b2 + hstepB, voffB);
;             PG8_WAIT_V(6); PG8_BAR; PG8_MMA(1, 1, At, B1); PG8_BAR;
;             PG8_LDB(B0, 1, 0); PG8_SCHED; PG8_LDA(At, 1, 0); PG8_STAGE(PG8_SA(0, 1), a2 + hstepA, voffA);
;             PG8_WAIT_L(8); PG8_BAR; PG8_WAIT_L(0); PG8_MMA(0, 0, At, B0); PG8_BAR; PG8_SCHED;
;             PG8_LDB(B1, 1, 1); PG8_STAGE(PG8_SB(1, 0), b3, voffB);
;             PG8_BAR; PG8_WAIT_L(0); PG8_MMA(0, 1, At, B1); PG8_BAR;
;             PG8_LDA(At, 1, 1); PG8_STAGE(PG8_SA(1, 0), a3, voffA);
;             PG8_BAR; PG8_WAIT_L(0); PG8_MMA(1, 0, At, B0); PG8_BAR; PG8_SCHED;
	v_mfma_f32_16x16x32_bf16 v[32:35], v[162:165], v[198:201], v[32:35]
	s_setprio 0
	s_add_u32 s82, s38, 0x80000
	s_addc_u32 s83, s39, 0
	s_add_i32 s84, s63, s34
	v_lshl_add_u64 v[150:151], s[82:83], 0, v[130:131]
	s_mov_b32 m0, s84
	s_nop 0
	global_load_lds_dwordx4 v[150:151], off
	v_lshl_add_u64 v[150:151], s[82:83], 0, v[128:129]
	s_add_i32 m0, s84, 0x2000
	s_nop 0
	global_load_lds_dwordx4 v[150:151], off
	s_waitcnt vmcnt(6)
	s_barrier
	s_setprio 1
	v_mfma_f32_16x16x32_bf16 v[28:31], v[202:205], v[166:169], v[28:31]
	v_mfma_f32_16x16x32_bf16 v[24:27], v[210:213], v[166:169], v[24:27]
	v_mfma_f32_16x16x32_bf16 v[20:23], v[202:205], v[174:177], v[20:23]
	v_mfma_f32_16x16x32_bf16 v[16:19], v[210:213], v[174:177], v[16:19]
	v_mfma_f32_16x16x32_bf16 v[12:15], v[202:205], v[182:185], v[12:15]
	v_mfma_f32_16x16x32_bf16 v[8:11], v[210:213], v[182:185], v[8:11]
	v_mfma_f32_16x16x32_bf16 v[4:7], v[202:205], v[194:197], v[4:7]
	v_mfma_f32_16x16x32_bf16 v[0:3], v[210:213], v[194:197], v[0:3]
	v_mfma_f32_16x16x32_bf16 v[28:31], v[206:209], v[170:173], v[28:31]
	v_mfma_f32_16x16x32_bf16 v[24:27], v[214:217], v[170:173], v[24:27]
	v_mfma_f32_16x16x32_bf16 v[20:23], v[206:209], v[178:181], v[20:23]
	v_mfma_f32_16x16x32_bf16 v[16:19], v[214:217], v[178:181], v[16:19]
	v_mfma_f32_16x16x32_bf16 v[12:15], v[206:209], v[186:189], v[12:15]
	v_mfma_f32_16x16x32_bf16 v[8:11], v[214:217], v[186:189], v[8:11]
	v_mfma_f32_16x16x32_bf16 v[4:7], v[206:209], v[198:201], v[4:7]
	s_barrier
	v_mfma_f32_16x16x32_bf16 v[0:3], v[214:217], v[198:201], v[0:3]
	s_setprio 0
	s_add_i32 s82, 0, 0x18000
	v_add_u32_e32 v162, s82, v148
	ds_read_b128 v[150:153], v162
	ds_read_b128 v[154:157], v162 offset:1024
	ds_read_b128 v[158:161], v162 offset:2048
	ds_read_b128 v[162:165], v162 offset:3072
	s_add_u32 s54, s54, 0x80000
	s_addc_u32 s55, s55, 0
	s_mov_b32 m0, s53
	v_lshl_add_u64 v[202:203], s[54:55], 0, v[130:131]
	ds_read_b128 v[166:169], v149 offset:32768
	ds_read_b128 v[170:173], v149 offset:33792
	ds_read_b128 v[174:177], v149 offset:34816
	ds_read_b128 v[178:181], v149 offset:35840
	ds_read_b128 v[182:185], v149 offset:36864
	ds_read_b128 v[186:189], v149 offset:37888
	ds_read_b128 v[194:197], v149 offset:38912
	ds_read_b128 v[198:201], v149 offset:39936
	global_load_lds_dwordx4 v[202:203], off
	v_lshl_add_u64 v[202:203], s[54:55], 0, v[128:129]
	s_mov_b32 m0, s56
	s_nop 0
	global_load_lds_dwordx4 v[202:203], off
	s_waitcnt lgkmcnt(8)
	s_barrier
	s_waitcnt lgkmcnt(0)
	s_setprio 1
	s_waitcnt lgkmcnt(0)
	v_mfma_f32_16x16x32_bf16 v[124:127], v[150:153], v[166:169], v[124:127]
	v_mfma_f32_16x16x32_bf16 v[120:123], v[158:161], v[166:169], v[120:123]
	v_mfma_f32_16x16x32_bf16 v[116:119], v[150:153], v[174:177], v[116:119]
	v_mfma_f32_16x16x32_bf16 v[112:115], v[158:161], v[174:177], v[112:115]
	v_mfma_f32_16x16x32_bf16 v[108:111], v[150:153], v[182:185], v[108:111]
	v_mfma_f32_16x16x32_bf16 v[104:107], v[158:161], v[182:185], v[104:107]
	v_mfma_f32_16x16x32_bf16 v[100:103], v[150:153], v[194:197], v[100:103]
	v_mfma_f32_16x16x32_bf16 v[96:99], v[158:161], v[194:197], v[96:99]
	v_mfma_f32_16x16x32_bf16 v[124:127], v[154:157], v[170:173], v[124:127]
	v_mfma_f32_16x16x32_bf16 v[120:123], v[162:165], v[170:173], v[120:123]
	v_mfma_f32_16x16x32_bf16 v[116:119], v[154:157], v[178:181], v[116:119]
	v_mfma_f32_16x16x32_bf16 v[112:115], v[162:165], v[178:181], v[112:115]
	v_mfma_f32_16x16x32_bf16 v[108:111], v[154:157], v[186:189], v[108:111]
	v_mfma_f32_16x16x32_bf16 v[104:107], v[162:165], v[186:189], v[104:107]
	v_mfma_f32_16x16x32_bf16 v[100:103], v[154:157], v[198:201], v[100:103]
	s_barrier
	v_mfma_f32_16x16x32_bf16 v[96:99], v[162:165], v[198:201], v[96:99]
	s_setprio 0
	s_add_i32 s54, 0, 0x1c000
	s_add_i32 s55, s82, s34
	v_add_u32_e32 v214, s54, v148
	v_lshl_add_u64 v[190:191], v[190:191], 0, s[16:17]
	s_mov_b32 m0, s55
	ds_read_b128 v[202:205], v214
	ds_read_b128 v[206:209], v214 offset:1024
	ds_read_b128 v[210:213], v214 offset:2048
	ds_read_b128 v[214:217], v214 offset:3072
	global_load_lds_dwordx4 v[190:191], off
	v_lshl_add_u64 v[190:191], v[218:219], 0, s[16:17]
	s_add_i32 m0, s55, 0x2000
	s_nop 0
	global_load_lds_dwordx4 v[190:191], off
	s_barrier
	s_waitcnt lgkmcnt(0)
	s_setprio 1
	s_waitcnt lgkmcnt(0)
	v_mfma_f32_16x16x32_bf16 v[92:95], v[202:205], v[166:169], v[92:95]
	v_mfma_f32_16x16x32_bf16 v[88:91], v[210:213], v[166:169], v[88:91]
	v_mfma_f32_16x16x32_bf16 v[84:87], v[202:205], v[174:177], v[84:87]
	v_mfma_f32_16x16x32_bf16 v[80:83], v[210:213], v[174:177], v[80:83]
	v_mfma_f32_16x16x32_bf16 v[76:79], v[202:205], v[182:185], v[76:79]
	v_mfma_f32_16x16x32_bf16 v[72:75], v[210:213], v[182:185], v[72:75]
	v_mfma_f32_16x16x32_bf16 v[68:71], v[202:205], v[194:197], v[68:71]
	v_mfma_f32_16x16x32_bf16 v[64:67], v[210:213], v[194:197], v[64:67]
	v_mfma_f32_16x16x32_bf16 v[92:95], v[206:209], v[170:173], v[92:95]
	v_mfma_f32_16x16x32_bf16 v[88:91], v[214:217], v[170:173], v[88:91]
	v_mfma_f32_16x16x32_bf16 v[84:87], v[206:209], v[178:181], v[84:87]
	v_mfma_f32_16x16x32_bf16 v[80:83], v[214:217], v[178:181], v[80:83]
	v_mfma_f32_16x16x32_bf16 v[76:79], v[206:209], v[186:189], v[76:79]
	v_mfma_f32_16x16x32_bf16 v[72:75], v[214:217], v[186:189], v[72:75]
	v_mfma_f32_16x16x32_bf16 v[68:71], v[206:209], v[198:201], v[68:71]
	s_barrier
	v_mfma_f32_16x16x32_bf16 v[64:67], v[214:217], v[198:201], v[64:67]
	s_setprio 0
	s_mov_b32 m0, s60
	v_lshl_add_u64 v[190:191], v[220:221], 0, s[16:17]
	ds_read_b128 v[166:169], v149 offset:49152
	ds_read_b128 v[170:173], v149 offset:50176
	ds_read_b128 v[174:177], v149 offset:51200
	ds_read_b128 v[178:181], v149 offset:52224
	ds_read_b128 v[182:185], v149 offset:53248
	ds_read_b128 v[186:189], v149 offset:54272
	ds_read_b128 v[194:197], v149 offset:55296
	ds_read_b128 v[198:201], v149 offset:56320
	global_load_lds_dwordx4 v[190:191], off
	v_lshl_add_u64 v[190:191], v[222:223], 0, s[16:17]
	s_mov_b32 m0, s61
	s_nop 0
	global_load_lds_dwordx4 v[190:191], off
	s_barrier
; __device__ __forceinline__ unsigned cvt_pk_bf16(float lo, float hi) { unsigned r; asm volatile("v_cvt_pk_bf16_f32 %0, %1, %2" : "=v"(r) : "v"(lo), "v"(hi)); return r; }
; #define PG8_STAGE(bufoff, gbase, voff) do { _Pragma("unroll") for (int _i = 0; _i < 2; ++_i) \
;         __builtin_amdgcn_global_load_lds((const unsigned*)((const char*)(gbase) + (voff)[_i]), (LAS unsigned*)(lds + (bufoff) + ldsw + _i * 8192), 16, 0, 0); } while (0)
; #define PG8_MMA(ai, bj, At, Bt) do { __builtin_amdgcn_s_setprio(1); _Pragma("unroll") for (int m = 0; m < 4; ++m) _Pragma("unroll") for (int n = 0; n < 2; ++n) _Pragma("unroll") for (int k = 0; k < 2; ++k) \
;         acc[ai][bj][m][n] = __builtin_amdgcn_mfma_f32_16x16x32_bf16(Bt[n][k], At[m][k], acc[ai][bj][m][n], 0, 0, 0); __builtin_amdgcn_s_setprio(0); } while (0)
; #define PG8_WAIT_V(n) asm volatile("s_waitcnt vmcnt(" #n ")" ::: "memory")
; #define PG8_WAIT_L(n) asm volatile("s_waitcnt lgkmcnt(" #n ")" ::: "memory")
; #define PG8_BAR __builtin_amdgcn_s_barrier()
; #define PG8_SCHED __builtin_amdgcn_sched_barrier(0)
; template <class Epi>
; __device__ __forceinline__ void gemm_phase(LAS unsigned char* lds, const Gemm g, const Sched& S, const Epi& E) {
;     ...
;             PG8_BAR; PG8_WAIT_L(0); PG8_MMA(1, 0, At, B0); PG8_BAR; PG8_SCHED;
;             PG8_STAGE(PG8_SB(1, 1), b3 + hstepB, voffB);
;             PG8_WAIT_V(6); PG8_BAR; PG8_MMA(1, 1, At, B1); PG8_BAR;
;     __device__ __forceinline__ void operator()(AccRef acc, const Unit& u, int wr, int wc, int fr, int fq) const {
; #pragma unroll
;         for (int ai = 0; ai < 2; ++ai)
; #pragma unroll
;             for (int m = 0; m < 4; ++m) { const size_t row = (size_t)u.pm * 256 + ai * 128 + wr * 64 + m * 16 + fr; float o[8];
; #pragma unroll
;                 for (int bj = 0; bj < 2; ++bj) { const f32x4 gg = acc[ai][bj][m][0], uu = acc[ai][bj][m][1];
; #pragma unroll
;                     for (int j = 0; j < 4; ++j) o[4 * bj + j] = gg[j] * __builtin_amdgcn_rcpf(1.0f + __expf(-gg[j])) * uu[j]; }
;                 u32x4 w; w.x = cvt_pk_bf16(o[0], o[1]); w.y = cvt_pk_bf16(o[2], o[3]); w.z = cvt_pk_bf16(o[4], o[5]); w.w = cvt_pk_bf16(o[6], o[7]);
;                 *(u32x4*)(act + row * FF_ + (u.pn * 4 + wc) * 32 + 8 * fq) = w; }
	s_waitcnt lgkmcnt(0)
	s_setprio 1
	s_waitcnt lgkmcnt(0)
	v_mfma_f32_16x16x32_bf16 v[60:63], v[150:153], v[166:169], v[60:63]
	v_mfma_f32_16x16x32_bf16 v[56:59], v[158:161], v[166:169], v[56:59]
	v_mfma_f32_16x16x32_bf16 v[52:55], v[150:153], v[174:177], v[52:55]
	v_mfma_f32_16x16x32_bf16 v[48:51], v[158:161], v[174:177], v[48:51]
	v_mfma_f32_16x16x32_bf16 v[44:47], v[150:153], v[182:185], v[44:47]
	v_mfma_f32_16x16x32_bf16 v[40:43], v[158:161], v[182:185], v[40:43]
	v_mfma_f32_16x16x32_bf16 v[36:39], v[150:153], v[194:197], v[36:39]
	v_mfma_f32_16x16x32_bf16 v[32:35], v[158:161], v[194:197], v[32:35]
	v_mfma_f32_16x16x32_bf16 v[60:63], v[154:157], v[170:173], v[60:63]
	v_mfma_f32_16x16x32_bf16 v[56:59], v[162:165], v[170:173], v[56:59]
	v_mfma_f32_16x16x32_bf16 v[52:55], v[154:157], v[178:181], v[52:55]
	v_mfma_f32_16x16x32_bf16 v[48:51], v[162:165], v[178:181], v[48:51]
	v_mfma_f32_16x16x32_bf16 v[44:47], v[154:157], v[186:189], v[44:47]
	v_mfma_f32_16x16x32_bf16 v[40:43], v[162:165], v[186:189], v[40:43]
	v_mfma_f32_16x16x32_bf16 v[36:39], v[154:157], v[198:201], v[36:39]
	s_barrier
	v_mfma_f32_16x16x32_bf16 v[32:35], v[162:165], v[198:201], v[32:35]
	s_setprio 0
	s_add_u32 s38, s38, 0x80080
	s_addc_u32 s39, s39, 0
	s_add_i32 s54, s54, s34
	v_lshl_add_u64 v[150:151], s[38:39], 0, v[130:131]
	s_mov_b32 m0, s54
	s_nop 0
	global_load_lds_dwordx4 v[150:151], off
	v_lshl_add_u64 v[150:151], s[38:39], 0, v[128:129]
	s_add_i32 m0, s54, 0x2000
	s_nop 0
	global_load_lds_dwordx4 v[150:151], off
	s_waitcnt vmcnt(6)
	s_barrier
	s_setprio 1
	v_mfma_f32_16x16x32_bf16 v[28:31], v[202:205], v[166:169], v[28:31]
	v_mfma_f32_16x16x32_bf16 v[24:27], v[210:213], v[166:169], v[24:27]
	v_mfma_f32_16x16x32_bf16 v[20:23], v[202:205], v[174:177], v[20:23]
	v_mfma_f32_16x16x32_bf16 v[16:19], v[210:213], v[174:177], v[16:19]
	v_mfma_f32_16x16x32_bf16 v[12:15], v[202:205], v[182:185], v[12:15]
	v_mfma_f32_16x16x32_bf16 v[8:11], v[210:213], v[182:185], v[8:11]
	v_mfma_f32_16x16x32_bf16 v[4:7], v[202:205], v[194:197], v[4:7]
	v_mfma_f32_16x16x32_bf16 v[0:3], v[210:213], v[194:197], v[0:3]
	v_mfma_f32_16x16x32_bf16 v[28:31], v[206:209], v[170:173], v[28:31]
	v_mfma_f32_16x16x32_bf16 v[24:27], v[214:217], v[170:173], v[24:27]
	v_mfma_f32_16x16x32_bf16 v[20:23], v[206:209], v[178:181], v[20:23]
	v_mfma_f32_16x16x32_bf16 v[16:19], v[214:217], v[178:181], v[16:19]
	v_mfma_f32_16x16x32_bf16 v[12:15], v[206:209], v[186:189], v[12:15]
	v_mfma_f32_16x16x32_bf16 v[8:11], v[214:217], v[186:189], v[8:11]
	v_mfma_f32_16x16x32_bf16 v[4:7], v[206:209], v[198:201], v[4:7]
	s_barrier
	v_mfma_f32_16x16x32_bf16 v[0:3], v[214:217], v[198:201], v[0:3]
	s_setprio 0
	s_add_i32 s81, s81, 2
	s_add_u32 s36, s36, 0x100
	s_addc_u32 s37, s37, 0
	s_cmp_gt_u32 s81, 29
	s_cbranch_scc0 .LBB0_2088
	v_mul_f32_e32 v150, 0xbfb8aa3b, v126
	v_exp_f32_e32 v150, v150
	v_mul_f32_e32 v151, 0xbfb8aa3b, v127
	v_exp_f32_e32 v151, v151
	v_mul_f32_e32 v152, 0xbfb8aa3b, v92
	v_add_f32_e32 v150, 1.0, v150
	v_rcp_f32_e32 v150, v150
	v_add_f32_e32 v151, 1.0, v151
	v_rcp_f32_e32 v151, v151
	v_exp_f32_e32 v152, v152
	v_mul_f32_e32 v150, v126, v150
	v_mul_f32_e32 v153, v122, v150
	v_mul_f32_e32 v150, v127, v151
	v_add_f32_e32 v151, 1.0, v152
	v_rcp_f32_e32 v151, v151
	v_mul_f32_e32 v152, 0xbfb8aa3b, v93
	v_exp_f32_e32 v152, v152
	v_mul_f32_e32 v146, 0xbfb8aa3b, v124
	v_mul_f32_e32 v147, 0xbfb8aa3b, v125
	v_mul_f32_e32 v154, v123, v150
	v_mul_f32_e32 v150, v92, v151
	v_mul_f32_e32 v151, 0xbfb8aa3b, v94
	v_exp_f32_e32 v146, v146
	v_exp_f32_e32 v147, v147
	v_mul_f32_e32 v155, v88, v150
	v_add_f32_e32 v150, 1.0, v152
	v_exp_f32_e32 v151, v151
	v_mul_f32_e32 v152, 0xbfb8aa3b, v95
	v_exp_f32_e32 v152, v152
	v_add_f32_e32 v146, 1.0, v146
	v_add_f32_e32 v147, 1.0, v147
	v_rcp_f32_e32 v150, v150
	v_add_f32_e32 v151, 1.0, v151
	v_rcp_f32_e32 v146, v146
	v_rcp_f32_e32 v147, v147
	v_rcp_f32_e32 v151, v151
	v_add_f32_e32 v152, 1.0, v152
	v_rcp_f32_e32 v152, v152
	s_add_u32 s36, s13, 0xffffff00
	v_mul_f32_e32 v150, v93, v150
	s_addc_u32 s37, s51, -1
	s_ashr_i32 s13, s12, 31
	v_mul_f32_e32 v146, v124, v146
	v_mul_f32_e32 v147, v125, v147
	v_mul_f32_e32 v156, v89, v150
	v_mul_f32_e32 v150, v94, v151
	s_lshl_b64 s[38:39], s[12:13], 8
	v_mul_f32_e32 v146, v120, v146
	v_mul_f32_e32 v147, v121, v147
	v_mul_f32_e32 v157, v90, v150
	v_mul_f32_e32 v150, v95, v152
	v_lshl_add_u64 v[144:145], v[134:135], 0, s[38:39]
	v_mul_f32_e32 v158, v91, v150
	v_cvt_pk_bf16_f32 v150, v146, v147
	v_mov_b64_e32 v[146:147], s[44:45]
	v_mad_u64_u32 v[146:147], s[54:55], v144, s64, v[146:147]
	s_lshl_b32 s13, s58, 7
	v_mov_b32_e32 v144, v147
	s_or_b32 s38, s13, s59
	v_mad_u64_u32 v[144:145], s[54:55], v145, s64, v[144:145]
	s_ashr_i32 s39, s38, 31
	v_mov_b32_e32 v147, v144
	v_lshl_add_u64 v[144:145], s[38:39], 1, v[146:147]
	v_lshl_add_u64 v[144:145], v[144:145], 0, v[132:133]
	v_cvt_pk_bf16_f32 v151, v153, v154
	v_cvt_pk_bf16_f32 v152, v155, v156
	v_cvt_pk_bf16_f32 v153, v157, v158
	global_store_dwordx4 v[144:145], v[150:153], off
	v_mul_f32_e32 v146, 0xbfb8aa3b, v116
	v_exp_f32_e32 v146, v146
	v_mul_f32_e32 v150, 0xbfb8aa3b, v118
	v_exp_f32_e32 v150, v150
	v_mul_f32_e32 v151, 0xbfb8aa3b, v119
	v_exp_f32_e32 v151, v151
	v_mul_f32_e32 v152, 0xbfb8aa3b, v84
	v_add_f32_e32 v150, 1.0, v150
	v_rcp_f32_e32 v150, v150
	v_add_f32_e32 v151, 1.0, v151
	v_rcp_f32_e32 v151, v151
	v_exp_f32_e32 v152, v152
	v_mul_f32_e32 v150, v118, v150
	v_mul_f32_e32 v153, v114, v150
	v_mul_f32_e32 v150, v119, v151
	v_add_f32_e32 v151, 1.0, v152
	v_rcp_f32_e32 v151, v151
	v_mul_f32_e32 v152, 0xbfb8aa3b, v85
	v_exp_f32_e32 v152, v152
	v_mul_f32_e32 v154, v115, v150
	v_mul_f32_e32 v150, v84, v151
; __device__ __forceinline__ unsigned cvt_pk_bf16(float lo, float hi) { unsigned r; asm volatile("v_cvt_pk_bf16_f32 %0, %1, %2" : "=v"(r) : "v"(lo), "v"(hi)); return r; }
;     __device__ __forceinline__ void operator()(AccRef acc, const Unit& u, int wr, int wc, int fr, int fq) const {
;     ...
;         for (int ai = 0; ai < 2; ++ai)
; #pragma unroll
;             for (int m = 0; m < 4; ++m) { const size_t row = (size_t)u.pm * 256 + ai * 128 + wr * 64 + m * 16 + fr; float o[8];
; #pragma unroll
;                 for (int bj = 0; bj < 2; ++bj) { const f32x4 gg = acc[ai][bj][m][0], uu = acc[ai][bj][m][1];
; #pragma unroll
;                     for (int j = 0; j < 4; ++j) o[4 * bj + j] = gg[j] * __builtin_amdgcn_rcpf(1.0f + __expf(-gg[j])) * uu[j]; }
;                 u32x4 w; w.x = cvt_pk_bf16(o[0], o[1]); w.y = cvt_pk_bf16(o[2], o[3]); w.z = cvt_pk_bf16(o[4], o[5]); w.w = cvt_pk_bf16(o[6], o[7]);
;                 *(u32x4*)(act + row * FF_ + (u.pn * 4 + wc) * 32 + 8 * fq) = w; }
	v_mul_f32_e32 v151, 0xbfb8aa3b, v86
	v_mul_f32_e32 v147, 0xbfb8aa3b, v117
	v_mul_f32_e32 v155, v80, v150
	v_add_f32_e32 v150, 1.0, v152
	v_exp_f32_e32 v151, v151
	v_mul_f32_e32 v152, 0xbfb8aa3b, v87
	v_exp_f32_e32 v147, v147
	v_exp_f32_e32 v152, v152
	v_add_f32_e32 v146, 1.0, v146
	v_rcp_f32_e32 v150, v150
	v_add_f32_e32 v151, 1.0, v151
	v_rcp_f32_e32 v146, v146
	v_add_f32_e32 v147, 1.0, v147
	v_rcp_f32_e32 v151, v151
	v_add_f32_e32 v152, 1.0, v152
	v_rcp_f32_e32 v147, v147
	v_rcp_f32_e32 v152, v152
	v_mul_f32_e32 v150, v85, v150
	v_mul_f32_e32 v146, v116, v146
	v_mul_f32_e32 v156, v81, v150
	v_mul_f32_e32 v150, v86, v151
	v_mul_f32_e32 v146, v112, v146
	v_mul_f32_e32 v147, v117, v147
	v_mul_f32_e32 v157, v82, v150
	v_mul_f32_e32 v150, v87, v152
	v_mul_f32_e32 v147, v113, v147
	v_mul_f32_e32 v158, v83, v150
	v_cvt_pk_bf16_f32 v150, v146, v147
	v_mul_f32_e32 v146, 0xbfb8aa3b, v108
	v_cvt_pk_bf16_f32 v151, v153, v154
	v_exp_f32_e32 v154, v146
	v_mul_f32_e32 v146, 0xbfb8aa3b, v109
	v_cvt_pk_bf16_f32 v152, v155, v156
	v_exp_f32_e32 v155, v146
	v_add_co_u32_e32 v146, vcc, s65, v144
	v_cvt_pk_bf16_f32 v153, v157, v158
	v_add_f32_e32 v154, 1.0, v154
	s_nop 0
	v_addc_co_u32_e32 v147, vcc, 0, v145, vcc
	global_store_dwordx4 v[146:147], v[150:153], off
	v_rcp_f32_e32 v154, v154
	v_add_f32_e32 v155, 1.0, v155
	v_mul_f32_e32 v150, 0xbfb8aa3b, v110
	v_exp_f32_e32 v150, v150
	v_mul_f32_e32 v151, 0xbfb8aa3b, v111
	v_exp_f32_e32 v151, v151
	v_mul_f32_e32 v152, 0xbfb8aa3b, v76
	v_add_f32_e32 v150, 1.0, v150
	v_rcp_f32_e32 v150, v150
	v_add_f32_e32 v151, 1.0, v151
	v_rcp_f32_e32 v151, v151
	v_exp_f32_e32 v152, v152
	v_mul_f32_e32 v150, v110, v150
	v_mul_f32_e32 v153, v106, v150
	v_mul_f32_e32 v150, v111, v151
	v_add_f32_e32 v151, 1.0, v152
	v_rcp_f32_e32 v151, v151
	v_mul_f32_e32 v152, 0xbfb8aa3b, v77
	v_rcp_f32_e32 v155, v155
	v_exp_f32_e32 v152, v152
	v_mul_f32_e32 v146, v108, v154
	v_mul_f32_e32 v154, v107, v150
	v_mul_f32_e32 v150, v76, v151
	v_mul_f32_e32 v151, 0xbfb8aa3b, v78
	v_mul_f32_e32 v147, v109, v155
	v_mul_f32_e32 v155, v72, v150
	v_add_f32_e32 v150, 1.0, v152
	v_exp_f32_e32 v151, v151
	v_mul_f32_e32 v152, 0xbfb8aa3b, v79
	v_exp_f32_e32 v152, v152
	v_rcp_f32_e32 v150, v150
	v_add_f32_e32 v151, 1.0, v151
	v_rcp_f32_e32 v151, v151
	v_add_f32_e32 v152, 1.0, v152
	v_rcp_f32_e32 v152, v152
	v_mul_f32_e32 v150, v77, v150
	v_mul_f32_e32 v156, v73, v150
	v_mul_f32_e32 v150, v78, v151
	v_mul_f32_e32 v146, v104, v146
	v_mul_f32_e32 v157, v74, v150
	v_mul_f32_e32 v150, v79, v152
	v_mul_f32_e32 v147, v105, v147
	v_mul_f32_e32 v158, v75, v150
	v_cvt_pk_bf16_f32 v150, v146, v147
	v_mul_f32_e32 v146, 0xbfb8aa3b, v100
	v_cvt_pk_bf16_f32 v151, v153, v154
	v_exp_f32_e32 v154, v146
	v_mul_f32_e32 v146, 0xbfb8aa3b, v101
	v_cvt_pk_bf16_f32 v152, v155, v156
	v_exp_f32_e32 v155, v146
	v_add_co_u32_e32 v146, vcc, s66, v144
	v_cvt_pk_bf16_f32 v153, v157, v158
	v_add_f32_e32 v154, 1.0, v154
	s_nop 0
	v_addc_co_u32_e32 v147, vcc, 0, v145, vcc
	global_store_dwordx4 v[146:147], v[150:153], off
	v_rcp_f32_e32 v154, v154
	v_add_f32_e32 v155, 1.0, v155
	v_mul_f32_e32 v150, 0xbfb8aa3b, v102
	v_exp_f32_e32 v150, v150
	v_mul_f32_e32 v151, 0xbfb8aa3b, v103
	v_exp_f32_e32 v151, v151
	v_mul_f32_e32 v152, 0xbfb8aa3b, v68
	v_add_f32_e32 v150, 1.0, v150
	v_rcp_f32_e32 v150, v150
	v_add_f32_e32 v151, 1.0, v151
	v_rcp_f32_e32 v151, v151
	v_exp_f32_e32 v152, v152
	v_mul_f32_e32 v150, v102, v150
	v_mul_f32_e32 v153, v98, v150
	v_mul_f32_e32 v150, v103, v151
	v_add_f32_e32 v151, 1.0, v152
	v_rcp_f32_e32 v151, v151
	v_mul_f32_e32 v152, 0xbfb8aa3b, v69
	v_rcp_f32_e32 v155, v155
	v_exp_f32_e32 v152, v152
	v_mul_f32_e32 v146, v100, v154
	v_mul_f32_e32 v154, v99, v150
	v_mul_f32_e32 v150, v68, v151
	v_mul_f32_e32 v151, 0xbfb8aa3b, v70
	v_mul_f32_e32 v147, v101, v155
	v_mul_f32_e32 v155, v64, v150
	v_add_f32_e32 v150, 1.0, v152
	v_exp_f32_e32 v151, v151
	v_mul_f32_e32 v152, 0xbfb8aa3b, v71
	v_exp_f32_e32 v152, v152
	v_rcp_f32_e32 v150, v150
	v_add_f32_e32 v151, 1.0, v151
	v_rcp_f32_e32 v151, v151
	v_add_f32_e32 v152, 1.0, v152
	v_rcp_f32_e32 v152, v152
	v_mul_f32_e32 v150, v69, v150
	v_mul_f32_e32 v156, v65, v150
	v_mul_f32_e32 v150, v70, v151
	v_mul_f32_e32 v146, v96, v146
	v_mul_f32_e32 v157, v66, v150
	v_mul_f32_e32 v150, v71, v152
	v_mul_f32_e32 v147, v97, v147
	v_mul_f32_e32 v158, v67, v150
	v_cvt_pk_bf16_f32 v150, v146, v147
	v_mul_f32_e32 v146, 0xbfb8aa3b, v60
	v_cvt_pk_bf16_f32 v151, v153, v154
	v_exp_f32_e32 v154, v146
	v_mul_f32_e32 v146, 0xbfb8aa3b, v61
	v_cvt_pk_bf16_f32 v152, v155, v156
	v_exp_f32_e32 v155, v146
	v_add_co_u32_e32 v146, vcc, s67, v144
	v_cvt_pk_bf16_f32 v153, v157, v158
	v_add_f32_e32 v154, 1.0, v154
	s_nop 0
	v_addc_co_u32_e32 v147, vcc, 0, v145, vcc
	global_store_dwordx4 v[146:147], v[150:153], off
	v_rcp_f32_e32 v154, v154
	v_add_f32_e32 v155, 1.0, v155
	v_mul_f32_e32 v150, 0xbfb8aa3b, v62
	v_exp_f32_e32 v150, v150
	v_mul_f32_e32 v151, 0xbfb8aa3b, v63
	v_exp_f32_e32 v151, v151
	v_mul_f32_e32 v152, 0xbfb8aa3b, v28
	v_add_f32_e32 v150, 1.0, v150
	v_rcp_f32_e32 v150, v150
	v_add_f32_e32 v151, 1.0, v151
	v_rcp_f32_e32 v151, v151
	v_exp_f32_e32 v152, v152
	v_mul_f32_e32 v150, v62, v150
	v_mul_f32_e32 v153, v58, v150
	v_mul_f32_e32 v150, v63, v151
	v_add_f32_e32 v151, 1.0, v152
	v_rcp_f32_e32 v151, v151
	v_mul_f32_e32 v152, 0xbfb8aa3b, v29
	v_rcp_f32_e32 v155, v155
	v_exp_f32_e32 v152, v152
	v_mul_f32_e32 v146, v60, v154
	v_mul_f32_e32 v154, v59, v150
	v_mul_f32_e32 v150, v28, v151
	v_mul_f32_e32 v151, 0xbfb8aa3b, v30
	v_mul_f32_e32 v147, v61, v155
	v_mul_f32_e32 v155, v24, v150
	v_add_f32_e32 v150, 1.0, v152
	v_exp_f32_e32 v151, v151
	v_mul_f32_e32 v152, 0xbfb8aa3b, v31
; __device__ __forceinline__ unsigned cvt_pk_bf16(float lo, float hi) { unsigned r; asm volatile("v_cvt_pk_bf16_f32 %0, %1, %2" : "=v"(r) : "v"(lo), "v"(hi)); return r; }
;     __device__ __forceinline__ void operator()(AccRef acc, const Unit& u, int wr, int wc, int fr, int fq) const {
;     ...
;         for (int ai = 0; ai < 2; ++ai)
; #pragma unroll
;             for (int m = 0; m < 4; ++m) { const size_t row = (size_t)u.pm * 256 + ai * 128 + wr * 64 + m * 16 + fr; float o[8];
; #pragma unroll
;                 for (int bj = 0; bj < 2; ++bj) { const f32x4 gg = acc[ai][bj][m][0], uu = acc[ai][bj][m][1];
; #pragma unroll
;                     for (int j = 0; j < 4; ++j) o[4 * bj + j] = gg[j] * __builtin_amdgcn_rcpf(1.0f + __expf(-gg[j])) * uu[j]; }
;                 u32x4 w; w.x = cvt_pk_bf16(o[0], o[1]); w.y = cvt_pk_bf16(o[2], o[3]); w.z = cvt_pk_bf16(o[4], o[5]); w.w = cvt_pk_bf16(o[6], o[7]);
;                 *(u32x4*)(act + row * FF_ + (u.pn * 4 + wc) * 32 + 8 * fq) = w; }
	v_exp_f32_e32 v152, v152
	v_rcp_f32_e32 v150, v150
	v_add_f32_e32 v151, 1.0, v151
	v_rcp_f32_e32 v151, v151
	v_add_f32_e32 v152, 1.0, v152
	v_rcp_f32_e32 v152, v152
	v_mul_f32_e32 v150, v29, v150
	v_mul_f32_e32 v156, v25, v150
	v_mul_f32_e32 v150, v30, v151
	v_mul_f32_e32 v146, v56, v146
	v_mul_f32_e32 v157, v26, v150
	v_mul_f32_e32 v150, v31, v152
	v_mul_f32_e32 v147, v57, v147
	v_mul_f32_e32 v158, v27, v150
	v_cvt_pk_bf16_f32 v150, v146, v147
	v_mul_f32_e32 v146, 0xbfb8aa3b, v52
	v_cvt_pk_bf16_f32 v151, v153, v154
	v_exp_f32_e32 v154, v146
	v_mul_f32_e32 v146, 0xbfb8aa3b, v53
	v_cvt_pk_bf16_f32 v152, v155, v156
	v_exp_f32_e32 v155, v146
	v_add_co_u32_e32 v146, vcc, s70, v144
	v_cvt_pk_bf16_f32 v153, v157, v158
	v_add_f32_e32 v154, 1.0, v154
	s_nop 0
	v_addc_co_u32_e32 v147, vcc, 0, v145, vcc
	global_store_dwordx4 v[146:147], v[150:153], off
	v_rcp_f32_e32 v154, v154
	v_add_f32_e32 v155, 1.0, v155
	v_mul_f32_e32 v150, 0xbfb8aa3b, v54
	v_exp_f32_e32 v150, v150
	v_mul_f32_e32 v151, 0xbfb8aa3b, v55
	v_exp_f32_e32 v151, v151
	v_mul_f32_e32 v152, 0xbfb8aa3b, v20
	v_add_f32_e32 v150, 1.0, v150
	v_rcp_f32_e32 v150, v150
	v_add_f32_e32 v151, 1.0, v151
	v_rcp_f32_e32 v151, v151
	v_exp_f32_e32 v152, v152
	v_mul_f32_e32 v150, v54, v150
	v_mul_f32_e32 v153, v50, v150
	v_mul_f32_e32 v150, v55, v151
	v_add_f32_e32 v151, 1.0, v152
	v_rcp_f32_e32 v151, v151
	v_mul_f32_e32 v152, 0xbfb8aa3b, v21
	v_rcp_f32_e32 v155, v155
	v_exp_f32_e32 v152, v152
	v_mul_f32_e32 v146, v52, v154
	v_mul_f32_e32 v154, v51, v150
	v_mul_f32_e32 v150, v20, v151
	v_mul_f32_e32 v151, 0xbfb8aa3b, v22
	v_mul_f32_e32 v147, v53, v155
	v_mul_f32_e32 v155, v16, v150
	v_add_f32_e32 v150, 1.0, v152
	v_exp_f32_e32 v151, v151
	v_mul_f32_e32 v152, 0xbfb8aa3b, v23
	v_exp_f32_e32 v152, v152
	v_rcp_f32_e32 v150, v150
	v_add_f32_e32 v151, 1.0, v151
	v_rcp_f32_e32 v151, v151
	v_add_f32_e32 v152, 1.0, v152
	v_rcp_f32_e32 v152, v152
	v_mul_f32_e32 v150, v21, v150
	v_mul_f32_e32 v156, v17, v150
	v_mul_f32_e32 v150, v22, v151
	v_mul_f32_e32 v146, v48, v146
	v_mul_f32_e32 v157, v18, v150
	v_mul_f32_e32 v150, v23, v152
	v_mul_f32_e32 v147, v49, v147
	v_mul_f32_e32 v158, v19, v150
	v_cvt_pk_bf16_f32 v150, v146, v147
	v_mul_f32_e32 v146, 0xbfb8aa3b, v44
	v_cvt_pk_bf16_f32 v151, v153, v154
	v_exp_f32_e32 v154, v146
	v_mul_f32_e32 v146, 0xbfb8aa3b, v45
	v_cvt_pk_bf16_f32 v152, v155, v156
	v_exp_f32_e32 v155, v146
	v_add_co_u32_e32 v146, vcc, s71, v144
	v_cvt_pk_bf16_f32 v153, v157, v158
	v_add_f32_e32 v154, 1.0, v154
	s_nop 0
	v_addc_co_u32_e32 v147, vcc, 0, v145, vcc
	global_store_dwordx4 v[146:147], v[150:153], off
	v_rcp_f32_e32 v154, v154
	v_add_f32_e32 v155, 1.0, v155
	v_mul_f32_e32 v150, 0xbfb8aa3b, v46
	v_exp_f32_e32 v150, v150
	v_mul_f32_e32 v151, 0xbfb8aa3b, v47
	v_exp_f32_e32 v151, v151
	v_mul_f32_e32 v152, 0xbfb8aa3b, v12
	v_add_f32_e32 v150, 1.0, v150
	v_rcp_f32_e32 v150, v150
	v_add_f32_e32 v151, 1.0, v151
	v_rcp_f32_e32 v151, v151
	v_exp_f32_e32 v152, v152
	v_mul_f32_e32 v150, v46, v150
	v_mul_f32_e32 v153, v42, v150
	v_mul_f32_e32 v150, v47, v151
	v_add_f32_e32 v151, 1.0, v152
	v_rcp_f32_e32 v151, v151
	v_mul_f32_e32 v152, 0xbfb8aa3b, v13
	v_rcp_f32_e32 v155, v155
	v_exp_f32_e32 v152, v152
	v_mul_f32_e32 v146, v44, v154
	v_mul_f32_e32 v154, v43, v150
	v_mul_f32_e32 v150, v12, v151
	v_mul_f32_e32 v151, 0xbfb8aa3b, v14
	v_mul_f32_e32 v147, v45, v155
	v_mul_f32_e32 v155, v8, v150
	v_add_f32_e32 v150, 1.0, v152
	v_exp_f32_e32 v151, v151
	v_mul_f32_e32 v152, 0xbfb8aa3b, v15
	v_exp_f32_e32 v152, v152
	v_rcp_f32_e32 v150, v150
	v_add_f32_e32 v151, 1.0, v151
	v_rcp_f32_e32 v151, v151
	v_add_f32_e32 v152, 1.0, v152
	v_rcp_f32_e32 v152, v152
	v_mul_f32_e32 v150, v13, v150
	v_mul_f32_e32 v156, v9, v150
	v_mul_f32_e32 v150, v14, v151
	v_mul_f32_e32 v146, v40, v146
	v_mul_f32_e32 v157, v10, v150
	v_mul_f32_e32 v150, v15, v152
	v_mul_f32_e32 v147, v41, v147
	v_mul_f32_e32 v158, v11, v150
	v_cvt_pk_bf16_f32 v150, v146, v147
	v_mul_f32_e32 v146, 0xbfb8aa3b, v36
	v_cvt_pk_bf16_f32 v151, v153, v154
	v_exp_f32_e32 v154, v146
	v_mul_f32_e32 v146, 0xbfb8aa3b, v37
	v_cvt_pk_bf16_f32 v152, v155, v156
	v_exp_f32_e32 v155, v146
	v_add_co_u32_e32 v146, vcc, s78, v144
	v_cvt_pk_bf16_f32 v153, v157, v158
	v_add_f32_e32 v154, 1.0, v154
	s_nop 0
	v_addc_co_u32_e32 v147, vcc, 0, v145, vcc
	global_store_dwordx4 v[146:147], v[150:153], off
	v_rcp_f32_e32 v154, v154
	v_add_f32_e32 v155, 1.0, v155
	v_mul_f32_e32 v150, 0xbfb8aa3b, v38
	v_exp_f32_e32 v150, v150
	v_mul_f32_e32 v151, 0xbfb8aa3b, v39
	v_exp_f32_e32 v151, v151
	v_mul_f32_e32 v152, 0xbfb8aa3b, v4
	v_add_f32_e32 v150, 1.0, v150
	v_rcp_f32_e32 v150, v150
	v_add_f32_e32 v151, 1.0, v151
	v_rcp_f32_e32 v151, v151
	v_exp_f32_e32 v152, v152
	v_mul_f32_e32 v150, v38, v150
	v_mul_f32_e32 v153, v34, v150
	v_mul_f32_e32 v150, v39, v151
	v_add_f32_e32 v151, 1.0, v152
	v_rcp_f32_e32 v151, v151
	v_mul_f32_e32 v152, 0xbfb8aa3b, v5
	v_rcp_f32_e32 v155, v155
	v_exp_f32_e32 v152, v152
	v_mul_f32_e32 v146, v36, v154
	v_mul_f32_e32 v154, v35, v150
	v_mul_f32_e32 v150, v4, v151
	v_mul_f32_e32 v151, 0xbfb8aa3b, v6
	v_mul_f32_e32 v147, v37, v155
	v_mul_f32_e32 v155, v0, v150
	v_add_f32_e32 v150, 1.0, v152
	v_exp_f32_e32 v151, v151
	v_mul_f32_e32 v152, 0xbfb8aa3b, v7
	v_exp_f32_e32 v152, v152
	v_rcp_f32_e32 v150, v150
	v_add_f32_e32 v151, 1.0, v151
	v_rcp_f32_e32 v151, v151
	v_add_f32_e32 v152, 1.0, v152
	v_rcp_f32_e32 v152, v152
	v_mul_f32_e32 v150, v5, v150
	v_add_co_u32_e32 v144, vcc, 0x1e4000, v144
	v_mul_f32_e32 v156, v1, v150
	v_mul_f32_e32 v150, v6, v151
	v_addc_co_u32_e32 v145, vcc, 0, v145, vcc
	v_mul_f32_e32 v157, v2, v150
	v_mul_f32_e32 v150, v7, v152
	s_andn2_b64 vcc, exec, s[10:11]
	v_mul_f32_e32 v146, v32, v146
	v_mul_f32_e32 v147, v33, v147
	v_mul_f32_e32 v158, v3, v150
	v_cvt_pk_bf16_f32 v150, v146, v147
	v_cvt_pk_bf16_f32 v151, v153, v154
	v_cvt_pk_bf16_f32 v152, v155, v156
	v_cvt_pk_bf16_f32 v153, v157, v158
	global_store_dwordx4 v[144:145], v[150:153], off
	s_cbranch_vccz .LBB0_2084
	s_mov_b64 s[22:23], s[36:37]
	s_andn2_b64 vcc, exec, s[8:9]
	s_mov_b64 s[36:37], s[22:23]
	s_cbranch_vccnz .LBB0_2085

; #define PG8_STAGE(bufoff, gbase, voff) do { _Pragma("unroll") for (int _i = 0; _i < 2; ++_i) \
;         __builtin_amdgcn_global_load_lds((const unsigned*)((const char*)(gbase) + (voff)[_i]), (LAS unsigned*)(lds + (bufoff) + ldsw + _i * 8192), 16, 0, 0); } while (0)
; #define PG8_LDA(dst, b, h) do { _Pragma("unroll") for (int m = 0; m < 4; ++m) _Pragma("unroll") for (int k = 0; k < 2; ++k) dst[m][k] = *(const LAS bf16x8*)(lds + PG8_SA(b, h) + aoff + m * 2048 + k * 1024); } while (0)
; #define PG8_LDB(dst, b, h) do { _Pragma("unroll") for (int n = 0; n < 2; ++n) _Pragma("unroll") for (int k = 0; k < 2; ++k) dst[n][k] = *(const LAS bf16x8*)(lds + PG8_SB(b, h) + boff + n * 2048 + k * 1024); } while (0)
; #define PG8_MMA(ai, bj, At, Bt) do { __builtin_amdgcn_s_setprio(1); _Pragma("unroll") for (int m = 0; m < 4; ++m) _Pragma("unroll") for (int n = 0; n < 2; ++n) _Pragma("unroll") for (int k = 0; k < 2; ++k) \
;         acc[ai][bj][m][n] = __builtin_amdgcn_mfma_f32_16x16x32_bf16(Bt[n][k], At[m][k], acc[ai][bj][m][n], 0, 0, 0); __builtin_amdgcn_s_setprio(0); } while (0)
; #define PG8_WAIT_V(n) asm volatile("s_waitcnt vmcnt(" #n ")" ::: "memory")
; #define PG8_WAIT_L(n) asm volatile("s_waitcnt lgkmcnt(" #n ")" ::: "memory")
; #define PG8_BAR __builtin_amdgcn_s_barrier()
; #define PG8_SCHED __builtin_amdgcn_sched_barrier(0)
; template <class Epi>
; __device__ __forceinline__ void gemm_phase(LAS unsigned char* lds, const Gemm g, const Sched& S, const Epi& E) {
;     ...
;             PG8_LDB(B0, 0, 0); PG8_SCHED; PG8_LDA(At, 0, 0); PG8_STAGE(PG8_SA(1, 1), a1 + hstepA, voffA);
;             PG8_WAIT_L(8); PG8_BAR; PG8_WAIT_L(0); PG8_MMA(0, 0, At, B0); PG8_BAR; PG8_SCHED;
;             PG8_LDB(B1, 0, 1); PG8_STAGE(PG8_SB(0, 0), b2, voffB);
;             PG8_BAR; PG8_WAIT_L(0); PG8_MMA(0, 1, At, B1); PG8_BAR;
;             PG8_LDA(At, 0, 1); PG8_STAGE(PG8_SA(0, 0), a2, voffA);
;             PG8_BAR; PG8_WAIT_L(0); PG8_MMA(1, 0, At, B0); PG8_BAR; PG8_SCHED;
;             PG8_STAGE(PG8_SB(0, 1), b2 + hstepB, voffB);
;             PG8_WAIT_V(6); PG8_BAR; PG8_MMA(1, 1, At, B1); PG8_BAR;
.LBB0_2166:
	v_add_u32_e32 v144, s56, v204
	s_add_u32 s24, s16, s22
	ds_read_b128 v[132:135], v144
	ds_read_b128 v[136:139], v144 offset:1024
	ds_read_b128 v[140:143], v144 offset:2048
	ds_read_b128 v[144:147], v144 offset:3072
	s_addc_u32 s25, s17, s23
	s_add_u32 s24, s24, 0x100
	s_addc_u32 s25, s25, 0
	s_add_u32 s70, s15, s22
	s_addc_u32 s71, s51, s23
	s_cmpk_eq_i32 s22, 0x2b00
	s_cselect_b32 s37, s21, s25
	s_cselect_b32 s36, s20, s24
	s_cselect_b32 s25, s13, s71
	s_cselect_b32 s24, s12, s70
	v_lshl_add_u64 v[196:197], v[128:129], 0, s[22:23]
	s_add_i32 m0, s35, 0xc000
	ds_read_b128 v[148:151], v205
	ds_read_b128 v[152:155], v205 offset:1024
	ds_read_b128 v[156:159], v205 offset:2048
	ds_read_b128 v[160:163], v205 offset:3072
	ds_read_b128 v[164:167], v205 offset:4096
	ds_read_b128 v[168:171], v205 offset:5120
	ds_read_b128 v[172:175], v205 offset:6144
	ds_read_b128 v[176:179], v205 offset:7168
	global_load_lds_dwordx4 v[196:197], off
	v_lshl_add_u64 v[196:197], v[130:131], 0, s[22:23]
	s_add_i32 m0, s35, 0xe000
	s_nop 0
	global_load_lds_dwordx4 v[196:197], off
	s_waitcnt lgkmcnt(8)
	s_barrier
	s_waitcnt lgkmcnt(0)
	s_setprio 1
	s_waitcnt lgkmcnt(0)
	v_mfma_f32_16x16x32_bf16 v[124:127], v[132:135], v[148:151], v[124:127]
	v_mfma_f32_16x16x32_bf16 v[120:123], v[140:143], v[148:151], v[120:123]
	v_mfma_f32_16x16x32_bf16 v[116:119], v[132:135], v[156:159], v[116:119]
	v_mfma_f32_16x16x32_bf16 v[112:115], v[140:143], v[156:159], v[112:115]
	v_mfma_f32_16x16x32_bf16 v[108:111], v[132:135], v[164:167], v[108:111]
	v_mfma_f32_16x16x32_bf16 v[104:107], v[140:143], v[164:167], v[104:107]
	v_mfma_f32_16x16x32_bf16 v[100:103], v[132:135], v[172:175], v[100:103]
	v_mfma_f32_16x16x32_bf16 v[96:99], v[140:143], v[172:175], v[96:99]
	v_mfma_f32_16x16x32_bf16 v[124:127], v[136:139], v[152:155], v[124:127]
	v_mfma_f32_16x16x32_bf16 v[120:123], v[144:147], v[152:155], v[120:123]
	v_mfma_f32_16x16x32_bf16 v[116:119], v[136:139], v[160:163], v[116:119]
	v_mfma_f32_16x16x32_bf16 v[112:115], v[144:147], v[160:163], v[112:115]
	v_mfma_f32_16x16x32_bf16 v[108:111], v[136:139], v[168:171], v[108:111]
	v_mfma_f32_16x16x32_bf16 v[104:107], v[144:147], v[168:171], v[104:107]
	v_mfma_f32_16x16x32_bf16 v[100:103], v[136:139], v[176:179], v[100:103]
	s_barrier
	v_mfma_f32_16x16x32_bf16 v[96:99], v[144:147], v[176:179], v[96:99]
	s_setprio 0
	s_add_i32 s70, s56, s34
	v_add_u32_e32 v210, s57, v204
	v_lshl_add_u64 v[214:215], s[24:25], 0, v[180:181]
	s_mov_b32 m0, s70
	ds_read_b128 v[196:199], v210
	ds_read_b128 v[200:203], v210 offset:1024
	ds_read_b128 v[206:209], v210 offset:2048
	ds_read_b128 v[210:213], v210 offset:3072
	global_load_lds_dwordx4 v[214:215], off
	v_lshl_add_u64 v[216:217], s[24:25], 0, v[182:183]
	s_add_i32 m0, s70, 0x2000
	s_nop 0
	global_load_lds_dwordx4 v[216:217], off
	s_barrier
	s_waitcnt lgkmcnt(0)
	s_setprio 1
	s_waitcnt lgkmcnt(0)
	v_mfma_f32_16x16x32_bf16 v[92:95], v[196:199], v[148:151], v[92:95]
	v_mfma_f32_16x16x32_bf16 v[88:91], v[206:209], v[148:151], v[88:91]
	v_mfma_f32_16x16x32_bf16 v[84:87], v[196:199], v[156:159], v[84:87]
	v_mfma_f32_16x16x32_bf16 v[80:83], v[206:209], v[156:159], v[80:83]
	v_mfma_f32_16x16x32_bf16 v[76:79], v[196:199], v[164:167], v[76:79]
	v_mfma_f32_16x16x32_bf16 v[72:75], v[206:209], v[164:167], v[72:75]
	v_mfma_f32_16x16x32_bf16 v[68:71], v[196:199], v[172:175], v[68:71]
	v_mfma_f32_16x16x32_bf16 v[64:67], v[206:209], v[172:175], v[64:67]
	v_mfma_f32_16x16x32_bf16 v[92:95], v[200:203], v[152:155], v[92:95]
	v_mfma_f32_16x16x32_bf16 v[88:91], v[210:213], v[152:155], v[88:91]
	v_mfma_f32_16x16x32_bf16 v[84:87], v[200:203], v[160:163], v[84:87]
	v_mfma_f32_16x16x32_bf16 v[80:83], v[210:213], v[160:163], v[80:83]
	v_mfma_f32_16x16x32_bf16 v[76:79], v[200:203], v[168:171], v[76:79]
	v_mfma_f32_16x16x32_bf16 v[72:75], v[210:213], v[168:171], v[72:75]
	v_mfma_f32_16x16x32_bf16 v[68:71], v[200:203], v[176:179], v[68:71]
	s_barrier
	v_mfma_f32_16x16x32_bf16 v[64:67], v[210:213], v[176:179], v[64:67]
	s_setprio 0
	s_mov_b32 m0, s35
	v_lshl_add_u64 v[218:219], s[36:37], 0, v[180:181]
	ds_read_b128 v[148:151], v205 offset:16384
	ds_read_b128 v[152:155], v205 offset:17408
	ds_read_b128 v[156:159], v205 offset:18432
	ds_read_b128 v[160:163], v205 offset:19456
	ds_read_b128 v[164:167], v205 offset:20480
	ds_read_b128 v[168:171], v205 offset:21504
	ds_read_b128 v[172:175], v205 offset:22528
	ds_read_b128 v[176:179], v205 offset:23552
	global_load_lds_dwordx4 v[218:219], off
	v_lshl_add_u64 v[220:221], s[36:37], 0, v[182:183]
	s_mov_b32 m0, s38
	s_nop 0
	global_load_lds_dwordx4 v[220:221], off
	s_barrier
	s_waitcnt lgkmcnt(0)
	s_setprio 1
	s_waitcnt lgkmcnt(0)
	v_mfma_f32_16x16x32_bf16 v[60:63], v[132:135], v[148:151], v[60:63]
	v_mfma_f32_16x16x32_bf16 v[56:59], v[140:143], v[148:151], v[56:59]
	v_mfma_f32_16x16x32_bf16 v[52:55], v[132:135], v[156:159], v[52:55]
	v_mfma_f32_16x16x32_bf16 v[48:51], v[140:143], v[156:159], v[48:51]
	v_mfma_f32_16x16x32_bf16 v[44:47], v[132:135], v[164:167], v[44:47]
	v_mfma_f32_16x16x32_bf16 v[40:43], v[140:143], v[164:167], v[40:43]
	v_mfma_f32_16x16x32_bf16 v[36:39], v[132:135], v[172:175], v[36:39]
	v_mfma_f32_16x16x32_bf16 v[32:35], v[140:143], v[172:175], v[32:35]
	v_mfma_f32_16x16x32_bf16 v[60:63], v[136:139], v[152:155], v[60:63]
	v_mfma_f32_16x16x32_bf16 v[56:59], v[144:147], v[152:155], v[56:59]
	v_mfma_f32_16x16x32_bf16 v[52:55], v[136:139], v[160:163], v[52:55]
	v_mfma_f32_16x16x32_bf16 v[48:51], v[144:147], v[160:163], v[48:51]
	v_mfma_f32_16x16x32_bf16 v[44:47], v[136:139], v[168:171], v[44:47]
	v_mfma_f32_16x16x32_bf16 v[40:43], v[144:147], v[168:171], v[40:43]
	v_mfma_f32_16x16x32_bf16 v[36:39], v[136:139], v[176:179], v[36:39]
	s_barrier
; #define PG8_STAGE(bufoff, gbase, voff) do { _Pragma("unroll") for (int _i = 0; _i < 2; ++_i) \
;         __builtin_amdgcn_global_load_lds((const unsigned*)((const char*)(gbase) + (voff)[_i]), (LAS unsigned*)(lds + (bufoff) + ldsw + _i * 8192), 16, 0, 0); } while (0)
; #define PG8_LDA(dst, b, h) do { _Pragma("unroll") for (int m = 0; m < 4; ++m) _Pragma("unroll") for (int k = 0; k < 2; ++k) dst[m][k] = *(const LAS bf16x8*)(lds + PG8_SA(b, h) + aoff + m * 2048 + k * 1024); } while (0)
; #define PG8_LDB(dst, b, h) do { _Pragma("unroll") for (int n = 0; n < 2; ++n) _Pragma("unroll") for (int k = 0; k < 2; ++k) dst[n][k] = *(const LAS bf16x8*)(lds + PG8_SB(b, h) + boff + n * 2048 + k * 1024); } while (0)
; #define PG8_MMA(ai, bj, At, Bt) do { __builtin_amdgcn_s_setprio(1); _Pragma("unroll") for (int m = 0; m < 4; ++m) _Pragma("unroll") for (int n = 0; n < 2; ++n) _Pragma("unroll") for (int k = 0; k < 2; ++k) \
;         acc[ai][bj][m][n] = __builtin_amdgcn_mfma_f32_16x16x32_bf16(Bt[n][k], At[m][k], acc[ai][bj][m][n], 0, 0, 0); __builtin_amdgcn_s_setprio(0); } while (0)
; #define PG8_WAIT_V(n) asm volatile("s_waitcnt vmcnt(" #n ")" ::: "memory")
; #define PG8_WAIT_L(n) asm volatile("s_waitcnt lgkmcnt(" #n ")" ::: "memory")
; #define PG8_BAR __builtin_amdgcn_s_barrier()
; #define PG8_SCHED __builtin_amdgcn_sched_barrier(0)
; template <class Epi>
; __device__ __forceinline__ void gemm_phase(LAS unsigned char* lds, const Gemm g, const Sched& S, const Epi& E) {
;     ...
;             PG8_BAR; PG8_WAIT_L(0); PG8_MMA(1, 0, At, B0); PG8_BAR; PG8_SCHED;
;             PG8_STAGE(PG8_SB(0, 1), b2 + hstepB, voffB);
;             PG8_WAIT_V(6); PG8_BAR; PG8_MMA(1, 1, At, B1); PG8_BAR;
;             PG8_LDB(B0, 1, 0); PG8_SCHED; PG8_LDA(At, 1, 0); PG8_STAGE(PG8_SA(0, 1), a2 + hstepA, voffA);
;             PG8_WAIT_L(8); PG8_BAR; PG8_WAIT_L(0); PG8_MMA(0, 0, At, B0); PG8_BAR; PG8_SCHED;
;             PG8_LDB(B1, 1, 1); PG8_STAGE(PG8_SB(1, 0), b3, voffB);
;             PG8_BAR; PG8_WAIT_L(0); PG8_MMA(0, 1, At, B1); PG8_BAR;
;             PG8_LDA(At, 1, 1); PG8_STAGE(PG8_SA(1, 0), a3, voffA);
;             PG8_BAR; PG8_WAIT_L(0); PG8_MMA(1, 0, At, B0); PG8_BAR; PG8_SCHED;
	v_mfma_f32_16x16x32_bf16 v[32:35], v[144:147], v[176:179], v[32:35]
	s_setprio 0
	s_add_u32 s70, s24, 0x160000
	s_addc_u32 s71, s25, 0
	s_add_i32 s78, s57, s34
	v_lshl_add_u64 v[132:133], s[70:71], 0, v[180:181]
	s_mov_b32 m0, s78
	s_nop 0
	global_load_lds_dwordx4 v[132:133], off
	v_lshl_add_u64 v[132:133], s[70:71], 0, v[182:183]
	s_add_i32 m0, s78, 0x2000
	s_nop 0
	global_load_lds_dwordx4 v[132:133], off
	s_waitcnt vmcnt(6)
	s_barrier
	s_setprio 1
	v_mfma_f32_16x16x32_bf16 v[28:31], v[196:199], v[148:151], v[28:31]
	v_mfma_f32_16x16x32_bf16 v[24:27], v[206:209], v[148:151], v[24:27]
	v_mfma_f32_16x16x32_bf16 v[20:23], v[196:199], v[156:159], v[20:23]
	v_mfma_f32_16x16x32_bf16 v[16:19], v[206:209], v[156:159], v[16:19]
	v_mfma_f32_16x16x32_bf16 v[12:15], v[196:199], v[164:167], v[12:15]
	v_mfma_f32_16x16x32_bf16 v[8:11], v[206:209], v[164:167], v[8:11]
	v_mfma_f32_16x16x32_bf16 v[4:7], v[196:199], v[172:175], v[4:7]
	v_mfma_f32_16x16x32_bf16 v[0:3], v[206:209], v[172:175], v[0:3]
	v_mfma_f32_16x16x32_bf16 v[28:31], v[200:203], v[152:155], v[28:31]
	v_mfma_f32_16x16x32_bf16 v[24:27], v[210:213], v[152:155], v[24:27]
	v_mfma_f32_16x16x32_bf16 v[20:23], v[200:203], v[160:163], v[20:23]
	v_mfma_f32_16x16x32_bf16 v[16:19], v[210:213], v[160:163], v[16:19]
	v_mfma_f32_16x16x32_bf16 v[12:15], v[200:203], v[168:171], v[12:15]
	v_mfma_f32_16x16x32_bf16 v[8:11], v[210:213], v[168:171], v[8:11]
	v_mfma_f32_16x16x32_bf16 v[4:7], v[200:203], v[176:179], v[4:7]
	s_barrier
	v_mfma_f32_16x16x32_bf16 v[0:3], v[210:213], v[176:179], v[0:3]
	s_setprio 0
	s_add_i32 s70, 0, 0x18000
	v_add_u32_e32 v144, s70, v204
	ds_read_b128 v[132:135], v144
	ds_read_b128 v[136:139], v144 offset:1024
	ds_read_b128 v[140:143], v144 offset:2048
	ds_read_b128 v[144:147], v144 offset:3072
	s_add_u32 s36, s36, 0x160000
	s_addc_u32 s37, s37, 0
	s_mov_b32 m0, s39
	v_lshl_add_u64 v[196:197], s[36:37], 0, v[180:181]
	ds_read_b128 v[148:151], v205 offset:32768
	ds_read_b128 v[152:155], v205 offset:33792
	ds_read_b128 v[156:159], v205 offset:34816
	ds_read_b128 v[160:163], v205 offset:35840
	ds_read_b128 v[164:167], v205 offset:36864
	ds_read_b128 v[168:171], v205 offset:37888
	ds_read_b128 v[172:175], v205 offset:38912
	ds_read_b128 v[176:179], v205 offset:39936
	global_load_lds_dwordx4 v[196:197], off
	v_lshl_add_u64 v[196:197], s[36:37], 0, v[182:183]
	s_mov_b32 m0, s43
	s_nop 0
	global_load_lds_dwordx4 v[196:197], off
	s_waitcnt lgkmcnt(8)
	s_barrier
	s_waitcnt lgkmcnt(0)
	s_setprio 1
	s_waitcnt lgkmcnt(0)
	v_mfma_f32_16x16x32_bf16 v[124:127], v[132:135], v[148:151], v[124:127]
	v_mfma_f32_16x16x32_bf16 v[120:123], v[140:143], v[148:151], v[120:123]
	v_mfma_f32_16x16x32_bf16 v[116:119], v[132:135], v[156:159], v[116:119]
	v_mfma_f32_16x16x32_bf16 v[112:115], v[140:143], v[156:159], v[112:115]
	v_mfma_f32_16x16x32_bf16 v[108:111], v[132:135], v[164:167], v[108:111]
	v_mfma_f32_16x16x32_bf16 v[104:107], v[140:143], v[164:167], v[104:107]
	v_mfma_f32_16x16x32_bf16 v[100:103], v[132:135], v[172:175], v[100:103]
	v_mfma_f32_16x16x32_bf16 v[96:99], v[140:143], v[172:175], v[96:99]
	v_mfma_f32_16x16x32_bf16 v[124:127], v[136:139], v[152:155], v[124:127]
	v_mfma_f32_16x16x32_bf16 v[120:123], v[144:147], v[152:155], v[120:123]
	v_mfma_f32_16x16x32_bf16 v[116:119], v[136:139], v[160:163], v[116:119]
	v_mfma_f32_16x16x32_bf16 v[112:115], v[144:147], v[160:163], v[112:115]
	v_mfma_f32_16x16x32_bf16 v[108:111], v[136:139], v[168:171], v[108:111]
	v_mfma_f32_16x16x32_bf16 v[104:107], v[144:147], v[168:171], v[104:107]
	v_mfma_f32_16x16x32_bf16 v[100:103], v[136:139], v[176:179], v[100:103]
	s_barrier
	v_mfma_f32_16x16x32_bf16 v[96:99], v[144:147], v[176:179], v[96:99]
	s_setprio 0
	s_add_i32 s36, 0, 0x1c000
	s_add_i32 s37, s70, s34
	v_add_u32_e32 v210, s36, v204
	v_lshl_add_u64 v[214:215], v[214:215], 0, s[18:19]
	s_mov_b32 m0, s37
	ds_read_b128 v[196:199], v210
	ds_read_b128 v[200:203], v210 offset:1024
	ds_read_b128 v[206:209], v210 offset:2048
	ds_read_b128 v[210:213], v210 offset:3072
	global_load_lds_dwordx4 v[214:215], off
	v_lshl_add_u64 v[214:215], v[216:217], 0, s[18:19]
	s_add_i32 m0, s37, 0x2000
	s_nop 0
	global_load_lds_dwordx4 v[214:215], off
	s_barrier
	s_waitcnt lgkmcnt(0)
	s_setprio 1
	s_waitcnt lgkmcnt(0)
	v_mfma_f32_16x16x32_bf16 v[92:95], v[196:199], v[148:151], v[92:95]
	v_mfma_f32_16x16x32_bf16 v[88:91], v[206:209], v[148:151], v[88:91]
	v_mfma_f32_16x16x32_bf16 v[84:87], v[196:199], v[156:159], v[84:87]
	v_mfma_f32_16x16x32_bf16 v[80:83], v[206:209], v[156:159], v[80:83]
	v_mfma_f32_16x16x32_bf16 v[76:79], v[196:199], v[164:167], v[76:79]
	v_mfma_f32_16x16x32_bf16 v[72:75], v[206:209], v[164:167], v[72:75]
	v_mfma_f32_16x16x32_bf16 v[68:71], v[196:199], v[172:175], v[68:71]
	v_mfma_f32_16x16x32_bf16 v[64:67], v[206:209], v[172:175], v[64:67]
	v_mfma_f32_16x16x32_bf16 v[92:95], v[200:203], v[152:155], v[92:95]
	v_mfma_f32_16x16x32_bf16 v[88:91], v[210:213], v[152:155], v[88:91]
	v_mfma_f32_16x16x32_bf16 v[84:87], v[200:203], v[160:163], v[84:87]
	v_mfma_f32_16x16x32_bf16 v[80:83], v[210:213], v[160:163], v[80:83]
	v_mfma_f32_16x16x32_bf16 v[76:79], v[200:203], v[168:171], v[76:79]
	v_mfma_f32_16x16x32_bf16 v[72:75], v[210:213], v[168:171], v[72:75]
	v_mfma_f32_16x16x32_bf16 v[68:71], v[200:203], v[176:179], v[68:71]
	s_barrier
	v_mfma_f32_16x16x32_bf16 v[64:67], v[210:213], v[176:179], v[64:67]
	s_setprio 0
	s_mov_b32 m0, s54
	v_lshl_add_u64 v[214:215], v[218:219], 0, s[18:19]
	ds_read_b128 v[148:151], v205 offset:49152
	ds_read_b128 v[152:155], v205 offset:50176
	ds_read_b128 v[156:159], v205 offset:51200
	ds_read_b128 v[160:163], v205 offset:52224
	ds_read_b128 v[164:167], v205 offset:53248
	ds_read_b128 v[168:171], v205 offset:54272
	ds_read_b128 v[172:175], v205 offset:55296
	ds_read_b128 v[176:179], v205 offset:56320
	global_load_lds_dwordx4 v[214:215], off
	v_lshl_add_u64 v[214:215], v[220:221], 0, s[18:19]
	s_mov_b32 m0, s55
	s_nop 0
	global_load_lds_dwordx4 v[214:215], off
	s_barrier
; #define PG8_STAGE(bufoff, gbase, voff) do { _Pragma("unroll") for (int _i = 0; _i < 2; ++_i) \
;         __builtin_amdgcn_global_load_lds((const unsigned*)((const char*)(gbase) + (voff)[_i]), (LAS unsigned*)(lds + (bufoff) + ldsw + _i * 8192), 16, 0, 0); } while (0)
; #define PG8_MMA(ai, bj, At, Bt) do { __builtin_amdgcn_s_setprio(1); _Pragma("unroll") for (int m = 0; m < 4; ++m) _Pragma("unroll") for (int n = 0; n < 2; ++n) _Pragma("unroll") for (int k = 0; k < 2; ++k) \
;         acc[ai][bj][m][n] = __builtin_amdgcn_mfma_f32_16x16x32_bf16(Bt[n][k], At[m][k], acc[ai][bj][m][n], 0, 0, 0); __builtin_amdgcn_s_setprio(0); } while (0)
; #define PG8_WAIT_V(n) asm volatile("s_waitcnt vmcnt(" #n ")" ::: "memory")
; #define PG8_WAIT_L(n) asm volatile("s_waitcnt lgkmcnt(" #n ")" ::: "memory")
; #define PG8_BAR __builtin_amdgcn_s_barrier()
; #define PG8_SCHED __builtin_amdgcn_sched_barrier(0)
; #define RES_LOAD(dst_, k_) do { _Pragma("unroll") for (int mm = 0; mm < 2; ++mm) _Pragma("unroll") for (int bj = 0; bj < 2; ++bj) _Pragma("unroll") for (int n = 0; n < 2; ++n) \
;             dst_[mm][bj][n] = *(const f32x4*)(xin + RES_OFF(k_, mm, bj, n)); } while (0)
; #define RES_STORE(src_, k_) do { _Pragma("unroll") for (int mm = 0; mm < 2; ++mm) _Pragma("unroll") for (int bj = 0; bj < 2; ++bj) _Pragma("unroll") for (int n = 0; n < 2; ++n) \
;             *(f32x4*)(xout + RES_OFF(k_, mm, bj, n)) = src_[mm][bj][n] + al * acc[(k_) >> 1][bj][((k_) & 1) * 2 + mm][n]; } while (0)
; template <class Epi>
; __device__ __forceinline__ void gemm_phase(LAS unsigned char* lds, const Gemm g, const Sched& S, const Epi& E) {
;     ...
;             PG8_BAR; PG8_WAIT_L(0); PG8_MMA(1, 0, At, B0); PG8_BAR; PG8_SCHED;
;             PG8_STAGE(PG8_SB(1, 1), b3 + hstepB, voffB);
;             PG8_WAIT_V(6); PG8_BAR; PG8_MMA(1, 1, At, B1); PG8_BAR;
;     __device__ __forceinline__ void operator()(AccRef acc, const Unit& u, int wr, int wc, int fr, int fq) const {
;         const float al = alpha;
;         const size_t base = ((size_t)u.pm * 256 + wr * 64 + fr) * D_ + u.pn * 256 + wc * 32 + 4 * fq;
;         f32x4 xa[2][2][2], xb[2][2][2];
;     ...
;         RES_LOAD(xa, 0); RES_LOAD(xb, 1);
;         RES_STORE(xa, 0); RES_LOAD(xa, 2);
;         RES_STORE(xb, 1); RES_LOAD(xb, 3);
;         RES_STORE(xa, 2); RES_STORE(xb, 3);
	s_waitcnt lgkmcnt(0)
	s_setprio 1
	s_waitcnt lgkmcnt(0)
	v_mfma_f32_16x16x32_bf16 v[60:63], v[132:135], v[148:151], v[60:63]
	v_mfma_f32_16x16x32_bf16 v[56:59], v[140:143], v[148:151], v[56:59]
	v_mfma_f32_16x16x32_bf16 v[52:55], v[132:135], v[156:159], v[52:55]
	v_mfma_f32_16x16x32_bf16 v[48:51], v[140:143], v[156:159], v[48:51]
	v_mfma_f32_16x16x32_bf16 v[44:47], v[132:135], v[164:167], v[44:47]
	v_mfma_f32_16x16x32_bf16 v[40:43], v[140:143], v[164:167], v[40:43]
	v_mfma_f32_16x16x32_bf16 v[36:39], v[132:135], v[172:175], v[36:39]
	v_mfma_f32_16x16x32_bf16 v[32:35], v[140:143], v[172:175], v[32:35]
	v_mfma_f32_16x16x32_bf16 v[60:63], v[136:139], v[152:155], v[60:63]
	v_mfma_f32_16x16x32_bf16 v[56:59], v[144:147], v[152:155], v[56:59]
	v_mfma_f32_16x16x32_bf16 v[52:55], v[136:139], v[160:163], v[52:55]
	v_mfma_f32_16x16x32_bf16 v[48:51], v[144:147], v[160:163], v[48:51]
	v_mfma_f32_16x16x32_bf16 v[44:47], v[136:139], v[168:171], v[44:47]
	v_mfma_f32_16x16x32_bf16 v[40:43], v[144:147], v[168:171], v[40:43]
	v_mfma_f32_16x16x32_bf16 v[36:39], v[136:139], v[176:179], v[36:39]
	s_barrier
	v_mfma_f32_16x16x32_bf16 v[32:35], v[144:147], v[176:179], v[32:35]
	s_setprio 0
	s_add_u32 s24, s24, 0x160080
	s_addc_u32 s25, s25, 0
	s_add_i32 s36, s36, s34
	v_lshl_add_u64 v[132:133], s[24:25], 0, v[180:181]
	s_mov_b32 m0, s36
	s_nop 0
	global_load_lds_dwordx4 v[132:133], off
	v_lshl_add_u64 v[132:133], s[24:25], 0, v[182:183]
	s_add_i32 m0, s36, 0x2000
	s_nop 0
	global_load_lds_dwordx4 v[132:133], off
	s_waitcnt vmcnt(6)
	s_barrier
	s_setprio 1
	v_mfma_f32_16x16x32_bf16 v[28:31], v[196:199], v[148:151], v[28:31]
	v_mfma_f32_16x16x32_bf16 v[24:27], v[206:209], v[148:151], v[24:27]
	v_mfma_f32_16x16x32_bf16 v[20:23], v[196:199], v[156:159], v[20:23]
	v_mfma_f32_16x16x32_bf16 v[16:19], v[206:209], v[156:159], v[16:19]
	v_mfma_f32_16x16x32_bf16 v[12:15], v[196:199], v[164:167], v[12:15]
	v_mfma_f32_16x16x32_bf16 v[8:11], v[206:209], v[164:167], v[8:11]
	v_mfma_f32_16x16x32_bf16 v[4:7], v[196:199], v[172:175], v[4:7]
	v_mfma_f32_16x16x32_bf16 v[0:3], v[206:209], v[172:175], v[0:3]
	v_mfma_f32_16x16x32_bf16 v[28:31], v[200:203], v[152:155], v[28:31]
	v_mfma_f32_16x16x32_bf16 v[24:27], v[210:213], v[152:155], v[24:27]
	v_mfma_f32_16x16x32_bf16 v[20:23], v[200:203], v[160:163], v[20:23]
	v_mfma_f32_16x16x32_bf16 v[16:19], v[210:213], v[160:163], v[16:19]
	v_mfma_f32_16x16x32_bf16 v[12:15], v[200:203], v[168:171], v[12:15]
	v_mfma_f32_16x16x32_bf16 v[8:11], v[210:213], v[168:171], v[8:11]
	v_mfma_f32_16x16x32_bf16 v[4:7], v[200:203], v[176:179], v[4:7]
	s_barrier
	v_mfma_f32_16x16x32_bf16 v[0:3], v[210:213], v[176:179], v[0:3]
	s_setprio 0
	s_add_i32 s67, s67, 2
	s_add_u32 s22, s22, 0x100
	s_addc_u32 s23, s23, 0
	s_cmpk_gt_u32 s67, 0x55
	s_cbranch_scc0 .LBB0_2166
	s_add_u32 s22, s15, 0xffffff00
	s_addc_u32 s23, s51, -1
	s_lshl_b32 s24, s53, 8
	s_ashr_i32 s15, s14, 31
	s_ashr_i32 s25, s24, 31
	v_lshl_add_u64 v[128:129], s[24:25], 2, v[184:185]
	s_lshl_b64 s[24:25], s[14:15], 21
	v_lshl_add_u64 v[176:177], v[128:129], 0, s[24:25]
	global_load_dwordx4 v[128:131], v[176:177], off
	global_load_dwordx4 v[132:135], v[176:177], off offset:64
	global_load_dwordx4 v[136:139], v[176:177], off offset:512
	global_load_dwordx4 v[140:143], v[176:177], off offset:576
	v_add_co_u32_e32 v178, vcc, s58, v176
	s_waitcnt vmcnt(0)
	v_pk_fma_f32 v[130:131], v[126:127], 0.5, v[130:131] op_sel_hi:[1,0,1]
	v_addc_co_u32_e32 v179, vcc, 0, v177, vcc
	global_load_dwordx4 v[144:147], v[178:179], off
	global_load_dwordx4 v[148:151], v[178:179], off offset:64
	global_load_dwordx4 v[152:155], v[178:179], off offset:512
	global_load_dwordx4 v[156:159], v[178:179], off offset:576
	v_add_co_u32_e32 v218, vcc, s59, v176
	v_pk_fma_f32 v[128:129], v[124:125], 0.5, v[128:129] op_sel_hi:[1,0,1]
	s_nop 0
	v_addc_co_u32_e32 v219, vcc, 0, v177, vcc
	global_load_dwordx4 v[160:163], v[218:219], off
	global_load_dwordx4 v[164:167], v[218:219], off offset:64
	global_load_dwordx4 v[168:171], v[218:219], off offset:512
	global_load_dwordx4 v[172:175], v[218:219], off offset:576
	v_add_co_u32_e32 v220, vcc, s60, v176
	s_waitcnt vmcnt(0)
	v_pk_fma_f32 v[162:163], v[110:111], 0.5, v[162:163] op_sel_hi:[1,0,1]
	v_addc_co_u32_e32 v221, vcc, 0, v177, vcc
	global_load_dwordx4 v[200:203], v[220:221], off
	global_load_dwordx4 v[206:209], v[220:221], off offset:64
	global_load_dwordx4 v[210:213], v[220:221], off offset:512
	global_load_dwordx4 v[214:217], v[220:221], off offset:576
	v_add_co_u32_e32 v198, vcc, s61, v176
	global_store_dwordx4 v[176:177], v[128:131], off
	s_nop 0
	v_addc_co_u32_e32 v199, vcc, 0, v177, vcc
	v_pk_fma_f32 v[130:131], v[122:123], 0.5, v[134:135] op_sel_hi:[1,0,1]
	v_pk_fma_f32 v[128:129], v[120:121], 0.5, v[132:133] op_sel_hi:[1,0,1]
	global_store_dwordx4 v[176:177], v[128:131], off offset:64
	v_add_co_u32_e32 v196, vcc, s62, v176
	s_nop 0
	v_pk_fma_f32 v[130:131], v[94:95], 0.5, v[138:139] op_sel_hi:[1,0,1]
	v_pk_fma_f32 v[128:129], v[92:93], 0.5, v[136:137] op_sel_hi:[1,0,1]
	global_store_dwordx4 v[176:177], v[128:131], off offset:512
	v_addc_co_u32_e32 v197, vcc, 0, v177, vcc
	s_nop 0
	v_pk_fma_f32 v[130:131], v[90:91], 0.5, v[142:143] op_sel_hi:[1,0,1]
	v_pk_fma_f32 v[128:129], v[88:89], 0.5, v[140:141] op_sel_hi:[1,0,1]
	global_store_dwordx4 v[176:177], v[128:131], off offset:576
	v_pk_fma_f32 v[160:161], v[108:109], 0.5, v[160:161] op_sel_hi:[1,0,1]
	s_nop 0
	v_pk_fma_f32 v[130:131], v[118:119], 0.5, v[146:147] op_sel_hi:[1,0,1]
	v_pk_fma_f32 v[128:129], v[116:117], 0.5, v[144:145] op_sel_hi:[1,0,1]
	global_store_dwordx4 v[178:179], v[128:131], off
	s_nop 1
	v_pk_fma_f32 v[130:131], v[114:115], 0.5, v[150:151] op_sel_hi:[1,0,1]
	v_pk_fma_f32 v[128:129], v[112:113], 0.5, v[148:149] op_sel_hi:[1,0,1]
	global_store_dwordx4 v[178:179], v[128:131], off offset:64
	s_nop 1
	v_pk_fma_f32 v[130:131], v[86:87], 0.5, v[154:155] op_sel_hi:[1,0,1]
	v_pk_fma_f32 v[128:129], v[84:85], 0.5, v[152:153] op_sel_hi:[1,0,1]
	global_store_dwordx4 v[178:179], v[128:131], off offset:512
	s_nop 1
	v_pk_fma_f32 v[130:131], v[82:83], 0.5, v[158:159] op_sel_hi:[1,0,1]
	v_pk_fma_f32 v[128:129], v[80:81], 0.5, v[156:157] op_sel_hi:[1,0,1]
	global_store_dwordx4 v[178:179], v[128:131], off offset:576
	global_load_dwordx4 v[156:159], v[198:199], off
	global_load_dwordx4 v[152:155], v[198:199], off offset:64
	global_load_dwordx4 v[144:147], v[198:199], off offset:512
	global_load_dwordx4 v[136:139], v[198:199], off offset:576
	global_load_dwordx4 v[148:151], v[196:197], off
	global_load_dwordx4 v[140:143], v[196:197], off offset:64
	global_load_dwordx4 v[132:135], v[196:197], off offset:512
	global_load_dwordx4 v[128:131], v[196:197], off offset:576
	s_waitcnt vmcnt(0)
; #define RES_LOAD(dst_, k_) do { _Pragma("unroll") for (int mm = 0; mm < 2; ++mm) _Pragma("unroll") for (int bj = 0; bj < 2; ++bj) _Pragma("unroll") for (int n = 0; n < 2; ++n) \
;             dst_[mm][bj][n] = *(const f32x4*)(xin + RES_OFF(k_, mm, bj, n)); } while (0)
; #define RES_STORE(src_, k_) do { _Pragma("unroll") for (int mm = 0; mm < 2; ++mm) _Pragma("unroll") for (int bj = 0; bj < 2; ++bj) _Pragma("unroll") for (int n = 0; n < 2; ++n) \
;             *(f32x4*)(xout + RES_OFF(k_, mm, bj, n)) = src_[mm][bj][n] + al * acc[(k_) >> 1][bj][((k_) & 1) * 2 + mm][n]; } while (0)
;     __device__ __forceinline__ void operator()(AccRef acc, const Unit& u, int wr, int wc, int fr, int fq) const {
;     ...
;         RES_LOAD(xa, 0); RES_LOAD(xb, 1);
;         RES_STORE(xa, 0); RES_LOAD(xa, 2);
;         RES_STORE(xb, 1); RES_LOAD(xb, 3);
;         RES_STORE(xa, 2); RES_STORE(xb, 3);
	v_pk_fma_f32 v[158:159], v[62:63], 0.5, v[158:159] op_sel_hi:[1,0,1]
	global_store_dwordx4 v[218:219], v[160:163], off
	v_pk_fma_f32 v[156:157], v[60:61], 0.5, v[156:157] op_sel_hi:[1,0,1]
	v_pk_fma_f32 v[138:139], v[26:27], 0.5, v[138:139] op_sel_hi:[1,0,1]
	v_pk_fma_f32 v[162:163], v[106:107], 0.5, v[166:167] op_sel_hi:[1,0,1]
	v_pk_fma_f32 v[160:161], v[104:105], 0.5, v[164:165] op_sel_hi:[1,0,1]
	global_store_dwordx4 v[218:219], v[160:163], off offset:64
	v_pk_fma_f32 v[130:131], v[18:19], 0.5, v[130:131] op_sel_hi:[1,0,1]
	v_pk_fma_f32 v[128:129], v[16:17], 0.5, v[128:129] op_sel_hi:[1,0,1]
	v_pk_fma_f32 v[162:163], v[78:79], 0.5, v[170:171] op_sel_hi:[1,0,1]
	v_pk_fma_f32 v[160:161], v[76:77], 0.5, v[168:169] op_sel_hi:[1,0,1]
	global_store_dwordx4 v[218:219], v[160:163], off offset:512
	v_pk_fma_f32 v[136:137], v[24:25], 0.5, v[136:137] op_sel_hi:[1,0,1]
	v_pk_fma_f32 v[154:155], v[58:59], 0.5, v[154:155] op_sel_hi:[1,0,1]
	v_pk_fma_f32 v[162:163], v[74:75], 0.5, v[174:175] op_sel_hi:[1,0,1]
	v_pk_fma_f32 v[160:161], v[72:73], 0.5, v[172:173] op_sel_hi:[1,0,1]
	global_store_dwordx4 v[218:219], v[160:163], off offset:576
	v_pk_fma_f32 v[152:153], v[56:57], 0.5, v[152:153] op_sel_hi:[1,0,1]
	v_pk_fma_f32 v[146:147], v[30:31], 0.5, v[146:147] op_sel_hi:[1,0,1]
	v_pk_fma_f32 v[162:163], v[102:103], 0.5, v[202:203] op_sel_hi:[1,0,1]
	v_pk_fma_f32 v[160:161], v[100:101], 0.5, v[200:201] op_sel_hi:[1,0,1]
	global_store_dwordx4 v[220:221], v[160:163], off
	v_add_co_u32_e32 v200, vcc, s63, v176
	s_nop 0
	v_pk_fma_f32 v[162:163], v[98:99], 0.5, v[208:209] op_sel_hi:[1,0,1]
	v_pk_fma_f32 v[160:161], v[96:97], 0.5, v[206:207] op_sel_hi:[1,0,1]
	global_store_dwordx4 v[220:221], v[160:163], off offset:64
	v_addc_co_u32_e32 v201, vcc, 0, v177, vcc
	s_nop 0
	v_pk_fma_f32 v[162:163], v[70:71], 0.5, v[212:213] op_sel_hi:[1,0,1]
	v_pk_fma_f32 v[160:161], v[68:69], 0.5, v[210:211] op_sel_hi:[1,0,1]
	global_store_dwordx4 v[220:221], v[160:163], off offset:512
	v_add_co_u32_e32 v202, vcc, s64, v176
	s_nop 0
	v_pk_fma_f32 v[162:163], v[66:67], 0.5, v[216:217] op_sel_hi:[1,0,1]
	v_pk_fma_f32 v[160:161], v[64:65], 0.5, v[214:215] op_sel_hi:[1,0,1]
	global_store_dwordx4 v[220:221], v[160:163], off offset:576
	global_load_dwordx4 v[172:175], v[200:201], off
	global_load_dwordx4 v[168:171], v[200:201], off offset:64
	global_load_dwordx4 v[164:167], v[200:201], off offset:512
	s_nop 0
	global_load_dwordx4 v[160:163], v[200:201], off offset:576
	v_addc_co_u32_e32 v203, vcc, 0, v177, vcc
	global_load_dwordx4 v[206:209], v[202:203], off
	global_load_dwordx4 v[210:213], v[202:203], off offset:64
	global_load_dwordx4 v[214:217], v[202:203], off offset:512
	global_load_dwordx4 v[176:179], v[202:203], off offset:576
	v_pk_fma_f32 v[144:145], v[28:29], 0.5, v[144:145] op_sel_hi:[1,0,1]
	global_store_dwordx4 v[196:197], v[128:131], off offset:576
	global_store_dwordx4 v[198:199], v[136:139], off offset:576
	v_pk_fma_f32 v[134:135], v[22:23], 0.5, v[134:135] op_sel_hi:[1,0,1]
	v_pk_fma_f32 v[132:133], v[20:21], 0.5, v[132:133] op_sel_hi:[1,0,1]
	v_pk_fma_f32 v[138:139], v[54:55], 0.5, v[150:151] op_sel_hi:[1,0,1]
	v_pk_fma_f32 v[136:137], v[52:53], 0.5, v[148:149] op_sel_hi:[1,0,1]
	global_store_dwordx4 v[196:197], v[136:139], off
	s_and_b64 vcc, exec, s[10:11]
	global_store_dwordx4 v[198:199], v[156:159], off
	v_pk_fma_f32 v[138:139], v[50:51], 0.5, v[142:143] op_sel_hi:[1,0,1]
	v_pk_fma_f32 v[136:137], v[48:49], 0.5, v[140:141] op_sel_hi:[1,0,1]
	global_store_dwordx4 v[198:199], v[152:155], off offset:64
	global_store_dwordx4 v[198:199], v[144:147], off offset:512
	global_store_dwordx4 v[196:197], v[136:139], off offset:64
	global_store_dwordx4 v[196:197], v[132:135], off offset:512
	s_waitcnt vmcnt(0)
	v_pk_fma_f32 v[130:131], v[46:47], 0.5, v[174:175] op_sel_hi:[1,0,1]
	v_pk_fma_f32 v[128:129], v[44:45], 0.5, v[172:173] op_sel_hi:[1,0,1]
	global_store_dwordx4 v[200:201], v[128:131], off
	s_nop 1
	v_pk_fma_f32 v[130:131], v[42:43], 0.5, v[170:171] op_sel_hi:[1,0,1]
	v_pk_fma_f32 v[128:129], v[40:41], 0.5, v[168:169] op_sel_hi:[1,0,1]
	global_store_dwordx4 v[200:201], v[128:131], off offset:64
	s_nop 1
	v_pk_fma_f32 v[130:131], v[14:15], 0.5, v[166:167] op_sel_hi:[1,0,1]
	v_pk_fma_f32 v[128:129], v[12:13], 0.5, v[164:165] op_sel_hi:[1,0,1]
	global_store_dwordx4 v[200:201], v[128:131], off offset:512
	s_nop 1
	v_pk_fma_f32 v[130:131], v[10:11], 0.5, v[162:163] op_sel_hi:[1,0,1]
	v_pk_fma_f32 v[128:129], v[8:9], 0.5, v[160:161] op_sel_hi:[1,0,1]
	global_store_dwordx4 v[200:201], v[128:131], off offset:576
	s_nop 1
	v_pk_fma_f32 v[130:131], v[38:39], 0.5, v[208:209] op_sel_hi:[1,0,1]
	v_pk_fma_f32 v[128:129], v[36:37], 0.5, v[206:207] op_sel_hi:[1,0,1]
	global_store_dwordx4 v[202:203], v[128:131], off
	s_nop 1
	v_pk_fma_f32 v[130:131], v[34:35], 0.5, v[212:213] op_sel_hi:[1,0,1]
	v_pk_fma_f32 v[128:129], v[32:33], 0.5, v[210:211] op_sel_hi:[1,0,1]
	global_store_dwordx4 v[202:203], v[128:131], off offset:64
	s_nop 1
	v_pk_fma_f32 v[130:131], v[6:7], 0.5, v[216:217] op_sel_hi:[1,0,1]
	v_pk_fma_f32 v[128:129], v[4:5], 0.5, v[214:215] op_sel_hi:[1,0,1]
	global_store_dwordx4 v[202:203], v[128:131], off offset:512
	s_nop 1
	v_pk_fma_f32 v[130:131], v[2:3], 0.5, v[178:179] op_sel_hi:[1,0,1]
	v_pk_fma_f32 v[128:129], v[0:1], 0.5, v[176:177] op_sel_hi:[1,0,1]
	global_store_dwordx4 v[202:203], v[128:131], off offset:576
	s_cbranch_vccz .LBB0_2154
	s_mov_b64 s[12:13], s[22:23]
	s_andn2_b64 vcc, exec, s[8:9]
	s_mov_b64 s[22:23], s[12:13]
	s_cbranch_vccnz .LBB0_2155

; #define PG8_STAGE(bufoff, gbase, voff) do { _Pragma("unroll") for (int _i = 0; _i < 2; ++_i) \
;         __builtin_amdgcn_global_load_lds((const unsigned*)((const char*)(gbase) + (voff)[_i]), (LAS unsigned*)(lds + (bufoff) + ldsw + _i * 8192), 16, 0, 0); } while (0)
; #define PG8_LDA(dst, b, h) do { _Pragma("unroll") for (int m = 0; m < 4; ++m) _Pragma("unroll") for (int k = 0; k < 2; ++k) dst[m][k] = *(const LAS bf16x8*)(lds + PG8_SA(b, h) + aoff + m * 2048 + k * 1024); } while (0)
; #define PG8_LDB(dst, b, h) do { _Pragma("unroll") for (int n = 0; n < 2; ++n) _Pragma("unroll") for (int k = 0; k < 2; ++k) dst[n][k] = *(const LAS bf16x8*)(lds + PG8_SB(b, h) + boff + n * 2048 + k * 1024); } while (0)
; #define PG8_MMA(ai, bj, At, Bt) do { __builtin_amdgcn_s_setprio(1); _Pragma("unroll") for (int m = 0; m < 4; ++m) _Pragma("unroll") for (int n = 0; n < 2; ++n) _Pragma("unroll") for (int k = 0; k < 2; ++k) \
;         acc[ai][bj][m][n] = __builtin_amdgcn_mfma_f32_16x16x32_bf16(Bt[n][k], At[m][k], acc[ai][bj][m][n], 0, 0, 0); __builtin_amdgcn_s_setprio(0); } while (0)
; #define PG8_WAIT_V(n) asm volatile("s_waitcnt vmcnt(" #n ")" ::: "memory")
; #define PG8_WAIT_L(n) asm volatile("s_waitcnt lgkmcnt(" #n ")" ::: "memory")
; #define PG8_BAR __builtin_amdgcn_s_barrier()
; #define PG8_SCHED __builtin_amdgcn_sched_barrier(0)
; template <class Epi>
; __device__ __forceinline__ void gemm_phase(LAS unsigned char* lds, const Gemm g, const Sched& S, const Epi& E) {
;     ...
;             PG8_LDB(B0, 0, 0); PG8_SCHED; PG8_LDA(At, 0, 0); PG8_STAGE(PG8_SA(1, 1), a1 + hstepA, voffA);
;             PG8_WAIT_L(8); PG8_BAR; PG8_WAIT_L(0); PG8_MMA(0, 0, At, B0); PG8_BAR; PG8_SCHED;
;             PG8_LDB(B1, 0, 1); PG8_STAGE(PG8_SB(0, 0), b2, voffB);
;             PG8_BAR; PG8_WAIT_L(0); PG8_MMA(0, 1, At, B1); PG8_BAR;
;             PG8_LDA(At, 0, 1); PG8_STAGE(PG8_SA(0, 0), a2, voffA);
;             PG8_BAR; PG8_WAIT_L(0); PG8_MMA(1, 0, At, B0); PG8_BAR; PG8_SCHED;
;             PG8_STAGE(PG8_SB(0, 1), b2 + hstepB, voffB);
;             PG8_WAIT_V(6); PG8_BAR; PG8_MMA(1, 1, At, B1); PG8_BAR;
.LBB0_2488:
	v_add_u32_e32 v146, s60, v148
	s_add_u32 s14, s22, s12
	ds_read_b128 v[152:155], v146
	ds_read_b128 v[156:159], v146 offset:1024
	ds_read_b128 v[160:163], v146 offset:2048
	ds_read_b128 v[164:167], v146 offset:3072
	s_addc_u32 s15, s23, s13
	s_add_u32 s14, s14, 0x100
	s_addc_u32 s15, s15, 0
	s_add_u32 s81, s51, s12
	s_addc_u32 s82, s70, s13
	s_cmpk_eq_i32 s12, 0xf00
	s_cselect_b32 s17, s21, s15
	s_cselect_b32 s16, s65, s14
	s_cselect_b32 s15, s59, s82
	s_cselect_b32 s14, s71, s81
	v_lshl_add_u64 v[146:147], v[142:143], 0, s[12:13]
	s_add_i32 m0, s19, 0xc000
	ds_read_b128 v[168:171], v150
	ds_read_b128 v[172:175], v150 offset:1024
	ds_read_b128 v[176:179], v150 offset:2048
	ds_read_b128 v[180:183], v150 offset:3072
	ds_read_b128 v[184:187], v150 offset:4096
	ds_read_b128 v[188:191], v150 offset:5120
	ds_read_b128 v[194:197], v150 offset:6144
	ds_read_b128 v[198:201], v150 offset:7168
	global_load_lds_dwordx4 v[146:147], off
	v_lshl_add_u64 v[146:147], v[144:145], 0, s[12:13]
	s_add_i32 m0, s19, 0xe000
	s_nop 0
	global_load_lds_dwordx4 v[146:147], off
	s_waitcnt lgkmcnt(8)
	s_barrier
	s_waitcnt lgkmcnt(0)
	s_setprio 1
	s_waitcnt lgkmcnt(0)
	v_mfma_f32_16x16x32_bf16 v[124:127], v[152:155], v[168:171], v[124:127]
	v_mfma_f32_16x16x32_bf16 v[120:123], v[160:163], v[168:171], v[120:123]
	v_mfma_f32_16x16x32_bf16 v[116:119], v[152:155], v[176:179], v[116:119]
	v_mfma_f32_16x16x32_bf16 v[112:115], v[160:163], v[176:179], v[112:115]
	v_mfma_f32_16x16x32_bf16 v[108:111], v[152:155], v[184:187], v[108:111]
	v_mfma_f32_16x16x32_bf16 v[104:107], v[160:163], v[184:187], v[104:107]
	v_mfma_f32_16x16x32_bf16 v[100:103], v[152:155], v[194:197], v[100:103]
	v_mfma_f32_16x16x32_bf16 v[96:99], v[160:163], v[194:197], v[96:99]
	v_mfma_f32_16x16x32_bf16 v[124:127], v[156:159], v[172:175], v[124:127]
	v_mfma_f32_16x16x32_bf16 v[120:123], v[164:167], v[172:175], v[120:123]
	v_mfma_f32_16x16x32_bf16 v[116:119], v[156:159], v[180:183], v[116:119]
	v_mfma_f32_16x16x32_bf16 v[112:115], v[164:167], v[180:183], v[112:115]
	v_mfma_f32_16x16x32_bf16 v[108:111], v[156:159], v[188:191], v[108:111]
	v_mfma_f32_16x16x32_bf16 v[104:107], v[164:167], v[188:191], v[104:107]
	v_mfma_f32_16x16x32_bf16 v[100:103], v[156:159], v[198:201], v[100:103]
	s_barrier
	v_mfma_f32_16x16x32_bf16 v[96:99], v[164:167], v[198:201], v[96:99]
	s_setprio 0
	v_add_u32_e32 v146, s61, v148
	s_add_i32 s81, s60, s1
	ds_read_b128 v[202:205], v146
	ds_read_b128 v[206:209], v146 offset:1024
	ds_read_b128 v[210:213], v146 offset:2048
	ds_read_b128 v[214:217], v146 offset:3072
	v_lshl_add_u64 v[146:147], s[14:15], 0, v[128:129]
	s_mov_b32 m0, s81
	v_lshl_add_u64 v[218:219], s[14:15], 0, v[130:131]
	global_load_lds_dwordx4 v[146:147], off
	s_add_i32 m0, s81, 0x2000
	s_nop 0
	global_load_lds_dwordx4 v[218:219], off
	s_barrier
	s_waitcnt lgkmcnt(0)
	s_setprio 1
	s_waitcnt lgkmcnt(0)
	v_mfma_f32_16x16x32_bf16 v[92:95], v[202:205], v[168:171], v[92:95]
	v_mfma_f32_16x16x32_bf16 v[88:91], v[210:213], v[168:171], v[88:91]
	v_mfma_f32_16x16x32_bf16 v[84:87], v[202:205], v[176:179], v[84:87]
	v_mfma_f32_16x16x32_bf16 v[80:83], v[210:213], v[176:179], v[80:83]
	v_mfma_f32_16x16x32_bf16 v[76:79], v[202:205], v[184:187], v[76:79]
	v_mfma_f32_16x16x32_bf16 v[72:75], v[210:213], v[184:187], v[72:75]
	v_mfma_f32_16x16x32_bf16 v[68:71], v[202:205], v[194:197], v[68:71]
	v_mfma_f32_16x16x32_bf16 v[64:67], v[210:213], v[194:197], v[64:67]
	v_mfma_f32_16x16x32_bf16 v[92:95], v[206:209], v[172:175], v[92:95]
	v_mfma_f32_16x16x32_bf16 v[88:91], v[214:217], v[172:175], v[88:91]
	v_mfma_f32_16x16x32_bf16 v[84:87], v[206:209], v[180:183], v[84:87]
	v_mfma_f32_16x16x32_bf16 v[80:83], v[214:217], v[180:183], v[80:83]
	v_mfma_f32_16x16x32_bf16 v[76:79], v[206:209], v[188:191], v[76:79]
	v_mfma_f32_16x16x32_bf16 v[72:75], v[214:217], v[188:191], v[72:75]
	v_mfma_f32_16x16x32_bf16 v[68:71], v[206:209], v[198:201], v[68:71]
	s_barrier
	v_mfma_f32_16x16x32_bf16 v[64:67], v[214:217], v[198:201], v[64:67]
	s_setprio 0
	s_mov_b32 m0, s19
	v_lshl_add_u64 v[220:221], s[16:17], 0, v[128:129]
	ds_read_b128 v[168:171], v150 offset:16384
	ds_read_b128 v[172:175], v150 offset:17408
	ds_read_b128 v[176:179], v150 offset:18432
	ds_read_b128 v[180:183], v150 offset:19456
	ds_read_b128 v[184:187], v150 offset:20480
	ds_read_b128 v[188:191], v150 offset:21504
	ds_read_b128 v[194:197], v150 offset:22528
	ds_read_b128 v[198:201], v150 offset:23552
	global_load_lds_dwordx4 v[220:221], off
	v_lshl_add_u64 v[222:223], s[16:17], 0, v[130:131]
	s_mov_b32 m0, s33
	s_nop 0
	global_load_lds_dwordx4 v[222:223], off
	s_barrier
	s_waitcnt lgkmcnt(0)
	s_setprio 1
	s_waitcnt lgkmcnt(0)
	v_mfma_f32_16x16x32_bf16 v[60:63], v[152:155], v[168:171], v[60:63]
	v_mfma_f32_16x16x32_bf16 v[56:59], v[160:163], v[168:171], v[56:59]
	v_mfma_f32_16x16x32_bf16 v[52:55], v[152:155], v[176:179], v[52:55]
	v_mfma_f32_16x16x32_bf16 v[48:51], v[160:163], v[176:179], v[48:51]
	v_mfma_f32_16x16x32_bf16 v[44:47], v[152:155], v[184:187], v[44:47]
	v_mfma_f32_16x16x32_bf16 v[40:43], v[160:163], v[184:187], v[40:43]
	v_mfma_f32_16x16x32_bf16 v[36:39], v[152:155], v[194:197], v[36:39]
	v_mfma_f32_16x16x32_bf16 v[32:35], v[160:163], v[194:197], v[32:35]
	v_mfma_f32_16x16x32_bf16 v[60:63], v[156:159], v[172:175], v[60:63]
	v_mfma_f32_16x16x32_bf16 v[56:59], v[164:167], v[172:175], v[56:59]
	v_mfma_f32_16x16x32_bf16 v[52:55], v[156:159], v[180:183], v[52:55]
	v_mfma_f32_16x16x32_bf16 v[48:51], v[164:167], v[180:183], v[48:51]
	v_mfma_f32_16x16x32_bf16 v[44:47], v[156:159], v[188:191], v[44:47]
	v_mfma_f32_16x16x32_bf16 v[40:43], v[164:167], v[188:191], v[40:43]
	v_mfma_f32_16x16x32_bf16 v[36:39], v[156:159], v[198:201], v[36:39]
	s_barrier
; #define PG8_STAGE(bufoff, gbase, voff) do { _Pragma("unroll") for (int _i = 0; _i < 2; ++_i) \
;         __builtin_amdgcn_global_load_lds((const unsigned*)((const char*)(gbase) + (voff)[_i]), (LAS unsigned*)(lds + (bufoff) + ldsw + _i * 8192), 16, 0, 0); } while (0)
; #define PG8_LDA(dst, b, h) do { _Pragma("unroll") for (int m = 0; m < 4; ++m) _Pragma("unroll") for (int k = 0; k < 2; ++k) dst[m][k] = *(const LAS bf16x8*)(lds + PG8_SA(b, h) + aoff + m * 2048 + k * 1024); } while (0)
; #define PG8_LDB(dst, b, h) do { _Pragma("unroll") for (int n = 0; n < 2; ++n) _Pragma("unroll") for (int k = 0; k < 2; ++k) dst[n][k] = *(const LAS bf16x8*)(lds + PG8_SB(b, h) + boff + n * 2048 + k * 1024); } while (0)
; #define PG8_MMA(ai, bj, At, Bt) do { __builtin_amdgcn_s_setprio(1); _Pragma("unroll") for (int m = 0; m < 4; ++m) _Pragma("unroll") for (int n = 0; n < 2; ++n) _Pragma("unroll") for (int k = 0; k < 2; ++k) \
;         acc[ai][bj][m][n] = __builtin_amdgcn_mfma_f32_16x16x32_bf16(Bt[n][k], At[m][k], acc[ai][bj][m][n], 0, 0, 0); __builtin_amdgcn_s_setprio(0); } while (0)
; #define PG8_WAIT_V(n) asm volatile("s_waitcnt vmcnt(" #n ")" ::: "memory")
; #define PG8_WAIT_L(n) asm volatile("s_waitcnt lgkmcnt(" #n ")" ::: "memory")
; #define PG8_BAR __builtin_amdgcn_s_barrier()
; #define PG8_SCHED __builtin_amdgcn_sched_barrier(0)
; template <class Epi>
; __device__ __forceinline__ void gemm_phase(LAS unsigned char* lds, const Gemm g, const Sched& S, const Epi& E) {
;     ...
;             PG8_BAR; PG8_WAIT_L(0); PG8_MMA(1, 0, At, B0); PG8_BAR; PG8_SCHED;
;             PG8_STAGE(PG8_SB(0, 1), b2 + hstepB, voffB);
;             PG8_WAIT_V(6); PG8_BAR; PG8_MMA(1, 1, At, B1); PG8_BAR;
;             PG8_LDB(B0, 1, 0); PG8_SCHED; PG8_LDA(At, 1, 0); PG8_STAGE(PG8_SA(0, 1), a2 + hstepA, voffA);
;             PG8_WAIT_L(8); PG8_BAR; PG8_WAIT_L(0); PG8_MMA(0, 0, At, B0); PG8_BAR; PG8_SCHED;
;             PG8_LDB(B1, 1, 1); PG8_STAGE(PG8_SB(1, 0), b3, voffB);
;             PG8_BAR; PG8_WAIT_L(0); PG8_MMA(0, 1, At, B1); PG8_BAR;
	v_mfma_f32_16x16x32_bf16 v[32:35], v[164:167], v[198:201], v[32:35]
	s_setprio 0
	s_add_u32 s82, s14, 0x80000
	s_addc_u32 s83, s15, 0
	s_add_i32 s81, s61, s1
	v_lshl_add_u64 v[152:153], s[82:83], 0, v[128:129]
	s_mov_b32 m0, s81
	s_nop 0
	global_load_lds_dwordx4 v[152:153], off
	v_lshl_add_u64 v[152:153], s[82:83], 0, v[130:131]
	s_add_i32 m0, s81, 0x2000
	s_nop 0
	global_load_lds_dwordx4 v[152:153], off
	s_waitcnt vmcnt(6)
	s_barrier
	s_setprio 1
	v_mfma_f32_16x16x32_bf16 v[28:31], v[202:205], v[168:171], v[28:31]
	v_mfma_f32_16x16x32_bf16 v[24:27], v[210:213], v[168:171], v[24:27]
	v_mfma_f32_16x16x32_bf16 v[20:23], v[202:205], v[176:179], v[20:23]
	v_mfma_f32_16x16x32_bf16 v[16:19], v[210:213], v[176:179], v[16:19]
	v_mfma_f32_16x16x32_bf16 v[12:15], v[202:205], v[184:187], v[12:15]
	v_mfma_f32_16x16x32_bf16 v[8:11], v[210:213], v[184:187], v[8:11]
	v_mfma_f32_16x16x32_bf16 v[4:7], v[202:205], v[194:197], v[4:7]
	v_mfma_f32_16x16x32_bf16 v[0:3], v[210:213], v[194:197], v[0:3]
	v_mfma_f32_16x16x32_bf16 v[28:31], v[206:209], v[172:175], v[28:31]
	v_mfma_f32_16x16x32_bf16 v[24:27], v[214:217], v[172:175], v[24:27]
	v_mfma_f32_16x16x32_bf16 v[20:23], v[206:209], v[180:183], v[20:23]
	v_mfma_f32_16x16x32_bf16 v[16:19], v[214:217], v[180:183], v[16:19]
	v_mfma_f32_16x16x32_bf16 v[12:15], v[206:209], v[188:191], v[12:15]
	v_mfma_f32_16x16x32_bf16 v[8:11], v[214:217], v[188:191], v[8:11]
	v_mfma_f32_16x16x32_bf16 v[4:7], v[206:209], v[198:201], v[4:7]
	s_barrier
	v_mfma_f32_16x16x32_bf16 v[0:3], v[214:217], v[198:201], v[0:3]
	s_setprio 0
	s_add_i32 s81, 0, 0x18000
	v_add_u32_e32 v151, s81, v148
	ds_read_b128 v[152:155], v151
	ds_read_b128 v[156:159], v151 offset:1024
	ds_read_b128 v[160:163], v151 offset:2048
	ds_read_b128 v[164:167], v151 offset:3072
	s_add_u32 s16, s16, 0x80000
	s_addc_u32 s17, s17, 0
	s_mov_b32 m0, s34
	v_lshl_add_u64 v[202:203], s[16:17], 0, v[128:129]
	ds_read_b128 v[168:171], v150 offset:32768
	ds_read_b128 v[172:175], v150 offset:33792
	ds_read_b128 v[176:179], v150 offset:34816
	ds_read_b128 v[180:183], v150 offset:35840
	ds_read_b128 v[184:187], v150 offset:36864
	ds_read_b128 v[188:191], v150 offset:37888
	ds_read_b128 v[194:197], v150 offset:38912
	ds_read_b128 v[198:201], v150 offset:39936
	global_load_lds_dwordx4 v[202:203], off
	v_lshl_add_u64 v[202:203], s[16:17], 0, v[130:131]
	s_mov_b32 m0, s35
	s_nop 0
	global_load_lds_dwordx4 v[202:203], off
	s_waitcnt lgkmcnt(8)
	s_barrier
	s_waitcnt lgkmcnt(0)
	s_setprio 1
	s_waitcnt lgkmcnt(0)
	v_mfma_f32_16x16x32_bf16 v[124:127], v[152:155], v[168:171], v[124:127]
	v_mfma_f32_16x16x32_bf16 v[120:123], v[160:163], v[168:171], v[120:123]
	v_mfma_f32_16x16x32_bf16 v[116:119], v[152:155], v[176:179], v[116:119]
	v_mfma_f32_16x16x32_bf16 v[112:115], v[160:163], v[176:179], v[112:115]
	v_mfma_f32_16x16x32_bf16 v[108:111], v[152:155], v[184:187], v[108:111]
	v_mfma_f32_16x16x32_bf16 v[104:107], v[160:163], v[184:187], v[104:107]
	v_mfma_f32_16x16x32_bf16 v[100:103], v[152:155], v[194:197], v[100:103]
	v_mfma_f32_16x16x32_bf16 v[96:99], v[160:163], v[194:197], v[96:99]
	v_mfma_f32_16x16x32_bf16 v[124:127], v[156:159], v[172:175], v[124:127]
	v_mfma_f32_16x16x32_bf16 v[120:123], v[164:167], v[172:175], v[120:123]
	v_mfma_f32_16x16x32_bf16 v[116:119], v[156:159], v[180:183], v[116:119]
	v_mfma_f32_16x16x32_bf16 v[112:115], v[164:167], v[180:183], v[112:115]
	v_mfma_f32_16x16x32_bf16 v[108:111], v[156:159], v[188:191], v[108:111]
	v_mfma_f32_16x16x32_bf16 v[104:107], v[164:167], v[188:191], v[104:107]
	v_mfma_f32_16x16x32_bf16 v[100:103], v[156:159], v[198:201], v[100:103]
	s_barrier
	v_mfma_f32_16x16x32_bf16 v[96:99], v[164:167], v[198:201], v[96:99]
	s_setprio 0
	s_add_i32 s16, 0, 0x1c000
	s_add_i32 s17, s81, s1
	v_add_u32_e32 v151, s16, v148
	v_lshl_add_u64 v[146:147], v[146:147], 0, s[24:25]
	s_mov_b32 m0, s17
	ds_read_b128 v[202:205], v151
	ds_read_b128 v[206:209], v151 offset:1024
	ds_read_b128 v[210:213], v151 offset:2048
	ds_read_b128 v[214:217], v151 offset:3072
	global_load_lds_dwordx4 v[146:147], off
	v_lshl_add_u64 v[146:147], v[218:219], 0, s[24:25]
	s_add_i32 m0, s17, 0x2000
	s_nop 0
	global_load_lds_dwordx4 v[146:147], off
	s_barrier
; #define PG8_STAGE(bufoff, gbase, voff) do { _Pragma("unroll") for (int _i = 0; _i < 2; ++_i) \
;         __builtin_amdgcn_global_load_lds((const unsigned*)((const char*)(gbase) + (voff)[_i]), (LAS unsigned*)(lds + (bufoff) + ldsw + _i * 8192), 16, 0, 0); } while (0)
; #define PG8_LDA(dst, b, h) do { _Pragma("unroll") for (int m = 0; m < 4; ++m) _Pragma("unroll") for (int k = 0; k < 2; ++k) dst[m][k] = *(const LAS bf16x8*)(lds + PG8_SA(b, h) + aoff + m * 2048 + k * 1024); } while (0)
; #define PG8_MMA(ai, bj, At, Bt) do { __builtin_amdgcn_s_setprio(1); _Pragma("unroll") for (int m = 0; m < 4; ++m) _Pragma("unroll") for (int n = 0; n < 2; ++n) _Pragma("unroll") for (int k = 0; k < 2; ++k) \
;         acc[ai][bj][m][n] = __builtin_amdgcn_mfma_f32_16x16x32_bf16(Bt[n][k], At[m][k], acc[ai][bj][m][n], 0, 0, 0); __builtin_amdgcn_s_setprio(0); } while (0)
; #define PG8_WAIT_V(n) asm volatile("s_waitcnt vmcnt(" #n ")" ::: "memory")
; #define PG8_WAIT_L(n) asm volatile("s_waitcnt lgkmcnt(" #n ")" ::: "memory")
; #define PG8_BAR __builtin_amdgcn_s_barrier()
; #define PG8_SCHED __builtin_amdgcn_sched_barrier(0)
; template <class Epi>
; __device__ __forceinline__ void gemm_phase(LAS unsigned char* lds, const Gemm g, const Sched& S, const Epi& E) {
;     ...
;             PG8_BAR; PG8_WAIT_L(0); PG8_MMA(0, 1, At, B1); PG8_BAR;
;             PG8_LDA(At, 1, 1); PG8_STAGE(PG8_SA(1, 0), a3, voffA);
;             PG8_BAR; PG8_WAIT_L(0); PG8_MMA(1, 0, At, B0); PG8_BAR; PG8_SCHED;
;             PG8_STAGE(PG8_SB(1, 1), b3 + hstepB, voffB);
;             PG8_WAIT_V(6); PG8_BAR; PG8_MMA(1, 1, At, B1); PG8_BAR;
;     __device__ __forceinline__ void operator()(AccRef acc, const Unit& u, int wr, int wc, int fr, int fq) const {
; #pragma unroll
;         for (int ai = 0; ai < 2; ++ai)
; #pragma unroll
;             for (int m = 0; m < 4; ++m) { const size_t row = (size_t)u.pm * 256 + ai * 128 + wr * 64 + m * 16 + fr;
; #pragma unroll
;                 for (int bj = 0; bj < 2; ++bj)
; #pragma unroll
;                     for (int n = 0; n < 2; ++n) { const int col = u.pn * 256 + bj * 128 + wc * 32 + n * 16 + 4 * fq; if (col < 1088) *(f32x4*)(P + row * 1088 + col) = acc[ai][bj][m][n]; } }
	s_waitcnt lgkmcnt(0)
	s_setprio 1
	s_waitcnt lgkmcnt(0)
	v_mfma_f32_16x16x32_bf16 v[92:95], v[202:205], v[168:171], v[92:95]
	v_mfma_f32_16x16x32_bf16 v[88:91], v[210:213], v[168:171], v[88:91]
	v_mfma_f32_16x16x32_bf16 v[84:87], v[202:205], v[176:179], v[84:87]
	v_mfma_f32_16x16x32_bf16 v[80:83], v[210:213], v[176:179], v[80:83]
	v_mfma_f32_16x16x32_bf16 v[76:79], v[202:205], v[184:187], v[76:79]
	v_mfma_f32_16x16x32_bf16 v[72:75], v[210:213], v[184:187], v[72:75]
	v_mfma_f32_16x16x32_bf16 v[68:71], v[202:205], v[194:197], v[68:71]
	v_mfma_f32_16x16x32_bf16 v[64:67], v[210:213], v[194:197], v[64:67]
	v_mfma_f32_16x16x32_bf16 v[92:95], v[206:209], v[172:175], v[92:95]
	v_mfma_f32_16x16x32_bf16 v[88:91], v[214:217], v[172:175], v[88:91]
	v_mfma_f32_16x16x32_bf16 v[84:87], v[206:209], v[180:183], v[84:87]
	v_mfma_f32_16x16x32_bf16 v[80:83], v[214:217], v[180:183], v[80:83]
	v_mfma_f32_16x16x32_bf16 v[76:79], v[206:209], v[188:191], v[76:79]
	v_mfma_f32_16x16x32_bf16 v[72:75], v[214:217], v[188:191], v[72:75]
	v_mfma_f32_16x16x32_bf16 v[68:71], v[206:209], v[198:201], v[68:71]
	s_barrier
	v_mfma_f32_16x16x32_bf16 v[64:67], v[214:217], v[198:201], v[64:67]
	s_setprio 0
	s_mov_b32 m0, s52
	v_lshl_add_u64 v[146:147], v[220:221], 0, s[24:25]
	ds_read_b128 v[168:171], v150 offset:49152
	ds_read_b128 v[172:175], v150 offset:50176
	ds_read_b128 v[176:179], v150 offset:51200
	ds_read_b128 v[180:183], v150 offset:52224
	ds_read_b128 v[184:187], v150 offset:53248
	ds_read_b128 v[188:191], v150 offset:54272
	ds_read_b128 v[194:197], v150 offset:55296
	ds_read_b128 v[198:201], v150 offset:56320
	global_load_lds_dwordx4 v[146:147], off
	v_lshl_add_u64 v[146:147], v[222:223], 0, s[24:25]
	s_mov_b32 m0, s53
	s_nop 0
	global_load_lds_dwordx4 v[146:147], off
	s_barrier
	s_waitcnt lgkmcnt(0)
	s_setprio 1
	s_waitcnt lgkmcnt(0)
	v_mfma_f32_16x16x32_bf16 v[60:63], v[152:155], v[168:171], v[60:63]
	v_mfma_f32_16x16x32_bf16 v[56:59], v[160:163], v[168:171], v[56:59]
	v_mfma_f32_16x16x32_bf16 v[52:55], v[152:155], v[176:179], v[52:55]
	v_mfma_f32_16x16x32_bf16 v[48:51], v[160:163], v[176:179], v[48:51]
	v_mfma_f32_16x16x32_bf16 v[44:47], v[152:155], v[184:187], v[44:47]
	v_mfma_f32_16x16x32_bf16 v[40:43], v[160:163], v[184:187], v[40:43]
	v_mfma_f32_16x16x32_bf16 v[36:39], v[152:155], v[194:197], v[36:39]
	v_mfma_f32_16x16x32_bf16 v[32:35], v[160:163], v[194:197], v[32:35]
	v_mfma_f32_16x16x32_bf16 v[60:63], v[156:159], v[172:175], v[60:63]
	v_mfma_f32_16x16x32_bf16 v[56:59], v[164:167], v[172:175], v[56:59]
	v_mfma_f32_16x16x32_bf16 v[52:55], v[156:159], v[180:183], v[52:55]
	v_mfma_f32_16x16x32_bf16 v[48:51], v[164:167], v[180:183], v[48:51]
	v_mfma_f32_16x16x32_bf16 v[44:47], v[156:159], v[188:191], v[44:47]
	v_mfma_f32_16x16x32_bf16 v[40:43], v[164:167], v[188:191], v[40:43]
	v_mfma_f32_16x16x32_bf16 v[36:39], v[156:159], v[198:201], v[36:39]
	s_barrier
	v_mfma_f32_16x16x32_bf16 v[32:35], v[164:167], v[198:201], v[32:35]
	s_setprio 0
	s_add_u32 s14, s14, 0x80080
	s_addc_u32 s15, s15, 0
	s_add_i32 s16, s16, s1
	v_lshl_add_u64 v[146:147], s[14:15], 0, v[128:129]
	s_mov_b32 m0, s16
	s_nop 0
	global_load_lds_dwordx4 v[146:147], off
	v_lshl_add_u64 v[146:147], s[14:15], 0, v[130:131]
	s_add_i32 m0, s16, 0x2000
	s_nop 0
	global_load_lds_dwordx4 v[146:147], off
	s_waitcnt vmcnt(6)
	s_barrier
	s_setprio 1
	v_mfma_f32_16x16x32_bf16 v[28:31], v[202:205], v[168:171], v[28:31]
	v_mfma_f32_16x16x32_bf16 v[24:27], v[210:213], v[168:171], v[24:27]
	v_mfma_f32_16x16x32_bf16 v[20:23], v[202:205], v[176:179], v[20:23]
	v_mfma_f32_16x16x32_bf16 v[16:19], v[210:213], v[176:179], v[16:19]
	v_mfma_f32_16x16x32_bf16 v[12:15], v[202:205], v[184:187], v[12:15]
	v_mfma_f32_16x16x32_bf16 v[8:11], v[210:213], v[184:187], v[8:11]
	v_mfma_f32_16x16x32_bf16 v[4:7], v[202:205], v[194:197], v[4:7]
	v_mfma_f32_16x16x32_bf16 v[0:3], v[210:213], v[194:197], v[0:3]
	v_mfma_f32_16x16x32_bf16 v[28:31], v[206:209], v[172:175], v[28:31]
	v_mfma_f32_16x16x32_bf16 v[24:27], v[214:217], v[172:175], v[24:27]
	v_mfma_f32_16x16x32_bf16 v[20:23], v[206:209], v[180:183], v[20:23]
	v_mfma_f32_16x16x32_bf16 v[16:19], v[214:217], v[180:183], v[16:19]
	v_mfma_f32_16x16x32_bf16 v[12:15], v[206:209], v[188:191], v[12:15]
	v_mfma_f32_16x16x32_bf16 v[8:11], v[214:217], v[188:191], v[8:11]
	v_mfma_f32_16x16x32_bf16 v[4:7], v[206:209], v[198:201], v[4:7]
	s_barrier
	v_mfma_f32_16x16x32_bf16 v[0:3], v[214:217], v[198:201], v[0:3]
	s_setprio 0
	s_add_i32 s80, s80, 2
	s_add_u32 s12, s12, 0x100
	s_addc_u32 s13, s13, 0
	s_cmp_gt_u32 s80, 29
	s_cbranch_scc0 .LBB0_2488
	s_ashr_i32 s21, s20, 31
	s_lshl_b64 s[12:13], s[20:21], 8
	v_lshl_add_u64 v[146:147], v[132:133], 0, s[12:13]
	v_mad_u64_u32 v[144:145], s[12:13], v146, s62, 0
	v_mov_b32_e32 v146, v145
	v_mad_u64_u32 v[146:147], s[12:13], v147, s62, v[146:147]
	v_lshl_or_b32 v142, s18, 8, v149
	v_mov_b32_e32 v145, v146
	v_cmp_gt_i32_e32 vcc, s63, v142
	v_lshl_add_u64 v[146:147], s[44:45], 0, v[144:145]
	v_ashrrev_i32_e32 v143, 31, v142
	s_and_saveexec_b64 s[12:13], vcc
	s_cbranch_execz .LBB0_2491
	v_lshl_add_u64 v[152:153], v[142:143], 2, v[146:147]
	global_store_dwordx4 v[152:153], v[124:127], off

; #define PG8_STAGE(bufoff, gbase, voff) do { _Pragma("unroll") for (int _i = 0; _i < 2; ++_i) \
;         __builtin_amdgcn_global_load_lds((const unsigned*)((const char*)(gbase) + (voff)[_i]), (LAS unsigned*)(lds + (bufoff) + ldsw + _i * 8192), 16, 0, 0); } while (0)
; #define PG8_LDA(dst, b, h) do { _Pragma("unroll") for (int m = 0; m < 4; ++m) _Pragma("unroll") for (int k = 0; k < 2; ++k) dst[m][k] = *(const LAS bf16x8*)(lds + PG8_SA(b, h) + aoff + m * 2048 + k * 1024); } while (0)
; #define PG8_LDB(dst, b, h) do { _Pragma("unroll") for (int n = 0; n < 2; ++n) _Pragma("unroll") for (int k = 0; k < 2; ++k) dst[n][k] = *(const LAS bf16x8*)(lds + PG8_SB(b, h) + boff + n * 2048 + k * 1024); } while (0)
; #define PG8_MMA(ai, bj, At, Bt) do { __builtin_amdgcn_s_setprio(1); _Pragma("unroll") for (int m = 0; m < 4; ++m) _Pragma("unroll") for (int n = 0; n < 2; ++n) _Pragma("unroll") for (int k = 0; k < 2; ++k) \
;         acc[ai][bj][m][n] = __builtin_amdgcn_mfma_f32_16x16x32_bf16(Bt[n][k], At[m][k], acc[ai][bj][m][n], 0, 0, 0); __builtin_amdgcn_s_setprio(0); } while (0)
; #define PG8_WAIT_V(n) asm volatile("s_waitcnt vmcnt(" #n ")" ::: "memory")
; #define PG8_WAIT_L(n) asm volatile("s_waitcnt lgkmcnt(" #n ")" ::: "memory")
; #define PG8_BAR __builtin_amdgcn_s_barrier()
; #define PG8_SCHED __builtin_amdgcn_sched_barrier(0)
; template <class Epi>
; __device__ __forceinline__ void gemm_phase(LAS unsigned char* lds, const Gemm g, const Sched& S, const Epi& E) {
;     ...
;             PG8_LDB(B0, 0, 0); PG8_SCHED; PG8_LDA(At, 0, 0); PG8_STAGE(PG8_SA(1, 1), a1 + hstepA, voffA);
;             PG8_WAIT_L(8); PG8_BAR; PG8_WAIT_L(0); PG8_MMA(0, 0, At, B0); PG8_BAR; PG8_SCHED;
;             PG8_LDB(B1, 0, 1); PG8_STAGE(PG8_SB(0, 0), b2, voffB);
;             PG8_BAR; PG8_WAIT_L(0); PG8_MMA(0, 1, At, B1); PG8_BAR;
;             PG8_LDA(At, 0, 1); PG8_STAGE(PG8_SA(0, 0), a2, voffA);
;             PG8_BAR; PG8_WAIT_L(0); PG8_MMA(1, 0, At, B0); PG8_BAR; PG8_SCHED;
;             PG8_STAGE(PG8_SB(0, 1), b2 + hstepB, voffB);
;             PG8_WAIT_V(6); PG8_BAR; PG8_MMA(1, 1, At, B1); PG8_BAR;
.LBB0_2675:
	ds_read_b128 v[104:107], v230
	ds_read_b128 v[120:123], v230 offset:1024
	ds_read_b128 v[128:131], v230 offset:2048
	ds_read_b128 v[132:135], v230 offset:3072
	s_add_u32 s14, s12, 0xfffe0080
	s_addc_u32 s15, s13, -1
	s_cmp_eq_u32 s84, 4
	s_cselect_b32 s17, s50, s15
	s_cselect_b32 s16, s51, s14
	s_cselect_b32 s15, s57, s65
	s_cselect_b32 s14, s59, s64
	v_lshl_add_u64 v[176:177], s[12:13], 0, v[202:203]
	s_add_i32 m0, s43, 0xc000
	ds_read_b128 v[140:143], v231
	ds_read_b128 v[144:147], v231 offset:1024
	ds_read_b128 v[152:155], v231 offset:2048
	ds_read_b128 v[156:159], v231 offset:3072
	ds_read_b128 v[160:163], v231 offset:4096
	ds_read_b128 v[164:167], v231 offset:5120
	ds_read_b128 v[168:171], v231 offset:6144
	ds_read_b128 v[172:175], v231 offset:7168
	global_load_lds_dwordx4 v[176:177], off
	v_lshl_add_u64 v[176:177], s[12:13], 0, v[204:205]
	s_add_i32 m0, s43, 0xe000
	s_nop 0
	global_load_lds_dwordx4 v[176:177], off
	s_waitcnt lgkmcnt(8)
	s_barrier
	s_waitcnt lgkmcnt(0)
	s_setprio 1
	s_waitcnt lgkmcnt(0)
	v_mfma_f32_16x16x32_bf16 v[148:151], v[104:107], v[140:143], v[148:151]
	v_mfma_f32_16x16x32_bf16 v[136:139], v[128:131], v[140:143], v[136:139]
	v_mfma_f32_16x16x32_bf16 v[116:119], v[104:107], v[152:155], v[116:119]
	v_mfma_f32_16x16x32_bf16 v[108:111], v[128:131], v[152:155], v[108:111]
	v_mfma_f32_16x16x32_bf16 v[96:99], v[104:107], v[160:163], v[96:99]
	v_mfma_f32_16x16x32_bf16 v[88:91], v[128:131], v[160:163], v[88:91]
	v_mfma_f32_16x16x32_bf16 v[80:83], v[104:107], v[168:171], v[80:83]
	v_mfma_f32_16x16x32_bf16 v[72:75], v[128:131], v[168:171], v[72:75]
	v_mfma_f32_16x16x32_bf16 v[148:151], v[120:123], v[144:147], v[148:151]
	v_mfma_f32_16x16x32_bf16 v[136:139], v[132:135], v[144:147], v[136:139]
	v_mfma_f32_16x16x32_bf16 v[116:119], v[120:123], v[156:159], v[116:119]
	v_mfma_f32_16x16x32_bf16 v[108:111], v[132:135], v[156:159], v[108:111]
	v_mfma_f32_16x16x32_bf16 v[96:99], v[120:123], v[164:167], v[96:99]
	v_mfma_f32_16x16x32_bf16 v[88:91], v[132:135], v[164:167], v[88:91]
	v_mfma_f32_16x16x32_bf16 v[80:83], v[120:123], v[172:175], v[80:83]
	s_barrier
	v_mfma_f32_16x16x32_bf16 v[72:75], v[132:135], v[172:175], v[72:75]
	s_setprio 0
	s_add_i32 s85, s80, s1
	v_lshl_add_u64 v[210:211], s[14:15], 0, v[196:197]
	s_mov_b32 m0, s85
	ds_read_b128 v[176:179], v232
	ds_read_b128 v[180:183], v232 offset:1024
	ds_read_b128 v[184:187], v232 offset:2048
	ds_read_b128 v[188:191], v232 offset:3072
	global_load_lds_dwordx4 v[210:211], off
	v_lshl_add_u64 v[212:213], s[14:15], 0, v[194:195]
	s_add_i32 m0, s85, 0x2000
	s_nop 0
	global_load_lds_dwordx4 v[212:213], off
	s_barrier
	s_waitcnt lgkmcnt(0)
	s_setprio 1
	s_waitcnt lgkmcnt(0)
	v_mfma_f32_16x16x32_bf16 v[124:127], v[176:179], v[140:143], v[124:127]
	v_mfma_f32_16x16x32_bf16 v[112:115], v[184:187], v[140:143], v[112:115]
	v_mfma_f32_16x16x32_bf16 v[100:103], v[176:179], v[152:155], v[100:103]
	v_mfma_f32_16x16x32_bf16 v[92:95], v[184:187], v[152:155], v[92:95]
	v_mfma_f32_16x16x32_bf16 v[84:87], v[176:179], v[160:163], v[84:87]
	v_mfma_f32_16x16x32_bf16 v[76:79], v[184:187], v[160:163], v[76:79]
	v_mfma_f32_16x16x32_bf16 v[68:71], v[176:179], v[168:171], v[68:71]
	v_mfma_f32_16x16x32_bf16 v[64:67], v[184:187], v[168:171], v[64:67]
	v_mfma_f32_16x16x32_bf16 v[124:127], v[180:183], v[144:147], v[124:127]
	v_mfma_f32_16x16x32_bf16 v[112:115], v[188:191], v[144:147], v[112:115]
	v_mfma_f32_16x16x32_bf16 v[100:103], v[180:183], v[156:159], v[100:103]
	v_mfma_f32_16x16x32_bf16 v[92:95], v[188:191], v[156:159], v[92:95]
	v_mfma_f32_16x16x32_bf16 v[84:87], v[180:183], v[164:167], v[84:87]
	v_mfma_f32_16x16x32_bf16 v[76:79], v[188:191], v[164:167], v[76:79]
	v_mfma_f32_16x16x32_bf16 v[68:71], v[180:183], v[172:175], v[68:71]
	s_barrier
	v_mfma_f32_16x16x32_bf16 v[64:67], v[188:191], v[172:175], v[64:67]
	s_setprio 0
	s_mov_b32 m0, s43
	v_lshl_add_u64 v[214:215], s[16:17], 0, v[196:197]
	ds_read_b128 v[140:143], v231 offset:16384
	ds_read_b128 v[144:147], v231 offset:17408
	ds_read_b128 v[152:155], v231 offset:18432
	ds_read_b128 v[156:159], v231 offset:19456
	ds_read_b128 v[160:163], v231 offset:20480
	ds_read_b128 v[164:167], v231 offset:21504
	ds_read_b128 v[168:171], v231 offset:22528
	ds_read_b128 v[172:175], v231 offset:23552
	global_load_lds_dwordx4 v[214:215], off
	v_lshl_add_u64 v[216:217], s[16:17], 0, v[194:195]
	s_mov_b32 m0, s52
	s_nop 0
	global_load_lds_dwordx4 v[216:217], off
	s_barrier
	s_waitcnt lgkmcnt(0)
	s_setprio 1
	s_waitcnt lgkmcnt(0)
	v_mfma_f32_16x16x32_bf16 v[60:63], v[104:107], v[140:143], v[60:63]
	v_mfma_f32_16x16x32_bf16 v[56:59], v[128:131], v[140:143], v[56:59]
	v_mfma_f32_16x16x32_bf16 v[48:51], v[104:107], v[152:155], v[48:51]
	v_mfma_f32_16x16x32_bf16 v[40:43], v[128:131], v[152:155], v[40:43]
	v_mfma_f32_16x16x32_bf16 v[32:35], v[104:107], v[160:163], v[32:35]
	v_mfma_f32_16x16x32_bf16 v[24:27], v[128:131], v[160:163], v[24:27]
	v_mfma_f32_16x16x32_bf16 v[16:19], v[104:107], v[168:171], v[16:19]
	v_mfma_f32_16x16x32_bf16 v[8:11], v[128:131], v[168:171], v[8:11]
	v_mfma_f32_16x16x32_bf16 v[60:63], v[120:123], v[144:147], v[60:63]
	v_mfma_f32_16x16x32_bf16 v[56:59], v[132:135], v[144:147], v[56:59]
	v_mfma_f32_16x16x32_bf16 v[48:51], v[120:123], v[156:159], v[48:51]
	v_mfma_f32_16x16x32_bf16 v[40:43], v[132:135], v[156:159], v[40:43]
	v_mfma_f32_16x16x32_bf16 v[32:35], v[120:123], v[164:167], v[32:35]
	v_mfma_f32_16x16x32_bf16 v[24:27], v[132:135], v[164:167], v[24:27]
	v_mfma_f32_16x16x32_bf16 v[16:19], v[120:123], v[172:175], v[16:19]
	s_barrier
; #define PG8_STAGE(bufoff, gbase, voff) do { _Pragma("unroll") for (int _i = 0; _i < 2; ++_i) \
;         __builtin_amdgcn_global_load_lds((const unsigned*)((const char*)(gbase) + (voff)[_i]), (LAS unsigned*)(lds + (bufoff) + ldsw + _i * 8192), 16, 0, 0); } while (0)
; #define PG8_LDA(dst, b, h) do { _Pragma("unroll") for (int m = 0; m < 4; ++m) _Pragma("unroll") for (int k = 0; k < 2; ++k) dst[m][k] = *(const LAS bf16x8*)(lds + PG8_SA(b, h) + aoff + m * 2048 + k * 1024); } while (0)
; #define PG8_LDB(dst, b, h) do { _Pragma("unroll") for (int n = 0; n < 2; ++n) _Pragma("unroll") for (int k = 0; k < 2; ++k) dst[n][k] = *(const LAS bf16x8*)(lds + PG8_SB(b, h) + boff + n * 2048 + k * 1024); } while (0)
; #define PG8_MMA(ai, bj, At, Bt) do { __builtin_amdgcn_s_setprio(1); _Pragma("unroll") for (int m = 0; m < 4; ++m) _Pragma("unroll") for (int n = 0; n < 2; ++n) _Pragma("unroll") for (int k = 0; k < 2; ++k) \
;         acc[ai][bj][m][n] = __builtin_amdgcn_mfma_f32_16x16x32_bf16(Bt[n][k], At[m][k], acc[ai][bj][m][n], 0, 0, 0); __builtin_amdgcn_s_setprio(0); } while (0)
; #define PG8_WAIT_V(n) asm volatile("s_waitcnt vmcnt(" #n ")" ::: "memory")
; #define PG8_WAIT_L(n) asm volatile("s_waitcnt lgkmcnt(" #n ")" ::: "memory")
; #define PG8_BAR __builtin_amdgcn_s_barrier()
; #define PG8_SCHED __builtin_amdgcn_sched_barrier(0)
; template <class Epi>
; __device__ __forceinline__ void gemm_phase(LAS unsigned char* lds, const Gemm g, const Sched& S, const Epi& E) {
;     ...
;             PG8_BAR; PG8_WAIT_L(0); PG8_MMA(1, 0, At, B0); PG8_BAR; PG8_SCHED;
;             PG8_STAGE(PG8_SB(0, 1), b2 + hstepB, voffB);
;             PG8_WAIT_V(6); PG8_BAR; PG8_MMA(1, 1, At, B1); PG8_BAR;
;             PG8_LDB(B0, 1, 0); PG8_SCHED; PG8_LDA(At, 1, 0); PG8_STAGE(PG8_SA(0, 1), a2 + hstepA, voffA);
;             PG8_WAIT_L(8); PG8_BAR; PG8_WAIT_L(0); PG8_MMA(0, 0, At, B0); PG8_BAR; PG8_SCHED;
;             PG8_LDB(B1, 1, 1); PG8_STAGE(PG8_SB(1, 0), b3, voffB);
;             PG8_BAR; PG8_WAIT_L(0); PG8_MMA(0, 1, At, B1); PG8_BAR;
	v_mfma_f32_16x16x32_bf16 v[8:11], v[132:135], v[172:175], v[8:11]
	s_setprio 0
	s_add_u32 s86, s14, 0x20000
	s_addc_u32 s87, s15, 0
	s_add_i32 s85, s81, s1
	v_lshl_add_u64 v[104:105], s[86:87], 0, v[196:197]
	s_mov_b32 m0, s85
	s_nop 0
	global_load_lds_dwordx4 v[104:105], off
	v_lshl_add_u64 v[104:105], s[86:87], 0, v[194:195]
	s_add_i32 m0, s85, 0x2000
	s_nop 0
	global_load_lds_dwordx4 v[104:105], off
	s_waitcnt vmcnt(6)
	s_barrier
	s_setprio 1
	v_mfma_f32_16x16x32_bf16 v[52:55], v[176:179], v[140:143], v[52:55]
	v_mfma_f32_16x16x32_bf16 v[44:47], v[184:187], v[140:143], v[44:47]
	v_mfma_f32_16x16x32_bf16 v[36:39], v[176:179], v[152:155], v[36:39]
	v_mfma_f32_16x16x32_bf16 v[28:31], v[184:187], v[152:155], v[28:31]
	v_mfma_f32_16x16x32_bf16 v[20:23], v[176:179], v[160:163], v[20:23]
	v_mfma_f32_16x16x32_bf16 v[12:15], v[184:187], v[160:163], v[12:15]
	v_mfma_f32_16x16x32_bf16 v[4:7], v[176:179], v[168:171], v[4:7]
	v_mfma_f32_16x16x32_bf16 v[0:3], v[184:187], v[168:171], v[0:3]
	v_mfma_f32_16x16x32_bf16 v[52:55], v[180:183], v[144:147], v[52:55]
	v_mfma_f32_16x16x32_bf16 v[44:47], v[188:191], v[144:147], v[44:47]
	v_mfma_f32_16x16x32_bf16 v[36:39], v[180:183], v[156:159], v[36:39]
	v_mfma_f32_16x16x32_bf16 v[28:31], v[188:191], v[156:159], v[28:31]
	v_mfma_f32_16x16x32_bf16 v[20:23], v[180:183], v[164:167], v[20:23]
	v_mfma_f32_16x16x32_bf16 v[12:15], v[188:191], v[164:167], v[12:15]
	v_mfma_f32_16x16x32_bf16 v[4:7], v[180:183], v[172:175], v[4:7]
	s_barrier
	v_mfma_f32_16x16x32_bf16 v[0:3], v[188:191], v[172:175], v[0:3]
	s_setprio 0
	s_add_i32 s85, 0, 0x18000
	v_add_u32_e32 v132, s85, v228
	ds_read_b128 v[104:107], v132
	ds_read_b128 v[120:123], v132 offset:1024
	ds_read_b128 v[128:131], v132 offset:2048
	ds_read_b128 v[132:135], v132 offset:3072
	s_add_u32 s16, s16, 0x20000
	s_addc_u32 s17, s17, 0
	s_mov_b32 m0, s53
	v_lshl_add_u64 v[176:177], s[16:17], 0, v[196:197]
	ds_read_b128 v[140:143], v231 offset:32768
	ds_read_b128 v[144:147], v231 offset:33792
	ds_read_b128 v[152:155], v231 offset:34816
	ds_read_b128 v[156:159], v231 offset:35840
	ds_read_b128 v[160:163], v231 offset:36864
	ds_read_b128 v[164:167], v231 offset:37888
	ds_read_b128 v[168:171], v231 offset:38912
	ds_read_b128 v[172:175], v231 offset:39936
	global_load_lds_dwordx4 v[176:177], off
	v_lshl_add_u64 v[176:177], s[16:17], 0, v[194:195]
	s_mov_b32 m0, s66
	s_nop 0
	global_load_lds_dwordx4 v[176:177], off
	s_waitcnt lgkmcnt(8)
	s_barrier
	s_waitcnt lgkmcnt(0)
	s_setprio 1
	s_waitcnt lgkmcnt(0)
	v_mfma_f32_16x16x32_bf16 v[148:151], v[104:107], v[140:143], v[148:151]
	v_mfma_f32_16x16x32_bf16 v[136:139], v[128:131], v[140:143], v[136:139]
	v_mfma_f32_16x16x32_bf16 v[116:119], v[104:107], v[152:155], v[116:119]
	v_mfma_f32_16x16x32_bf16 v[108:111], v[128:131], v[152:155], v[108:111]
	v_mfma_f32_16x16x32_bf16 v[96:99], v[104:107], v[160:163], v[96:99]
	v_mfma_f32_16x16x32_bf16 v[88:91], v[128:131], v[160:163], v[88:91]
	v_mfma_f32_16x16x32_bf16 v[80:83], v[104:107], v[168:171], v[80:83]
	v_mfma_f32_16x16x32_bf16 v[72:75], v[128:131], v[168:171], v[72:75]
	v_mfma_f32_16x16x32_bf16 v[148:151], v[120:123], v[144:147], v[148:151]
	v_mfma_f32_16x16x32_bf16 v[136:139], v[132:135], v[144:147], v[136:139]
	v_mfma_f32_16x16x32_bf16 v[116:119], v[120:123], v[156:159], v[116:119]
	v_mfma_f32_16x16x32_bf16 v[108:111], v[132:135], v[156:159], v[108:111]
	v_mfma_f32_16x16x32_bf16 v[96:99], v[120:123], v[164:167], v[96:99]
	v_mfma_f32_16x16x32_bf16 v[88:91], v[132:135], v[164:167], v[88:91]
	v_mfma_f32_16x16x32_bf16 v[80:83], v[120:123], v[172:175], v[80:83]
	s_barrier
	v_mfma_f32_16x16x32_bf16 v[72:75], v[132:135], v[172:175], v[72:75]
	s_setprio 0
	s_add_i32 s16, 0, 0x1c000
	s_add_i32 s17, s85, s1
	v_add_u32_e32 v188, s16, v228
	v_lshl_add_u64 v[210:211], v[210:211], 0, s[22:23]
	s_mov_b32 m0, s17
	ds_read_b128 v[176:179], v188
	ds_read_b128 v[180:183], v188 offset:1024
	ds_read_b128 v[184:187], v188 offset:2048
	ds_read_b128 v[188:191], v188 offset:3072
	global_load_lds_dwordx4 v[210:211], off
	v_lshl_add_u64 v[210:211], v[212:213], 0, s[22:23]
	s_add_i32 m0, s17, 0x2000
	s_nop 0
	global_load_lds_dwordx4 v[210:211], off
	s_barrier
	s_waitcnt lgkmcnt(0)
	s_setprio 1
	s_waitcnt lgkmcnt(0)
	v_mfma_f32_16x16x32_bf16 v[124:127], v[176:179], v[140:143], v[124:127]
	v_mfma_f32_16x16x32_bf16 v[112:115], v[184:187], v[140:143], v[112:115]
	v_mfma_f32_16x16x32_bf16 v[100:103], v[176:179], v[152:155], v[100:103]
	v_mfma_f32_16x16x32_bf16 v[92:95], v[184:187], v[152:155], v[92:95]
	v_mfma_f32_16x16x32_bf16 v[84:87], v[176:179], v[160:163], v[84:87]
	v_mfma_f32_16x16x32_bf16 v[76:79], v[184:187], v[160:163], v[76:79]
	v_mfma_f32_16x16x32_bf16 v[68:71], v[176:179], v[168:171], v[68:71]
	v_mfma_f32_16x16x32_bf16 v[64:67], v[184:187], v[168:171], v[64:67]
	v_mfma_f32_16x16x32_bf16 v[124:127], v[180:183], v[144:147], v[124:127]
	v_mfma_f32_16x16x32_bf16 v[112:115], v[188:191], v[144:147], v[112:115]
	v_mfma_f32_16x16x32_bf16 v[100:103], v[180:183], v[156:159], v[100:103]
	v_mfma_f32_16x16x32_bf16 v[92:95], v[188:191], v[156:159], v[92:95]
	v_mfma_f32_16x16x32_bf16 v[84:87], v[180:183], v[164:167], v[84:87]
	v_mfma_f32_16x16x32_bf16 v[76:79], v[188:191], v[164:167], v[76:79]
	v_mfma_f32_16x16x32_bf16 v[68:71], v[180:183], v[172:175], v[68:71]
	s_barrier
; #define PG8_STAGE(bufoff, gbase, voff) do { _Pragma("unroll") for (int _i = 0; _i < 2; ++_i) \
;         __builtin_amdgcn_global_load_lds((const unsigned*)((const char*)(gbase) + (voff)[_i]), (LAS unsigned*)(lds + (bufoff) + ldsw + _i * 8192), 16, 0, 0); } while (0)
; #define PG8_LDA(dst, b, h) do { _Pragma("unroll") for (int m = 0; m < 4; ++m) _Pragma("unroll") for (int k = 0; k < 2; ++k) dst[m][k] = *(const LAS bf16x8*)(lds + PG8_SA(b, h) + aoff + m * 2048 + k * 1024); } while (0)
; #define PG8_MMA(ai, bj, At, Bt) do { __builtin_amdgcn_s_setprio(1); _Pragma("unroll") for (int m = 0; m < 4; ++m) _Pragma("unroll") for (int n = 0; n < 2; ++n) _Pragma("unroll") for (int k = 0; k < 2; ++k) \
;         acc[ai][bj][m][n] = __builtin_amdgcn_mfma_f32_16x16x32_bf16(Bt[n][k], At[m][k], acc[ai][bj][m][n], 0, 0, 0); __builtin_amdgcn_s_setprio(0); } while (0)
; #define PG8_WAIT_V(n) asm volatile("s_waitcnt vmcnt(" #n ")" ::: "memory")
; #define PG8_WAIT_L(n) asm volatile("s_waitcnt lgkmcnt(" #n ")" ::: "memory")
; #define PG8_BAR __builtin_amdgcn_s_barrier()
; #define PG8_SCHED __builtin_amdgcn_sched_barrier(0)
; template <class Epi>
; __device__ __forceinline__ void gemm_phase(LAS unsigned char* lds, const Gemm g, const Sched& S, const Epi& E) {
;     ...
;             PG8_BAR; PG8_WAIT_L(0); PG8_MMA(0, 1, At, B1); PG8_BAR;
;             PG8_LDA(At, 1, 1); PG8_STAGE(PG8_SA(1, 0), a3, voffA);
;             PG8_BAR; PG8_WAIT_L(0); PG8_MMA(1, 0, At, B0); PG8_BAR; PG8_SCHED;
;             PG8_STAGE(PG8_SB(1, 1), b3 + hstepB, voffB);
;             PG8_WAIT_V(6); PG8_BAR; PG8_MMA(1, 1, At, B1); PG8_BAR;
;     __device__ __forceinline__ void operator()(AccRef acc, const Unit& u, int wr, int wc, int fr, int fq) const {
; #pragma unroll
;         for (int ai = 0; ai < 2; ++ai) {
;             f32x2 t0[4][2][2], t1[4][2][2];
; #pragma unroll
;             for (int bj = 0; bj < 2; ++bj)
; #pragma unroll
;                 for (int n = 0; n < 2; ++n) { const int col = u.pn * 256 + bj * 128 + wc * 32 + n * 16 + 4 * fq; const int hd = col / 192, p = col - hd * 192;
;                     if (p >= 128) {
; #pragma unroll
;                         for (int m = 0; m < 4; ++m) { const size_t row = (size_t)u.pm * 256 + ai * 128 + wr * 64 + m * 16 + fr; const f32x2* tb = rope + row * 32 + ((p - 128) >> 1); t0[m][bj][n] = tb[0]; t1[m][bj][n] = tb[1]; } } }
	v_mfma_f32_16x16x32_bf16 v[64:67], v[188:191], v[172:175], v[64:67]
	s_setprio 0
	s_mov_b32 m0, s76
	v_lshl_add_u64 v[210:211], v[214:215], 0, s[22:23]
	ds_read_b128 v[140:143], v231 offset:49152
	ds_read_b128 v[144:147], v231 offset:50176
	ds_read_b128 v[152:155], v231 offset:51200
	ds_read_b128 v[156:159], v231 offset:52224
	ds_read_b128 v[160:163], v231 offset:53248
	ds_read_b128 v[164:167], v231 offset:54272
	ds_read_b128 v[168:171], v231 offset:55296
	ds_read_b128 v[172:175], v231 offset:56320
	global_load_lds_dwordx4 v[210:211], off
	v_lshl_add_u64 v[210:211], v[216:217], 0, s[22:23]
	s_mov_b32 m0, s77
	s_nop 0
	global_load_lds_dwordx4 v[210:211], off
	s_barrier
	s_waitcnt lgkmcnt(0)
	s_setprio 1
	s_waitcnt lgkmcnt(0)
	v_mfma_f32_16x16x32_bf16 v[60:63], v[104:107], v[140:143], v[60:63]
	v_mfma_f32_16x16x32_bf16 v[56:59], v[128:131], v[140:143], v[56:59]
	v_mfma_f32_16x16x32_bf16 v[48:51], v[104:107], v[152:155], v[48:51]
	v_mfma_f32_16x16x32_bf16 v[40:43], v[128:131], v[152:155], v[40:43]
	v_mfma_f32_16x16x32_bf16 v[32:35], v[104:107], v[160:163], v[32:35]
	v_mfma_f32_16x16x32_bf16 v[24:27], v[128:131], v[160:163], v[24:27]
	v_mfma_f32_16x16x32_bf16 v[16:19], v[104:107], v[168:171], v[16:19]
	v_mfma_f32_16x16x32_bf16 v[8:11], v[128:131], v[168:171], v[8:11]
	v_mfma_f32_16x16x32_bf16 v[60:63], v[120:123], v[144:147], v[60:63]
	v_mfma_f32_16x16x32_bf16 v[56:59], v[132:135], v[144:147], v[56:59]
	v_mfma_f32_16x16x32_bf16 v[48:51], v[120:123], v[156:159], v[48:51]
	v_mfma_f32_16x16x32_bf16 v[40:43], v[132:135], v[156:159], v[40:43]
	v_mfma_f32_16x16x32_bf16 v[32:35], v[120:123], v[164:167], v[32:35]
	v_mfma_f32_16x16x32_bf16 v[24:27], v[132:135], v[164:167], v[24:27]
	v_mfma_f32_16x16x32_bf16 v[16:19], v[120:123], v[172:175], v[16:19]
	s_barrier
	v_mfma_f32_16x16x32_bf16 v[8:11], v[132:135], v[172:175], v[8:11]
	s_setprio 0
	s_add_u32 s14, s14, 0x20080
	s_addc_u32 s15, s15, 0
	s_add_i32 s16, s16, s1
	v_lshl_add_u64 v[104:105], s[14:15], 0, v[196:197]
	s_mov_b32 m0, s16
	s_nop 0
	global_load_lds_dwordx4 v[104:105], off
	v_lshl_add_u64 v[104:105], s[14:15], 0, v[194:195]
	s_add_i32 m0, s16, 0x2000
	s_nop 0
	global_load_lds_dwordx4 v[104:105], off
	s_waitcnt vmcnt(6)
	s_barrier
	s_setprio 1
	v_mfma_f32_16x16x32_bf16 v[52:55], v[176:179], v[140:143], v[52:55]
	v_mfma_f32_16x16x32_bf16 v[44:47], v[184:187], v[140:143], v[44:47]
	v_mfma_f32_16x16x32_bf16 v[36:39], v[176:179], v[152:155], v[36:39]
	v_mfma_f32_16x16x32_bf16 v[28:31], v[184:187], v[152:155], v[28:31]
	v_mfma_f32_16x16x32_bf16 v[20:23], v[176:179], v[160:163], v[20:23]
	v_mfma_f32_16x16x32_bf16 v[12:15], v[184:187], v[160:163], v[12:15]
	v_mfma_f32_16x16x32_bf16 v[4:7], v[176:179], v[168:171], v[4:7]
	v_mfma_f32_16x16x32_bf16 v[0:3], v[184:187], v[168:171], v[0:3]
	v_mfma_f32_16x16x32_bf16 v[52:55], v[180:183], v[144:147], v[52:55]
	v_mfma_f32_16x16x32_bf16 v[44:47], v[188:191], v[144:147], v[44:47]
	v_mfma_f32_16x16x32_bf16 v[36:39], v[180:183], v[156:159], v[36:39]
	v_mfma_f32_16x16x32_bf16 v[28:31], v[188:191], v[156:159], v[28:31]
	v_mfma_f32_16x16x32_bf16 v[20:23], v[180:183], v[164:167], v[20:23]
	v_mfma_f32_16x16x32_bf16 v[12:15], v[188:191], v[164:167], v[12:15]
	v_mfma_f32_16x16x32_bf16 v[4:7], v[180:183], v[172:175], v[4:7]
	s_barrier
	v_mfma_f32_16x16x32_bf16 v[0:3], v[188:191], v[172:175], v[0:3]
	s_setprio 0
	s_add_i32 s84, s84, 2
	s_add_u32 s12, s12, 0x100
	s_addc_u32 s13, s13, 0
	s_add_u32 s64, s64, 0x100
	s_addc_u32 s65, s65, 0
	s_cmp_gt_u32 s84, 5
	s_cbranch_scc0 .LBB0_2675
	v_lshl_or_b32 v222, s11, 8, v229
	v_mul_hi_i32 v104, v222, s71
	v_lshrrev_b32_e32 v105, 31, v104
	v_lshrrev_b32_e32 v104, 5, v104
	v_add_u32_e32 v104, v104, v105
	s_ashr_i32 s11, s10, 31
	v_mul_lo_u32 v104, v104, s67
	s_lshl_b64 s[10:11], s[10:11], 8
	v_sub_u32_e32 v104, v222, v104
	v_lshl_add_u64 v[212:213], s[10:11], 0, v[200:201]
	v_cmp_lt_i32_e64 s[10:11], s82, v104
	v_add_u32_e32 v104, 0xffffff80, v104
	v_lshlrev_b64 v[210:211], 8, v[212:213]
	v_lshrrev_b32_e32 v198, 1, v104
	s_and_saveexec_b64 s[12:13], s[10:11]
	s_cbranch_execz .LBB0_2678
	v_lshl_add_u64 v[104:105], v[198:199], 3, s[18:19]
	v_lshl_add_u64 v[104:105], v[104:105], 0, v[210:211]
	v_add_co_u32_e32 v106, vcc, 0x1000, v104
	s_nop 1
	v_addc_co_u32_e32 v107, vcc, 0, v105, vcc
	global_load_dwordx4 v[160:163], v[104:105], off
	global_load_dwordx4 v[132:135], v[106:107], off
	v_add_co_u32_e32 v106, vcc, 0x2000, v104
	s_nop 1
	v_addc_co_u32_e32 v107, vcc, 0, v105, vcc
	v_add_co_u32_e32 v104, vcc, 0x3000, v104
	s_nop 1
	v_addc_co_u32_e32 v105, vcc, 0, v105, vcc
	global_load_dwordx4 v[128:131], v[106:107], off
	s_nop 0
	global_load_dwordx4 v[104:107], v[104:105], off

; #define PG8_STAGE(bufoff, gbase, voff) do { _Pragma("unroll") for (int _i = 0; _i < 2; ++_i) \
;         __builtin_amdgcn_global_load_lds((const unsigned*)((const char*)(gbase) + (voff)[_i]), (LAS unsigned*)(lds + (bufoff) + ldsw + _i * 8192), 16, 0, 0); } while (0)
; #define PG8_LDA(dst, b, h) do { _Pragma("unroll") for (int m = 0; m < 4; ++m) _Pragma("unroll") for (int k = 0; k < 2; ++k) dst[m][k] = *(const LAS bf16x8*)(lds + PG8_SA(b, h) + aoff + m * 2048 + k * 1024); } while (0)
; #define PG8_LDB(dst, b, h) do { _Pragma("unroll") for (int n = 0; n < 2; ++n) _Pragma("unroll") for (int k = 0; k < 2; ++k) dst[n][k] = *(const LAS bf16x8*)(lds + PG8_SB(b, h) + boff + n * 2048 + k * 1024); } while (0)
; #define PG8_MMA(ai, bj, At, Bt) do { __builtin_amdgcn_s_setprio(1); _Pragma("unroll") for (int m = 0; m < 4; ++m) _Pragma("unroll") for (int n = 0; n < 2; ++n) _Pragma("unroll") for (int k = 0; k < 2; ++k) \
;         acc[ai][bj][m][n] = __builtin_amdgcn_mfma_f32_16x16x32_bf16(Bt[n][k], At[m][k], acc[ai][bj][m][n], 0, 0, 0); __builtin_amdgcn_s_setprio(0); } while (0)
; #define PG8_WAIT_L(n) asm volatile("s_waitcnt lgkmcnt(" #n ")" ::: "memory")
; #define PG8_BAR __builtin_amdgcn_s_barrier()
; #define PG8_SCHED __builtin_amdgcn_sched_barrier(0)
; template <class Epi>
; __device__ __forceinline__ void gemm_phase(LAS unsigned char* lds, const Gemm g, const Sched& S, const Epi& E) {
;     ...
;             PG8_LDB(B0, 0, 0); PG8_SCHED; PG8_LDA(At, 0, 0); PG8_STAGE(PG8_SA(1, 1), a1 + hstepA, voffA);
;             PG8_WAIT_L(8); PG8_BAR; PG8_WAIT_L(0); PG8_MMA(0, 0, At, B0); PG8_BAR; PG8_SCHED;
;             PG8_LDB(B1, 0, 1); PG8_STAGE(PG8_SB(0, 0), b2, voffB);
;             PG8_BAR; PG8_WAIT_L(0); PG8_MMA(0, 1, At, B1); PG8_BAR;
;             PG8_LDA(At, 0, 1); PG8_STAGE(PG8_SA(0, 0), a2, voffA);
;             PG8_BAR; PG8_WAIT_L(0); PG8_MMA(1, 0, At, B0); PG8_BAR; PG8_SCHED;
.LBB0_2710:
	ds_read_b128 v[152:155], v149
	ds_read_b128 v[156:159], v149 offset:1024
	ds_read_b128 v[160:163], v149 offset:2048
	ds_read_b128 v[164:167], v149 offset:3072
	s_add_u32 s38, s36, 0xfffe0080
	s_addc_u32 s39, s37, -1
	s_cmp_eq_u32 s75, 4
	s_cselect_b32 s47, s15, s39
	s_cselect_b32 s46, s25, s38
	s_cselect_b32 s39, s13, s74
	s_cselect_b32 s38, s70, s71
	v_lshl_add_u64 v[202:203], s[36:37], 0, v[138:139]
	s_add_i32 m0, s35, 0xc000
	ds_read_b128 v[168:171], v150
	ds_read_b128 v[172:175], v150 offset:1024
	ds_read_b128 v[176:179], v150 offset:2048
	ds_read_b128 v[180:183], v150 offset:3072
	ds_read_b128 v[184:187], v150 offset:4096
	ds_read_b128 v[188:191], v150 offset:5120
	ds_read_b128 v[194:197], v150 offset:6144
	ds_read_b128 v[198:201], v150 offset:7168
	global_load_lds_dwordx4 v[202:203], off
	v_lshl_add_u64 v[202:203], s[36:37], 0, v[140:141]
	s_add_i32 m0, s35, 0xe000
	s_nop 0
	global_load_lds_dwordx4 v[202:203], off
	s_waitcnt lgkmcnt(8)
	s_barrier
	s_waitcnt lgkmcnt(0)
	s_setprio 1
	s_waitcnt lgkmcnt(0)
	v_mfma_f32_16x16x32_bf16 v[124:127], v[152:155], v[168:171], v[124:127]
	v_mfma_f32_16x16x32_bf16 v[120:123], v[160:163], v[168:171], v[120:123]
	v_mfma_f32_16x16x32_bf16 v[112:115], v[152:155], v[176:179], v[112:115]
	v_mfma_f32_16x16x32_bf16 v[104:107], v[160:163], v[176:179], v[104:107]
	v_mfma_f32_16x16x32_bf16 v[96:99], v[152:155], v[184:187], v[96:99]
	v_mfma_f32_16x16x32_bf16 v[88:91], v[160:163], v[184:187], v[88:91]
	v_mfma_f32_16x16x32_bf16 v[80:83], v[152:155], v[194:197], v[80:83]
	v_mfma_f32_16x16x32_bf16 v[72:75], v[160:163], v[194:197], v[72:75]
	v_mfma_f32_16x16x32_bf16 v[124:127], v[156:159], v[172:175], v[124:127]
	v_mfma_f32_16x16x32_bf16 v[120:123], v[164:167], v[172:175], v[120:123]
	v_mfma_f32_16x16x32_bf16 v[112:115], v[156:159], v[180:183], v[112:115]
	v_mfma_f32_16x16x32_bf16 v[104:107], v[164:167], v[180:183], v[104:107]
	v_mfma_f32_16x16x32_bf16 v[96:99], v[156:159], v[188:191], v[96:99]
	v_mfma_f32_16x16x32_bf16 v[88:91], v[164:167], v[188:191], v[88:91]
	v_mfma_f32_16x16x32_bf16 v[80:83], v[156:159], v[198:201], v[80:83]
	s_barrier
	v_mfma_f32_16x16x32_bf16 v[72:75], v[164:167], v[198:201], v[72:75]
	s_setprio 0
	s_add_i32 s76, s61, s1
	v_lshl_add_u64 v[218:219], s[38:39], 0, v[128:129]
	s_mov_b32 m0, s76
	ds_read_b128 v[202:205], v151
	ds_read_b128 v[206:209], v151 offset:1024
	ds_read_b128 v[210:213], v151 offset:2048
	ds_read_b128 v[214:217], v151 offset:3072
	global_load_lds_dwordx4 v[218:219], off
	v_lshl_add_u64 v[220:221], s[38:39], 0, v[130:131]
	s_add_i32 m0, s76, 0x2000
	s_nop 0
	global_load_lds_dwordx4 v[220:221], off
	s_barrier
	s_waitcnt lgkmcnt(0)
	s_setprio 1
	s_waitcnt lgkmcnt(0)
	v_mfma_f32_16x16x32_bf16 v[116:119], v[202:205], v[168:171], v[116:119]
	v_mfma_f32_16x16x32_bf16 v[108:111], v[210:213], v[168:171], v[108:111]
	v_mfma_f32_16x16x32_bf16 v[100:103], v[202:205], v[176:179], v[100:103]
	v_mfma_f32_16x16x32_bf16 v[92:95], v[210:213], v[176:179], v[92:95]
	v_mfma_f32_16x16x32_bf16 v[84:87], v[202:205], v[184:187], v[84:87]
	v_mfma_f32_16x16x32_bf16 v[76:79], v[210:213], v[184:187], v[76:79]
	v_mfma_f32_16x16x32_bf16 v[68:71], v[202:205], v[194:197], v[68:71]
	v_mfma_f32_16x16x32_bf16 v[64:67], v[210:213], v[194:197], v[64:67]
	v_mfma_f32_16x16x32_bf16 v[116:119], v[206:209], v[172:175], v[116:119]
	v_mfma_f32_16x16x32_bf16 v[108:111], v[214:217], v[172:175], v[108:111]
	v_mfma_f32_16x16x32_bf16 v[100:103], v[206:209], v[180:183], v[100:103]
	v_mfma_f32_16x16x32_bf16 v[92:95], v[214:217], v[180:183], v[92:95]
	v_mfma_f32_16x16x32_bf16 v[84:87], v[206:209], v[188:191], v[84:87]
	v_mfma_f32_16x16x32_bf16 v[76:79], v[214:217], v[188:191], v[76:79]
	v_mfma_f32_16x16x32_bf16 v[68:71], v[206:209], v[198:201], v[68:71]
	s_barrier
	v_mfma_f32_16x16x32_bf16 v[64:67], v[214:217], v[198:201], v[64:67]
	s_setprio 0
	s_mov_b32 m0, s35
	v_lshl_add_u64 v[222:223], s[46:47], 0, v[128:129]
	ds_read_b128 v[168:171], v150 offset:16384
	ds_read_b128 v[172:175], v150 offset:17408
	ds_read_b128 v[176:179], v150 offset:18432
	ds_read_b128 v[180:183], v150 offset:19456
	ds_read_b128 v[184:187], v150 offset:20480
	ds_read_b128 v[188:191], v150 offset:21504
	ds_read_b128 v[194:197], v150 offset:22528
	ds_read_b128 v[198:201], v150 offset:23552
	global_load_lds_dwordx4 v[222:223], off
	v_lshl_add_u64 v[224:225], s[46:47], 0, v[130:131]
	s_mov_b32 m0, s43
	s_nop 0
	global_load_lds_dwordx4 v[224:225], off
	s_barrier
	s_waitcnt lgkmcnt(0)
	s_setprio 1
	s_waitcnt lgkmcnt(0)
	v_mfma_f32_16x16x32_bf16 v[60:63], v[152:155], v[168:171], v[60:63]
	v_mfma_f32_16x16x32_bf16 v[56:59], v[160:163], v[168:171], v[56:59]
	v_mfma_f32_16x16x32_bf16 v[48:51], v[152:155], v[176:179], v[48:51]
	v_mfma_f32_16x16x32_bf16 v[40:43], v[160:163], v[176:179], v[40:43]
	v_mfma_f32_16x16x32_bf16 v[32:35], v[152:155], v[184:187], v[32:35]
	v_mfma_f32_16x16x32_bf16 v[24:27], v[160:163], v[184:187], v[24:27]
	v_mfma_f32_16x16x32_bf16 v[16:19], v[152:155], v[194:197], v[16:19]
	v_mfma_f32_16x16x32_bf16 v[8:11], v[160:163], v[194:197], v[8:11]
	v_mfma_f32_16x16x32_bf16 v[60:63], v[156:159], v[172:175], v[60:63]
	v_mfma_f32_16x16x32_bf16 v[56:59], v[164:167], v[172:175], v[56:59]
	v_mfma_f32_16x16x32_bf16 v[48:51], v[156:159], v[180:183], v[48:51]
	v_mfma_f32_16x16x32_bf16 v[40:43], v[164:167], v[180:183], v[40:43]
	v_mfma_f32_16x16x32_bf16 v[32:35], v[156:159], v[188:191], v[32:35]
	v_mfma_f32_16x16x32_bf16 v[24:27], v[164:167], v[188:191], v[24:27]
	v_mfma_f32_16x16x32_bf16 v[16:19], v[156:159], v[198:201], v[16:19]
	s_barrier
; #define PG8_STAGE(bufoff, gbase, voff) do { _Pragma("unroll") for (int _i = 0; _i < 2; ++_i) \
;         __builtin_amdgcn_global_load_lds((const unsigned*)((const char*)(gbase) + (voff)[_i]), (LAS unsigned*)(lds + (bufoff) + ldsw + _i * 8192), 16, 0, 0); } while (0)
; #define PG8_LDA(dst, b, h) do { _Pragma("unroll") for (int m = 0; m < 4; ++m) _Pragma("unroll") for (int k = 0; k < 2; ++k) dst[m][k] = *(const LAS bf16x8*)(lds + PG8_SA(b, h) + aoff + m * 2048 + k * 1024); } while (0)
; #define PG8_LDB(dst, b, h) do { _Pragma("unroll") for (int n = 0; n < 2; ++n) _Pragma("unroll") for (int k = 0; k < 2; ++k) dst[n][k] = *(const LAS bf16x8*)(lds + PG8_SB(b, h) + boff + n * 2048 + k * 1024); } while (0)
; #define PG8_WAIT_V(n) asm volatile("s_waitcnt vmcnt(" #n ")" ::: "memory")
; #define PG8_WAIT_L(n) asm volatile("s_waitcnt lgkmcnt(" #n ")" ::: "memory")
; #define PG8_BAR __builtin_amdgcn_s_barrier()
; #define PG8_SCHED __builtin_amdgcn_sched_barrier(0)
; template <class Epi>
; __device__ __forceinline__ void gemm_phase(LAS unsigned char* lds, const Gemm g, const Sched& S, const Epi& E) {
;     ...
;             PG8_LDB(B0, 0, 0); PG8_SCHED; PG8_LDA(At, 0, 0); PG8_STAGE(PG8_SA(1, 1), a1 + hstepA, voffA);
;             PG8_WAIT_L(8); PG8_BAR; PG8_WAIT_L(0); PG8_MMA(0, 0, At, B0); PG8_BAR; PG8_SCHED;
;             PG8_LDB(B1, 0, 1); PG8_STAGE(PG8_SB(0, 0), b2, voffB);
;             PG8_BAR; PG8_WAIT_L(0); PG8_MMA(0, 1, At, B1); PG8_BAR;
;             PG8_LDA(At, 0, 1); PG8_STAGE(PG8_SA(0, 0), a2, voffA);
;             PG8_BAR; PG8_WAIT_L(0); PG8_MMA(1, 0, At, B0); PG8_BAR; PG8_SCHED;
;             PG8_STAGE(PG8_SB(0, 1), b2 + hstepB, voffB);
;             PG8_WAIT_V(6); PG8_BAR; PG8_MMA(1, 1, At, B1); PG8_BAR;
;             PG8_LDB(B0, 1, 0); PG8_SCHED; PG8_LDA(At, 1, 0); PG8_STAGE(PG8_SA(0, 1), a2 + hstepA, voffA);
;             PG8_WAIT_L(8); PG8_BAR; PG8_WAIT_L(0); PG8_MMA(0, 0, At, B0); PG8_BAR; PG8_SCHED;
;             PG8_LDB(B1, 1, 1); PG8_STAGE(PG8_SB(1, 0), b3, voffB);
;             PG8_BAR; PG8_WAIT_L(0); PG8_MMA(0, 1, At, B1); PG8_BAR;
;             PG8_LDA(At, 1, 1); PG8_STAGE(PG8_SA(1, 0), a3, voffA);
;             PG8_BAR; PG8_WAIT_L(0); PG8_MMA(1, 0, At, B0); PG8_BAR; PG8_SCHED;
;             PG8_STAGE(PG8_SB(1, 1), b3 + hstepB, voffB);
;             PG8_WAIT_V(6); PG8_BAR; PG8_MMA(1, 1, At, B1); PG8_BAR;
	v_mfma_f32_16x16x32_bf16 v[8:11], v[164:167], v[198:201], v[8:11]
	s_setprio 0
	s_add_u32 s76, s38, 0x20000
	s_addc_u32 s77, s39, 0
	s_add_i32 s78, s62, s1
	v_lshl_add_u64 v[152:153], s[76:77], 0, v[128:129]
	s_mov_b32 m0, s78
	s_nop 0
	global_load_lds_dwordx4 v[152:153], off
	v_lshl_add_u64 v[152:153], s[76:77], 0, v[130:131]
	s_add_i32 m0, s78, 0x2000
	s_nop 0
	global_load_lds_dwordx4 v[152:153], off
	s_waitcnt vmcnt(6)
	s_barrier
	s_setprio 1
	v_mfma_f32_16x16x32_bf16 v[52:55], v[202:205], v[168:171], v[52:55]
	v_mfma_f32_16x16x32_bf16 v[44:47], v[210:213], v[168:171], v[44:47]
	v_mfma_f32_16x16x32_bf16 v[36:39], v[202:205], v[176:179], v[36:39]
	v_mfma_f32_16x16x32_bf16 v[28:31], v[210:213], v[176:179], v[28:31]
	v_mfma_f32_16x16x32_bf16 v[20:23], v[202:205], v[184:187], v[20:23]
	v_mfma_f32_16x16x32_bf16 v[12:15], v[210:213], v[184:187], v[12:15]
	v_mfma_f32_16x16x32_bf16 v[4:7], v[202:205], v[194:197], v[4:7]
	v_mfma_f32_16x16x32_bf16 v[0:3], v[210:213], v[194:197], v[0:3]
	v_mfma_f32_16x16x32_bf16 v[52:55], v[206:209], v[172:175], v[52:55]
	v_mfma_f32_16x16x32_bf16 v[44:47], v[214:217], v[172:175], v[44:47]
	v_mfma_f32_16x16x32_bf16 v[36:39], v[206:209], v[180:183], v[36:39]
	v_mfma_f32_16x16x32_bf16 v[28:31], v[214:217], v[180:183], v[28:31]
	v_mfma_f32_16x16x32_bf16 v[20:23], v[206:209], v[188:191], v[20:23]
	v_mfma_f32_16x16x32_bf16 v[12:15], v[214:217], v[188:191], v[12:15]
	v_mfma_f32_16x16x32_bf16 v[4:7], v[206:209], v[198:201], v[4:7]
	s_barrier
	v_mfma_f32_16x16x32_bf16 v[0:3], v[214:217], v[198:201], v[0:3]
	s_setprio 0
	s_add_i32 s76, 0, 0x18000
	v_add_u32_e32 v164, s76, v147
	ds_read_b128 v[152:155], v164
	ds_read_b128 v[156:159], v164 offset:1024
	ds_read_b128 v[160:163], v164 offset:2048
	ds_read_b128 v[164:167], v164 offset:3072
	s_add_u32 s46, s46, 0x20000
	s_addc_u32 s47, s47, 0
	s_mov_b32 m0, s50
	v_lshl_add_u64 v[202:203], s[46:47], 0, v[128:129]
	ds_read_b128 v[168:171], v150 offset:32768
	ds_read_b128 v[172:175], v150 offset:33792
	ds_read_b128 v[176:179], v150 offset:34816
	ds_read_b128 v[180:183], v150 offset:35840
	ds_read_b128 v[184:187], v150 offset:36864
	ds_read_b128 v[188:191], v150 offset:37888
	ds_read_b128 v[194:197], v150 offset:38912
	ds_read_b128 v[198:201], v150 offset:39936
	global_load_lds_dwordx4 v[202:203], off
	v_lshl_add_u64 v[202:203], s[46:47], 0, v[130:131]
	s_mov_b32 m0, s51
	s_nop 0
	global_load_lds_dwordx4 v[202:203], off
	s_waitcnt lgkmcnt(8)
	s_barrier
	s_waitcnt lgkmcnt(0)
	s_setprio 1
	s_waitcnt lgkmcnt(0)
	v_mfma_f32_16x16x32_bf16 v[124:127], v[152:155], v[168:171], v[124:127]
	v_mfma_f32_16x16x32_bf16 v[120:123], v[160:163], v[168:171], v[120:123]
	v_mfma_f32_16x16x32_bf16 v[112:115], v[152:155], v[176:179], v[112:115]
	v_mfma_f32_16x16x32_bf16 v[104:107], v[160:163], v[176:179], v[104:107]
	v_mfma_f32_16x16x32_bf16 v[96:99], v[152:155], v[184:187], v[96:99]
	v_mfma_f32_16x16x32_bf16 v[88:91], v[160:163], v[184:187], v[88:91]
	v_mfma_f32_16x16x32_bf16 v[80:83], v[152:155], v[194:197], v[80:83]
	v_mfma_f32_16x16x32_bf16 v[72:75], v[160:163], v[194:197], v[72:75]
	v_mfma_f32_16x16x32_bf16 v[124:127], v[156:159], v[172:175], v[124:127]
	v_mfma_f32_16x16x32_bf16 v[120:123], v[164:167], v[172:175], v[120:123]
	v_mfma_f32_16x16x32_bf16 v[112:115], v[156:159], v[180:183], v[112:115]
	v_mfma_f32_16x16x32_bf16 v[104:107], v[164:167], v[180:183], v[104:107]
	v_mfma_f32_16x16x32_bf16 v[96:99], v[156:159], v[188:191], v[96:99]
	v_mfma_f32_16x16x32_bf16 v[88:91], v[164:167], v[188:191], v[88:91]
	v_mfma_f32_16x16x32_bf16 v[80:83], v[156:159], v[198:201], v[80:83]
	s_barrier
	v_mfma_f32_16x16x32_bf16 v[72:75], v[164:167], v[198:201], v[72:75]
	s_setprio 0
	s_add_i32 s46, 0, 0x1c000
	s_add_i32 s47, s76, s1
	v_add_u32_e32 v214, s46, v147
	v_lshl_add_u64 v[218:219], v[218:219], 0, s[10:11]
	s_mov_b32 m0, s47
	ds_read_b128 v[202:205], v214
	ds_read_b128 v[206:209], v214 offset:1024
	ds_read_b128 v[210:213], v214 offset:2048
	ds_read_b128 v[214:217], v214 offset:3072
	global_load_lds_dwordx4 v[218:219], off
	v_lshl_add_u64 v[218:219], v[220:221], 0, s[10:11]
	s_add_i32 m0, s47, 0x2000
	s_nop 0
	global_load_lds_dwordx4 v[218:219], off
	s_barrier
	s_waitcnt lgkmcnt(0)
	s_setprio 1
	s_waitcnt lgkmcnt(0)
	v_mfma_f32_16x16x32_bf16 v[116:119], v[202:205], v[168:171], v[116:119]
	v_mfma_f32_16x16x32_bf16 v[108:111], v[210:213], v[168:171], v[108:111]
	v_mfma_f32_16x16x32_bf16 v[100:103], v[202:205], v[176:179], v[100:103]
	v_mfma_f32_16x16x32_bf16 v[92:95], v[210:213], v[176:179], v[92:95]
	v_mfma_f32_16x16x32_bf16 v[84:87], v[202:205], v[184:187], v[84:87]
	v_mfma_f32_16x16x32_bf16 v[76:79], v[210:213], v[184:187], v[76:79]
	v_mfma_f32_16x16x32_bf16 v[68:71], v[202:205], v[194:197], v[68:71]
	v_mfma_f32_16x16x32_bf16 v[64:67], v[210:213], v[194:197], v[64:67]
	v_mfma_f32_16x16x32_bf16 v[116:119], v[206:209], v[172:175], v[116:119]
	v_mfma_f32_16x16x32_bf16 v[108:111], v[214:217], v[172:175], v[108:111]
	v_mfma_f32_16x16x32_bf16 v[100:103], v[206:209], v[180:183], v[100:103]
	v_mfma_f32_16x16x32_bf16 v[92:95], v[214:217], v[180:183], v[92:95]
	v_mfma_f32_16x16x32_bf16 v[84:87], v[206:209], v[188:191], v[84:87]
	v_mfma_f32_16x16x32_bf16 v[76:79], v[214:217], v[188:191], v[76:79]
	v_mfma_f32_16x16x32_bf16 v[68:71], v[206:209], v[198:201], v[68:71]
	s_barrier
	v_mfma_f32_16x16x32_bf16 v[64:67], v[214:217], v[198:201], v[64:67]
	s_setprio 0
	s_mov_b32 m0, s55
	v_lshl_add_u64 v[218:219], v[222:223], 0, s[10:11]
	ds_read_b128 v[168:171], v150 offset:49152
	ds_read_b128 v[172:175], v150 offset:50176
	ds_read_b128 v[176:179], v150 offset:51200
	ds_read_b128 v[180:183], v150 offset:52224
	ds_read_b128 v[184:187], v150 offset:53248
	ds_read_b128 v[188:191], v150 offset:54272
	ds_read_b128 v[194:197], v150 offset:55296
	ds_read_b128 v[198:201], v150 offset:56320
	global_load_lds_dwordx4 v[218:219], off
	v_lshl_add_u64 v[218:219], v[224:225], 0, s[10:11]
	s_mov_b32 m0, s56
	s_nop 0
	global_load_lds_dwordx4 v[218:219], off
	s_barrier
; #define PG8_STAGE(bufoff, gbase, voff) do { _Pragma("unroll") for (int _i = 0; _i < 2; ++_i) \
;         __builtin_amdgcn_global_load_lds((const unsigned*)((const char*)(gbase) + (voff)[_i]), (LAS unsigned*)(lds + (bufoff) + ldsw + _i * 8192), 16, 0, 0); } while (0)
; #define PG8_LDA(dst, b, h) do { _Pragma("unroll") for (int m = 0; m < 4; ++m) _Pragma("unroll") for (int k = 0; k < 2; ++k) dst[m][k] = *(const LAS bf16x8*)(lds + PG8_SA(b, h) + aoff + m * 2048 + k * 1024); } while (0)
; #define PG8_LDB(dst, b, h) do { _Pragma("unroll") for (int n = 0; n < 2; ++n) _Pragma("unroll") for (int k = 0; k < 2; ++k) dst[n][k] = *(const LAS bf16x8*)(lds + PG8_SB(b, h) + boff + n * 2048 + k * 1024); } while (0)
; #define PG8_BAR __builtin_amdgcn_s_barrier()
; template <class Epi>
; __device__ __forceinline__ void gemm_phase(LAS unsigned char* lds, const Gemm g, const Sched& S, const Epi& E) {
;     ...
;             PG8_WAIT_V(6); PG8_BAR; PG8_MMA(1, 1, At, B1); PG8_BAR;
;             PG8_LDB(B0, 1, 0); PG8_SCHED; PG8_LDA(At, 1, 0); PG8_STAGE(PG8_SA(0, 1), a2 + hstepA, voffA);
;             PG8_WAIT_L(8); PG8_BAR; PG8_WAIT_L(0); PG8_MMA(0, 0, At, B0); PG8_BAR; PG8_SCHED;
;             PG8_LDB(B1, 1, 1); PG8_STAGE(PG8_SB(1, 0), b3, voffB);
;             PG8_BAR; PG8_WAIT_L(0); PG8_MMA(0, 1, At, B1); PG8_BAR;
;             PG8_LDA(At, 1, 1); PG8_STAGE(PG8_SA(1, 0), a3, voffA);
;             PG8_BAR; PG8_WAIT_L(0); PG8_MMA(1, 0, At, B0); PG8_BAR; PG8_SCHED;
;             PG8_STAGE(PG8_SB(1, 1), b3 + hstepB, voffB);
;             PG8_WAIT_V(6); PG8_BAR; PG8_MMA(1, 1, At, B1); PG8_BAR;
;     __device__ __forceinline__ void operator()(AccRef acc, const Unit& u, int wr, int wc, int fr, int fq) const {
;         const int hd = u.pn;
; #pragma unroll
;         for (int ai = 0; ai < 2; ++ai)
; #pragma unroll
;             for (int m = 0; m < 4; ++m) { const int row = u.pm * 256 + ai * 128 + wr * 64 + m * 16 + fr; const int b = row >> 14, s = row & (S_ - 1);
; #pragma unroll
;                 for (int n = 0; n < 2; ++n) { const int p0 = wc * 32 + n * 16 + 4 * fq;
;                     st_bf4(KN + (size_t)row * 2048 + hd * 128 + p0, acc[ai][0][m][n]);
;                     const f32x4 v = acc[ai][1][m][n]; bf16_t* base = VT + ((size_t)(b * 16 + hd) * 128 + p0) * S_ + kperm(s);
; #pragma unroll
;                     for (int j = 0; j < 4; ++j) base[(size_t)j * S_] = f2bf(v[j]); } }
	s_waitcnt lgkmcnt(0)
	s_setprio 1
	s_waitcnt lgkmcnt(0)
	v_mfma_f32_16x16x32_bf16 v[60:63], v[152:155], v[168:171], v[60:63]
	v_mfma_f32_16x16x32_bf16 v[56:59], v[160:163], v[168:171], v[56:59]
	v_mfma_f32_16x16x32_bf16 v[48:51], v[152:155], v[176:179], v[48:51]
	v_mfma_f32_16x16x32_bf16 v[40:43], v[160:163], v[176:179], v[40:43]
	v_mfma_f32_16x16x32_bf16 v[32:35], v[152:155], v[184:187], v[32:35]
	v_mfma_f32_16x16x32_bf16 v[24:27], v[160:163], v[184:187], v[24:27]
	v_mfma_f32_16x16x32_bf16 v[16:19], v[152:155], v[194:197], v[16:19]
	v_mfma_f32_16x16x32_bf16 v[8:11], v[160:163], v[194:197], v[8:11]
	v_mfma_f32_16x16x32_bf16 v[60:63], v[156:159], v[172:175], v[60:63]
	v_mfma_f32_16x16x32_bf16 v[56:59], v[164:167], v[172:175], v[56:59]
	v_mfma_f32_16x16x32_bf16 v[48:51], v[156:159], v[180:183], v[48:51]
	v_mfma_f32_16x16x32_bf16 v[40:43], v[164:167], v[180:183], v[40:43]
	v_mfma_f32_16x16x32_bf16 v[32:35], v[156:159], v[188:191], v[32:35]
	v_mfma_f32_16x16x32_bf16 v[24:27], v[164:167], v[188:191], v[24:27]
	v_mfma_f32_16x16x32_bf16 v[16:19], v[156:159], v[198:201], v[16:19]
	s_barrier
	v_mfma_f32_16x16x32_bf16 v[8:11], v[164:167], v[198:201], v[8:11]
	s_setprio 0
	s_add_u32 s38, s38, 0x20080
	s_addc_u32 s39, s39, 0
	s_add_i32 s46, s46, s1
	v_lshl_add_u64 v[152:153], s[38:39], 0, v[128:129]
	s_mov_b32 m0, s46
	s_nop 0
	global_load_lds_dwordx4 v[152:153], off
	v_lshl_add_u64 v[152:153], s[38:39], 0, v[130:131]
	s_add_i32 m0, s46, 0x2000
	s_nop 0
	global_load_lds_dwordx4 v[152:153], off
	s_waitcnt vmcnt(6)
	s_barrier
	s_setprio 1
	v_mfma_f32_16x16x32_bf16 v[52:55], v[202:205], v[168:171], v[52:55]
	v_mfma_f32_16x16x32_bf16 v[44:47], v[210:213], v[168:171], v[44:47]
	v_mfma_f32_16x16x32_bf16 v[36:39], v[202:205], v[176:179], v[36:39]
	v_mfma_f32_16x16x32_bf16 v[28:31], v[210:213], v[176:179], v[28:31]
	v_mfma_f32_16x16x32_bf16 v[20:23], v[202:205], v[184:187], v[20:23]
	v_mfma_f32_16x16x32_bf16 v[12:15], v[210:213], v[184:187], v[12:15]
	v_mfma_f32_16x16x32_bf16 v[4:7], v[202:205], v[194:197], v[4:7]
	v_mfma_f32_16x16x32_bf16 v[0:3], v[210:213], v[194:197], v[0:3]
	v_mfma_f32_16x16x32_bf16 v[52:55], v[206:209], v[172:175], v[52:55]
	v_mfma_f32_16x16x32_bf16 v[44:47], v[214:217], v[172:175], v[44:47]
	v_mfma_f32_16x16x32_bf16 v[36:39], v[206:209], v[180:183], v[36:39]
	v_mfma_f32_16x16x32_bf16 v[28:31], v[214:217], v[180:183], v[28:31]
	v_mfma_f32_16x16x32_bf16 v[20:23], v[206:209], v[188:191], v[20:23]
	v_mfma_f32_16x16x32_bf16 v[12:15], v[214:217], v[188:191], v[12:15]
	v_mfma_f32_16x16x32_bf16 v[4:7], v[206:209], v[198:201], v[4:7]
	s_barrier
	v_mfma_f32_16x16x32_bf16 v[0:3], v[214:217], v[198:201], v[0:3]
	s_setprio 0
	s_add_i32 s75, s75, 2
	s_add_u32 s36, s36, 0x100
	s_addc_u32 s37, s37, 0
	s_add_u32 s71, s71, 0x100
	s_addc_u32 s74, s74, 0
	s_cmp_gt_u32 s75, 5
	s_cbranch_scc0 .LBB0_2710
	s_lshl_b32 s13, s24, 8
	s_add_i32 s13, s13, s54
	v_or_b32_e32 v152, s13, v146
	s_lshl_b32 s24, s67, 7
	s_ashr_i32 s15, s13, 10
	v_ashrrev_i32_e32 v153, 31, v152
	s_ashr_i32 s25, s24, 31
	s_and_b32 s15, s15, -16
	v_lshlrev_b64 v[154:155], 12, v[152:153]
	s_add_i32 s36, s15, s67
	v_lshl_add_u64 v[154:155], s[44:45], 0, v[154:155]
	s_lshl_b64 s[24:25], s[24:25], 1
	s_ashr_i32 s37, s36, 31
	v_lshl_add_u64 v[154:155], v[154:155], 0, s[24:25]
	v_and_or_b32 v153, v152, s63, v148
	v_lshl_add_u64 v[154:155], v[154:155], 0, v[132:133]
	v_cvt_pk_bf16_f32 v124, v124, v125
	v_cvt_pk_bf16_f32 v125, v126, v127
	s_lshl_b64 s[36:37], s[36:37], 22
	global_store_dwordx2 v[154:155], v[124:125], off
	v_lshl_add_u64 v[124:125], v[134:135], 0, s[36:37]
	v_lshlrev_b32_e32 v126, 1, v153
	v_mov_b32_e32 v127, v133
	v_lshl_add_u64 v[156:157], v[124:125], 0, v[126:127]
	v_cvt_pk_bf16_f32 v116, v116, v133
	global_store_short v[156:157], v116, off
	v_add_co_u32_e32 v116, vcc, s58, v156
	v_cvt_pk_bf16_f32 v153, v117, v133
	s_addk_i32 s13, 0x80
	s_nop 0
	v_addc_co_u32_e32 v117, vcc, 0, v157, vcc
	global_store_short v[116:117], v153, off
	v_add_co_u32_e32 v116, vcc, s53, v156
	v_cvt_pk_bf16_f32 v118, v118, v133
	s_mov_b64 s[38:39], s[18:19]
	s_nop 0
	v_addc_co_u32_e32 v117, vcc, 0, v157, vcc
	global_store_short v[116:117], v118, off
	v_add_co_u32_e32 v116, vcc, s57, v156
	v_cvt_pk_bf16_f32 v118, v119, v133
	s_nop 1
	v_addc_co_u32_e32 v117, vcc, 0, v157, vcc
	global_store_short v[116:117], v118, off
	v_cvt_pk_bf16_f32 v116, v120, v121
	v_cvt_pk_bf16_f32 v117, v122, v123
	global_store_dwordx2 v[154:155], v[116:117], off offset:32
	v_lshl_add_u64 v[116:117], v[136:137], 0, s[36:37]
	v_lshl_add_u64 v[118:119], v[116:117], 0, v[126:127]
	v_cvt_pk_bf16_f32 v108, v108, v133
	global_store_short v[118:119], v108, off
	v_add_co_u32_e32 v108, vcc, s58, v118
	v_cvt_pk_bf16_f32 v120, v109, v133
	s_nop 1
	v_addc_co_u32_e32 v109, vcc, 0, v119, vcc
	global_store_short v[108:109], v120, off
	v_add_co_u32_e32 v108, vcc, s53, v118
	v_cvt_pk_bf16_f32 v110, v110, v133
	s_nop 1
	v_addc_co_u32_e32 v109, vcc, 0, v119, vcc
	global_store_short v[108:109], v110, off
	v_add_co_u32_e32 v108, vcc, s57, v118
	v_cvt_pk_bf16_f32 v110, v111, v133
	s_nop 1
	v_addc_co_u32_e32 v109, vcc, 0, v119, vcc
	global_store_short v[108:109], v110, off
	v_or_b32_e32 v108, 16, v152
	v_ashrrev_i32_e32 v109, 31, v108
	v_lshlrev_b64 v[110:111], 12, v[108:109]
	v_and_or_b32 v118, v108, s64, v148
	v_lshl_add_u64 v[108:109], s[44:45], 0, v[110:111]
	v_lshl_add_u64 v[108:109], v[108:109], 0, s[24:25]
	v_lshl_add_u64 v[108:109], v[108:109], 0, v[132:133]
	v_cvt_pk_bf16_f32 v110, v112, v113
	v_cvt_pk_bf16_f32 v111, v114, v115
	global_store_dwordx2 v[108:109], v[110:111], off
	v_lshlrev_b32_e32 v110, 1, v118
	v_mov_b32_e32 v111, v133
; __device__ __forceinline__ void st_bf4(bf16_t* p, const f32x4 v) { u32x2 w; w.x = cvt_pk_bf16(v[0], v[1]); w.y = cvt_pk_bf16(v[2], v[3]); *(u32x2*)p = w; }
; __device__ __forceinline__ int kperm(int s) { return (s & ~12) | ((s & 4) << 1) | ((s & 8) >> 1); }
; __device__ __forceinline__ bf16_t f2bf(float f) { return (bf16_t)(cvt_pk_bf16(f, 0.f) & 0xffffu); }
;     __device__ __forceinline__ void operator()(AccRef acc, const Unit& u, int wr, int wc, int fr, int fq) const {
;         const int hd = u.pn;
; #pragma unroll
;         for (int ai = 0; ai < 2; ++ai)
; #pragma unroll
;             for (int m = 0; m < 4; ++m) { const int row = u.pm * 256 + ai * 128 + wr * 64 + m * 16 + fr; const int b = row >> 14, s = row & (S_ - 1);
; #pragma unroll
;                 for (int n = 0; n < 2; ++n) { const int p0 = wc * 32 + n * 16 + 4 * fq;
;                     st_bf4(KN + (size_t)row * 2048 + hd * 128 + p0, acc[ai][0][m][n]);
;                     const f32x4 v = acc[ai][1][m][n]; bf16_t* base = VT + ((size_t)(b * 16 + hd) * 128 + p0) * S_ + kperm(s);
; #pragma unroll
;                     for (int j = 0; j < 4; ++j) base[(size_t)j * S_] = f2bf(v[j]); } }
	v_lshl_add_u64 v[112:113], v[124:125], 0, v[110:111]
	v_cvt_pk_bf16_f32 v100, v100, v133
	global_store_short v[112:113], v100, off
	v_add_co_u32_e32 v100, vcc, s58, v112
	v_cvt_pk_bf16_f32 v114, v101, v133
	s_nop 1
	v_addc_co_u32_e32 v101, vcc, 0, v113, vcc
	global_store_short v[100:101], v114, off
	v_add_co_u32_e32 v100, vcc, s53, v112
	v_cvt_pk_bf16_f32 v102, v102, v133
	s_nop 1
	v_addc_co_u32_e32 v101, vcc, 0, v113, vcc
	global_store_short v[100:101], v102, off
	v_add_co_u32_e32 v100, vcc, s57, v112
	v_cvt_pk_bf16_f32 v102, v103, v133
	s_nop 1
	v_addc_co_u32_e32 v101, vcc, 0, v113, vcc
	global_store_short v[100:101], v102, off
	v_cvt_pk_bf16_f32 v100, v104, v105
	v_cvt_pk_bf16_f32 v101, v106, v107
	global_store_dwordx2 v[108:109], v[100:101], off offset:32
	v_lshl_add_u64 v[100:101], v[116:117], 0, v[110:111]
	v_cvt_pk_bf16_f32 v92, v92, v133
	global_store_short v[100:101], v92, off
	v_add_co_u32_e32 v92, vcc, s58, v100
	v_cvt_pk_bf16_f32 v102, v93, v133
	s_nop 1
	v_addc_co_u32_e32 v93, vcc, 0, v101, vcc
	global_store_short v[92:93], v102, off
	v_add_co_u32_e32 v92, vcc, s53, v100
	v_cvt_pk_bf16_f32 v94, v94, v133
	s_nop 1
	v_addc_co_u32_e32 v93, vcc, 0, v101, vcc
	global_store_short v[92:93], v94, off
	v_add_co_u32_e32 v92, vcc, s57, v100
	v_cvt_pk_bf16_f32 v94, v95, v133
	s_nop 1
	v_addc_co_u32_e32 v93, vcc, 0, v101, vcc
	global_store_short v[92:93], v94, off
	v_or_b32_e32 v92, 32, v152
	v_ashrrev_i32_e32 v93, 31, v92
	v_lshlrev_b64 v[94:95], 12, v[92:93]
	v_and_or_b32 v100, v92, s65, v148
	v_lshl_add_u64 v[92:93], s[44:45], 0, v[94:95]
	v_lshl_add_u64 v[92:93], v[92:93], 0, s[24:25]
	v_lshl_add_u64 v[92:93], v[92:93], 0, v[132:133]
	v_cvt_pk_bf16_f32 v94, v96, v97
	v_cvt_pk_bf16_f32 v95, v98, v99
	global_store_dwordx2 v[92:93], v[94:95], off
	v_lshlrev_b32_e32 v94, 1, v100
	v_mov_b32_e32 v95, v133
	v_lshl_add_u64 v[96:97], v[124:125], 0, v[94:95]
	v_cvt_pk_bf16_f32 v84, v84, v133
	global_store_short v[96:97], v84, off
	v_add_co_u32_e32 v84, vcc, s58, v96
	v_cvt_pk_bf16_f32 v98, v85, v133
	s_nop 1
	v_addc_co_u32_e32 v85, vcc, 0, v97, vcc
	global_store_short v[84:85], v98, off
	v_add_co_u32_e32 v84, vcc, s53, v96
	v_cvt_pk_bf16_f32 v86, v86, v133
	s_nop 1
	v_addc_co_u32_e32 v85, vcc, 0, v97, vcc
	global_store_short v[84:85], v86, off
	v_add_co_u32_e32 v84, vcc, s57, v96
	v_cvt_pk_bf16_f32 v86, v87, v133
	s_nop 1
	v_addc_co_u32_e32 v85, vcc, 0, v97, vcc
	global_store_short v[84:85], v86, off
	v_cvt_pk_bf16_f32 v84, v88, v89
	v_cvt_pk_bf16_f32 v85, v90, v91
	global_store_dwordx2 v[92:93], v[84:85], off offset:32
	v_lshl_add_u64 v[84:85], v[116:117], 0, v[94:95]
	v_cvt_pk_bf16_f32 v76, v76, v133
	global_store_short v[84:85], v76, off
	v_add_co_u32_e32 v76, vcc, s58, v84
	v_cvt_pk_bf16_f32 v86, v77, v133
	s_nop 1
	v_addc_co_u32_e32 v77, vcc, 0, v85, vcc
	global_store_short v[76:77], v86, off
	v_add_co_u32_e32 v76, vcc, s53, v84
	v_cvt_pk_bf16_f32 v78, v78, v133
	s_nop 1
	v_addc_co_u32_e32 v77, vcc, 0, v85, vcc
	global_store_short v[76:77], v78, off
	v_add_co_u32_e32 v76, vcc, s57, v84
	v_cvt_pk_bf16_f32 v78, v79, v133
	s_nop 1
	v_addc_co_u32_e32 v77, vcc, 0, v85, vcc
	global_store_short v[76:77], v78, off
	v_or_b32_e32 v76, 48, v152
	v_ashrrev_i32_e32 v77, 31, v76
	v_lshlrev_b64 v[78:79], 12, v[76:77]
	v_and_or_b32 v84, v76, s66, v148
	v_lshl_add_u64 v[76:77], s[44:45], 0, v[78:79]
	v_lshl_add_u64 v[76:77], v[76:77], 0, s[24:25]
	v_lshl_add_u64 v[76:77], v[76:77], 0, v[132:133]
	v_cvt_pk_bf16_f32 v78, v80, v81
	v_cvt_pk_bf16_f32 v79, v82, v83
	global_store_dwordx2 v[76:77], v[78:79], off
	v_lshlrev_b32_e32 v78, 1, v84
	v_mov_b32_e32 v79, v133
	v_lshl_add_u64 v[80:81], v[124:125], 0, v[78:79]
	v_cvt_pk_bf16_f32 v68, v68, v133
	global_store_short v[80:81], v68, off
	v_add_co_u32_e32 v68, vcc, s58, v80
	v_cvt_pk_bf16_f32 v82, v69, v133
	s_nop 1
	v_addc_co_u32_e32 v69, vcc, 0, v81, vcc
	global_store_short v[68:69], v82, off
	v_add_co_u32_e32 v68, vcc, s53, v80
	v_cvt_pk_bf16_f32 v70, v70, v133
	s_nop 1
	v_addc_co_u32_e32 v69, vcc, 0, v81, vcc
	global_store_short v[68:69], v70, off
	v_add_co_u32_e32 v68, vcc, s57, v80
	v_cvt_pk_bf16_f32 v70, v71, v133
	s_nop 1
	v_addc_co_u32_e32 v69, vcc, 0, v81, vcc
	global_store_short v[68:69], v70, off
	v_cvt_pk_bf16_f32 v68, v72, v73
	v_cvt_pk_bf16_f32 v69, v74, v75
	global_store_dwordx2 v[76:77], v[68:69], off offset:32
	v_lshl_add_u64 v[68:69], v[116:117], 0, v[78:79]
	v_cvt_pk_bf16_f32 v64, v64, v133
	global_store_short v[68:69], v64, off
	v_add_co_u32_e32 v64, vcc, s58, v68
	v_cvt_pk_bf16_f32 v70, v65, v133
	s_nop 1
	v_addc_co_u32_e32 v65, vcc, 0, v69, vcc
	global_store_short v[64:65], v70, off
	v_add_co_u32_e32 v64, vcc, s53, v68
	v_cvt_pk_bf16_f32 v66, v66, v133
	s_nop 1
	v_addc_co_u32_e32 v65, vcc, 0, v69, vcc
	global_store_short v[64:65], v66, off
	v_add_co_u32_e32 v64, vcc, s57, v68
	v_cvt_pk_bf16_f32 v66, v67, v133
	s_nop 1
	v_addc_co_u32_e32 v65, vcc, 0, v69, vcc
	global_store_short v[64:65], v66, off
	v_or_b32_e32 v64, s13, v146
	s_ashr_i32 s13, s13, 10
	v_ashrrev_i32_e32 v65, 31, v64
	s_and_b32 s13, s13, -16
	v_lshlrev_b64 v[66:67], 12, v[64:65]
	s_add_i32 s36, s13, s67
	v_lshl_add_u64 v[66:67], s[44:45], 0, v[66:67]
	s_ashr_i32 s37, s36, 31
	v_lshl_add_u64 v[66:67], v[66:67], 0, s[24:25]
	v_and_or_b32 v65, v64, s63, v148
	v_lshl_add_u64 v[66:67], v[66:67], 0, v[132:133]
	v_cvt_pk_bf16_f32 v60, v60, v61
	v_cvt_pk_bf16_f32 v61, v62, v63
	s_lshl_b64 s[36:37], s[36:37], 22
	global_store_dwordx2 v[66:67], v[60:61], off
	v_lshl_add_u64 v[60:61], v[134:135], 0, s[36:37]
	v_lshlrev_b32_e32 v62, 1, v65
	v_mov_b32_e32 v63, v133
	v_lshl_add_u64 v[68:69], v[60:61], 0, v[62:63]
	v_cvt_pk_bf16_f32 v52, v52, v133
; #define PG8_WAIT_V(n) asm volatile("s_waitcnt vmcnt(" #n ")" ::: "memory")
; #define PG8_BAR __builtin_amdgcn_s_barrier()
; __device__ __forceinline__ void st_bf4(bf16_t* p, const f32x4 v) { u32x2 w; w.x = cvt_pk_bf16(v[0], v[1]); w.y = cvt_pk_bf16(v[2], v[3]); *(u32x2*)p = w; }
; __device__ __forceinline__ int kperm(int s) { return (s & ~12) | ((s & 4) << 1) | ((s & 8) >> 1); }
; __device__ __forceinline__ bf16_t f2bf(float f) { return (bf16_t)(cvt_pk_bf16(f, 0.f) & 0xffffu); }
; template <class Epi>
; __device__ __forceinline__ void gemm_phase(LAS unsigned char* lds, const Gemm g, const Sched& S, const Epi& E) {
;     ...
;         if (!has_next) break;
; #pragma unroll
;         for (int a = 0; a < 2; ++a)
; #pragma unroll
;             for (int b = 0; b < 2; ++b)
; #pragma unroll
;                 for (int m = 0; m < 4; ++m)
; #pragma unroll
;                     for (int n = 0; n < 2; ++n) acc[a][b][m][n] = (f32x4){0.f, 0.f, 0.f, 0.f};
;         cur = nxt; cA = nA; cB = nB; ++ui;
;     }
;     PG8_WAIT_V(0);
;     if (wr == 0) PG8_BAR;
;     PG8_BAR;
;     __device__ __forceinline__ void operator()(AccRef acc, const Unit& u, int wr, int wc, int fr, int fq) const {
;     ...
;         for (int ai = 0; ai < 2; ++ai)
; #pragma unroll
;             for (int m = 0; m < 4; ++m) { const int row = u.pm * 256 + ai * 128 + wr * 64 + m * 16 + fr; const int b = row >> 14, s = row & (S_ - 1);
; #pragma unroll
;                 for (int n = 0; n < 2; ++n) { const int p0 = wc * 32 + n * 16 + 4 * fq;
;                     st_bf4(KN + (size_t)row * 2048 + hd * 128 + p0, acc[ai][0][m][n]);
;                     const f32x4 v = acc[ai][1][m][n]; bf16_t* base = VT + ((size_t)(b * 16 + hd) * 128 + p0) * S_ + kperm(s);
; #pragma unroll
;                     for (int j = 0; j < 4; ++j) base[(size_t)j * S_] = f2bf(v[j]); } }
	global_store_short v[68:69], v52, off
	v_add_co_u32_e32 v52, vcc, s58, v68
	v_cvt_pk_bf16_f32 v65, v53, v133
	s_mov_b32 s67, s12
	s_nop 0
	v_addc_co_u32_e32 v53, vcc, 0, v69, vcc
	global_store_short v[52:53], v65, off
	v_add_co_u32_e32 v52, vcc, s53, v68
	v_cvt_pk_bf16_f32 v54, v54, v133
	s_nop 1
	v_addc_co_u32_e32 v53, vcc, 0, v69, vcc
	global_store_short v[52:53], v54, off
	v_add_co_u32_e32 v52, vcc, s57, v68
	v_cvt_pk_bf16_f32 v54, v55, v133
	s_nop 1
	v_addc_co_u32_e32 v53, vcc, 0, v69, vcc
	global_store_short v[52:53], v54, off
	v_cvt_pk_bf16_f32 v52, v56, v57
	v_cvt_pk_bf16_f32 v53, v58, v59
	global_store_dwordx2 v[66:67], v[52:53], off offset:32
	v_lshl_add_u64 v[52:53], v[136:137], 0, s[36:37]
	v_lshl_add_u64 v[54:55], v[52:53], 0, v[62:63]
	v_cvt_pk_bf16_f32 v44, v44, v133
	global_store_short v[54:55], v44, off
	v_add_co_u32_e32 v44, vcc, s58, v54
	v_cvt_pk_bf16_f32 v56, v45, v133
	s_mov_b64 s[36:37], s[16:17]
	s_nop 0
	v_addc_co_u32_e32 v45, vcc, 0, v55, vcc
	global_store_short v[44:45], v56, off
	v_add_co_u32_e32 v44, vcc, s53, v54
	v_cvt_pk_bf16_f32 v46, v46, v133
	s_nop 1
	v_addc_co_u32_e32 v45, vcc, 0, v55, vcc
	global_store_short v[44:45], v46, off
	v_add_co_u32_e32 v44, vcc, s57, v54
	v_cvt_pk_bf16_f32 v46, v47, v133
	s_nop 1
	v_addc_co_u32_e32 v45, vcc, 0, v55, vcc
	global_store_short v[44:45], v46, off
	v_or_b32_e32 v44, 16, v64
	v_ashrrev_i32_e32 v45, 31, v44
	v_lshlrev_b64 v[46:47], 12, v[44:45]
	v_and_or_b32 v54, v44, s64, v148
	v_lshl_add_u64 v[44:45], s[44:45], 0, v[46:47]
	v_lshl_add_u64 v[44:45], v[44:45], 0, s[24:25]
	v_lshl_add_u64 v[44:45], v[44:45], 0, v[132:133]
	v_cvt_pk_bf16_f32 v46, v48, v49
	v_cvt_pk_bf16_f32 v47, v50, v51
	global_store_dwordx2 v[44:45], v[46:47], off
	v_lshlrev_b32_e32 v46, 1, v54
	v_mov_b32_e32 v47, v133
	v_lshl_add_u64 v[48:49], v[60:61], 0, v[46:47]
	v_cvt_pk_bf16_f32 v36, v36, v133
	global_store_short v[48:49], v36, off
	v_add_co_u32_e32 v36, vcc, s58, v48
	v_cvt_pk_bf16_f32 v50, v37, v133
	s_nop 1
	v_addc_co_u32_e32 v37, vcc, 0, v49, vcc
	global_store_short v[36:37], v50, off
	v_add_co_u32_e32 v36, vcc, s53, v48
	v_cvt_pk_bf16_f32 v38, v38, v133
	s_nop 1
	v_addc_co_u32_e32 v37, vcc, 0, v49, vcc
	global_store_short v[36:37], v38, off
	v_add_co_u32_e32 v36, vcc, s57, v48
	v_cvt_pk_bf16_f32 v38, v39, v133
	s_nop 1
	v_addc_co_u32_e32 v37, vcc, 0, v49, vcc
	global_store_short v[36:37], v38, off
	v_cvt_pk_bf16_f32 v36, v40, v41
	v_cvt_pk_bf16_f32 v37, v42, v43
	global_store_dwordx2 v[44:45], v[36:37], off offset:32
	v_lshl_add_u64 v[36:37], v[52:53], 0, v[46:47]
	v_cvt_pk_bf16_f32 v28, v28, v133
	global_store_short v[36:37], v28, off
	v_add_co_u32_e32 v28, vcc, s58, v36
	v_cvt_pk_bf16_f32 v38, v29, v133
	s_nop 1
	v_addc_co_u32_e32 v29, vcc, 0, v37, vcc
	global_store_short v[28:29], v38, off
	v_add_co_u32_e32 v28, vcc, s53, v36
	v_cvt_pk_bf16_f32 v30, v30, v133
	s_nop 1
	v_addc_co_u32_e32 v29, vcc, 0, v37, vcc
	global_store_short v[28:29], v30, off
	v_add_co_u32_e32 v28, vcc, s57, v36
	v_cvt_pk_bf16_f32 v30, v31, v133
	s_nop 1
	v_addc_co_u32_e32 v29, vcc, 0, v37, vcc
	global_store_short v[28:29], v30, off
	v_or_b32_e32 v28, 32, v64
	v_ashrrev_i32_e32 v29, 31, v28
	v_lshlrev_b64 v[30:31], 12, v[28:29]
	v_and_or_b32 v36, v28, s65, v148
	v_lshl_add_u64 v[28:29], s[44:45], 0, v[30:31]
	v_lshl_add_u64 v[28:29], v[28:29], 0, s[24:25]
	v_lshl_add_u64 v[28:29], v[28:29], 0, v[132:133]
	v_cvt_pk_bf16_f32 v30, v32, v33
	v_cvt_pk_bf16_f32 v31, v34, v35
	global_store_dwordx2 v[28:29], v[30:31], off
	v_lshlrev_b32_e32 v30, 1, v36
	v_mov_b32_e32 v31, v133
	v_lshl_add_u64 v[32:33], v[60:61], 0, v[30:31]
	v_cvt_pk_bf16_f32 v20, v20, v133
	global_store_short v[32:33], v20, off
	v_add_co_u32_e32 v20, vcc, s58, v32
	v_cvt_pk_bf16_f32 v34, v21, v133
	s_nop 1
	v_addc_co_u32_e32 v21, vcc, 0, v33, vcc
	global_store_short v[20:21], v34, off
	v_add_co_u32_e32 v20, vcc, s53, v32
	v_cvt_pk_bf16_f32 v22, v22, v133
	s_nop 1
	v_addc_co_u32_e32 v21, vcc, 0, v33, vcc
	global_store_short v[20:21], v22, off
	v_add_co_u32_e32 v20, vcc, s57, v32
	v_cvt_pk_bf16_f32 v22, v23, v133
	s_nop 1
	v_addc_co_u32_e32 v21, vcc, 0, v33, vcc
	global_store_short v[20:21], v22, off
	v_cvt_pk_bf16_f32 v20, v24, v25
	v_cvt_pk_bf16_f32 v21, v26, v27
	global_store_dwordx2 v[28:29], v[20:21], off offset:32
	v_lshl_add_u64 v[20:21], v[52:53], 0, v[30:31]
	v_cvt_pk_bf16_f32 v12, v12, v133
	global_store_short v[20:21], v12, off
	v_add_co_u32_e32 v12, vcc, s58, v20
	v_cvt_pk_bf16_f32 v22, v13, v133
	s_nop 1
	v_addc_co_u32_e32 v13, vcc, 0, v21, vcc
	global_store_short v[12:13], v22, off
	v_add_co_u32_e32 v12, vcc, s53, v20
	v_cvt_pk_bf16_f32 v14, v14, v133
	s_nop 1
	v_addc_co_u32_e32 v13, vcc, 0, v21, vcc
	global_store_short v[12:13], v14, off
	v_add_co_u32_e32 v12, vcc, s57, v20
	v_cvt_pk_bf16_f32 v14, v15, v133
	s_nop 1
	v_addc_co_u32_e32 v13, vcc, 0, v21, vcc
	global_store_short v[12:13], v14, off
	v_or_b32_e32 v12, 48, v64
	v_ashrrev_i32_e32 v13, 31, v12
	v_lshlrev_b64 v[14:15], 12, v[12:13]
	v_and_or_b32 v20, v12, s66, v148
	v_lshl_add_u64 v[12:13], s[44:45], 0, v[14:15]
	v_lshl_add_u64 v[12:13], v[12:13], 0, s[24:25]
	v_lshl_add_u64 v[12:13], v[12:13], 0, v[132:133]
	v_cvt_pk_bf16_f32 v14, v16, v17
	v_cvt_pk_bf16_f32 v15, v18, v19
	global_store_dwordx2 v[12:13], v[14:15], off
	v_lshlrev_b32_e32 v14, 1, v20
	v_mov_b32_e32 v15, v133
	v_lshl_add_u64 v[16:17], v[60:61], 0, v[14:15]
	v_cvt_pk_bf16_f32 v4, v4, v133
	global_store_short v[16:17], v4, off
	v_add_co_u32_e32 v4, vcc, s58, v16
	v_cvt_pk_bf16_f32 v18, v5, v133
	s_mov_b32 s24, s14
	s_nop 0
	v_addc_co_u32_e32 v5, vcc, 0, v17, vcc
	global_store_short v[4:5], v18, off
	v_add_co_u32_e32 v4, vcc, s53, v16
	v_cvt_pk_bf16_f32 v6, v6, v133
	s_nop 1
	v_addc_co_u32_e32 v5, vcc, 0, v17, vcc
	global_store_short v[4:5], v6, off
	v_add_co_u32_e32 v4, vcc, s57, v16
	v_cvt_pk_bf16_f32 v6, v7, v133
	s_nop 1
	v_addc_co_u32_e32 v5, vcc, 0, v17, vcc
	global_store_short v[4:5], v6, off
	v_cvt_pk_bf16_f32 v4, v8, v9
	v_cvt_pk_bf16_f32 v5, v10, v11
	global_store_dwordx2 v[12:13], v[4:5], off offset:32
	v_lshl_add_u64 v[4:5], v[52:53], 0, v[14:15]
	v_cvt_pk_bf16_f32 v0, v0, v133
	global_store_short v[4:5], v0, off
	v_add_co_u32_e32 v0, vcc, 0x8000, v4
	v_cvt_pk_bf16_f32 v6, v1, v133
	s_nop 1
	v_addc_co_u32_e32 v1, vcc, 0, v5, vcc
	global_store_short v[0:1], v6, off
	v_add_co_u32_e32 v0, vcc, 0x10000, v4
	v_cvt_pk_bf16_f32 v2, v2, v133
	s_nop 1
	v_addc_co_u32_e32 v1, vcc, 0, v5, vcc
	global_store_short v[0:1], v2, off
	v_add_co_u32_e32 v0, vcc, 0x18000, v4
	v_cvt_pk_bf16_f32 v2, v3, v133
	s_nop 1
	v_addc_co_u32_e32 v1, vcc, 0, v5, vcc
	s_and_b64 vcc, exec, s[8:9]
	global_store_short v[0:1], v2, off
	s_cbranch_vccz .LBB0_2703
	s_waitcnt vmcnt(0)
	s_cmpk_gt_u32 s0, 0xff
	s_cbranch_scc1 .LBB0_2714
	s_barrier

; #define PG8_STAGE(bufoff, gbase, voff) do { _Pragma("unroll") for (int _i = 0; _i < 2; ++_i) \
;         __builtin_amdgcn_global_load_lds((const unsigned*)((const char*)(gbase) + (voff)[_i]), (LAS unsigned*)(lds + (bufoff) + ldsw + _i * 8192), 16, 0, 0); } while (0)
; #define PG8_LDA(dst, b, h) do { _Pragma("unroll") for (int m = 0; m < 4; ++m) _Pragma("unroll") for (int k = 0; k < 2; ++k) dst[m][k] = *(const LAS bf16x8*)(lds + PG8_SA(b, h) + aoff + m * 2048 + k * 1024); } while (0)
; #define PG8_LDB(dst, b, h) do { _Pragma("unroll") for (int n = 0; n < 2; ++n) _Pragma("unroll") for (int k = 0; k < 2; ++k) dst[n][k] = *(const LAS bf16x8*)(lds + PG8_SB(b, h) + boff + n * 2048 + k * 1024); } while (0)
; #define PG8_WAIT_V(n) asm volatile("s_waitcnt vmcnt(" #n ")" ::: "memory")
; #define PG8_WAIT_L(n) asm volatile("s_waitcnt lgkmcnt(" #n ")" ::: "memory")
; #define PG8_BAR __builtin_amdgcn_s_barrier()
; #define PG8_SCHED __builtin_amdgcn_sched_barrier(0)
; template <class Epi>
; __device__ __forceinline__ void gemm_phase(LAS unsigned char* lds, const Gemm g, const Sched& S, const Epi& E) {
;     ...
;             PG8_LDB(B0, 0, 0); PG8_SCHED; PG8_LDA(At, 0, 0); PG8_STAGE(PG8_SA(1, 1), a1 + hstepA, voffA);
;             PG8_WAIT_L(8); PG8_BAR; PG8_WAIT_L(0); PG8_MMA(0, 0, At, B0); PG8_BAR; PG8_SCHED;
;             PG8_LDB(B1, 0, 1); PG8_STAGE(PG8_SB(0, 0), b2, voffB);
;             PG8_BAR; PG8_WAIT_L(0); PG8_MMA(0, 1, At, B1); PG8_BAR;
;             PG8_LDA(At, 0, 1); PG8_STAGE(PG8_SA(0, 0), a2, voffA);
;             PG8_BAR; PG8_WAIT_L(0); PG8_MMA(1, 0, At, B0); PG8_BAR; PG8_SCHED;
;             PG8_STAGE(PG8_SB(0, 1), b2 + hstepB, voffB);
;             PG8_WAIT_V(6); PG8_BAR; PG8_MMA(1, 1, At, B1); PG8_BAR;
;             PG8_LDB(B0, 1, 0); PG8_SCHED; PG8_LDA(At, 1, 0); PG8_STAGE(PG8_SA(0, 1), a2 + hstepA, voffA);
;             PG8_WAIT_L(8); PG8_BAR; PG8_WAIT_L(0); PG8_MMA(0, 0, At, B0); PG8_BAR; PG8_SCHED;
;             PG8_LDB(B1, 1, 1); PG8_STAGE(PG8_SB(1, 0), b3, voffB);
;             PG8_BAR; PG8_WAIT_L(0); PG8_MMA(0, 1, At, B1); PG8_BAR;
;             PG8_LDA(At, 1, 1); PG8_STAGE(PG8_SA(1, 0), a3, voffA);
;             PG8_BAR; PG8_WAIT_L(0); PG8_MMA(1, 0, At, B0); PG8_BAR; PG8_SCHED;
;             PG8_STAGE(PG8_SB(1, 1), b3 + hstepB, voffB);
;             PG8_WAIT_V(6); PG8_BAR; PG8_MMA(1, 1, At, B1); PG8_BAR;
.LBB0_2964:
	v_add_u32_e32 v144, s56, v202
	s_add_u32 s38, s14, s36
	ds_read_b128 v[132:135], v144
	ds_read_b128 v[136:139], v144 offset:1024
	ds_read_b128 v[140:143], v144 offset:2048
	ds_read_b128 v[144:147], v144 offset:3072
	s_addc_u32 s39, s15, s37
	s_add_u32 s38, s38, 0x100
	s_addc_u32 s39, s39, 0
	s_add_u32 s70, s13, s36
	s_addc_u32 s71, s51, s37
	s_cmpk_eq_i32 s36, 0xf00
	s_cselect_b32 s47, s21, s39
	s_cselect_b32 s46, s65, s38
	s_cselect_b32 s39, s19, s71
	s_cselect_b32 s38, s66, s70
	v_lshl_add_u64 v[198:199], v[128:129], 0, s[36:37]
	s_add_i32 m0, s33, 0xc000
	ds_read_b128 v[148:151], v203
	ds_read_b128 v[152:155], v203 offset:1024
	ds_read_b128 v[156:159], v203 offset:2048
	ds_read_b128 v[160:163], v203 offset:3072
	ds_read_b128 v[164:167], v203 offset:4096
	ds_read_b128 v[168:171], v203 offset:5120
	ds_read_b128 v[172:175], v203 offset:6144
	ds_read_b128 v[194:197], v203 offset:7168
	global_load_lds_dwordx4 v[198:199], off
	v_lshl_add_u64 v[198:199], v[130:131], 0, s[36:37]
	s_add_i32 m0, s33, 0xe000
	s_nop 0
	global_load_lds_dwordx4 v[198:199], off
	s_waitcnt lgkmcnt(8)
	s_barrier
	s_waitcnt lgkmcnt(0)
	s_setprio 1
	s_waitcnt lgkmcnt(0)
	v_mfma_f32_16x16x32_bf16 v[124:127], v[132:135], v[148:151], v[124:127]
	v_mfma_f32_16x16x32_bf16 v[120:123], v[140:143], v[148:151], v[120:123]
	v_mfma_f32_16x16x32_bf16 v[116:119], v[132:135], v[156:159], v[116:119]
	v_mfma_f32_16x16x32_bf16 v[112:115], v[140:143], v[156:159], v[112:115]
	v_mfma_f32_16x16x32_bf16 v[108:111], v[132:135], v[164:167], v[108:111]
	v_mfma_f32_16x16x32_bf16 v[104:107], v[140:143], v[164:167], v[104:107]
	v_mfma_f32_16x16x32_bf16 v[100:103], v[132:135], v[172:175], v[100:103]
	v_mfma_f32_16x16x32_bf16 v[96:99], v[140:143], v[172:175], v[96:99]
	v_mfma_f32_16x16x32_bf16 v[124:127], v[136:139], v[152:155], v[124:127]
	v_mfma_f32_16x16x32_bf16 v[120:123], v[144:147], v[152:155], v[120:123]
	v_mfma_f32_16x16x32_bf16 v[116:119], v[136:139], v[160:163], v[116:119]
	v_mfma_f32_16x16x32_bf16 v[112:115], v[144:147], v[160:163], v[112:115]
	v_mfma_f32_16x16x32_bf16 v[108:111], v[136:139], v[168:171], v[108:111]
	v_mfma_f32_16x16x32_bf16 v[104:107], v[144:147], v[168:171], v[104:107]
	v_mfma_f32_16x16x32_bf16 v[100:103], v[136:139], v[194:197], v[100:103]
	s_barrier
	v_mfma_f32_16x16x32_bf16 v[96:99], v[144:147], v[194:197], v[96:99]
	s_setprio 0
	s_add_i32 s70, s56, s1
	v_add_u32_e32 v212, s57, v202
	v_lshl_add_u64 v[216:217], s[38:39], 0, v[176:177]
	s_mov_b32 m0, s70
	ds_read_b128 v[198:201], v212
	ds_read_b128 v[204:207], v212 offset:1024
	ds_read_b128 v[208:211], v212 offset:2048
	ds_read_b128 v[212:215], v212 offset:3072
	global_load_lds_dwordx4 v[216:217], off
	v_lshl_add_u64 v[218:219], s[38:39], 0, v[178:179]
	s_add_i32 m0, s70, 0x2000
	s_nop 0
	global_load_lds_dwordx4 v[218:219], off
	s_barrier
	s_waitcnt lgkmcnt(0)
	s_setprio 1
	s_waitcnt lgkmcnt(0)
	v_mfma_f32_16x16x32_bf16 v[92:95], v[198:201], v[148:151], v[92:95]
	v_mfma_f32_16x16x32_bf16 v[88:91], v[208:211], v[148:151], v[88:91]
	v_mfma_f32_16x16x32_bf16 v[84:87], v[198:201], v[156:159], v[84:87]
	v_mfma_f32_16x16x32_bf16 v[80:83], v[208:211], v[156:159], v[80:83]
	v_mfma_f32_16x16x32_bf16 v[76:79], v[198:201], v[164:167], v[76:79]
	v_mfma_f32_16x16x32_bf16 v[72:75], v[208:211], v[164:167], v[72:75]
	v_mfma_f32_16x16x32_bf16 v[68:71], v[198:201], v[172:175], v[68:71]
	v_mfma_f32_16x16x32_bf16 v[64:67], v[208:211], v[172:175], v[64:67]
	v_mfma_f32_16x16x32_bf16 v[92:95], v[204:207], v[152:155], v[92:95]
	v_mfma_f32_16x16x32_bf16 v[88:91], v[212:215], v[152:155], v[88:91]
	v_mfma_f32_16x16x32_bf16 v[84:87], v[204:207], v[160:163], v[84:87]
	v_mfma_f32_16x16x32_bf16 v[80:83], v[212:215], v[160:163], v[80:83]
	v_mfma_f32_16x16x32_bf16 v[76:79], v[204:207], v[168:171], v[76:79]
	v_mfma_f32_16x16x32_bf16 v[72:75], v[212:215], v[168:171], v[72:75]
	v_mfma_f32_16x16x32_bf16 v[68:71], v[204:207], v[194:197], v[68:71]
	s_barrier
	v_mfma_f32_16x16x32_bf16 v[64:67], v[212:215], v[194:197], v[64:67]
	s_setprio 0
	s_mov_b32 m0, s33
	v_lshl_add_u64 v[220:221], s[46:47], 0, v[176:177]
	ds_read_b128 v[148:151], v203 offset:16384
	ds_read_b128 v[152:155], v203 offset:17408
	ds_read_b128 v[156:159], v203 offset:18432
	ds_read_b128 v[160:163], v203 offset:19456
	ds_read_b128 v[164:167], v203 offset:20480
	ds_read_b128 v[168:171], v203 offset:21504
	ds_read_b128 v[172:175], v203 offset:22528
	ds_read_b128 v[194:197], v203 offset:23552
	global_load_lds_dwordx4 v[220:221], off
	v_lshl_add_u64 v[222:223], s[46:47], 0, v[178:179]
	s_mov_b32 m0, s34
	s_nop 0
	global_load_lds_dwordx4 v[222:223], off
	s_barrier
	s_waitcnt lgkmcnt(0)
	s_setprio 1
	s_waitcnt lgkmcnt(0)
	v_mfma_f32_16x16x32_bf16 v[60:63], v[132:135], v[148:151], v[60:63]
	v_mfma_f32_16x16x32_bf16 v[56:59], v[140:143], v[148:151], v[56:59]
	v_mfma_f32_16x16x32_bf16 v[52:55], v[132:135], v[156:159], v[52:55]
	v_mfma_f32_16x16x32_bf16 v[48:51], v[140:143], v[156:159], v[48:51]
	v_mfma_f32_16x16x32_bf16 v[44:47], v[132:135], v[164:167], v[44:47]
	v_mfma_f32_16x16x32_bf16 v[40:43], v[140:143], v[164:167], v[40:43]
	v_mfma_f32_16x16x32_bf16 v[36:39], v[132:135], v[172:175], v[36:39]
	v_mfma_f32_16x16x32_bf16 v[32:35], v[140:143], v[172:175], v[32:35]
	v_mfma_f32_16x16x32_bf16 v[60:63], v[136:139], v[152:155], v[60:63]
	v_mfma_f32_16x16x32_bf16 v[56:59], v[144:147], v[152:155], v[56:59]
	v_mfma_f32_16x16x32_bf16 v[52:55], v[136:139], v[160:163], v[52:55]
	v_mfma_f32_16x16x32_bf16 v[48:51], v[144:147], v[160:163], v[48:51]
	v_mfma_f32_16x16x32_bf16 v[44:47], v[136:139], v[168:171], v[44:47]
	v_mfma_f32_16x16x32_bf16 v[40:43], v[144:147], v[168:171], v[40:43]
	v_mfma_f32_16x16x32_bf16 v[36:39], v[136:139], v[194:197], v[36:39]
	s_barrier
; #define PG8_STAGE(bufoff, gbase, voff) do { _Pragma("unroll") for (int _i = 0; _i < 2; ++_i) \
;         __builtin_amdgcn_global_load_lds((const unsigned*)((const char*)(gbase) + (voff)[_i]), (LAS unsigned*)(lds + (bufoff) + ldsw + _i * 8192), 16, 0, 0); } while (0)
; #define PG8_LDA(dst, b, h) do { _Pragma("unroll") for (int m = 0; m < 4; ++m) _Pragma("unroll") for (int k = 0; k < 2; ++k) dst[m][k] = *(const LAS bf16x8*)(lds + PG8_SA(b, h) + aoff + m * 2048 + k * 1024); } while (0)
; #define PG8_LDB(dst, b, h) do { _Pragma("unroll") for (int n = 0; n < 2; ++n) _Pragma("unroll") for (int k = 0; k < 2; ++k) dst[n][k] = *(const LAS bf16x8*)(lds + PG8_SB(b, h) + boff + n * 2048 + k * 1024); } while (0)
; #define PG8_WAIT_V(n) asm volatile("s_waitcnt vmcnt(" #n ")" ::: "memory")
; #define PG8_WAIT_L(n) asm volatile("s_waitcnt lgkmcnt(" #n ")" ::: "memory")
; #define PG8_BAR __builtin_amdgcn_s_barrier()
; #define PG8_SCHED __builtin_amdgcn_sched_barrier(0)
; template <class Epi>
; __device__ __forceinline__ void gemm_phase(LAS unsigned char* lds, const Gemm g, const Sched& S, const Epi& E) {
;     ...
;             PG8_LDB(B0, 0, 0); PG8_SCHED; PG8_LDA(At, 0, 0); PG8_STAGE(PG8_SA(1, 1), a1 + hstepA, voffA);
;             PG8_WAIT_L(8); PG8_BAR; PG8_WAIT_L(0); PG8_MMA(0, 0, At, B0); PG8_BAR; PG8_SCHED;
;             PG8_LDB(B1, 0, 1); PG8_STAGE(PG8_SB(0, 0), b2, voffB);
;             PG8_BAR; PG8_WAIT_L(0); PG8_MMA(0, 1, At, B1); PG8_BAR;
;             PG8_LDA(At, 0, 1); PG8_STAGE(PG8_SA(0, 0), a2, voffA);
;             PG8_BAR; PG8_WAIT_L(0); PG8_MMA(1, 0, At, B0); PG8_BAR; PG8_SCHED;
;             PG8_STAGE(PG8_SB(0, 1), b2 + hstepB, voffB);
;             PG8_WAIT_V(6); PG8_BAR; PG8_MMA(1, 1, At, B1); PG8_BAR;
;             PG8_LDB(B0, 1, 0); PG8_SCHED; PG8_LDA(At, 1, 0); PG8_STAGE(PG8_SA(0, 1), a2 + hstepA, voffA);
;             PG8_WAIT_L(8); PG8_BAR; PG8_WAIT_L(0); PG8_MMA(0, 0, At, B0); PG8_BAR; PG8_SCHED;
;             PG8_LDB(B1, 1, 1); PG8_STAGE(PG8_SB(1, 0), b3, voffB);
;             PG8_BAR; PG8_WAIT_L(0); PG8_MMA(0, 1, At, B1); PG8_BAR;
;             PG8_LDA(At, 1, 1); PG8_STAGE(PG8_SA(1, 0), a3, voffA);
;             PG8_BAR; PG8_WAIT_L(0); PG8_MMA(1, 0, At, B0); PG8_BAR; PG8_SCHED;
;             PG8_STAGE(PG8_SB(1, 1), b3 + hstepB, voffB);
;             PG8_WAIT_V(6); PG8_BAR; PG8_MMA(1, 1, At, B1); PG8_BAR;
	v_mfma_f32_16x16x32_bf16 v[32:35], v[144:147], v[194:197], v[32:35]
	s_setprio 0
	s_add_u32 s70, s38, 0x80000
	s_addc_u32 s71, s39, 0
	s_add_i32 s72, s57, s1
	v_lshl_add_u64 v[132:133], s[70:71], 0, v[176:177]
	s_mov_b32 m0, s72
	s_nop 0
	global_load_lds_dwordx4 v[132:133], off
	v_lshl_add_u64 v[132:133], s[70:71], 0, v[178:179]
	s_add_i32 m0, s72, 0x2000
	s_nop 0
	global_load_lds_dwordx4 v[132:133], off
	s_waitcnt vmcnt(6)
	s_barrier
	s_setprio 1
	v_mfma_f32_16x16x32_bf16 v[28:31], v[198:201], v[148:151], v[28:31]
	v_mfma_f32_16x16x32_bf16 v[24:27], v[208:211], v[148:151], v[24:27]
	v_mfma_f32_16x16x32_bf16 v[20:23], v[198:201], v[156:159], v[20:23]
	v_mfma_f32_16x16x32_bf16 v[16:19], v[208:211], v[156:159], v[16:19]
	v_mfma_f32_16x16x32_bf16 v[12:15], v[198:201], v[164:167], v[12:15]
	v_mfma_f32_16x16x32_bf16 v[8:11], v[208:211], v[164:167], v[8:11]
	v_mfma_f32_16x16x32_bf16 v[4:7], v[198:201], v[172:175], v[4:7]
	v_mfma_f32_16x16x32_bf16 v[0:3], v[208:211], v[172:175], v[0:3]
	v_mfma_f32_16x16x32_bf16 v[28:31], v[204:207], v[152:155], v[28:31]
	v_mfma_f32_16x16x32_bf16 v[24:27], v[212:215], v[152:155], v[24:27]
	v_mfma_f32_16x16x32_bf16 v[20:23], v[204:207], v[160:163], v[20:23]
	v_mfma_f32_16x16x32_bf16 v[16:19], v[212:215], v[160:163], v[16:19]
	v_mfma_f32_16x16x32_bf16 v[12:15], v[204:207], v[168:171], v[12:15]
	v_mfma_f32_16x16x32_bf16 v[8:11], v[212:215], v[168:171], v[8:11]
	v_mfma_f32_16x16x32_bf16 v[4:7], v[204:207], v[194:197], v[4:7]
	s_barrier
	v_mfma_f32_16x16x32_bf16 v[0:3], v[212:215], v[194:197], v[0:3]
	s_setprio 0
	s_add_i32 s70, 0, 0x18000
	v_add_u32_e32 v144, s70, v202
	ds_read_b128 v[132:135], v144
	ds_read_b128 v[136:139], v144 offset:1024
	ds_read_b128 v[140:143], v144 offset:2048
	ds_read_b128 v[144:147], v144 offset:3072
	s_add_u32 s46, s46, 0x80000
	s_addc_u32 s47, s47, 0
	s_mov_b32 m0, s35
	v_lshl_add_u64 v[198:199], s[46:47], 0, v[176:177]
	ds_read_b128 v[148:151], v203 offset:32768
	ds_read_b128 v[152:155], v203 offset:33792
	ds_read_b128 v[156:159], v203 offset:34816
	ds_read_b128 v[160:163], v203 offset:35840
	ds_read_b128 v[164:167], v203 offset:36864
	ds_read_b128 v[168:171], v203 offset:37888
	ds_read_b128 v[172:175], v203 offset:38912
	ds_read_b128 v[194:197], v203 offset:39936
	global_load_lds_dwordx4 v[198:199], off
	v_lshl_add_u64 v[198:199], s[46:47], 0, v[178:179]
	s_mov_b32 m0, s43
	s_nop 0
	global_load_lds_dwordx4 v[198:199], off
	s_waitcnt lgkmcnt(8)
	s_barrier
	s_waitcnt lgkmcnt(0)
	s_setprio 1
	s_waitcnt lgkmcnt(0)
	v_mfma_f32_16x16x32_bf16 v[124:127], v[132:135], v[148:151], v[124:127]
	v_mfma_f32_16x16x32_bf16 v[120:123], v[140:143], v[148:151], v[120:123]
	v_mfma_f32_16x16x32_bf16 v[116:119], v[132:135], v[156:159], v[116:119]
	v_mfma_f32_16x16x32_bf16 v[112:115], v[140:143], v[156:159], v[112:115]
	v_mfma_f32_16x16x32_bf16 v[108:111], v[132:135], v[164:167], v[108:111]
	v_mfma_f32_16x16x32_bf16 v[104:107], v[140:143], v[164:167], v[104:107]
	v_mfma_f32_16x16x32_bf16 v[100:103], v[132:135], v[172:175], v[100:103]
	v_mfma_f32_16x16x32_bf16 v[96:99], v[140:143], v[172:175], v[96:99]
	v_mfma_f32_16x16x32_bf16 v[124:127], v[136:139], v[152:155], v[124:127]
	v_mfma_f32_16x16x32_bf16 v[120:123], v[144:147], v[152:155], v[120:123]
	v_mfma_f32_16x16x32_bf16 v[116:119], v[136:139], v[160:163], v[116:119]
	v_mfma_f32_16x16x32_bf16 v[112:115], v[144:147], v[160:163], v[112:115]
	v_mfma_f32_16x16x32_bf16 v[108:111], v[136:139], v[168:171], v[108:111]
	v_mfma_f32_16x16x32_bf16 v[104:107], v[144:147], v[168:171], v[104:107]
	v_mfma_f32_16x16x32_bf16 v[100:103], v[136:139], v[194:197], v[100:103]
	s_barrier
	v_mfma_f32_16x16x32_bf16 v[96:99], v[144:147], v[194:197], v[96:99]
	s_setprio 0
	s_add_i32 s46, 0, 0x1c000
	s_add_i32 s47, s70, s1
	v_add_u32_e32 v212, s46, v202
	v_lshl_add_u64 v[216:217], v[216:217], 0, s[16:17]
	s_mov_b32 m0, s47
	ds_read_b128 v[198:201], v212
	ds_read_b128 v[204:207], v212 offset:1024
	ds_read_b128 v[208:211], v212 offset:2048
	ds_read_b128 v[212:215], v212 offset:3072
	global_load_lds_dwordx4 v[216:217], off
	v_lshl_add_u64 v[216:217], v[218:219], 0, s[16:17]
	s_add_i32 m0, s47, 0x2000
	s_nop 0
	global_load_lds_dwordx4 v[216:217], off
	s_barrier
	s_waitcnt lgkmcnt(0)
	s_setprio 1
	s_waitcnt lgkmcnt(0)
	v_mfma_f32_16x16x32_bf16 v[92:95], v[198:201], v[148:151], v[92:95]
	v_mfma_f32_16x16x32_bf16 v[88:91], v[208:211], v[148:151], v[88:91]
	v_mfma_f32_16x16x32_bf16 v[84:87], v[198:201], v[156:159], v[84:87]
	v_mfma_f32_16x16x32_bf16 v[80:83], v[208:211], v[156:159], v[80:83]
	v_mfma_f32_16x16x32_bf16 v[76:79], v[198:201], v[164:167], v[76:79]
	v_mfma_f32_16x16x32_bf16 v[72:75], v[208:211], v[164:167], v[72:75]
	v_mfma_f32_16x16x32_bf16 v[68:71], v[198:201], v[172:175], v[68:71]
	v_mfma_f32_16x16x32_bf16 v[64:67], v[208:211], v[172:175], v[64:67]
	v_mfma_f32_16x16x32_bf16 v[92:95], v[204:207], v[152:155], v[92:95]
	v_mfma_f32_16x16x32_bf16 v[88:91], v[212:215], v[152:155], v[88:91]
	v_mfma_f32_16x16x32_bf16 v[84:87], v[204:207], v[160:163], v[84:87]
	v_mfma_f32_16x16x32_bf16 v[80:83], v[212:215], v[160:163], v[80:83]
	v_mfma_f32_16x16x32_bf16 v[76:79], v[204:207], v[168:171], v[76:79]
	v_mfma_f32_16x16x32_bf16 v[72:75], v[212:215], v[168:171], v[72:75]
	v_mfma_f32_16x16x32_bf16 v[68:71], v[204:207], v[194:197], v[68:71]
	s_barrier
	v_mfma_f32_16x16x32_bf16 v[64:67], v[212:215], v[194:197], v[64:67]
	s_setprio 0
	s_mov_b32 m0, s54
	v_lshl_add_u64 v[216:217], v[220:221], 0, s[16:17]
	ds_read_b128 v[148:151], v203 offset:49152
	ds_read_b128 v[152:155], v203 offset:50176
	ds_read_b128 v[156:159], v203 offset:51200
	ds_read_b128 v[160:163], v203 offset:52224
	ds_read_b128 v[164:167], v203 offset:53248
	ds_read_b128 v[168:171], v203 offset:54272
	ds_read_b128 v[172:175], v203 offset:55296
	ds_read_b128 v[194:197], v203 offset:56320
	global_load_lds_dwordx4 v[216:217], off
	v_lshl_add_u64 v[216:217], v[222:223], 0, s[16:17]
	s_mov_b32 m0, s55
	s_nop 0
	global_load_lds_dwordx4 v[216:217], off
	s_barrier
; #define PG8_STAGE(bufoff, gbase, voff) do { _Pragma("unroll") for (int _i = 0; _i < 2; ++_i) \
;         __builtin_amdgcn_global_load_lds((const unsigned*)((const char*)(gbase) + (voff)[_i]), (LAS unsigned*)(lds + (bufoff) + ldsw + _i * 8192), 16, 0, 0); } while (0)
; #define PG8_LDA(dst, b, h) do { _Pragma("unroll") for (int m = 0; m < 4; ++m) _Pragma("unroll") for (int k = 0; k < 2; ++k) dst[m][k] = *(const LAS bf16x8*)(lds + PG8_SA(b, h) + aoff + m * 2048 + k * 1024); } while (0)
; #define PG8_LDB(dst, b, h) do { _Pragma("unroll") for (int n = 0; n < 2; ++n) _Pragma("unroll") for (int k = 0; k < 2; ++k) dst[n][k] = *(const LAS bf16x8*)(lds + PG8_SB(b, h) + boff + n * 2048 + k * 1024); } while (0)
; #define PG8_MMA(ai, bj, At, Bt) do { __builtin_amdgcn_s_setprio(1); _Pragma("unroll") for (int m = 0; m < 4; ++m) _Pragma("unroll") for (int n = 0; n < 2; ++n) _Pragma("unroll") for (int k = 0; k < 2; ++k) \
;         acc[ai][bj][m][n] = __builtin_amdgcn_mfma_f32_16x16x32_bf16(Bt[n][k], At[m][k], acc[ai][bj][m][n], 0, 0, 0); __builtin_amdgcn_s_setprio(0); } while (0)
; template <class Epi>
; __device__ __forceinline__ void gemm_phase(LAS unsigned char* lds, const Gemm g, const Sched& S, const Epi& E) {
;     ...
;             PG8_WAIT_V(6); PG8_BAR; PG8_MMA(1, 1, At, B1); PG8_BAR;
;             PG8_LDB(B0, 1, 0); PG8_SCHED; PG8_LDA(At, 1, 0); PG8_STAGE(PG8_SA(0, 1), a2 + hstepA, voffA);
;             PG8_WAIT_L(8); PG8_BAR; PG8_WAIT_L(0); PG8_MMA(0, 0, At, B0); PG8_BAR; PG8_SCHED;
;             PG8_LDB(B1, 1, 1); PG8_STAGE(PG8_SB(1, 0), b3, voffB);
;             PG8_BAR; PG8_WAIT_L(0); PG8_MMA(0, 1, At, B1); PG8_BAR;
;             PG8_LDA(At, 1, 1); PG8_STAGE(PG8_SA(1, 0), a3, voffA);
;             PG8_BAR; PG8_WAIT_L(0); PG8_MMA(1, 0, At, B0); PG8_BAR; PG8_SCHED;
;             PG8_STAGE(PG8_SB(1, 1), b3 + hstepB, voffB);
;             PG8_WAIT_V(6); PG8_BAR; PG8_MMA(1, 1, At, B1); PG8_BAR;
;     __device__ __forceinline__ void operator()(AccRef acc, const Unit& u, int wr, int wc, int fr, int fq) const {
;         const float al = alpha;
;         const size_t base = ((size_t)u.pm * 256 + wr * 64 + fr) * D_ + u.pn * 256 + wc * 32 + 4 * fq;
;         f32x4 xa[2][2][2], xb[2][2][2];
;     ...
;         RES_LOAD(xa, 0); RES_LOAD(xb, 1);
;         RES_STORE(xa, 0); RES_LOAD(xa, 2);
;         RES_STORE(xb, 1); RES_LOAD(xb, 3);
;         RES_STORE(xa, 2); RES_STORE(xb, 3);
	s_waitcnt lgkmcnt(0)
	s_setprio 1
	s_waitcnt lgkmcnt(0)
	v_mfma_f32_16x16x32_bf16 v[60:63], v[132:135], v[148:151], v[60:63]
	v_mfma_f32_16x16x32_bf16 v[56:59], v[140:143], v[148:151], v[56:59]
	v_mfma_f32_16x16x32_bf16 v[52:55], v[132:135], v[156:159], v[52:55]
	v_mfma_f32_16x16x32_bf16 v[48:51], v[140:143], v[156:159], v[48:51]
	v_mfma_f32_16x16x32_bf16 v[44:47], v[132:135], v[164:167], v[44:47]
	v_mfma_f32_16x16x32_bf16 v[40:43], v[140:143], v[164:167], v[40:43]
	v_mfma_f32_16x16x32_bf16 v[36:39], v[132:135], v[172:175], v[36:39]
	v_mfma_f32_16x16x32_bf16 v[32:35], v[140:143], v[172:175], v[32:35]
	v_mfma_f32_16x16x32_bf16 v[60:63], v[136:139], v[152:155], v[60:63]
	v_mfma_f32_16x16x32_bf16 v[56:59], v[144:147], v[152:155], v[56:59]
	v_mfma_f32_16x16x32_bf16 v[52:55], v[136:139], v[160:163], v[52:55]
	v_mfma_f32_16x16x32_bf16 v[48:51], v[144:147], v[160:163], v[48:51]
	v_mfma_f32_16x16x32_bf16 v[44:47], v[136:139], v[168:171], v[44:47]
	v_mfma_f32_16x16x32_bf16 v[40:43], v[144:147], v[168:171], v[40:43]
	v_mfma_f32_16x16x32_bf16 v[36:39], v[136:139], v[194:197], v[36:39]
	s_barrier
	v_mfma_f32_16x16x32_bf16 v[32:35], v[144:147], v[194:197], v[32:35]
	s_setprio 0
	s_add_u32 s38, s38, 0x80080
	s_addc_u32 s39, s39, 0
	s_add_i32 s46, s46, s1
	v_lshl_add_u64 v[132:133], s[38:39], 0, v[176:177]
	s_mov_b32 m0, s46
	s_nop 0
	global_load_lds_dwordx4 v[132:133], off
	v_lshl_add_u64 v[132:133], s[38:39], 0, v[178:179]
	s_add_i32 m0, s46, 0x2000
	s_nop 0
	global_load_lds_dwordx4 v[132:133], off
	s_waitcnt vmcnt(6)
	s_barrier
	s_setprio 1
	v_mfma_f32_16x16x32_bf16 v[28:31], v[198:201], v[148:151], v[28:31]
	v_mfma_f32_16x16x32_bf16 v[24:27], v[208:211], v[148:151], v[24:27]
	v_mfma_f32_16x16x32_bf16 v[20:23], v[198:201], v[156:159], v[20:23]
	v_mfma_f32_16x16x32_bf16 v[16:19], v[208:211], v[156:159], v[16:19]
	v_mfma_f32_16x16x32_bf16 v[12:15], v[198:201], v[164:167], v[12:15]
	v_mfma_f32_16x16x32_bf16 v[8:11], v[208:211], v[164:167], v[8:11]
	v_mfma_f32_16x16x32_bf16 v[4:7], v[198:201], v[172:175], v[4:7]
	v_mfma_f32_16x16x32_bf16 v[0:3], v[208:211], v[172:175], v[0:3]
	v_mfma_f32_16x16x32_bf16 v[28:31], v[204:207], v[152:155], v[28:31]
	v_mfma_f32_16x16x32_bf16 v[24:27], v[212:215], v[152:155], v[24:27]
	v_mfma_f32_16x16x32_bf16 v[20:23], v[204:207], v[160:163], v[20:23]
	v_mfma_f32_16x16x32_bf16 v[16:19], v[212:215], v[160:163], v[16:19]
	v_mfma_f32_16x16x32_bf16 v[12:15], v[204:207], v[168:171], v[12:15]
	v_mfma_f32_16x16x32_bf16 v[8:11], v[212:215], v[168:171], v[8:11]
	v_mfma_f32_16x16x32_bf16 v[4:7], v[204:207], v[194:197], v[4:7]
	s_barrier
	v_mfma_f32_16x16x32_bf16 v[0:3], v[212:215], v[194:197], v[0:3]
	s_setprio 0
	s_add_i32 s67, s67, 2
	s_add_u32 s36, s36, 0x100
	s_addc_u32 s37, s37, 0
	s_cmp_gt_u32 s67, 29
	s_cbranch_scc0 .LBB0_2964
	s_add_u32 s36, s13, 0xffffff00
	s_addc_u32 s37, s51, -1
	s_ashr_i32 s13, s12, 31
	s_lshl_b32 s38, s53, 8
	s_lshl_b64 s[46:47], s[12:13], 21
	s_ashr_i32 s39, s38, 31
	v_lshl_add_u64 v[128:129], v[182:183], 0, s[46:47]
	v_lshl_add_u64 v[128:129], s[38:39], 2, v[128:129]
	v_lshl_add_u64 v[194:195], v[128:129], 0, v[180:181]
	global_load_dwordx4 v[128:131], v[194:195], off
	global_load_dwordx4 v[132:135], v[194:195], off offset:64
	global_load_dwordx4 v[136:139], v[194:195], off offset:512
	global_load_dwordx4 v[140:143], v[194:195], off offset:576
	v_add_co_u32_e32 v196, vcc, s58, v194
	s_waitcnt vmcnt(0)
	v_pk_add_f32 v[130:131], v[126:127], v[130:131]
	v_addc_co_u32_e32 v197, vcc, 0, v195, vcc
	global_load_dwordx4 v[144:147], v[196:197], off
	global_load_dwordx4 v[148:151], v[196:197], off offset:64
	global_load_dwordx4 v[152:155], v[196:197], off offset:512
	global_load_dwordx4 v[156:159], v[196:197], off offset:576
	v_add_co_u32_e32 v200, vcc, s59, v194
	v_pk_add_f32 v[128:129], v[124:125], v[128:129]
	s_nop 0
	v_addc_co_u32_e32 v201, vcc, 0, v195, vcc
	global_load_dwordx4 v[160:163], v[200:201], off
	global_load_dwordx4 v[164:167], v[200:201], off offset:64
	global_load_dwordx4 v[168:171], v[200:201], off offset:512
	global_load_dwordx4 v[172:175], v[200:201], off offset:576
	v_add_co_u32_e32 v220, vcc, s60, v194
	s_waitcnt vmcnt(0)
	v_pk_add_f32 v[162:163], v[110:111], v[162:163]
	v_addc_co_u32_e32 v221, vcc, 0, v195, vcc
	global_load_dwordx4 v[204:207], v[220:221], off
	global_load_dwordx4 v[208:211], v[220:221], off offset:64
	global_load_dwordx4 v[212:215], v[220:221], off offset:512
	global_load_dwordx4 v[216:219], v[220:221], off offset:576
	v_add_co_u32_e32 v198, vcc, s61, v194
	global_store_dwordx4 v[194:195], v[128:131], off
	s_nop 0
	v_addc_co_u32_e32 v199, vcc, 0, v195, vcc
	v_pk_add_f32 v[130:131], v[122:123], v[134:135]
	v_pk_add_f32 v[128:129], v[120:121], v[132:133]
	global_store_dwordx4 v[194:195], v[128:131], off offset:64
	v_pk_add_f32 v[160:161], v[108:109], v[160:161]
	s_nop 0
	v_pk_add_f32 v[130:131], v[94:95], v[138:139]
	v_pk_add_f32 v[128:129], v[92:93], v[136:137]
	global_store_dwordx4 v[194:195], v[128:131], off offset:512
	s_nop 1
	v_pk_add_f32 v[130:131], v[90:91], v[142:143]
	v_pk_add_f32 v[128:129], v[88:89], v[140:141]
	global_store_dwordx4 v[194:195], v[128:131], off offset:576
	s_nop 1
	v_pk_add_f32 v[130:131], v[118:119], v[146:147]
	v_pk_add_f32 v[128:129], v[116:117], v[144:145]
	global_store_dwordx4 v[196:197], v[128:131], off
	s_nop 1
	v_pk_add_f32 v[130:131], v[114:115], v[150:151]
	v_pk_add_f32 v[128:129], v[112:113], v[148:149]
	global_store_dwordx4 v[196:197], v[128:131], off offset:64
	s_nop 1
	v_pk_add_f32 v[130:131], v[86:87], v[154:155]
	v_pk_add_f32 v[128:129], v[84:85], v[152:153]
	global_store_dwordx4 v[196:197], v[128:131], off offset:512
	s_nop 1
	v_pk_add_f32 v[130:131], v[82:83], v[158:159]
	v_pk_add_f32 v[128:129], v[80:81], v[156:157]
	global_store_dwordx4 v[196:197], v[128:131], off offset:576
	v_add_co_u32_e32 v196, vcc, s62, v194
	global_load_dwordx4 v[156:159], v[198:199], off
	global_load_dwordx4 v[152:155], v[198:199], off offset:64
	global_load_dwordx4 v[144:147], v[198:199], off offset:512
	global_load_dwordx4 v[136:139], v[198:199], off offset:576
	v_addc_co_u32_e32 v197, vcc, 0, v195, vcc
	global_load_dwordx4 v[148:151], v[196:197], off
	global_load_dwordx4 v[140:143], v[196:197], off offset:64
	global_load_dwordx4 v[132:135], v[196:197], off offset:512
	global_load_dwordx4 v[128:131], v[196:197], off offset:576
	s_waitcnt vmcnt(0)
; #define RES_LOAD(dst_, k_) do { _Pragma("unroll") for (int mm = 0; mm < 2; ++mm) _Pragma("unroll") for (int bj = 0; bj < 2; ++bj) _Pragma("unroll") for (int n = 0; n < 2; ++n) \
;             dst_[mm][bj][n] = *(const f32x4*)(xin + RES_OFF(k_, mm, bj, n)); } while (0)
; #define RES_STORE(src_, k_) do { _Pragma("unroll") for (int mm = 0; mm < 2; ++mm) _Pragma("unroll") for (int bj = 0; bj < 2; ++bj) _Pragma("unroll") for (int n = 0; n < 2; ++n) \
;             *(f32x4*)(xout + RES_OFF(k_, mm, bj, n)) = src_[mm][bj][n] + al * acc[(k_) >> 1][bj][((k_) & 1) * 2 + mm][n]; } while (0)
; template <class Epi>
; __device__ __forceinline__ void gemm_phase(LAS unsigned char* lds, const Gemm g, const Sched& S, const Epi& E) {
;     ...
;         if (!has_next) break;
; #pragma unroll
;         for (int a = 0; a < 2; ++a)
; #pragma unroll
;             for (int b = 0; b < 2; ++b)
; #pragma unroll
;                 for (int m = 0; m < 4; ++m)
; #pragma unroll
;                     for (int n = 0; n < 2; ++n) acc[a][b][m][n] = (f32x4){0.f, 0.f, 0.f, 0.f};
;         cur = nxt; cA = nA; cB = nB; ++ui;
;     __device__ __forceinline__ void operator()(AccRef acc, const Unit& u, int wr, int wc, int fr, int fq) const {
;         const float al = alpha;
;         const size_t base = ((size_t)u.pm * 256 + wr * 64 + fr) * D_ + u.pn * 256 + wc * 32 + 4 * fq;
;         f32x4 xa[2][2][2], xb[2][2][2];
;     ...
;         RES_LOAD(xa, 0); RES_LOAD(xb, 1);
;         RES_STORE(xa, 0); RES_LOAD(xa, 2);
;         RES_STORE(xb, 1); RES_LOAD(xb, 3);
;         RES_STORE(xa, 2); RES_STORE(xb, 3);
	v_pk_add_f32 v[158:159], v[62:63], v[158:159]
	global_store_dwordx4 v[200:201], v[160:163], off
	v_pk_add_f32 v[156:157], v[60:61], v[156:157]
	v_pk_add_f32 v[138:139], v[26:27], v[138:139]
	v_pk_add_f32 v[162:163], v[106:107], v[166:167]
	v_pk_add_f32 v[160:161], v[104:105], v[164:165]
	global_store_dwordx4 v[200:201], v[160:163], off offset:64
	v_pk_add_f32 v[130:131], v[18:19], v[130:131]
	v_pk_add_f32 v[128:129], v[16:17], v[128:129]
	v_pk_add_f32 v[162:163], v[78:79], v[170:171]
	v_pk_add_f32 v[160:161], v[76:77], v[168:169]
	global_store_dwordx4 v[200:201], v[160:163], off offset:512
	v_pk_add_f32 v[136:137], v[24:25], v[136:137]
	v_pk_add_f32 v[154:155], v[58:59], v[154:155]
	v_pk_add_f32 v[162:163], v[74:75], v[174:175]
	v_pk_add_f32 v[160:161], v[72:73], v[172:173]
	global_store_dwordx4 v[200:201], v[160:163], off offset:576
	v_add_co_u32_e32 v200, vcc, s63, v194
	s_nop 0
	v_pk_add_f32 v[162:163], v[102:103], v[206:207]
	v_pk_add_f32 v[160:161], v[100:101], v[204:205]
	global_store_dwordx4 v[220:221], v[160:163], off
	v_addc_co_u32_e32 v201, vcc, 0, v195, vcc
	s_nop 0
	v_pk_add_f32 v[162:163], v[98:99], v[210:211]
	v_pk_add_f32 v[160:161], v[96:97], v[208:209]
	global_store_dwordx4 v[220:221], v[160:163], off offset:64
	v_add_co_u32_e32 v194, vcc, s64, v194
	s_nop 0
	v_pk_add_f32 v[162:163], v[70:71], v[214:215]
	v_pk_add_f32 v[160:161], v[68:69], v[212:213]
	global_store_dwordx4 v[220:221], v[160:163], off offset:512
	v_addc_co_u32_e32 v195, vcc, 0, v195, vcc
	s_nop 0
	v_pk_add_f32 v[162:163], v[66:67], v[218:219]
	v_pk_add_f32 v[160:161], v[64:65], v[216:217]
	global_store_dwordx4 v[220:221], v[160:163], off offset:576
	global_load_dwordx4 v[172:175], v[200:201], off
	global_load_dwordx4 v[168:171], v[200:201], off offset:64
	global_load_dwordx4 v[164:167], v[200:201], off offset:512
	s_nop 0
	global_load_dwordx4 v[160:163], v[200:201], off offset:576
	global_load_dwordx4 v[204:207], v[194:195], off
	global_load_dwordx4 v[208:211], v[194:195], off offset:64
	global_load_dwordx4 v[212:215], v[194:195], off offset:512
	global_load_dwordx4 v[216:219], v[194:195], off offset:576
	v_pk_add_f32 v[152:153], v[56:57], v[152:153]
	global_store_dwordx4 v[196:197], v[128:131], off offset:576
	global_store_dwordx4 v[198:199], v[136:139], off offset:576
	v_pk_add_f32 v[146:147], v[30:31], v[146:147]
	v_pk_add_f32 v[144:145], v[28:29], v[144:145]
	v_pk_add_f32 v[138:139], v[54:55], v[150:151]
	v_pk_add_f32 v[136:137], v[52:53], v[148:149]
	global_store_dwordx4 v[196:197], v[136:139], off
	v_pk_add_f32 v[134:135], v[22:23], v[134:135]
	v_pk_add_f32 v[132:133], v[20:21], v[132:133]
	v_pk_add_f32 v[138:139], v[50:51], v[142:143]
	v_pk_add_f32 v[136:137], v[48:49], v[140:141]
	s_andn2_b64 vcc, exec, s[10:11]
	global_store_dwordx4 v[198:199], v[156:159], off
	global_store_dwordx4 v[198:199], v[152:155], off offset:64
	global_store_dwordx4 v[198:199], v[144:147], off offset:512
	global_store_dwordx4 v[196:197], v[136:139], off offset:64
	global_store_dwordx4 v[196:197], v[132:135], off offset:512
	s_waitcnt vmcnt(0)
	v_pk_add_f32 v[130:131], v[46:47], v[174:175]
	v_pk_add_f32 v[128:129], v[44:45], v[172:173]
	global_store_dwordx4 v[200:201], v[128:131], off
	s_nop 1
	v_pk_add_f32 v[130:131], v[42:43], v[170:171]
	v_pk_add_f32 v[128:129], v[40:41], v[168:169]
	global_store_dwordx4 v[200:201], v[128:131], off offset:64
	s_nop 1
	v_pk_add_f32 v[130:131], v[14:15], v[166:167]
	v_pk_add_f32 v[128:129], v[12:13], v[164:165]
	global_store_dwordx4 v[200:201], v[128:131], off offset:512
	s_nop 1
	v_pk_add_f32 v[130:131], v[10:11], v[162:163]
	v_pk_add_f32 v[128:129], v[8:9], v[160:161]
	global_store_dwordx4 v[200:201], v[128:131], off offset:576
	s_nop 1
	v_pk_add_f32 v[130:131], v[38:39], v[206:207]
	v_pk_add_f32 v[128:129], v[36:37], v[204:205]
	global_store_dwordx4 v[194:195], v[128:131], off
	s_nop 1
	v_pk_add_f32 v[130:131], v[34:35], v[210:211]
	v_pk_add_f32 v[128:129], v[32:33], v[208:209]
	global_store_dwordx4 v[194:195], v[128:131], off offset:64
	s_nop 1
	v_pk_add_f32 v[130:131], v[6:7], v[214:215]
	v_pk_add_f32 v[128:129], v[4:5], v[212:213]
	global_store_dwordx4 v[194:195], v[128:131], off offset:512
	s_nop 1
	v_pk_add_f32 v[130:131], v[2:3], v[218:219]
	v_pk_add_f32 v[128:129], v[0:1], v[216:217]
	global_store_dwordx4 v[194:195], v[128:131], off offset:576
	s_cbranch_vccz .LBB0_2956
	s_mov_b64 s[22:23], s[36:37]
	s_andn2_b64 vcc, exec, s[8:9]
	s_mov_b64 s[36:37], s[22:23]
	s_cbranch_vccnz .LBB0_2957

; #define PG8_STAGE(bufoff, gbase, voff) do { _Pragma("unroll") for (int _i = 0; _i < 2; ++_i) \
;         __builtin_amdgcn_global_load_lds((const unsigned*)((const char*)(gbase) + (voff)[_i]), (LAS unsigned*)(lds + (bufoff) + ldsw + _i * 8192), 16, 0, 0); } while (0)
; #define PG8_LDA(dst, b, h) do { _Pragma("unroll") for (int m = 0; m < 4; ++m) _Pragma("unroll") for (int k = 0; k < 2; ++k) dst[m][k] = *(const LAS bf16x8*)(lds + PG8_SA(b, h) + aoff + m * 2048 + k * 1024); } while (0)
; #define PG8_LDB(dst, b, h) do { _Pragma("unroll") for (int n = 0; n < 2; ++n) _Pragma("unroll") for (int k = 0; k < 2; ++k) dst[n][k] = *(const LAS bf16x8*)(lds + PG8_SB(b, h) + boff + n * 2048 + k * 1024); } while (0)
; #define PG8_WAIT_V(n) asm volatile("s_waitcnt vmcnt(" #n ")" ::: "memory")
; #define PG8_WAIT_L(n) asm volatile("s_waitcnt lgkmcnt(" #n ")" ::: "memory")
; #define PG8_BAR __builtin_amdgcn_s_barrier()
; #define PG8_SCHED __builtin_amdgcn_sched_barrier(0)
; template <class Epi>
; __device__ __forceinline__ void gemm_phase(LAS unsigned char* lds, const Gemm g, const Sched& S, const Epi& E) {
;     ...
;             PG8_LDB(B0, 0, 0); PG8_SCHED; PG8_LDA(At, 0, 0); PG8_STAGE(PG8_SA(1, 1), a1 + hstepA, voffA);
;             PG8_WAIT_L(8); PG8_BAR; PG8_WAIT_L(0); PG8_MMA(0, 0, At, B0); PG8_BAR; PG8_SCHED;
;             PG8_LDB(B1, 0, 1); PG8_STAGE(PG8_SB(0, 0), b2, voffB);
;             PG8_BAR; PG8_WAIT_L(0); PG8_MMA(0, 1, At, B1); PG8_BAR;
;             PG8_LDA(At, 0, 1); PG8_STAGE(PG8_SA(0, 0), a2, voffA);
;             PG8_BAR; PG8_WAIT_L(0); PG8_MMA(1, 0, At, B0); PG8_BAR; PG8_SCHED;
;             PG8_STAGE(PG8_SB(0, 1), b2 + hstepB, voffB);
;             PG8_WAIT_V(6); PG8_BAR; PG8_MMA(1, 1, At, B1); PG8_BAR;
;             PG8_LDB(B0, 1, 0); PG8_SCHED; PG8_LDA(At, 1, 0); PG8_STAGE(PG8_SA(0, 1), a2 + hstepA, voffA);
;             PG8_WAIT_L(8); PG8_BAR; PG8_WAIT_L(0); PG8_MMA(0, 0, At, B0); PG8_BAR; PG8_SCHED;
;             PG8_LDB(B1, 1, 1); PG8_STAGE(PG8_SB(1, 0), b3, voffB);
;             PG8_BAR; PG8_WAIT_L(0); PG8_MMA(0, 1, At, B1); PG8_BAR;
;             PG8_LDA(At, 1, 1); PG8_STAGE(PG8_SA(1, 0), a3, voffA);
;             PG8_BAR; PG8_WAIT_L(0); PG8_MMA(1, 0, At, B0); PG8_BAR; PG8_SCHED;
;             PG8_STAGE(PG8_SB(1, 1), b3 + hstepB, voffB);
;             PG8_WAIT_V(6); PG8_BAR; PG8_MMA(1, 1, At, B1); PG8_BAR;
.LBB0_3085:
	v_add_u32_e32 v162, s54, v148
	s_add_u32 s36, s12, s24
	ds_read_b128 v[150:153], v162
	ds_read_b128 v[154:157], v162 offset:1024
	ds_read_b128 v[158:161], v162 offset:2048
	ds_read_b128 v[162:165], v162 offset:3072
	s_addc_u32 s37, s13, s25
	s_add_u32 s36, s36, 0x100
	s_addc_u32 s37, s37, 0
	s_add_u32 s70, s11, s24
	s_addc_u32 s71, s64, s25
	s_cmpk_eq_i32 s24, 0xf00
	s_cselect_b32 s39, s19, s37
	s_cselect_b32 s38, s65, s36
	s_cselect_b32 s37, s17, s71
	s_cselect_b32 s36, s66, s70
	v_lshl_add_u64 v[190:191], v[144:145], 0, s[24:25]
	s_add_i32 m0, s40, 0xc000
	ds_read_b128 v[166:169], v149
	ds_read_b128 v[170:173], v149 offset:1024
	ds_read_b128 v[174:177], v149 offset:2048
	ds_read_b128 v[178:181], v149 offset:3072
	ds_read_b128 v[182:185], v149 offset:4096
	ds_read_b128 v[186:189], v149 offset:5120
	ds_read_b128 v[194:197], v149 offset:6144
	ds_read_b128 v[198:201], v149 offset:7168
	global_load_lds_dwordx4 v[190:191], off
	v_lshl_add_u64 v[190:191], v[146:147], 0, s[24:25]
	s_add_i32 m0, s40, 0xe000
	s_nop 0
	global_load_lds_dwordx4 v[190:191], off
	s_waitcnt lgkmcnt(8)
	s_barrier
	s_waitcnt lgkmcnt(0)
	s_setprio 1
	s_waitcnt lgkmcnt(0)
	v_mfma_f32_16x16x32_bf16 v[124:127], v[150:153], v[166:169], v[124:127]
	v_mfma_f32_16x16x32_bf16 v[120:123], v[158:161], v[166:169], v[120:123]
	v_mfma_f32_16x16x32_bf16 v[116:119], v[150:153], v[174:177], v[116:119]
	v_mfma_f32_16x16x32_bf16 v[112:115], v[158:161], v[174:177], v[112:115]
	v_mfma_f32_16x16x32_bf16 v[108:111], v[150:153], v[182:185], v[108:111]
	v_mfma_f32_16x16x32_bf16 v[104:107], v[158:161], v[182:185], v[104:107]
	v_mfma_f32_16x16x32_bf16 v[100:103], v[150:153], v[194:197], v[100:103]
	v_mfma_f32_16x16x32_bf16 v[96:99], v[158:161], v[194:197], v[96:99]
	v_mfma_f32_16x16x32_bf16 v[124:127], v[154:157], v[170:173], v[124:127]
	v_mfma_f32_16x16x32_bf16 v[120:123], v[162:165], v[170:173], v[120:123]
	v_mfma_f32_16x16x32_bf16 v[116:119], v[154:157], v[178:181], v[116:119]
	v_mfma_f32_16x16x32_bf16 v[112:115], v[162:165], v[178:181], v[112:115]
	v_mfma_f32_16x16x32_bf16 v[108:111], v[154:157], v[186:189], v[108:111]
	v_mfma_f32_16x16x32_bf16 v[104:107], v[162:165], v[186:189], v[104:107]
	v_mfma_f32_16x16x32_bf16 v[100:103], v[154:157], v[198:201], v[100:103]
	s_barrier
	v_mfma_f32_16x16x32_bf16 v[96:99], v[162:165], v[198:201], v[96:99]
	s_setprio 0
	v_add_u32_e32 v190, s55, v148
	s_add_i32 s70, s54, s34
	ds_read_b128 v[202:205], v190
	ds_read_b128 v[206:209], v190 offset:1024
	ds_read_b128 v[210:213], v190 offset:2048
	ds_read_b128 v[214:217], v190 offset:3072
	v_lshl_add_u64 v[190:191], s[36:37], 0, v[130:131]
	s_mov_b32 m0, s70
	v_lshl_add_u64 v[218:219], s[36:37], 0, v[128:129]
	global_load_lds_dwordx4 v[190:191], off
	s_add_i32 m0, s70, 0x2000
	s_nop 0
	global_load_lds_dwordx4 v[218:219], off
	s_barrier
	s_waitcnt lgkmcnt(0)
	s_setprio 1
	s_waitcnt lgkmcnt(0)
	v_mfma_f32_16x16x32_bf16 v[92:95], v[202:205], v[166:169], v[92:95]
	v_mfma_f32_16x16x32_bf16 v[88:91], v[210:213], v[166:169], v[88:91]
	v_mfma_f32_16x16x32_bf16 v[84:87], v[202:205], v[174:177], v[84:87]
	v_mfma_f32_16x16x32_bf16 v[80:83], v[210:213], v[174:177], v[80:83]
	v_mfma_f32_16x16x32_bf16 v[76:79], v[202:205], v[182:185], v[76:79]
	v_mfma_f32_16x16x32_bf16 v[72:75], v[210:213], v[182:185], v[72:75]
	v_mfma_f32_16x16x32_bf16 v[68:71], v[202:205], v[194:197], v[68:71]
	v_mfma_f32_16x16x32_bf16 v[64:67], v[210:213], v[194:197], v[64:67]
	v_mfma_f32_16x16x32_bf16 v[92:95], v[206:209], v[170:173], v[92:95]
	v_mfma_f32_16x16x32_bf16 v[88:91], v[214:217], v[170:173], v[88:91]
	v_mfma_f32_16x16x32_bf16 v[84:87], v[206:209], v[178:181], v[84:87]
	v_mfma_f32_16x16x32_bf16 v[80:83], v[214:217], v[178:181], v[80:83]
	v_mfma_f32_16x16x32_bf16 v[76:79], v[206:209], v[186:189], v[76:79]
	v_mfma_f32_16x16x32_bf16 v[72:75], v[214:217], v[186:189], v[72:75]
	v_mfma_f32_16x16x32_bf16 v[68:71], v[206:209], v[198:201], v[68:71]
	s_barrier
	v_mfma_f32_16x16x32_bf16 v[64:67], v[214:217], v[198:201], v[64:67]
	s_setprio 0
	s_mov_b32 m0, s40
	v_lshl_add_u64 v[220:221], s[38:39], 0, v[130:131]
	ds_read_b128 v[166:169], v149 offset:16384
	ds_read_b128 v[170:173], v149 offset:17408
	ds_read_b128 v[174:177], v149 offset:18432
	ds_read_b128 v[178:181], v149 offset:19456
	ds_read_b128 v[182:185], v149 offset:20480
	ds_read_b128 v[186:189], v149 offset:21504
	ds_read_b128 v[194:197], v149 offset:22528
	ds_read_b128 v[198:201], v149 offset:23552
	global_load_lds_dwordx4 v[220:221], off
	v_lshl_add_u64 v[222:223], s[38:39], 0, v[128:129]
	s_mov_b32 m0, s41
	s_nop 0
	global_load_lds_dwordx4 v[222:223], off
	s_barrier
	s_waitcnt lgkmcnt(0)
	s_setprio 1
	s_waitcnt lgkmcnt(0)
	v_mfma_f32_16x16x32_bf16 v[60:63], v[150:153], v[166:169], v[60:63]
	v_mfma_f32_16x16x32_bf16 v[56:59], v[158:161], v[166:169], v[56:59]
	v_mfma_f32_16x16x32_bf16 v[52:55], v[150:153], v[174:177], v[52:55]
	v_mfma_f32_16x16x32_bf16 v[48:51], v[158:161], v[174:177], v[48:51]
	v_mfma_f32_16x16x32_bf16 v[44:47], v[150:153], v[182:185], v[44:47]
	v_mfma_f32_16x16x32_bf16 v[40:43], v[158:161], v[182:185], v[40:43]
	v_mfma_f32_16x16x32_bf16 v[36:39], v[150:153], v[194:197], v[36:39]
	v_mfma_f32_16x16x32_bf16 v[32:35], v[158:161], v[194:197], v[32:35]
	v_mfma_f32_16x16x32_bf16 v[60:63], v[154:157], v[170:173], v[60:63]
	v_mfma_f32_16x16x32_bf16 v[56:59], v[162:165], v[170:173], v[56:59]
	v_mfma_f32_16x16x32_bf16 v[52:55], v[154:157], v[178:181], v[52:55]
	v_mfma_f32_16x16x32_bf16 v[48:51], v[162:165], v[178:181], v[48:51]
	v_mfma_f32_16x16x32_bf16 v[44:47], v[154:157], v[186:189], v[44:47]
	v_mfma_f32_16x16x32_bf16 v[40:43], v[162:165], v[186:189], v[40:43]
	v_mfma_f32_16x16x32_bf16 v[36:39], v[154:157], v[198:201], v[36:39]
	s_barrier
; #define PG8_STAGE(bufoff, gbase, voff) do { _Pragma("unroll") for (int _i = 0; _i < 2; ++_i) \
;         __builtin_amdgcn_global_load_lds((const unsigned*)((const char*)(gbase) + (voff)[_i]), (LAS unsigned*)(lds + (bufoff) + ldsw + _i * 8192), 16, 0, 0); } while (0)
; #define PG8_LDA(dst, b, h) do { _Pragma("unroll") for (int m = 0; m < 4; ++m) _Pragma("unroll") for (int k = 0; k < 2; ++k) dst[m][k] = *(const LAS bf16x8*)(lds + PG8_SA(b, h) + aoff + m * 2048 + k * 1024); } while (0)
; #define PG8_LDB(dst, b, h) do { _Pragma("unroll") for (int n = 0; n < 2; ++n) _Pragma("unroll") for (int k = 0; k < 2; ++k) dst[n][k] = *(const LAS bf16x8*)(lds + PG8_SB(b, h) + boff + n * 2048 + k * 1024); } while (0)
; #define PG8_WAIT_V(n) asm volatile("s_waitcnt vmcnt(" #n ")" ::: "memory")
; #define PG8_WAIT_L(n) asm volatile("s_waitcnt lgkmcnt(" #n ")" ::: "memory")
; #define PG8_BAR __builtin_amdgcn_s_barrier()
; #define PG8_SCHED __builtin_amdgcn_sched_barrier(0)
; template <class Epi>
; __device__ __forceinline__ void gemm_phase(LAS unsigned char* lds, const Gemm g, const Sched& S, const Epi& E) {
;     ...
;             PG8_LDB(B0, 0, 0); PG8_SCHED; PG8_LDA(At, 0, 0); PG8_STAGE(PG8_SA(1, 1), a1 + hstepA, voffA);
;             PG8_WAIT_L(8); PG8_BAR; PG8_WAIT_L(0); PG8_MMA(0, 0, At, B0); PG8_BAR; PG8_SCHED;
;             PG8_LDB(B1, 0, 1); PG8_STAGE(PG8_SB(0, 0), b2, voffB);
;             PG8_BAR; PG8_WAIT_L(0); PG8_MMA(0, 1, At, B1); PG8_BAR;
;             PG8_LDA(At, 0, 1); PG8_STAGE(PG8_SA(0, 0), a2, voffA);
;             PG8_BAR; PG8_WAIT_L(0); PG8_MMA(1, 0, At, B0); PG8_BAR; PG8_SCHED;
;             PG8_STAGE(PG8_SB(0, 1), b2 + hstepB, voffB);
;             PG8_WAIT_V(6); PG8_BAR; PG8_MMA(1, 1, At, B1); PG8_BAR;
;             PG8_LDB(B0, 1, 0); PG8_SCHED; PG8_LDA(At, 1, 0); PG8_STAGE(PG8_SA(0, 1), a2 + hstepA, voffA);
;             PG8_WAIT_L(8); PG8_BAR; PG8_WAIT_L(0); PG8_MMA(0, 0, At, B0); PG8_BAR; PG8_SCHED;
;             PG8_LDB(B1, 1, 1); PG8_STAGE(PG8_SB(1, 0), b3, voffB);
;             PG8_BAR; PG8_WAIT_L(0); PG8_MMA(0, 1, At, B1); PG8_BAR;
;             PG8_LDA(At, 1, 1); PG8_STAGE(PG8_SA(1, 0), a3, voffA);
;             PG8_BAR; PG8_WAIT_L(0); PG8_MMA(1, 0, At, B0); PG8_BAR; PG8_SCHED;
;             PG8_STAGE(PG8_SB(1, 1), b3 + hstepB, voffB);
;             PG8_WAIT_V(6); PG8_BAR; PG8_MMA(1, 1, At, B1); PG8_BAR;
	v_mfma_f32_16x16x32_bf16 v[32:35], v[162:165], v[198:201], v[32:35]
	s_setprio 0
	s_add_u32 s70, s36, 0x80000
	s_addc_u32 s71, s37, 0
	s_add_i32 s72, s55, s34
	v_lshl_add_u64 v[150:151], s[70:71], 0, v[130:131]
	s_mov_b32 m0, s72
	s_nop 0
	global_load_lds_dwordx4 v[150:151], off
	v_lshl_add_u64 v[150:151], s[70:71], 0, v[128:129]
	s_add_i32 m0, s72, 0x2000
	s_nop 0
	global_load_lds_dwordx4 v[150:151], off
	s_waitcnt vmcnt(6)
	s_barrier
	s_setprio 1
	v_mfma_f32_16x16x32_bf16 v[28:31], v[202:205], v[166:169], v[28:31]
	v_mfma_f32_16x16x32_bf16 v[24:27], v[210:213], v[166:169], v[24:27]
	v_mfma_f32_16x16x32_bf16 v[20:23], v[202:205], v[174:177], v[20:23]
	v_mfma_f32_16x16x32_bf16 v[16:19], v[210:213], v[174:177], v[16:19]
	v_mfma_f32_16x16x32_bf16 v[12:15], v[202:205], v[182:185], v[12:15]
	v_mfma_f32_16x16x32_bf16 v[8:11], v[210:213], v[182:185], v[8:11]
	v_mfma_f32_16x16x32_bf16 v[4:7], v[202:205], v[194:197], v[4:7]
	v_mfma_f32_16x16x32_bf16 v[0:3], v[210:213], v[194:197], v[0:3]
	v_mfma_f32_16x16x32_bf16 v[28:31], v[206:209], v[170:173], v[28:31]
	v_mfma_f32_16x16x32_bf16 v[24:27], v[214:217], v[170:173], v[24:27]
	v_mfma_f32_16x16x32_bf16 v[20:23], v[206:209], v[178:181], v[20:23]
	v_mfma_f32_16x16x32_bf16 v[16:19], v[214:217], v[178:181], v[16:19]
	v_mfma_f32_16x16x32_bf16 v[12:15], v[206:209], v[186:189], v[12:15]
	v_mfma_f32_16x16x32_bf16 v[8:11], v[214:217], v[186:189], v[8:11]
	v_mfma_f32_16x16x32_bf16 v[4:7], v[206:209], v[198:201], v[4:7]
	s_barrier
	v_mfma_f32_16x16x32_bf16 v[0:3], v[214:217], v[198:201], v[0:3]
	s_setprio 0
	s_add_i32 s70, 0, 0x18000
	v_add_u32_e32 v162, s70, v148
	ds_read_b128 v[150:153], v162
	ds_read_b128 v[154:157], v162 offset:1024
	ds_read_b128 v[158:161], v162 offset:2048
	ds_read_b128 v[162:165], v162 offset:3072
	s_add_u32 s38, s38, 0x80000
	s_addc_u32 s39, s39, 0
	s_mov_b32 m0, s43
	v_lshl_add_u64 v[202:203], s[38:39], 0, v[130:131]
	ds_read_b128 v[166:169], v149 offset:32768
	ds_read_b128 v[170:173], v149 offset:33792
	ds_read_b128 v[174:177], v149 offset:34816
	ds_read_b128 v[178:181], v149 offset:35840
	ds_read_b128 v[182:185], v149 offset:36864
	ds_read_b128 v[186:189], v149 offset:37888
	ds_read_b128 v[194:197], v149 offset:38912
	ds_read_b128 v[198:201], v149 offset:39936
	global_load_lds_dwordx4 v[202:203], off
	v_lshl_add_u64 v[202:203], s[38:39], 0, v[128:129]
	s_mov_b32 m0, s46
	s_nop 0
	global_load_lds_dwordx4 v[202:203], off
	s_waitcnt lgkmcnt(8)
	s_barrier
	s_waitcnt lgkmcnt(0)
	s_setprio 1
	s_waitcnt lgkmcnt(0)
	v_mfma_f32_16x16x32_bf16 v[124:127], v[150:153], v[166:169], v[124:127]
	v_mfma_f32_16x16x32_bf16 v[120:123], v[158:161], v[166:169], v[120:123]
	v_mfma_f32_16x16x32_bf16 v[116:119], v[150:153], v[174:177], v[116:119]
	v_mfma_f32_16x16x32_bf16 v[112:115], v[158:161], v[174:177], v[112:115]
	v_mfma_f32_16x16x32_bf16 v[108:111], v[150:153], v[182:185], v[108:111]
	v_mfma_f32_16x16x32_bf16 v[104:107], v[158:161], v[182:185], v[104:107]
	v_mfma_f32_16x16x32_bf16 v[100:103], v[150:153], v[194:197], v[100:103]
	v_mfma_f32_16x16x32_bf16 v[96:99], v[158:161], v[194:197], v[96:99]
	v_mfma_f32_16x16x32_bf16 v[124:127], v[154:157], v[170:173], v[124:127]
	v_mfma_f32_16x16x32_bf16 v[120:123], v[162:165], v[170:173], v[120:123]
	v_mfma_f32_16x16x32_bf16 v[116:119], v[154:157], v[178:181], v[116:119]
	v_mfma_f32_16x16x32_bf16 v[112:115], v[162:165], v[178:181], v[112:115]
	v_mfma_f32_16x16x32_bf16 v[108:111], v[154:157], v[186:189], v[108:111]
	v_mfma_f32_16x16x32_bf16 v[104:107], v[162:165], v[186:189], v[104:107]
	v_mfma_f32_16x16x32_bf16 v[100:103], v[154:157], v[198:201], v[100:103]
	s_barrier
	v_mfma_f32_16x16x32_bf16 v[96:99], v[162:165], v[198:201], v[96:99]
	s_setprio 0
	s_add_i32 s38, 0, 0x1c000
	s_add_i32 s39, s70, s34
	v_add_u32_e32 v214, s38, v148
	v_lshl_add_u64 v[190:191], v[190:191], 0, s[14:15]
	s_mov_b32 m0, s39
	ds_read_b128 v[202:205], v214
	ds_read_b128 v[206:209], v214 offset:1024
	ds_read_b128 v[210:213], v214 offset:2048
	ds_read_b128 v[214:217], v214 offset:3072
	global_load_lds_dwordx4 v[190:191], off
	v_lshl_add_u64 v[190:191], v[218:219], 0, s[14:15]
	s_add_i32 m0, s39, 0x2000
	s_nop 0
	global_load_lds_dwordx4 v[190:191], off
	s_barrier
	s_waitcnt lgkmcnt(0)
	s_setprio 1
	s_waitcnt lgkmcnt(0)
	v_mfma_f32_16x16x32_bf16 v[92:95], v[202:205], v[166:169], v[92:95]
	v_mfma_f32_16x16x32_bf16 v[88:91], v[210:213], v[166:169], v[88:91]
	v_mfma_f32_16x16x32_bf16 v[84:87], v[202:205], v[174:177], v[84:87]
	v_mfma_f32_16x16x32_bf16 v[80:83], v[210:213], v[174:177], v[80:83]
	v_mfma_f32_16x16x32_bf16 v[76:79], v[202:205], v[182:185], v[76:79]
	v_mfma_f32_16x16x32_bf16 v[72:75], v[210:213], v[182:185], v[72:75]
	v_mfma_f32_16x16x32_bf16 v[68:71], v[202:205], v[194:197], v[68:71]
	v_mfma_f32_16x16x32_bf16 v[64:67], v[210:213], v[194:197], v[64:67]
	v_mfma_f32_16x16x32_bf16 v[92:95], v[206:209], v[170:173], v[92:95]
	v_mfma_f32_16x16x32_bf16 v[88:91], v[214:217], v[170:173], v[88:91]
	v_mfma_f32_16x16x32_bf16 v[84:87], v[206:209], v[178:181], v[84:87]
	v_mfma_f32_16x16x32_bf16 v[80:83], v[214:217], v[178:181], v[80:83]
	v_mfma_f32_16x16x32_bf16 v[76:79], v[206:209], v[186:189], v[76:79]
	v_mfma_f32_16x16x32_bf16 v[72:75], v[214:217], v[186:189], v[72:75]
	v_mfma_f32_16x16x32_bf16 v[68:71], v[206:209], v[198:201], v[68:71]
	s_barrier
	v_mfma_f32_16x16x32_bf16 v[64:67], v[214:217], v[198:201], v[64:67]
	s_setprio 0
	s_mov_b32 m0, s52
	v_lshl_add_u64 v[190:191], v[220:221], 0, s[14:15]
	ds_read_b128 v[166:169], v149 offset:49152
	ds_read_b128 v[170:173], v149 offset:50176
	ds_read_b128 v[174:177], v149 offset:51200
	ds_read_b128 v[178:181], v149 offset:52224
	ds_read_b128 v[182:185], v149 offset:53248
	ds_read_b128 v[186:189], v149 offset:54272
	ds_read_b128 v[194:197], v149 offset:55296
	ds_read_b128 v[198:201], v149 offset:56320
	global_load_lds_dwordx4 v[190:191], off
	v_lshl_add_u64 v[190:191], v[222:223], 0, s[14:15]
	s_mov_b32 m0, s53
	s_nop 0
	global_load_lds_dwordx4 v[190:191], off
	s_barrier
; __device__ __forceinline__ unsigned cvt_pk_bf16(float lo, float hi) { unsigned r; asm volatile("v_cvt_pk_bf16_f32 %0, %1, %2" : "=v"(r) : "v"(lo), "v"(hi)); return r; }
; #define PG8_STAGE(bufoff, gbase, voff) do { _Pragma("unroll") for (int _i = 0; _i < 2; ++_i) \
;         __builtin_amdgcn_global_load_lds((const unsigned*)((const char*)(gbase) + (voff)[_i]), (LAS unsigned*)(lds + (bufoff) + ldsw + _i * 8192), 16, 0, 0); } while (0)
; #define PG8_LDA(dst, b, h) do { _Pragma("unroll") for (int m = 0; m < 4; ++m) _Pragma("unroll") for (int k = 0; k < 2; ++k) dst[m][k] = *(const LAS bf16x8*)(lds + PG8_SA(b, h) + aoff + m * 2048 + k * 1024); } while (0)
; #define PG8_WAIT_V(n) asm volatile("s_waitcnt vmcnt(" #n ")" ::: "memory")
; template <class Epi>
; __device__ __forceinline__ void gemm_phase(LAS unsigned char* lds, const Gemm g, const Sched& S, const Epi& E) {
;     ...
;             PG8_WAIT_V(6); PG8_BAR; PG8_MMA(1, 1, At, B1); PG8_BAR;
;             PG8_LDB(B0, 1, 0); PG8_SCHED; PG8_LDA(At, 1, 0); PG8_STAGE(PG8_SA(0, 1), a2 + hstepA, voffA);
;             PG8_WAIT_L(8); PG8_BAR; PG8_WAIT_L(0); PG8_MMA(0, 0, At, B0); PG8_BAR; PG8_SCHED;
;             PG8_LDB(B1, 1, 1); PG8_STAGE(PG8_SB(1, 0), b3, voffB);
;             PG8_BAR; PG8_WAIT_L(0); PG8_MMA(0, 1, At, B1); PG8_BAR;
;             PG8_LDA(At, 1, 1); PG8_STAGE(PG8_SA(1, 0), a3, voffA);
;             PG8_BAR; PG8_WAIT_L(0); PG8_MMA(1, 0, At, B0); PG8_BAR; PG8_SCHED;
;             PG8_STAGE(PG8_SB(1, 1), b3 + hstepB, voffB);
;             PG8_WAIT_V(6); PG8_BAR; PG8_MMA(1, 1, At, B1); PG8_BAR;
;     __device__ __forceinline__ void operator()(AccRef acc, const Unit& u, int wr, int wc, int fr, int fq) const {
; #pragma unroll
;         for (int ai = 0; ai < 2; ++ai)
; #pragma unroll
;             for (int m = 0; m < 4; ++m) { const size_t row = (size_t)u.pm * 256 + ai * 128 + wr * 64 + m * 16 + fr; float o[8];
; #pragma unroll
;                 for (int bj = 0; bj < 2; ++bj) { const f32x4 gg = acc[ai][bj][m][0], uu = acc[ai][bj][m][1];
; #pragma unroll
;                     for (int j = 0; j < 4; ++j) o[4 * bj + j] = gg[j] * __builtin_amdgcn_rcpf(1.0f + __expf(-gg[j])) * uu[j]; }
;                 u32x4 w; w.x = cvt_pk_bf16(o[0], o[1]); w.y = cvt_pk_bf16(o[2], o[3]); w.z = cvt_pk_bf16(o[4], o[5]); w.w = cvt_pk_bf16(o[6], o[7]);
;                 *(u32x4*)(act + row * FF_ + (u.pn * 4 + wc) * 32 + 8 * fq) = w; }
	s_waitcnt lgkmcnt(0)
	s_setprio 1
	s_waitcnt lgkmcnt(0)
	v_mfma_f32_16x16x32_bf16 v[60:63], v[150:153], v[166:169], v[60:63]
	v_mfma_f32_16x16x32_bf16 v[56:59], v[158:161], v[166:169], v[56:59]
	v_mfma_f32_16x16x32_bf16 v[52:55], v[150:153], v[174:177], v[52:55]
	v_mfma_f32_16x16x32_bf16 v[48:51], v[158:161], v[174:177], v[48:51]
	v_mfma_f32_16x16x32_bf16 v[44:47], v[150:153], v[182:185], v[44:47]
	v_mfma_f32_16x16x32_bf16 v[40:43], v[158:161], v[182:185], v[40:43]
	v_mfma_f32_16x16x32_bf16 v[36:39], v[150:153], v[194:197], v[36:39]
	v_mfma_f32_16x16x32_bf16 v[32:35], v[158:161], v[194:197], v[32:35]
	v_mfma_f32_16x16x32_bf16 v[60:63], v[154:157], v[170:173], v[60:63]
	v_mfma_f32_16x16x32_bf16 v[56:59], v[162:165], v[170:173], v[56:59]
	v_mfma_f32_16x16x32_bf16 v[52:55], v[154:157], v[178:181], v[52:55]
	v_mfma_f32_16x16x32_bf16 v[48:51], v[162:165], v[178:181], v[48:51]
	v_mfma_f32_16x16x32_bf16 v[44:47], v[154:157], v[186:189], v[44:47]
	v_mfma_f32_16x16x32_bf16 v[40:43], v[162:165], v[186:189], v[40:43]
	v_mfma_f32_16x16x32_bf16 v[36:39], v[154:157], v[198:201], v[36:39]
	s_barrier
	v_mfma_f32_16x16x32_bf16 v[32:35], v[162:165], v[198:201], v[32:35]
	s_setprio 0
	s_add_u32 s36, s36, 0x80080
	s_addc_u32 s37, s37, 0
	s_add_i32 s38, s38, s34
	v_lshl_add_u64 v[150:151], s[36:37], 0, v[130:131]
	s_mov_b32 m0, s38
	s_nop 0
	global_load_lds_dwordx4 v[150:151], off
	v_lshl_add_u64 v[150:151], s[36:37], 0, v[128:129]
	s_add_i32 m0, s38, 0x2000
	s_nop 0
	global_load_lds_dwordx4 v[150:151], off
	s_waitcnt vmcnt(6)
	s_barrier
	s_setprio 1
	v_mfma_f32_16x16x32_bf16 v[28:31], v[202:205], v[166:169], v[28:31]
	v_mfma_f32_16x16x32_bf16 v[24:27], v[210:213], v[166:169], v[24:27]
	v_mfma_f32_16x16x32_bf16 v[20:23], v[202:205], v[174:177], v[20:23]
	v_mfma_f32_16x16x32_bf16 v[16:19], v[210:213], v[174:177], v[16:19]
	v_mfma_f32_16x16x32_bf16 v[12:15], v[202:205], v[182:185], v[12:15]
	v_mfma_f32_16x16x32_bf16 v[8:11], v[210:213], v[182:185], v[8:11]
	v_mfma_f32_16x16x32_bf16 v[4:7], v[202:205], v[194:197], v[4:7]
	v_mfma_f32_16x16x32_bf16 v[0:3], v[210:213], v[194:197], v[0:3]
	v_mfma_f32_16x16x32_bf16 v[28:31], v[206:209], v[170:173], v[28:31]
	v_mfma_f32_16x16x32_bf16 v[24:27], v[214:217], v[170:173], v[24:27]
	v_mfma_f32_16x16x32_bf16 v[20:23], v[206:209], v[178:181], v[20:23]
	v_mfma_f32_16x16x32_bf16 v[16:19], v[214:217], v[178:181], v[16:19]
	v_mfma_f32_16x16x32_bf16 v[12:15], v[206:209], v[186:189], v[12:15]
	v_mfma_f32_16x16x32_bf16 v[8:11], v[214:217], v[186:189], v[8:11]
	v_mfma_f32_16x16x32_bf16 v[4:7], v[206:209], v[198:201], v[4:7]
	s_barrier
	v_mfma_f32_16x16x32_bf16 v[0:3], v[214:217], v[198:201], v[0:3]
	s_setprio 0
	s_add_i32 s67, s67, 2
	s_add_u32 s24, s24, 0x100
	s_addc_u32 s25, s25, 0
	s_cmp_gt_u32 s67, 29
	s_cbranch_scc0 .LBB0_3085
	v_mul_f32_e32 v150, 0xbfb8aa3b, v126
	v_exp_f32_e32 v150, v150
	v_mul_f32_e32 v151, 0xbfb8aa3b, v127
	v_exp_f32_e32 v151, v151
	v_mul_f32_e32 v152, 0xbfb8aa3b, v92
	v_add_f32_e32 v150, 1.0, v150
	v_rcp_f32_e32 v150, v150
	v_add_f32_e32 v151, 1.0, v151
	v_rcp_f32_e32 v151, v151
	v_exp_f32_e32 v152, v152
	v_mul_f32_e32 v150, v126, v150
	v_mul_f32_e32 v153, v122, v150
	v_mul_f32_e32 v150, v127, v151
	v_add_f32_e32 v151, 1.0, v152
	v_rcp_f32_e32 v151, v151
	v_mul_f32_e32 v152, 0xbfb8aa3b, v93
	v_exp_f32_e32 v152, v152
	v_mul_f32_e32 v146, 0xbfb8aa3b, v124
	v_mul_f32_e32 v147, 0xbfb8aa3b, v125
	v_mul_f32_e32 v154, v123, v150
	v_mul_f32_e32 v150, v92, v151
	v_mul_f32_e32 v151, 0xbfb8aa3b, v94
	v_exp_f32_e32 v146, v146
	v_exp_f32_e32 v147, v147
	v_mul_f32_e32 v155, v88, v150
	v_add_f32_e32 v150, 1.0, v152
	v_exp_f32_e32 v151, v151
	v_mul_f32_e32 v152, 0xbfb8aa3b, v95
	v_exp_f32_e32 v152, v152
	v_add_f32_e32 v146, 1.0, v146
	v_add_f32_e32 v147, 1.0, v147
	v_rcp_f32_e32 v150, v150
	v_add_f32_e32 v151, 1.0, v151
	v_rcp_f32_e32 v146, v146
	v_rcp_f32_e32 v147, v147
	v_rcp_f32_e32 v151, v151
	v_add_f32_e32 v152, 1.0, v152
	v_rcp_f32_e32 v152, v152
	s_add_u32 s24, s11, 0xffffff00
	v_mul_f32_e32 v150, v93, v150
	s_addc_u32 s25, s64, -1
	s_ashr_i32 s11, s10, 31
	v_mul_f32_e32 v146, v124, v146
	v_mul_f32_e32 v147, v125, v147
	v_mul_f32_e32 v156, v89, v150
	v_mul_f32_e32 v150, v94, v151
	s_lshl_b64 s[36:37], s[10:11], 8
	v_mul_f32_e32 v146, v120, v146
	v_mul_f32_e32 v147, v121, v147
	v_mul_f32_e32 v157, v90, v150
	v_mul_f32_e32 v150, v95, v152
	v_lshl_add_u64 v[144:145], v[134:135], 0, s[36:37]
	v_mul_f32_e32 v158, v91, v150
	v_cvt_pk_bf16_f32 v150, v146, v147
	v_mov_b64_e32 v[146:147], s[44:45]
	v_mad_u64_u32 v[146:147], s[38:39], v144, s56, v[146:147]
	s_lshl_b32 s11, s50, 7
	v_mov_b32_e32 v144, v147
	s_or_b32 s36, s11, s51
	v_mad_u64_u32 v[144:145], s[38:39], v145, s56, v[144:145]
	s_ashr_i32 s37, s36, 31
	v_mov_b32_e32 v147, v144
	v_lshl_add_u64 v[144:145], s[36:37], 1, v[146:147]
	v_lshl_add_u64 v[144:145], v[144:145], 0, v[132:133]
	v_cvt_pk_bf16_f32 v151, v153, v154
	v_cvt_pk_bf16_f32 v152, v155, v156
	v_cvt_pk_bf16_f32 v153, v157, v158
	global_store_dwordx4 v[144:145], v[150:153], off
	v_mul_f32_e32 v146, 0xbfb8aa3b, v116
	v_exp_f32_e32 v146, v146
	v_mul_f32_e32 v150, 0xbfb8aa3b, v118
	v_exp_f32_e32 v150, v150
	v_mul_f32_e32 v151, 0xbfb8aa3b, v119
	v_exp_f32_e32 v151, v151
	v_mul_f32_e32 v152, 0xbfb8aa3b, v84
	v_add_f32_e32 v150, 1.0, v150
	v_rcp_f32_e32 v150, v150
	v_add_f32_e32 v151, 1.0, v151
	v_rcp_f32_e32 v151, v151
	v_exp_f32_e32 v152, v152
	v_mul_f32_e32 v150, v118, v150
	v_mul_f32_e32 v153, v114, v150
	v_mul_f32_e32 v150, v119, v151
	v_add_f32_e32 v151, 1.0, v152
	v_rcp_f32_e32 v151, v151
	v_mul_f32_e32 v152, 0xbfb8aa3b, v85
	v_exp_f32_e32 v152, v152
	v_mul_f32_e32 v154, v115, v150
	v_mul_f32_e32 v150, v84, v151
; __device__ __forceinline__ unsigned cvt_pk_bf16(float lo, float hi) { unsigned r; asm volatile("v_cvt_pk_bf16_f32 %0, %1, %2" : "=v"(r) : "v"(lo), "v"(hi)); return r; }
;     __device__ __forceinline__ void operator()(AccRef acc, const Unit& u, int wr, int wc, int fr, int fq) const {
; #pragma unroll
;         for (int ai = 0; ai < 2; ++ai)
; #pragma unroll
;             for (int m = 0; m < 4; ++m) { const size_t row = (size_t)u.pm * 256 + ai * 128 + wr * 64 + m * 16 + fr; float o[8];
; #pragma unroll
;                 for (int bj = 0; bj < 2; ++bj) { const f32x4 gg = acc[ai][bj][m][0], uu = acc[ai][bj][m][1];
; #pragma unroll
;                     for (int j = 0; j < 4; ++j) o[4 * bj + j] = gg[j] * __builtin_amdgcn_rcpf(1.0f + __expf(-gg[j])) * uu[j]; }
;                 u32x4 w; w.x = cvt_pk_bf16(o[0], o[1]); w.y = cvt_pk_bf16(o[2], o[3]); w.z = cvt_pk_bf16(o[4], o[5]); w.w = cvt_pk_bf16(o[6], o[7]);
;                 *(u32x4*)(act + row * FF_ + (u.pn * 4 + wc) * 32 + 8 * fq) = w; }
	v_mul_f32_e32 v151, 0xbfb8aa3b, v86
	v_mul_f32_e32 v147, 0xbfb8aa3b, v117
	v_mul_f32_e32 v155, v80, v150
	v_add_f32_e32 v150, 1.0, v152
	v_exp_f32_e32 v151, v151
	v_mul_f32_e32 v152, 0xbfb8aa3b, v87
	v_exp_f32_e32 v147, v147
	v_exp_f32_e32 v152, v152
	v_add_f32_e32 v146, 1.0, v146
	v_rcp_f32_e32 v150, v150
	v_add_f32_e32 v151, 1.0, v151
	v_rcp_f32_e32 v146, v146
	v_add_f32_e32 v147, 1.0, v147
	v_rcp_f32_e32 v151, v151
	v_add_f32_e32 v152, 1.0, v152
	v_rcp_f32_e32 v147, v147
	v_rcp_f32_e32 v152, v152
	v_mul_f32_e32 v150, v85, v150
	v_mul_f32_e32 v146, v116, v146
	v_mul_f32_e32 v156, v81, v150
	v_mul_f32_e32 v150, v86, v151
	v_mul_f32_e32 v146, v112, v146
	v_mul_f32_e32 v147, v117, v147
	v_mul_f32_e32 v157, v82, v150
	v_mul_f32_e32 v150, v87, v152
	v_mul_f32_e32 v147, v113, v147
	v_mul_f32_e32 v158, v83, v150
	v_cvt_pk_bf16_f32 v150, v146, v147
	v_mul_f32_e32 v146, 0xbfb8aa3b, v108
	v_cvt_pk_bf16_f32 v151, v153, v154
	v_exp_f32_e32 v154, v146
	v_mul_f32_e32 v146, 0xbfb8aa3b, v109
	v_cvt_pk_bf16_f32 v152, v155, v156
	v_exp_f32_e32 v155, v146
	v_add_co_u32_e32 v146, vcc, s57, v144
	v_cvt_pk_bf16_f32 v153, v157, v158
	v_add_f32_e32 v154, 1.0, v154
	s_nop 0
	v_addc_co_u32_e32 v147, vcc, 0, v145, vcc
	global_store_dwordx4 v[146:147], v[150:153], off
	v_rcp_f32_e32 v154, v154
	v_add_f32_e32 v155, 1.0, v155
	v_mul_f32_e32 v150, 0xbfb8aa3b, v110
	v_exp_f32_e32 v150, v150
	v_mul_f32_e32 v151, 0xbfb8aa3b, v111
	v_exp_f32_e32 v151, v151
	v_mul_f32_e32 v152, 0xbfb8aa3b, v76
	v_add_f32_e32 v150, 1.0, v150
	v_rcp_f32_e32 v150, v150
	v_add_f32_e32 v151, 1.0, v151
	v_rcp_f32_e32 v151, v151
	v_exp_f32_e32 v152, v152
	v_mul_f32_e32 v150, v110, v150
	v_mul_f32_e32 v153, v106, v150
	v_mul_f32_e32 v150, v111, v151
	v_add_f32_e32 v151, 1.0, v152
	v_rcp_f32_e32 v151, v151
	v_mul_f32_e32 v152, 0xbfb8aa3b, v77
	v_rcp_f32_e32 v155, v155
	v_exp_f32_e32 v152, v152
	v_mul_f32_e32 v146, v108, v154
	v_mul_f32_e32 v154, v107, v150
	v_mul_f32_e32 v150, v76, v151
	v_mul_f32_e32 v151, 0xbfb8aa3b, v78
	v_mul_f32_e32 v147, v109, v155
	v_mul_f32_e32 v155, v72, v150
	v_add_f32_e32 v150, 1.0, v152
	v_exp_f32_e32 v151, v151
	v_mul_f32_e32 v152, 0xbfb8aa3b, v79
	v_exp_f32_e32 v152, v152
	v_rcp_f32_e32 v150, v150
	v_add_f32_e32 v151, 1.0, v151
	v_rcp_f32_e32 v151, v151
	v_add_f32_e32 v152, 1.0, v152
	v_rcp_f32_e32 v152, v152
	v_mul_f32_e32 v150, v77, v150
	v_mul_f32_e32 v156, v73, v150
	v_mul_f32_e32 v150, v78, v151
	v_mul_f32_e32 v146, v104, v146
	v_mul_f32_e32 v157, v74, v150
	v_mul_f32_e32 v150, v79, v152
	v_mul_f32_e32 v147, v105, v147
	v_mul_f32_e32 v158, v75, v150
	v_cvt_pk_bf16_f32 v150, v146, v147
	v_mul_f32_e32 v146, 0xbfb8aa3b, v100
	v_cvt_pk_bf16_f32 v151, v153, v154
	v_exp_f32_e32 v154, v146
	v_mul_f32_e32 v146, 0xbfb8aa3b, v101
	v_cvt_pk_bf16_f32 v152, v155, v156
	v_exp_f32_e32 v155, v146
	v_add_co_u32_e32 v146, vcc, s58, v144
	v_cvt_pk_bf16_f32 v153, v157, v158
	v_add_f32_e32 v154, 1.0, v154
	s_nop 0
	v_addc_co_u32_e32 v147, vcc, 0, v145, vcc
	global_store_dwordx4 v[146:147], v[150:153], off
	v_rcp_f32_e32 v154, v154
	v_add_f32_e32 v155, 1.0, v155
	v_mul_f32_e32 v150, 0xbfb8aa3b, v102
	v_exp_f32_e32 v150, v150
	v_mul_f32_e32 v151, 0xbfb8aa3b, v103
	v_exp_f32_e32 v151, v151
	v_mul_f32_e32 v152, 0xbfb8aa3b, v68
	v_add_f32_e32 v150, 1.0, v150
	v_rcp_f32_e32 v150, v150
	v_add_f32_e32 v151, 1.0, v151
	v_rcp_f32_e32 v151, v151
	v_exp_f32_e32 v152, v152
	v_mul_f32_e32 v150, v102, v150
	v_mul_f32_e32 v153, v98, v150
	v_mul_f32_e32 v150, v103, v151
	v_add_f32_e32 v151, 1.0, v152
	v_rcp_f32_e32 v151, v151
	v_mul_f32_e32 v152, 0xbfb8aa3b, v69
	v_rcp_f32_e32 v155, v155
	v_exp_f32_e32 v152, v152
	v_mul_f32_e32 v146, v100, v154
	v_mul_f32_e32 v154, v99, v150
	v_mul_f32_e32 v150, v68, v151
	v_mul_f32_e32 v151, 0xbfb8aa3b, v70
	v_mul_f32_e32 v147, v101, v155
	v_mul_f32_e32 v155, v64, v150
	v_add_f32_e32 v150, 1.0, v152
	v_exp_f32_e32 v151, v151
	v_mul_f32_e32 v152, 0xbfb8aa3b, v71
	v_exp_f32_e32 v152, v152
	v_rcp_f32_e32 v150, v150
	v_add_f32_e32 v151, 1.0, v151
	v_rcp_f32_e32 v151, v151
	v_add_f32_e32 v152, 1.0, v152
	v_rcp_f32_e32 v152, v152
	v_mul_f32_e32 v150, v69, v150
	v_mul_f32_e32 v156, v65, v150
	v_mul_f32_e32 v150, v70, v151
	v_mul_f32_e32 v146, v96, v146
	v_mul_f32_e32 v157, v66, v150
	v_mul_f32_e32 v150, v71, v152
	v_mul_f32_e32 v147, v97, v147
	v_mul_f32_e32 v158, v67, v150
	v_cvt_pk_bf16_f32 v150, v146, v147
	v_mul_f32_e32 v146, 0xbfb8aa3b, v60
	v_cvt_pk_bf16_f32 v151, v153, v154
	v_exp_f32_e32 v154, v146
	v_mul_f32_e32 v146, 0xbfb8aa3b, v61
	v_cvt_pk_bf16_f32 v152, v155, v156
	v_exp_f32_e32 v155, v146
	v_add_co_u32_e32 v146, vcc, s59, v144
	v_cvt_pk_bf16_f32 v153, v157, v158
	v_add_f32_e32 v154, 1.0, v154
	s_nop 0
	v_addc_co_u32_e32 v147, vcc, 0, v145, vcc
	global_store_dwordx4 v[146:147], v[150:153], off
	v_rcp_f32_e32 v154, v154
	v_add_f32_e32 v155, 1.0, v155
	v_mul_f32_e32 v150, 0xbfb8aa3b, v62
	v_exp_f32_e32 v150, v150
	v_mul_f32_e32 v151, 0xbfb8aa3b, v63
	v_exp_f32_e32 v151, v151
	v_mul_f32_e32 v152, 0xbfb8aa3b, v28
	v_add_f32_e32 v150, 1.0, v150
	v_rcp_f32_e32 v150, v150
	v_add_f32_e32 v151, 1.0, v151
	v_rcp_f32_e32 v151, v151
	v_exp_f32_e32 v152, v152
	v_mul_f32_e32 v150, v62, v150
	v_mul_f32_e32 v153, v58, v150
	v_mul_f32_e32 v150, v63, v151
	v_add_f32_e32 v151, 1.0, v152
	v_rcp_f32_e32 v151, v151
	v_mul_f32_e32 v152, 0xbfb8aa3b, v29
	v_rcp_f32_e32 v155, v155
	v_exp_f32_e32 v152, v152
	v_mul_f32_e32 v146, v60, v154
	v_mul_f32_e32 v154, v59, v150
	v_mul_f32_e32 v150, v28, v151
	v_mul_f32_e32 v151, 0xbfb8aa3b, v30
	v_mul_f32_e32 v147, v61, v155
	v_mul_f32_e32 v155, v24, v150
	v_add_f32_e32 v150, 1.0, v152
	v_exp_f32_e32 v151, v151
	v_mul_f32_e32 v152, 0xbfb8aa3b, v31
; __device__ __forceinline__ unsigned cvt_pk_bf16(float lo, float hi) { unsigned r; asm volatile("v_cvt_pk_bf16_f32 %0, %1, %2" : "=v"(r) : "v"(lo), "v"(hi)); return r; }
; template <class Epi>
; __device__ __forceinline__ void gemm_phase(LAS unsigned char* lds, const Gemm g, const Sched& S, const Epi& E) {
;     ...
;         if (!has_next) break;
; #pragma unroll
;         for (int a = 0; a < 2; ++a)
; #pragma unroll
;             for (int b = 0; b < 2; ++b)
; #pragma unroll
;                 for (int m = 0; m < 4; ++m)
; #pragma unroll
;                     for (int n = 0; n < 2; ++n) acc[a][b][m][n] = (f32x4){0.f, 0.f, 0.f, 0.f};
;         cur = nxt; cA = nA; cB = nB; ++ui;
;     __device__ __forceinline__ void operator()(AccRef acc, const Unit& u, int wr, int wc, int fr, int fq) const {
; #pragma unroll
;         for (int ai = 0; ai < 2; ++ai)
; #pragma unroll
;             for (int m = 0; m < 4; ++m) { const size_t row = (size_t)u.pm * 256 + ai * 128 + wr * 64 + m * 16 + fr; float o[8];
; #pragma unroll
;                 for (int bj = 0; bj < 2; ++bj) { const f32x4 gg = acc[ai][bj][m][0], uu = acc[ai][bj][m][1];
; #pragma unroll
;                     for (int j = 0; j < 4; ++j) o[4 * bj + j] = gg[j] * __builtin_amdgcn_rcpf(1.0f + __expf(-gg[j])) * uu[j]; }
;                 u32x4 w; w.x = cvt_pk_bf16(o[0], o[1]); w.y = cvt_pk_bf16(o[2], o[3]); w.z = cvt_pk_bf16(o[4], o[5]); w.w = cvt_pk_bf16(o[6], o[7]);
;                 *(u32x4*)(act + row * FF_ + (u.pn * 4 + wc) * 32 + 8 * fq) = w; }
	v_exp_f32_e32 v152, v152
	v_rcp_f32_e32 v150, v150
	v_add_f32_e32 v151, 1.0, v151
	v_rcp_f32_e32 v151, v151
	v_add_f32_e32 v152, 1.0, v152
	v_rcp_f32_e32 v152, v152
	v_mul_f32_e32 v150, v29, v150
	v_mul_f32_e32 v156, v25, v150
	v_mul_f32_e32 v150, v30, v151
	v_mul_f32_e32 v146, v56, v146
	v_mul_f32_e32 v157, v26, v150
	v_mul_f32_e32 v150, v31, v152
	v_mul_f32_e32 v147, v57, v147
	v_mul_f32_e32 v158, v27, v150
	v_cvt_pk_bf16_f32 v150, v146, v147
	v_mul_f32_e32 v146, 0xbfb8aa3b, v52
	v_cvt_pk_bf16_f32 v151, v153, v154
	v_exp_f32_e32 v154, v146
	v_mul_f32_e32 v146, 0xbfb8aa3b, v53
	v_cvt_pk_bf16_f32 v152, v155, v156
	v_exp_f32_e32 v155, v146
	v_add_co_u32_e32 v146, vcc, s60, v144
	v_cvt_pk_bf16_f32 v153, v157, v158
	v_add_f32_e32 v154, 1.0, v154
	s_nop 0
	v_addc_co_u32_e32 v147, vcc, 0, v145, vcc
	global_store_dwordx4 v[146:147], v[150:153], off
	v_rcp_f32_e32 v154, v154
	v_add_f32_e32 v155, 1.0, v155
	v_mul_f32_e32 v150, 0xbfb8aa3b, v54
	v_exp_f32_e32 v150, v150
	v_mul_f32_e32 v151, 0xbfb8aa3b, v55
	v_exp_f32_e32 v151, v151
	v_mul_f32_e32 v152, 0xbfb8aa3b, v20
	v_add_f32_e32 v150, 1.0, v150
	v_rcp_f32_e32 v150, v150
	v_add_f32_e32 v151, 1.0, v151
	v_rcp_f32_e32 v151, v151
	v_exp_f32_e32 v152, v152
	v_mul_f32_e32 v150, v54, v150
	v_mul_f32_e32 v153, v50, v150
	v_mul_f32_e32 v150, v55, v151
	v_add_f32_e32 v151, 1.0, v152
	v_rcp_f32_e32 v151, v151
	v_mul_f32_e32 v152, 0xbfb8aa3b, v21
	v_rcp_f32_e32 v155, v155
	v_exp_f32_e32 v152, v152
	v_mul_f32_e32 v146, v52, v154
	v_mul_f32_e32 v154, v51, v150
	v_mul_f32_e32 v150, v20, v151
	v_mul_f32_e32 v151, 0xbfb8aa3b, v22
	v_mul_f32_e32 v147, v53, v155
	v_mul_f32_e32 v155, v16, v150
	v_add_f32_e32 v150, 1.0, v152
	v_exp_f32_e32 v151, v151
	v_mul_f32_e32 v152, 0xbfb8aa3b, v23
	v_exp_f32_e32 v152, v152
	v_rcp_f32_e32 v150, v150
	v_add_f32_e32 v151, 1.0, v151
	v_rcp_f32_e32 v151, v151
	v_add_f32_e32 v152, 1.0, v152
	v_rcp_f32_e32 v152, v152
	v_mul_f32_e32 v150, v21, v150
	v_mul_f32_e32 v156, v17, v150
	v_mul_f32_e32 v150, v22, v151
	v_mul_f32_e32 v146, v48, v146
	v_mul_f32_e32 v157, v18, v150
	v_mul_f32_e32 v150, v23, v152
	v_mul_f32_e32 v147, v49, v147
	v_mul_f32_e32 v158, v19, v150
	v_cvt_pk_bf16_f32 v150, v146, v147
	v_mul_f32_e32 v146, 0xbfb8aa3b, v44
	v_cvt_pk_bf16_f32 v151, v153, v154
	v_exp_f32_e32 v154, v146
	v_mul_f32_e32 v146, 0xbfb8aa3b, v45
	v_cvt_pk_bf16_f32 v152, v155, v156
	v_exp_f32_e32 v155, v146
	v_add_co_u32_e32 v146, vcc, s61, v144
	v_cvt_pk_bf16_f32 v153, v157, v158
	v_add_f32_e32 v154, 1.0, v154
	s_nop 0
	v_addc_co_u32_e32 v147, vcc, 0, v145, vcc
	global_store_dwordx4 v[146:147], v[150:153], off
	v_rcp_f32_e32 v154, v154
	v_add_f32_e32 v155, 1.0, v155
	v_mul_f32_e32 v150, 0xbfb8aa3b, v46
	v_exp_f32_e32 v150, v150
	v_mul_f32_e32 v151, 0xbfb8aa3b, v47
	v_exp_f32_e32 v151, v151
	v_mul_f32_e32 v152, 0xbfb8aa3b, v12
	v_add_f32_e32 v150, 1.0, v150
	v_rcp_f32_e32 v150, v150
	v_add_f32_e32 v151, 1.0, v151
	v_rcp_f32_e32 v151, v151
	v_exp_f32_e32 v152, v152
	v_mul_f32_e32 v150, v46, v150
	v_mul_f32_e32 v153, v42, v150
	v_mul_f32_e32 v150, v47, v151
	v_add_f32_e32 v151, 1.0, v152
	v_rcp_f32_e32 v151, v151
	v_mul_f32_e32 v152, 0xbfb8aa3b, v13
	v_rcp_f32_e32 v155, v155
	v_exp_f32_e32 v152, v152
	v_mul_f32_e32 v146, v44, v154
	v_mul_f32_e32 v154, v43, v150
	v_mul_f32_e32 v150, v12, v151
	v_mul_f32_e32 v151, 0xbfb8aa3b, v14
	v_mul_f32_e32 v147, v45, v155
	v_mul_f32_e32 v155, v8, v150
	v_add_f32_e32 v150, 1.0, v152
	v_exp_f32_e32 v151, v151
	v_mul_f32_e32 v152, 0xbfb8aa3b, v15
	v_exp_f32_e32 v152, v152
	v_rcp_f32_e32 v150, v150
	v_add_f32_e32 v151, 1.0, v151
	v_rcp_f32_e32 v151, v151
	v_add_f32_e32 v152, 1.0, v152
	v_rcp_f32_e32 v152, v152
	v_mul_f32_e32 v150, v13, v150
	v_mul_f32_e32 v156, v9, v150
	v_mul_f32_e32 v150, v14, v151
	v_mul_f32_e32 v146, v40, v146
	v_mul_f32_e32 v157, v10, v150
	v_mul_f32_e32 v150, v15, v152
	v_mul_f32_e32 v147, v41, v147
	v_mul_f32_e32 v158, v11, v150
	v_cvt_pk_bf16_f32 v150, v146, v147
	v_mul_f32_e32 v146, 0xbfb8aa3b, v36
	v_cvt_pk_bf16_f32 v151, v153, v154
	v_exp_f32_e32 v154, v146
	v_mul_f32_e32 v146, 0xbfb8aa3b, v37
	v_cvt_pk_bf16_f32 v152, v155, v156
	v_exp_f32_e32 v155, v146
	v_add_co_u32_e32 v146, vcc, s62, v144
	v_cvt_pk_bf16_f32 v153, v157, v158
	v_add_f32_e32 v154, 1.0, v154
	s_nop 0
	v_addc_co_u32_e32 v147, vcc, 0, v145, vcc
	global_store_dwordx4 v[146:147], v[150:153], off
	v_rcp_f32_e32 v154, v154
	v_add_f32_e32 v155, 1.0, v155
	v_mul_f32_e32 v150, 0xbfb8aa3b, v38
	v_exp_f32_e32 v150, v150
	v_mul_f32_e32 v151, 0xbfb8aa3b, v39
	v_exp_f32_e32 v151, v151
	v_mul_f32_e32 v152, 0xbfb8aa3b, v4
	v_add_f32_e32 v150, 1.0, v150
	v_rcp_f32_e32 v150, v150
	v_add_f32_e32 v151, 1.0, v151
	v_rcp_f32_e32 v151, v151
	v_exp_f32_e32 v152, v152
	v_mul_f32_e32 v150, v38, v150
	v_mul_f32_e32 v153, v34, v150
	v_mul_f32_e32 v150, v39, v151
	v_add_f32_e32 v151, 1.0, v152
	v_rcp_f32_e32 v151, v151
	v_mul_f32_e32 v152, 0xbfb8aa3b, v5
	v_rcp_f32_e32 v155, v155
	v_exp_f32_e32 v152, v152
	v_mul_f32_e32 v146, v36, v154
	v_mul_f32_e32 v154, v35, v150
	v_mul_f32_e32 v150, v4, v151
	v_mul_f32_e32 v151, 0xbfb8aa3b, v6
	v_mul_f32_e32 v147, v37, v155
	v_mul_f32_e32 v155, v0, v150
	v_add_f32_e32 v150, 1.0, v152
	v_exp_f32_e32 v151, v151
	v_mul_f32_e32 v152, 0xbfb8aa3b, v7
	v_exp_f32_e32 v152, v152
	v_rcp_f32_e32 v150, v150
	v_add_f32_e32 v151, 1.0, v151
	v_rcp_f32_e32 v151, v151
	v_add_f32_e32 v152, 1.0, v152
	v_rcp_f32_e32 v152, v152
	v_mul_f32_e32 v150, v5, v150
	v_add_co_u32_e32 v144, vcc, 0x1e4000, v144
	v_mul_f32_e32 v156, v1, v150
	v_mul_f32_e32 v150, v6, v151
	v_addc_co_u32_e32 v145, vcc, 0, v145, vcc
	v_mul_f32_e32 v157, v2, v150
	v_mul_f32_e32 v150, v7, v152
	s_andn2_b64 vcc, exec, s[8:9]
	v_mul_f32_e32 v146, v32, v146
	v_mul_f32_e32 v147, v33, v147
	v_mul_f32_e32 v158, v3, v150
	v_cvt_pk_bf16_f32 v150, v146, v147
	v_cvt_pk_bf16_f32 v151, v153, v154
	v_cvt_pk_bf16_f32 v152, v155, v156
	v_cvt_pk_bf16_f32 v153, v157, v158
	global_store_dwordx4 v[144:145], v[150:153], off
	s_cbranch_vccz .LBB0_3081
	s_mov_b64 s[20:21], s[24:25]
	s_andn2_b64 vcc, exec, s[6:7]
	s_mov_b64 s[24:25], s[20:21]
	s_cbranch_vccnz .LBB0_3082

; #define PG8_STAGE(bufoff, gbase, voff) do { _Pragma("unroll") for (int _i = 0; _i < 2; ++_i) \
;         __builtin_amdgcn_global_load_lds((const unsigned*)((const char*)(gbase) + (voff)[_i]), (LAS unsigned*)(lds + (bufoff) + ldsw + _i * 8192), 16, 0, 0); } while (0)
; #define PG8_LDA(dst, b, h) do { _Pragma("unroll") for (int m = 0; m < 4; ++m) _Pragma("unroll") for (int k = 0; k < 2; ++k) dst[m][k] = *(const LAS bf16x8*)(lds + PG8_SA(b, h) + aoff + m * 2048 + k * 1024); } while (0)
; #define PG8_LDB(dst, b, h) do { _Pragma("unroll") for (int n = 0; n < 2; ++n) _Pragma("unroll") for (int k = 0; k < 2; ++k) dst[n][k] = *(const LAS bf16x8*)(lds + PG8_SB(b, h) + boff + n * 2048 + k * 1024); } while (0)
; #define PG8_WAIT_V(n) asm volatile("s_waitcnt vmcnt(" #n ")" ::: "memory")
; #define PG8_WAIT_L(n) asm volatile("s_waitcnt lgkmcnt(" #n ")" ::: "memory")
; #define PG8_BAR __builtin_amdgcn_s_barrier()
; #define PG8_SCHED __builtin_amdgcn_sched_barrier(0)
; template <class Epi>
; __device__ __forceinline__ void gemm_phase(LAS unsigned char* lds, const Gemm g, const Sched& S, const Epi& E) {
;     ...
;             PG8_LDB(B0, 0, 0); PG8_SCHED; PG8_LDA(At, 0, 0); PG8_STAGE(PG8_SA(1, 1), a1 + hstepA, voffA);
;             PG8_WAIT_L(8); PG8_BAR; PG8_WAIT_L(0); PG8_MMA(0, 0, At, B0); PG8_BAR; PG8_SCHED;
;             PG8_LDB(B1, 0, 1); PG8_STAGE(PG8_SB(0, 0), b2, voffB);
;             PG8_BAR; PG8_WAIT_L(0); PG8_MMA(0, 1, At, B1); PG8_BAR;
;             PG8_LDA(At, 0, 1); PG8_STAGE(PG8_SA(0, 0), a2, voffA);
;             PG8_BAR; PG8_WAIT_L(0); PG8_MMA(1, 0, At, B0); PG8_BAR; PG8_SCHED;
;             PG8_STAGE(PG8_SB(0, 1), b2 + hstepB, voffB);
;             PG8_WAIT_V(6); PG8_BAR; PG8_MMA(1, 1, At, B1); PG8_BAR;
;             PG8_LDB(B0, 1, 0); PG8_SCHED; PG8_LDA(At, 1, 0); PG8_STAGE(PG8_SA(0, 1), a2 + hstepA, voffA);
;             PG8_WAIT_L(8); PG8_BAR; PG8_WAIT_L(0); PG8_MMA(0, 0, At, B0); PG8_BAR; PG8_SCHED;
;             PG8_LDB(B1, 1, 1); PG8_STAGE(PG8_SB(1, 0), b3, voffB);
;             PG8_BAR; PG8_WAIT_L(0); PG8_MMA(0, 1, At, B1); PG8_BAR;
;             PG8_LDA(At, 1, 1); PG8_STAGE(PG8_SA(1, 0), a3, voffA);
;             PG8_BAR; PG8_WAIT_L(0); PG8_MMA(1, 0, At, B0); PG8_BAR; PG8_SCHED;
;             PG8_STAGE(PG8_SB(1, 1), b3 + hstepB, voffB);
;             PG8_WAIT_V(6); PG8_BAR; PG8_MMA(1, 1, At, B1); PG8_BAR;
.LBB0_3163:
	v_add_u32_e32 v144, s41, v204
	s_add_u32 s20, s12, s18
	ds_read_b128 v[132:135], v144
	ds_read_b128 v[136:139], v144 offset:1024
	ds_read_b128 v[140:143], v144 offset:2048
	ds_read_b128 v[144:147], v144 offset:3072
	s_addc_u32 s21, s13, s19
	s_add_u32 s20, s20, 0x100
	s_addc_u32 s21, s21, 0
	s_add_u32 s58, s11, s18
	s_addc_u32 s59, s56, s19
	s_cmpk_eq_i32 s18, 0x2b00
	s_cselect_b32 s23, s17, s21
	s_cselect_b32 s22, s16, s20
	s_cselect_b32 s21, s9, s59
	s_cselect_b32 s20, s8, s58
	v_lshl_add_u64 v[196:197], v[128:129], 0, s[18:19]
	s_add_i32 m0, s33, 0xc000
	ds_read_b128 v[148:151], v205
	ds_read_b128 v[152:155], v205 offset:1024
	ds_read_b128 v[156:159], v205 offset:2048
	ds_read_b128 v[160:163], v205 offset:3072
	ds_read_b128 v[164:167], v205 offset:4096
	ds_read_b128 v[168:171], v205 offset:5120
	ds_read_b128 v[172:175], v205 offset:6144
	ds_read_b128 v[176:179], v205 offset:7168
	global_load_lds_dwordx4 v[196:197], off
	v_lshl_add_u64 v[196:197], v[130:131], 0, s[18:19]
	s_add_i32 m0, s33, 0xe000
	s_nop 0
	global_load_lds_dwordx4 v[196:197], off
	s_waitcnt lgkmcnt(8)
	s_barrier
	s_waitcnt lgkmcnt(0)
	s_setprio 1
	s_waitcnt lgkmcnt(0)
	v_mfma_f32_16x16x32_bf16 v[124:127], v[132:135], v[148:151], v[124:127]
	v_mfma_f32_16x16x32_bf16 v[120:123], v[140:143], v[148:151], v[120:123]
	v_mfma_f32_16x16x32_bf16 v[116:119], v[132:135], v[156:159], v[116:119]
	v_mfma_f32_16x16x32_bf16 v[112:115], v[140:143], v[156:159], v[112:115]
	v_mfma_f32_16x16x32_bf16 v[108:111], v[132:135], v[164:167], v[108:111]
	v_mfma_f32_16x16x32_bf16 v[104:107], v[140:143], v[164:167], v[104:107]
	v_mfma_f32_16x16x32_bf16 v[100:103], v[132:135], v[172:175], v[100:103]
	v_mfma_f32_16x16x32_bf16 v[96:99], v[140:143], v[172:175], v[96:99]
	v_mfma_f32_16x16x32_bf16 v[124:127], v[136:139], v[152:155], v[124:127]
	v_mfma_f32_16x16x32_bf16 v[120:123], v[144:147], v[152:155], v[120:123]
	v_mfma_f32_16x16x32_bf16 v[116:119], v[136:139], v[160:163], v[116:119]
	v_mfma_f32_16x16x32_bf16 v[112:115], v[144:147], v[160:163], v[112:115]
	v_mfma_f32_16x16x32_bf16 v[108:111], v[136:139], v[168:171], v[108:111]
	v_mfma_f32_16x16x32_bf16 v[104:107], v[144:147], v[168:171], v[104:107]
	v_mfma_f32_16x16x32_bf16 v[100:103], v[136:139], v[176:179], v[100:103]
	s_barrier
	v_mfma_f32_16x16x32_bf16 v[96:99], v[144:147], v[176:179], v[96:99]
	s_setprio 0
	s_add_i32 s58, s41, s25
	v_add_u32_e32 v210, s43, v204
	v_lshl_add_u64 v[214:215], s[20:21], 0, v[180:181]
	s_mov_b32 m0, s58
	ds_read_b128 v[196:199], v210
	ds_read_b128 v[200:203], v210 offset:1024
	ds_read_b128 v[206:209], v210 offset:2048
	ds_read_b128 v[210:213], v210 offset:3072
	global_load_lds_dwordx4 v[214:215], off
	v_lshl_add_u64 v[216:217], s[20:21], 0, v[182:183]
	s_add_i32 m0, s58, 0x2000
	s_nop 0
	global_load_lds_dwordx4 v[216:217], off
	s_barrier
	s_waitcnt lgkmcnt(0)
	s_setprio 1
	s_waitcnt lgkmcnt(0)
	v_mfma_f32_16x16x32_bf16 v[92:95], v[196:199], v[148:151], v[92:95]
	v_mfma_f32_16x16x32_bf16 v[88:91], v[206:209], v[148:151], v[88:91]
	v_mfma_f32_16x16x32_bf16 v[84:87], v[196:199], v[156:159], v[84:87]
	v_mfma_f32_16x16x32_bf16 v[80:83], v[206:209], v[156:159], v[80:83]
	v_mfma_f32_16x16x32_bf16 v[76:79], v[196:199], v[164:167], v[76:79]
	v_mfma_f32_16x16x32_bf16 v[72:75], v[206:209], v[164:167], v[72:75]
	v_mfma_f32_16x16x32_bf16 v[68:71], v[196:199], v[172:175], v[68:71]
	v_mfma_f32_16x16x32_bf16 v[64:67], v[206:209], v[172:175], v[64:67]
	v_mfma_f32_16x16x32_bf16 v[92:95], v[200:203], v[152:155], v[92:95]
	v_mfma_f32_16x16x32_bf16 v[88:91], v[210:213], v[152:155], v[88:91]
	v_mfma_f32_16x16x32_bf16 v[84:87], v[200:203], v[160:163], v[84:87]
	v_mfma_f32_16x16x32_bf16 v[80:83], v[210:213], v[160:163], v[80:83]
	v_mfma_f32_16x16x32_bf16 v[76:79], v[200:203], v[168:171], v[76:79]
	v_mfma_f32_16x16x32_bf16 v[72:75], v[210:213], v[168:171], v[72:75]
	v_mfma_f32_16x16x32_bf16 v[68:71], v[200:203], v[176:179], v[68:71]
	s_barrier
	v_mfma_f32_16x16x32_bf16 v[64:67], v[210:213], v[176:179], v[64:67]
	s_setprio 0
	s_mov_b32 m0, s33
	v_lshl_add_u64 v[218:219], s[22:23], 0, v[180:181]
	ds_read_b128 v[148:151], v205 offset:16384
	ds_read_b128 v[152:155], v205 offset:17408
	ds_read_b128 v[156:159], v205 offset:18432
	ds_read_b128 v[160:163], v205 offset:19456
	ds_read_b128 v[164:167], v205 offset:20480
	ds_read_b128 v[168:171], v205 offset:21504
	ds_read_b128 v[172:175], v205 offset:22528
	ds_read_b128 v[176:179], v205 offset:23552
	global_load_lds_dwordx4 v[218:219], off
	v_lshl_add_u64 v[220:221], s[22:23], 0, v[182:183]
	s_mov_b32 m0, s34
	s_nop 0
	global_load_lds_dwordx4 v[220:221], off
	s_barrier
	s_waitcnt lgkmcnt(0)
	s_setprio 1
	s_waitcnt lgkmcnt(0)
	v_mfma_f32_16x16x32_bf16 v[60:63], v[132:135], v[148:151], v[60:63]
	v_mfma_f32_16x16x32_bf16 v[56:59], v[140:143], v[148:151], v[56:59]
	v_mfma_f32_16x16x32_bf16 v[52:55], v[132:135], v[156:159], v[52:55]
	v_mfma_f32_16x16x32_bf16 v[48:51], v[140:143], v[156:159], v[48:51]
	v_mfma_f32_16x16x32_bf16 v[44:47], v[132:135], v[164:167], v[44:47]
	v_mfma_f32_16x16x32_bf16 v[40:43], v[140:143], v[164:167], v[40:43]
	v_mfma_f32_16x16x32_bf16 v[36:39], v[132:135], v[172:175], v[36:39]
	v_mfma_f32_16x16x32_bf16 v[32:35], v[140:143], v[172:175], v[32:35]
	v_mfma_f32_16x16x32_bf16 v[60:63], v[136:139], v[152:155], v[60:63]
	v_mfma_f32_16x16x32_bf16 v[56:59], v[144:147], v[152:155], v[56:59]
	v_mfma_f32_16x16x32_bf16 v[52:55], v[136:139], v[160:163], v[52:55]
	v_mfma_f32_16x16x32_bf16 v[48:51], v[144:147], v[160:163], v[48:51]
	v_mfma_f32_16x16x32_bf16 v[44:47], v[136:139], v[168:171], v[44:47]
	v_mfma_f32_16x16x32_bf16 v[40:43], v[144:147], v[168:171], v[40:43]
	v_mfma_f32_16x16x32_bf16 v[36:39], v[136:139], v[176:179], v[36:39]
	s_barrier
; #define PG8_STAGE(bufoff, gbase, voff) do { _Pragma("unroll") for (int _i = 0; _i < 2; ++_i) \
;         __builtin_amdgcn_global_load_lds((const unsigned*)((const char*)(gbase) + (voff)[_i]), (LAS unsigned*)(lds + (bufoff) + ldsw + _i * 8192), 16, 0, 0); } while (0)
; #define PG8_LDA(dst, b, h) do { _Pragma("unroll") for (int m = 0; m < 4; ++m) _Pragma("unroll") for (int k = 0; k < 2; ++k) dst[m][k] = *(const LAS bf16x8*)(lds + PG8_SA(b, h) + aoff + m * 2048 + k * 1024); } while (0)
; #define PG8_LDB(dst, b, h) do { _Pragma("unroll") for (int n = 0; n < 2; ++n) _Pragma("unroll") for (int k = 0; k < 2; ++k) dst[n][k] = *(const LAS bf16x8*)(lds + PG8_SB(b, h) + boff + n * 2048 + k * 1024); } while (0)
; #define PG8_WAIT_V(n) asm volatile("s_waitcnt vmcnt(" #n ")" ::: "memory")
; #define PG8_WAIT_L(n) asm volatile("s_waitcnt lgkmcnt(" #n ")" ::: "memory")
; #define PG8_BAR __builtin_amdgcn_s_barrier()
; #define PG8_SCHED __builtin_amdgcn_sched_barrier(0)
; template <class Epi>
; __device__ __forceinline__ void gemm_phase(LAS unsigned char* lds, const Gemm g, const Sched& S, const Epi& E) {
;     ...
;             PG8_LDB(B0, 0, 0); PG8_SCHED; PG8_LDA(At, 0, 0); PG8_STAGE(PG8_SA(1, 1), a1 + hstepA, voffA);
;             PG8_WAIT_L(8); PG8_BAR; PG8_WAIT_L(0); PG8_MMA(0, 0, At, B0); PG8_BAR; PG8_SCHED;
;             PG8_LDB(B1, 0, 1); PG8_STAGE(PG8_SB(0, 0), b2, voffB);
;             PG8_BAR; PG8_WAIT_L(0); PG8_MMA(0, 1, At, B1); PG8_BAR;
;             PG8_LDA(At, 0, 1); PG8_STAGE(PG8_SA(0, 0), a2, voffA);
;             PG8_BAR; PG8_WAIT_L(0); PG8_MMA(1, 0, At, B0); PG8_BAR; PG8_SCHED;
;             PG8_STAGE(PG8_SB(0, 1), b2 + hstepB, voffB);
;             PG8_WAIT_V(6); PG8_BAR; PG8_MMA(1, 1, At, B1); PG8_BAR;
;             PG8_LDB(B0, 1, 0); PG8_SCHED; PG8_LDA(At, 1, 0); PG8_STAGE(PG8_SA(0, 1), a2 + hstepA, voffA);
;             PG8_WAIT_L(8); PG8_BAR; PG8_WAIT_L(0); PG8_MMA(0, 0, At, B0); PG8_BAR; PG8_SCHED;
;             PG8_LDB(B1, 1, 1); PG8_STAGE(PG8_SB(1, 0), b3, voffB);
;             PG8_BAR; PG8_WAIT_L(0); PG8_MMA(0, 1, At, B1); PG8_BAR;
;             PG8_LDA(At, 1, 1); PG8_STAGE(PG8_SA(1, 0), a3, voffA);
;             PG8_BAR; PG8_WAIT_L(0); PG8_MMA(1, 0, At, B0); PG8_BAR; PG8_SCHED;
;             PG8_STAGE(PG8_SB(1, 1), b3 + hstepB, voffB);
;             PG8_WAIT_V(6); PG8_BAR; PG8_MMA(1, 1, At, B1); PG8_BAR;
	v_mfma_f32_16x16x32_bf16 v[32:35], v[144:147], v[176:179], v[32:35]
	s_setprio 0
	s_add_u32 s58, s20, 0x160000
	s_addc_u32 s59, s21, 0
	s_add_i32 s60, s43, s25
	v_lshl_add_u64 v[132:133], s[58:59], 0, v[180:181]
	s_mov_b32 m0, s60
	s_nop 0
	global_load_lds_dwordx4 v[132:133], off
	v_lshl_add_u64 v[132:133], s[58:59], 0, v[182:183]
	s_add_i32 m0, s60, 0x2000
	s_nop 0
	global_load_lds_dwordx4 v[132:133], off
	s_waitcnt vmcnt(6)
	s_barrier
	s_setprio 1
	v_mfma_f32_16x16x32_bf16 v[28:31], v[196:199], v[148:151], v[28:31]
	v_mfma_f32_16x16x32_bf16 v[24:27], v[206:209], v[148:151], v[24:27]
	v_mfma_f32_16x16x32_bf16 v[20:23], v[196:199], v[156:159], v[20:23]
	v_mfma_f32_16x16x32_bf16 v[16:19], v[206:209], v[156:159], v[16:19]
	v_mfma_f32_16x16x32_bf16 v[12:15], v[196:199], v[164:167], v[12:15]
	v_mfma_f32_16x16x32_bf16 v[8:11], v[206:209], v[164:167], v[8:11]
	v_mfma_f32_16x16x32_bf16 v[4:7], v[196:199], v[172:175], v[4:7]
	v_mfma_f32_16x16x32_bf16 v[0:3], v[206:209], v[172:175], v[0:3]
	v_mfma_f32_16x16x32_bf16 v[28:31], v[200:203], v[152:155], v[28:31]
	v_mfma_f32_16x16x32_bf16 v[24:27], v[210:213], v[152:155], v[24:27]
	v_mfma_f32_16x16x32_bf16 v[20:23], v[200:203], v[160:163], v[20:23]
	v_mfma_f32_16x16x32_bf16 v[16:19], v[210:213], v[160:163], v[16:19]
	v_mfma_f32_16x16x32_bf16 v[12:15], v[200:203], v[168:171], v[12:15]
	v_mfma_f32_16x16x32_bf16 v[8:11], v[210:213], v[168:171], v[8:11]
	v_mfma_f32_16x16x32_bf16 v[4:7], v[200:203], v[176:179], v[4:7]
	s_barrier
	v_mfma_f32_16x16x32_bf16 v[0:3], v[210:213], v[176:179], v[0:3]
	s_setprio 0
	s_add_i32 s58, 0, 0x18000
	v_add_u32_e32 v144, s58, v204
	ds_read_b128 v[132:135], v144
	ds_read_b128 v[136:139], v144 offset:1024
	ds_read_b128 v[140:143], v144 offset:2048
	ds_read_b128 v[144:147], v144 offset:3072
	s_add_u32 s22, s22, 0x160000
	s_addc_u32 s23, s23, 0
	s_mov_b32 m0, s35
	v_lshl_add_u64 v[196:197], s[22:23], 0, v[180:181]
	ds_read_b128 v[148:151], v205 offset:32768
	ds_read_b128 v[152:155], v205 offset:33792
	ds_read_b128 v[156:159], v205 offset:34816
	ds_read_b128 v[160:163], v205 offset:35840
	ds_read_b128 v[164:167], v205 offset:36864
	ds_read_b128 v[168:171], v205 offset:37888
	ds_read_b128 v[172:175], v205 offset:38912
	ds_read_b128 v[176:179], v205 offset:39936
	global_load_lds_dwordx4 v[196:197], off
	v_lshl_add_u64 v[196:197], s[22:23], 0, v[182:183]
	s_mov_b32 m0, s36
	s_nop 0
	global_load_lds_dwordx4 v[196:197], off
	s_waitcnt lgkmcnt(8)
	s_barrier
	s_waitcnt lgkmcnt(0)
	s_setprio 1
	s_waitcnt lgkmcnt(0)
	v_mfma_f32_16x16x32_bf16 v[124:127], v[132:135], v[148:151], v[124:127]
	v_mfma_f32_16x16x32_bf16 v[120:123], v[140:143], v[148:151], v[120:123]
	v_mfma_f32_16x16x32_bf16 v[116:119], v[132:135], v[156:159], v[116:119]
	v_mfma_f32_16x16x32_bf16 v[112:115], v[140:143], v[156:159], v[112:115]
	v_mfma_f32_16x16x32_bf16 v[108:111], v[132:135], v[164:167], v[108:111]
	v_mfma_f32_16x16x32_bf16 v[104:107], v[140:143], v[164:167], v[104:107]
	v_mfma_f32_16x16x32_bf16 v[100:103], v[132:135], v[172:175], v[100:103]
	v_mfma_f32_16x16x32_bf16 v[96:99], v[140:143], v[172:175], v[96:99]
	v_mfma_f32_16x16x32_bf16 v[124:127], v[136:139], v[152:155], v[124:127]
	v_mfma_f32_16x16x32_bf16 v[120:123], v[144:147], v[152:155], v[120:123]
	v_mfma_f32_16x16x32_bf16 v[116:119], v[136:139], v[160:163], v[116:119]
	v_mfma_f32_16x16x32_bf16 v[112:115], v[144:147], v[160:163], v[112:115]
	v_mfma_f32_16x16x32_bf16 v[108:111], v[136:139], v[168:171], v[108:111]
	v_mfma_f32_16x16x32_bf16 v[104:107], v[144:147], v[168:171], v[104:107]
	v_mfma_f32_16x16x32_bf16 v[100:103], v[136:139], v[176:179], v[100:103]
	s_barrier
	v_mfma_f32_16x16x32_bf16 v[96:99], v[144:147], v[176:179], v[96:99]
	s_setprio 0
	s_add_i32 s22, 0, 0x1c000
	s_add_i32 s23, s58, s25
	v_add_u32_e32 v210, s22, v204
	v_lshl_add_u64 v[214:215], v[214:215], 0, s[14:15]
	s_mov_b32 m0, s23
	ds_read_b128 v[196:199], v210
	ds_read_b128 v[200:203], v210 offset:1024
	ds_read_b128 v[206:209], v210 offset:2048
	ds_read_b128 v[210:213], v210 offset:3072
	global_load_lds_dwordx4 v[214:215], off
	v_lshl_add_u64 v[214:215], v[216:217], 0, s[14:15]
	s_add_i32 m0, s23, 0x2000
	s_nop 0
	global_load_lds_dwordx4 v[214:215], off
	s_barrier
	s_waitcnt lgkmcnt(0)
	s_setprio 1
	s_waitcnt lgkmcnt(0)
	v_mfma_f32_16x16x32_bf16 v[92:95], v[196:199], v[148:151], v[92:95]
	v_mfma_f32_16x16x32_bf16 v[88:91], v[206:209], v[148:151], v[88:91]
	v_mfma_f32_16x16x32_bf16 v[84:87], v[196:199], v[156:159], v[84:87]
	v_mfma_f32_16x16x32_bf16 v[80:83], v[206:209], v[156:159], v[80:83]
	v_mfma_f32_16x16x32_bf16 v[76:79], v[196:199], v[164:167], v[76:79]
	v_mfma_f32_16x16x32_bf16 v[72:75], v[206:209], v[164:167], v[72:75]
	v_mfma_f32_16x16x32_bf16 v[68:71], v[196:199], v[172:175], v[68:71]
	v_mfma_f32_16x16x32_bf16 v[64:67], v[206:209], v[172:175], v[64:67]
	v_mfma_f32_16x16x32_bf16 v[92:95], v[200:203], v[152:155], v[92:95]
	v_mfma_f32_16x16x32_bf16 v[88:91], v[210:213], v[152:155], v[88:91]
	v_mfma_f32_16x16x32_bf16 v[84:87], v[200:203], v[160:163], v[84:87]
	v_mfma_f32_16x16x32_bf16 v[80:83], v[210:213], v[160:163], v[80:83]
	v_mfma_f32_16x16x32_bf16 v[76:79], v[200:203], v[168:171], v[76:79]
	v_mfma_f32_16x16x32_bf16 v[72:75], v[210:213], v[168:171], v[72:75]
	v_mfma_f32_16x16x32_bf16 v[68:71], v[200:203], v[176:179], v[68:71]
	s_barrier
	v_mfma_f32_16x16x32_bf16 v[64:67], v[210:213], v[176:179], v[64:67]
	s_setprio 0
	s_mov_b32 m0, s39
	v_lshl_add_u64 v[214:215], v[218:219], 0, s[14:15]
	ds_read_b128 v[148:151], v205 offset:49152
	ds_read_b128 v[152:155], v205 offset:50176
	ds_read_b128 v[156:159], v205 offset:51200
	ds_read_b128 v[160:163], v205 offset:52224
	ds_read_b128 v[164:167], v205 offset:53248
	ds_read_b128 v[168:171], v205 offset:54272
	ds_read_b128 v[172:175], v205 offset:55296
	ds_read_b128 v[176:179], v205 offset:56320
	global_load_lds_dwordx4 v[214:215], off
	v_lshl_add_u64 v[214:215], v[220:221], 0, s[14:15]
	s_mov_b32 m0, s40
	s_nop 0
	global_load_lds_dwordx4 v[214:215], off
	s_barrier
; #define PG8_STAGE(bufoff, gbase, voff) do { _Pragma("unroll") for (int _i = 0; _i < 2; ++_i) \
;         __builtin_amdgcn_global_load_lds((const unsigned*)((const char*)(gbase) + (voff)[_i]), (LAS unsigned*)(lds + (bufoff) + ldsw + _i * 8192), 16, 0, 0); } while (0)
; #define PG8_LDA(dst, b, h) do { _Pragma("unroll") for (int m = 0; m < 4; ++m) _Pragma("unroll") for (int k = 0; k < 2; ++k) dst[m][k] = *(const LAS bf16x8*)(lds + PG8_SA(b, h) + aoff + m * 2048 + k * 1024); } while (0)
; #define PG8_LDB(dst, b, h) do { _Pragma("unroll") for (int n = 0; n < 2; ++n) _Pragma("unroll") for (int k = 0; k < 2; ++k) dst[n][k] = *(const LAS bf16x8*)(lds + PG8_SB(b, h) + boff + n * 2048 + k * 1024); } while (0)
; #define PG8_MMA(ai, bj, At, Bt) do { __builtin_amdgcn_s_setprio(1); _Pragma("unroll") for (int m = 0; m < 4; ++m) _Pragma("unroll") for (int n = 0; n < 2; ++n) _Pragma("unroll") for (int k = 0; k < 2; ++k) \
;         acc[ai][bj][m][n] = __builtin_amdgcn_mfma_f32_16x16x32_bf16(Bt[n][k], At[m][k], acc[ai][bj][m][n], 0, 0, 0); __builtin_amdgcn_s_setprio(0); } while (0)
; template <class Epi>
; __device__ __forceinline__ void gemm_phase(LAS unsigned char* lds, const Gemm g, const Sched& S, const Epi& E) {
;     ...
;             PG8_WAIT_V(6); PG8_BAR; PG8_MMA(1, 1, At, B1); PG8_BAR;
;             PG8_LDB(B0, 1, 0); PG8_SCHED; PG8_LDA(At, 1, 0); PG8_STAGE(PG8_SA(0, 1), a2 + hstepA, voffA);
;             PG8_WAIT_L(8); PG8_BAR; PG8_WAIT_L(0); PG8_MMA(0, 0, At, B0); PG8_BAR; PG8_SCHED;
;             PG8_LDB(B1, 1, 1); PG8_STAGE(PG8_SB(1, 0), b3, voffB);
;             PG8_BAR; PG8_WAIT_L(0); PG8_MMA(0, 1, At, B1); PG8_BAR;
;             PG8_LDA(At, 1, 1); PG8_STAGE(PG8_SA(1, 0), a3, voffA);
;             PG8_BAR; PG8_WAIT_L(0); PG8_MMA(1, 0, At, B0); PG8_BAR; PG8_SCHED;
;             PG8_STAGE(PG8_SB(1, 1), b3 + hstepB, voffB);
;             PG8_WAIT_V(6); PG8_BAR; PG8_MMA(1, 1, At, B1); PG8_BAR;
;     __device__ __forceinline__ void operator()(AccRef acc, const Unit& u, int wr, int wc, int fr, int fq) const {
;         const float al = alpha;
;         const size_t base = ((size_t)u.pm * 256 + wr * 64 + fr) * D_ + u.pn * 256 + wc * 32 + 4 * fq;
;         f32x4 xa[2][2][2], xb[2][2][2];
;     ...
;         RES_LOAD(xa, 0); RES_LOAD(xb, 1);
;         RES_STORE(xa, 0); RES_LOAD(xa, 2);
;         RES_STORE(xb, 1); RES_LOAD(xb, 3);
;         RES_STORE(xa, 2); RES_STORE(xb, 3);
	s_waitcnt lgkmcnt(0)
	s_setprio 1
	s_waitcnt lgkmcnt(0)
	v_mfma_f32_16x16x32_bf16 v[60:63], v[132:135], v[148:151], v[60:63]
	v_mfma_f32_16x16x32_bf16 v[56:59], v[140:143], v[148:151], v[56:59]
	v_mfma_f32_16x16x32_bf16 v[52:55], v[132:135], v[156:159], v[52:55]
	v_mfma_f32_16x16x32_bf16 v[48:51], v[140:143], v[156:159], v[48:51]
	v_mfma_f32_16x16x32_bf16 v[44:47], v[132:135], v[164:167], v[44:47]
	v_mfma_f32_16x16x32_bf16 v[40:43], v[140:143], v[164:167], v[40:43]
	v_mfma_f32_16x16x32_bf16 v[36:39], v[132:135], v[172:175], v[36:39]
	v_mfma_f32_16x16x32_bf16 v[32:35], v[140:143], v[172:175], v[32:35]
	v_mfma_f32_16x16x32_bf16 v[60:63], v[136:139], v[152:155], v[60:63]
	v_mfma_f32_16x16x32_bf16 v[56:59], v[144:147], v[152:155], v[56:59]
	v_mfma_f32_16x16x32_bf16 v[52:55], v[136:139], v[160:163], v[52:55]
	v_mfma_f32_16x16x32_bf16 v[48:51], v[144:147], v[160:163], v[48:51]
	v_mfma_f32_16x16x32_bf16 v[44:47], v[136:139], v[168:171], v[44:47]
	v_mfma_f32_16x16x32_bf16 v[40:43], v[144:147], v[168:171], v[40:43]
	v_mfma_f32_16x16x32_bf16 v[36:39], v[136:139], v[176:179], v[36:39]
	s_barrier
	v_mfma_f32_16x16x32_bf16 v[32:35], v[144:147], v[176:179], v[32:35]
	s_setprio 0
	s_add_u32 s20, s20, 0x160080
	s_addc_u32 s21, s21, 0
	s_add_i32 s22, s22, s25
	v_lshl_add_u64 v[132:133], s[20:21], 0, v[180:181]
	s_mov_b32 m0, s22
	s_nop 0
	global_load_lds_dwordx4 v[132:133], off
	v_lshl_add_u64 v[132:133], s[20:21], 0, v[182:183]
	s_add_i32 m0, s22, 0x2000
	s_nop 0
	global_load_lds_dwordx4 v[132:133], off
	s_waitcnt vmcnt(6)
	s_barrier
	s_setprio 1
	v_mfma_f32_16x16x32_bf16 v[28:31], v[196:199], v[148:151], v[28:31]
	v_mfma_f32_16x16x32_bf16 v[24:27], v[206:209], v[148:151], v[24:27]
	v_mfma_f32_16x16x32_bf16 v[20:23], v[196:199], v[156:159], v[20:23]
	v_mfma_f32_16x16x32_bf16 v[16:19], v[206:209], v[156:159], v[16:19]
	v_mfma_f32_16x16x32_bf16 v[12:15], v[196:199], v[164:167], v[12:15]
	v_mfma_f32_16x16x32_bf16 v[8:11], v[206:209], v[164:167], v[8:11]
	v_mfma_f32_16x16x32_bf16 v[4:7], v[196:199], v[172:175], v[4:7]
	v_mfma_f32_16x16x32_bf16 v[0:3], v[206:209], v[172:175], v[0:3]
	v_mfma_f32_16x16x32_bf16 v[28:31], v[200:203], v[152:155], v[28:31]
	v_mfma_f32_16x16x32_bf16 v[24:27], v[210:213], v[152:155], v[24:27]
	v_mfma_f32_16x16x32_bf16 v[20:23], v[200:203], v[160:163], v[20:23]
	v_mfma_f32_16x16x32_bf16 v[16:19], v[210:213], v[160:163], v[16:19]
	v_mfma_f32_16x16x32_bf16 v[12:15], v[200:203], v[168:171], v[12:15]
	v_mfma_f32_16x16x32_bf16 v[8:11], v[210:213], v[168:171], v[8:11]
	v_mfma_f32_16x16x32_bf16 v[4:7], v[200:203], v[176:179], v[4:7]
	s_barrier
	v_mfma_f32_16x16x32_bf16 v[0:3], v[210:213], v[176:179], v[0:3]
	s_setprio 0
	s_add_i32 s57, s57, 2
	s_add_u32 s18, s18, 0x100
	s_addc_u32 s19, s19, 0
	s_cmpk_gt_u32 s57, 0x55
	s_cbranch_scc0 .LBB0_3163
	s_add_u32 s18, s11, 0xffffff00
	s_addc_u32 s19, s56, -1
	s_lshl_b32 s20, s38, 8
	s_ashr_i32 s11, s10, 31
	s_ashr_i32 s21, s20, 31
	v_lshl_add_u64 v[128:129], s[20:21], 2, v[184:185]
	s_lshl_b64 s[20:21], s[10:11], 21
	v_lshl_add_u64 v[176:177], v[128:129], 0, s[20:21]
	global_load_dwordx4 v[128:131], v[176:177], off
	global_load_dwordx4 v[132:135], v[176:177], off offset:64
	global_load_dwordx4 v[136:139], v[176:177], off offset:512
	global_load_dwordx4 v[140:143], v[176:177], off offset:576
	v_add_co_u32_e32 v178, vcc, s46, v176
	s_waitcnt vmcnt(0)
	v_pk_fma_f32 v[130:131], v[126:127], 0.5, v[130:131] op_sel_hi:[1,0,1]
	v_addc_co_u32_e32 v179, vcc, 0, v177, vcc
	global_load_dwordx4 v[144:147], v[178:179], off
	global_load_dwordx4 v[148:151], v[178:179], off offset:64
	global_load_dwordx4 v[152:155], v[178:179], off offset:512
	global_load_dwordx4 v[156:159], v[178:179], off offset:576
	v_add_co_u32_e32 v218, vcc, s47, v176
	v_pk_fma_f32 v[128:129], v[124:125], 0.5, v[128:129] op_sel_hi:[1,0,1]
	s_nop 0
	v_addc_co_u32_e32 v219, vcc, 0, v177, vcc
	global_load_dwordx4 v[160:163], v[218:219], off
	global_load_dwordx4 v[164:167], v[218:219], off offset:64
	global_load_dwordx4 v[168:171], v[218:219], off offset:512
	global_load_dwordx4 v[172:175], v[218:219], off offset:576
	v_add_co_u32_e32 v220, vcc, s48, v176
	s_waitcnt vmcnt(0)
	v_pk_fma_f32 v[162:163], v[110:111], 0.5, v[162:163] op_sel_hi:[1,0,1]
	v_addc_co_u32_e32 v221, vcc, 0, v177, vcc
	global_load_dwordx4 v[200:203], v[220:221], off
	global_load_dwordx4 v[206:209], v[220:221], off offset:64
	global_load_dwordx4 v[210:213], v[220:221], off offset:512
	global_load_dwordx4 v[214:217], v[220:221], off offset:576
	v_add_co_u32_e32 v198, vcc, s49, v176
	global_store_dwordx4 v[176:177], v[128:131], off
	s_nop 0
	v_addc_co_u32_e32 v199, vcc, 0, v177, vcc
	v_pk_fma_f32 v[130:131], v[122:123], 0.5, v[134:135] op_sel_hi:[1,0,1]
	v_pk_fma_f32 v[128:129], v[120:121], 0.5, v[132:133] op_sel_hi:[1,0,1]
	global_store_dwordx4 v[176:177], v[128:131], off offset:64
	v_add_co_u32_e32 v196, vcc, s50, v176
	s_nop 0
	v_pk_fma_f32 v[130:131], v[94:95], 0.5, v[138:139] op_sel_hi:[1,0,1]
	v_pk_fma_f32 v[128:129], v[92:93], 0.5, v[136:137] op_sel_hi:[1,0,1]
	global_store_dwordx4 v[176:177], v[128:131], off offset:512
	v_addc_co_u32_e32 v197, vcc, 0, v177, vcc
	s_nop 0
	v_pk_fma_f32 v[130:131], v[90:91], 0.5, v[142:143] op_sel_hi:[1,0,1]
	v_pk_fma_f32 v[128:129], v[88:89], 0.5, v[140:141] op_sel_hi:[1,0,1]
	global_store_dwordx4 v[176:177], v[128:131], off offset:576
	v_pk_fma_f32 v[160:161], v[108:109], 0.5, v[160:161] op_sel_hi:[1,0,1]
	s_nop 0
	v_pk_fma_f32 v[130:131], v[118:119], 0.5, v[146:147] op_sel_hi:[1,0,1]
	v_pk_fma_f32 v[128:129], v[116:117], 0.5, v[144:145] op_sel_hi:[1,0,1]
	global_store_dwordx4 v[178:179], v[128:131], off
	s_nop 1
	v_pk_fma_f32 v[130:131], v[114:115], 0.5, v[150:151] op_sel_hi:[1,0,1]
	v_pk_fma_f32 v[128:129], v[112:113], 0.5, v[148:149] op_sel_hi:[1,0,1]
	global_store_dwordx4 v[178:179], v[128:131], off offset:64
	s_nop 1
	v_pk_fma_f32 v[130:131], v[86:87], 0.5, v[154:155] op_sel_hi:[1,0,1]
	v_pk_fma_f32 v[128:129], v[84:85], 0.5, v[152:153] op_sel_hi:[1,0,1]
	global_store_dwordx4 v[178:179], v[128:131], off offset:512
	s_nop 1
	v_pk_fma_f32 v[130:131], v[82:83], 0.5, v[158:159] op_sel_hi:[1,0,1]
	v_pk_fma_f32 v[128:129], v[80:81], 0.5, v[156:157] op_sel_hi:[1,0,1]
	global_store_dwordx4 v[178:179], v[128:131], off offset:576
	global_load_dwordx4 v[156:159], v[198:199], off
	global_load_dwordx4 v[152:155], v[198:199], off offset:64
	global_load_dwordx4 v[144:147], v[198:199], off offset:512
	global_load_dwordx4 v[136:139], v[198:199], off offset:576
	global_load_dwordx4 v[148:151], v[196:197], off
	global_load_dwordx4 v[140:143], v[196:197], off offset:64
	global_load_dwordx4 v[132:135], v[196:197], off offset:512
	global_load_dwordx4 v[128:131], v[196:197], off offset:576
	s_waitcnt vmcnt(0)
; #define RES_LOAD(dst_, k_) do { _Pragma("unroll") for (int mm = 0; mm < 2; ++mm) _Pragma("unroll") for (int bj = 0; bj < 2; ++bj) _Pragma("unroll") for (int n = 0; n < 2; ++n) \
;             dst_[mm][bj][n] = *(const f32x4*)(xin + RES_OFF(k_, mm, bj, n)); } while (0)
; #define RES_STORE(src_, k_) do { _Pragma("unroll") for (int mm = 0; mm < 2; ++mm) _Pragma("unroll") for (int bj = 0; bj < 2; ++bj) _Pragma("unroll") for (int n = 0; n < 2; ++n) \
;             *(f32x4*)(xout + RES_OFF(k_, mm, bj, n)) = src_[mm][bj][n] + al * acc[(k_) >> 1][bj][((k_) & 1) * 2 + mm][n]; } while (0)
; template <class Epi>
; __device__ __forceinline__ void gemm_phase(LAS unsigned char* lds, const Gemm g, const Sched& S, const Epi& E) {
;     ...
;         if (!has_next) break;
; #pragma unroll
;         for (int a = 0; a < 2; ++a)
; #pragma unroll
;             for (int b = 0; b < 2; ++b)
; #pragma unroll
;                 for (int m = 0; m < 4; ++m)
; #pragma unroll
;                     for (int n = 0; n < 2; ++n) acc[a][b][m][n] = (f32x4){0.f, 0.f, 0.f, 0.f};
;         cur = nxt; cA = nA; cB = nB; ++ui;
;     __device__ __forceinline__ void operator()(AccRef acc, const Unit& u, int wr, int wc, int fr, int fq) const {
;         const float al = alpha;
;         const size_t base = ((size_t)u.pm * 256 + wr * 64 + fr) * D_ + u.pn * 256 + wc * 32 + 4 * fq;
;         f32x4 xa[2][2][2], xb[2][2][2];
;     ...
;         RES_LOAD(xa, 0); RES_LOAD(xb, 1);
;         RES_STORE(xa, 0); RES_LOAD(xa, 2);
;         RES_STORE(xb, 1); RES_LOAD(xb, 3);
;         RES_STORE(xa, 2); RES_STORE(xb, 3);
	v_pk_fma_f32 v[158:159], v[62:63], 0.5, v[158:159] op_sel_hi:[1,0,1]
	global_store_dwordx4 v[218:219], v[160:163], off
	v_pk_fma_f32 v[156:157], v[60:61], 0.5, v[156:157] op_sel_hi:[1,0,1]
	v_pk_fma_f32 v[138:139], v[26:27], 0.5, v[138:139] op_sel_hi:[1,0,1]
	v_pk_fma_f32 v[162:163], v[106:107], 0.5, v[166:167] op_sel_hi:[1,0,1]
	v_pk_fma_f32 v[160:161], v[104:105], 0.5, v[164:165] op_sel_hi:[1,0,1]
	global_store_dwordx4 v[218:219], v[160:163], off offset:64
	v_pk_fma_f32 v[130:131], v[18:19], 0.5, v[130:131] op_sel_hi:[1,0,1]
	v_pk_fma_f32 v[128:129], v[16:17], 0.5, v[128:129] op_sel_hi:[1,0,1]
	v_pk_fma_f32 v[162:163], v[78:79], 0.5, v[170:171] op_sel_hi:[1,0,1]
	v_pk_fma_f32 v[160:161], v[76:77], 0.5, v[168:169] op_sel_hi:[1,0,1]
	global_store_dwordx4 v[218:219], v[160:163], off offset:512
	v_pk_fma_f32 v[136:137], v[24:25], 0.5, v[136:137] op_sel_hi:[1,0,1]
	v_pk_fma_f32 v[154:155], v[58:59], 0.5, v[154:155] op_sel_hi:[1,0,1]
	v_pk_fma_f32 v[162:163], v[74:75], 0.5, v[174:175] op_sel_hi:[1,0,1]
	v_pk_fma_f32 v[160:161], v[72:73], 0.5, v[172:173] op_sel_hi:[1,0,1]
	global_store_dwordx4 v[218:219], v[160:163], off offset:576
	v_pk_fma_f32 v[152:153], v[56:57], 0.5, v[152:153] op_sel_hi:[1,0,1]
	v_pk_fma_f32 v[146:147], v[30:31], 0.5, v[146:147] op_sel_hi:[1,0,1]
	v_pk_fma_f32 v[162:163], v[102:103], 0.5, v[202:203] op_sel_hi:[1,0,1]
	v_pk_fma_f32 v[160:161], v[100:101], 0.5, v[200:201] op_sel_hi:[1,0,1]
	global_store_dwordx4 v[220:221], v[160:163], off
	v_add_co_u32_e32 v200, vcc, s51, v176
	s_nop 0
	v_pk_fma_f32 v[162:163], v[98:99], 0.5, v[208:209] op_sel_hi:[1,0,1]
	v_pk_fma_f32 v[160:161], v[96:97], 0.5, v[206:207] op_sel_hi:[1,0,1]
	global_store_dwordx4 v[220:221], v[160:163], off offset:64
	v_addc_co_u32_e32 v201, vcc, 0, v177, vcc
	s_nop 0
	v_pk_fma_f32 v[162:163], v[70:71], 0.5, v[212:213] op_sel_hi:[1,0,1]
	v_pk_fma_f32 v[160:161], v[68:69], 0.5, v[210:211] op_sel_hi:[1,0,1]
	global_store_dwordx4 v[220:221], v[160:163], off offset:512
	v_add_co_u32_e32 v202, vcc, s52, v176
	s_nop 0
	v_pk_fma_f32 v[162:163], v[66:67], 0.5, v[216:217] op_sel_hi:[1,0,1]
	v_pk_fma_f32 v[160:161], v[64:65], 0.5, v[214:215] op_sel_hi:[1,0,1]
	global_store_dwordx4 v[220:221], v[160:163], off offset:576
	global_load_dwordx4 v[172:175], v[200:201], off
	global_load_dwordx4 v[168:171], v[200:201], off offset:64
	global_load_dwordx4 v[164:167], v[200:201], off offset:512
	s_nop 0
	global_load_dwordx4 v[160:163], v[200:201], off offset:576
	v_addc_co_u32_e32 v203, vcc, 0, v177, vcc
	global_load_dwordx4 v[206:209], v[202:203], off
	global_load_dwordx4 v[210:213], v[202:203], off offset:64
	global_load_dwordx4 v[214:217], v[202:203], off offset:512
	global_load_dwordx4 v[176:179], v[202:203], off offset:576
	v_pk_fma_f32 v[144:145], v[28:29], 0.5, v[144:145] op_sel_hi:[1,0,1]
	global_store_dwordx4 v[196:197], v[128:131], off offset:576
	global_store_dwordx4 v[198:199], v[136:139], off offset:576
	v_pk_fma_f32 v[134:135], v[22:23], 0.5, v[134:135] op_sel_hi:[1,0,1]
	v_pk_fma_f32 v[132:133], v[20:21], 0.5, v[132:133] op_sel_hi:[1,0,1]
	v_pk_fma_f32 v[138:139], v[54:55], 0.5, v[150:151] op_sel_hi:[1,0,1]
	v_pk_fma_f32 v[136:137], v[52:53], 0.5, v[148:149] op_sel_hi:[1,0,1]
	global_store_dwordx4 v[196:197], v[136:139], off
	s_and_b64 vcc, exec, s[6:7]
	global_store_dwordx4 v[198:199], v[156:159], off
	v_pk_fma_f32 v[138:139], v[50:51], 0.5, v[142:143] op_sel_hi:[1,0,1]
	v_pk_fma_f32 v[136:137], v[48:49], 0.5, v[140:141] op_sel_hi:[1,0,1]
	global_store_dwordx4 v[198:199], v[152:155], off offset:64
	global_store_dwordx4 v[198:199], v[144:147], off offset:512
	global_store_dwordx4 v[196:197], v[136:139], off offset:64
	global_store_dwordx4 v[196:197], v[132:135], off offset:512
	s_waitcnt vmcnt(0)
	v_pk_fma_f32 v[130:131], v[46:47], 0.5, v[174:175] op_sel_hi:[1,0,1]
	v_pk_fma_f32 v[128:129], v[44:45], 0.5, v[172:173] op_sel_hi:[1,0,1]
	global_store_dwordx4 v[200:201], v[128:131], off
	s_nop 1
	v_pk_fma_f32 v[130:131], v[42:43], 0.5, v[170:171] op_sel_hi:[1,0,1]
	v_pk_fma_f32 v[128:129], v[40:41], 0.5, v[168:169] op_sel_hi:[1,0,1]
	global_store_dwordx4 v[200:201], v[128:131], off offset:64
	s_nop 1
	v_pk_fma_f32 v[130:131], v[14:15], 0.5, v[166:167] op_sel_hi:[1,0,1]
	v_pk_fma_f32 v[128:129], v[12:13], 0.5, v[164:165] op_sel_hi:[1,0,1]
	global_store_dwordx4 v[200:201], v[128:131], off offset:512
	s_nop 1
	v_pk_fma_f32 v[130:131], v[10:11], 0.5, v[162:163] op_sel_hi:[1,0,1]
	v_pk_fma_f32 v[128:129], v[8:9], 0.5, v[160:161] op_sel_hi:[1,0,1]
	global_store_dwordx4 v[200:201], v[128:131], off offset:576
	s_nop 1
	v_pk_fma_f32 v[130:131], v[38:39], 0.5, v[208:209] op_sel_hi:[1,0,1]
	v_pk_fma_f32 v[128:129], v[36:37], 0.5, v[206:207] op_sel_hi:[1,0,1]
	global_store_dwordx4 v[202:203], v[128:131], off
	s_nop 1
	v_pk_fma_f32 v[130:131], v[34:35], 0.5, v[212:213] op_sel_hi:[1,0,1]
	v_pk_fma_f32 v[128:129], v[32:33], 0.5, v[210:211] op_sel_hi:[1,0,1]
	global_store_dwordx4 v[202:203], v[128:131], off offset:64
	s_nop 1
	v_pk_fma_f32 v[130:131], v[6:7], 0.5, v[216:217] op_sel_hi:[1,0,1]
	v_pk_fma_f32 v[128:129], v[4:5], 0.5, v[214:215] op_sel_hi:[1,0,1]
	global_store_dwordx4 v[202:203], v[128:131], off offset:512
	s_nop 1
	v_pk_fma_f32 v[130:131], v[2:3], 0.5, v[178:179] op_sel_hi:[1,0,1]
	v_pk_fma_f32 v[128:129], v[0:1], 0.5, v[176:177] op_sel_hi:[1,0,1]
	global_store_dwordx4 v[202:203], v[128:131], off offset:576
	s_cbranch_vccz .LBB0_3151
	s_mov_b64 s[8:9], s[18:19]
	s_andn2_b64 vcc, exec, s[4:5]
	s_mov_b64 s[18:19], s[8:9]
	s_cbranch_vccnz .LBB0_3152
